# GEMM loops: removed the duplicate lgkmcnt(0) between the barrier and the first MFMA of each segment; on top of setprio-before-barrier
# baseline (speedup 1.0000x reference)
; #define PG8_STAGE(bufoff, gbase, voff) do { _Pragma("unroll") for (int _i = 0; _i < 2; ++_i) \
;         __builtin_amdgcn_global_load_lds((const unsigned*)((const char*)(gbase) + (voff)[_i]), (LAS unsigned*)(lds + (bufoff) + ldsw + _i * 8192), 16, 0, 0); } while (0)
; #define PG8_LDA(dst, b, h) do { _Pragma("unroll") for (int m = 0; m < 4; ++m) _Pragma("unroll") for (int k = 0; k < 2; ++k) dst[m][k] = *(const LAS bf16x8*)(lds + PG8_SA(b, h) + aoff + m * 2048 + k * 1024); } while (0)
; #define PG8_LDB(dst, b, h) do { _Pragma("unroll") for (int n = 0; n < 2; ++n) _Pragma("unroll") for (int k = 0; k < 2; ++k) dst[n][k] = *(const LAS bf16x8*)(lds + PG8_SB(b, h) + boff + n * 2048 + k * 1024); } while (0)
; #define PG8_WAIT_V(n) asm volatile("s_waitcnt vmcnt(" #n ")" ::: "memory")
; #define PG8_BAR __builtin_amdgcn_s_barrier()
; template <class Epi, class Sched>
; __device__ __forceinline__ void gemm_phase(LAS unsigned char* lds, const Gemm g, const Sched& S, const Epi& E) {
;     ...
;         const bool has_next = S.next(ui + 1, nxt);
;         const char* nA = has_next ? (const char*)g.A + (size_t)nxt.pm * tstep : cA; const char* nB = has_next ? (const char*)g.Bt + (size_t)nxt.pn * tstep : cB;
;         for (int t = 0; t < nt; t += 2) {
;             const bool last = (t == nt - 2);
;             const char* a1 = cA + (size_t)(t + 1) * kstep;
;             const char* a2 = last ? nA : cA + (size_t)(t + 2) * kstep; const char* b2 = last ? nB : cB + (size_t)(t + 2) * kstep;
;             const char* a3 = a2 + kstep; const char* b3 = b2 + kstep;
;             PG8_LDB(B0, 0, 0); PG8_SCHED; PG8_LDA(At, 0, 0); PG8_STAGE(PG8_SA(1, 1), a1 + hstep, voffA);
;             PG8_WAIT_L(8); PG8_BAR; PG8_WAIT_L(0); PG8_MMA(0, 0, At, B0); PG8_BAR; PG8_SCHED;
;             PG8_LDB(B1, 0, 1); PG8_STAGE(PG8_SB(0, 0), b2, voffB);
;             PG8_BAR; PG8_WAIT_L(0); PG8_MMA(0, 1, At, B1); PG8_BAR;
;             PG8_LDA(At, 0, 1); PG8_STAGE(PG8_SA(0, 0), a2, voffA);
;             PG8_BAR; PG8_WAIT_L(0); PG8_MMA(1, 0, At, B0); PG8_BAR; PG8_SCHED;
;             PG8_STAGE(PG8_SB(0, 1), b2 + hstep, voffB);
;             PG8_WAIT_V(6); PG8_BAR; PG8_MMA(1, 1, At, B1); PG8_BAR;
;             PG8_LDB(B0, 1, 0); PG8_SCHED; PG8_LDA(At, 1, 0); PG8_STAGE(PG8_SA(0, 1), a2 + hstep, voffA);
;             PG8_WAIT_L(8); PG8_BAR; PG8_WAIT_L(0); PG8_MMA(0, 0, At, B0); PG8_BAR; PG8_SCHED;
.LBB0_234:
	s_ashr_i32 s7, s6, 31
	v_cmp_lt_i64_e32 vcc, s[8:9], v[140:141]
	s_lshl_b64 s[8:9], s[6:7], 19
	s_add_u32 s8, s96, s8
	s_addc_u32 s9, s97, s9
	s_and_b64 s[10:11], vcc, exec
	s_cselect_b32 s7, s9, s15
	s_cselect_b32 s44, s8, s14
	s_ashr_i32 s5, s4, 31
	s_lshl_b64 s[10:11], s[4:5], 19
	s_add_u32 s10, s72, s10
	s_addc_u32 s11, s73, s11
	s_and_b64 s[16:17], vcc, exec
	s_cselect_b32 s5, s11, s19
	s_cselect_b32 s45, s10, s18
	s_add_u32 s14, s14, 0x40080
	s_addc_u32 s15, s15, 0
	s_add_u32 s46, s18, 0x100
	s_addc_u32 s47, s19, 0
	s_mov_b32 s48, -2
	ds_read_b128 v[150:153], v147
	ds_read_b128 v[154:157], v147 offset:1024
	ds_read_b128 v[158:161], v147 offset:2048
	ds_read_b128 v[162:165], v147 offset:3072
	s_add_u32 s16, s14, 0xfffc0080
	s_addc_u32 s17, s15, -1
	s_cmp_eq_u32 s48, 12
	s_cselect_b32 s23, s7, s17
	s_cselect_b32 s22, s44, s16
	s_cselect_b32 s19, s5, s47
	s_cselect_b32 s18, s45, s46
	s_add_i32 m0, s13, 0xc000
	ds_read_b128 v[166:169], v148
	ds_read_b128 v[170:173], v148 offset:1024
	ds_read_b128 v[174:177], v148 offset:2048
	ds_read_b128 v[178:181], v148 offset:3072
	ds_read_b128 v[182:185], v148 offset:4096
	ds_read_b128 v[186:189], v148 offset:5120
	ds_read_b128 v[190:193], v148 offset:6144
	ds_read_b128 v[194:197], v148 offset:7168
	global_load_lds_dwordx4 v136, s[14:15]
	s_add_i32 m0, s13, 0xe000
	s_nop 0
	global_load_lds_dwordx4 v138, s[14:15]
	s_waitcnt lgkmcnt(8)
	s_waitcnt vmcnt(8)
	s_setprio 1
	s_barrier
	s_waitcnt lgkmcnt(0)
	v_mfma_f32_16x16x32_bf16 v[124:127], v[150:153], v[166:169], 0
	v_mfma_f32_16x16x32_bf16 v[116:119], v[158:161], v[166:169], 0
	v_mfma_f32_16x16x32_bf16 v[108:111], v[150:153], v[174:177], 0
	v_mfma_f32_16x16x32_bf16 v[100:103], v[158:161], v[174:177], 0
	v_mfma_f32_16x16x32_bf16 v[92:95], v[150:153], v[182:185], 0
	v_mfma_f32_16x16x32_bf16 v[84:87], v[158:161], v[182:185], 0
	v_mfma_f32_16x16x32_bf16 v[76:79], v[150:153], v[190:193], 0
	v_mfma_f32_16x16x32_bf16 v[68:71], v[158:161], v[190:193], 0
	v_mfma_f32_16x16x32_bf16 v[124:127], v[154:157], v[170:173], v[124:127]
	v_mfma_f32_16x16x32_bf16 v[116:119], v[162:165], v[170:173], v[116:119]
	v_mfma_f32_16x16x32_bf16 v[108:111], v[154:157], v[178:181], v[108:111]
	v_mfma_f32_16x16x32_bf16 v[100:103], v[162:165], v[178:181], v[100:103]
	v_mfma_f32_16x16x32_bf16 v[92:95], v[154:157], v[186:189], v[92:95]
	v_mfma_f32_16x16x32_bf16 v[84:87], v[162:165], v[186:189], v[84:87]
	v_mfma_f32_16x16x32_bf16 v[76:79], v[154:157], v[194:197], v[76:79]
	v_mfma_f32_16x16x32_bf16 v[68:71], v[162:165], v[194:197], v[68:71]
	s_setprio 0
	s_barrier
	s_add_i32 s16, s40, s25
	s_mov_b32 m0, s16
	ds_read_b128 v[202:205], v149
	ds_read_b128 v[206:209], v149 offset:1024
	ds_read_b128 v[210:213], v149 offset:2048
	ds_read_b128 v[214:217], v149 offset:3072
	global_load_lds_dwordx4 v132, s[18:19]
	s_add_i32 m0, s16, 0x2000
	s_nop 0
	global_load_lds_dwordx4 v128, s[18:19]
	s_waitcnt vmcnt(8)
	s_setprio 1
	s_barrier
	s_waitcnt lgkmcnt(0)
	v_mfma_f32_16x16x32_bf16 v[120:123], v[202:205], v[166:169], 0
	v_mfma_f32_16x16x32_bf16 v[112:115], v[210:213], v[166:169], 0
	v_mfma_f32_16x16x32_bf16 v[104:107], v[202:205], v[174:177], 0
	v_mfma_f32_16x16x32_bf16 v[96:99], v[210:213], v[174:177], 0
	v_mfma_f32_16x16x32_bf16 v[88:91], v[202:205], v[182:185], 0
	v_mfma_f32_16x16x32_bf16 v[80:83], v[210:213], v[182:185], 0
	v_mfma_f32_16x16x32_bf16 v[72:75], v[202:205], v[190:193], 0
	v_mfma_f32_16x16x32_bf16 v[64:67], v[210:213], v[190:193], 0
	v_mfma_f32_16x16x32_bf16 v[120:123], v[206:209], v[170:173], v[120:123]
	v_mfma_f32_16x16x32_bf16 v[112:115], v[214:217], v[170:173], v[112:115]
	v_mfma_f32_16x16x32_bf16 v[104:107], v[206:209], v[178:181], v[104:107]
	v_mfma_f32_16x16x32_bf16 v[96:99], v[214:217], v[178:181], v[96:99]
	v_mfma_f32_16x16x32_bf16 v[88:91], v[206:209], v[186:189], v[88:91]
	v_mfma_f32_16x16x32_bf16 v[80:83], v[214:217], v[186:189], v[80:83]
	v_mfma_f32_16x16x32_bf16 v[72:75], v[206:209], v[194:197], v[72:75]
	v_mfma_f32_16x16x32_bf16 v[64:67], v[214:217], v[194:197], v[64:67]
	s_setprio 0
	s_mov_b32 m0, s13
	s_barrier
	ds_read_b128 v[166:169], v148 offset:16384
	ds_read_b128 v[170:173], v148 offset:17408
	ds_read_b128 v[174:177], v148 offset:18432
	ds_read_b128 v[178:181], v148 offset:19456
	ds_read_b128 v[182:185], v148 offset:20480
	ds_read_b128 v[186:189], v148 offset:21504
	ds_read_b128 v[190:193], v148 offset:22528
	ds_read_b128 v[194:197], v148 offset:23552
	global_load_lds_dwordx4 v134, s[22:23]
	s_mov_b32 m0, s28
	s_nop 0
	global_load_lds_dwordx4 v130, s[22:23]
	s_setprio 1
	s_barrier
	s_waitcnt lgkmcnt(0)
	v_mfma_f32_16x16x32_bf16 v[60:63], v[150:153], v[166:169], 0
	v_mfma_f32_16x16x32_bf16 v[56:59], v[158:161], v[166:169], 0
	v_mfma_f32_16x16x32_bf16 v[44:47], v[150:153], v[174:177], 0
	v_mfma_f32_16x16x32_bf16 v[40:43], v[158:161], v[174:177], 0
	v_mfma_f32_16x16x32_bf16 v[28:31], v[150:153], v[182:185], 0
	v_mfma_f32_16x16x32_bf16 v[24:27], v[158:161], v[182:185], 0
	v_mfma_f32_16x16x32_bf16 v[12:15], v[150:153], v[190:193], 0
	v_mfma_f32_16x16x32_bf16 v[8:11], v[158:161], v[190:193], 0
	v_mfma_f32_16x16x32_bf16 v[60:63], v[154:157], v[170:173], v[60:63]
	v_mfma_f32_16x16x32_bf16 v[56:59], v[162:165], v[170:173], v[56:59]
	v_mfma_f32_16x16x32_bf16 v[44:47], v[154:157], v[178:181], v[44:47]
	v_mfma_f32_16x16x32_bf16 v[40:43], v[162:165], v[178:181], v[40:43]
	v_mfma_f32_16x16x32_bf16 v[28:31], v[154:157], v[186:189], v[28:31]
	v_mfma_f32_16x16x32_bf16 v[24:27], v[162:165], v[186:189], v[24:27]
	v_mfma_f32_16x16x32_bf16 v[12:15], v[154:157], v[194:197], v[12:15]
	v_mfma_f32_16x16x32_bf16 v[8:11], v[162:165], v[194:197], v[8:11]
	s_setprio 0
	s_barrier
; #define PG8_STAGE(bufoff, gbase, voff) do { _Pragma("unroll") for (int _i = 0; _i < 2; ++_i) \
;         __builtin_amdgcn_global_load_lds((const unsigned*)((const char*)(gbase) + (voff)[_i]), (LAS unsigned*)(lds + (bufoff) + ldsw + _i * 8192), 16, 0, 0); } while (0)
; #define PG8_LDA(dst, b, h) do { _Pragma("unroll") for (int m = 0; m < 4; ++m) _Pragma("unroll") for (int k = 0; k < 2; ++k) dst[m][k] = *(const LAS bf16x8*)(lds + PG8_SA(b, h) + aoff + m * 2048 + k * 1024); } while (0)
; #define PG8_LDB(dst, b, h) do { _Pragma("unroll") for (int n = 0; n < 2; ++n) _Pragma("unroll") for (int k = 0; k < 2; ++k) dst[n][k] = *(const LAS bf16x8*)(lds + PG8_SB(b, h) + boff + n * 2048 + k * 1024); } while (0)
; #define PG8_MMA(ai, bj, At, Bt) do { __builtin_amdgcn_s_setprio(1); _Pragma("unroll") for (int m = 0; m < 4; ++m) _Pragma("unroll") for (int n = 0; n < 2; ++n) _Pragma("unroll") for (int k = 0; k < 2; ++k) \
;         acc[ai][bj][m][n] = __builtin_amdgcn_mfma_f32_16x16x32_bf16(Bt[n][k], At[m][k], acc[ai][bj][m][n], 0, 0, 0); __builtin_amdgcn_s_setprio(0); } while (0)
; #define PG8_WAIT_V(n) asm volatile("s_waitcnt vmcnt(" #n ")" ::: "memory")
; #define PG8_WAIT_L(n) asm volatile("s_waitcnt lgkmcnt(" #n ")" ::: "memory")
; #define PG8_BAR __builtin_amdgcn_s_barrier()
; #define PG8_SCHED __builtin_amdgcn_sched_barrier(0)
; template <class Epi, class Sched>
; __device__ __forceinline__ void gemm_phase(LAS unsigned char* lds, const Gemm g, const Sched& S, const Epi& E) {
;     ...
;             PG8_STAGE(PG8_SB(0, 1), b2 + hstep, voffB);
;             PG8_WAIT_V(6); PG8_BAR; PG8_MMA(1, 1, At, B1); PG8_BAR;
;             PG8_LDB(B0, 1, 0); PG8_SCHED; PG8_LDA(At, 1, 0); PG8_STAGE(PG8_SA(0, 1), a2 + hstep, voffA);
;             PG8_WAIT_L(8); PG8_BAR; PG8_WAIT_L(0); PG8_MMA(0, 0, At, B0); PG8_BAR; PG8_SCHED;
;             PG8_LDB(B1, 1, 1); PG8_STAGE(PG8_SB(1, 0), b3, voffB);
;             PG8_BAR; PG8_WAIT_L(0); PG8_MMA(0, 1, At, B1); PG8_BAR;
;             PG8_LDA(At, 1, 1); PG8_STAGE(PG8_SA(1, 0), a3, voffA);
;             PG8_BAR; PG8_WAIT_L(0); PG8_MMA(1, 0, At, B0); PG8_BAR; PG8_SCHED;
	s_add_u32 s16, s18, 0x40000
	s_addc_u32 s17, s19, 0
	s_add_i32 s20, s41, s25
	s_mov_b32 m0, s20
	s_nop 0
	global_load_lds_dwordx4 v132, s[16:17]
	s_add_i32 m0, s20, 0x2000
	s_nop 0
	global_load_lds_dwordx4 v128, s[16:17]
	s_add_u32 s16, s22, 0x40000
	s_addc_u32 s17, s23, 0
	s_mov_b32 m0, s29
	s_nop 0
	global_load_lds_dwordx4 v134, s[16:17]
	s_mov_b32 m0, s33
	s_nop 0
	global_load_lds_dwordx4 v130, s[16:17]
	s_waitcnt vmcnt(10)
	s_setprio 1
	s_barrier
	v_mfma_f32_16x16x32_bf16 v[52:55], v[202:205], v[166:169], 0
	v_mfma_f32_16x16x32_bf16 v[48:51], v[210:213], v[166:169], 0
	v_mfma_f32_16x16x32_bf16 v[36:39], v[202:205], v[174:177], 0
	v_mfma_f32_16x16x32_bf16 v[32:35], v[210:213], v[174:177], 0
	v_mfma_f32_16x16x32_bf16 v[20:23], v[202:205], v[182:185], 0
	v_mfma_f32_16x16x32_bf16 v[16:19], v[210:213], v[182:185], 0
	v_mfma_f32_16x16x32_bf16 v[4:7], v[202:205], v[190:193], 0
	v_mfma_f32_16x16x32_bf16 v[0:3], v[210:213], v[190:193], 0
	v_mfma_f32_16x16x32_bf16 v[52:55], v[206:209], v[170:173], v[52:55]
	v_mfma_f32_16x16x32_bf16 v[48:51], v[214:217], v[170:173], v[48:51]
	v_mfma_f32_16x16x32_bf16 v[36:39], v[206:209], v[178:181], v[36:39]
	v_mfma_f32_16x16x32_bf16 v[32:35], v[214:217], v[178:181], v[32:35]
	v_mfma_f32_16x16x32_bf16 v[20:23], v[206:209], v[186:189], v[20:23]
	v_mfma_f32_16x16x32_bf16 v[16:19], v[214:217], v[186:189], v[16:19]
	v_mfma_f32_16x16x32_bf16 v[4:7], v[206:209], v[194:197], v[4:7]
	v_mfma_f32_16x16x32_bf16 v[0:3], v[214:217], v[194:197], v[0:3]
	s_setprio 0
	s_add_i32 s20, 0, 0x18000
	v_add_u32_e32 v162, s20, v146
	s_barrier
	ds_read_b128 v[150:153], v162
	ds_read_b128 v[154:157], v162 offset:1024
	ds_read_b128 v[158:161], v162 offset:2048
	ds_read_b128 v[162:165], v162 offset:3072
	ds_read_b128 v[166:169], v148 offset:32768
	ds_read_b128 v[170:173], v148 offset:33792
	ds_read_b128 v[174:177], v148 offset:34816
	ds_read_b128 v[178:181], v148 offset:35840
	ds_read_b128 v[182:185], v148 offset:36864
	ds_read_b128 v[186:189], v148 offset:37888
	ds_read_b128 v[190:193], v148 offset:38912
	ds_read_b128 v[194:197], v148 offset:39936
	s_waitcnt lgkmcnt(8)
	s_waitcnt vmcnt(8)
	s_setprio 1
	s_barrier
	s_waitcnt lgkmcnt(0)
	v_mfma_f32_16x16x32_bf16 v[124:127], v[150:153], v[166:169], v[124:127]
	v_mfma_f32_16x16x32_bf16 v[116:119], v[158:161], v[166:169], v[116:119]
	v_mfma_f32_16x16x32_bf16 v[108:111], v[150:153], v[174:177], v[108:111]
	v_mfma_f32_16x16x32_bf16 v[100:103], v[158:161], v[174:177], v[100:103]
	v_mfma_f32_16x16x32_bf16 v[92:95], v[150:153], v[182:185], v[92:95]
	v_mfma_f32_16x16x32_bf16 v[84:87], v[158:161], v[182:185], v[84:87]
	v_mfma_f32_16x16x32_bf16 v[76:79], v[150:153], v[190:193], v[76:79]
	v_mfma_f32_16x16x32_bf16 v[68:71], v[158:161], v[190:193], v[68:71]
	v_mfma_f32_16x16x32_bf16 v[124:127], v[154:157], v[170:173], v[124:127]
	v_mfma_f32_16x16x32_bf16 v[116:119], v[162:165], v[170:173], v[116:119]
	v_mfma_f32_16x16x32_bf16 v[108:111], v[154:157], v[178:181], v[108:111]
	v_mfma_f32_16x16x32_bf16 v[100:103], v[162:165], v[178:181], v[100:103]
	v_mfma_f32_16x16x32_bf16 v[92:95], v[154:157], v[186:189], v[92:95]
	v_mfma_f32_16x16x32_bf16 v[84:87], v[162:165], v[186:189], v[84:87]
	v_mfma_f32_16x16x32_bf16 v[76:79], v[154:157], v[194:197], v[76:79]
	v_mfma_f32_16x16x32_bf16 v[68:71], v[162:165], v[194:197], v[68:71]
	s_setprio 0
	s_barrier
	s_add_i32 s21, 0, 0x1c000
	s_add_i32 s16, s20, s25
	v_add_u32_e32 v214, s21, v146
	s_add_u32 s0, s18, 0x80
	s_addc_u32 s1, s19, 0
	s_mov_b32 m0, s16
	ds_read_b128 v[202:205], v214
	ds_read_b128 v[206:209], v214 offset:1024
	ds_read_b128 v[210:213], v214 offset:2048
	ds_read_b128 v[214:217], v214 offset:3072
	global_load_lds_dwordx4 v132, s[0:1]
	s_add_i32 m0, s16, 0x2000
	s_nop 0
	global_load_lds_dwordx4 v128, s[0:1]
	s_waitcnt vmcnt(8)
	s_setprio 1
	s_barrier
	s_waitcnt lgkmcnt(0)
	v_mfma_f32_16x16x32_bf16 v[120:123], v[202:205], v[166:169], v[120:123]
	v_mfma_f32_16x16x32_bf16 v[112:115], v[210:213], v[166:169], v[112:115]
	v_mfma_f32_16x16x32_bf16 v[104:107], v[202:205], v[174:177], v[104:107]
	v_mfma_f32_16x16x32_bf16 v[96:99], v[210:213], v[174:177], v[96:99]
	v_mfma_f32_16x16x32_bf16 v[88:91], v[202:205], v[182:185], v[88:91]
	v_mfma_f32_16x16x32_bf16 v[80:83], v[210:213], v[182:185], v[80:83]
	v_mfma_f32_16x16x32_bf16 v[72:75], v[202:205], v[190:193], v[72:75]
	v_mfma_f32_16x16x32_bf16 v[64:67], v[210:213], v[190:193], v[64:67]
	v_mfma_f32_16x16x32_bf16 v[120:123], v[206:209], v[170:173], v[120:123]
	v_mfma_f32_16x16x32_bf16 v[112:115], v[214:217], v[170:173], v[112:115]
	v_mfma_f32_16x16x32_bf16 v[104:107], v[206:209], v[178:181], v[104:107]
	v_mfma_f32_16x16x32_bf16 v[96:99], v[214:217], v[178:181], v[96:99]
	v_mfma_f32_16x16x32_bf16 v[88:91], v[206:209], v[186:189], v[88:91]
	v_mfma_f32_16x16x32_bf16 v[80:83], v[214:217], v[186:189], v[80:83]
	v_mfma_f32_16x16x32_bf16 v[72:75], v[206:209], v[194:197], v[72:75]
	v_mfma_f32_16x16x32_bf16 v[64:67], v[214:217], v[194:197], v[64:67]
	s_setprio 0
	s_mov_b32 m0, s36
	s_add_u32 s0, s22, 0x80
	s_addc_u32 s1, s23, 0
	s_barrier
	ds_read_b128 v[166:169], v148 offset:49152
	ds_read_b128 v[170:173], v148 offset:50176
	ds_read_b128 v[174:177], v148 offset:51200
	ds_read_b128 v[178:181], v148 offset:52224
	ds_read_b128 v[182:185], v148 offset:53248
	ds_read_b128 v[186:189], v148 offset:54272
	ds_read_b128 v[190:193], v148 offset:55296
	ds_read_b128 v[194:197], v148 offset:56320
	global_load_lds_dwordx4 v134, s[0:1]
	s_mov_b32 m0, s37
	s_nop 0
	global_load_lds_dwordx4 v130, s[0:1]
	s_setprio 1
	s_barrier
; #define PG8_STAGE(bufoff, gbase, voff) do { _Pragma("unroll") for (int _i = 0; _i < 2; ++_i) \
;         __builtin_amdgcn_global_load_lds((const unsigned*)((const char*)(gbase) + (voff)[_i]), (LAS unsigned*)(lds + (bufoff) + ldsw + _i * 8192), 16, 0, 0); } while (0)
; #define PG8_LDA(dst, b, h) do { _Pragma("unroll") for (int m = 0; m < 4; ++m) _Pragma("unroll") for (int k = 0; k < 2; ++k) dst[m][k] = *(const LAS bf16x8*)(lds + PG8_SA(b, h) + aoff + m * 2048 + k * 1024); } while (0)
; #define PG8_LDB(dst, b, h) do { _Pragma("unroll") for (int n = 0; n < 2; ++n) _Pragma("unroll") for (int k = 0; k < 2; ++k) dst[n][k] = *(const LAS bf16x8*)(lds + PG8_SB(b, h) + boff + n * 2048 + k * 1024); } while (0)
; #define PG8_MMA(ai, bj, At, Bt) do { __builtin_amdgcn_s_setprio(1); _Pragma("unroll") for (int m = 0; m < 4; ++m) _Pragma("unroll") for (int n = 0; n < 2; ++n) _Pragma("unroll") for (int k = 0; k < 2; ++k) \
;         acc[ai][bj][m][n] = __builtin_amdgcn_mfma_f32_16x16x32_bf16(Bt[n][k], At[m][k], acc[ai][bj][m][n], 0, 0, 0); __builtin_amdgcn_s_setprio(0); } while (0)
; #define PG8_BAR __builtin_amdgcn_s_barrier()
; template <class Epi, class Sched>
; __device__ __forceinline__ void gemm_phase(LAS unsigned char* lds, const Gemm g, const Sched& S, const Epi& E) {
;     ...
;         for (int t = 0; t < nt; t += 2) {
;             const bool last = (t == nt - 2);
;             const char* a1 = cA + (size_t)(t + 1) * kstep;
;             const char* a2 = last ? nA : cA + (size_t)(t + 2) * kstep; const char* b2 = last ? nB : cB + (size_t)(t + 2) * kstep;
;             const char* a3 = a2 + kstep; const char* b3 = b2 + kstep;
;             PG8_LDB(B0, 0, 0); PG8_SCHED; PG8_LDA(At, 0, 0); PG8_STAGE(PG8_SA(1, 1), a1 + hstep, voffA);
;             PG8_WAIT_L(8); PG8_BAR; PG8_WAIT_L(0); PG8_MMA(0, 0, At, B0); PG8_BAR; PG8_SCHED;
;             PG8_LDB(B1, 0, 1); PG8_STAGE(PG8_SB(0, 0), b2, voffB);
;             PG8_BAR; PG8_WAIT_L(0); PG8_MMA(0, 1, At, B1); PG8_BAR;
;             PG8_LDA(At, 0, 1); PG8_STAGE(PG8_SA(0, 0), a2, voffA);
;             PG8_BAR; PG8_WAIT_L(0); PG8_MMA(1, 0, At, B0); PG8_BAR; PG8_SCHED;
;             PG8_STAGE(PG8_SB(0, 1), b2 + hstep, voffB);
;     ...
;             PG8_BAR; PG8_WAIT_L(0); PG8_MMA(1, 0, At, B0); PG8_BAR; PG8_SCHED;
;             PG8_STAGE(PG8_SB(1, 1), b3 + hstep, voffB);
;             PG8_WAIT_V(6); PG8_BAR; PG8_MMA(1, 1, At, B1); PG8_BAR;
	s_waitcnt lgkmcnt(0)
	v_mfma_f32_16x16x32_bf16 v[60:63], v[150:153], v[166:169], v[60:63]
	v_mfma_f32_16x16x32_bf16 v[56:59], v[158:161], v[166:169], v[56:59]
	v_mfma_f32_16x16x32_bf16 v[44:47], v[150:153], v[174:177], v[44:47]
	v_mfma_f32_16x16x32_bf16 v[40:43], v[158:161], v[174:177], v[40:43]
	v_mfma_f32_16x16x32_bf16 v[28:31], v[150:153], v[182:185], v[28:31]
	v_mfma_f32_16x16x32_bf16 v[24:27], v[158:161], v[182:185], v[24:27]
	v_mfma_f32_16x16x32_bf16 v[12:15], v[150:153], v[190:193], v[12:15]
	v_mfma_f32_16x16x32_bf16 v[8:11], v[158:161], v[190:193], v[8:11]
	v_mfma_f32_16x16x32_bf16 v[60:63], v[154:157], v[170:173], v[60:63]
	v_mfma_f32_16x16x32_bf16 v[56:59], v[162:165], v[170:173], v[56:59]
	v_mfma_f32_16x16x32_bf16 v[44:47], v[154:157], v[178:181], v[44:47]
	v_mfma_f32_16x16x32_bf16 v[40:43], v[162:165], v[178:181], v[40:43]
	v_mfma_f32_16x16x32_bf16 v[28:31], v[154:157], v[186:189], v[28:31]
	v_mfma_f32_16x16x32_bf16 v[24:27], v[162:165], v[186:189], v[24:27]
	v_mfma_f32_16x16x32_bf16 v[12:15], v[154:157], v[194:197], v[12:15]
	v_mfma_f32_16x16x32_bf16 v[8:11], v[162:165], v[194:197], v[8:11]
	s_setprio 0
	s_barrier
	s_add_u32 s16, s18, 0x40080
	s_addc_u32 s17, s19, 0
	s_add_i32 s18, s21, s25
	s_mov_b32 m0, s18
	s_nop 0
	global_load_lds_dwordx4 v132, s[16:17]
	s_add_i32 m0, s18, 0x2000
	s_nop 0
	global_load_lds_dwordx4 v128, s[16:17]
	s_waitcnt vmcnt(8)
	s_setprio 1
	s_barrier
	v_mfma_f32_16x16x32_bf16 v[52:55], v[202:205], v[166:169], v[52:55]
	v_mfma_f32_16x16x32_bf16 v[48:51], v[210:213], v[166:169], v[48:51]
	v_mfma_f32_16x16x32_bf16 v[36:39], v[202:205], v[174:177], v[36:39]
	v_mfma_f32_16x16x32_bf16 v[32:35], v[210:213], v[174:177], v[32:35]
	v_mfma_f32_16x16x32_bf16 v[20:23], v[202:205], v[182:185], v[20:23]
	v_mfma_f32_16x16x32_bf16 v[16:19], v[210:213], v[182:185], v[16:19]
	v_mfma_f32_16x16x32_bf16 v[4:7], v[202:205], v[190:193], v[4:7]
	v_mfma_f32_16x16x32_bf16 v[0:3], v[210:213], v[190:193], v[0:3]
	v_mfma_f32_16x16x32_bf16 v[52:55], v[206:209], v[170:173], v[52:55]
	v_mfma_f32_16x16x32_bf16 v[48:51], v[214:217], v[170:173], v[48:51]
	v_mfma_f32_16x16x32_bf16 v[36:39], v[206:209], v[178:181], v[36:39]
	v_mfma_f32_16x16x32_bf16 v[32:35], v[214:217], v[178:181], v[32:35]
	v_mfma_f32_16x16x32_bf16 v[20:23], v[206:209], v[186:189], v[20:23]
	v_mfma_f32_16x16x32_bf16 v[16:19], v[214:217], v[186:189], v[16:19]
	v_mfma_f32_16x16x32_bf16 v[4:7], v[206:209], v[194:197], v[4:7]
	v_mfma_f32_16x16x32_bf16 v[0:3], v[214:217], v[194:197], v[0:3]
	s_setprio 0
	s_add_i32 s48, s48, 2
	s_add_u32 s14, s14, 0x100
	s_addc_u32 s15, s15, 0
	s_add_u32 s46, s46, 0x100
	s_addc_u32 s47, s47, 0
	s_cmp_gt_u32 s48, 13
	s_barrier
.LBB0_235:
	ds_read_b128 v[150:153], v147
	ds_read_b128 v[154:157], v147 offset:1024
	ds_read_b128 v[158:161], v147 offset:2048
	ds_read_b128 v[162:165], v147 offset:3072
	s_add_u32 s16, s14, 0xfffc0080
	s_addc_u32 s17, s15, -1
	s_cmp_eq_u32 s48, 12
	s_cselect_b32 s23, s7, s17
	s_cselect_b32 s22, s44, s16
	s_cselect_b32 s19, s5, s47
	s_cselect_b32 s18, s45, s46
	s_add_i32 m0, s13, 0xc000
	ds_read_b128 v[166:169], v148
	ds_read_b128 v[170:173], v148 offset:1024
	ds_read_b128 v[174:177], v148 offset:2048
	ds_read_b128 v[178:181], v148 offset:3072
	ds_read_b128 v[182:185], v148 offset:4096
	ds_read_b128 v[186:189], v148 offset:5120
	ds_read_b128 v[190:193], v148 offset:6144
	ds_read_b128 v[194:197], v148 offset:7168
	global_load_lds_dwordx4 v136, s[14:15]
	s_add_i32 m0, s13, 0xe000
	s_nop 0
	global_load_lds_dwordx4 v138, s[14:15]
	s_waitcnt lgkmcnt(8)
	s_waitcnt vmcnt(8)
	s_setprio 1
	s_barrier
	s_waitcnt lgkmcnt(0)
	v_mfma_f32_16x16x32_bf16 v[124:127], v[150:153], v[166:169], v[124:127]
	v_mfma_f32_16x16x32_bf16 v[116:119], v[158:161], v[166:169], v[116:119]
	v_mfma_f32_16x16x32_bf16 v[108:111], v[150:153], v[174:177], v[108:111]
	v_mfma_f32_16x16x32_bf16 v[100:103], v[158:161], v[174:177], v[100:103]
	v_mfma_f32_16x16x32_bf16 v[92:95], v[150:153], v[182:185], v[92:95]
	v_mfma_f32_16x16x32_bf16 v[84:87], v[158:161], v[182:185], v[84:87]
	v_mfma_f32_16x16x32_bf16 v[76:79], v[150:153], v[190:193], v[76:79]
	v_mfma_f32_16x16x32_bf16 v[68:71], v[158:161], v[190:193], v[68:71]
	v_mfma_f32_16x16x32_bf16 v[124:127], v[154:157], v[170:173], v[124:127]
	v_mfma_f32_16x16x32_bf16 v[116:119], v[162:165], v[170:173], v[116:119]
	v_mfma_f32_16x16x32_bf16 v[108:111], v[154:157], v[178:181], v[108:111]
	v_mfma_f32_16x16x32_bf16 v[100:103], v[162:165], v[178:181], v[100:103]
	v_mfma_f32_16x16x32_bf16 v[92:95], v[154:157], v[186:189], v[92:95]
	v_mfma_f32_16x16x32_bf16 v[84:87], v[162:165], v[186:189], v[84:87]
	v_mfma_f32_16x16x32_bf16 v[76:79], v[154:157], v[194:197], v[76:79]
	v_mfma_f32_16x16x32_bf16 v[68:71], v[162:165], v[194:197], v[68:71]
	s_setprio 0
	s_barrier
	s_add_i32 s16, s40, s25
	s_mov_b32 m0, s16
	ds_read_b128 v[202:205], v149
	ds_read_b128 v[206:209], v149 offset:1024
	ds_read_b128 v[210:213], v149 offset:2048
	ds_read_b128 v[214:217], v149 offset:3072
	global_load_lds_dwordx4 v132, s[18:19]
	s_add_i32 m0, s16, 0x2000
	s_nop 0
	global_load_lds_dwordx4 v128, s[18:19]
	s_waitcnt vmcnt(8)
	s_setprio 1
	s_barrier
; #define PG8_STAGE(bufoff, gbase, voff) do { _Pragma("unroll") for (int _i = 0; _i < 2; ++_i) \
;         __builtin_amdgcn_global_load_lds((const unsigned*)((const char*)(gbase) + (voff)[_i]), (LAS unsigned*)(lds + (bufoff) + ldsw + _i * 8192), 16, 0, 0); } while (0)
; #define PG8_LDA(dst, b, h) do { _Pragma("unroll") for (int m = 0; m < 4; ++m) _Pragma("unroll") for (int k = 0; k < 2; ++k) dst[m][k] = *(const LAS bf16x8*)(lds + PG8_SA(b, h) + aoff + m * 2048 + k * 1024); } while (0)
; #define PG8_LDB(dst, b, h) do { _Pragma("unroll") for (int n = 0; n < 2; ++n) _Pragma("unroll") for (int k = 0; k < 2; ++k) dst[n][k] = *(const LAS bf16x8*)(lds + PG8_SB(b, h) + boff + n * 2048 + k * 1024); } while (0)
; #define PG8_MMA(ai, bj, At, Bt) do { __builtin_amdgcn_s_setprio(1); _Pragma("unroll") for (int m = 0; m < 4; ++m) _Pragma("unroll") for (int n = 0; n < 2; ++n) _Pragma("unroll") for (int k = 0; k < 2; ++k) \
;         acc[ai][bj][m][n] = __builtin_amdgcn_mfma_f32_16x16x32_bf16(Bt[n][k], At[m][k], acc[ai][bj][m][n], 0, 0, 0); __builtin_amdgcn_s_setprio(0); } while (0)
; #define PG8_WAIT_V(n) asm volatile("s_waitcnt vmcnt(" #n ")" ::: "memory")
; #define PG8_WAIT_L(n) asm volatile("s_waitcnt lgkmcnt(" #n ")" ::: "memory")
; #define PG8_BAR __builtin_amdgcn_s_barrier()
; #define PG8_SCHED __builtin_amdgcn_sched_barrier(0)
; template <class Epi, class Sched>
; __device__ __forceinline__ void gemm_phase(LAS unsigned char* lds, const Gemm g, const Sched& S, const Epi& E) {
;     ...
;             PG8_BAR; PG8_WAIT_L(0); PG8_MMA(0, 1, At, B1); PG8_BAR;
;             PG8_LDA(At, 0, 1); PG8_STAGE(PG8_SA(0, 0), a2, voffA);
;             PG8_BAR; PG8_WAIT_L(0); PG8_MMA(1, 0, At, B0); PG8_BAR; PG8_SCHED;
;             PG8_STAGE(PG8_SB(0, 1), b2 + hstep, voffB);
;             PG8_WAIT_V(6); PG8_BAR; PG8_MMA(1, 1, At, B1); PG8_BAR;
;             PG8_LDB(B0, 1, 0); PG8_SCHED; PG8_LDA(At, 1, 0); PG8_STAGE(PG8_SA(0, 1), a2 + hstep, voffA);
;             PG8_WAIT_L(8); PG8_BAR; PG8_WAIT_L(0); PG8_MMA(0, 0, At, B0); PG8_BAR; PG8_SCHED;
	s_waitcnt lgkmcnt(0)
	v_mfma_f32_16x16x32_bf16 v[120:123], v[202:205], v[166:169], v[120:123]
	v_mfma_f32_16x16x32_bf16 v[112:115], v[210:213], v[166:169], v[112:115]
	v_mfma_f32_16x16x32_bf16 v[104:107], v[202:205], v[174:177], v[104:107]
	v_mfma_f32_16x16x32_bf16 v[96:99], v[210:213], v[174:177], v[96:99]
	v_mfma_f32_16x16x32_bf16 v[88:91], v[202:205], v[182:185], v[88:91]
	v_mfma_f32_16x16x32_bf16 v[80:83], v[210:213], v[182:185], v[80:83]
	v_mfma_f32_16x16x32_bf16 v[72:75], v[202:205], v[190:193], v[72:75]
	v_mfma_f32_16x16x32_bf16 v[64:67], v[210:213], v[190:193], v[64:67]
	v_mfma_f32_16x16x32_bf16 v[120:123], v[206:209], v[170:173], v[120:123]
	v_mfma_f32_16x16x32_bf16 v[112:115], v[214:217], v[170:173], v[112:115]
	v_mfma_f32_16x16x32_bf16 v[104:107], v[206:209], v[178:181], v[104:107]
	v_mfma_f32_16x16x32_bf16 v[96:99], v[214:217], v[178:181], v[96:99]
	v_mfma_f32_16x16x32_bf16 v[88:91], v[206:209], v[186:189], v[88:91]
	v_mfma_f32_16x16x32_bf16 v[80:83], v[214:217], v[186:189], v[80:83]
	v_mfma_f32_16x16x32_bf16 v[72:75], v[206:209], v[194:197], v[72:75]
	v_mfma_f32_16x16x32_bf16 v[64:67], v[214:217], v[194:197], v[64:67]
	s_setprio 0
	s_mov_b32 m0, s13
	s_barrier
	ds_read_b128 v[166:169], v148 offset:16384
	ds_read_b128 v[170:173], v148 offset:17408
	ds_read_b128 v[174:177], v148 offset:18432
	ds_read_b128 v[178:181], v148 offset:19456
	ds_read_b128 v[182:185], v148 offset:20480
	ds_read_b128 v[186:189], v148 offset:21504
	ds_read_b128 v[190:193], v148 offset:22528
	ds_read_b128 v[194:197], v148 offset:23552
	global_load_lds_dwordx4 v134, s[22:23]
	s_mov_b32 m0, s28
	s_nop 0
	global_load_lds_dwordx4 v130, s[22:23]
	s_setprio 1
	s_barrier
	s_waitcnt lgkmcnt(0)
	v_mfma_f32_16x16x32_bf16 v[60:63], v[150:153], v[166:169], v[60:63]
	v_mfma_f32_16x16x32_bf16 v[56:59], v[158:161], v[166:169], v[56:59]
	v_mfma_f32_16x16x32_bf16 v[44:47], v[150:153], v[174:177], v[44:47]
	v_mfma_f32_16x16x32_bf16 v[40:43], v[158:161], v[174:177], v[40:43]
	v_mfma_f32_16x16x32_bf16 v[28:31], v[150:153], v[182:185], v[28:31]
	v_mfma_f32_16x16x32_bf16 v[24:27], v[158:161], v[182:185], v[24:27]
	v_mfma_f32_16x16x32_bf16 v[12:15], v[150:153], v[190:193], v[12:15]
	v_mfma_f32_16x16x32_bf16 v[8:11], v[158:161], v[190:193], v[8:11]
	v_mfma_f32_16x16x32_bf16 v[60:63], v[154:157], v[170:173], v[60:63]
	v_mfma_f32_16x16x32_bf16 v[56:59], v[162:165], v[170:173], v[56:59]
	v_mfma_f32_16x16x32_bf16 v[44:47], v[154:157], v[178:181], v[44:47]
	v_mfma_f32_16x16x32_bf16 v[40:43], v[162:165], v[178:181], v[40:43]
	v_mfma_f32_16x16x32_bf16 v[28:31], v[154:157], v[186:189], v[28:31]
	v_mfma_f32_16x16x32_bf16 v[24:27], v[162:165], v[186:189], v[24:27]
	v_mfma_f32_16x16x32_bf16 v[12:15], v[154:157], v[194:197], v[12:15]
	v_mfma_f32_16x16x32_bf16 v[8:11], v[162:165], v[194:197], v[8:11]
	s_setprio 0
	s_barrier
	s_add_u32 s16, s18, 0x40000
	s_addc_u32 s17, s19, 0
	s_add_i32 s20, s41, s25
	s_mov_b32 m0, s20
	s_nop 0
	global_load_lds_dwordx4 v132, s[16:17]
	s_add_i32 m0, s20, 0x2000
	s_nop 0
	global_load_lds_dwordx4 v128, s[16:17]
	s_add_u32 s16, s22, 0x40000
	s_addc_u32 s17, s23, 0
	s_mov_b32 m0, s29
	s_nop 0
	global_load_lds_dwordx4 v134, s[16:17]
	s_mov_b32 m0, s33
	s_nop 0
	global_load_lds_dwordx4 v130, s[16:17]
	s_waitcnt vmcnt(10)
	s_setprio 1
	s_barrier
	v_mfma_f32_16x16x32_bf16 v[52:55], v[202:205], v[166:169], v[52:55]
	v_mfma_f32_16x16x32_bf16 v[48:51], v[210:213], v[166:169], v[48:51]
	v_mfma_f32_16x16x32_bf16 v[36:39], v[202:205], v[174:177], v[36:39]
	v_mfma_f32_16x16x32_bf16 v[32:35], v[210:213], v[174:177], v[32:35]
	v_mfma_f32_16x16x32_bf16 v[20:23], v[202:205], v[182:185], v[20:23]
	v_mfma_f32_16x16x32_bf16 v[16:19], v[210:213], v[182:185], v[16:19]
	v_mfma_f32_16x16x32_bf16 v[4:7], v[202:205], v[190:193], v[4:7]
	v_mfma_f32_16x16x32_bf16 v[0:3], v[210:213], v[190:193], v[0:3]
	v_mfma_f32_16x16x32_bf16 v[52:55], v[206:209], v[170:173], v[52:55]
	v_mfma_f32_16x16x32_bf16 v[48:51], v[214:217], v[170:173], v[48:51]
	v_mfma_f32_16x16x32_bf16 v[36:39], v[206:209], v[178:181], v[36:39]
	v_mfma_f32_16x16x32_bf16 v[32:35], v[214:217], v[178:181], v[32:35]
	v_mfma_f32_16x16x32_bf16 v[20:23], v[206:209], v[186:189], v[20:23]
	v_mfma_f32_16x16x32_bf16 v[16:19], v[214:217], v[186:189], v[16:19]
	v_mfma_f32_16x16x32_bf16 v[4:7], v[206:209], v[194:197], v[4:7]
	v_mfma_f32_16x16x32_bf16 v[0:3], v[214:217], v[194:197], v[0:3]
	s_setprio 0
	s_add_i32 s20, 0, 0x18000
	v_add_u32_e32 v162, s20, v146
	s_barrier
	ds_read_b128 v[150:153], v162
	ds_read_b128 v[154:157], v162 offset:1024
	ds_read_b128 v[158:161], v162 offset:2048
	ds_read_b128 v[162:165], v162 offset:3072
	ds_read_b128 v[166:169], v148 offset:32768
	ds_read_b128 v[170:173], v148 offset:33792
	ds_read_b128 v[174:177], v148 offset:34816
	ds_read_b128 v[178:181], v148 offset:35840
	ds_read_b128 v[182:185], v148 offset:36864
	ds_read_b128 v[186:189], v148 offset:37888
	ds_read_b128 v[190:193], v148 offset:38912
	ds_read_b128 v[194:197], v148 offset:39936
	s_waitcnt lgkmcnt(8)
	s_waitcnt vmcnt(8)
	s_setprio 1
	s_barrier
; #define PG8_STAGE(bufoff, gbase, voff) do { _Pragma("unroll") for (int _i = 0; _i < 2; ++_i) \
;         __builtin_amdgcn_global_load_lds((const unsigned*)((const char*)(gbase) + (voff)[_i]), (LAS unsigned*)(lds + (bufoff) + ldsw + _i * 8192), 16, 0, 0); } while (0)
; #define PG8_LDA(dst, b, h) do { _Pragma("unroll") for (int m = 0; m < 4; ++m) _Pragma("unroll") for (int k = 0; k < 2; ++k) dst[m][k] = *(const LAS bf16x8*)(lds + PG8_SA(b, h) + aoff + m * 2048 + k * 1024); } while (0)
; #define PG8_LDB(dst, b, h) do { _Pragma("unroll") for (int n = 0; n < 2; ++n) _Pragma("unroll") for (int k = 0; k < 2; ++k) dst[n][k] = *(const LAS bf16x8*)(lds + PG8_SB(b, h) + boff + n * 2048 + k * 1024); } while (0)
; #define PG8_MMA(ai, bj, At, Bt) do { __builtin_amdgcn_s_setprio(1); _Pragma("unroll") for (int m = 0; m < 4; ++m) _Pragma("unroll") for (int n = 0; n < 2; ++n) _Pragma("unroll") for (int k = 0; k < 2; ++k) \
;         acc[ai][bj][m][n] = __builtin_amdgcn_mfma_f32_16x16x32_bf16(Bt[n][k], At[m][k], acc[ai][bj][m][n], 0, 0, 0); __builtin_amdgcn_s_setprio(0); } while (0)
; #define PG8_WAIT_V(n) asm volatile("s_waitcnt vmcnt(" #n ")" ::: "memory")
; #define PG8_WAIT_L(n) asm volatile("s_waitcnt lgkmcnt(" #n ")" ::: "memory")
; #define PG8_BAR __builtin_amdgcn_s_barrier()
; #define PG8_SCHED __builtin_amdgcn_sched_barrier(0)
; template <class Epi, class Sched>
; __device__ __forceinline__ void gemm_phase(LAS unsigned char* lds, const Gemm g, const Sched& S, const Epi& E) {
;     ...
;             PG8_WAIT_L(8); PG8_BAR; PG8_WAIT_L(0); PG8_MMA(0, 0, At, B0); PG8_BAR; PG8_SCHED;
;             PG8_LDB(B1, 1, 1); PG8_STAGE(PG8_SB(1, 0), b3, voffB);
;             PG8_BAR; PG8_WAIT_L(0); PG8_MMA(0, 1, At, B1); PG8_BAR;
;             PG8_LDA(At, 1, 1); PG8_STAGE(PG8_SA(1, 0), a3, voffA);
;             PG8_BAR; PG8_WAIT_L(0); PG8_MMA(1, 0, At, B0); PG8_BAR; PG8_SCHED;
;             PG8_STAGE(PG8_SB(1, 1), b3 + hstep, voffB);
;             PG8_WAIT_V(6); PG8_BAR; PG8_MMA(1, 1, At, B1); PG8_BAR;
	s_waitcnt lgkmcnt(0)
	v_mfma_f32_16x16x32_bf16 v[124:127], v[150:153], v[166:169], v[124:127]
	v_mfma_f32_16x16x32_bf16 v[116:119], v[158:161], v[166:169], v[116:119]
	v_mfma_f32_16x16x32_bf16 v[108:111], v[150:153], v[174:177], v[108:111]
	v_mfma_f32_16x16x32_bf16 v[100:103], v[158:161], v[174:177], v[100:103]
	v_mfma_f32_16x16x32_bf16 v[92:95], v[150:153], v[182:185], v[92:95]
	v_mfma_f32_16x16x32_bf16 v[84:87], v[158:161], v[182:185], v[84:87]
	v_mfma_f32_16x16x32_bf16 v[76:79], v[150:153], v[190:193], v[76:79]
	v_mfma_f32_16x16x32_bf16 v[68:71], v[158:161], v[190:193], v[68:71]
	v_mfma_f32_16x16x32_bf16 v[124:127], v[154:157], v[170:173], v[124:127]
	v_mfma_f32_16x16x32_bf16 v[116:119], v[162:165], v[170:173], v[116:119]
	v_mfma_f32_16x16x32_bf16 v[108:111], v[154:157], v[178:181], v[108:111]
	v_mfma_f32_16x16x32_bf16 v[100:103], v[162:165], v[178:181], v[100:103]
	v_mfma_f32_16x16x32_bf16 v[92:95], v[154:157], v[186:189], v[92:95]
	v_mfma_f32_16x16x32_bf16 v[84:87], v[162:165], v[186:189], v[84:87]
	v_mfma_f32_16x16x32_bf16 v[76:79], v[154:157], v[194:197], v[76:79]
	v_mfma_f32_16x16x32_bf16 v[68:71], v[162:165], v[194:197], v[68:71]
	s_setprio 0
	s_barrier
	s_add_i32 s21, 0, 0x1c000
	s_add_i32 s16, s20, s25
	v_add_u32_e32 v214, s21, v146
	s_add_u32 s0, s18, 0x80
	s_addc_u32 s1, s19, 0
	s_mov_b32 m0, s16
	ds_read_b128 v[202:205], v214
	ds_read_b128 v[206:209], v214 offset:1024
	ds_read_b128 v[210:213], v214 offset:2048
	ds_read_b128 v[214:217], v214 offset:3072
	global_load_lds_dwordx4 v132, s[0:1]
	s_add_i32 m0, s16, 0x2000
	s_nop 0
	global_load_lds_dwordx4 v128, s[0:1]
	s_waitcnt vmcnt(8)
	s_setprio 1
	s_barrier
	s_waitcnt lgkmcnt(0)
	v_mfma_f32_16x16x32_bf16 v[120:123], v[202:205], v[166:169], v[120:123]
	v_mfma_f32_16x16x32_bf16 v[112:115], v[210:213], v[166:169], v[112:115]
	v_mfma_f32_16x16x32_bf16 v[104:107], v[202:205], v[174:177], v[104:107]
	v_mfma_f32_16x16x32_bf16 v[96:99], v[210:213], v[174:177], v[96:99]
	v_mfma_f32_16x16x32_bf16 v[88:91], v[202:205], v[182:185], v[88:91]
	v_mfma_f32_16x16x32_bf16 v[80:83], v[210:213], v[182:185], v[80:83]
	v_mfma_f32_16x16x32_bf16 v[72:75], v[202:205], v[190:193], v[72:75]
	v_mfma_f32_16x16x32_bf16 v[64:67], v[210:213], v[190:193], v[64:67]
	v_mfma_f32_16x16x32_bf16 v[120:123], v[206:209], v[170:173], v[120:123]
	v_mfma_f32_16x16x32_bf16 v[112:115], v[214:217], v[170:173], v[112:115]
	v_mfma_f32_16x16x32_bf16 v[104:107], v[206:209], v[178:181], v[104:107]
	v_mfma_f32_16x16x32_bf16 v[96:99], v[214:217], v[178:181], v[96:99]
	v_mfma_f32_16x16x32_bf16 v[88:91], v[206:209], v[186:189], v[88:91]
	v_mfma_f32_16x16x32_bf16 v[80:83], v[214:217], v[186:189], v[80:83]
	v_mfma_f32_16x16x32_bf16 v[72:75], v[206:209], v[194:197], v[72:75]
	v_mfma_f32_16x16x32_bf16 v[64:67], v[214:217], v[194:197], v[64:67]
	s_setprio 0
	s_mov_b32 m0, s36
	s_add_u32 s0, s22, 0x80
	s_addc_u32 s1, s23, 0
	s_barrier
	ds_read_b128 v[166:169], v148 offset:49152
	ds_read_b128 v[170:173], v148 offset:50176
	ds_read_b128 v[174:177], v148 offset:51200
	ds_read_b128 v[178:181], v148 offset:52224
	ds_read_b128 v[182:185], v148 offset:53248
	ds_read_b128 v[186:189], v148 offset:54272
	ds_read_b128 v[190:193], v148 offset:55296
	ds_read_b128 v[194:197], v148 offset:56320
	global_load_lds_dwordx4 v134, s[0:1]
	s_mov_b32 m0, s37
	s_nop 0
	global_load_lds_dwordx4 v130, s[0:1]
	s_setprio 1
	s_barrier
	s_waitcnt lgkmcnt(0)
	v_mfma_f32_16x16x32_bf16 v[60:63], v[150:153], v[166:169], v[60:63]
	v_mfma_f32_16x16x32_bf16 v[56:59], v[158:161], v[166:169], v[56:59]
	v_mfma_f32_16x16x32_bf16 v[44:47], v[150:153], v[174:177], v[44:47]
	v_mfma_f32_16x16x32_bf16 v[40:43], v[158:161], v[174:177], v[40:43]
	v_mfma_f32_16x16x32_bf16 v[28:31], v[150:153], v[182:185], v[28:31]
	v_mfma_f32_16x16x32_bf16 v[24:27], v[158:161], v[182:185], v[24:27]
	v_mfma_f32_16x16x32_bf16 v[12:15], v[150:153], v[190:193], v[12:15]
	v_mfma_f32_16x16x32_bf16 v[8:11], v[158:161], v[190:193], v[8:11]
	v_mfma_f32_16x16x32_bf16 v[60:63], v[154:157], v[170:173], v[60:63]
	v_mfma_f32_16x16x32_bf16 v[56:59], v[162:165], v[170:173], v[56:59]
	v_mfma_f32_16x16x32_bf16 v[44:47], v[154:157], v[178:181], v[44:47]
	v_mfma_f32_16x16x32_bf16 v[40:43], v[162:165], v[178:181], v[40:43]
	v_mfma_f32_16x16x32_bf16 v[28:31], v[154:157], v[186:189], v[28:31]
	v_mfma_f32_16x16x32_bf16 v[24:27], v[162:165], v[186:189], v[24:27]
	v_mfma_f32_16x16x32_bf16 v[12:15], v[154:157], v[194:197], v[12:15]
	v_mfma_f32_16x16x32_bf16 v[8:11], v[162:165], v[194:197], v[8:11]
	s_setprio 0
	s_barrier
	s_add_u32 s16, s18, 0x40080
	s_addc_u32 s17, s19, 0
	s_add_i32 s18, s21, s25
	s_mov_b32 m0, s18
	s_nop 0
	global_load_lds_dwordx4 v132, s[16:17]
	s_add_i32 m0, s18, 0x2000
	s_nop 0
	global_load_lds_dwordx4 v128, s[16:17]
	s_waitcnt vmcnt(8)
	s_setprio 1
	s_barrier
	v_mfma_f32_16x16x32_bf16 v[52:55], v[202:205], v[166:169], v[52:55]
	v_mfma_f32_16x16x32_bf16 v[48:51], v[210:213], v[166:169], v[48:51]
	v_mfma_f32_16x16x32_bf16 v[36:39], v[202:205], v[174:177], v[36:39]
	v_mfma_f32_16x16x32_bf16 v[32:35], v[210:213], v[174:177], v[32:35]
	v_mfma_f32_16x16x32_bf16 v[20:23], v[202:205], v[182:185], v[20:23]
	v_mfma_f32_16x16x32_bf16 v[16:19], v[210:213], v[182:185], v[16:19]
	v_mfma_f32_16x16x32_bf16 v[4:7], v[202:205], v[190:193], v[4:7]
	v_mfma_f32_16x16x32_bf16 v[0:3], v[210:213], v[190:193], v[0:3]
	v_mfma_f32_16x16x32_bf16 v[52:55], v[206:209], v[170:173], v[52:55]
	v_mfma_f32_16x16x32_bf16 v[48:51], v[214:217], v[170:173], v[48:51]
	v_mfma_f32_16x16x32_bf16 v[36:39], v[206:209], v[178:181], v[36:39]
	v_mfma_f32_16x16x32_bf16 v[32:35], v[214:217], v[178:181], v[32:35]
	v_mfma_f32_16x16x32_bf16 v[20:23], v[206:209], v[186:189], v[20:23]
	v_mfma_f32_16x16x32_bf16 v[16:19], v[214:217], v[186:189], v[16:19]
	v_mfma_f32_16x16x32_bf16 v[4:7], v[206:209], v[194:197], v[4:7]
	v_mfma_f32_16x16x32_bf16 v[0:3], v[214:217], v[194:197], v[0:3]
	s_setprio 0
	s_add_i32 s48, s48, 2
	s_add_u32 s14, s14, 0x100
	s_addc_u32 s15, s15, 0
	s_add_u32 s46, s46, 0x100
	s_addc_u32 s47, s47, 0
	s_cmp_gt_u32 s48, 13
	s_cbranch_scc1 .Lconc_last_g0
	s_barrier
	s_branch .LBB0_235

; #define PG8_STAGE(bufoff, gbase, voff) do { _Pragma("unroll") for (int _i = 0; _i < 2; ++_i) \
;         __builtin_amdgcn_global_load_lds((const unsigned*)((const char*)(gbase) + (voff)[_i]), (LAS unsigned*)(lds + (bufoff) + ldsw + _i * 8192), 16, 0, 0); } while (0)
; #define PG8_LDA(dst, b, h) do { _Pragma("unroll") for (int m = 0; m < 4; ++m) _Pragma("unroll") for (int k = 0; k < 2; ++k) dst[m][k] = *(const LAS bf16x8*)(lds + PG8_SA(b, h) + aoff + m * 2048 + k * 1024); } while (0)
; #define PG8_LDB(dst, b, h) do { _Pragma("unroll") for (int n = 0; n < 2; ++n) _Pragma("unroll") for (int k = 0; k < 2; ++k) dst[n][k] = *(const LAS bf16x8*)(lds + PG8_SB(b, h) + boff + n * 2048 + k * 1024); } while (0)
; #define PG8_WAIT_V(n) asm volatile("s_waitcnt vmcnt(" #n ")" ::: "memory")
; #define PG8_WAIT_L(n) asm volatile("s_waitcnt lgkmcnt(" #n ")" ::: "memory")
; #define PG8_BAR __builtin_amdgcn_s_barrier()
; #define PG8_SCHED __builtin_amdgcn_sched_barrier(0)
; template <class Epi, class Sched>
; __device__ __forceinline__ void gemm_phase(LAS unsigned char* lds, const Gemm g, const Sched& S, const Epi& E) {
;     ...
;         const bool has_next = S.next(ui + 1, nxt);
;         const char* nA = has_next ? (const char*)g.A + (size_t)nxt.pm * tstep : cA; const char* nB = has_next ? (const char*)g.Bt + (size_t)nxt.pn * tstep : cB;
;         for (int t = 0; t < nt; t += 2) {
;             const bool last = (t == nt - 2);
;             const char* a1 = cA + (size_t)(t + 1) * kstep;
;             const char* a2 = last ? nA : cA + (size_t)(t + 2) * kstep; const char* b2 = last ? nB : cB + (size_t)(t + 2) * kstep;
;             const char* a3 = a2 + kstep; const char* b3 = b2 + kstep;
;             PG8_LDB(B0, 0, 0); PG8_SCHED; PG8_LDA(At, 0, 0); PG8_STAGE(PG8_SA(1, 1), a1 + hstep, voffA);
;             PG8_WAIT_L(8); PG8_BAR; PG8_WAIT_L(0); PG8_MMA(0, 0, At, B0); PG8_BAR; PG8_SCHED;
;             PG8_LDB(B1, 0, 1); PG8_STAGE(PG8_SB(0, 0), b2, voffB);
;             PG8_BAR; PG8_WAIT_L(0); PG8_MMA(0, 1, At, B1); PG8_BAR;
;             PG8_LDA(At, 0, 1); PG8_STAGE(PG8_SA(0, 0), a2, voffA);
;             PG8_BAR; PG8_WAIT_L(0); PG8_MMA(1, 0, At, B0); PG8_BAR; PG8_SCHED;
;             PG8_STAGE(PG8_SB(0, 1), b2 + hstep, voffB);
;             PG8_WAIT_V(6); PG8_BAR; PG8_MMA(1, 1, At, B1); PG8_BAR;
.LBB0_304:
	s_add_u32 s0, s28, 0x100
	s_addc_u32 s67, s29, 0
	s_mov_b32 s68, -2
	ds_read_b128 v[144:147], v165
	ds_read_b128 v[148:151], v165 offset:1024
	ds_read_b128 v[152:155], v165 offset:2048
	ds_read_b128 v[156:159], v165 offset:3072
	s_add_u32 s28, s26, 0x100
	s_addc_u32 s29, s27, 0
	s_cmp_eq_u32 s68, 40
	s_cselect_b32 s37, s5, s29
	s_cselect_b32 s36, s4, s28
	s_cselect_b32 s35, s7, s67
	s_cselect_b32 s34, s6, s0
	v_lshl_add_u64 v[160:161], s[26:27], 0, v[136:137]
	s_add_i32 m0, s42, 0xc000
	ds_read_b128 v[168:171], v166
	ds_read_b128 v[172:175], v166 offset:1024
	ds_read_b128 v[176:179], v166 offset:2048
	ds_read_b128 v[180:183], v166 offset:3072
	ds_read_b128 v[184:187], v166 offset:4096
	ds_read_b128 v[188:191], v166 offset:5120
	ds_read_b128 v[192:195], v166 offset:6144
	ds_read_b128 v[196:199], v166 offset:7168
	global_load_lds_dwordx4 v[160:161], off
	v_lshl_add_u64 v[160:161], s[26:27], 0, v[138:139]
	s_add_i32 m0, s42, 0xe000
	s_nop 0
	global_load_lds_dwordx4 v[160:161], off
	s_waitcnt lgkmcnt(8)
	s_waitcnt vmcnt(8)
	s_setprio 1
	s_barrier
	s_waitcnt lgkmcnt(0)
	v_mfma_f32_16x16x32_bf16 v[124:127], v[144:147], v[168:171], 0
	v_mfma_f32_16x16x32_bf16 v[120:123], v[152:155], v[168:171], 0
	v_mfma_f32_16x16x32_bf16 v[116:119], v[144:147], v[176:179], 0
	v_mfma_f32_16x16x32_bf16 v[104:107], v[152:155], v[176:179], 0
	v_mfma_f32_16x16x32_bf16 v[96:99], v[144:147], v[184:187], 0
	v_mfma_f32_16x16x32_bf16 v[88:91], v[152:155], v[184:187], 0
	v_mfma_f32_16x16x32_bf16 v[80:83], v[144:147], v[192:195], 0
	v_mfma_f32_16x16x32_bf16 v[72:75], v[152:155], v[192:195], 0
	v_mfma_f32_16x16x32_bf16 v[124:127], v[148:151], v[172:175], v[124:127]
	v_mfma_f32_16x16x32_bf16 v[120:123], v[156:159], v[172:175], v[120:123]
	v_mfma_f32_16x16x32_bf16 v[116:119], v[148:151], v[180:183], v[116:119]
	v_mfma_f32_16x16x32_bf16 v[104:107], v[156:159], v[180:183], v[104:107]
	v_mfma_f32_16x16x32_bf16 v[96:99], v[148:151], v[188:191], v[96:99]
	v_mfma_f32_16x16x32_bf16 v[88:91], v[156:159], v[188:191], v[88:91]
	v_mfma_f32_16x16x32_bf16 v[80:83], v[148:151], v[196:199], v[80:83]
	v_mfma_f32_16x16x32_bf16 v[72:75], v[156:159], v[196:199], v[72:75]
	s_setprio 0
	s_barrier
	s_add_i32 s16, s58, s40
	s_mov_b32 m0, s16
	ds_read_b128 v[202:205], v167
	ds_read_b128 v[206:209], v167 offset:1024
	ds_read_b128 v[210:213], v167 offset:2048
	ds_read_b128 v[214:217], v167 offset:3072
	global_load_lds_dwordx4 v132, s[34:35]
	s_add_i32 m0, s16, 0x2000
	s_nop 0
	global_load_lds_dwordx4 v128, s[34:35]
	s_waitcnt vmcnt(8)
	s_setprio 1
	s_barrier
	s_waitcnt lgkmcnt(0)
	v_mfma_f32_16x16x32_bf16 v[112:115], v[202:205], v[168:171], 0
	v_mfma_f32_16x16x32_bf16 v[108:111], v[210:213], v[168:171], 0
	v_mfma_f32_16x16x32_bf16 v[100:103], v[202:205], v[176:179], 0
	v_mfma_f32_16x16x32_bf16 v[92:95], v[210:213], v[176:179], 0
	v_mfma_f32_16x16x32_bf16 v[84:87], v[202:205], v[184:187], 0
	v_mfma_f32_16x16x32_bf16 v[76:79], v[210:213], v[184:187], 0
	v_mfma_f32_16x16x32_bf16 v[68:71], v[202:205], v[192:195], 0
	v_mfma_f32_16x16x32_bf16 v[64:67], v[210:213], v[192:195], 0
	v_mfma_f32_16x16x32_bf16 v[112:115], v[206:209], v[172:175], v[112:115]
	v_mfma_f32_16x16x32_bf16 v[108:111], v[214:217], v[172:175], v[108:111]
	v_mfma_f32_16x16x32_bf16 v[100:103], v[206:209], v[180:183], v[100:103]
	v_mfma_f32_16x16x32_bf16 v[92:95], v[214:217], v[180:183], v[92:95]
	v_mfma_f32_16x16x32_bf16 v[84:87], v[206:209], v[188:191], v[84:87]
	v_mfma_f32_16x16x32_bf16 v[76:79], v[214:217], v[188:191], v[76:79]
	v_mfma_f32_16x16x32_bf16 v[68:71], v[206:209], v[196:199], v[68:71]
	v_mfma_f32_16x16x32_bf16 v[64:67], v[214:217], v[196:199], v[64:67]
	s_setprio 0
	s_mov_b32 m0, s42
	s_barrier
	ds_read_b128 v[168:171], v166 offset:16384
	ds_read_b128 v[172:175], v166 offset:17408
	ds_read_b128 v[176:179], v166 offset:18432
	ds_read_b128 v[180:183], v166 offset:19456
	ds_read_b128 v[184:187], v166 offset:20480
	ds_read_b128 v[188:191], v166 offset:21504
	ds_read_b128 v[192:195], v166 offset:22528
	ds_read_b128 v[196:199], v166 offset:23552
	global_load_lds_dwordx4 v134, s[36:37]
	s_mov_b32 m0, s43
	s_nop 0
	global_load_lds_dwordx4 v130, s[36:37]
	s_setprio 1
	s_barrier
	s_waitcnt lgkmcnt(0)
	v_mfma_f32_16x16x32_bf16 v[60:63], v[144:147], v[168:171], 0
	v_mfma_f32_16x16x32_bf16 v[56:59], v[152:155], v[168:171], 0
	v_mfma_f32_16x16x32_bf16 v[48:51], v[144:147], v[176:179], 0
	v_mfma_f32_16x16x32_bf16 v[40:43], v[152:155], v[176:179], 0
	v_mfma_f32_16x16x32_bf16 v[32:35], v[144:147], v[184:187], 0
	v_mfma_f32_16x16x32_bf16 v[24:27], v[152:155], v[184:187], 0
	v_mfma_f32_16x16x32_bf16 v[16:19], v[144:147], v[192:195], 0
	v_mfma_f32_16x16x32_bf16 v[8:11], v[152:155], v[192:195], 0
	v_mfma_f32_16x16x32_bf16 v[60:63], v[148:151], v[172:175], v[60:63]
	v_mfma_f32_16x16x32_bf16 v[56:59], v[156:159], v[172:175], v[56:59]
	v_mfma_f32_16x16x32_bf16 v[48:51], v[148:151], v[180:183], v[48:51]
	v_mfma_f32_16x16x32_bf16 v[40:43], v[156:159], v[180:183], v[40:43]
	v_mfma_f32_16x16x32_bf16 v[32:35], v[148:151], v[188:191], v[32:35]
	v_mfma_f32_16x16x32_bf16 v[24:27], v[156:159], v[188:191], v[24:27]
	v_mfma_f32_16x16x32_bf16 v[16:19], v[148:151], v[196:199], v[16:19]
	v_mfma_f32_16x16x32_bf16 v[8:11], v[156:159], v[196:199], v[8:11]
	s_setprio 0
	s_barrier
	s_add_u32 s16, s34, 0xb0000
	s_addc_u32 s17, s35, 0
	s_add_i32 s20, s59, s40
	s_mov_b32 m0, s20
	s_nop 0
	global_load_lds_dwordx4 v132, s[16:17]
	s_add_i32 m0, s20, 0x2000
	s_nop 0
	global_load_lds_dwordx4 v128, s[16:17]
	s_add_u32 s16, s36, 0xb0000
	s_addc_u32 s17, s37, 0
	s_mov_b32 m0, s44
	s_nop 0
	global_load_lds_dwordx4 v134, s[16:17]
	s_mov_b32 m0, s45
	s_nop 0
	global_load_lds_dwordx4 v130, s[16:17]
	s_waitcnt vmcnt(10)
	s_setprio 1
	s_barrier
; #define PG8_STAGE(bufoff, gbase, voff) do { _Pragma("unroll") for (int _i = 0; _i < 2; ++_i) \
;         __builtin_amdgcn_global_load_lds((const unsigned*)((const char*)(gbase) + (voff)[_i]), (LAS unsigned*)(lds + (bufoff) + ldsw + _i * 8192), 16, 0, 0); } while (0)
; #define PG8_LDA(dst, b, h) do { _Pragma("unroll") for (int m = 0; m < 4; ++m) _Pragma("unroll") for (int k = 0; k < 2; ++k) dst[m][k] = *(const LAS bf16x8*)(lds + PG8_SA(b, h) + aoff + m * 2048 + k * 1024); } while (0)
; #define PG8_LDB(dst, b, h) do { _Pragma("unroll") for (int n = 0; n < 2; ++n) _Pragma("unroll") for (int k = 0; k < 2; ++k) dst[n][k] = *(const LAS bf16x8*)(lds + PG8_SB(b, h) + boff + n * 2048 + k * 1024); } while (0)
; #define PG8_MMA(ai, bj, At, Bt) do { __builtin_amdgcn_s_setprio(1); _Pragma("unroll") for (int m = 0; m < 4; ++m) _Pragma("unroll") for (int n = 0; n < 2; ++n) _Pragma("unroll") for (int k = 0; k < 2; ++k) \
;         acc[ai][bj][m][n] = __builtin_amdgcn_mfma_f32_16x16x32_bf16(Bt[n][k], At[m][k], acc[ai][bj][m][n], 0, 0, 0); __builtin_amdgcn_s_setprio(0); } while (0)
; #define PG8_WAIT_V(n) asm volatile("s_waitcnt vmcnt(" #n ")" ::: "memory")
; #define PG8_WAIT_L(n) asm volatile("s_waitcnt lgkmcnt(" #n ")" ::: "memory")
; #define PG8_BAR __builtin_amdgcn_s_barrier()
; #define PG8_SCHED __builtin_amdgcn_sched_barrier(0)
; template <class Epi, class Sched>
; __device__ __forceinline__ void gemm_phase(LAS unsigned char* lds, const Gemm g, const Sched& S, const Epi& E) {
;     ...
;             PG8_WAIT_V(6); PG8_BAR; PG8_MMA(1, 1, At, B1); PG8_BAR;
;             PG8_LDB(B0, 1, 0); PG8_SCHED; PG8_LDA(At, 1, 0); PG8_STAGE(PG8_SA(0, 1), a2 + hstep, voffA);
;             PG8_WAIT_L(8); PG8_BAR; PG8_WAIT_L(0); PG8_MMA(0, 0, At, B0); PG8_BAR; PG8_SCHED;
;             PG8_LDB(B1, 1, 1); PG8_STAGE(PG8_SB(1, 0), b3, voffB);
;             PG8_BAR; PG8_WAIT_L(0); PG8_MMA(0, 1, At, B1); PG8_BAR;
;             PG8_LDA(At, 1, 1); PG8_STAGE(PG8_SA(1, 0), a3, voffA);
;             PG8_BAR; PG8_WAIT_L(0); PG8_MMA(1, 0, At, B0); PG8_BAR; PG8_SCHED;
	v_mfma_f32_16x16x32_bf16 v[52:55], v[202:205], v[168:171], 0
	v_mfma_f32_16x16x32_bf16 v[44:47], v[210:213], v[168:171], 0
	v_mfma_f32_16x16x32_bf16 v[36:39], v[202:205], v[176:179], 0
	v_mfma_f32_16x16x32_bf16 v[28:31], v[210:213], v[176:179], 0
	v_mfma_f32_16x16x32_bf16 v[20:23], v[202:205], v[184:187], 0
	v_mfma_f32_16x16x32_bf16 v[12:15], v[210:213], v[184:187], 0
	v_mfma_f32_16x16x32_bf16 v[4:7], v[202:205], v[192:195], 0
	v_mfma_f32_16x16x32_bf16 v[0:3], v[210:213], v[192:195], 0
	v_mfma_f32_16x16x32_bf16 v[52:55], v[206:209], v[172:175], v[52:55]
	v_mfma_f32_16x16x32_bf16 v[44:47], v[214:217], v[172:175], v[44:47]
	v_mfma_f32_16x16x32_bf16 v[36:39], v[206:209], v[180:183], v[36:39]
	v_mfma_f32_16x16x32_bf16 v[28:31], v[214:217], v[180:183], v[28:31]
	v_mfma_f32_16x16x32_bf16 v[20:23], v[206:209], v[188:191], v[20:23]
	v_mfma_f32_16x16x32_bf16 v[12:15], v[214:217], v[188:191], v[12:15]
	v_mfma_f32_16x16x32_bf16 v[4:7], v[206:209], v[196:199], v[4:7]
	v_mfma_f32_16x16x32_bf16 v[0:3], v[214:217], v[196:199], v[0:3]
	s_setprio 0
	s_add_i32 s20, 0, 0x18000
	v_add_u32_e32 v156, s20, v164
	s_barrier
	ds_read_b128 v[144:147], v156
	ds_read_b128 v[148:151], v156 offset:1024
	ds_read_b128 v[152:155], v156 offset:2048
	ds_read_b128 v[156:159], v156 offset:3072
	ds_read_b128 v[168:171], v166 offset:32768
	ds_read_b128 v[172:175], v166 offset:33792
	ds_read_b128 v[176:179], v166 offset:34816
	ds_read_b128 v[180:183], v166 offset:35840
	ds_read_b128 v[184:187], v166 offset:36864
	ds_read_b128 v[188:191], v166 offset:37888
	ds_read_b128 v[192:195], v166 offset:38912
	ds_read_b128 v[196:199], v166 offset:39936
	s_waitcnt lgkmcnt(8)
	s_waitcnt vmcnt(8)
	s_setprio 1
	s_barrier
	s_waitcnt lgkmcnt(0)
	v_mfma_f32_16x16x32_bf16 v[124:127], v[144:147], v[168:171], v[124:127]
	v_mfma_f32_16x16x32_bf16 v[120:123], v[152:155], v[168:171], v[120:123]
	v_mfma_f32_16x16x32_bf16 v[116:119], v[144:147], v[176:179], v[116:119]
	v_mfma_f32_16x16x32_bf16 v[104:107], v[152:155], v[176:179], v[104:107]
	v_mfma_f32_16x16x32_bf16 v[96:99], v[144:147], v[184:187], v[96:99]
	v_mfma_f32_16x16x32_bf16 v[88:91], v[152:155], v[184:187], v[88:91]
	v_mfma_f32_16x16x32_bf16 v[80:83], v[144:147], v[192:195], v[80:83]
	v_mfma_f32_16x16x32_bf16 v[72:75], v[152:155], v[192:195], v[72:75]
	v_mfma_f32_16x16x32_bf16 v[124:127], v[148:151], v[172:175], v[124:127]
	v_mfma_f32_16x16x32_bf16 v[120:123], v[156:159], v[172:175], v[120:123]
	v_mfma_f32_16x16x32_bf16 v[116:119], v[148:151], v[180:183], v[116:119]
	v_mfma_f32_16x16x32_bf16 v[104:107], v[156:159], v[180:183], v[104:107]
	v_mfma_f32_16x16x32_bf16 v[96:99], v[148:151], v[188:191], v[96:99]
	v_mfma_f32_16x16x32_bf16 v[88:91], v[156:159], v[188:191], v[88:91]
	v_mfma_f32_16x16x32_bf16 v[80:83], v[148:151], v[196:199], v[80:83]
	v_mfma_f32_16x16x32_bf16 v[72:75], v[156:159], v[196:199], v[72:75]
	s_setprio 0
	s_barrier
	s_add_i32 s21, 0, 0x1c000
	s_add_i32 s16, s20, s40
	v_add_u32_e32 v214, s21, v164
	s_add_u32 s8, s34, 0x80
	s_addc_u32 s9, s35, 0
	s_mov_b32 m0, s16
	ds_read_b128 v[202:205], v214
	ds_read_b128 v[206:209], v214 offset:1024
	ds_read_b128 v[210:213], v214 offset:2048
	ds_read_b128 v[214:217], v214 offset:3072
	global_load_lds_dwordx4 v132, s[8:9]
	s_add_i32 m0, s16, 0x2000
	s_nop 0
	global_load_lds_dwordx4 v128, s[8:9]
	s_waitcnt vmcnt(8)
	s_setprio 1
	s_barrier
	s_waitcnt lgkmcnt(0)
	v_mfma_f32_16x16x32_bf16 v[112:115], v[202:205], v[168:171], v[112:115]
	v_mfma_f32_16x16x32_bf16 v[108:111], v[210:213], v[168:171], v[108:111]
	v_mfma_f32_16x16x32_bf16 v[100:103], v[202:205], v[176:179], v[100:103]
	v_mfma_f32_16x16x32_bf16 v[92:95], v[210:213], v[176:179], v[92:95]
	v_mfma_f32_16x16x32_bf16 v[84:87], v[202:205], v[184:187], v[84:87]
	v_mfma_f32_16x16x32_bf16 v[76:79], v[210:213], v[184:187], v[76:79]
	v_mfma_f32_16x16x32_bf16 v[68:71], v[202:205], v[192:195], v[68:71]
	v_mfma_f32_16x16x32_bf16 v[64:67], v[210:213], v[192:195], v[64:67]
	v_mfma_f32_16x16x32_bf16 v[112:115], v[206:209], v[172:175], v[112:115]
	v_mfma_f32_16x16x32_bf16 v[108:111], v[214:217], v[172:175], v[108:111]
	v_mfma_f32_16x16x32_bf16 v[100:103], v[206:209], v[180:183], v[100:103]
	v_mfma_f32_16x16x32_bf16 v[92:95], v[214:217], v[180:183], v[92:95]
	v_mfma_f32_16x16x32_bf16 v[84:87], v[206:209], v[188:191], v[84:87]
	v_mfma_f32_16x16x32_bf16 v[76:79], v[214:217], v[188:191], v[76:79]
	v_mfma_f32_16x16x32_bf16 v[68:71], v[206:209], v[196:199], v[68:71]
	v_mfma_f32_16x16x32_bf16 v[64:67], v[214:217], v[196:199], v[64:67]
	s_setprio 0
	s_mov_b32 m0, s52
	s_add_u32 s8, s36, 0x80
	s_addc_u32 s9, s37, 0
	s_barrier
	ds_read_b128 v[168:171], v166 offset:49152
	ds_read_b128 v[172:175], v166 offset:50176
	ds_read_b128 v[176:179], v166 offset:51200
	ds_read_b128 v[180:183], v166 offset:52224
	ds_read_b128 v[184:187], v166 offset:53248
	ds_read_b128 v[188:191], v166 offset:54272
	ds_read_b128 v[192:195], v166 offset:55296
	ds_read_b128 v[196:199], v166 offset:56320
	global_load_lds_dwordx4 v134, s[8:9]
	s_mov_b32 m0, s53
	s_nop 0
	global_load_lds_dwordx4 v130, s[8:9]
	s_setprio 1
	s_barrier
	s_waitcnt lgkmcnt(0)
	v_mfma_f32_16x16x32_bf16 v[60:63], v[144:147], v[168:171], v[60:63]
	v_mfma_f32_16x16x32_bf16 v[56:59], v[152:155], v[168:171], v[56:59]
	v_mfma_f32_16x16x32_bf16 v[48:51], v[144:147], v[176:179], v[48:51]
	v_mfma_f32_16x16x32_bf16 v[40:43], v[152:155], v[176:179], v[40:43]
	v_mfma_f32_16x16x32_bf16 v[32:35], v[144:147], v[184:187], v[32:35]
	v_mfma_f32_16x16x32_bf16 v[24:27], v[152:155], v[184:187], v[24:27]
	v_mfma_f32_16x16x32_bf16 v[16:19], v[144:147], v[192:195], v[16:19]
	v_mfma_f32_16x16x32_bf16 v[8:11], v[152:155], v[192:195], v[8:11]
	v_mfma_f32_16x16x32_bf16 v[60:63], v[148:151], v[172:175], v[60:63]
	v_mfma_f32_16x16x32_bf16 v[56:59], v[156:159], v[172:175], v[56:59]
	v_mfma_f32_16x16x32_bf16 v[48:51], v[148:151], v[180:183], v[48:51]
	v_mfma_f32_16x16x32_bf16 v[40:43], v[156:159], v[180:183], v[40:43]
	v_mfma_f32_16x16x32_bf16 v[32:35], v[148:151], v[188:191], v[32:35]
	v_mfma_f32_16x16x32_bf16 v[24:27], v[156:159], v[188:191], v[24:27]
	v_mfma_f32_16x16x32_bf16 v[16:19], v[148:151], v[196:199], v[16:19]
	v_mfma_f32_16x16x32_bf16 v[8:11], v[156:159], v[196:199], v[8:11]
	s_setprio 0
	s_barrier
; #define PG8_STAGE(bufoff, gbase, voff) do { _Pragma("unroll") for (int _i = 0; _i < 2; ++_i) \
;         __builtin_amdgcn_global_load_lds((const unsigned*)((const char*)(gbase) + (voff)[_i]), (LAS unsigned*)(lds + (bufoff) + ldsw + _i * 8192), 16, 0, 0); } while (0)
; #define PG8_LDA(dst, b, h) do { _Pragma("unroll") for (int m = 0; m < 4; ++m) _Pragma("unroll") for (int k = 0; k < 2; ++k) dst[m][k] = *(const LAS bf16x8*)(lds + PG8_SA(b, h) + aoff + m * 2048 + k * 1024); } while (0)
; #define PG8_LDB(dst, b, h) do { _Pragma("unroll") for (int n = 0; n < 2; ++n) _Pragma("unroll") for (int k = 0; k < 2; ++k) dst[n][k] = *(const LAS bf16x8*)(lds + PG8_SB(b, h) + boff + n * 2048 + k * 1024); } while (0)
; #define PG8_MMA(ai, bj, At, Bt) do { __builtin_amdgcn_s_setprio(1); _Pragma("unroll") for (int m = 0; m < 4; ++m) _Pragma("unroll") for (int n = 0; n < 2; ++n) _Pragma("unroll") for (int k = 0; k < 2; ++k) \
;         acc[ai][bj][m][n] = __builtin_amdgcn_mfma_f32_16x16x32_bf16(Bt[n][k], At[m][k], acc[ai][bj][m][n], 0, 0, 0); __builtin_amdgcn_s_setprio(0); } while (0)
; #define PG8_WAIT_V(n) asm volatile("s_waitcnt vmcnt(" #n ")" ::: "memory")
; #define PG8_WAIT_L(n) asm volatile("s_waitcnt lgkmcnt(" #n ")" ::: "memory")
; #define PG8_BAR __builtin_amdgcn_s_barrier()
; #define PG8_SCHED __builtin_amdgcn_sched_barrier(0)
; template <class Epi, class Sched>
; __device__ __forceinline__ void gemm_phase(LAS unsigned char* lds, const Gemm g, const Sched& S, const Epi& E) {
;     ...
;         for (int t = 0; t < nt; t += 2) {
;             const bool last = (t == nt - 2);
;             const char* a1 = cA + (size_t)(t + 1) * kstep;
;             const char* a2 = last ? nA : cA + (size_t)(t + 2) * kstep; const char* b2 = last ? nB : cB + (size_t)(t + 2) * kstep;
;             const char* a3 = a2 + kstep; const char* b3 = b2 + kstep;
;             PG8_LDB(B0, 0, 0); PG8_SCHED; PG8_LDA(At, 0, 0); PG8_STAGE(PG8_SA(1, 1), a1 + hstep, voffA);
;             PG8_WAIT_L(8); PG8_BAR; PG8_WAIT_L(0); PG8_MMA(0, 0, At, B0); PG8_BAR; PG8_SCHED;
;             PG8_LDB(B1, 0, 1); PG8_STAGE(PG8_SB(0, 0), b2, voffB);
;             PG8_BAR; PG8_WAIT_L(0); PG8_MMA(0, 1, At, B1); PG8_BAR;
;             PG8_LDA(At, 0, 1); PG8_STAGE(PG8_SA(0, 0), a2, voffA);
;     ...
;             PG8_STAGE(PG8_SB(1, 1), b3 + hstep, voffB);
;             PG8_WAIT_V(6); PG8_BAR; PG8_MMA(1, 1, At, B1); PG8_BAR;
	s_add_u32 s16, s34, 0xb0080
	s_addc_u32 s17, s35, 0
	s_add_i32 s20, s21, s40
	s_mov_b32 m0, s20
	s_nop 0
	global_load_lds_dwordx4 v132, s[16:17]
	s_add_i32 m0, s20, 0x2000
	s_nop 0
	global_load_lds_dwordx4 v128, s[16:17]
	s_waitcnt vmcnt(8)
	s_setprio 1
	s_barrier
	v_mfma_f32_16x16x32_bf16 v[52:55], v[202:205], v[168:171], v[52:55]
	v_mfma_f32_16x16x32_bf16 v[44:47], v[210:213], v[168:171], v[44:47]
	v_mfma_f32_16x16x32_bf16 v[36:39], v[202:205], v[176:179], v[36:39]
	v_mfma_f32_16x16x32_bf16 v[28:31], v[210:213], v[176:179], v[28:31]
	v_mfma_f32_16x16x32_bf16 v[20:23], v[202:205], v[184:187], v[20:23]
	v_mfma_f32_16x16x32_bf16 v[12:15], v[210:213], v[184:187], v[12:15]
	v_mfma_f32_16x16x32_bf16 v[4:7], v[202:205], v[192:195], v[4:7]
	v_mfma_f32_16x16x32_bf16 v[0:3], v[210:213], v[192:195], v[0:3]
	v_mfma_f32_16x16x32_bf16 v[52:55], v[206:209], v[172:175], v[52:55]
	v_mfma_f32_16x16x32_bf16 v[44:47], v[214:217], v[172:175], v[44:47]
	v_mfma_f32_16x16x32_bf16 v[36:39], v[206:209], v[180:183], v[36:39]
	v_mfma_f32_16x16x32_bf16 v[28:31], v[214:217], v[180:183], v[28:31]
	v_mfma_f32_16x16x32_bf16 v[20:23], v[206:209], v[188:191], v[20:23]
	v_mfma_f32_16x16x32_bf16 v[12:15], v[214:217], v[188:191], v[12:15]
	v_mfma_f32_16x16x32_bf16 v[4:7], v[206:209], v[196:199], v[4:7]
	v_mfma_f32_16x16x32_bf16 v[0:3], v[214:217], v[196:199], v[0:3]
	s_setprio 0
	s_add_i32 s68, s68, 2
	s_add_u32 s0, s0, 0x100
	s_addc_u32 s67, s67, 0
	s_cmp_gt_u32 s68, 41
	s_mov_b64 s[26:27], s[28:29]
	s_barrier
.LBB0_305:
	ds_read_b128 v[144:147], v165
	ds_read_b128 v[148:151], v165 offset:1024
	ds_read_b128 v[152:155], v165 offset:2048
	ds_read_b128 v[156:159], v165 offset:3072
	s_add_u32 s28, s26, 0x100
	s_addc_u32 s29, s27, 0
	s_cmp_eq_u32 s68, 40
	s_cselect_b32 s37, s5, s29
	s_cselect_b32 s36, s4, s28
	s_cselect_b32 s35, s7, s67
	s_cselect_b32 s34, s6, s0
	v_lshl_add_u64 v[160:161], s[26:27], 0, v[136:137]
	s_add_i32 m0, s42, 0xc000
	ds_read_b128 v[168:171], v166
	ds_read_b128 v[172:175], v166 offset:1024
	ds_read_b128 v[176:179], v166 offset:2048
	ds_read_b128 v[180:183], v166 offset:3072
	ds_read_b128 v[184:187], v166 offset:4096
	ds_read_b128 v[188:191], v166 offset:5120
	ds_read_b128 v[192:195], v166 offset:6144
	ds_read_b128 v[196:199], v166 offset:7168
	global_load_lds_dwordx4 v[160:161], off
	v_lshl_add_u64 v[160:161], s[26:27], 0, v[138:139]
	s_add_i32 m0, s42, 0xe000
	s_nop 0
	global_load_lds_dwordx4 v[160:161], off
	s_waitcnt lgkmcnt(8)
	s_waitcnt vmcnt(8)
	s_setprio 1
	s_barrier
	s_waitcnt lgkmcnt(0)
	v_mfma_f32_16x16x32_bf16 v[124:127], v[144:147], v[168:171], v[124:127]
	v_mfma_f32_16x16x32_bf16 v[120:123], v[152:155], v[168:171], v[120:123]
	v_mfma_f32_16x16x32_bf16 v[116:119], v[144:147], v[176:179], v[116:119]
	v_mfma_f32_16x16x32_bf16 v[104:107], v[152:155], v[176:179], v[104:107]
	v_mfma_f32_16x16x32_bf16 v[96:99], v[144:147], v[184:187], v[96:99]
	v_mfma_f32_16x16x32_bf16 v[88:91], v[152:155], v[184:187], v[88:91]
	v_mfma_f32_16x16x32_bf16 v[80:83], v[144:147], v[192:195], v[80:83]
	v_mfma_f32_16x16x32_bf16 v[72:75], v[152:155], v[192:195], v[72:75]
	v_mfma_f32_16x16x32_bf16 v[124:127], v[148:151], v[172:175], v[124:127]
	v_mfma_f32_16x16x32_bf16 v[120:123], v[156:159], v[172:175], v[120:123]
	v_mfma_f32_16x16x32_bf16 v[116:119], v[148:151], v[180:183], v[116:119]
	v_mfma_f32_16x16x32_bf16 v[104:107], v[156:159], v[180:183], v[104:107]
	v_mfma_f32_16x16x32_bf16 v[96:99], v[148:151], v[188:191], v[96:99]
	v_mfma_f32_16x16x32_bf16 v[88:91], v[156:159], v[188:191], v[88:91]
	v_mfma_f32_16x16x32_bf16 v[80:83], v[148:151], v[196:199], v[80:83]
	v_mfma_f32_16x16x32_bf16 v[72:75], v[156:159], v[196:199], v[72:75]
	s_setprio 0
	s_barrier
	s_add_i32 s16, s58, s40
	s_mov_b32 m0, s16
	ds_read_b128 v[202:205], v167
	ds_read_b128 v[206:209], v167 offset:1024
	ds_read_b128 v[210:213], v167 offset:2048
	ds_read_b128 v[214:217], v167 offset:3072
	global_load_lds_dwordx4 v132, s[34:35]
	s_add_i32 m0, s16, 0x2000
	s_nop 0
	global_load_lds_dwordx4 v128, s[34:35]
	s_waitcnt vmcnt(8)
	s_setprio 1
	s_barrier
	s_waitcnt lgkmcnt(0)
	v_mfma_f32_16x16x32_bf16 v[112:115], v[202:205], v[168:171], v[112:115]
	v_mfma_f32_16x16x32_bf16 v[108:111], v[210:213], v[168:171], v[108:111]
	v_mfma_f32_16x16x32_bf16 v[100:103], v[202:205], v[176:179], v[100:103]
	v_mfma_f32_16x16x32_bf16 v[92:95], v[210:213], v[176:179], v[92:95]
	v_mfma_f32_16x16x32_bf16 v[84:87], v[202:205], v[184:187], v[84:87]
	v_mfma_f32_16x16x32_bf16 v[76:79], v[210:213], v[184:187], v[76:79]
	v_mfma_f32_16x16x32_bf16 v[68:71], v[202:205], v[192:195], v[68:71]
	v_mfma_f32_16x16x32_bf16 v[64:67], v[210:213], v[192:195], v[64:67]
	v_mfma_f32_16x16x32_bf16 v[112:115], v[206:209], v[172:175], v[112:115]
	v_mfma_f32_16x16x32_bf16 v[108:111], v[214:217], v[172:175], v[108:111]
	v_mfma_f32_16x16x32_bf16 v[100:103], v[206:209], v[180:183], v[100:103]
	v_mfma_f32_16x16x32_bf16 v[92:95], v[214:217], v[180:183], v[92:95]
	v_mfma_f32_16x16x32_bf16 v[84:87], v[206:209], v[188:191], v[84:87]
	v_mfma_f32_16x16x32_bf16 v[76:79], v[214:217], v[188:191], v[76:79]
	v_mfma_f32_16x16x32_bf16 v[68:71], v[206:209], v[196:199], v[68:71]
	v_mfma_f32_16x16x32_bf16 v[64:67], v[214:217], v[196:199], v[64:67]
	s_setprio 0
	s_mov_b32 m0, s42
	s_barrier
	ds_read_b128 v[168:171], v166 offset:16384
	ds_read_b128 v[172:175], v166 offset:17408
	ds_read_b128 v[176:179], v166 offset:18432
	ds_read_b128 v[180:183], v166 offset:19456
	ds_read_b128 v[184:187], v166 offset:20480
	ds_read_b128 v[188:191], v166 offset:21504
	ds_read_b128 v[192:195], v166 offset:22528
	ds_read_b128 v[196:199], v166 offset:23552
	global_load_lds_dwordx4 v134, s[36:37]
	s_mov_b32 m0, s43
	s_nop 0
	global_load_lds_dwordx4 v130, s[36:37]
	s_setprio 1
	s_barrier
; #define PG8_STAGE(bufoff, gbase, voff) do { _Pragma("unroll") for (int _i = 0; _i < 2; ++_i) \
;         __builtin_amdgcn_global_load_lds((const unsigned*)((const char*)(gbase) + (voff)[_i]), (LAS unsigned*)(lds + (bufoff) + ldsw + _i * 8192), 16, 0, 0); } while (0)
; #define PG8_LDA(dst, b, h) do { _Pragma("unroll") for (int m = 0; m < 4; ++m) _Pragma("unroll") for (int k = 0; k < 2; ++k) dst[m][k] = *(const LAS bf16x8*)(lds + PG8_SA(b, h) + aoff + m * 2048 + k * 1024); } while (0)
; #define PG8_LDB(dst, b, h) do { _Pragma("unroll") for (int n = 0; n < 2; ++n) _Pragma("unroll") for (int k = 0; k < 2; ++k) dst[n][k] = *(const LAS bf16x8*)(lds + PG8_SB(b, h) + boff + n * 2048 + k * 1024); } while (0)
; #define PG8_MMA(ai, bj, At, Bt) do { __builtin_amdgcn_s_setprio(1); _Pragma("unroll") for (int m = 0; m < 4; ++m) _Pragma("unroll") for (int n = 0; n < 2; ++n) _Pragma("unroll") for (int k = 0; k < 2; ++k) \
;         acc[ai][bj][m][n] = __builtin_amdgcn_mfma_f32_16x16x32_bf16(Bt[n][k], At[m][k], acc[ai][bj][m][n], 0, 0, 0); __builtin_amdgcn_s_setprio(0); } while (0)
; #define PG8_WAIT_V(n) asm volatile("s_waitcnt vmcnt(" #n ")" ::: "memory")
; #define PG8_WAIT_L(n) asm volatile("s_waitcnt lgkmcnt(" #n ")" ::: "memory")
; #define PG8_BAR __builtin_amdgcn_s_barrier()
; #define PG8_SCHED __builtin_amdgcn_sched_barrier(0)
; template <class Epi, class Sched>
; __device__ __forceinline__ void gemm_phase(LAS unsigned char* lds, const Gemm g, const Sched& S, const Epi& E) {
;     ...
;             PG8_BAR; PG8_WAIT_L(0); PG8_MMA(0, 1, At, B1); PG8_BAR;
;             PG8_LDA(At, 0, 1); PG8_STAGE(PG8_SA(0, 0), a2, voffA);
;             PG8_BAR; PG8_WAIT_L(0); PG8_MMA(1, 0, At, B0); PG8_BAR; PG8_SCHED;
;             PG8_STAGE(PG8_SB(0, 1), b2 + hstep, voffB);
;             PG8_WAIT_V(6); PG8_BAR; PG8_MMA(1, 1, At, B1); PG8_BAR;
;             PG8_LDB(B0, 1, 0); PG8_SCHED; PG8_LDA(At, 1, 0); PG8_STAGE(PG8_SA(0, 1), a2 + hstep, voffA);
;             PG8_WAIT_L(8); PG8_BAR; PG8_WAIT_L(0); PG8_MMA(0, 0, At, B0); PG8_BAR; PG8_SCHED;
	s_waitcnt lgkmcnt(0)
	v_mfma_f32_16x16x32_bf16 v[60:63], v[144:147], v[168:171], v[60:63]
	v_mfma_f32_16x16x32_bf16 v[56:59], v[152:155], v[168:171], v[56:59]
	v_mfma_f32_16x16x32_bf16 v[48:51], v[144:147], v[176:179], v[48:51]
	v_mfma_f32_16x16x32_bf16 v[40:43], v[152:155], v[176:179], v[40:43]
	v_mfma_f32_16x16x32_bf16 v[32:35], v[144:147], v[184:187], v[32:35]
	v_mfma_f32_16x16x32_bf16 v[24:27], v[152:155], v[184:187], v[24:27]
	v_mfma_f32_16x16x32_bf16 v[16:19], v[144:147], v[192:195], v[16:19]
	v_mfma_f32_16x16x32_bf16 v[8:11], v[152:155], v[192:195], v[8:11]
	v_mfma_f32_16x16x32_bf16 v[60:63], v[148:151], v[172:175], v[60:63]
	v_mfma_f32_16x16x32_bf16 v[56:59], v[156:159], v[172:175], v[56:59]
	v_mfma_f32_16x16x32_bf16 v[48:51], v[148:151], v[180:183], v[48:51]
	v_mfma_f32_16x16x32_bf16 v[40:43], v[156:159], v[180:183], v[40:43]
	v_mfma_f32_16x16x32_bf16 v[32:35], v[148:151], v[188:191], v[32:35]
	v_mfma_f32_16x16x32_bf16 v[24:27], v[156:159], v[188:191], v[24:27]
	v_mfma_f32_16x16x32_bf16 v[16:19], v[148:151], v[196:199], v[16:19]
	v_mfma_f32_16x16x32_bf16 v[8:11], v[156:159], v[196:199], v[8:11]
	s_setprio 0
	s_barrier
	s_add_u32 s16, s34, 0xb0000
	s_addc_u32 s17, s35, 0
	s_add_i32 s20, s59, s40
	s_mov_b32 m0, s20
	s_nop 0
	global_load_lds_dwordx4 v132, s[16:17]
	s_add_i32 m0, s20, 0x2000
	s_nop 0
	global_load_lds_dwordx4 v128, s[16:17]
	s_add_u32 s16, s36, 0xb0000
	s_addc_u32 s17, s37, 0
	s_mov_b32 m0, s44
	s_nop 0
	global_load_lds_dwordx4 v134, s[16:17]
	s_mov_b32 m0, s45
	s_nop 0
	global_load_lds_dwordx4 v130, s[16:17]
	s_waitcnt vmcnt(10)
	s_setprio 1
	s_barrier
	v_mfma_f32_16x16x32_bf16 v[52:55], v[202:205], v[168:171], v[52:55]
	v_mfma_f32_16x16x32_bf16 v[44:47], v[210:213], v[168:171], v[44:47]
	v_mfma_f32_16x16x32_bf16 v[36:39], v[202:205], v[176:179], v[36:39]
	v_mfma_f32_16x16x32_bf16 v[28:31], v[210:213], v[176:179], v[28:31]
	v_mfma_f32_16x16x32_bf16 v[20:23], v[202:205], v[184:187], v[20:23]
	v_mfma_f32_16x16x32_bf16 v[12:15], v[210:213], v[184:187], v[12:15]
	v_mfma_f32_16x16x32_bf16 v[4:7], v[202:205], v[192:195], v[4:7]
	v_mfma_f32_16x16x32_bf16 v[0:3], v[210:213], v[192:195], v[0:3]
	v_mfma_f32_16x16x32_bf16 v[52:55], v[206:209], v[172:175], v[52:55]
	v_mfma_f32_16x16x32_bf16 v[44:47], v[214:217], v[172:175], v[44:47]
	v_mfma_f32_16x16x32_bf16 v[36:39], v[206:209], v[180:183], v[36:39]
	v_mfma_f32_16x16x32_bf16 v[28:31], v[214:217], v[180:183], v[28:31]
	v_mfma_f32_16x16x32_bf16 v[20:23], v[206:209], v[188:191], v[20:23]
	v_mfma_f32_16x16x32_bf16 v[12:15], v[214:217], v[188:191], v[12:15]
	v_mfma_f32_16x16x32_bf16 v[4:7], v[206:209], v[196:199], v[4:7]
	v_mfma_f32_16x16x32_bf16 v[0:3], v[214:217], v[196:199], v[0:3]
	s_setprio 0
	s_add_i32 s20, 0, 0x18000
	v_add_u32_e32 v156, s20, v164
	s_barrier
	ds_read_b128 v[144:147], v156
	ds_read_b128 v[148:151], v156 offset:1024
	ds_read_b128 v[152:155], v156 offset:2048
	ds_read_b128 v[156:159], v156 offset:3072
	ds_read_b128 v[168:171], v166 offset:32768
	ds_read_b128 v[172:175], v166 offset:33792
	ds_read_b128 v[176:179], v166 offset:34816
	ds_read_b128 v[180:183], v166 offset:35840
	ds_read_b128 v[184:187], v166 offset:36864
	ds_read_b128 v[188:191], v166 offset:37888
	ds_read_b128 v[192:195], v166 offset:38912
	ds_read_b128 v[196:199], v166 offset:39936
	s_waitcnt lgkmcnt(8)
	s_waitcnt vmcnt(8)
	s_setprio 1
	s_barrier
	s_waitcnt lgkmcnt(0)
	v_mfma_f32_16x16x32_bf16 v[124:127], v[144:147], v[168:171], v[124:127]
	v_mfma_f32_16x16x32_bf16 v[120:123], v[152:155], v[168:171], v[120:123]
	v_mfma_f32_16x16x32_bf16 v[116:119], v[144:147], v[176:179], v[116:119]
	v_mfma_f32_16x16x32_bf16 v[104:107], v[152:155], v[176:179], v[104:107]
	v_mfma_f32_16x16x32_bf16 v[96:99], v[144:147], v[184:187], v[96:99]
	v_mfma_f32_16x16x32_bf16 v[88:91], v[152:155], v[184:187], v[88:91]
	v_mfma_f32_16x16x32_bf16 v[80:83], v[144:147], v[192:195], v[80:83]
	v_mfma_f32_16x16x32_bf16 v[72:75], v[152:155], v[192:195], v[72:75]
	v_mfma_f32_16x16x32_bf16 v[124:127], v[148:151], v[172:175], v[124:127]
	v_mfma_f32_16x16x32_bf16 v[120:123], v[156:159], v[172:175], v[120:123]
	v_mfma_f32_16x16x32_bf16 v[116:119], v[148:151], v[180:183], v[116:119]
	v_mfma_f32_16x16x32_bf16 v[104:107], v[156:159], v[180:183], v[104:107]
	v_mfma_f32_16x16x32_bf16 v[96:99], v[148:151], v[188:191], v[96:99]
	v_mfma_f32_16x16x32_bf16 v[88:91], v[156:159], v[188:191], v[88:91]
	v_mfma_f32_16x16x32_bf16 v[80:83], v[148:151], v[196:199], v[80:83]
	v_mfma_f32_16x16x32_bf16 v[72:75], v[156:159], v[196:199], v[72:75]
	s_setprio 0
	s_barrier
	s_add_i32 s21, 0, 0x1c000
	s_add_i32 s16, s20, s40
	v_add_u32_e32 v214, s21, v164
	s_add_u32 s8, s34, 0x80
	s_addc_u32 s9, s35, 0
	s_mov_b32 m0, s16
	ds_read_b128 v[202:205], v214
	ds_read_b128 v[206:209], v214 offset:1024
	ds_read_b128 v[210:213], v214 offset:2048
	ds_read_b128 v[214:217], v214 offset:3072
	global_load_lds_dwordx4 v132, s[8:9]
	s_add_i32 m0, s16, 0x2000
	s_nop 0
	global_load_lds_dwordx4 v128, s[8:9]
	s_waitcnt vmcnt(8)
	s_setprio 1
	s_barrier
; #define PG8_STAGE(bufoff, gbase, voff) do { _Pragma("unroll") for (int _i = 0; _i < 2; ++_i) \
;         __builtin_amdgcn_global_load_lds((const unsigned*)((const char*)(gbase) + (voff)[_i]), (LAS unsigned*)(lds + (bufoff) + ldsw + _i * 8192), 16, 0, 0); } while (0)
; #define PG8_LDA(dst, b, h) do { _Pragma("unroll") for (int m = 0; m < 4; ++m) _Pragma("unroll") for (int k = 0; k < 2; ++k) dst[m][k] = *(const LAS bf16x8*)(lds + PG8_SA(b, h) + aoff + m * 2048 + k * 1024); } while (0)
; #define PG8_LDB(dst, b, h) do { _Pragma("unroll") for (int n = 0; n < 2; ++n) _Pragma("unroll") for (int k = 0; k < 2; ++k) dst[n][k] = *(const LAS bf16x8*)(lds + PG8_SB(b, h) + boff + n * 2048 + k * 1024); } while (0)
; #define PG8_MMA(ai, bj, At, Bt) do { __builtin_amdgcn_s_setprio(1); _Pragma("unroll") for (int m = 0; m < 4; ++m) _Pragma("unroll") for (int n = 0; n < 2; ++n) _Pragma("unroll") for (int k = 0; k < 2; ++k) \
;         acc[ai][bj][m][n] = __builtin_amdgcn_mfma_f32_16x16x32_bf16(Bt[n][k], At[m][k], acc[ai][bj][m][n], 0, 0, 0); __builtin_amdgcn_s_setprio(0); } while (0)
; #define PG8_WAIT_V(n) asm volatile("s_waitcnt vmcnt(" #n ")" ::: "memory")
; #define PG8_WAIT_L(n) asm volatile("s_waitcnt lgkmcnt(" #n ")" ::: "memory")
; #define PG8_BAR __builtin_amdgcn_s_barrier()
; template <class Epi, class Sched>
; __device__ __forceinline__ void gemm_phase(LAS unsigned char* lds, const Gemm g, const Sched& S, const Epi& E) {
;     ...
;             PG8_WAIT_L(8); PG8_BAR; PG8_WAIT_L(0); PG8_MMA(0, 0, At, B0); PG8_BAR; PG8_SCHED;
;             PG8_LDB(B1, 1, 1); PG8_STAGE(PG8_SB(1, 0), b3, voffB);
;             PG8_BAR; PG8_WAIT_L(0); PG8_MMA(0, 1, At, B1); PG8_BAR;
;             PG8_LDA(At, 1, 1); PG8_STAGE(PG8_SA(1, 0), a3, voffA);
;             PG8_BAR; PG8_WAIT_L(0); PG8_MMA(1, 0, At, B0); PG8_BAR; PG8_SCHED;
;             PG8_STAGE(PG8_SB(1, 1), b3 + hstep, voffB);
;             PG8_WAIT_V(6); PG8_BAR; PG8_MMA(1, 1, At, B1); PG8_BAR;
;     __device__ __forceinline__ void operator()(const AccT& acc, const Unit& u, int wr, int wc, int fr, int fq) const {
;         asm volatile("" : "+v"(fr), "+v"(fq));
;         const int rowt = u.pm * 256; const bool isc = rowt >= MX; const int b = isc ? 32 : (rowt >> 11);
;         const float* res = isc ? res_c + (size_t)(rowt - MX) * DM : res_x + (size_t)rowt * DM; bf16_t* out = hb + (size_t)rowt * DM;
	s_waitcnt lgkmcnt(0)
	v_mfma_f32_16x16x32_bf16 v[112:115], v[202:205], v[168:171], v[112:115]
	v_mfma_f32_16x16x32_bf16 v[108:111], v[210:213], v[168:171], v[108:111]
	v_mfma_f32_16x16x32_bf16 v[100:103], v[202:205], v[176:179], v[100:103]
	v_mfma_f32_16x16x32_bf16 v[92:95], v[210:213], v[176:179], v[92:95]
	v_mfma_f32_16x16x32_bf16 v[84:87], v[202:205], v[184:187], v[84:87]
	v_mfma_f32_16x16x32_bf16 v[76:79], v[210:213], v[184:187], v[76:79]
	v_mfma_f32_16x16x32_bf16 v[68:71], v[202:205], v[192:195], v[68:71]
	v_mfma_f32_16x16x32_bf16 v[64:67], v[210:213], v[192:195], v[64:67]
	v_mfma_f32_16x16x32_bf16 v[112:115], v[206:209], v[172:175], v[112:115]
	v_mfma_f32_16x16x32_bf16 v[108:111], v[214:217], v[172:175], v[108:111]
	v_mfma_f32_16x16x32_bf16 v[100:103], v[206:209], v[180:183], v[100:103]
	v_mfma_f32_16x16x32_bf16 v[92:95], v[214:217], v[180:183], v[92:95]
	v_mfma_f32_16x16x32_bf16 v[84:87], v[206:209], v[188:191], v[84:87]
	v_mfma_f32_16x16x32_bf16 v[76:79], v[214:217], v[188:191], v[76:79]
	v_mfma_f32_16x16x32_bf16 v[68:71], v[206:209], v[196:199], v[68:71]
	v_mfma_f32_16x16x32_bf16 v[64:67], v[214:217], v[196:199], v[64:67]
	s_setprio 0
	s_mov_b32 m0, s52
	s_add_u32 s8, s36, 0x80
	s_addc_u32 s9, s37, 0
	s_barrier
	ds_read_b128 v[168:171], v166 offset:49152
	ds_read_b128 v[172:175], v166 offset:50176
	ds_read_b128 v[176:179], v166 offset:51200
	ds_read_b128 v[180:183], v166 offset:52224
	ds_read_b128 v[184:187], v166 offset:53248
	ds_read_b128 v[188:191], v166 offset:54272
	ds_read_b128 v[192:195], v166 offset:55296
	ds_read_b128 v[196:199], v166 offset:56320
	global_load_lds_dwordx4 v134, s[8:9]
	s_mov_b32 m0, s53
	s_nop 0
	global_load_lds_dwordx4 v130, s[8:9]
	s_setprio 1
	s_barrier
	s_waitcnt lgkmcnt(0)
	v_mfma_f32_16x16x32_bf16 v[60:63], v[144:147], v[168:171], v[60:63]
	v_mfma_f32_16x16x32_bf16 v[56:59], v[152:155], v[168:171], v[56:59]
	v_mfma_f32_16x16x32_bf16 v[48:51], v[144:147], v[176:179], v[48:51]
	v_mfma_f32_16x16x32_bf16 v[40:43], v[152:155], v[176:179], v[40:43]
	v_mfma_f32_16x16x32_bf16 v[32:35], v[144:147], v[184:187], v[32:35]
	v_mfma_f32_16x16x32_bf16 v[24:27], v[152:155], v[184:187], v[24:27]
	v_mfma_f32_16x16x32_bf16 v[16:19], v[144:147], v[192:195], v[16:19]
	v_mfma_f32_16x16x32_bf16 v[8:11], v[152:155], v[192:195], v[8:11]
	v_mfma_f32_16x16x32_bf16 v[60:63], v[148:151], v[172:175], v[60:63]
	v_mfma_f32_16x16x32_bf16 v[56:59], v[156:159], v[172:175], v[56:59]
	v_mfma_f32_16x16x32_bf16 v[48:51], v[148:151], v[180:183], v[48:51]
	v_mfma_f32_16x16x32_bf16 v[40:43], v[156:159], v[180:183], v[40:43]
	v_mfma_f32_16x16x32_bf16 v[32:35], v[148:151], v[188:191], v[32:35]
	v_mfma_f32_16x16x32_bf16 v[24:27], v[156:159], v[188:191], v[24:27]
	v_mfma_f32_16x16x32_bf16 v[16:19], v[148:151], v[196:199], v[16:19]
	v_mfma_f32_16x16x32_bf16 v[8:11], v[156:159], v[196:199], v[8:11]
	s_setprio 0
	s_barrier
	s_add_u32 s16, s34, 0xb0080
	s_addc_u32 s17, s35, 0
	s_add_i32 s20, s21, s40
	s_mov_b32 m0, s20
	s_nop 0
	global_load_lds_dwordx4 v132, s[16:17]
	s_add_i32 m0, s20, 0x2000
	s_nop 0
	global_load_lds_dwordx4 v128, s[16:17]
	s_waitcnt vmcnt(8)
	s_setprio 1
	s_barrier
	v_mfma_f32_16x16x32_bf16 v[52:55], v[202:205], v[168:171], v[52:55]
	v_mfma_f32_16x16x32_bf16 v[44:47], v[210:213], v[168:171], v[44:47]
	v_mfma_f32_16x16x32_bf16 v[36:39], v[202:205], v[176:179], v[36:39]
	v_mfma_f32_16x16x32_bf16 v[28:31], v[210:213], v[176:179], v[28:31]
	v_mfma_f32_16x16x32_bf16 v[20:23], v[202:205], v[184:187], v[20:23]
	v_mfma_f32_16x16x32_bf16 v[12:15], v[210:213], v[184:187], v[12:15]
	v_mfma_f32_16x16x32_bf16 v[4:7], v[202:205], v[192:195], v[4:7]
	v_mfma_f32_16x16x32_bf16 v[0:3], v[210:213], v[192:195], v[0:3]
	v_mfma_f32_16x16x32_bf16 v[52:55], v[206:209], v[172:175], v[52:55]
	v_mfma_f32_16x16x32_bf16 v[44:47], v[214:217], v[172:175], v[44:47]
	v_mfma_f32_16x16x32_bf16 v[36:39], v[206:209], v[180:183], v[36:39]
	v_mfma_f32_16x16x32_bf16 v[28:31], v[214:217], v[180:183], v[28:31]
	v_mfma_f32_16x16x32_bf16 v[20:23], v[206:209], v[188:191], v[20:23]
	v_mfma_f32_16x16x32_bf16 v[12:15], v[214:217], v[188:191], v[12:15]
	v_mfma_f32_16x16x32_bf16 v[4:7], v[206:209], v[196:199], v[4:7]
	v_mfma_f32_16x16x32_bf16 v[0:3], v[214:217], v[196:199], v[0:3]
	s_setprio 0
	s_add_i32 s68, s68, 2
	s_add_u32 s0, s0, 0x100
	s_addc_u32 s67, s67, 0
	s_cmp_gt_u32 s68, 41
	s_mov_b64 s[26:27], s[28:29]
	s_barrier
	s_cbranch_scc0 .LBB0_305
	s_lshl_b32 s0, s66, 8
	v_mov_b32_e32 v145, v163
	v_mov_b32_e32 v144, v162
	s_cmpk_lt_i32 s66, 0x100
	s_cbranch_scc0 .LBB0_308
	s_ashr_i32 s29, s0, 31
	s_mov_b32 s28, s0
	s_lshl_b64 s[16:17], s[28:29], 12
	v_readlane_b32 s80, v254, 23
	v_readlane_b32 s81, v254, 24
	s_add_u32 s26, s80, s16
	v_readlane_b32 s82, v254, 25
	v_readlane_b32 s83, v254, 26
	v_readlane_b32 s84, v254, 27
	v_readlane_b32 s85, v254, 28
	v_readlane_b32 s86, v254, 29
	v_readlane_b32 s87, v254, 30
	v_readlane_b32 s88, v254, 31
	v_readlane_b32 s89, v254, 32
	v_readlane_b32 s90, v254, 33
	v_readlane_b32 s91, v254, 34
	v_readlane_b32 s92, v254, 35
	v_readlane_b32 s93, v254, 36
	v_readlane_b32 s94, v254, 37
	v_readlane_b32 s95, v254, 38
	s_addc_u32 s27, s81, s17
	s_cbranch_execnz .LBB0_297
	s_branch .LBB0_296

; #define PG8_STAGE(bufoff, gbase, voff) do { _Pragma("unroll") for (int _i = 0; _i < 2; ++_i) \
;         __builtin_amdgcn_global_load_lds((const unsigned*)((const char*)(gbase) + (voff)[_i]), (LAS unsigned*)(lds + (bufoff) + ldsw + _i * 8192), 16, 0, 0); } while (0)
; #define PG8_LDA(dst, b, h) do { _Pragma("unroll") for (int m = 0; m < 4; ++m) _Pragma("unroll") for (int k = 0; k < 2; ++k) dst[m][k] = *(const LAS bf16x8*)(lds + PG8_SA(b, h) + aoff + m * 2048 + k * 1024); } while (0)
; #define PG8_LDB(dst, b, h) do { _Pragma("unroll") for (int n = 0; n < 2; ++n) _Pragma("unroll") for (int k = 0; k < 2; ++k) dst[n][k] = *(const LAS bf16x8*)(lds + PG8_SB(b, h) + boff + n * 2048 + k * 1024); } while (0)
; #define PG8_WAIT_V(n) asm volatile("s_waitcnt vmcnt(" #n ")" ::: "memory")
; #define PG8_WAIT_L(n) asm volatile("s_waitcnt lgkmcnt(" #n ")" ::: "memory")
; #define PG8_BAR __builtin_amdgcn_s_barrier()
; #define PG8_SCHED __builtin_amdgcn_sched_barrier(0)
; template <class Epi, class Sched>
; __device__ __forceinline__ void gemm_phase(LAS unsigned char* lds, const Gemm g, const Sched& S, const Epi& E) {
;     ...
;         const bool has_next = S.next(ui + 1, nxt);
;         const char* nA = has_next ? (const char*)g.A + (size_t)nxt.pm * tstep : cA; const char* nB = has_next ? (const char*)g.Bt + (size_t)nxt.pn * tstep : cB;
;         for (int t = 0; t < nt; t += 2) {
;             const bool last = (t == nt - 2);
;             const char* a1 = cA + (size_t)(t + 1) * kstep;
;             const char* a2 = last ? nA : cA + (size_t)(t + 2) * kstep; const char* b2 = last ? nB : cB + (size_t)(t + 2) * kstep;
;             const char* a3 = a2 + kstep; const char* b3 = b2 + kstep;
;             PG8_LDB(B0, 0, 0); PG8_SCHED; PG8_LDA(At, 0, 0); PG8_STAGE(PG8_SA(1, 1), a1 + hstep, voffA);
;             PG8_WAIT_L(8); PG8_BAR; PG8_WAIT_L(0); PG8_MMA(0, 0, At, B0); PG8_BAR; PG8_SCHED;
;             PG8_LDB(B1, 0, 1); PG8_STAGE(PG8_SB(0, 0), b2, voffB);
;             PG8_BAR; PG8_WAIT_L(0); PG8_MMA(0, 1, At, B1); PG8_BAR;
;             PG8_LDA(At, 0, 1); PG8_STAGE(PG8_SA(0, 0), a2, voffA);
;             PG8_BAR; PG8_WAIT_L(0); PG8_MMA(1, 0, At, B0); PG8_BAR; PG8_SCHED;
;             PG8_STAGE(PG8_SB(0, 1), b2 + hstep, voffB);
;             PG8_WAIT_V(6); PG8_BAR; PG8_MMA(1, 1, At, B1); PG8_BAR;
.LBB0_577:
	s_ashr_i32 s21, s20, 31
	v_cmp_lt_i64_e32 vcc, s[22:23], v[156:157]
	s_lshl_b64 s[22:23], s[20:21], 19
	s_add_u32 s22, s96, s22
	s_addc_u32 s23, s97, s23
	s_and_b64 s[24:25], vcc, exec
	s_cselect_b32 s5, s23, s7
	s_cselect_b32 s21, s22, s6
	s_ashr_i32 s19, s18, 31
	s_lshl_b64 s[24:25], s[18:19], 19
	s_add_u32 s24, s31, s24
	s_addc_u32 s25, s33, s25
	s_and_b64 s[28:29], vcc, exec
	s_cselect_b32 s19, s25, s27
	s_cselect_b32 s53, s24, s26
	s_add_u32 s6, s6, 0x40080
	s_addc_u32 s7, s7, 0
	s_add_u32 s54, s26, 0x100
	s_addc_u32 s55, s27, 0
	s_mov_b32 s56, -2
	s_waitcnt lgkmcnt(0)
	ds_read_b128 v[128:131], v167
	ds_read_b128 v[132:135], v167 offset:1024
	ds_read_b128 v[136:139], v167 offset:2048
	ds_read_b128 v[160:163], v167 offset:3072
	s_add_u32 s26, s6, 0xfffc0080
	s_addc_u32 s27, s7, -1
	s_cmp_eq_u32 s56, 12
	s_cselect_b32 s29, s5, s27
	s_cselect_b32 s28, s21, s26
	s_cselect_b32 s27, s19, s55
	s_cselect_b32 s26, s53, s54
	s_add_i32 m0, s37, 0xc000
	ds_read_b128 v[170:173], v168
	ds_read_b128 v[174:177], v168 offset:1024
	ds_read_b128 v[178:181], v168 offset:2048
	ds_read_b128 v[182:185], v168 offset:3072
	ds_read_b128 v[186:189], v168 offset:4096
	ds_read_b128 v[190:193], v168 offset:5120
	ds_read_b128 v[194:197], v168 offset:6144
	ds_read_b128 v[202:205], v168 offset:7168
	global_load_lds_dwordx4 v152, s[6:7]
	s_add_i32 m0, s37, 0xe000
	s_nop 0
	global_load_lds_dwordx4 v154, s[6:7]
	s_waitcnt lgkmcnt(8)
	s_waitcnt vmcnt(8)
	s_setprio 1
	s_barrier
	s_waitcnt lgkmcnt(0)
	v_mfma_f32_16x16x32_bf16 v[124:127], v[128:131], v[170:173], 0
	v_mfma_f32_16x16x32_bf16 v[120:123], v[136:139], v[170:173], 0
	v_mfma_f32_16x16x32_bf16 v[108:111], v[128:131], v[178:181], 0
	v_mfma_f32_16x16x32_bf16 v[104:107], v[136:139], v[178:181], 0
	v_mfma_f32_16x16x32_bf16 v[92:95], v[128:131], v[186:189], 0
	v_mfma_f32_16x16x32_bf16 v[88:91], v[136:139], v[186:189], 0
	v_mfma_f32_16x16x32_bf16 v[76:79], v[128:131], v[194:197], 0
	v_mfma_f32_16x16x32_bf16 v[72:75], v[136:139], v[194:197], 0
	v_mfma_f32_16x16x32_bf16 v[124:127], v[132:135], v[174:177], v[124:127]
	v_mfma_f32_16x16x32_bf16 v[120:123], v[160:163], v[174:177], v[120:123]
	v_mfma_f32_16x16x32_bf16 v[108:111], v[132:135], v[182:185], v[108:111]
	v_mfma_f32_16x16x32_bf16 v[104:107], v[160:163], v[182:185], v[104:107]
	v_mfma_f32_16x16x32_bf16 v[92:95], v[132:135], v[190:193], v[92:95]
	v_mfma_f32_16x16x32_bf16 v[88:91], v[160:163], v[190:193], v[88:91]
	v_mfma_f32_16x16x32_bf16 v[76:79], v[132:135], v[202:205], v[76:79]
	v_mfma_f32_16x16x32_bf16 v[72:75], v[160:163], v[202:205], v[72:75]
	s_setprio 0
	s_barrier
	s_add_i32 s57, s48, s34
	s_mov_b32 m0, s57
	ds_read_b128 v[206:209], v169
	ds_read_b128 v[210:213], v169 offset:1024
	ds_read_b128 v[214:217], v169 offset:2048
	ds_read_b128 v[218:221], v169 offset:3072
	global_load_lds_dwordx4 v146, s[26:27]
	s_add_i32 m0, s57, 0x2000
	s_nop 0
	global_load_lds_dwordx4 v142, s[26:27]
	s_waitcnt vmcnt(8)
	s_setprio 1
	s_barrier
	s_waitcnt lgkmcnt(0)
	v_mfma_f32_16x16x32_bf16 v[116:119], v[206:209], v[170:173], 0
	v_mfma_f32_16x16x32_bf16 v[112:115], v[214:217], v[170:173], 0
	v_mfma_f32_16x16x32_bf16 v[100:103], v[206:209], v[178:181], 0
	v_mfma_f32_16x16x32_bf16 v[96:99], v[214:217], v[178:181], 0
	v_mfma_f32_16x16x32_bf16 v[84:87], v[206:209], v[186:189], 0
	v_mfma_f32_16x16x32_bf16 v[80:83], v[214:217], v[186:189], 0
	v_mfma_f32_16x16x32_bf16 v[68:71], v[206:209], v[194:197], 0
	v_mfma_f32_16x16x32_bf16 v[64:67], v[214:217], v[194:197], 0
	v_mfma_f32_16x16x32_bf16 v[116:119], v[210:213], v[174:177], v[116:119]
	v_mfma_f32_16x16x32_bf16 v[112:115], v[218:221], v[174:177], v[112:115]
	v_mfma_f32_16x16x32_bf16 v[100:103], v[210:213], v[182:185], v[100:103]
	v_mfma_f32_16x16x32_bf16 v[96:99], v[218:221], v[182:185], v[96:99]
	v_mfma_f32_16x16x32_bf16 v[84:87], v[210:213], v[190:193], v[84:87]
	v_mfma_f32_16x16x32_bf16 v[80:83], v[218:221], v[190:193], v[80:83]
	v_mfma_f32_16x16x32_bf16 v[68:71], v[210:213], v[202:205], v[68:71]
	v_mfma_f32_16x16x32_bf16 v[64:67], v[218:221], v[202:205], v[64:67]
	s_setprio 0
	s_mov_b32 m0, s37
	v_lshl_add_u64 v[222:223], s[28:29], 0, v[148:149]
	s_barrier
	ds_read_b128 v[170:173], v168 offset:16384
	ds_read_b128 v[174:177], v168 offset:17408
	ds_read_b128 v[178:181], v168 offset:18432
	ds_read_b128 v[182:185], v168 offset:19456
	ds_read_b128 v[186:189], v168 offset:20480
	ds_read_b128 v[190:193], v168 offset:21504
	ds_read_b128 v[194:197], v168 offset:22528
	ds_read_b128 v[202:205], v168 offset:23552
	global_load_lds_dwordx4 v148, s[28:29]
	v_lshl_add_u64 v[224:225], s[28:29], 0, v[144:145]
	s_mov_b32 m0, s38
	s_nop 0
	global_load_lds_dwordx4 v144, s[28:29]
	s_setprio 1
	s_barrier
	s_waitcnt lgkmcnt(0)
	v_mfma_f32_16x16x32_bf16 v[60:63], v[128:131], v[170:173], 0
	v_mfma_f32_16x16x32_bf16 v[56:59], v[136:139], v[170:173], 0
	v_mfma_f32_16x16x32_bf16 v[44:47], v[128:131], v[178:181], 0
	v_mfma_f32_16x16x32_bf16 v[40:43], v[136:139], v[178:181], 0
	v_mfma_f32_16x16x32_bf16 v[28:31], v[128:131], v[186:189], 0
	v_mfma_f32_16x16x32_bf16 v[24:27], v[136:139], v[186:189], 0
	v_mfma_f32_16x16x32_bf16 v[12:15], v[128:131], v[194:197], 0
	v_mfma_f32_16x16x32_bf16 v[8:11], v[136:139], v[194:197], 0
	v_mfma_f32_16x16x32_bf16 v[60:63], v[132:135], v[174:177], v[60:63]
	v_mfma_f32_16x16x32_bf16 v[56:59], v[160:163], v[174:177], v[56:59]
	v_mfma_f32_16x16x32_bf16 v[44:47], v[132:135], v[182:185], v[44:47]
	v_mfma_f32_16x16x32_bf16 v[40:43], v[160:163], v[182:185], v[40:43]
	v_mfma_f32_16x16x32_bf16 v[28:31], v[132:135], v[190:193], v[28:31]
	v_mfma_f32_16x16x32_bf16 v[24:27], v[160:163], v[190:193], v[24:27]
	v_mfma_f32_16x16x32_bf16 v[12:15], v[132:135], v[202:205], v[12:15]
	v_mfma_f32_16x16x32_bf16 v[8:11], v[160:163], v[202:205], v[8:11]
	s_setprio 0
	s_barrier
; #define PG8_STAGE(bufoff, gbase, voff) do { _Pragma("unroll") for (int _i = 0; _i < 2; ++_i) \
;         __builtin_amdgcn_global_load_lds((const unsigned*)((const char*)(gbase) + (voff)[_i]), (LAS unsigned*)(lds + (bufoff) + ldsw + _i * 8192), 16, 0, 0); } while (0)
; #define PG8_LDA(dst, b, h) do { _Pragma("unroll") for (int m = 0; m < 4; ++m) _Pragma("unroll") for (int k = 0; k < 2; ++k) dst[m][k] = *(const LAS bf16x8*)(lds + PG8_SA(b, h) + aoff + m * 2048 + k * 1024); } while (0)
; #define PG8_LDB(dst, b, h) do { _Pragma("unroll") for (int n = 0; n < 2; ++n) _Pragma("unroll") for (int k = 0; k < 2; ++k) dst[n][k] = *(const LAS bf16x8*)(lds + PG8_SB(b, h) + boff + n * 2048 + k * 1024); } while (0)
; #define PG8_MMA(ai, bj, At, Bt) do { __builtin_amdgcn_s_setprio(1); _Pragma("unroll") for (int m = 0; m < 4; ++m) _Pragma("unroll") for (int n = 0; n < 2; ++n) _Pragma("unroll") for (int k = 0; k < 2; ++k) \
;         acc[ai][bj][m][n] = __builtin_amdgcn_mfma_f32_16x16x32_bf16(Bt[n][k], At[m][k], acc[ai][bj][m][n], 0, 0, 0); __builtin_amdgcn_s_setprio(0); } while (0)
; #define PG8_WAIT_V(n) asm volatile("s_waitcnt vmcnt(" #n ")" ::: "memory")
; #define PG8_WAIT_L(n) asm volatile("s_waitcnt lgkmcnt(" #n ")" ::: "memory")
; #define PG8_BAR __builtin_amdgcn_s_barrier()
; #define PG8_SCHED __builtin_amdgcn_sched_barrier(0)
; template <class Epi, class Sched>
; __device__ __forceinline__ void gemm_phase(LAS unsigned char* lds, const Gemm g, const Sched& S, const Epi& E) {
;     ...
;             PG8_STAGE(PG8_SB(0, 1), b2 + hstep, voffB);
;             PG8_WAIT_V(6); PG8_BAR; PG8_MMA(1, 1, At, B1); PG8_BAR;
;             PG8_LDB(B0, 1, 0); PG8_SCHED; PG8_LDA(At, 1, 0); PG8_STAGE(PG8_SA(0, 1), a2 + hstep, voffA);
;             PG8_WAIT_L(8); PG8_BAR; PG8_WAIT_L(0); PG8_MMA(0, 0, At, B0); PG8_BAR; PG8_SCHED;
;             PG8_LDB(B1, 1, 1); PG8_STAGE(PG8_SB(1, 0), b3, voffB);
;             PG8_BAR; PG8_WAIT_L(0); PG8_MMA(0, 1, At, B1); PG8_BAR;
;             PG8_LDA(At, 1, 1); PG8_STAGE(PG8_SA(1, 0), a3, voffA);
;             PG8_BAR; PG8_WAIT_L(0); PG8_MMA(1, 0, At, B0); PG8_BAR; PG8_SCHED;
	s_add_u32 s58, s26, 0x40000
	s_addc_u32 s59, s27, 0
	s_add_i32 s57, s49, s34
	s_mov_b32 m0, s57
	s_nop 0
	global_load_lds_dwordx4 v146, s[58:59]
	s_add_i32 m0, s57, 0x2000
	s_nop 0
	global_load_lds_dwordx4 v142, s[58:59]
	s_add_u32 s28, s28, 0x40000
	s_addc_u32 s29, s29, 0
	s_mov_b32 m0, s39
	s_nop 0
	global_load_lds_dwordx4 v148, s[28:29]
	s_mov_b32 m0, s40
	s_nop 0
	global_load_lds_dwordx4 v144, s[28:29]
	s_waitcnt vmcnt(10)
	s_setprio 1
	s_barrier
	v_mfma_f32_16x16x32_bf16 v[52:55], v[206:209], v[170:173], 0
	v_mfma_f32_16x16x32_bf16 v[48:51], v[214:217], v[170:173], 0
	v_mfma_f32_16x16x32_bf16 v[36:39], v[206:209], v[178:181], 0
	v_mfma_f32_16x16x32_bf16 v[32:35], v[214:217], v[178:181], 0
	v_mfma_f32_16x16x32_bf16 v[20:23], v[206:209], v[186:189], 0
	v_mfma_f32_16x16x32_bf16 v[16:19], v[214:217], v[186:189], 0
	v_mfma_f32_16x16x32_bf16 v[4:7], v[206:209], v[194:197], 0
	v_mfma_f32_16x16x32_bf16 v[0:3], v[214:217], v[194:197], 0
	v_mfma_f32_16x16x32_bf16 v[52:55], v[210:213], v[174:177], v[52:55]
	v_mfma_f32_16x16x32_bf16 v[48:51], v[218:221], v[174:177], v[48:51]
	v_mfma_f32_16x16x32_bf16 v[36:39], v[210:213], v[182:185], v[36:39]
	v_mfma_f32_16x16x32_bf16 v[32:35], v[218:221], v[182:185], v[32:35]
	v_mfma_f32_16x16x32_bf16 v[20:23], v[210:213], v[190:193], v[20:23]
	v_mfma_f32_16x16x32_bf16 v[16:19], v[218:221], v[190:193], v[16:19]
	v_mfma_f32_16x16x32_bf16 v[4:7], v[210:213], v[202:205], v[4:7]
	v_mfma_f32_16x16x32_bf16 v[0:3], v[218:221], v[202:205], v[0:3]
	s_setprio 0
	s_add_i32 s57, 0, 0x18000
	v_add_u32_e32 v150, s57, v166
	s_barrier
	ds_read_b128 v[128:131], v150
	ds_read_b128 v[132:135], v150 offset:1024
	ds_read_b128 v[136:139], v150 offset:2048
	ds_read_b128 v[160:163], v150 offset:3072
	ds_read_b128 v[170:173], v168 offset:32768
	ds_read_b128 v[174:177], v168 offset:33792
	ds_read_b128 v[178:181], v168 offset:34816
	ds_read_b128 v[182:185], v168 offset:35840
	ds_read_b128 v[186:189], v168 offset:36864
	ds_read_b128 v[190:193], v168 offset:37888
	ds_read_b128 v[194:197], v168 offset:38912
	ds_read_b128 v[202:205], v168 offset:39936
	s_waitcnt lgkmcnt(8)
	s_waitcnt vmcnt(8)
	s_setprio 1
	s_barrier
	s_waitcnt lgkmcnt(0)
	v_mfma_f32_16x16x32_bf16 v[124:127], v[128:131], v[170:173], v[124:127]
	v_mfma_f32_16x16x32_bf16 v[120:123], v[136:139], v[170:173], v[120:123]
	v_mfma_f32_16x16x32_bf16 v[108:111], v[128:131], v[178:181], v[108:111]
	v_mfma_f32_16x16x32_bf16 v[104:107], v[136:139], v[178:181], v[104:107]
	v_mfma_f32_16x16x32_bf16 v[92:95], v[128:131], v[186:189], v[92:95]
	v_mfma_f32_16x16x32_bf16 v[88:91], v[136:139], v[186:189], v[88:91]
	v_mfma_f32_16x16x32_bf16 v[76:79], v[128:131], v[194:197], v[76:79]
	v_mfma_f32_16x16x32_bf16 v[72:75], v[136:139], v[194:197], v[72:75]
	v_mfma_f32_16x16x32_bf16 v[124:127], v[132:135], v[174:177], v[124:127]
	v_mfma_f32_16x16x32_bf16 v[120:123], v[160:163], v[174:177], v[120:123]
	v_mfma_f32_16x16x32_bf16 v[108:111], v[132:135], v[182:185], v[108:111]
	v_mfma_f32_16x16x32_bf16 v[104:107], v[160:163], v[182:185], v[104:107]
	v_mfma_f32_16x16x32_bf16 v[92:95], v[132:135], v[190:193], v[92:95]
	v_mfma_f32_16x16x32_bf16 v[88:91], v[160:163], v[190:193], v[88:91]
	v_mfma_f32_16x16x32_bf16 v[76:79], v[132:135], v[202:205], v[76:79]
	v_mfma_f32_16x16x32_bf16 v[72:75], v[160:163], v[202:205], v[72:75]
	s_setprio 0
	s_barrier
	s_add_i32 s28, 0, 0x1c000
	s_add_i32 s29, s57, s34
	v_add_u32_e32 v150, s28, v166
	s_add_u32 s0, s26, 0x80
	s_addc_u32 s1, s27, 0
	s_mov_b32 m0, s29
	ds_read_b128 v[206:209], v150
	ds_read_b128 v[210:213], v150 offset:1024
	ds_read_b128 v[214:217], v150 offset:2048
	ds_read_b128 v[218:221], v150 offset:3072
	global_load_lds_dwordx4 v146, s[0:1]
	s_add_i32 m0, s29, 0x2000
	s_nop 0
	global_load_lds_dwordx4 v142, s[0:1]
	s_waitcnt vmcnt(8)
	s_setprio 1
	s_barrier
	s_waitcnt lgkmcnt(0)
	v_mfma_f32_16x16x32_bf16 v[116:119], v[206:209], v[170:173], v[116:119]
	v_mfma_f32_16x16x32_bf16 v[112:115], v[214:217], v[170:173], v[112:115]
	v_mfma_f32_16x16x32_bf16 v[100:103], v[206:209], v[178:181], v[100:103]
	v_mfma_f32_16x16x32_bf16 v[96:99], v[214:217], v[178:181], v[96:99]
	v_mfma_f32_16x16x32_bf16 v[84:87], v[206:209], v[186:189], v[84:87]
	v_mfma_f32_16x16x32_bf16 v[80:83], v[214:217], v[186:189], v[80:83]
	v_mfma_f32_16x16x32_bf16 v[68:71], v[206:209], v[194:197], v[68:71]
	v_mfma_f32_16x16x32_bf16 v[64:67], v[214:217], v[194:197], v[64:67]
	v_mfma_f32_16x16x32_bf16 v[116:119], v[210:213], v[174:177], v[116:119]
	v_mfma_f32_16x16x32_bf16 v[112:115], v[218:221], v[174:177], v[112:115]
	v_mfma_f32_16x16x32_bf16 v[100:103], v[210:213], v[182:185], v[100:103]
	v_mfma_f32_16x16x32_bf16 v[96:99], v[218:221], v[182:185], v[96:99]
	v_mfma_f32_16x16x32_bf16 v[84:87], v[210:213], v[190:193], v[84:87]
	v_mfma_f32_16x16x32_bf16 v[80:83], v[218:221], v[190:193], v[80:83]
	v_mfma_f32_16x16x32_bf16 v[68:71], v[210:213], v[202:205], v[68:71]
	v_mfma_f32_16x16x32_bf16 v[64:67], v[218:221], v[202:205], v[64:67]
	s_setprio 0
	s_mov_b32 m0, s44
	s_mov_b64 s[0:1], 0x80
	v_lshl_add_u64 v[140:141], v[222:223], 0, s[0:1]
	s_barrier
	ds_read_b128 v[170:173], v168 offset:49152
	ds_read_b128 v[174:177], v168 offset:50176
	ds_read_b128 v[178:181], v168 offset:51200
	ds_read_b128 v[182:185], v168 offset:52224
	ds_read_b128 v[186:189], v168 offset:53248
	ds_read_b128 v[190:193], v168 offset:54272
	ds_read_b128 v[194:197], v168 offset:55296
	ds_read_b128 v[202:205], v168 offset:56320
	global_load_lds_dwordx4 v[140:141], off
	v_lshl_add_u64 v[140:141], v[224:225], 0, s[0:1]
	s_mov_b32 m0, s45
	s_nop 0
	global_load_lds_dwordx4 v[140:141], off
	s_setprio 1
	s_barrier
; #define PG8_STAGE(bufoff, gbase, voff) do { _Pragma("unroll") for (int _i = 0; _i < 2; ++_i) \
;         __builtin_amdgcn_global_load_lds((const unsigned*)((const char*)(gbase) + (voff)[_i]), (LAS unsigned*)(lds + (bufoff) + ldsw + _i * 8192), 16, 0, 0); } while (0)
; #define PG8_LDA(dst, b, h) do { _Pragma("unroll") for (int m = 0; m < 4; ++m) _Pragma("unroll") for (int k = 0; k < 2; ++k) dst[m][k] = *(const LAS bf16x8*)(lds + PG8_SA(b, h) + aoff + m * 2048 + k * 1024); } while (0)
; #define PG8_LDB(dst, b, h) do { _Pragma("unroll") for (int n = 0; n < 2; ++n) _Pragma("unroll") for (int k = 0; k < 2; ++k) dst[n][k] = *(const LAS bf16x8*)(lds + PG8_SB(b, h) + boff + n * 2048 + k * 1024); } while (0)
; #define PG8_MMA(ai, bj, At, Bt) do { __builtin_amdgcn_s_setprio(1); _Pragma("unroll") for (int m = 0; m < 4; ++m) _Pragma("unroll") for (int n = 0; n < 2; ++n) _Pragma("unroll") for (int k = 0; k < 2; ++k) \
;         acc[ai][bj][m][n] = __builtin_amdgcn_mfma_f32_16x16x32_bf16(Bt[n][k], At[m][k], acc[ai][bj][m][n], 0, 0, 0); __builtin_amdgcn_s_setprio(0); } while (0)
; #define PG8_BAR __builtin_amdgcn_s_barrier()
; template <class Epi, class Sched>
; __device__ __forceinline__ void gemm_phase(LAS unsigned char* lds, const Gemm g, const Sched& S, const Epi& E) {
;     ...
;         for (int t = 0; t < nt; t += 2) {
;             const bool last = (t == nt - 2);
;             const char* a1 = cA + (size_t)(t + 1) * kstep;
;             const char* a2 = last ? nA : cA + (size_t)(t + 2) * kstep; const char* b2 = last ? nB : cB + (size_t)(t + 2) * kstep;
;             const char* a3 = a2 + kstep; const char* b3 = b2 + kstep;
;             PG8_LDB(B0, 0, 0); PG8_SCHED; PG8_LDA(At, 0, 0); PG8_STAGE(PG8_SA(1, 1), a1 + hstep, voffA);
;             PG8_WAIT_L(8); PG8_BAR; PG8_WAIT_L(0); PG8_MMA(0, 0, At, B0); PG8_BAR; PG8_SCHED;
;             PG8_LDB(B1, 0, 1); PG8_STAGE(PG8_SB(0, 0), b2, voffB);
;             PG8_BAR; PG8_WAIT_L(0); PG8_MMA(0, 1, At, B1); PG8_BAR;
;             PG8_LDA(At, 0, 1); PG8_STAGE(PG8_SA(0, 0), a2, voffA);
;             PG8_BAR; PG8_WAIT_L(0); PG8_MMA(1, 0, At, B0); PG8_BAR; PG8_SCHED;
;             PG8_STAGE(PG8_SB(0, 1), b2 + hstep, voffB);
;     ...
;             PG8_BAR; PG8_WAIT_L(0); PG8_MMA(1, 0, At, B0); PG8_BAR; PG8_SCHED;
;             PG8_STAGE(PG8_SB(1, 1), b3 + hstep, voffB);
;             PG8_WAIT_V(6); PG8_BAR; PG8_MMA(1, 1, At, B1); PG8_BAR;
	s_waitcnt lgkmcnt(0)
	v_mfma_f32_16x16x32_bf16 v[60:63], v[128:131], v[170:173], v[60:63]
	v_mfma_f32_16x16x32_bf16 v[56:59], v[136:139], v[170:173], v[56:59]
	v_mfma_f32_16x16x32_bf16 v[44:47], v[128:131], v[178:181], v[44:47]
	v_mfma_f32_16x16x32_bf16 v[40:43], v[136:139], v[178:181], v[40:43]
	v_mfma_f32_16x16x32_bf16 v[28:31], v[128:131], v[186:189], v[28:31]
	v_mfma_f32_16x16x32_bf16 v[24:27], v[136:139], v[186:189], v[24:27]
	v_mfma_f32_16x16x32_bf16 v[12:15], v[128:131], v[194:197], v[12:15]
	v_mfma_f32_16x16x32_bf16 v[8:11], v[136:139], v[194:197], v[8:11]
	v_mfma_f32_16x16x32_bf16 v[60:63], v[132:135], v[174:177], v[60:63]
	v_mfma_f32_16x16x32_bf16 v[56:59], v[160:163], v[174:177], v[56:59]
	v_mfma_f32_16x16x32_bf16 v[44:47], v[132:135], v[182:185], v[44:47]
	v_mfma_f32_16x16x32_bf16 v[40:43], v[160:163], v[182:185], v[40:43]
	v_mfma_f32_16x16x32_bf16 v[28:31], v[132:135], v[190:193], v[28:31]
	v_mfma_f32_16x16x32_bf16 v[24:27], v[160:163], v[190:193], v[24:27]
	v_mfma_f32_16x16x32_bf16 v[12:15], v[132:135], v[202:205], v[12:15]
	v_mfma_f32_16x16x32_bf16 v[8:11], v[160:163], v[202:205], v[8:11]
	s_setprio 0
	s_barrier
	s_add_u32 s26, s26, 0x40080
	s_addc_u32 s27, s27, 0
	s_add_i32 s28, s28, s34
	s_mov_b32 m0, s28
	s_nop 0
	global_load_lds_dwordx4 v146, s[26:27]
	s_add_i32 m0, s28, 0x2000
	s_nop 0
	global_load_lds_dwordx4 v142, s[26:27]
	s_waitcnt vmcnt(8)
	s_setprio 1
	s_barrier
	v_mfma_f32_16x16x32_bf16 v[52:55], v[206:209], v[170:173], v[52:55]
	v_mfma_f32_16x16x32_bf16 v[48:51], v[214:217], v[170:173], v[48:51]
	v_mfma_f32_16x16x32_bf16 v[36:39], v[206:209], v[178:181], v[36:39]
	v_mfma_f32_16x16x32_bf16 v[32:35], v[214:217], v[178:181], v[32:35]
	v_mfma_f32_16x16x32_bf16 v[20:23], v[206:209], v[186:189], v[20:23]
	v_mfma_f32_16x16x32_bf16 v[16:19], v[214:217], v[186:189], v[16:19]
	v_mfma_f32_16x16x32_bf16 v[4:7], v[206:209], v[194:197], v[4:7]
	v_mfma_f32_16x16x32_bf16 v[0:3], v[214:217], v[194:197], v[0:3]
	v_mfma_f32_16x16x32_bf16 v[52:55], v[210:213], v[174:177], v[52:55]
	v_mfma_f32_16x16x32_bf16 v[48:51], v[218:221], v[174:177], v[48:51]
	v_mfma_f32_16x16x32_bf16 v[36:39], v[210:213], v[182:185], v[36:39]
	v_mfma_f32_16x16x32_bf16 v[32:35], v[218:221], v[182:185], v[32:35]
	v_mfma_f32_16x16x32_bf16 v[20:23], v[210:213], v[190:193], v[20:23]
	v_mfma_f32_16x16x32_bf16 v[16:19], v[218:221], v[190:193], v[16:19]
	v_mfma_f32_16x16x32_bf16 v[4:7], v[210:213], v[202:205], v[4:7]
	v_mfma_f32_16x16x32_bf16 v[0:3], v[218:221], v[202:205], v[0:3]
	s_setprio 0
	s_add_i32 s56, s56, 2
	s_add_u32 s6, s6, 0x100
	s_addc_u32 s7, s7, 0
	s_add_u32 s54, s54, 0x100
	s_addc_u32 s55, s55, 0
	s_cmp_gt_u32 s56, 13
	s_barrier
.LBB0_578:
	ds_read_b128 v[128:131], v167
	ds_read_b128 v[132:135], v167 offset:1024
	ds_read_b128 v[136:139], v167 offset:2048
	ds_read_b128 v[160:163], v167 offset:3072
	s_add_u32 s26, s6, 0xfffc0080
	s_addc_u32 s27, s7, -1
	s_cmp_eq_u32 s56, 12
	s_cselect_b32 s29, s5, s27
	s_cselect_b32 s28, s21, s26
	s_cselect_b32 s27, s19, s55
	s_cselect_b32 s26, s53, s54
	s_add_i32 m0, s37, 0xc000
	ds_read_b128 v[170:173], v168
	ds_read_b128 v[174:177], v168 offset:1024
	ds_read_b128 v[178:181], v168 offset:2048
	ds_read_b128 v[182:185], v168 offset:3072
	ds_read_b128 v[186:189], v168 offset:4096
	ds_read_b128 v[190:193], v168 offset:5120
	ds_read_b128 v[194:197], v168 offset:6144
	ds_read_b128 v[202:205], v168 offset:7168
	global_load_lds_dwordx4 v152, s[6:7]
	s_add_i32 m0, s37, 0xe000
	s_nop 0
	global_load_lds_dwordx4 v154, s[6:7]
	s_waitcnt lgkmcnt(8)
	s_waitcnt vmcnt(8)
	s_setprio 1
	s_barrier
	s_waitcnt lgkmcnt(0)
	v_mfma_f32_16x16x32_bf16 v[124:127], v[128:131], v[170:173], v[124:127]
	v_mfma_f32_16x16x32_bf16 v[120:123], v[136:139], v[170:173], v[120:123]
	v_mfma_f32_16x16x32_bf16 v[108:111], v[128:131], v[178:181], v[108:111]
	v_mfma_f32_16x16x32_bf16 v[104:107], v[136:139], v[178:181], v[104:107]
	v_mfma_f32_16x16x32_bf16 v[92:95], v[128:131], v[186:189], v[92:95]
	v_mfma_f32_16x16x32_bf16 v[88:91], v[136:139], v[186:189], v[88:91]
	v_mfma_f32_16x16x32_bf16 v[76:79], v[128:131], v[194:197], v[76:79]
	v_mfma_f32_16x16x32_bf16 v[72:75], v[136:139], v[194:197], v[72:75]
	v_mfma_f32_16x16x32_bf16 v[124:127], v[132:135], v[174:177], v[124:127]
	v_mfma_f32_16x16x32_bf16 v[120:123], v[160:163], v[174:177], v[120:123]
	v_mfma_f32_16x16x32_bf16 v[108:111], v[132:135], v[182:185], v[108:111]
	v_mfma_f32_16x16x32_bf16 v[104:107], v[160:163], v[182:185], v[104:107]
	v_mfma_f32_16x16x32_bf16 v[92:95], v[132:135], v[190:193], v[92:95]
	v_mfma_f32_16x16x32_bf16 v[88:91], v[160:163], v[190:193], v[88:91]
	v_mfma_f32_16x16x32_bf16 v[76:79], v[132:135], v[202:205], v[76:79]
	v_mfma_f32_16x16x32_bf16 v[72:75], v[160:163], v[202:205], v[72:75]
	s_setprio 0
	s_barrier
	s_add_i32 s57, s48, s34
	s_mov_b32 m0, s57
	ds_read_b128 v[206:209], v169
	ds_read_b128 v[210:213], v169 offset:1024
	ds_read_b128 v[214:217], v169 offset:2048
	ds_read_b128 v[218:221], v169 offset:3072
	global_load_lds_dwordx4 v146, s[26:27]
	s_add_i32 m0, s57, 0x2000
	s_nop 0
	global_load_lds_dwordx4 v142, s[26:27]
	s_waitcnt vmcnt(8)
	s_setprio 1
	s_barrier
; #define PG8_STAGE(bufoff, gbase, voff) do { _Pragma("unroll") for (int _i = 0; _i < 2; ++_i) \
;         __builtin_amdgcn_global_load_lds((const unsigned*)((const char*)(gbase) + (voff)[_i]), (LAS unsigned*)(lds + (bufoff) + ldsw + _i * 8192), 16, 0, 0); } while (0)
; #define PG8_LDA(dst, b, h) do { _Pragma("unroll") for (int m = 0; m < 4; ++m) _Pragma("unroll") for (int k = 0; k < 2; ++k) dst[m][k] = *(const LAS bf16x8*)(lds + PG8_SA(b, h) + aoff + m * 2048 + k * 1024); } while (0)
; #define PG8_LDB(dst, b, h) do { _Pragma("unroll") for (int n = 0; n < 2; ++n) _Pragma("unroll") for (int k = 0; k < 2; ++k) dst[n][k] = *(const LAS bf16x8*)(lds + PG8_SB(b, h) + boff + n * 2048 + k * 1024); } while (0)
; #define PG8_MMA(ai, bj, At, Bt) do { __builtin_amdgcn_s_setprio(1); _Pragma("unroll") for (int m = 0; m < 4; ++m) _Pragma("unroll") for (int n = 0; n < 2; ++n) _Pragma("unroll") for (int k = 0; k < 2; ++k) \
;         acc[ai][bj][m][n] = __builtin_amdgcn_mfma_f32_16x16x32_bf16(Bt[n][k], At[m][k], acc[ai][bj][m][n], 0, 0, 0); __builtin_amdgcn_s_setprio(0); } while (0)
; #define PG8_WAIT_V(n) asm volatile("s_waitcnt vmcnt(" #n ")" ::: "memory")
; #define PG8_WAIT_L(n) asm volatile("s_waitcnt lgkmcnt(" #n ")" ::: "memory")
; #define PG8_BAR __builtin_amdgcn_s_barrier()
; #define PG8_SCHED __builtin_amdgcn_sched_barrier(0)
; template <class Epi, class Sched>
; __device__ __forceinline__ void gemm_phase(LAS unsigned char* lds, const Gemm g, const Sched& S, const Epi& E) {
;     ...
;             PG8_BAR; PG8_WAIT_L(0); PG8_MMA(0, 1, At, B1); PG8_BAR;
;             PG8_LDA(At, 0, 1); PG8_STAGE(PG8_SA(0, 0), a2, voffA);
;             PG8_BAR; PG8_WAIT_L(0); PG8_MMA(1, 0, At, B0); PG8_BAR; PG8_SCHED;
;             PG8_STAGE(PG8_SB(0, 1), b2 + hstep, voffB);
;             PG8_WAIT_V(6); PG8_BAR; PG8_MMA(1, 1, At, B1); PG8_BAR;
;             PG8_LDB(B0, 1, 0); PG8_SCHED; PG8_LDA(At, 1, 0); PG8_STAGE(PG8_SA(0, 1), a2 + hstep, voffA);
;             PG8_WAIT_L(8); PG8_BAR; PG8_WAIT_L(0); PG8_MMA(0, 0, At, B0); PG8_BAR; PG8_SCHED;
	s_waitcnt lgkmcnt(0)
	v_mfma_f32_16x16x32_bf16 v[116:119], v[206:209], v[170:173], v[116:119]
	v_mfma_f32_16x16x32_bf16 v[112:115], v[214:217], v[170:173], v[112:115]
	v_mfma_f32_16x16x32_bf16 v[100:103], v[206:209], v[178:181], v[100:103]
	v_mfma_f32_16x16x32_bf16 v[96:99], v[214:217], v[178:181], v[96:99]
	v_mfma_f32_16x16x32_bf16 v[84:87], v[206:209], v[186:189], v[84:87]
	v_mfma_f32_16x16x32_bf16 v[80:83], v[214:217], v[186:189], v[80:83]
	v_mfma_f32_16x16x32_bf16 v[68:71], v[206:209], v[194:197], v[68:71]
	v_mfma_f32_16x16x32_bf16 v[64:67], v[214:217], v[194:197], v[64:67]
	v_mfma_f32_16x16x32_bf16 v[116:119], v[210:213], v[174:177], v[116:119]
	v_mfma_f32_16x16x32_bf16 v[112:115], v[218:221], v[174:177], v[112:115]
	v_mfma_f32_16x16x32_bf16 v[100:103], v[210:213], v[182:185], v[100:103]
	v_mfma_f32_16x16x32_bf16 v[96:99], v[218:221], v[182:185], v[96:99]
	v_mfma_f32_16x16x32_bf16 v[84:87], v[210:213], v[190:193], v[84:87]
	v_mfma_f32_16x16x32_bf16 v[80:83], v[218:221], v[190:193], v[80:83]
	v_mfma_f32_16x16x32_bf16 v[68:71], v[210:213], v[202:205], v[68:71]
	v_mfma_f32_16x16x32_bf16 v[64:67], v[218:221], v[202:205], v[64:67]
	s_setprio 0
	s_mov_b32 m0, s37
	v_lshl_add_u64 v[222:223], s[28:29], 0, v[148:149]
	s_barrier
	ds_read_b128 v[170:173], v168 offset:16384
	ds_read_b128 v[174:177], v168 offset:17408
	ds_read_b128 v[178:181], v168 offset:18432
	ds_read_b128 v[182:185], v168 offset:19456
	ds_read_b128 v[186:189], v168 offset:20480
	ds_read_b128 v[190:193], v168 offset:21504
	ds_read_b128 v[194:197], v168 offset:22528
	ds_read_b128 v[202:205], v168 offset:23552
	global_load_lds_dwordx4 v148, s[28:29]
	v_lshl_add_u64 v[224:225], s[28:29], 0, v[144:145]
	s_mov_b32 m0, s38
	s_nop 0
	global_load_lds_dwordx4 v144, s[28:29]
	s_setprio 1
	s_barrier
	s_waitcnt lgkmcnt(0)
	v_mfma_f32_16x16x32_bf16 v[60:63], v[128:131], v[170:173], v[60:63]
	v_mfma_f32_16x16x32_bf16 v[56:59], v[136:139], v[170:173], v[56:59]
	v_mfma_f32_16x16x32_bf16 v[44:47], v[128:131], v[178:181], v[44:47]
	v_mfma_f32_16x16x32_bf16 v[40:43], v[136:139], v[178:181], v[40:43]
	v_mfma_f32_16x16x32_bf16 v[28:31], v[128:131], v[186:189], v[28:31]
	v_mfma_f32_16x16x32_bf16 v[24:27], v[136:139], v[186:189], v[24:27]
	v_mfma_f32_16x16x32_bf16 v[12:15], v[128:131], v[194:197], v[12:15]
	v_mfma_f32_16x16x32_bf16 v[8:11], v[136:139], v[194:197], v[8:11]
	v_mfma_f32_16x16x32_bf16 v[60:63], v[132:135], v[174:177], v[60:63]
	v_mfma_f32_16x16x32_bf16 v[56:59], v[160:163], v[174:177], v[56:59]
	v_mfma_f32_16x16x32_bf16 v[44:47], v[132:135], v[182:185], v[44:47]
	v_mfma_f32_16x16x32_bf16 v[40:43], v[160:163], v[182:185], v[40:43]
	v_mfma_f32_16x16x32_bf16 v[28:31], v[132:135], v[190:193], v[28:31]
	v_mfma_f32_16x16x32_bf16 v[24:27], v[160:163], v[190:193], v[24:27]
	v_mfma_f32_16x16x32_bf16 v[12:15], v[132:135], v[202:205], v[12:15]
	v_mfma_f32_16x16x32_bf16 v[8:11], v[160:163], v[202:205], v[8:11]
	s_setprio 0
	s_barrier
	s_add_u32 s58, s26, 0x40000
	s_addc_u32 s59, s27, 0
	s_add_i32 s57, s49, s34
	s_mov_b32 m0, s57
	s_nop 0
	global_load_lds_dwordx4 v146, s[58:59]
	s_add_i32 m0, s57, 0x2000
	s_nop 0
	global_load_lds_dwordx4 v142, s[58:59]
	s_add_u32 s28, s28, 0x40000
	s_addc_u32 s29, s29, 0
	s_mov_b32 m0, s39
	s_nop 0
	global_load_lds_dwordx4 v148, s[28:29]
	s_mov_b32 m0, s40
	s_nop 0
	global_load_lds_dwordx4 v144, s[28:29]
	s_waitcnt vmcnt(10)
	s_setprio 1
	s_barrier
	v_mfma_f32_16x16x32_bf16 v[52:55], v[206:209], v[170:173], v[52:55]
	v_mfma_f32_16x16x32_bf16 v[48:51], v[214:217], v[170:173], v[48:51]
	v_mfma_f32_16x16x32_bf16 v[36:39], v[206:209], v[178:181], v[36:39]
	v_mfma_f32_16x16x32_bf16 v[32:35], v[214:217], v[178:181], v[32:35]
	v_mfma_f32_16x16x32_bf16 v[20:23], v[206:209], v[186:189], v[20:23]
	v_mfma_f32_16x16x32_bf16 v[16:19], v[214:217], v[186:189], v[16:19]
	v_mfma_f32_16x16x32_bf16 v[4:7], v[206:209], v[194:197], v[4:7]
	v_mfma_f32_16x16x32_bf16 v[0:3], v[214:217], v[194:197], v[0:3]
	v_mfma_f32_16x16x32_bf16 v[52:55], v[210:213], v[174:177], v[52:55]
	v_mfma_f32_16x16x32_bf16 v[48:51], v[218:221], v[174:177], v[48:51]
	v_mfma_f32_16x16x32_bf16 v[36:39], v[210:213], v[182:185], v[36:39]
	v_mfma_f32_16x16x32_bf16 v[32:35], v[218:221], v[182:185], v[32:35]
	v_mfma_f32_16x16x32_bf16 v[20:23], v[210:213], v[190:193], v[20:23]
	v_mfma_f32_16x16x32_bf16 v[16:19], v[218:221], v[190:193], v[16:19]
	v_mfma_f32_16x16x32_bf16 v[4:7], v[210:213], v[202:205], v[4:7]
	v_mfma_f32_16x16x32_bf16 v[0:3], v[218:221], v[202:205], v[0:3]
	s_setprio 0
	s_add_i32 s57, 0, 0x18000
	v_add_u32_e32 v150, s57, v166
	s_barrier
	ds_read_b128 v[128:131], v150
	ds_read_b128 v[132:135], v150 offset:1024
	ds_read_b128 v[136:139], v150 offset:2048
	ds_read_b128 v[160:163], v150 offset:3072
	ds_read_b128 v[170:173], v168 offset:32768
	ds_read_b128 v[174:177], v168 offset:33792
	ds_read_b128 v[178:181], v168 offset:34816
	ds_read_b128 v[182:185], v168 offset:35840
	ds_read_b128 v[186:189], v168 offset:36864
	ds_read_b128 v[190:193], v168 offset:37888
	ds_read_b128 v[194:197], v168 offset:38912
	ds_read_b128 v[202:205], v168 offset:39936
	s_waitcnt lgkmcnt(8)
	s_waitcnt vmcnt(8)
	s_setprio 1
	s_barrier
; #define PG8_STAGE(bufoff, gbase, voff) do { _Pragma("unroll") for (int _i = 0; _i < 2; ++_i) \
;         __builtin_amdgcn_global_load_lds((const unsigned*)((const char*)(gbase) + (voff)[_i]), (LAS unsigned*)(lds + (bufoff) + ldsw + _i * 8192), 16, 0, 0); } while (0)
; #define PG8_LDA(dst, b, h) do { _Pragma("unroll") for (int m = 0; m < 4; ++m) _Pragma("unroll") for (int k = 0; k < 2; ++k) dst[m][k] = *(const LAS bf16x8*)(lds + PG8_SA(b, h) + aoff + m * 2048 + k * 1024); } while (0)
; #define PG8_LDB(dst, b, h) do { _Pragma("unroll") for (int n = 0; n < 2; ++n) _Pragma("unroll") for (int k = 0; k < 2; ++k) dst[n][k] = *(const LAS bf16x8*)(lds + PG8_SB(b, h) + boff + n * 2048 + k * 1024); } while (0)
; #define PG8_MMA(ai, bj, At, Bt) do { __builtin_amdgcn_s_setprio(1); _Pragma("unroll") for (int m = 0; m < 4; ++m) _Pragma("unroll") for (int n = 0; n < 2; ++n) _Pragma("unroll") for (int k = 0; k < 2; ++k) \
;         acc[ai][bj][m][n] = __builtin_amdgcn_mfma_f32_16x16x32_bf16(Bt[n][k], At[m][k], acc[ai][bj][m][n], 0, 0, 0); __builtin_amdgcn_s_setprio(0); } while (0)
; #define PG8_WAIT_L(n) asm volatile("s_waitcnt lgkmcnt(" #n ")" ::: "memory")
; #define PG8_BAR __builtin_amdgcn_s_barrier()
; #define PG8_SCHED __builtin_amdgcn_sched_barrier(0)
; template <class Epi, class Sched>
; __device__ __forceinline__ void gemm_phase(LAS unsigned char* lds, const Gemm g, const Sched& S, const Epi& E) {
;     ...
;             PG8_WAIT_L(8); PG8_BAR; PG8_WAIT_L(0); PG8_MMA(0, 0, At, B0); PG8_BAR; PG8_SCHED;
;             PG8_LDB(B1, 1, 1); PG8_STAGE(PG8_SB(1, 0), b3, voffB);
;             PG8_BAR; PG8_WAIT_L(0); PG8_MMA(0, 1, At, B1); PG8_BAR;
;             PG8_LDA(At, 1, 1); PG8_STAGE(PG8_SA(1, 0), a3, voffA);
;             PG8_BAR; PG8_WAIT_L(0); PG8_MMA(1, 0, At, B0); PG8_BAR; PG8_SCHED;
	s_waitcnt lgkmcnt(0)
	v_mfma_f32_16x16x32_bf16 v[124:127], v[128:131], v[170:173], v[124:127]
	v_mfma_f32_16x16x32_bf16 v[120:123], v[136:139], v[170:173], v[120:123]
	v_mfma_f32_16x16x32_bf16 v[108:111], v[128:131], v[178:181], v[108:111]
	v_mfma_f32_16x16x32_bf16 v[104:107], v[136:139], v[178:181], v[104:107]
	v_mfma_f32_16x16x32_bf16 v[92:95], v[128:131], v[186:189], v[92:95]
	v_mfma_f32_16x16x32_bf16 v[88:91], v[136:139], v[186:189], v[88:91]
	v_mfma_f32_16x16x32_bf16 v[76:79], v[128:131], v[194:197], v[76:79]
	v_mfma_f32_16x16x32_bf16 v[72:75], v[136:139], v[194:197], v[72:75]
	v_mfma_f32_16x16x32_bf16 v[124:127], v[132:135], v[174:177], v[124:127]
	v_mfma_f32_16x16x32_bf16 v[120:123], v[160:163], v[174:177], v[120:123]
	v_mfma_f32_16x16x32_bf16 v[108:111], v[132:135], v[182:185], v[108:111]
	v_mfma_f32_16x16x32_bf16 v[104:107], v[160:163], v[182:185], v[104:107]
	v_mfma_f32_16x16x32_bf16 v[92:95], v[132:135], v[190:193], v[92:95]
	v_mfma_f32_16x16x32_bf16 v[88:91], v[160:163], v[190:193], v[88:91]
	v_mfma_f32_16x16x32_bf16 v[76:79], v[132:135], v[202:205], v[76:79]
	v_mfma_f32_16x16x32_bf16 v[72:75], v[160:163], v[202:205], v[72:75]
	s_setprio 0
	s_barrier
	s_add_i32 s28, 0, 0x1c000
	s_add_i32 s29, s57, s34
	v_add_u32_e32 v150, s28, v166
	s_add_u32 s0, s26, 0x80
	s_addc_u32 s1, s27, 0
	s_mov_b32 m0, s29
	ds_read_b128 v[206:209], v150
	ds_read_b128 v[210:213], v150 offset:1024
	ds_read_b128 v[214:217], v150 offset:2048
	ds_read_b128 v[218:221], v150 offset:3072
	global_load_lds_dwordx4 v146, s[0:1]
	s_add_i32 m0, s29, 0x2000
	s_nop 0
	global_load_lds_dwordx4 v142, s[0:1]
	s_waitcnt vmcnt(8)
	s_setprio 1
	s_barrier
	s_waitcnt lgkmcnt(0)
	v_mfma_f32_16x16x32_bf16 v[116:119], v[206:209], v[170:173], v[116:119]
	v_mfma_f32_16x16x32_bf16 v[112:115], v[214:217], v[170:173], v[112:115]
	v_mfma_f32_16x16x32_bf16 v[100:103], v[206:209], v[178:181], v[100:103]
	v_mfma_f32_16x16x32_bf16 v[96:99], v[214:217], v[178:181], v[96:99]
	v_mfma_f32_16x16x32_bf16 v[84:87], v[206:209], v[186:189], v[84:87]
	v_mfma_f32_16x16x32_bf16 v[80:83], v[214:217], v[186:189], v[80:83]
	v_mfma_f32_16x16x32_bf16 v[68:71], v[206:209], v[194:197], v[68:71]
	v_mfma_f32_16x16x32_bf16 v[64:67], v[214:217], v[194:197], v[64:67]
	v_mfma_f32_16x16x32_bf16 v[116:119], v[210:213], v[174:177], v[116:119]
	v_mfma_f32_16x16x32_bf16 v[112:115], v[218:221], v[174:177], v[112:115]
	v_mfma_f32_16x16x32_bf16 v[100:103], v[210:213], v[182:185], v[100:103]
	v_mfma_f32_16x16x32_bf16 v[96:99], v[218:221], v[182:185], v[96:99]
	v_mfma_f32_16x16x32_bf16 v[84:87], v[210:213], v[190:193], v[84:87]
	v_mfma_f32_16x16x32_bf16 v[80:83], v[218:221], v[190:193], v[80:83]
	v_mfma_f32_16x16x32_bf16 v[68:71], v[210:213], v[202:205], v[68:71]
	v_mfma_f32_16x16x32_bf16 v[64:67], v[218:221], v[202:205], v[64:67]
	s_setprio 0
	s_mov_b32 m0, s44
	s_mov_b64 s[0:1], 0x80
	v_lshl_add_u64 v[140:141], v[222:223], 0, s[0:1]
	s_barrier
	ds_read_b128 v[170:173], v168 offset:49152
	ds_read_b128 v[174:177], v168 offset:50176
	ds_read_b128 v[178:181], v168 offset:51200
	ds_read_b128 v[182:185], v168 offset:52224
	ds_read_b128 v[186:189], v168 offset:53248
	ds_read_b128 v[190:193], v168 offset:54272
	ds_read_b128 v[194:197], v168 offset:55296
	ds_read_b128 v[202:205], v168 offset:56320
	global_load_lds_dwordx4 v[140:141], off
	v_lshl_add_u64 v[140:141], v[224:225], 0, s[0:1]
	s_mov_b32 m0, s45
	s_nop 0
	global_load_lds_dwordx4 v[140:141], off
	s_setprio 1
	s_barrier
; #define PG8_STAGE(bufoff, gbase, voff) do { _Pragma("unroll") for (int _i = 0; _i < 2; ++_i) \
;         __builtin_amdgcn_global_load_lds((const unsigned*)((const char*)(gbase) + (voff)[_i]), (LAS unsigned*)(lds + (bufoff) + ldsw + _i * 8192), 16, 0, 0); } while (0)
; #define PG8_MMA(ai, bj, At, Bt) do { __builtin_amdgcn_s_setprio(1); _Pragma("unroll") for (int m = 0; m < 4; ++m) _Pragma("unroll") for (int n = 0; n < 2; ++n) _Pragma("unroll") for (int k = 0; k < 2; ++k) \
;         acc[ai][bj][m][n] = __builtin_amdgcn_mfma_f32_16x16x32_bf16(Bt[n][k], At[m][k], acc[ai][bj][m][n], 0, 0, 0); __builtin_amdgcn_s_setprio(0); } while (0)
; #define PG8_WAIT_V(n) asm volatile("s_waitcnt vmcnt(" #n ")" ::: "memory")
; #define PG8_BAR __builtin_amdgcn_s_barrier()
; template <class Epi, class Sched>
; __device__ __forceinline__ void gemm_phase(LAS unsigned char* lds, const Gemm g, const Sched& S, const Epi& E) {
;     ...
;             PG8_STAGE(PG8_SB(1, 1), b3 + hstep, voffB);
;             PG8_WAIT_V(6); PG8_BAR; PG8_MMA(1, 1, At, B1); PG8_BAR;
;     __device__ __forceinline__ void operator()(const AccT& acc, const Unit& u, int wr, int wc, int fr, int fq) const {
;         asm volatile("" : "+v"(fr), "+v"(fq));
;         const int row0 = u.pm * 256 + wr * 64 + fr, col0 = u.pn * 256 + wc * 32 + 8 * fq;
;         const bool rope = u.pn < 2;
;         const int i = 4 * (wc & 1) + fq;
; #pragma unroll
;         for (int ai = 0; ai < 2; ++ai)
; #pragma unroll
;             for (int m = 0; m < 4; ++m) {
;                 const int row = row0 + ai * 128 + m * 16;
;                 f32x4 cs = {1.f, 1.f, 1.f, 1.f}, sn = {0.f, 0.f, 0.f, 0.f};
;                 if (rope) { const int t = row & 2047; const int pos = (i < 4) ? (t >> 6) : (t & 63);
;                     cs = *(const f32x4*)(ropeA + pos * 16 + ((4 * i) & 15)); sn = *(const f32x4*)(ropeA + 1024 + pos * 16 + ((4 * i) & 15)); }
	s_waitcnt lgkmcnt(0)
	v_mfma_f32_16x16x32_bf16 v[60:63], v[128:131], v[170:173], v[60:63]
	v_mfma_f32_16x16x32_bf16 v[56:59], v[136:139], v[170:173], v[56:59]
	v_mfma_f32_16x16x32_bf16 v[44:47], v[128:131], v[178:181], v[44:47]
	v_mfma_f32_16x16x32_bf16 v[40:43], v[136:139], v[178:181], v[40:43]
	v_mfma_f32_16x16x32_bf16 v[28:31], v[128:131], v[186:189], v[28:31]
	v_mfma_f32_16x16x32_bf16 v[24:27], v[136:139], v[186:189], v[24:27]
	v_mfma_f32_16x16x32_bf16 v[12:15], v[128:131], v[194:197], v[12:15]
	v_mfma_f32_16x16x32_bf16 v[8:11], v[136:139], v[194:197], v[8:11]
	v_mfma_f32_16x16x32_bf16 v[60:63], v[132:135], v[174:177], v[60:63]
	v_mfma_f32_16x16x32_bf16 v[56:59], v[160:163], v[174:177], v[56:59]
	v_mfma_f32_16x16x32_bf16 v[44:47], v[132:135], v[182:185], v[44:47]
	v_mfma_f32_16x16x32_bf16 v[40:43], v[160:163], v[182:185], v[40:43]
	v_mfma_f32_16x16x32_bf16 v[28:31], v[132:135], v[190:193], v[28:31]
	v_mfma_f32_16x16x32_bf16 v[24:27], v[160:163], v[190:193], v[24:27]
	v_mfma_f32_16x16x32_bf16 v[12:15], v[132:135], v[202:205], v[12:15]
	v_mfma_f32_16x16x32_bf16 v[8:11], v[160:163], v[202:205], v[8:11]
	s_setprio 0
	s_barrier
	s_add_u32 s26, s26, 0x40080
	s_addc_u32 s27, s27, 0
	s_add_i32 s28, s28, s34
	s_mov_b32 m0, s28
	s_nop 0
	global_load_lds_dwordx4 v146, s[26:27]
	s_add_i32 m0, s28, 0x2000
	s_nop 0
	global_load_lds_dwordx4 v142, s[26:27]
	s_waitcnt vmcnt(8)
	s_setprio 1
	s_barrier
	v_mfma_f32_16x16x32_bf16 v[52:55], v[206:209], v[170:173], v[52:55]
	v_mfma_f32_16x16x32_bf16 v[48:51], v[214:217], v[170:173], v[48:51]
	v_mfma_f32_16x16x32_bf16 v[36:39], v[206:209], v[178:181], v[36:39]
	v_mfma_f32_16x16x32_bf16 v[32:35], v[214:217], v[178:181], v[32:35]
	v_mfma_f32_16x16x32_bf16 v[20:23], v[206:209], v[186:189], v[20:23]
	v_mfma_f32_16x16x32_bf16 v[16:19], v[214:217], v[186:189], v[16:19]
	v_mfma_f32_16x16x32_bf16 v[4:7], v[206:209], v[194:197], v[4:7]
	v_mfma_f32_16x16x32_bf16 v[0:3], v[214:217], v[194:197], v[0:3]
	v_mfma_f32_16x16x32_bf16 v[52:55], v[210:213], v[174:177], v[52:55]
	v_mfma_f32_16x16x32_bf16 v[48:51], v[218:221], v[174:177], v[48:51]
	v_mfma_f32_16x16x32_bf16 v[36:39], v[210:213], v[182:185], v[36:39]
	v_mfma_f32_16x16x32_bf16 v[32:35], v[218:221], v[182:185], v[32:35]
	v_mfma_f32_16x16x32_bf16 v[20:23], v[210:213], v[190:193], v[20:23]
	v_mfma_f32_16x16x32_bf16 v[16:19], v[218:221], v[190:193], v[16:19]
	v_mfma_f32_16x16x32_bf16 v[4:7], v[210:213], v[202:205], v[4:7]
	v_mfma_f32_16x16x32_bf16 v[0:3], v[218:221], v[202:205], v[0:3]
	s_setprio 0
	s_add_i32 s56, s56, 2
	s_add_u32 s6, s6, 0x100
	s_addc_u32 s7, s7, 0
	s_add_u32 s54, s54, 0x100
	s_addc_u32 s55, s55, 0
	s_cmp_gt_u32 s56, 13
	s_barrier
	s_cbranch_scc0 .LBB0_578
	v_mov_b32_e32 v129, v165
	v_mov_b32_e32 v173, v164
	s_lshl_b32 s4, s4, 8
	s_add_i32 s4, s4, s42
	v_add_u32_e32 v128, s46, v129
	v_add_u32_e32 v170, s4, v173
	v_cmp_gt_i32_e64 s[4:5], 4, v128
	v_lshlrev_b32_e32 v128, 2, v128
	s_cmp_lt_i32 s52, 2
	v_and_b32_e32 v130, 12, v128
	s_cselect_b64 s[26:27], -1, 0
	s_cmp_gt_i32 s52, 1
	v_and_b32_e32 v172, 63, v173
	v_mov_b32_e32 v128, 1.0
	v_mov_b32_e32 v132, 0
	v_lshlrev_b32_e32 v162, 2, v130
	v_mov_b32_e32 v134, 0
	v_mov_b32_e32 v135, 0
	v_mov_b32_e32 v136, 0
	v_mov_b32_e32 v137, 0
	v_mov_b32_e32 v138, 1.0
	v_mov_b32_e32 v139, 1.0
	v_mov_b32_e32 v140, 1.0
	v_mov_b32_e32 v141, 1.0
	s_cbranch_scc1 .LBB0_581
	v_bfe_u32 v130, v170, 6, 5
	v_cndmask_b32_e64 v130, v172, v130, s[4:5]
	v_lshlrev_b32_e32 v150, 6, v130
	v_lshl_add_u64 v[130:131], s[16:17], 0, v[150:151]
	v_mov_b32_e32 v163, v151
	v_lshl_add_u64 v[134:135], s[8:9], 0, v[150:151]
	v_lshl_add_u64 v[130:131], v[130:131], 0, v[162:163]
	v_lshl_add_u64 v[134:135], v[134:135], 0, v[162:163]
	global_load_dwordx4 v[138:141], v[130:131], off
	s_nop 0
	global_load_dwordx4 v[134:137], v[134:135], off
	s_waitcnt vmcnt(0)

; #define PG8_STAGE(bufoff, gbase, voff) do { _Pragma("unroll") for (int _i = 0; _i < 2; ++_i) \
;         __builtin_amdgcn_global_load_lds((const unsigned*)((const char*)(gbase) + (voff)[_i]), (LAS unsigned*)(lds + (bufoff) + ldsw + _i * 8192), 16, 0, 0); } while (0)
; #define PG8_LDA(dst, b, h) do { _Pragma("unroll") for (int m = 0; m < 4; ++m) _Pragma("unroll") for (int k = 0; k < 2; ++k) dst[m][k] = *(const LAS bf16x8*)(lds + PG8_SA(b, h) + aoff + m * 2048 + k * 1024); } while (0)
; #define PG8_LDB(dst, b, h) do { _Pragma("unroll") for (int n = 0; n < 2; ++n) _Pragma("unroll") for (int k = 0; k < 2; ++k) dst[n][k] = *(const LAS bf16x8*)(lds + PG8_SB(b, h) + boff + n * 2048 + k * 1024); } while (0)
; #define PG8_MMA(ai, bj, At, Bt) do { __builtin_amdgcn_s_setprio(1); _Pragma("unroll") for (int m = 0; m < 4; ++m) _Pragma("unroll") for (int n = 0; n < 2; ++n) _Pragma("unroll") for (int k = 0; k < 2; ++k) \
;         acc[ai][bj][m][n] = __builtin_amdgcn_mfma_f32_16x16x32_bf16(Bt[n][k], At[m][k], acc[ai][bj][m][n], 0, 0, 0); __builtin_amdgcn_s_setprio(0); } while (0)
; #define PG8_WAIT_L(n) asm volatile("s_waitcnt lgkmcnt(" #n ")" ::: "memory")
; template <class Epi, class Sched>
; __device__ __forceinline__ void gemm_phase(LAS unsigned char* lds, const Gemm g, const Sched& S, const Epi& E) {
;     ...
;         const bool has_next = S.next(ui + 1, nxt);
;         const char* nA = has_next ? (const char*)g.A + (size_t)nxt.pm * tstep : cA; const char* nB = has_next ? (const char*)g.Bt + (size_t)nxt.pn * tstep : cB;
;         for (int t = 0; t < nt; t += 2) {
;             const bool last = (t == nt - 2);
;             const char* a1 = cA + (size_t)(t + 1) * kstep;
;             const char* a2 = last ? nA : cA + (size_t)(t + 2) * kstep; const char* b2 = last ? nB : cB + (size_t)(t + 2) * kstep;
;             const char* a3 = a2 + kstep; const char* b3 = b2 + kstep;
;             PG8_LDB(B0, 0, 0); PG8_SCHED; PG8_LDA(At, 0, 0); PG8_STAGE(PG8_SA(1, 1), a1 + hstep, voffA);
;             PG8_WAIT_L(8); PG8_BAR; PG8_WAIT_L(0); PG8_MMA(0, 0, At, B0); PG8_BAR; PG8_SCHED;
;             PG8_LDB(B1, 0, 1); PG8_STAGE(PG8_SB(0, 0), b2, voffB);
;             PG8_BAR; PG8_WAIT_L(0); PG8_MMA(0, 1, At, B1); PG8_BAR;
;             PG8_LDA(At, 0, 1); PG8_STAGE(PG8_SA(0, 0), a2, voffA);
;             PG8_BAR; PG8_WAIT_L(0); PG8_MMA(1, 0, At, B0); PG8_BAR; PG8_SCHED;
.LBB0_612:
	s_ashr_i32 s35, s34, 31
	v_cmp_lt_i64_e32 vcc, s[6:7], v[142:143]
	s_lshl_b64 s[6:7], s[34:35], 19
	s_add_u32 s36, s40, s6
	s_addc_u32 s37, s41, s7
	s_and_b64 s[6:7], vcc, exec
	s_cselect_b32 s8, s37, s1
	s_cselect_b32 s9, s36, s0
	s_ashr_i32 s31, s30, 31
	s_lshl_b64 s[6:7], s[30:31], 19
	s_add_u32 s38, s96, s6
	s_addc_u32 s39, s97, s7
	s_and_b64 s[6:7], vcc, exec
	s_cselect_b32 s31, s39, s5
	s_cselect_b32 s35, s38, s4
	s_add_u32 s0, s0, 0x40080
	s_addc_u32 s1, s1, 0
	s_add_u32 s65, s4, 0x100
	s_addc_u32 s66, s5, 0
	s_mov_b32 s67, -2
	s_waitcnt lgkmcnt(0)
	ds_read_b128 v[146:149], v171
	ds_read_b128 v[150:153], v171 offset:1024
	ds_read_b128 v[154:157], v171 offset:2048
	ds_read_b128 v[158:161], v171 offset:3072
	s_add_u32 s4, s0, 0xfffc0080
	s_addc_u32 s5, s1, -1
	s_cmp_eq_u32 s67, 12
	s_cselect_b32 s7, s8, s5
	s_cselect_b32 s6, s9, s4
	s_cselect_b32 s5, s31, s66
	s_cselect_b32 s4, s35, s65
	s_add_i32 m0, s45, 0xc000
	ds_read_b128 v[162:165], v172
	ds_read_b128 v[178:181], v172 offset:1024
	ds_read_b128 v[182:185], v172 offset:2048
	ds_read_b128 v[186:189], v172 offset:3072
	ds_read_b128 v[190:193], v172 offset:4096
	ds_read_b128 v[194:197], v172 offset:5120
	ds_read_b128 v[202:205], v172 offset:6144
	ds_read_b128 v[206:209], v172 offset:7168
	global_load_lds_dwordx4 v138, s[0:1]
	s_add_i32 m0, s45, 0xe000
	s_nop 0
	global_load_lds_dwordx4 v140, s[0:1]
	s_waitcnt lgkmcnt(8)
	s_waitcnt vmcnt(8)
	s_setprio 1
	s_barrier
	s_waitcnt lgkmcnt(0)
	v_mfma_f32_16x16x32_bf16 v[124:127], v[146:149], v[162:165], 0
	v_mfma_f32_16x16x32_bf16 v[120:123], v[154:157], v[162:165], 0
	v_mfma_f32_16x16x32_bf16 v[108:111], v[146:149], v[182:185], 0
	v_mfma_f32_16x16x32_bf16 v[104:107], v[154:157], v[182:185], 0
	v_mfma_f32_16x16x32_bf16 v[92:95], v[146:149], v[190:193], 0
	v_mfma_f32_16x16x32_bf16 v[88:91], v[154:157], v[190:193], 0
	v_mfma_f32_16x16x32_bf16 v[76:79], v[146:149], v[202:205], 0
	v_mfma_f32_16x16x32_bf16 v[72:75], v[154:157], v[202:205], 0
	v_mfma_f32_16x16x32_bf16 v[124:127], v[150:153], v[178:181], v[124:127]
	v_mfma_f32_16x16x32_bf16 v[120:123], v[158:161], v[178:181], v[120:123]
	v_mfma_f32_16x16x32_bf16 v[108:111], v[150:153], v[186:189], v[108:111]
	v_mfma_f32_16x16x32_bf16 v[104:107], v[158:161], v[186:189], v[104:107]
	v_mfma_f32_16x16x32_bf16 v[92:95], v[150:153], v[194:197], v[92:95]
	v_mfma_f32_16x16x32_bf16 v[88:91], v[158:161], v[194:197], v[88:91]
	v_mfma_f32_16x16x32_bf16 v[76:79], v[150:153], v[206:209], v[76:79]
	v_mfma_f32_16x16x32_bf16 v[72:75], v[158:161], v[206:209], v[72:75]
	s_setprio 0
	s_barrier
	s_add_i32 s68, s57, s44
	s_mov_b32 m0, s68
	ds_read_b128 v[210:213], v173
	ds_read_b128 v[214:217], v173 offset:1024
	ds_read_b128 v[218:221], v173 offset:2048
	ds_read_b128 v[222:225], v173 offset:3072
	global_load_lds_dwordx4 v130, s[4:5]
	s_add_i32 m0, s68, 0x2000
	s_nop 0
	global_load_lds_dwordx4 v134, s[4:5]
	s_waitcnt vmcnt(8)
	s_setprio 1
	s_barrier
	s_waitcnt lgkmcnt(0)
	v_mfma_f32_16x16x32_bf16 v[116:119], v[210:213], v[162:165], 0
	v_mfma_f32_16x16x32_bf16 v[112:115], v[218:221], v[162:165], 0
	v_mfma_f32_16x16x32_bf16 v[100:103], v[210:213], v[182:185], 0
	v_mfma_f32_16x16x32_bf16 v[96:99], v[218:221], v[182:185], 0
	v_mfma_f32_16x16x32_bf16 v[84:87], v[210:213], v[190:193], 0
	v_mfma_f32_16x16x32_bf16 v[80:83], v[218:221], v[190:193], 0
	v_mfma_f32_16x16x32_bf16 v[68:71], v[210:213], v[202:205], 0
	v_mfma_f32_16x16x32_bf16 v[64:67], v[218:221], v[202:205], 0
	v_mfma_f32_16x16x32_bf16 v[116:119], v[214:217], v[178:181], v[116:119]
	v_mfma_f32_16x16x32_bf16 v[112:115], v[222:225], v[178:181], v[112:115]
	v_mfma_f32_16x16x32_bf16 v[100:103], v[214:217], v[186:189], v[100:103]
	v_mfma_f32_16x16x32_bf16 v[96:99], v[222:225], v[186:189], v[96:99]
	v_mfma_f32_16x16x32_bf16 v[84:87], v[214:217], v[194:197], v[84:87]
	v_mfma_f32_16x16x32_bf16 v[80:83], v[222:225], v[194:197], v[80:83]
	v_mfma_f32_16x16x32_bf16 v[68:71], v[214:217], v[206:209], v[68:71]
	v_mfma_f32_16x16x32_bf16 v[64:67], v[222:225], v[206:209], v[64:67]
	s_setprio 0
	s_mov_b32 m0, s45
	v_lshl_add_u64 v[226:227], s[6:7], 0, v[128:129]
	s_barrier
	ds_read_b128 v[162:165], v172 offset:16384
	ds_read_b128 v[178:181], v172 offset:17408
	ds_read_b128 v[182:185], v172 offset:18432
	ds_read_b128 v[186:189], v172 offset:19456
	ds_read_b128 v[190:193], v172 offset:20480
	ds_read_b128 v[194:197], v172 offset:21504
	ds_read_b128 v[202:205], v172 offset:22528
	ds_read_b128 v[206:209], v172 offset:23552
	global_load_lds_dwordx4 v128, s[6:7]
	v_lshl_add_u64 v[228:229], s[6:7], 0, v[132:133]
	s_mov_b32 m0, s46
	s_nop 0
	global_load_lds_dwordx4 v132, s[6:7]
	s_setprio 1
	s_barrier
	s_waitcnt lgkmcnt(0)
	v_mfma_f32_16x16x32_bf16 v[60:63], v[146:149], v[162:165], 0
	v_mfma_f32_16x16x32_bf16 v[56:59], v[154:157], v[162:165], 0
	v_mfma_f32_16x16x32_bf16 v[44:47], v[146:149], v[182:185], 0
	v_mfma_f32_16x16x32_bf16 v[40:43], v[154:157], v[182:185], 0
	v_mfma_f32_16x16x32_bf16 v[28:31], v[146:149], v[190:193], 0
	v_mfma_f32_16x16x32_bf16 v[24:27], v[154:157], v[190:193], 0
	v_mfma_f32_16x16x32_bf16 v[12:15], v[146:149], v[202:205], 0
	v_mfma_f32_16x16x32_bf16 v[8:11], v[154:157], v[202:205], 0
	v_mfma_f32_16x16x32_bf16 v[60:63], v[150:153], v[178:181], v[60:63]
	v_mfma_f32_16x16x32_bf16 v[56:59], v[158:161], v[178:181], v[56:59]
	v_mfma_f32_16x16x32_bf16 v[44:47], v[150:153], v[186:189], v[44:47]
	v_mfma_f32_16x16x32_bf16 v[40:43], v[158:161], v[186:189], v[40:43]
	v_mfma_f32_16x16x32_bf16 v[28:31], v[150:153], v[194:197], v[28:31]
	v_mfma_f32_16x16x32_bf16 v[24:27], v[158:161], v[194:197], v[24:27]
	v_mfma_f32_16x16x32_bf16 v[12:15], v[150:153], v[206:209], v[12:15]
	v_mfma_f32_16x16x32_bf16 v[8:11], v[158:161], v[206:209], v[8:11]
	s_setprio 0
	s_barrier
; #define PG8_STAGE(bufoff, gbase, voff) do { _Pragma("unroll") for (int _i = 0; _i < 2; ++_i) \
;         __builtin_amdgcn_global_load_lds((const unsigned*)((const char*)(gbase) + (voff)[_i]), (LAS unsigned*)(lds + (bufoff) + ldsw + _i * 8192), 16, 0, 0); } while (0)
; #define PG8_LDA(dst, b, h) do { _Pragma("unroll") for (int m = 0; m < 4; ++m) _Pragma("unroll") for (int k = 0; k < 2; ++k) dst[m][k] = *(const LAS bf16x8*)(lds + PG8_SA(b, h) + aoff + m * 2048 + k * 1024); } while (0)
; #define PG8_LDB(dst, b, h) do { _Pragma("unroll") for (int n = 0; n < 2; ++n) _Pragma("unroll") for (int k = 0; k < 2; ++k) dst[n][k] = *(const LAS bf16x8*)(lds + PG8_SB(b, h) + boff + n * 2048 + k * 1024); } while (0)
; #define PG8_MMA(ai, bj, At, Bt) do { __builtin_amdgcn_s_setprio(1); _Pragma("unroll") for (int m = 0; m < 4; ++m) _Pragma("unroll") for (int n = 0; n < 2; ++n) _Pragma("unroll") for (int k = 0; k < 2; ++k) \
;         acc[ai][bj][m][n] = __builtin_amdgcn_mfma_f32_16x16x32_bf16(Bt[n][k], At[m][k], acc[ai][bj][m][n], 0, 0, 0); __builtin_amdgcn_s_setprio(0); } while (0)
; #define PG8_WAIT_V(n) asm volatile("s_waitcnt vmcnt(" #n ")" ::: "memory")
; #define PG8_WAIT_L(n) asm volatile("s_waitcnt lgkmcnt(" #n ")" ::: "memory")
; #define PG8_BAR __builtin_amdgcn_s_barrier()
; #define PG8_SCHED __builtin_amdgcn_sched_barrier(0)
; template <class Epi, class Sched>
; __device__ __forceinline__ void gemm_phase(LAS unsigned char* lds, const Gemm g, const Sched& S, const Epi& E) {
;     ...
;             PG8_STAGE(PG8_SB(0, 1), b2 + hstep, voffB);
;             PG8_WAIT_V(6); PG8_BAR; PG8_MMA(1, 1, At, B1); PG8_BAR;
;             PG8_LDB(B0, 1, 0); PG8_SCHED; PG8_LDA(At, 1, 0); PG8_STAGE(PG8_SA(0, 1), a2 + hstep, voffA);
;             PG8_WAIT_L(8); PG8_BAR; PG8_WAIT_L(0); PG8_MMA(0, 0, At, B0); PG8_BAR; PG8_SCHED;
;             PG8_LDB(B1, 1, 1); PG8_STAGE(PG8_SB(1, 0), b3, voffB);
;             PG8_BAR; PG8_WAIT_L(0); PG8_MMA(0, 1, At, B1); PG8_BAR;
;             PG8_LDA(At, 1, 1); PG8_STAGE(PG8_SA(1, 0), a3, voffA);
;             PG8_BAR; PG8_WAIT_L(0); PG8_MMA(1, 0, At, B0); PG8_BAR; PG8_SCHED;
	s_add_u32 s68, s4, 0x40000
	s_addc_u32 s69, s5, 0
	s_add_i32 s70, s58, s44
	s_mov_b32 m0, s70
	s_nop 0
	global_load_lds_dwordx4 v130, s[68:69]
	s_add_i32 m0, s70, 0x2000
	s_nop 0
	global_load_lds_dwordx4 v134, s[68:69]
	s_add_u32 s6, s6, 0x40000
	s_addc_u32 s7, s7, 0
	s_mov_b32 m0, s47
	s_nop 0
	global_load_lds_dwordx4 v128, s[6:7]
	s_mov_b32 m0, s48
	s_nop 0
	global_load_lds_dwordx4 v132, s[6:7]
	s_waitcnt vmcnt(10)
	s_setprio 1
	s_barrier
	v_mfma_f32_16x16x32_bf16 v[52:55], v[210:213], v[162:165], 0
	v_mfma_f32_16x16x32_bf16 v[48:51], v[218:221], v[162:165], 0
	v_mfma_f32_16x16x32_bf16 v[36:39], v[210:213], v[182:185], 0
	v_mfma_f32_16x16x32_bf16 v[32:35], v[218:221], v[182:185], 0
	v_mfma_f32_16x16x32_bf16 v[20:23], v[210:213], v[190:193], 0
	v_mfma_f32_16x16x32_bf16 v[16:19], v[218:221], v[190:193], 0
	v_mfma_f32_16x16x32_bf16 v[4:7], v[210:213], v[202:205], 0
	v_mfma_f32_16x16x32_bf16 v[0:3], v[218:221], v[202:205], 0
	v_mfma_f32_16x16x32_bf16 v[52:55], v[214:217], v[178:181], v[52:55]
	v_mfma_f32_16x16x32_bf16 v[48:51], v[222:225], v[178:181], v[48:51]
	v_mfma_f32_16x16x32_bf16 v[36:39], v[214:217], v[186:189], v[36:39]
	v_mfma_f32_16x16x32_bf16 v[32:35], v[222:225], v[186:189], v[32:35]
	v_mfma_f32_16x16x32_bf16 v[20:23], v[214:217], v[194:197], v[20:23]
	v_mfma_f32_16x16x32_bf16 v[16:19], v[222:225], v[194:197], v[16:19]
	v_mfma_f32_16x16x32_bf16 v[4:7], v[214:217], v[206:209], v[4:7]
	v_mfma_f32_16x16x32_bf16 v[0:3], v[222:225], v[206:209], v[0:3]
	s_setprio 0
	s_add_i32 s68, 0, 0x18000
	v_add_u32_e32 v136, s68, v170
	s_barrier
	ds_read_b128 v[146:149], v136
	ds_read_b128 v[150:153], v136 offset:1024
	ds_read_b128 v[154:157], v136 offset:2048
	ds_read_b128 v[158:161], v136 offset:3072
	ds_read_b128 v[162:165], v172 offset:32768
	ds_read_b128 v[178:181], v172 offset:33792
	ds_read_b128 v[182:185], v172 offset:34816
	ds_read_b128 v[186:189], v172 offset:35840
	ds_read_b128 v[190:193], v172 offset:36864
	ds_read_b128 v[194:197], v172 offset:37888
	ds_read_b128 v[202:205], v172 offset:38912
	ds_read_b128 v[206:209], v172 offset:39936
	s_waitcnt lgkmcnt(8)
	s_waitcnt vmcnt(8)
	s_setprio 1
	s_barrier
	s_waitcnt lgkmcnt(0)
	v_mfma_f32_16x16x32_bf16 v[124:127], v[146:149], v[162:165], v[124:127]
	v_mfma_f32_16x16x32_bf16 v[120:123], v[154:157], v[162:165], v[120:123]
	v_mfma_f32_16x16x32_bf16 v[108:111], v[146:149], v[182:185], v[108:111]
	v_mfma_f32_16x16x32_bf16 v[104:107], v[154:157], v[182:185], v[104:107]
	v_mfma_f32_16x16x32_bf16 v[92:95], v[146:149], v[190:193], v[92:95]
	v_mfma_f32_16x16x32_bf16 v[88:91], v[154:157], v[190:193], v[88:91]
	v_mfma_f32_16x16x32_bf16 v[76:79], v[146:149], v[202:205], v[76:79]
	v_mfma_f32_16x16x32_bf16 v[72:75], v[154:157], v[202:205], v[72:75]
	v_mfma_f32_16x16x32_bf16 v[124:127], v[150:153], v[178:181], v[124:127]
	v_mfma_f32_16x16x32_bf16 v[120:123], v[158:161], v[178:181], v[120:123]
	v_mfma_f32_16x16x32_bf16 v[108:111], v[150:153], v[186:189], v[108:111]
	v_mfma_f32_16x16x32_bf16 v[104:107], v[158:161], v[186:189], v[104:107]
	v_mfma_f32_16x16x32_bf16 v[92:95], v[150:153], v[194:197], v[92:95]
	v_mfma_f32_16x16x32_bf16 v[88:91], v[158:161], v[194:197], v[88:91]
	v_mfma_f32_16x16x32_bf16 v[76:79], v[150:153], v[206:209], v[76:79]
	v_mfma_f32_16x16x32_bf16 v[72:75], v[158:161], v[206:209], v[72:75]
	s_setprio 0
	s_barrier
	s_add_i32 s6, 0, 0x1c000
	s_add_i32 s7, s68, s44
	v_add_u32_e32 v136, s6, v170
	s_add_u32 s20, s4, 0x80
	s_addc_u32 s21, s5, 0
	s_mov_b32 m0, s7
	ds_read_b128 v[210:213], v136
	ds_read_b128 v[214:217], v136 offset:1024
	ds_read_b128 v[218:221], v136 offset:2048
	ds_read_b128 v[222:225], v136 offset:3072
	global_load_lds_dwordx4 v130, s[20:21]
	s_add_i32 m0, s7, 0x2000
	s_nop 0
	global_load_lds_dwordx4 v134, s[20:21]
	s_waitcnt vmcnt(8)
	s_setprio 1
	s_barrier
	s_waitcnt lgkmcnt(0)
	v_mfma_f32_16x16x32_bf16 v[116:119], v[210:213], v[162:165], v[116:119]
	v_mfma_f32_16x16x32_bf16 v[112:115], v[218:221], v[162:165], v[112:115]
	v_mfma_f32_16x16x32_bf16 v[100:103], v[210:213], v[182:185], v[100:103]
	v_mfma_f32_16x16x32_bf16 v[96:99], v[218:221], v[182:185], v[96:99]
	v_mfma_f32_16x16x32_bf16 v[84:87], v[210:213], v[190:193], v[84:87]
	v_mfma_f32_16x16x32_bf16 v[80:83], v[218:221], v[190:193], v[80:83]
	v_mfma_f32_16x16x32_bf16 v[68:71], v[210:213], v[202:205], v[68:71]
	v_mfma_f32_16x16x32_bf16 v[64:67], v[218:221], v[202:205], v[64:67]
	v_mfma_f32_16x16x32_bf16 v[116:119], v[214:217], v[178:181], v[116:119]
	v_mfma_f32_16x16x32_bf16 v[112:115], v[222:225], v[178:181], v[112:115]
	v_mfma_f32_16x16x32_bf16 v[100:103], v[214:217], v[186:189], v[100:103]
	v_mfma_f32_16x16x32_bf16 v[96:99], v[222:225], v[186:189], v[96:99]
	v_mfma_f32_16x16x32_bf16 v[84:87], v[214:217], v[194:197], v[84:87]
	v_mfma_f32_16x16x32_bf16 v[80:83], v[222:225], v[194:197], v[80:83]
	v_mfma_f32_16x16x32_bf16 v[68:71], v[214:217], v[206:209], v[68:71]
	v_mfma_f32_16x16x32_bf16 v[64:67], v[222:225], v[206:209], v[64:67]
	s_setprio 0
	s_mov_b32 m0, s54
	s_mov_b64 s[20:21], 0x80
	v_lshl_add_u64 v[166:167], v[226:227], 0, s[20:21]
	s_barrier
	ds_read_b128 v[162:165], v172 offset:49152
	ds_read_b128 v[178:181], v172 offset:50176
	ds_read_b128 v[182:185], v172 offset:51200
	ds_read_b128 v[186:189], v172 offset:52224
	ds_read_b128 v[190:193], v172 offset:53248
	ds_read_b128 v[194:197], v172 offset:54272
	ds_read_b128 v[202:205], v172 offset:55296
	ds_read_b128 v[206:209], v172 offset:56320
	global_load_lds_dwordx4 v[166:167], off
	v_lshl_add_u64 v[166:167], v[228:229], 0, s[20:21]
	s_mov_b32 m0, s55
	s_nop 0
	global_load_lds_dwordx4 v[166:167], off
	s_setprio 1
	s_barrier
; #define PG8_STAGE(bufoff, gbase, voff) do { _Pragma("unroll") for (int _i = 0; _i < 2; ++_i) \
;         __builtin_amdgcn_global_load_lds((const unsigned*)((const char*)(gbase) + (voff)[_i]), (LAS unsigned*)(lds + (bufoff) + ldsw + _i * 8192), 16, 0, 0); } while (0)
; #define PG8_LDA(dst, b, h) do { _Pragma("unroll") for (int m = 0; m < 4; ++m) _Pragma("unroll") for (int k = 0; k < 2; ++k) dst[m][k] = *(const LAS bf16x8*)(lds + PG8_SA(b, h) + aoff + m * 2048 + k * 1024); } while (0)
; #define PG8_LDB(dst, b, h) do { _Pragma("unroll") for (int n = 0; n < 2; ++n) _Pragma("unroll") for (int k = 0; k < 2; ++k) dst[n][k] = *(const LAS bf16x8*)(lds + PG8_SB(b, h) + boff + n * 2048 + k * 1024); } while (0)
; #define PG8_MMA(ai, bj, At, Bt) do { __builtin_amdgcn_s_setprio(1); _Pragma("unroll") for (int m = 0; m < 4; ++m) _Pragma("unroll") for (int n = 0; n < 2; ++n) _Pragma("unroll") for (int k = 0; k < 2; ++k) \
;         acc[ai][bj][m][n] = __builtin_amdgcn_mfma_f32_16x16x32_bf16(Bt[n][k], At[m][k], acc[ai][bj][m][n], 0, 0, 0); __builtin_amdgcn_s_setprio(0); } while (0)
; #define PG8_WAIT_V(n) asm volatile("s_waitcnt vmcnt(" #n ")" ::: "memory")
; #define PG8_WAIT_L(n) asm volatile("s_waitcnt lgkmcnt(" #n ")" ::: "memory")
; #define PG8_BAR __builtin_amdgcn_s_barrier()
; #define PG8_SCHED __builtin_amdgcn_sched_barrier(0)
; template <class Epi, class Sched>
; __device__ __forceinline__ void gemm_phase(LAS unsigned char* lds, const Gemm g, const Sched& S, const Epi& E) {
;     ...
;             PG8_LDB(B0, 0, 0); PG8_SCHED; PG8_LDA(At, 0, 0); PG8_STAGE(PG8_SA(1, 1), a1 + hstep, voffA);
;             PG8_WAIT_L(8); PG8_BAR; PG8_WAIT_L(0); PG8_MMA(0, 0, At, B0); PG8_BAR; PG8_SCHED;
;             PG8_LDB(B1, 0, 1); PG8_STAGE(PG8_SB(0, 0), b2, voffB);
;             PG8_BAR; PG8_WAIT_L(0); PG8_MMA(0, 1, At, B1); PG8_BAR;
;     ...
;             PG8_BAR; PG8_WAIT_L(0); PG8_MMA(1, 0, At, B0); PG8_BAR; PG8_SCHED;
;             PG8_STAGE(PG8_SB(1, 1), b3 + hstep, voffB);
;             PG8_WAIT_V(6); PG8_BAR; PG8_MMA(1, 1, At, B1); PG8_BAR;
	s_waitcnt lgkmcnt(0)
	v_mfma_f32_16x16x32_bf16 v[60:63], v[146:149], v[162:165], v[60:63]
	v_mfma_f32_16x16x32_bf16 v[56:59], v[154:157], v[162:165], v[56:59]
	v_mfma_f32_16x16x32_bf16 v[44:47], v[146:149], v[182:185], v[44:47]
	v_mfma_f32_16x16x32_bf16 v[40:43], v[154:157], v[182:185], v[40:43]
	v_mfma_f32_16x16x32_bf16 v[28:31], v[146:149], v[190:193], v[28:31]
	v_mfma_f32_16x16x32_bf16 v[24:27], v[154:157], v[190:193], v[24:27]
	v_mfma_f32_16x16x32_bf16 v[12:15], v[146:149], v[202:205], v[12:15]
	v_mfma_f32_16x16x32_bf16 v[8:11], v[154:157], v[202:205], v[8:11]
	v_mfma_f32_16x16x32_bf16 v[60:63], v[150:153], v[178:181], v[60:63]
	v_mfma_f32_16x16x32_bf16 v[56:59], v[158:161], v[178:181], v[56:59]
	v_mfma_f32_16x16x32_bf16 v[44:47], v[150:153], v[186:189], v[44:47]
	v_mfma_f32_16x16x32_bf16 v[40:43], v[158:161], v[186:189], v[40:43]
	v_mfma_f32_16x16x32_bf16 v[28:31], v[150:153], v[194:197], v[28:31]
	v_mfma_f32_16x16x32_bf16 v[24:27], v[158:161], v[194:197], v[24:27]
	v_mfma_f32_16x16x32_bf16 v[12:15], v[150:153], v[206:209], v[12:15]
	v_mfma_f32_16x16x32_bf16 v[8:11], v[158:161], v[206:209], v[8:11]
	s_setprio 0
	s_barrier
	s_add_u32 s4, s4, 0x40080
	s_addc_u32 s5, s5, 0
	s_add_i32 s6, s6, s44
	s_mov_b32 m0, s6
	s_nop 0
	global_load_lds_dwordx4 v130, s[4:5]
	s_add_i32 m0, s6, 0x2000
	s_nop 0
	global_load_lds_dwordx4 v134, s[4:5]
	s_waitcnt vmcnt(8)
	s_setprio 1
	s_barrier
	v_mfma_f32_16x16x32_bf16 v[52:55], v[210:213], v[162:165], v[52:55]
	v_mfma_f32_16x16x32_bf16 v[48:51], v[218:221], v[162:165], v[48:51]
	v_mfma_f32_16x16x32_bf16 v[36:39], v[210:213], v[182:185], v[36:39]
	v_mfma_f32_16x16x32_bf16 v[32:35], v[218:221], v[182:185], v[32:35]
	v_mfma_f32_16x16x32_bf16 v[20:23], v[210:213], v[190:193], v[20:23]
	v_mfma_f32_16x16x32_bf16 v[16:19], v[218:221], v[190:193], v[16:19]
	v_mfma_f32_16x16x32_bf16 v[4:7], v[210:213], v[202:205], v[4:7]
	v_mfma_f32_16x16x32_bf16 v[0:3], v[218:221], v[202:205], v[0:3]
	v_mfma_f32_16x16x32_bf16 v[52:55], v[214:217], v[178:181], v[52:55]
	v_mfma_f32_16x16x32_bf16 v[48:51], v[222:225], v[178:181], v[48:51]
	v_mfma_f32_16x16x32_bf16 v[36:39], v[214:217], v[186:189], v[36:39]
	v_mfma_f32_16x16x32_bf16 v[32:35], v[222:225], v[186:189], v[32:35]
	v_mfma_f32_16x16x32_bf16 v[20:23], v[214:217], v[194:197], v[20:23]
	v_mfma_f32_16x16x32_bf16 v[16:19], v[222:225], v[194:197], v[16:19]
	v_mfma_f32_16x16x32_bf16 v[4:7], v[214:217], v[206:209], v[4:7]
	v_mfma_f32_16x16x32_bf16 v[0:3], v[222:225], v[206:209], v[0:3]
	s_setprio 0
	s_add_i32 s67, s67, 2
	s_add_u32 s0, s0, 0x100
	s_addc_u32 s1, s1, 0
	s_add_u32 s65, s65, 0x100
	s_addc_u32 s66, s66, 0
	s_cmp_gt_u32 s67, 13
	s_barrier
.LBB0_613:
	ds_read_b128 v[146:149], v171
	ds_read_b128 v[150:153], v171 offset:1024
	ds_read_b128 v[154:157], v171 offset:2048
	ds_read_b128 v[158:161], v171 offset:3072
	s_add_u32 s4, s0, 0xfffc0080
	s_addc_u32 s5, s1, -1
	s_cmp_eq_u32 s67, 12
	s_cselect_b32 s7, s8, s5
	s_cselect_b32 s6, s9, s4
	s_cselect_b32 s5, s31, s66
	s_cselect_b32 s4, s35, s65
	s_add_i32 m0, s45, 0xc000
	ds_read_b128 v[162:165], v172
	ds_read_b128 v[178:181], v172 offset:1024
	ds_read_b128 v[182:185], v172 offset:2048
	ds_read_b128 v[186:189], v172 offset:3072
	ds_read_b128 v[190:193], v172 offset:4096
	ds_read_b128 v[194:197], v172 offset:5120
	ds_read_b128 v[202:205], v172 offset:6144
	ds_read_b128 v[206:209], v172 offset:7168
	global_load_lds_dwordx4 v138, s[0:1]
	s_add_i32 m0, s45, 0xe000
	s_nop 0
	global_load_lds_dwordx4 v140, s[0:1]
	s_waitcnt lgkmcnt(8)
	s_waitcnt vmcnt(8)
	s_setprio 1
	s_barrier
	s_waitcnt lgkmcnt(0)
	v_mfma_f32_16x16x32_bf16 v[124:127], v[146:149], v[162:165], v[124:127]
	v_mfma_f32_16x16x32_bf16 v[120:123], v[154:157], v[162:165], v[120:123]
	v_mfma_f32_16x16x32_bf16 v[108:111], v[146:149], v[182:185], v[108:111]
	v_mfma_f32_16x16x32_bf16 v[104:107], v[154:157], v[182:185], v[104:107]
	v_mfma_f32_16x16x32_bf16 v[92:95], v[146:149], v[190:193], v[92:95]
	v_mfma_f32_16x16x32_bf16 v[88:91], v[154:157], v[190:193], v[88:91]
	v_mfma_f32_16x16x32_bf16 v[76:79], v[146:149], v[202:205], v[76:79]
	v_mfma_f32_16x16x32_bf16 v[72:75], v[154:157], v[202:205], v[72:75]
	v_mfma_f32_16x16x32_bf16 v[124:127], v[150:153], v[178:181], v[124:127]
	v_mfma_f32_16x16x32_bf16 v[120:123], v[158:161], v[178:181], v[120:123]
	v_mfma_f32_16x16x32_bf16 v[108:111], v[150:153], v[186:189], v[108:111]
	v_mfma_f32_16x16x32_bf16 v[104:107], v[158:161], v[186:189], v[104:107]
	v_mfma_f32_16x16x32_bf16 v[92:95], v[150:153], v[194:197], v[92:95]
	v_mfma_f32_16x16x32_bf16 v[88:91], v[158:161], v[194:197], v[88:91]
	v_mfma_f32_16x16x32_bf16 v[76:79], v[150:153], v[206:209], v[76:79]
	v_mfma_f32_16x16x32_bf16 v[72:75], v[158:161], v[206:209], v[72:75]
	s_setprio 0
	s_barrier
	s_add_i32 s68, s57, s44
	s_mov_b32 m0, s68
	ds_read_b128 v[210:213], v173
	ds_read_b128 v[214:217], v173 offset:1024
	ds_read_b128 v[218:221], v173 offset:2048
	ds_read_b128 v[222:225], v173 offset:3072
	global_load_lds_dwordx4 v130, s[4:5]
	s_add_i32 m0, s68, 0x2000
	s_nop 0
	global_load_lds_dwordx4 v134, s[4:5]
	s_waitcnt vmcnt(8)
	s_setprio 1
	s_barrier
; #define PG8_STAGE(bufoff, gbase, voff) do { _Pragma("unroll") for (int _i = 0; _i < 2; ++_i) \
;         __builtin_amdgcn_global_load_lds((const unsigned*)((const char*)(gbase) + (voff)[_i]), (LAS unsigned*)(lds + (bufoff) + ldsw + _i * 8192), 16, 0, 0); } while (0)
; #define PG8_LDA(dst, b, h) do { _Pragma("unroll") for (int m = 0; m < 4; ++m) _Pragma("unroll") for (int k = 0; k < 2; ++k) dst[m][k] = *(const LAS bf16x8*)(lds + PG8_SA(b, h) + aoff + m * 2048 + k * 1024); } while (0)
; #define PG8_LDB(dst, b, h) do { _Pragma("unroll") for (int n = 0; n < 2; ++n) _Pragma("unroll") for (int k = 0; k < 2; ++k) dst[n][k] = *(const LAS bf16x8*)(lds + PG8_SB(b, h) + boff + n * 2048 + k * 1024); } while (0)
; #define PG8_MMA(ai, bj, At, Bt) do { __builtin_amdgcn_s_setprio(1); _Pragma("unroll") for (int m = 0; m < 4; ++m) _Pragma("unroll") for (int n = 0; n < 2; ++n) _Pragma("unroll") for (int k = 0; k < 2; ++k) \
;         acc[ai][bj][m][n] = __builtin_amdgcn_mfma_f32_16x16x32_bf16(Bt[n][k], At[m][k], acc[ai][bj][m][n], 0, 0, 0); __builtin_amdgcn_s_setprio(0); } while (0)
; #define PG8_WAIT_V(n) asm volatile("s_waitcnt vmcnt(" #n ")" ::: "memory")
; #define PG8_WAIT_L(n) asm volatile("s_waitcnt lgkmcnt(" #n ")" ::: "memory")
; #define PG8_BAR __builtin_amdgcn_s_barrier()
; #define PG8_SCHED __builtin_amdgcn_sched_barrier(0)
; template <class Epi, class Sched>
; __device__ __forceinline__ void gemm_phase(LAS unsigned char* lds, const Gemm g, const Sched& S, const Epi& E) {
;     ...
;             PG8_BAR; PG8_WAIT_L(0); PG8_MMA(0, 1, At, B1); PG8_BAR;
;             PG8_LDA(At, 0, 1); PG8_STAGE(PG8_SA(0, 0), a2, voffA);
;             PG8_BAR; PG8_WAIT_L(0); PG8_MMA(1, 0, At, B0); PG8_BAR; PG8_SCHED;
;             PG8_STAGE(PG8_SB(0, 1), b2 + hstep, voffB);
;             PG8_WAIT_V(6); PG8_BAR; PG8_MMA(1, 1, At, B1); PG8_BAR;
;             PG8_LDB(B0, 1, 0); PG8_SCHED; PG8_LDA(At, 1, 0); PG8_STAGE(PG8_SA(0, 1), a2 + hstep, voffA);
;             PG8_WAIT_L(8); PG8_BAR; PG8_WAIT_L(0); PG8_MMA(0, 0, At, B0); PG8_BAR; PG8_SCHED;
	s_waitcnt lgkmcnt(0)
	v_mfma_f32_16x16x32_bf16 v[116:119], v[210:213], v[162:165], v[116:119]
	v_mfma_f32_16x16x32_bf16 v[112:115], v[218:221], v[162:165], v[112:115]
	v_mfma_f32_16x16x32_bf16 v[100:103], v[210:213], v[182:185], v[100:103]
	v_mfma_f32_16x16x32_bf16 v[96:99], v[218:221], v[182:185], v[96:99]
	v_mfma_f32_16x16x32_bf16 v[84:87], v[210:213], v[190:193], v[84:87]
	v_mfma_f32_16x16x32_bf16 v[80:83], v[218:221], v[190:193], v[80:83]
	v_mfma_f32_16x16x32_bf16 v[68:71], v[210:213], v[202:205], v[68:71]
	v_mfma_f32_16x16x32_bf16 v[64:67], v[218:221], v[202:205], v[64:67]
	v_mfma_f32_16x16x32_bf16 v[116:119], v[214:217], v[178:181], v[116:119]
	v_mfma_f32_16x16x32_bf16 v[112:115], v[222:225], v[178:181], v[112:115]
	v_mfma_f32_16x16x32_bf16 v[100:103], v[214:217], v[186:189], v[100:103]
	v_mfma_f32_16x16x32_bf16 v[96:99], v[222:225], v[186:189], v[96:99]
	v_mfma_f32_16x16x32_bf16 v[84:87], v[214:217], v[194:197], v[84:87]
	v_mfma_f32_16x16x32_bf16 v[80:83], v[222:225], v[194:197], v[80:83]
	v_mfma_f32_16x16x32_bf16 v[68:71], v[214:217], v[206:209], v[68:71]
	v_mfma_f32_16x16x32_bf16 v[64:67], v[222:225], v[206:209], v[64:67]
	s_setprio 0
	s_mov_b32 m0, s45
	v_lshl_add_u64 v[226:227], s[6:7], 0, v[128:129]
	s_barrier
	ds_read_b128 v[162:165], v172 offset:16384
	ds_read_b128 v[178:181], v172 offset:17408
	ds_read_b128 v[182:185], v172 offset:18432
	ds_read_b128 v[186:189], v172 offset:19456
	ds_read_b128 v[190:193], v172 offset:20480
	ds_read_b128 v[194:197], v172 offset:21504
	ds_read_b128 v[202:205], v172 offset:22528
	ds_read_b128 v[206:209], v172 offset:23552
	global_load_lds_dwordx4 v128, s[6:7]
	v_lshl_add_u64 v[228:229], s[6:7], 0, v[132:133]
	s_mov_b32 m0, s46
	s_nop 0
	global_load_lds_dwordx4 v132, s[6:7]
	s_setprio 1
	s_barrier
	s_waitcnt lgkmcnt(0)
	v_mfma_f32_16x16x32_bf16 v[60:63], v[146:149], v[162:165], v[60:63]
	v_mfma_f32_16x16x32_bf16 v[56:59], v[154:157], v[162:165], v[56:59]
	v_mfma_f32_16x16x32_bf16 v[44:47], v[146:149], v[182:185], v[44:47]
	v_mfma_f32_16x16x32_bf16 v[40:43], v[154:157], v[182:185], v[40:43]
	v_mfma_f32_16x16x32_bf16 v[28:31], v[146:149], v[190:193], v[28:31]
	v_mfma_f32_16x16x32_bf16 v[24:27], v[154:157], v[190:193], v[24:27]
	v_mfma_f32_16x16x32_bf16 v[12:15], v[146:149], v[202:205], v[12:15]
	v_mfma_f32_16x16x32_bf16 v[8:11], v[154:157], v[202:205], v[8:11]
	v_mfma_f32_16x16x32_bf16 v[60:63], v[150:153], v[178:181], v[60:63]
	v_mfma_f32_16x16x32_bf16 v[56:59], v[158:161], v[178:181], v[56:59]
	v_mfma_f32_16x16x32_bf16 v[44:47], v[150:153], v[186:189], v[44:47]
	v_mfma_f32_16x16x32_bf16 v[40:43], v[158:161], v[186:189], v[40:43]
	v_mfma_f32_16x16x32_bf16 v[28:31], v[150:153], v[194:197], v[28:31]
	v_mfma_f32_16x16x32_bf16 v[24:27], v[158:161], v[194:197], v[24:27]
	v_mfma_f32_16x16x32_bf16 v[12:15], v[150:153], v[206:209], v[12:15]
	v_mfma_f32_16x16x32_bf16 v[8:11], v[158:161], v[206:209], v[8:11]
	s_setprio 0
	s_barrier
	s_add_u32 s68, s4, 0x40000
	s_addc_u32 s69, s5, 0
	s_add_i32 s70, s58, s44
	s_mov_b32 m0, s70
	s_nop 0
	global_load_lds_dwordx4 v130, s[68:69]
	s_add_i32 m0, s70, 0x2000
	s_nop 0
	global_load_lds_dwordx4 v134, s[68:69]
	s_add_u32 s6, s6, 0x40000
	s_addc_u32 s7, s7, 0
	s_mov_b32 m0, s47
	s_nop 0
	global_load_lds_dwordx4 v128, s[6:7]
	s_mov_b32 m0, s48
	s_nop 0
	global_load_lds_dwordx4 v132, s[6:7]
	s_waitcnt vmcnt(10)
	s_setprio 1
	s_barrier
	v_mfma_f32_16x16x32_bf16 v[52:55], v[210:213], v[162:165], v[52:55]
	v_mfma_f32_16x16x32_bf16 v[48:51], v[218:221], v[162:165], v[48:51]
	v_mfma_f32_16x16x32_bf16 v[36:39], v[210:213], v[182:185], v[36:39]
	v_mfma_f32_16x16x32_bf16 v[32:35], v[218:221], v[182:185], v[32:35]
	v_mfma_f32_16x16x32_bf16 v[20:23], v[210:213], v[190:193], v[20:23]
	v_mfma_f32_16x16x32_bf16 v[16:19], v[218:221], v[190:193], v[16:19]
	v_mfma_f32_16x16x32_bf16 v[4:7], v[210:213], v[202:205], v[4:7]
	v_mfma_f32_16x16x32_bf16 v[0:3], v[218:221], v[202:205], v[0:3]
	v_mfma_f32_16x16x32_bf16 v[52:55], v[214:217], v[178:181], v[52:55]
	v_mfma_f32_16x16x32_bf16 v[48:51], v[222:225], v[178:181], v[48:51]
	v_mfma_f32_16x16x32_bf16 v[36:39], v[214:217], v[186:189], v[36:39]
	v_mfma_f32_16x16x32_bf16 v[32:35], v[222:225], v[186:189], v[32:35]
	v_mfma_f32_16x16x32_bf16 v[20:23], v[214:217], v[194:197], v[20:23]
	v_mfma_f32_16x16x32_bf16 v[16:19], v[222:225], v[194:197], v[16:19]
	v_mfma_f32_16x16x32_bf16 v[4:7], v[214:217], v[206:209], v[4:7]
	v_mfma_f32_16x16x32_bf16 v[0:3], v[222:225], v[206:209], v[0:3]
	s_setprio 0
	s_add_i32 s68, 0, 0x18000
	v_add_u32_e32 v136, s68, v170
	s_barrier
	ds_read_b128 v[146:149], v136
	ds_read_b128 v[150:153], v136 offset:1024
	ds_read_b128 v[154:157], v136 offset:2048
	ds_read_b128 v[158:161], v136 offset:3072
	ds_read_b128 v[162:165], v172 offset:32768
	ds_read_b128 v[178:181], v172 offset:33792
	ds_read_b128 v[182:185], v172 offset:34816
	ds_read_b128 v[186:189], v172 offset:35840
	ds_read_b128 v[190:193], v172 offset:36864
	ds_read_b128 v[194:197], v172 offset:37888
	ds_read_b128 v[202:205], v172 offset:38912
	ds_read_b128 v[206:209], v172 offset:39936
	s_waitcnt lgkmcnt(8)
	s_waitcnt vmcnt(8)
	s_setprio 1
	s_barrier
; #define PG8_STAGE(bufoff, gbase, voff) do { _Pragma("unroll") for (int _i = 0; _i < 2; ++_i) \
;         __builtin_amdgcn_global_load_lds((const unsigned*)((const char*)(gbase) + (voff)[_i]), (LAS unsigned*)(lds + (bufoff) + ldsw + _i * 8192), 16, 0, 0); } while (0)
; #define PG8_LDA(dst, b, h) do { _Pragma("unroll") for (int m = 0; m < 4; ++m) _Pragma("unroll") for (int k = 0; k < 2; ++k) dst[m][k] = *(const LAS bf16x8*)(lds + PG8_SA(b, h) + aoff + m * 2048 + k * 1024); } while (0)
; #define PG8_LDB(dst, b, h) do { _Pragma("unroll") for (int n = 0; n < 2; ++n) _Pragma("unroll") for (int k = 0; k < 2; ++k) dst[n][k] = *(const LAS bf16x8*)(lds + PG8_SB(b, h) + boff + n * 2048 + k * 1024); } while (0)
; #define PG8_MMA(ai, bj, At, Bt) do { __builtin_amdgcn_s_setprio(1); _Pragma("unroll") for (int m = 0; m < 4; ++m) _Pragma("unroll") for (int n = 0; n < 2; ++n) _Pragma("unroll") for (int k = 0; k < 2; ++k) \
;         acc[ai][bj][m][n] = __builtin_amdgcn_mfma_f32_16x16x32_bf16(Bt[n][k], At[m][k], acc[ai][bj][m][n], 0, 0, 0); __builtin_amdgcn_s_setprio(0); } while (0)
; #define PG8_WAIT_V(n) asm volatile("s_waitcnt vmcnt(" #n ")" ::: "memory")
; #define PG8_WAIT_L(n) asm volatile("s_waitcnt lgkmcnt(" #n ")" ::: "memory")
; #define PG8_BAR __builtin_amdgcn_s_barrier()
; #define PG8_SCHED __builtin_amdgcn_sched_barrier(0)
; template <class Epi, class Sched>
; __device__ __forceinline__ void gemm_phase(LAS unsigned char* lds, const Gemm g, const Sched& S, const Epi& E) {
;     ...
;             PG8_WAIT_L(8); PG8_BAR; PG8_WAIT_L(0); PG8_MMA(0, 0, At, B0); PG8_BAR; PG8_SCHED;
;             PG8_LDB(B1, 1, 1); PG8_STAGE(PG8_SB(1, 0), b3, voffB);
;             PG8_BAR; PG8_WAIT_L(0); PG8_MMA(0, 1, At, B1); PG8_BAR;
;             PG8_LDA(At, 1, 1); PG8_STAGE(PG8_SA(1, 0), a3, voffA);
;             PG8_BAR; PG8_WAIT_L(0); PG8_MMA(1, 0, At, B0); PG8_BAR; PG8_SCHED;
;             PG8_STAGE(PG8_SB(1, 1), b3 + hstep, voffB);
;             PG8_WAIT_V(6); PG8_BAR; PG8_MMA(1, 1, At, B1); PG8_BAR;
	s_waitcnt lgkmcnt(0)
	v_mfma_f32_16x16x32_bf16 v[124:127], v[146:149], v[162:165], v[124:127]
	v_mfma_f32_16x16x32_bf16 v[120:123], v[154:157], v[162:165], v[120:123]
	v_mfma_f32_16x16x32_bf16 v[108:111], v[146:149], v[182:185], v[108:111]
	v_mfma_f32_16x16x32_bf16 v[104:107], v[154:157], v[182:185], v[104:107]
	v_mfma_f32_16x16x32_bf16 v[92:95], v[146:149], v[190:193], v[92:95]
	v_mfma_f32_16x16x32_bf16 v[88:91], v[154:157], v[190:193], v[88:91]
	v_mfma_f32_16x16x32_bf16 v[76:79], v[146:149], v[202:205], v[76:79]
	v_mfma_f32_16x16x32_bf16 v[72:75], v[154:157], v[202:205], v[72:75]
	v_mfma_f32_16x16x32_bf16 v[124:127], v[150:153], v[178:181], v[124:127]
	v_mfma_f32_16x16x32_bf16 v[120:123], v[158:161], v[178:181], v[120:123]
	v_mfma_f32_16x16x32_bf16 v[108:111], v[150:153], v[186:189], v[108:111]
	v_mfma_f32_16x16x32_bf16 v[104:107], v[158:161], v[186:189], v[104:107]
	v_mfma_f32_16x16x32_bf16 v[92:95], v[150:153], v[194:197], v[92:95]
	v_mfma_f32_16x16x32_bf16 v[88:91], v[158:161], v[194:197], v[88:91]
	v_mfma_f32_16x16x32_bf16 v[76:79], v[150:153], v[206:209], v[76:79]
	v_mfma_f32_16x16x32_bf16 v[72:75], v[158:161], v[206:209], v[72:75]
	s_setprio 0
	s_barrier
	s_add_i32 s6, 0, 0x1c000
	s_add_i32 s7, s68, s44
	v_add_u32_e32 v136, s6, v170
	s_add_u32 s20, s4, 0x80
	s_addc_u32 s21, s5, 0
	s_mov_b32 m0, s7
	ds_read_b128 v[210:213], v136
	ds_read_b128 v[214:217], v136 offset:1024
	ds_read_b128 v[218:221], v136 offset:2048
	ds_read_b128 v[222:225], v136 offset:3072
	global_load_lds_dwordx4 v130, s[20:21]
	s_add_i32 m0, s7, 0x2000
	s_nop 0
	global_load_lds_dwordx4 v134, s[20:21]
	s_waitcnt vmcnt(8)
	s_setprio 1
	s_barrier
	s_waitcnt lgkmcnt(0)
	v_mfma_f32_16x16x32_bf16 v[116:119], v[210:213], v[162:165], v[116:119]
	v_mfma_f32_16x16x32_bf16 v[112:115], v[218:221], v[162:165], v[112:115]
	v_mfma_f32_16x16x32_bf16 v[100:103], v[210:213], v[182:185], v[100:103]
	v_mfma_f32_16x16x32_bf16 v[96:99], v[218:221], v[182:185], v[96:99]
	v_mfma_f32_16x16x32_bf16 v[84:87], v[210:213], v[190:193], v[84:87]
	v_mfma_f32_16x16x32_bf16 v[80:83], v[218:221], v[190:193], v[80:83]
	v_mfma_f32_16x16x32_bf16 v[68:71], v[210:213], v[202:205], v[68:71]
	v_mfma_f32_16x16x32_bf16 v[64:67], v[218:221], v[202:205], v[64:67]
	v_mfma_f32_16x16x32_bf16 v[116:119], v[214:217], v[178:181], v[116:119]
	v_mfma_f32_16x16x32_bf16 v[112:115], v[222:225], v[178:181], v[112:115]
	v_mfma_f32_16x16x32_bf16 v[100:103], v[214:217], v[186:189], v[100:103]
	v_mfma_f32_16x16x32_bf16 v[96:99], v[222:225], v[186:189], v[96:99]
	v_mfma_f32_16x16x32_bf16 v[84:87], v[214:217], v[194:197], v[84:87]
	v_mfma_f32_16x16x32_bf16 v[80:83], v[222:225], v[194:197], v[80:83]
	v_mfma_f32_16x16x32_bf16 v[68:71], v[214:217], v[206:209], v[68:71]
	v_mfma_f32_16x16x32_bf16 v[64:67], v[222:225], v[206:209], v[64:67]
	s_setprio 0
	s_mov_b32 m0, s54
	s_mov_b64 s[20:21], 0x80
	v_lshl_add_u64 v[166:167], v[226:227], 0, s[20:21]
	s_barrier
	ds_read_b128 v[162:165], v172 offset:49152
	ds_read_b128 v[178:181], v172 offset:50176
	ds_read_b128 v[182:185], v172 offset:51200
	ds_read_b128 v[186:189], v172 offset:52224
	ds_read_b128 v[190:193], v172 offset:53248
	ds_read_b128 v[194:197], v172 offset:54272
	ds_read_b128 v[202:205], v172 offset:55296
	ds_read_b128 v[206:209], v172 offset:56320
	global_load_lds_dwordx4 v[166:167], off
	v_lshl_add_u64 v[166:167], v[228:229], 0, s[20:21]
	s_mov_b32 m0, s55
	s_nop 0
	global_load_lds_dwordx4 v[166:167], off
	s_setprio 1
	s_barrier
	s_waitcnt lgkmcnt(0)
	v_mfma_f32_16x16x32_bf16 v[60:63], v[146:149], v[162:165], v[60:63]
	v_mfma_f32_16x16x32_bf16 v[56:59], v[154:157], v[162:165], v[56:59]
	v_mfma_f32_16x16x32_bf16 v[44:47], v[146:149], v[182:185], v[44:47]
	v_mfma_f32_16x16x32_bf16 v[40:43], v[154:157], v[182:185], v[40:43]
	v_mfma_f32_16x16x32_bf16 v[28:31], v[146:149], v[190:193], v[28:31]
	v_mfma_f32_16x16x32_bf16 v[24:27], v[154:157], v[190:193], v[24:27]
	v_mfma_f32_16x16x32_bf16 v[12:15], v[146:149], v[202:205], v[12:15]
	v_mfma_f32_16x16x32_bf16 v[8:11], v[154:157], v[202:205], v[8:11]
	v_mfma_f32_16x16x32_bf16 v[60:63], v[150:153], v[178:181], v[60:63]
	v_mfma_f32_16x16x32_bf16 v[56:59], v[158:161], v[178:181], v[56:59]
	v_mfma_f32_16x16x32_bf16 v[44:47], v[150:153], v[186:189], v[44:47]
	v_mfma_f32_16x16x32_bf16 v[40:43], v[158:161], v[186:189], v[40:43]
	v_mfma_f32_16x16x32_bf16 v[28:31], v[150:153], v[194:197], v[28:31]
	v_mfma_f32_16x16x32_bf16 v[24:27], v[158:161], v[194:197], v[24:27]
	v_mfma_f32_16x16x32_bf16 v[12:15], v[150:153], v[206:209], v[12:15]
	v_mfma_f32_16x16x32_bf16 v[8:11], v[158:161], v[206:209], v[8:11]
	s_setprio 0
	s_barrier
	s_add_u32 s4, s4, 0x40080
	s_addc_u32 s5, s5, 0
	s_add_i32 s6, s6, s44
	s_mov_b32 m0, s6
	s_nop 0
	global_load_lds_dwordx4 v130, s[4:5]
	s_add_i32 m0, s6, 0x2000
	s_nop 0
	global_load_lds_dwordx4 v134, s[4:5]
	s_waitcnt vmcnt(8)
	s_setprio 1
	s_barrier
	v_mfma_f32_16x16x32_bf16 v[52:55], v[210:213], v[162:165], v[52:55]
	v_mfma_f32_16x16x32_bf16 v[48:51], v[218:221], v[162:165], v[48:51]
	v_mfma_f32_16x16x32_bf16 v[36:39], v[210:213], v[182:185], v[36:39]
	v_mfma_f32_16x16x32_bf16 v[32:35], v[218:221], v[182:185], v[32:35]
	v_mfma_f32_16x16x32_bf16 v[20:23], v[210:213], v[190:193], v[20:23]
	v_mfma_f32_16x16x32_bf16 v[16:19], v[218:221], v[190:193], v[16:19]
	v_mfma_f32_16x16x32_bf16 v[4:7], v[210:213], v[202:205], v[4:7]
	v_mfma_f32_16x16x32_bf16 v[0:3], v[218:221], v[202:205], v[0:3]
	v_mfma_f32_16x16x32_bf16 v[52:55], v[214:217], v[178:181], v[52:55]
	v_mfma_f32_16x16x32_bf16 v[48:51], v[222:225], v[178:181], v[48:51]
	v_mfma_f32_16x16x32_bf16 v[36:39], v[214:217], v[186:189], v[36:39]
	v_mfma_f32_16x16x32_bf16 v[32:35], v[222:225], v[186:189], v[32:35]
	v_mfma_f32_16x16x32_bf16 v[20:23], v[214:217], v[194:197], v[20:23]
	v_mfma_f32_16x16x32_bf16 v[16:19], v[222:225], v[194:197], v[16:19]
	v_mfma_f32_16x16x32_bf16 v[4:7], v[214:217], v[206:209], v[4:7]
	v_mfma_f32_16x16x32_bf16 v[0:3], v[222:225], v[206:209], v[0:3]
	s_setprio 0
	s_add_i32 s67, s67, 2
	s_add_u32 s0, s0, 0x100
	s_addc_u32 s1, s1, 0
	s_add_u32 s65, s65, 0x100
	s_addc_u32 s66, s66, 0
	s_cmp_gt_u32 s67, 13
	s_barrier
;     __device__ __forceinline__ void operator()(const AccT& acc, const Unit& u, int wr, int wc, int fr, int fq) const {
;     ...
;         const int j = fr & 3; const float sgn = ((fr >> 2) & 1) ? 1.0f : -1.0f;
; #pragma unroll
;         for (int ai = 0; ai < 2; ++ai) {
;             const int hh = 2 * ai + wr;
;             const float l2f = lgd[hh] * 1.4426950408889634f, l2b = lgd[4 + hh] * 1.4426950408889634f;
;             const float zf0 = exp2f((float)(127 - o0) * l2f), zfs = exp2f(-l2f), zb0 = exp2f((float)o0 * l2b), zbs = exp2f(l2b);
; #pragma unroll
;             for (int m = 0; m < 4; ++m) {
;                 const int r = rbase + ai * 128 + m * 16;
;                 const int d = 4 * (2 * m + (fr >> 3)) + j;
; #pragma unroll
;                 for (int bj = 0; bj < 2; ++bj) {
;                     const int t0 = tb + bj * 128;
;                     float v[8];
; #pragma unroll
;                     for (int jj = 0; jj < 4; ++jj) { v[jj] = acc[ai][bj][m][0][jj]; v[4 + jj] = acc[ai][bj][m][1][jj]; }
;                     if constexpr (ROPE) {
;                         const int t = t0 & 2047;
; #pragma unroll
;                         for (int hf = 0; hf < 2; ++hf) {
;                             f32x4 cs, sn;
;                             if (m < 2) { const float c1 = ropeA[(t >> 6) * 16 + d], s1 = ropeA[1024 + (t >> 6) * 16 + d]; cs = (f32x4){c1, c1, c1, c1}; sn = (f32x4){s1, s1, s1, s1}; }
;                             else { const float* cb = ropeA + 2048 + (d - 16) * 64 + (t & 63) + 4 * hf; cs = *(const f32x4*)(cb); sn = *(const f32x4*)(cb + 1024); }
; #pragma unroll
;                             for (int jj = 0; jj < 4; ++jj) { const float pr = __shfl_xor(v[4 * hf + jj], 4); v[4 * hf + jj] = v[4 * hf + jj] * cs[jj] + sgn * pr * sn[jj]; }
;                             __builtin_amdgcn_sched_barrier(0);
;                         }
;                     }
;                     float zf[8], zb[8]; zf[0] = zf0; zb[0] = zb0;
; #pragma unroll
;                     for (int jj = 1; jj < 8; ++jj) { zf[jj] = zf[jj - 1] * zfs; zb[jj] = zb[jj - 1] * zbs; }
;                     u32x4 wf, wb;
;                     wf.x = cvt_pk_bf16(v[0] * zf[0], v[1] * zf[1]); wf.y = cvt_pk_bf16(v[2] * zf[2], v[3] * zf[3]); wf.z = cvt_pk_bf16(v[4] * zf[4], v[5] * zf[5]); wf.w = cvt_pk_bf16(v[6] * zf[6], v[7] * zf[7]);
	s_cbranch_scc0 .LBB0_613
	v_mov_b32_e32 v136, v169
	v_mov_b32_e32 v150, v168
	s_lshl_b32 s0, s33, 8
	global_load_dword v154, v137, s[22:23]
	global_load_dword v155, v137, s[22:23] offset:16
	s_or_b32 s0, s0, s53
	v_lshlrev_b32_e32 v151, 3, v136
	v_ashrrev_i32_e32 v136, 1, v150
	v_add_u32_e32 v162, s0, v151
	v_bfi_b32 v136, -4, v136, v150
	v_lshrrev_b32_e32 v146, 2, v162
	v_add_u32_e32 v192, 0x400, v136
	v_and_b32_e32 v187, 0x1f0, v146
	v_add_u32_e32 v146, v192, v187
	v_add_u32_e32 v148, v187, v136
	v_ashrrev_i32_e32 v147, 31, v146
	v_ashrrev_i32_e32 v149, 31, v148
	v_lshl_add_u64 v[146:147], v[146:147], 2, s[16:17]
	v_lshl_add_u64 v[148:149], v[148:149], 2, s[16:17]
	global_load_dword v153, v[146:147], off
	global_load_dword v166, v[148:149], off
	v_and_b32_e32 v157, 64, v174
	v_xor_b32_e32 v156, 4, v174
	v_add_u32_e32 v157, 64, v157
	v_cmp_lt_i32_e32 vcc, v156, v157
	v_mov_b32_e32 v152, v124
	v_add_u32_e32 v151, s53, v151
	v_cndmask_b32_e32 v156, v174, v156, vcc
	v_lshlrev_b32_e32 v177, 2, v156
	ds_bpermute_b32 v124, v177, v124
	v_sub_u32_e32 v156, 0x7f, v151
	v_add_u32_e32 v164, s52, v150
	v_and_b32_e32 v150, 4, v150
	v_cvt_f32_i32_e32 v179, v156
	v_cvt_f32_i32_e32 v178, v151
	v_cmp_eq_u32_e32 vcc, 0, v150
	ds_bpermute_b32 v157, v177, v125
	ds_bpermute_b32 v158, v177, v127
	s_waitcnt lgkmcnt(0)
	v_cndmask_b32_e64 v167, v124, -v124, vcc
	ds_bpermute_b32 v151, v177, v126
	v_ashrrev_i32_e32 v165, 31, v164
	v_and_b32_e32 v186, 56, v162
	s_waitcnt lgkmcnt(0)
	v_cndmask_b32_e64 v151, v151, -v151, vcc
	s_waitcnt vmcnt(0)
	v_mul_f32_e32 v124, 0x3fb8aa3b, v154
	v_mul_f32_e32 v150, 0x3fb8aa3b, v155
	v_cmp_lt_f32_e64 s[4:5], s60, v124
	v_mul_f32_e32 v156, v124, v179
	v_cmp_gt_f32_e64 s[6:7], s59, v150
	v_cndmask_b32_e64 v159, 0, v176, s[4:5]
	v_mul_f32_e32 v160, v150, v178
	v_cndmask_b32_e64 v161, 0, v176, s[6:7]
	v_cmp_gt_f32_e64 s[8:9], s59, v156
	v_fmac_f32_e32 v159, 0xbfb8aa3b, v154
	s_and_b64 s[0:1], s[4:5], exec
	v_cmp_gt_f32_e64 s[4:5], s59, v160
	v_fmac_f32_e32 v161, 0x3fb8aa3b, v155
	v_cndmask_b32_e64 v154, 0, v176, s[8:9]
	v_exp_f32_e32 v155, v159
	v_cndmask_b32_e64 v159, 0, v176, s[4:5]
	v_fmac_f32_e32 v154, v124, v179
	v_fmac_f32_e32 v159, v150, v178
	v_exp_f32_e32 v150, v154
	v_cndmask_b32_e64 v156, 0, v175, s[8:9]
	s_cselect_b32 s8, 0xffffffc0, 0
	v_exp_f32_e32 v161, v161
	v_exp_f32_e32 v159, v159
	v_ldexp_f32 v163, v155, s8
	v_pk_mul_f32 v[154:155], v[152:153], v[166:167]
	v_cndmask_b32_e64 v167, v157, -v157, vcc
	v_mov_b32_e32 v152, v125
	s_and_b64 s[0:1], s[6:7], exec
	v_add_f32_e32 v190, v154, v155
	v_pk_mul_f32 v[154:155], v[152:153], v[166:167]
	v_cndmask_b32_e64 v167, v158, -v158, vcc
	v_mov_b32_e32 v152, v127
	v_cndmask_b32_e64 v160, 0, v175, s[4:5]
	s_cselect_b32 s0, 0xffffffc0, 0
	v_ldexp_f32 v180, v150, v156
	v_add_f32_e32 v191, v154, v155
	v_pk_mul_f32 v[154:155], v[152:153], v[166:167]
	v_ldexp_f32 v124, v161, s0
	v_mul_f32_e32 v161, v126, v166
	v_ldexp_f32 v150, v159, v160
	v_mul_f32_e32 v181, v163, v180
	v_add_f32_e32 v193, v154, v155
	global_load_dword v188, v[148:149], off
	global_load_dword v157, v[146:147], off
	ds_bpermute_b32 v127, v177, v121
	v_mov_b32_e32 v156, v121
	ds_bpermute_b32 v121, v177, v123
	ds_bpermute_b32 v125, v177, v120
	ds_bpermute_b32 v152, v177, v122
	s_waitcnt lgkmcnt(3)
	v_cndmask_b32_e64 v189, v127, -v127, vcc
	s_waitcnt lgkmcnt(1)
	v_cndmask_b32_e64 v158, v125, -v125, vcc
	s_waitcnt lgkmcnt(0)
	v_cndmask_b32_e64 v127, v152, -v152, vcc
	s_waitcnt vmcnt(1)
	v_mul_f32_e32 v159, v120, v188
	s_waitcnt vmcnt(0)
	v_pk_mul_f32 v[154:155], v[156:157], v[188:189]
	v_cndmask_b32_e64 v189, v121, -v121, vcc
	v_mov_b32_e32 v156, v123
	v_add_f32_e32 v121, v154, v155
	v_pk_mul_f32 v[154:155], v[156:157], v[188:189]
	s_nop 0
	v_add_f32_e32 v123, v154, v155
	v_mov_b32_e32 v125, v153
	v_pk_mul_f32 v[152:153], v[124:125], v[150:151]
	v_mov_b32_e32 v125, v161
	v_pk_mul_f32 v[154:155], v[124:125], v[152:153]
	v_mov_b32_e32 v125, v157
	v_mov_b32_e32 v155, v158
	v_pk_mul_f32 v[156:157], v[124:125], v[154:155]
	v_mov_b32_e32 v158, v124
	v_pk_mul_f32 v[158:159], v[158:159], v[156:157]
	v_mul_f32_e32 v167, v163, v181
	v_mov_b32_e32 v159, v127
	v_mul_f32_e32 v183, v163, v167
	v_pk_mul_f32 v[160:161], v[124:125], v[158:159]
	v_mul_f32_e32 v182, v163, v183
	v_mul_f32_e32 v151, v124, v160
	v_mul_f32_e32 v185, v163, v182
	v_mul_f32_e32 v155, v124, v151
	v_mul_f32_e32 v124, v180, v190
	v_mul_f32_e32 v125, v181, v191
	v_fma_f32 v153, v126, v166, v153
	v_mul_f32_e32 v184, v163, v185
	v_cvt_pk_bf16_f32 v124, v124, v125
	v_mul_f32_e32 v125, v167, v153
	v_mul_f32_e32 v126, v183, v193
	v_fma_f32 v120, v120, v188, v157
	v_mul_f32_e32 v159, v163, v184
	v_cvt_pk_bf16_f32 v125, v125, v126
	v_mul_f32_e32 v126, v182, v120
	v_mul_f32_e32 v127, v185, v121
	v_fma_f32 v122, v122, v188, v161
	v_cvt_pk_bf16_f32 v126, v126, v127
	v_mul_f32_e32 v127, v184, v122
	v_mul_f32_e32 v157, v159, v123
	v_cvt_pk_bf16_f32 v127, v127, v157
	v_mul_f32_e32 v157, v150, v190
	v_mul_f32_e32 v120, v158, v120
	v_mul_f32_e32 v121, v160, v121
	v_mul_f32_e32 v161, v152, v191
	v_cvt_pk_bf16_f32 v188, v157, v161
	v_mul_f32_e32 v153, v154, v153
	v_mul_f32_e32 v157, v156, v193
	v_cvt_pk_bf16_f32 v189, v153, v157
	v_cvt_pk_bf16_f32 v190, v120, v121
	v_mul_f32_e32 v120, v151, v122
	v_mul_f32_e32 v121, v155, v123
	v_cvt_pk_bf16_f32 v191, v120, v121
	v_lshlrev_b64 v[120:121], 17, v[164:165]
	v_lshl_add_u64 v[120:121], s[80:81], 0, v[120:121]
	v_ashrrev_i32_e32 v163, 31, v162
	v_lshl_add_u64 v[120:121], v[162:163], 1, v[120:121]
	s_mov_b64 s[0:1], 0x2000000
	global_store_dwordx4 v[120:121], v[124:127], off
	s_nop 1
	v_lshl_add_u64 v[126:127], v[120:121], 0, s[0:1]
	s_brev_b32 s0, 64
	v_add_co_u32_e64 v122, s[4:5], s0, v120
	s_nop 1
	v_addc_co_u32_e64 v123, s[4:5], 0, v121, s[4:5]
	global_store_dwordx4 v[122:123], v[188:191], off
	v_add_u32_e32 v122, 0x80, v162
	v_lshrrev_b32_e32 v122, 2, v122
	v_and_b32_e32 v153, 0x1f0, v122
	v_add_u32_e32 v122, v153, v192
	v_add_u32_e32 v124, v153, v136
	v_ashrrev_i32_e32 v123, 31, v122
	v_ashrrev_i32_e32 v125, 31, v124
	v_lshl_add_u64 v[122:123], v[122:123], 2, s[16:17]
	v_lshl_add_u64 v[124:125], v[124:125], 2, s[16:17]
	global_load_dword v163, v[122:123], off
	global_load_dword v164, v[124:125], off
	ds_bpermute_b32 v157, v177, v116
	v_mov_b32_e32 v162, v116
	ds_bpermute_b32 v116, v177, v117
	ds_bpermute_b32 v161, v177, v118
	ds_bpermute_b32 v166, v177, v119
	s_waitcnt lgkmcnt(3)
; __device__ __forceinline__ unsigned cvt_pk_bf16(float lo, float hi) { unsigned r; asm volatile("v_cvt_pk_bf16_f32 %0, %1, %2" : "=v"(r) : "v"(lo), "v"(hi)); return r; }
;     __device__ __forceinline__ void operator()(const AccT& acc, const Unit& u, int wr, int wc, int fr, int fq) const {
;     ...
;                 const int r = rbase + ai * 128 + m * 16;
;                 const int d = 4 * (2 * m + (fr >> 3)) + j;
; #pragma unroll
;                 for (int bj = 0; bj < 2; ++bj) {
;                     const int t0 = tb + bj * 128;
;                     float v[8];
; #pragma unroll
;                     for (int jj = 0; jj < 4; ++jj) { v[jj] = acc[ai][bj][m][0][jj]; v[4 + jj] = acc[ai][bj][m][1][jj]; }
;                     if constexpr (ROPE) {
;                         const int t = t0 & 2047;
; #pragma unroll
;                         for (int hf = 0; hf < 2; ++hf) {
;                             f32x4 cs, sn;
;                             if (m < 2) { const float c1 = ropeA[(t >> 6) * 16 + d], s1 = ropeA[1024 + (t >> 6) * 16 + d]; cs = (f32x4){c1, c1, c1, c1}; sn = (f32x4){s1, s1, s1, s1}; }
;                             else { const float* cb = ropeA + 2048 + (d - 16) * 64 + (t & 63) + 4 * hf; cs = *(const f32x4*)(cb); sn = *(const f32x4*)(cb + 1024); }
; #pragma unroll
;                             for (int jj = 0; jj < 4; ++jj) { const float pr = __shfl_xor(v[4 * hf + jj], 4); v[4 * hf + jj] = v[4 * hf + jj] * cs[jj] + sgn * pr * sn[jj]; }
;                             __builtin_amdgcn_sched_barrier(0);
;                         }
;                     }
;                     float zf[8], zb[8]; zf[0] = zf0; zb[0] = zb0;
; #pragma unroll
;                     for (int jj = 1; jj < 8; ++jj) { zf[jj] = zf[jj - 1] * zfs; zb[jj] = zb[jj - 1] * zbs; }
;                     u32x4 wf, wb;
;                     wf.x = cvt_pk_bf16(v[0] * zf[0], v[1] * zf[1]); wf.y = cvt_pk_bf16(v[2] * zf[2], v[3] * zf[3]); wf.z = cvt_pk_bf16(v[4] * zf[4], v[5] * zf[5]); wf.w = cvt_pk_bf16(v[6] * zf[6], v[7] * zf[7]);
;                     wb.x = cvt_pk_bf16(v[0] * zb[0], v[1] * zb[1]); wb.y = cvt_pk_bf16(v[2] * zb[2], v[3] * zb[3]); wb.z = cvt_pk_bf16(v[4] * zb[4], v[5] * zb[5]); wb.w = cvt_pk_bf16(v[6] * zb[6], v[7] * zb[7]);
;                     *(u32x4*)(KTZ + (size_t)r * NT + t0) = wf;
;                     *(u32x4*)(KTZ + (size_t)(256 + r) * NT + t0) = wb;
	v_cndmask_b32_e64 v165, v157, -v157, vcc
	s_waitcnt vmcnt(0)
	v_pk_mul_f32 v[188:189], v[162:163], v[164:165]
	s_waitcnt lgkmcnt(2)
	v_cndmask_b32_e64 v165, v116, -v116, vcc
	v_mov_b32_e32 v162, v117
	v_pk_mul_f32 v[116:117], v[162:163], v[164:165]
	s_waitcnt lgkmcnt(1)
	v_cndmask_b32_e64 v165, v161, -v161, vcc
	v_mov_b32_e32 v162, v118
	v_add_f32_e32 v161, v116, v117
	v_pk_mul_f32 v[116:117], v[162:163], v[164:165]
	s_waitcnt lgkmcnt(0)
	v_cndmask_b32_e64 v165, v166, -v166, vcc
	v_mov_b32_e32 v162, v119
	v_add_f32_e32 v166, v116, v117
	v_pk_mul_f32 v[116:117], v[162:163], v[164:165]
	v_add_f32_e32 v157, v188, v189
	v_add_f32_e32 v164, v116, v117
	global_load_dword v117, v[122:123], off
	global_load_dword v118, v[124:125], off
	ds_bpermute_b32 v119, v177, v112
	v_mov_b32_e32 v116, v112
	ds_bpermute_b32 v112, v177, v113
	ds_bpermute_b32 v165, v177, v114
	ds_bpermute_b32 v188, v177, v115
	s_waitcnt lgkmcnt(3)
	v_cndmask_b32_e64 v119, v119, -v119, vcc
	s_waitcnt vmcnt(0)
	v_pk_mul_f32 v[162:163], v[116:117], v[118:119]
	s_waitcnt lgkmcnt(2)
	v_cndmask_b32_e64 v119, v112, -v112, vcc
	v_mov_b32_e32 v116, v113
	v_pk_mul_f32 v[112:113], v[116:117], v[118:119]
	s_waitcnt lgkmcnt(1)
	v_cndmask_b32_e64 v119, v165, -v165, vcc
	v_mov_b32_e32 v116, v114
	v_add_f32_e32 v162, v162, v163
	v_add_f32_e32 v163, v112, v113
	v_pk_mul_f32 v[112:113], v[116:117], v[118:119]
	s_waitcnt lgkmcnt(0)
	v_cndmask_b32_e64 v119, v188, -v188, vcc
	v_mov_b32_e32 v116, v115
	v_add_f32_e32 v165, v112, v113
	v_pk_mul_f32 v[112:113], v[116:117], v[118:119]
	s_nop 0
	v_add_f32_e32 v119, v112, v113
	v_mul_f32_e32 v112, v180, v157
	v_mul_f32_e32 v113, v181, v161
	v_cvt_pk_bf16_f32 v112, v112, v113
	v_mul_f32_e32 v113, v167, v166
	v_mul_f32_e32 v114, v183, v164
	v_cvt_pk_bf16_f32 v113, v113, v114
	v_mul_f32_e32 v114, v182, v162
	v_mul_f32_e32 v115, v185, v163
	v_cvt_pk_bf16_f32 v114, v114, v115
	v_mul_f32_e32 v115, v184, v165
	v_mul_f32_e32 v116, v159, v119
	v_cvt_pk_bf16_f32 v115, v115, v116
	v_mul_f32_e32 v116, v150, v157
	v_mul_f32_e32 v117, v152, v161
	v_cvt_pk_bf16_f32 v116, v116, v117
	v_mul_f32_e32 v117, v154, v166
	v_mul_f32_e32 v118, v156, v164
	v_cvt_pk_bf16_f32 v117, v117, v118
	v_mul_f32_e32 v118, v158, v162
	v_mul_f32_e32 v157, v160, v163
	v_mul_f32_e32 v119, v155, v119
	v_cvt_pk_bf16_f32 v118, v118, v157
	v_mul_f32_e32 v157, v151, v165
	v_cvt_pk_bf16_f32 v119, v157, v119
	global_store_dwordx4 v[120:121], v[112:115], off offset:256
	global_store_dwordx4 v[126:127], v[116:119], off offset:256
	v_add_u32_e32 v161, 0x408, v136
	v_add_u32_e32 v157, 8, v136
	v_add_u32_e32 v112, v161, v187
	v_add_u32_e32 v114, v187, v157
	v_ashrrev_i32_e32 v113, 31, v112
	v_ashrrev_i32_e32 v115, 31, v114
	v_lshl_add_u64 v[112:113], v[112:113], 2, s[16:17]
	v_lshl_add_u64 v[114:115], v[114:115], 2, s[16:17]
	global_load_dword v117, v[112:113], off
	global_load_dword v118, v[114:115], off
	ds_bpermute_b32 v119, v177, v108
	v_mov_b32_e32 v116, v108
	ds_bpermute_b32 v108, v177, v109
	ds_bpermute_b32 v162, v177, v110
	ds_bpermute_b32 v163, v177, v111
	s_waitcnt lgkmcnt(3)
	v_cndmask_b32_e64 v119, v119, -v119, vcc
	s_waitcnt vmcnt(0)
	v_pk_mul_f32 v[126:127], v[116:117], v[118:119]
	s_waitcnt lgkmcnt(2)
	v_cndmask_b32_e64 v119, v108, -v108, vcc
	v_mov_b32_e32 v116, v109
	v_pk_mul_f32 v[108:109], v[116:117], v[118:119]
	s_waitcnt lgkmcnt(1)
	v_cndmask_b32_e64 v119, v162, -v162, vcc
	v_mov_b32_e32 v116, v110
	v_add_f32_e32 v126, v126, v127
	v_add_f32_e32 v127, v108, v109
	v_pk_mul_f32 v[108:109], v[116:117], v[118:119]
	s_waitcnt lgkmcnt(0)
	v_cndmask_b32_e64 v119, v163, -v163, vcc
	v_mov_b32_e32 v116, v111
	v_add_f32_e32 v162, v108, v109
	v_pk_mul_f32 v[108:109], v[116:117], v[118:119]
	s_nop 0
	v_add_f32_e32 v118, v108, v109
	global_load_dword v109, v[112:113], off
	global_load_dword v110, v[114:115], off
	ds_bpermute_b32 v111, v177, v104
	v_mov_b32_e32 v108, v104
	ds_bpermute_b32 v104, v177, v105
	ds_bpermute_b32 v119, v177, v106
	ds_bpermute_b32 v163, v177, v107
	s_waitcnt lgkmcnt(3)
	v_cndmask_b32_e64 v111, v111, -v111, vcc
	s_waitcnt vmcnt(0)
	v_pk_mul_f32 v[116:117], v[108:109], v[110:111]
	s_waitcnt lgkmcnt(2)
	v_cndmask_b32_e64 v111, v104, -v104, vcc
	v_mov_b32_e32 v108, v105
	v_pk_mul_f32 v[104:105], v[108:109], v[110:111]
	s_waitcnt lgkmcnt(1)
	v_cndmask_b32_e64 v111, v119, -v119, vcc
	v_mov_b32_e32 v108, v106
	v_add_f32_e32 v119, v104, v105
	v_pk_mul_f32 v[104:105], v[108:109], v[110:111]
	s_waitcnt lgkmcnt(0)
	v_cndmask_b32_e64 v111, v163, -v163, vcc
	v_mov_b32_e32 v108, v107
	v_add_f32_e32 v163, v104, v105
	v_pk_mul_f32 v[104:105], v[108:109], v[110:111]
	v_add_f32_e32 v164, v116, v117
	v_add_f32_e32 v108, v104, v105
	v_mul_f32_e32 v104, v180, v126
	v_mul_f32_e32 v105, v181, v127
	v_cvt_pk_bf16_f32 v104, v104, v105
	v_mul_f32_e32 v105, v167, v162
	v_mul_f32_e32 v106, v183, v118
	v_cvt_pk_bf16_f32 v105, v105, v106
	v_mul_f32_e32 v106, v182, v164
	v_mul_f32_e32 v107, v185, v119
	v_cvt_pk_bf16_f32 v106, v106, v107
	v_mul_f32_e32 v107, v184, v163
	v_mul_f32_e32 v109, v159, v108
	v_cvt_pk_bf16_f32 v107, v107, v109
	v_mul_f32_e32 v109, v150, v126
	v_mul_f32_e32 v110, v152, v127
	v_cvt_pk_bf16_f32 v116, v109, v110
	v_mul_f32_e32 v109, v154, v162
	v_mul_f32_e32 v110, v156, v118
	v_cvt_pk_bf16_f32 v117, v109, v110
	v_mul_f32_e32 v109, v158, v164
	v_mul_f32_e32 v110, v160, v119
	v_cvt_pk_bf16_f32 v118, v109, v110
	v_mul_f32_e32 v109, v151, v163
	v_mul_f32_e32 v108, v155, v108
	s_mov_b64 s[0:1], 0x200000
	v_cvt_pk_bf16_f32 v119, v109, v108
	v_lshl_add_u64 v[108:109], v[120:121], 0, s[0:1]
	s_mov_b32 s0, 0x200000
	v_add_co_u32_e64 v110, s[4:5], s0, v120
	s_mov_b64 s[0:1], 0x2200000
	s_nop 0
	v_addc_co_u32_e64 v111, s[4:5], 0, v121, s[4:5]
	global_store_dwordx4 v[110:111], v[104:107], off
	v_lshl_add_u64 v[110:111], v[120:121], 0, s[0:1]
	s_mov_b32 s0, 0x2200000
	v_add_co_u32_e64 v104, s[4:5], s0, v120
	s_nop 1
	v_addc_co_u32_e64 v105, s[4:5], 0, v121, s[4:5]
	global_store_dwordx4 v[104:105], v[116:119], off
	v_add_u32_e32 v104, v153, v161
	v_add_u32_e32 v106, v153, v157
	v_ashrrev_i32_e32 v105, 31, v104
	v_ashrrev_i32_e32 v107, 31, v106
	v_lshl_add_u64 v[104:105], v[104:105], 2, s[16:17]
	v_lshl_add_u64 v[106:107], v[106:107], 2, s[16:17]
	global_load_dword v117, v[104:105], off
	global_load_dword v118, v[106:107], off
	ds_bpermute_b32 v119, v177, v100
	v_mov_b32_e32 v116, v100
	ds_bpermute_b32 v100, v177, v101
	ds_bpermute_b32 v153, v177, v102
	ds_bpermute_b32 v157, v177, v103
	s_waitcnt lgkmcnt(3)
; __device__ __forceinline__ unsigned cvt_pk_bf16(float lo, float hi) { unsigned r; asm volatile("v_cvt_pk_bf16_f32 %0, %1, %2" : "=v"(r) : "v"(lo), "v"(hi)); return r; }
;     __device__ __forceinline__ void operator()(const AccT& acc, const Unit& u, int wr, int wc, int fr, int fq) const {
;     ...
;                         const int t = t0 & 2047;
; #pragma unroll
;                         for (int hf = 0; hf < 2; ++hf) {
;                             f32x4 cs, sn;
;                             if (m < 2) { const float c1 = ropeA[(t >> 6) * 16 + d], s1 = ropeA[1024 + (t >> 6) * 16 + d]; cs = (f32x4){c1, c1, c1, c1}; sn = (f32x4){s1, s1, s1, s1}; }
;                             else { const float* cb = ropeA + 2048 + (d - 16) * 64 + (t & 63) + 4 * hf; cs = *(const f32x4*)(cb); sn = *(const f32x4*)(cb + 1024); }
; #pragma unroll
;                             for (int jj = 0; jj < 4; ++jj) { const float pr = __shfl_xor(v[4 * hf + jj], 4); v[4 * hf + jj] = v[4 * hf + jj] * cs[jj] + sgn * pr * sn[jj]; }
;                             __builtin_amdgcn_sched_barrier(0);
;                         }
;                     }
;                     float zf[8], zb[8]; zf[0] = zf0; zb[0] = zb0;
; #pragma unroll
;                     for (int jj = 1; jj < 8; ++jj) { zf[jj] = zf[jj - 1] * zfs; zb[jj] = zb[jj - 1] * zbs; }
;                     u32x4 wf, wb;
;                     wf.x = cvt_pk_bf16(v[0] * zf[0], v[1] * zf[1]); wf.y = cvt_pk_bf16(v[2] * zf[2], v[3] * zf[3]); wf.z = cvt_pk_bf16(v[4] * zf[4], v[5] * zf[5]); wf.w = cvt_pk_bf16(v[6] * zf[6], v[7] * zf[7]);
;                     wb.x = cvt_pk_bf16(v[0] * zb[0], v[1] * zb[1]); wb.y = cvt_pk_bf16(v[2] * zb[2], v[3] * zb[3]); wb.z = cvt_pk_bf16(v[4] * zb[4], v[5] * zb[5]); wb.w = cvt_pk_bf16(v[6] * zb[6], v[7] * zb[7]);
;                     *(u32x4*)(KTZ + (size_t)r * NT + t0) = wf;
;                     *(u32x4*)(KTZ + (size_t)(256 + r) * NT + t0) = wb;
	v_cndmask_b32_e64 v119, v119, -v119, vcc
	s_waitcnt vmcnt(0)
	v_pk_mul_f32 v[126:127], v[116:117], v[118:119]
	s_waitcnt lgkmcnt(2)
	v_cndmask_b32_e64 v119, v100, -v100, vcc
	v_mov_b32_e32 v116, v101
	v_pk_mul_f32 v[100:101], v[116:117], v[118:119]
	s_waitcnt lgkmcnt(1)
	v_cndmask_b32_e64 v119, v153, -v153, vcc
	v_mov_b32_e32 v116, v102
	v_add_f32_e32 v126, v126, v127
	v_add_f32_e32 v127, v100, v101
	v_pk_mul_f32 v[100:101], v[116:117], v[118:119]
	s_waitcnt lgkmcnt(0)
	v_cndmask_b32_e64 v119, v157, -v157, vcc
	v_mov_b32_e32 v116, v103
	v_add_f32_e32 v153, v100, v101
	v_pk_mul_f32 v[100:101], v[116:117], v[118:119]
	s_nop 0
	v_add_f32_e32 v118, v100, v101
	global_load_dword v101, v[104:105], off
	global_load_dword v102, v[106:107], off
	ds_bpermute_b32 v103, v177, v96
	v_mov_b32_e32 v100, v96
	ds_bpermute_b32 v96, v177, v97
	ds_bpermute_b32 v119, v177, v98
	ds_bpermute_b32 v157, v177, v99
	s_waitcnt lgkmcnt(3)
	v_cndmask_b32_e64 v103, v103, -v103, vcc
	s_waitcnt vmcnt(0)
	v_pk_mul_f32 v[116:117], v[100:101], v[102:103]
	s_waitcnt lgkmcnt(2)
	v_cndmask_b32_e64 v103, v96, -v96, vcc
	v_mov_b32_e32 v100, v97
	v_pk_mul_f32 v[96:97], v[100:101], v[102:103]
	s_waitcnt lgkmcnt(1)
	v_cndmask_b32_e64 v103, v119, -v119, vcc
	v_mov_b32_e32 v100, v98
	v_add_f32_e32 v116, v116, v117
	v_add_f32_e32 v117, v96, v97
	v_pk_mul_f32 v[96:97], v[100:101], v[102:103]
	s_waitcnt lgkmcnt(0)
	v_cndmask_b32_e64 v103, v157, -v157, vcc
	v_mov_b32_e32 v100, v99
	v_add_f32_e32 v119, v96, v97
	v_pk_mul_f32 v[96:97], v[100:101], v[102:103]
	s_nop 0
	v_add_f32_e32 v103, v96, v97
	v_mul_f32_e32 v96, v180, v126
	v_mul_f32_e32 v97, v181, v127
	v_cvt_pk_bf16_f32 v96, v96, v97
	v_mul_f32_e32 v97, v167, v153
	v_mul_f32_e32 v98, v183, v118
	v_cvt_pk_bf16_f32 v97, v97, v98
	v_mul_f32_e32 v98, v182, v116
	v_mul_f32_e32 v99, v185, v117
	v_cvt_pk_bf16_f32 v98, v98, v99
	v_mul_f32_e32 v99, v184, v119
	v_mul_f32_e32 v100, v159, v103
	v_cvt_pk_bf16_f32 v99, v99, v100
	v_mul_f32_e32 v100, v150, v126
	v_mul_f32_e32 v101, v152, v127
	v_cvt_pk_bf16_f32 v100, v100, v101
	v_mul_f32_e32 v101, v154, v153
	v_mul_f32_e32 v102, v156, v118
	v_cvt_pk_bf16_f32 v101, v101, v102
	v_mul_f32_e32 v102, v158, v116
	v_mul_f32_e32 v116, v160, v117
	v_mul_f32_e32 v103, v155, v103
	v_cvt_pk_bf16_f32 v102, v102, v116
	v_mul_f32_e32 v116, v151, v119
	v_cvt_pk_bf16_f32 v103, v116, v103
	global_store_dwordx4 v[108:109], v[96:99], off offset:256
	global_store_dwordx4 v[110:111], v[100:103], off offset:256
	s_nop 1
	v_lshlrev_b32_e32 v100, 6, v136
	v_ashrrev_i32_e32 v101, 31, v100
	v_lshlrev_b64 v[102:103], 2, v[100:101]
	v_lshl_add_u64 v[96:97], s[24:25], 0, v[102:103]
	v_lshlrev_b32_e32 v136, 2, v186
	v_lshl_add_u64 v[96:97], v[96:97], 0, v[136:137]
	v_add_co_u32_e64 v98, s[4:5], s61, v96
	ds_bpermute_b32 v101, v177, v92
	s_nop 0
	v_addc_co_u32_e64 v99, s[4:5], 0, v97, s[4:5]
	global_load_dwordx4 v[108:111], v[98:99], off
	global_load_dwordx4 v[116:119], v[96:97], off
	ds_bpermute_b32 v127, v177, v93
	ds_bpermute_b32 v153, v177, v94
	ds_bpermute_b32 v157, v177, v95
	v_mov_b32_e32 v126, v92
	v_mov_b32_e32 v92, v94
	s_waitcnt lgkmcnt(3)
	v_cndmask_b32_e64 v163, v101, -v101, vcc
	s_waitcnt lgkmcnt(2)
	v_cndmask_b32_e64 v165, v127, -v127, vcc
	s_waitcnt lgkmcnt(1)
	v_cndmask_b32_e64 v187, v153, -v153, vcc
	s_waitcnt lgkmcnt(0)
	v_cndmask_b32_e64 v189, v157, -v157, vcc
	s_waitcnt vmcnt(1)
	v_mov_b32_e32 v127, v108
	s_waitcnt vmcnt(0)
	v_mov_b32_e32 v162, v116
	v_mov_b32_e32 v108, v93
	v_mov_b32_e32 v164, v117
	v_mov_b32_e32 v93, v110
	v_mov_b32_e32 v186, v118
	v_mov_b32_e32 v110, v95
	v_mov_b32_e32 v188, v119
	v_pk_mul_f32 v[94:95], v[126:127], v[162:163]
	v_pk_mul_f32 v[108:109], v[108:109], v[164:165]
	v_pk_mul_f32 v[92:93], v[92:93], v[186:187]
	v_pk_mul_f32 v[110:111], v[110:111], v[188:189]
	v_add_f32_e32 v101, v94, v95
	v_add_f32_e32 v153, v108, v109
	v_add_f32_e32 v157, v92, v93
	v_add_f32_e32 v161, v110, v111
	v_lshl_add_u64 v[92:93], s[16:17], 0, v[102:103]
	v_lshl_add_u64 v[94:95], v[92:93], 0, v[136:137]
	v_add_co_u32_e64 v92, s[4:5], s62, v94
	ds_bpermute_b32 v103, v177, v88
	s_nop 0
	v_addc_co_u32_e64 v93, s[4:5], 0, v95, s[4:5]
	v_add_co_u32_e64 v94, s[4:5], s49, v94
	ds_bpermute_b32 v126, v177, v89
	s_nop 0
	v_addc_co_u32_e64 v95, s[4:5], 0, v95, s[4:5]
	global_load_dwordx4 v[108:111], v[92:93], off offset:16
	global_load_dwordx4 v[116:119], v[94:95], off offset:16
	ds_bpermute_b32 v162, v177, v90
	ds_bpermute_b32 v164, v177, v91
	v_mov_b32_e32 v102, v88
	v_mov_b32_e32 v88, v90
	s_waitcnt lgkmcnt(3)
	v_cndmask_b32_e64 v127, v103, -v103, vcc
	s_waitcnt lgkmcnt(2)
	v_cndmask_b32_e64 v163, v126, -v126, vcc
	s_waitcnt lgkmcnt(1)
	v_cndmask_b32_e64 v165, v162, -v162, vcc
	s_waitcnt lgkmcnt(0)
	v_cndmask_b32_e64 v187, v164, -v164, vcc
	s_waitcnt vmcnt(1)
	v_mov_b32_e32 v103, v108
	s_waitcnt vmcnt(0)
; __device__ __forceinline__ unsigned cvt_pk_bf16(float lo, float hi) { unsigned r; asm volatile("v_cvt_pk_bf16_f32 %0, %1, %2" : "=v"(r) : "v"(lo), "v"(hi)); return r; }
;     __device__ __forceinline__ void operator()(const AccT& acc, const Unit& u, int wr, int wc, int fr, int fq) const {
;     ...
;                         const int t = t0 & 2047;
; #pragma unroll
;                         for (int hf = 0; hf < 2; ++hf) {
;                             f32x4 cs, sn;
;                             if (m < 2) { const float c1 = ropeA[(t >> 6) * 16 + d], s1 = ropeA[1024 + (t >> 6) * 16 + d]; cs = (f32x4){c1, c1, c1, c1}; sn = (f32x4){s1, s1, s1, s1}; }
;                             else { const float* cb = ropeA + 2048 + (d - 16) * 64 + (t & 63) + 4 * hf; cs = *(const f32x4*)(cb); sn = *(const f32x4*)(cb + 1024); }
; #pragma unroll
;                             for (int jj = 0; jj < 4; ++jj) { const float pr = __shfl_xor(v[4 * hf + jj], 4); v[4 * hf + jj] = v[4 * hf + jj] * cs[jj] + sgn * pr * sn[jj]; }
;                             __builtin_amdgcn_sched_barrier(0);
;                         }
;                     }
;                     float zf[8], zb[8]; zf[0] = zf0; zb[0] = zb0;
; #pragma unroll
;                     for (int jj = 1; jj < 8; ++jj) { zf[jj] = zf[jj - 1] * zfs; zb[jj] = zb[jj - 1] * zbs; }
;                     u32x4 wf, wb;
;                     wf.x = cvt_pk_bf16(v[0] * zf[0], v[1] * zf[1]); wf.y = cvt_pk_bf16(v[2] * zf[2], v[3] * zf[3]); wf.z = cvt_pk_bf16(v[4] * zf[4], v[5] * zf[5]); wf.w = cvt_pk_bf16(v[6] * zf[6], v[7] * zf[7]);
;                     wb.x = cvt_pk_bf16(v[0] * zb[0], v[1] * zb[1]); wb.y = cvt_pk_bf16(v[2] * zb[2], v[3] * zb[3]); wb.z = cvt_pk_bf16(v[4] * zb[4], v[5] * zb[5]); wb.w = cvt_pk_bf16(v[6] * zb[6], v[7] * zb[7]);
;                     *(u32x4*)(KTZ + (size_t)r * NT + t0) = wf;
;                     *(u32x4*)(KTZ + (size_t)(256 + r) * NT + t0) = wb;
	v_mov_b32_e32 v126, v116
	v_mov_b32_e32 v108, v89
	v_mov_b32_e32 v162, v117
	v_mov_b32_e32 v89, v110
	v_mov_b32_e32 v164, v118
	v_mov_b32_e32 v110, v91
	v_mov_b32_e32 v186, v119
	v_pk_mul_f32 v[90:91], v[102:103], v[126:127]
	v_pk_mul_f32 v[102:103], v[108:109], v[162:163]
	v_pk_mul_f32 v[88:89], v[88:89], v[164:165]
	v_pk_mul_f32 v[108:109], v[110:111], v[186:187]
	v_add_f32_e32 v90, v90, v91
	v_add_f32_e32 v91, v102, v103
	v_add_f32_e32 v88, v88, v89
	v_add_f32_e32 v89, v108, v109
	v_mul_f32_e32 v102, v180, v101
	v_mul_f32_e32 v103, v181, v153
	v_cvt_pk_bf16_f32 v108, v102, v103
	v_mul_f32_e32 v102, v167, v157
	v_mul_f32_e32 v103, v183, v161
	v_cvt_pk_bf16_f32 v109, v102, v103
	v_mul_f32_e32 v102, v182, v90
	v_mul_f32_e32 v103, v185, v91
	v_cvt_pk_bf16_f32 v110, v102, v103
	v_mul_f32_e32 v102, v184, v88
	v_mul_f32_e32 v103, v159, v89
	v_cvt_pk_bf16_f32 v111, v102, v103
	v_mul_f32_e32 v101, v150, v101
	v_mul_f32_e32 v102, v152, v153
	v_mul_f32_e32 v88, v151, v88
	v_mul_f32_e32 v89, v155, v89
	s_mov_b64 s[0:1], 0x400000
	v_cvt_pk_bf16_f32 v116, v101, v102
	v_mul_f32_e32 v101, v154, v157
	v_mul_f32_e32 v102, v156, v161
	v_cvt_pk_bf16_f32 v117, v101, v102
	v_mul_f32_e32 v90, v158, v90
	v_mul_f32_e32 v91, v160, v91
	v_cvt_pk_bf16_f32 v118, v90, v91
	v_cvt_pk_bf16_f32 v119, v88, v89
	v_lshl_add_u64 v[88:89], v[120:121], 0, s[0:1]
	s_mov_b32 s0, 0x400000
	v_add_co_u32_e64 v90, s[4:5], s0, v120
	s_mov_b64 s[0:1], 0x2400000
	s_nop 0
	v_addc_co_u32_e64 v91, s[4:5], 0, v121, s[4:5]
	global_store_dwordx4 v[90:91], v[108:111], off
	v_lshl_add_u64 v[90:91], v[120:121], 0, s[0:1]
	s_mov_b32 s0, 0x2400000
	v_add_co_u32_e64 v102, s[4:5], s0, v120
	s_nop 1
	v_addc_co_u32_e64 v103, s[4:5], 0, v121, s[4:5]
	global_store_dwordx4 v[102:103], v[116:119], off
	global_load_dwordx4 v[108:111], v[98:99], off
	s_nop 0
	global_load_dwordx4 v[116:119], v[96:97], off
	ds_bpermute_b32 v101, v177, v84
	ds_bpermute_b32 v103, v177, v85
	ds_bpermute_b32 v126, v177, v86
	ds_bpermute_b32 v153, v177, v87
	v_mov_b32_e32 v102, v84
	v_mov_b32_e32 v84, v86
	s_waitcnt lgkmcnt(3)
	v_cndmask_b32_e64 v127, v101, -v101, vcc
	s_waitcnt lgkmcnt(2)
	v_cndmask_b32_e64 v163, v103, -v103, vcc
	s_waitcnt lgkmcnt(1)
	v_cndmask_b32_e64 v165, v126, -v126, vcc
	s_waitcnt lgkmcnt(0)
	v_cndmask_b32_e64 v187, v153, -v153, vcc
	s_waitcnt vmcnt(1)
	v_mov_b32_e32 v103, v108
	s_waitcnt vmcnt(0)
	v_mov_b32_e32 v126, v116
	v_mov_b32_e32 v108, v85
	v_mov_b32_e32 v162, v117
	v_mov_b32_e32 v85, v110
	v_mov_b32_e32 v164, v118
	v_mov_b32_e32 v110, v87
	v_mov_b32_e32 v186, v119
	v_pk_mul_f32 v[86:87], v[102:103], v[126:127]
	v_pk_mul_f32 v[102:103], v[108:109], v[162:163]
	v_pk_mul_f32 v[84:85], v[84:85], v[164:165]
	v_pk_mul_f32 v[108:109], v[110:111], v[186:187]
	v_add_f32_e32 v101, v86, v87
	v_add_f32_e32 v153, v102, v103
	v_add_f32_e32 v157, v84, v85
	v_add_f32_e32 v161, v108, v109
	global_load_dwordx4 v[84:87], v[92:93], off offset:16
	global_load_dwordx4 v[108:111], v[94:95], off offset:16
	ds_bpermute_b32 v103, v177, v80
	ds_bpermute_b32 v116, v177, v81
	ds_bpermute_b32 v118, v177, v82
	ds_bpermute_b32 v126, v177, v83
	v_mov_b32_e32 v102, v80
	v_mov_b32_e32 v80, v82
	s_waitcnt lgkmcnt(3)
	v_cndmask_b32_e64 v117, v103, -v103, vcc
	s_waitcnt lgkmcnt(2)
	v_cndmask_b32_e64 v119, v116, -v116, vcc
	s_waitcnt lgkmcnt(1)
	v_cndmask_b32_e64 v127, v118, -v118, vcc
	s_waitcnt lgkmcnt(0)
	v_cndmask_b32_e64 v163, v126, -v126, vcc
	s_waitcnt vmcnt(1)
	v_mov_b32_e32 v103, v84
	s_waitcnt vmcnt(0)
	v_mov_b32_e32 v116, v108
	v_mov_b32_e32 v84, v81
	v_mov_b32_e32 v118, v109
	v_mov_b32_e32 v81, v86
	v_mov_b32_e32 v126, v110
	v_mov_b32_e32 v86, v83
	v_mov_b32_e32 v162, v111
	v_pk_mul_f32 v[82:83], v[102:103], v[116:117]
	v_pk_mul_f32 v[84:85], v[84:85], v[118:119]
	v_pk_mul_f32 v[80:81], v[80:81], v[126:127]
	v_pk_mul_f32 v[86:87], v[86:87], v[162:163]
	v_add_f32_e32 v102, v82, v83
	v_add_f32_e32 v103, v84, v85
	v_add_f32_e32 v108, v80, v81
	v_add_f32_e32 v87, v86, v87
	v_mul_f32_e32 v80, v180, v101
	v_mul_f32_e32 v81, v181, v153
	v_cvt_pk_bf16_f32 v80, v80, v81
	v_mul_f32_e32 v81, v167, v157
	v_mul_f32_e32 v82, v183, v161
	v_cvt_pk_bf16_f32 v81, v81, v82
	v_mul_f32_e32 v82, v182, v102
	v_mul_f32_e32 v83, v185, v103
	v_cvt_pk_bf16_f32 v82, v82, v83
	v_mul_f32_e32 v83, v184, v108
	v_mul_f32_e32 v84, v159, v87
	v_cvt_pk_bf16_f32 v83, v83, v84
	v_mul_f32_e32 v84, v150, v101
	v_mul_f32_e32 v85, v152, v153
	v_cvt_pk_bf16_f32 v84, v84, v85
	v_mul_f32_e32 v85, v154, v157
	v_mul_f32_e32 v86, v156, v161
	v_cvt_pk_bf16_f32 v85, v85, v86
	v_mul_f32_e32 v86, v158, v102
	v_mul_f32_e32 v101, v160, v103
	v_mul_f32_e32 v87, v155, v87
	v_cvt_pk_bf16_f32 v86, v86, v101
	v_mul_f32_e32 v101, v151, v108
	v_cvt_pk_bf16_f32 v87, v101, v87
	global_store_dwordx4 v[88:89], v[80:83], off offset:256
	global_store_dwordx4 v[90:91], v[84:87], off offset:256
	s_nop 0
	v_add_u32_e32 v80, 0x200, v100
	v_ashrrev_i32_e32 v81, 31, v80
	v_lshl_add_u64 v[82:83], s[24:25], 0, v[136:137]
	v_lshlrev_b64 v[100:101], 2, v[80:81]
	v_lshl_add_u64 v[80:81], v[82:83], 0, v[100:101]
	v_add_co_u32_e64 v82, s[4:5], s61, v80
	ds_bpermute_b32 v103, v177, v76
	s_nop 0
	v_addc_co_u32_e64 v83, s[4:5], 0, v81, s[4:5]
	global_load_dwordx4 v[84:87], v[82:83], off
	global_load_dwordx4 v[88:91], v[80:81], off
	ds_bpermute_b32 v108, v177, v77
	ds_bpermute_b32 v110, v177, v78
	ds_bpermute_b32 v116, v177, v79
	v_mov_b32_e32 v102, v76
	v_mov_b32_e32 v76, v78
	s_waitcnt lgkmcnt(3)
	v_cndmask_b32_e64 v109, v103, -v103, vcc
	s_waitcnt lgkmcnt(2)
	v_cndmask_b32_e64 v111, v108, -v108, vcc
	s_waitcnt lgkmcnt(1)
	v_cndmask_b32_e64 v117, v110, -v110, vcc
	s_waitcnt lgkmcnt(0)
; __device__ __forceinline__ unsigned cvt_pk_bf16(float lo, float hi) { unsigned r; asm volatile("v_cvt_pk_bf16_f32 %0, %1, %2" : "=v"(r) : "v"(lo), "v"(hi)); return r; }
;     __device__ __forceinline__ void operator()(const AccT& acc, const Unit& u, int wr, int wc, int fr, int fq) const {
;     ...
;                         const int t = t0 & 2047;
; #pragma unroll
;                         for (int hf = 0; hf < 2; ++hf) {
;                             f32x4 cs, sn;
;                             if (m < 2) { const float c1 = ropeA[(t >> 6) * 16 + d], s1 = ropeA[1024 + (t >> 6) * 16 + d]; cs = (f32x4){c1, c1, c1, c1}; sn = (f32x4){s1, s1, s1, s1}; }
;                             else { const float* cb = ropeA + 2048 + (d - 16) * 64 + (t & 63) + 4 * hf; cs = *(const f32x4*)(cb); sn = *(const f32x4*)(cb + 1024); }
; #pragma unroll
;                             for (int jj = 0; jj < 4; ++jj) { const float pr = __shfl_xor(v[4 * hf + jj], 4); v[4 * hf + jj] = v[4 * hf + jj] * cs[jj] + sgn * pr * sn[jj]; }
;                             __builtin_amdgcn_sched_barrier(0);
;                         }
;                     }
;                     float zf[8], zb[8]; zf[0] = zf0; zb[0] = zb0;
; #pragma unroll
;                     for (int jj = 1; jj < 8; ++jj) { zf[jj] = zf[jj - 1] * zfs; zb[jj] = zb[jj - 1] * zbs; }
;                     u32x4 wf, wb;
;                     wf.x = cvt_pk_bf16(v[0] * zf[0], v[1] * zf[1]); wf.y = cvt_pk_bf16(v[2] * zf[2], v[3] * zf[3]); wf.z = cvt_pk_bf16(v[4] * zf[4], v[5] * zf[5]); wf.w = cvt_pk_bf16(v[6] * zf[6], v[7] * zf[7]);
;                     wb.x = cvt_pk_bf16(v[0] * zb[0], v[1] * zb[1]); wb.y = cvt_pk_bf16(v[2] * zb[2], v[3] * zb[3]); wb.z = cvt_pk_bf16(v[4] * zb[4], v[5] * zb[5]); wb.w = cvt_pk_bf16(v[6] * zb[6], v[7] * zb[7]);
;                     *(u32x4*)(KTZ + (size_t)r * NT + t0) = wf;
;                     *(u32x4*)(KTZ + (size_t)(256 + r) * NT + t0) = wb;
	v_cndmask_b32_e64 v119, v116, -v116, vcc
	s_waitcnt vmcnt(1)
	v_mov_b32_e32 v103, v84
	s_waitcnt vmcnt(0)
	v_mov_b32_e32 v108, v88
	v_mov_b32_e32 v84, v77
	v_mov_b32_e32 v110, v89
	v_mov_b32_e32 v77, v86
	v_mov_b32_e32 v116, v90
	v_mov_b32_e32 v86, v79
	v_mov_b32_e32 v118, v91
	v_pk_mul_f32 v[78:79], v[102:103], v[108:109]
	v_pk_mul_f32 v[84:85], v[84:85], v[110:111]
	v_pk_mul_f32 v[76:77], v[76:77], v[116:117]
	v_pk_mul_f32 v[86:87], v[86:87], v[118:119]
	v_add_f32_e32 v118, v78, v79
	v_add_f32_e32 v119, v84, v85
	v_add_f32_e32 v126, v76, v77
	v_add_f32_e32 v127, v86, v87
	v_lshl_add_u64 v[76:77], s[16:17], 0, v[100:101]
	v_lshl_add_u64 v[78:79], v[76:77], 0, v[136:137]
	v_add_co_u32_e64 v76, s[4:5], s62, v78
	ds_bpermute_b32 v101, v177, v72
	s_nop 0
	v_addc_co_u32_e64 v77, s[4:5], 0, v79, s[4:5]
	v_add_co_u32_e64 v78, s[4:5], s49, v78
	ds_bpermute_b32 v102, v177, v73
	s_nop 0
	v_addc_co_u32_e64 v79, s[4:5], 0, v79, s[4:5]
	global_load_dwordx4 v[84:87], v[76:77], off offset:16
	global_load_dwordx4 v[88:91], v[78:79], off offset:16
	ds_bpermute_b32 v108, v177, v74
	ds_bpermute_b32 v110, v177, v75
	v_mov_b32_e32 v100, v72
	v_mov_b32_e32 v72, v74
	s_waitcnt lgkmcnt(3)
	v_cndmask_b32_e64 v103, v101, -v101, vcc
	s_waitcnt lgkmcnt(2)
	v_cndmask_b32_e64 v109, v102, -v102, vcc
	s_waitcnt lgkmcnt(1)
	v_cndmask_b32_e64 v111, v108, -v108, vcc
	s_waitcnt lgkmcnt(0)
	v_cndmask_b32_e64 v117, v110, -v110, vcc
	s_waitcnt vmcnt(1)
	v_mov_b32_e32 v101, v84
	s_waitcnt vmcnt(0)
	v_mov_b32_e32 v102, v88
	v_mov_b32_e32 v84, v73
	v_mov_b32_e32 v108, v89
	v_mov_b32_e32 v73, v86
	v_mov_b32_e32 v110, v90
	v_mov_b32_e32 v86, v75
	v_mov_b32_e32 v116, v91
	v_pk_mul_f32 v[74:75], v[100:101], v[102:103]
	v_pk_mul_f32 v[84:85], v[84:85], v[108:109]
	v_pk_mul_f32 v[72:73], v[72:73], v[110:111]
	v_pk_mul_f32 v[86:87], v[86:87], v[116:117]
	v_add_f32_e32 v74, v74, v75
	v_add_f32_e32 v75, v84, v85
	v_add_f32_e32 v72, v72, v73
	v_add_f32_e32 v73, v86, v87
	v_mul_f32_e32 v84, v180, v118
	v_mul_f32_e32 v85, v181, v119
	v_cvt_pk_bf16_f32 v84, v84, v85
	v_mul_f32_e32 v85, v167, v126
	v_mul_f32_e32 v86, v183, v127
	v_cvt_pk_bf16_f32 v85, v85, v86
	v_mul_f32_e32 v86, v182, v74
	v_mul_f32_e32 v87, v185, v75
	v_cvt_pk_bf16_f32 v86, v86, v87
	v_mul_f32_e32 v87, v184, v72
	v_mul_f32_e32 v88, v159, v73
	v_cvt_pk_bf16_f32 v87, v87, v88
	v_mul_f32_e32 v88, v150, v118
	v_mul_f32_e32 v89, v152, v119
	v_cvt_pk_bf16_f32 v88, v88, v89
	v_mul_f32_e32 v89, v154, v126
	v_mul_f32_e32 v90, v156, v127
	v_mul_f32_e32 v72, v151, v72
	v_mul_f32_e32 v73, v155, v73
	s_mov_b64 s[0:1], 0x600000
	v_cvt_pk_bf16_f32 v89, v89, v90
	v_mul_f32_e32 v74, v158, v74
	v_mul_f32_e32 v75, v160, v75
	v_cvt_pk_bf16_f32 v90, v74, v75
	v_cvt_pk_bf16_f32 v91, v72, v73
	v_lshl_add_u64 v[72:73], v[120:121], 0, s[0:1]
	s_mov_b32 s0, 0x600000
	v_add_co_u32_e64 v74, s[4:5], s0, v120
	s_mov_b64 s[0:1], 0x2600000
	s_nop 0
	v_addc_co_u32_e64 v75, s[4:5], 0, v121, s[4:5]
	global_store_dwordx4 v[74:75], v[84:87], off
	v_lshl_add_u64 v[74:75], v[120:121], 0, s[0:1]
	s_mov_b32 s0, 0x2600000
	v_add_co_u32_e64 v84, s[4:5], s0, v120
	s_nop 1
	v_addc_co_u32_e64 v85, s[4:5], 0, v121, s[4:5]
	global_store_dwordx4 v[84:85], v[88:91], off
	global_load_dwordx4 v[84:87], v[82:83], off
	s_nop 0
	global_load_dwordx4 v[88:91], v[80:81], off
	ds_bpermute_b32 v101, v177, v68
	ds_bpermute_b32 v102, v177, v69
	ds_bpermute_b32 v108, v177, v70
	ds_bpermute_b32 v110, v177, v71
	v_mov_b32_e32 v100, v68
	v_mov_b32_e32 v68, v70
	s_waitcnt lgkmcnt(3)
	v_cndmask_b32_e64 v103, v101, -v101, vcc
	s_waitcnt lgkmcnt(2)
	v_cndmask_b32_e64 v109, v102, -v102, vcc
	s_waitcnt lgkmcnt(1)
	v_cndmask_b32_e64 v111, v108, -v108, vcc
	s_waitcnt lgkmcnt(0)
	v_cndmask_b32_e64 v117, v110, -v110, vcc
	s_waitcnt vmcnt(1)
	v_mov_b32_e32 v101, v84
	s_waitcnt vmcnt(0)
	v_mov_b32_e32 v102, v88
	v_mov_b32_e32 v84, v69
	v_mov_b32_e32 v108, v89
	v_mov_b32_e32 v69, v86
	v_mov_b32_e32 v110, v90
	v_mov_b32_e32 v86, v71
	v_mov_b32_e32 v116, v91
	v_pk_mul_f32 v[70:71], v[100:101], v[102:103]
	v_pk_mul_f32 v[84:85], v[84:85], v[108:109]
	v_pk_mul_f32 v[68:69], v[68:69], v[110:111]
	v_pk_mul_f32 v[86:87], v[86:87], v[116:117]
	v_add_f32_e32 v110, v70, v71
	v_add_f32_e32 v111, v84, v85
	v_add_f32_e32 v116, v68, v69
	v_add_f32_e32 v117, v86, v87
	global_load_dwordx4 v[68:71], v[76:77], off offset:16
	global_load_dwordx4 v[84:87], v[78:79], off offset:16
	ds_bpermute_b32 v89, v177, v64
	ds_bpermute_b32 v90, v177, v65
	ds_bpermute_b32 v100, v177, v66
	ds_bpermute_b32 v102, v177, v67
	v_mov_b32_e32 v88, v64
	v_mov_b32_e32 v64, v66
	s_waitcnt lgkmcnt(3)
	v_cndmask_b32_e64 v91, v89, -v89, vcc
	s_waitcnt lgkmcnt(2)
	v_cndmask_b32_e64 v101, v90, -v90, vcc
	s_waitcnt lgkmcnt(1)
	v_cndmask_b32_e64 v103, v100, -v100, vcc
	s_waitcnt lgkmcnt(0)
	v_cndmask_b32_e64 v109, v102, -v102, vcc
	s_waitcnt vmcnt(1)
	v_mov_b32_e32 v89, v68
	s_waitcnt vmcnt(0)
;     __device__ __forceinline__ void operator()(const AccT& acc, const Unit& u, int wr, int wc, int fr, int fq) const {
;     ...
;         for (int ai = 0; ai < 2; ++ai) {
;             const int hh = 2 * ai + wr;
;             const float l2f = lgd[hh] * 1.4426950408889634f, l2b = lgd[4 + hh] * 1.4426950408889634f;
;             const float zf0 = exp2f((float)(127 - o0) * l2f), zfs = exp2f(-l2f), zb0 = exp2f((float)o0 * l2b), zbs = exp2f(l2b);
; #pragma unroll
;             for (int m = 0; m < 4; ++m) {
;                 const int r = rbase + ai * 128 + m * 16;
;                 const int d = 4 * (2 * m + (fr >> 3)) + j;
; #pragma unroll
;                 for (int bj = 0; bj < 2; ++bj) {
;                     const int t0 = tb + bj * 128;
;                     float v[8];
; #pragma unroll
;                     for (int jj = 0; jj < 4; ++jj) { v[jj] = acc[ai][bj][m][0][jj]; v[4 + jj] = acc[ai][bj][m][1][jj]; }
;                     if constexpr (ROPE) {
;                         const int t = t0 & 2047;
; #pragma unroll
;                         for (int hf = 0; hf < 2; ++hf) {
;                             f32x4 cs, sn;
;                             if (m < 2) { const float c1 = ropeA[(t >> 6) * 16 + d], s1 = ropeA[1024 + (t >> 6) * 16 + d]; cs = (f32x4){c1, c1, c1, c1}; sn = (f32x4){s1, s1, s1, s1}; }
;                             else { const float* cb = ropeA + 2048 + (d - 16) * 64 + (t & 63) + 4 * hf; cs = *(const f32x4*)(cb); sn = *(const f32x4*)(cb + 1024); }
; #pragma unroll
;                             for (int jj = 0; jj < 4; ++jj) { const float pr = __shfl_xor(v[4 * hf + jj], 4); v[4 * hf + jj] = v[4 * hf + jj] * cs[jj] + sgn * pr * sn[jj]; }
;                             __builtin_amdgcn_sched_barrier(0);
;                         }
;                     }
;                     float zf[8], zb[8]; zf[0] = zf0; zb[0] = zb0;
; #pragma unroll
;                     for (int jj = 1; jj < 8; ++jj) { zf[jj] = zf[jj - 1] * zfs; zb[jj] = zb[jj - 1] * zbs; }
;                     u32x4 wf, wb;
;                     wf.x = cvt_pk_bf16(v[0] * zf[0], v[1] * zf[1]); wf.y = cvt_pk_bf16(v[2] * zf[2], v[3] * zf[3]); wf.z = cvt_pk_bf16(v[4] * zf[4], v[5] * zf[5]); wf.w = cvt_pk_bf16(v[6] * zf[6], v[7] * zf[7]);
	v_mov_b32_e32 v90, v84
	v_mov_b32_e32 v68, v65
	v_mov_b32_e32 v100, v85
	v_mov_b32_e32 v65, v70
	v_mov_b32_e32 v102, v86
	v_mov_b32_e32 v70, v67
	v_mov_b32_e32 v108, v87
	v_pk_mul_f32 v[66:67], v[88:89], v[90:91]
	v_pk_mul_f32 v[68:69], v[68:69], v[100:101]
	v_pk_mul_f32 v[64:65], v[64:65], v[102:103]
	v_pk_mul_f32 v[70:71], v[70:71], v[108:109]
	v_add_f32_e32 v84, v66, v67
	v_add_f32_e32 v85, v68, v69
	v_add_f32_e32 v86, v64, v65
	v_add_f32_e32 v71, v70, v71
	v_mul_f32_e32 v64, v180, v110
	v_mul_f32_e32 v65, v181, v111
	v_cvt_pk_bf16_f32 v64, v64, v65
	v_mul_f32_e32 v65, v167, v116
	v_mul_f32_e32 v66, v183, v117
	v_cvt_pk_bf16_f32 v65, v65, v66
	v_mul_f32_e32 v66, v182, v84
	v_mul_f32_e32 v67, v185, v85
	v_cvt_pk_bf16_f32 v66, v66, v67
	v_mul_f32_e32 v67, v184, v86
	v_mul_f32_e32 v68, v159, v71
	v_cvt_pk_bf16_f32 v67, v67, v68
	v_mul_f32_e32 v68, v150, v110
	v_mul_f32_e32 v69, v152, v111
	v_cvt_pk_bf16_f32 v68, v68, v69
	v_mul_f32_e32 v69, v154, v116
	v_mul_f32_e32 v70, v156, v117
	v_cvt_pk_bf16_f32 v69, v69, v70
	v_mul_f32_e32 v70, v158, v84
	v_mul_f32_e32 v84, v160, v85
	v_mul_f32_e32 v71, v155, v71
	v_cvt_pk_bf16_f32 v70, v70, v84
	v_mul_f32_e32 v84, v151, v86
	v_cvt_pk_bf16_f32 v71, v84, v71
	global_store_dwordx4 v[72:73], v[64:67], off offset:256
	global_store_dwordx4 v[74:75], v[68:71], off offset:256
	global_load_dword v64, v137, s[22:23] offset:8
	s_nop 0
	global_load_dword v70, v137, s[22:23] offset:24
	global_load_dword v67, v[146:147], off
	global_load_dword v74, v[148:149], off
	ds_bpermute_b32 v65, v177, v60
	ds_bpermute_b32 v68, v177, v62
	v_mov_b32_e32 v66, v60
	ds_bpermute_b32 v60, v177, v61
	ds_bpermute_b32 v71, v177, v63
	s_waitcnt lgkmcnt(3)
	v_cndmask_b32_e64 v75, v65, -v65, vcc
	s_waitcnt lgkmcnt(2)
	v_cndmask_b32_e64 v65, v68, -v68, vcc
	s_waitcnt vmcnt(3)
	v_mul_f32_e32 v72, 0x3fb8aa3b, v64
	s_waitcnt vmcnt(2)
	v_mul_f32_e32 v73, 0x3fb8aa3b, v70
	v_mul_f32_e32 v84, v72, v179
	s_waitcnt vmcnt(0)
	v_pk_mul_f32 v[68:69], v[66:67], v[74:75]
	s_waitcnt lgkmcnt(1)
	v_cndmask_b32_e64 v75, v60, -v60, vcc
	v_mov_b32_e32 v66, v61
	v_cmp_lt_f32_e64 s[4:5], s60, v72
	v_mul_f32_e32 v87, v73, v178
	v_pk_mul_f32 v[60:61], v[66:67], v[74:75]
	s_waitcnt lgkmcnt(0)
	v_cndmask_b32_e64 v75, v71, -v71, vcc
	v_mov_b32_e32 v66, v63
	v_cmp_gt_f32_e64 s[8:9], s59, v84
	v_cndmask_b32_e64 v86, 0, v176, s[4:5]
	v_cmp_gt_f32_e64 s[6:7], s59, v73
	s_and_b64 s[0:1], s[4:5], exec
	v_cmp_gt_f32_e64 s[4:5], s59, v87
	v_add_f32_e32 v110, v60, v61
	v_pk_mul_f32 v[60:61], v[66:67], v[74:75]
	v_cndmask_b32_e64 v66, 0, v176, s[8:9]
	v_cndmask_b32_e64 v88, 0, v176, s[6:7]
	v_add_f32_e32 v89, v68, v69
	v_fmac_f32_e32 v86, 0xbfb8aa3b, v64
	v_cndmask_b32_e64 v69, 0, v176, s[4:5]
	v_fmac_f32_e32 v66, v72, v179
	v_fmac_f32_e32 v88, 0x3fb8aa3b, v70
	v_exp_f32_e32 v68, v86
	v_fmac_f32_e32 v69, v73, v178
	v_exp_f32_e32 v66, v66
	v_exp_f32_e32 v70, v88
	v_exp_f32_e32 v69, v69
	v_cndmask_b32_e64 v63, 0, v175, s[8:9]
	s_cselect_b32 s8, 0xffffffc0, 0
	s_and_b64 s[0:1], s[6:7], exec
	v_cndmask_b32_e64 v64, 0, v175, s[4:5]
	s_cselect_b32 s0, 0xffffffc0, 0
	v_ldexp_f32 v100, v68, s8
	v_ldexp_f32 v63, v66, v63
	v_mul_f32_e32 v85, v62, v74
	v_ldexp_f32 v90, v70, s0
	v_ldexp_f32 v64, v69, v64
	v_mul_f32_e32 v75, v100, v63
	v_add_f32_e32 v111, v60, v61
	global_load_dword v108, v[148:149], off
	global_load_dword v69, v[146:147], off
	ds_bpermute_b32 v61, v177, v57
	ds_bpermute_b32 v60, v177, v56
	v_mov_b32_e32 v68, v57
	ds_bpermute_b32 v57, v177, v59
	ds_bpermute_b32 v66, v177, v58
	s_waitcnt lgkmcnt(3)
	v_cndmask_b32_e64 v109, v61, -v61, vcc
	s_waitcnt lgkmcnt(2)
	v_cndmask_b32_e64 v70, v60, -v60, vcc
	s_waitcnt lgkmcnt(0)
	v_cndmask_b32_e64 v72, v66, -v66, vcc
	s_waitcnt vmcnt(1)
	v_mul_f32_e32 v71, v56, v108
	s_waitcnt vmcnt(0)
	v_pk_mul_f32 v[60:61], v[68:69], v[108:109]
	v_cndmask_b32_e64 v109, v57, -v57, vcc
	v_mov_b32_e32 v68, v59
	v_add_f32_e32 v57, v60, v61
	v_pk_mul_f32 v[60:61], v[68:69], v[108:109]
	s_nop 0
	v_add_f32_e32 v59, v60, v61
	v_mov_b32_e32 v91, v67
	v_pk_mul_f32 v[60:61], v[90:91], v[64:65]
	v_mov_b32_e32 v91, v85
	v_pk_mul_f32 v[66:67], v[90:91], v[60:61]
	v_mov_b32_e32 v91, v69
	v_mov_b32_e32 v67, v70
	v_mul_f32_e32 v84, v100, v75
	v_pk_mul_f32 v[68:69], v[90:91], v[66:67]
	v_mov_b32_e32 v70, v90
	v_mul_f32_e32 v86, v100, v84
	v_pk_mul_f32 v[70:71], v[70:71], v[68:69]
	v_mul_f32_e32 v85, v100, v86
	v_mov_b32_e32 v71, v72
	v_mul_f32_e32 v88, v100, v85
	v_pk_mul_f32 v[72:73], v[90:91], v[70:71]
	v_fma_f32 v61, v62, v74, v61
	v_mul_f32_e32 v87, v100, v88
	v_mul_f32_e32 v65, v90, v72
	v_mul_f32_e32 v62, v84, v61
	v_fma_f32 v56, v56, v108, v69
	v_mul_f32_e32 v71, v100, v87
	v_mul_f32_e32 v67, v90, v65
	v_mul_f32_e32 v90, v63, v89
	v_mul_f32_e32 v91, v75, v110
	v_cvt_pk_bf16_f32 v100, v90, v91
	v_mul_f32_e32 v74, v86, v111
	v_cvt_pk_bf16_f32 v101, v62, v74
	v_mul_f32_e32 v62, v85, v56
	v_fma_f32 v58, v58, v108, v73
	v_mul_f32_e32 v69, v88, v57
	v_cvt_pk_bf16_f32 v102, v62, v69
	v_mul_f32_e32 v62, v87, v58
	v_mul_f32_e32 v69, v71, v59
	v_cvt_pk_bf16_f32 v103, v62, v69
	v_mul_f32_e32 v62, v64, v89
	v_mul_f32_e32 v56, v70, v56
	v_mul_f32_e32 v57, v72, v57
	v_mul_f32_e32 v69, v60, v110
	v_cvt_pk_bf16_f32 v108, v62, v69
	v_mul_f32_e32 v61, v66, v61
	v_mul_f32_e32 v62, v68, v111
	v_cvt_pk_bf16_f32 v109, v61, v62
	v_cvt_pk_bf16_f32 v110, v56, v57
	v_mul_f32_e32 v56, v65, v58
	v_mul_f32_e32 v57, v67, v59
	s_mov_b64 s[0:1], 0x1000000
	v_cvt_pk_bf16_f32 v111, v56, v57
	v_lshl_add_u64 v[56:57], v[120:121], 0, s[0:1]
	s_mov_b32 s0, 0x1000000
	v_add_co_u32_e64 v58, s[4:5], s0, v120
	s_mov_b64 s[0:1], 0x3000000
	s_nop 0
	v_addc_co_u32_e64 v59, s[4:5], 0, v121, s[4:5]
	global_store_dwordx4 v[58:59], v[100:103], off
	v_lshl_add_u64 v[58:59], v[120:121], 0, s[0:1]
	s_mov_b32 s0, 0x3000000
	v_add_co_u32_e64 v90, s[4:5], s0, v120
	s_nop 1
	v_addc_co_u32_e64 v91, s[4:5], 0, v121, s[4:5]
	global_store_dwordx4 v[90:91], v[108:111], off
	global_load_dword v91, v[122:123], off
	s_nop 0
	global_load_dword v100, v[124:125], off
	ds_bpermute_b32 v61, v177, v52
	v_mov_b32_e32 v90, v52
	ds_bpermute_b32 v52, v177, v53
	ds_bpermute_b32 v62, v177, v54
	ds_bpermute_b32 v69, v177, v55
	s_waitcnt lgkmcnt(3)
; __device__ __forceinline__ unsigned cvt_pk_bf16(float lo, float hi) { unsigned r; asm volatile("v_cvt_pk_bf16_f32 %0, %1, %2" : "=v"(r) : "v"(lo), "v"(hi)); return r; }
;     __device__ __forceinline__ void operator()(const AccT& acc, const Unit& u, int wr, int wc, int fr, int fq) const {
;     ...
;                 const int r = rbase + ai * 128 + m * 16;
;                 const int d = 4 * (2 * m + (fr >> 3)) + j;
; #pragma unroll
;                 for (int bj = 0; bj < 2; ++bj) {
;                     const int t0 = tb + bj * 128;
;                     float v[8];
; #pragma unroll
;                     for (int jj = 0; jj < 4; ++jj) { v[jj] = acc[ai][bj][m][0][jj]; v[4 + jj] = acc[ai][bj][m][1][jj]; }
;                     if constexpr (ROPE) {
;                         const int t = t0 & 2047;
; #pragma unroll
;                         for (int hf = 0; hf < 2; ++hf) {
;                             f32x4 cs, sn;
;                             if (m < 2) { const float c1 = ropeA[(t >> 6) * 16 + d], s1 = ropeA[1024 + (t >> 6) * 16 + d]; cs = (f32x4){c1, c1, c1, c1}; sn = (f32x4){s1, s1, s1, s1}; }
;                             else { const float* cb = ropeA + 2048 + (d - 16) * 64 + (t & 63) + 4 * hf; cs = *(const f32x4*)(cb); sn = *(const f32x4*)(cb + 1024); }
; #pragma unroll
;                             for (int jj = 0; jj < 4; ++jj) { const float pr = __shfl_xor(v[4 * hf + jj], 4); v[4 * hf + jj] = v[4 * hf + jj] * cs[jj] + sgn * pr * sn[jj]; }
;                             __builtin_amdgcn_sched_barrier(0);
;                         }
;                     }
;                     float zf[8], zb[8]; zf[0] = zf0; zb[0] = zb0;
; #pragma unroll
;                     for (int jj = 1; jj < 8; ++jj) { zf[jj] = zf[jj - 1] * zfs; zb[jj] = zb[jj - 1] * zbs; }
;                     u32x4 wf, wb;
;                     wf.x = cvt_pk_bf16(v[0] * zf[0], v[1] * zf[1]); wf.y = cvt_pk_bf16(v[2] * zf[2], v[3] * zf[3]); wf.z = cvt_pk_bf16(v[4] * zf[4], v[5] * zf[5]); wf.w = cvt_pk_bf16(v[6] * zf[6], v[7] * zf[7]);
;                     wb.x = cvt_pk_bf16(v[0] * zb[0], v[1] * zb[1]); wb.y = cvt_pk_bf16(v[2] * zb[2], v[3] * zb[3]); wb.z = cvt_pk_bf16(v[4] * zb[4], v[5] * zb[5]); wb.w = cvt_pk_bf16(v[6] * zb[6], v[7] * zb[7]);
;                     *(u32x4*)(KTZ + (size_t)r * NT + t0) = wf;
;                     *(u32x4*)(KTZ + (size_t)(256 + r) * NT + t0) = wb;
	v_cndmask_b32_e64 v101, v61, -v61, vcc
	s_waitcnt vmcnt(0)
	v_pk_mul_f32 v[102:103], v[90:91], v[100:101]
	s_waitcnt lgkmcnt(2)
	v_cndmask_b32_e64 v101, v52, -v52, vcc
	v_mov_b32_e32 v90, v53
	v_pk_mul_f32 v[52:53], v[90:91], v[100:101]
	s_waitcnt lgkmcnt(1)
	v_cndmask_b32_e64 v101, v62, -v62, vcc
	v_mov_b32_e32 v90, v54
	v_add_f32_e32 v62, v52, v53
	v_pk_mul_f32 v[52:53], v[90:91], v[100:101]
	s_waitcnt lgkmcnt(0)
	v_cndmask_b32_e64 v101, v69, -v69, vcc
	v_mov_b32_e32 v90, v55
	v_add_f32_e32 v69, v52, v53
	v_pk_mul_f32 v[52:53], v[90:91], v[100:101]
	v_add_f32_e32 v61, v102, v103
	v_add_f32_e32 v73, v52, v53
	global_load_dword v53, v[122:123], off
	global_load_dword v54, v[124:125], off
	ds_bpermute_b32 v55, v177, v48
	v_mov_b32_e32 v52, v48
	ds_bpermute_b32 v48, v177, v49
	ds_bpermute_b32 v74, v177, v50
	ds_bpermute_b32 v89, v177, v51
	s_waitcnt lgkmcnt(3)
	v_cndmask_b32_e64 v55, v55, -v55, vcc
	s_waitcnt vmcnt(0)
	v_pk_mul_f32 v[90:91], v[52:53], v[54:55]
	s_waitcnt lgkmcnt(2)
	v_cndmask_b32_e64 v55, v48, -v48, vcc
	v_mov_b32_e32 v52, v49
	v_pk_mul_f32 v[48:49], v[52:53], v[54:55]
	s_waitcnt lgkmcnt(1)
	v_cndmask_b32_e64 v55, v74, -v74, vcc
	v_mov_b32_e32 v52, v50
	v_add_f32_e32 v74, v48, v49
	v_pk_mul_f32 v[48:49], v[52:53], v[54:55]
	s_waitcnt lgkmcnt(0)
	v_cndmask_b32_e64 v55, v89, -v89, vcc
	v_mov_b32_e32 v52, v51
	v_add_f32_e32 v89, v48, v49
	v_pk_mul_f32 v[48:49], v[52:53], v[54:55]
	v_add_f32_e32 v90, v90, v91
	v_add_f32_e32 v55, v48, v49
	v_mul_f32_e32 v48, v63, v61
	v_mul_f32_e32 v49, v75, v62
	v_cvt_pk_bf16_f32 v48, v48, v49
	v_mul_f32_e32 v49, v84, v69
	v_mul_f32_e32 v50, v86, v73
	v_cvt_pk_bf16_f32 v49, v49, v50
	v_mul_f32_e32 v50, v85, v90
	v_mul_f32_e32 v51, v88, v74
	v_cvt_pk_bf16_f32 v50, v50, v51
	v_mul_f32_e32 v51, v87, v89
	v_mul_f32_e32 v52, v71, v55
	v_cvt_pk_bf16_f32 v51, v51, v52
	v_mul_f32_e32 v52, v64, v61
	v_mul_f32_e32 v53, v60, v62
	v_cvt_pk_bf16_f32 v52, v52, v53
	v_mul_f32_e32 v53, v66, v69
	v_mul_f32_e32 v54, v68, v73
	v_cvt_pk_bf16_f32 v53, v53, v54
	v_mul_f32_e32 v54, v70, v90
	v_mul_f32_e32 v61, v72, v74
	v_mul_f32_e32 v55, v67, v55
	v_cvt_pk_bf16_f32 v54, v54, v61
	v_mul_f32_e32 v61, v65, v89
	v_cvt_pk_bf16_f32 v55, v61, v55
	global_store_dwordx4 v[56:57], v[48:51], off offset:256
	global_store_dwordx4 v[58:59], v[52:55], off offset:256
	global_load_dword v49, v[112:113], off
	s_nop 0
	global_load_dword v50, v[114:115], off
	ds_bpermute_b32 v51, v177, v44
	v_mov_b32_e32 v48, v44
	ds_bpermute_b32 v44, v177, v45
	ds_bpermute_b32 v54, v177, v46
	ds_bpermute_b32 v55, v177, v47
	s_waitcnt lgkmcnt(3)
	v_cndmask_b32_e64 v51, v51, -v51, vcc
	s_waitcnt vmcnt(0)
	v_pk_mul_f32 v[52:53], v[48:49], v[50:51]
	s_waitcnt lgkmcnt(2)
	v_cndmask_b32_e64 v51, v44, -v44, vcc
	v_mov_b32_e32 v48, v45
	v_pk_mul_f32 v[44:45], v[48:49], v[50:51]
	s_waitcnt lgkmcnt(1)
	v_cndmask_b32_e64 v51, v54, -v54, vcc
	v_mov_b32_e32 v48, v46
	v_add_f32_e32 v52, v52, v53
	v_add_f32_e32 v53, v44, v45
	v_pk_mul_f32 v[44:45], v[48:49], v[50:51]
	s_waitcnt lgkmcnt(0)
	v_cndmask_b32_e64 v51, v55, -v55, vcc
	v_mov_b32_e32 v48, v47
	v_add_f32_e32 v54, v44, v45
	v_pk_mul_f32 v[44:45], v[48:49], v[50:51]
	s_nop 0
	v_add_f32_e32 v50, v44, v45
	global_load_dword v45, v[112:113], off
	global_load_dword v46, v[114:115], off
	ds_bpermute_b32 v47, v177, v40
	v_mov_b32_e32 v44, v40
	ds_bpermute_b32 v40, v177, v41
	ds_bpermute_b32 v51, v177, v42
	ds_bpermute_b32 v55, v177, v43
	s_waitcnt lgkmcnt(3)
	v_cndmask_b32_e64 v47, v47, -v47, vcc
	s_waitcnt vmcnt(0)
	v_pk_mul_f32 v[48:49], v[44:45], v[46:47]
	s_waitcnt lgkmcnt(2)
	v_cndmask_b32_e64 v47, v40, -v40, vcc
	v_mov_b32_e32 v44, v41
	v_pk_mul_f32 v[40:41], v[44:45], v[46:47]
	s_waitcnt lgkmcnt(1)
	v_cndmask_b32_e64 v47, v51, -v51, vcc
	v_mov_b32_e32 v44, v42
	v_add_f32_e32 v48, v48, v49
	v_add_f32_e32 v49, v40, v41
	v_pk_mul_f32 v[40:41], v[44:45], v[46:47]
	s_waitcnt lgkmcnt(0)
	v_cndmask_b32_e64 v47, v55, -v55, vcc
	v_mov_b32_e32 v44, v43
	v_add_f32_e32 v51, v40, v41
	v_pk_mul_f32 v[40:41], v[44:45], v[46:47]
	s_nop 0
	v_add_f32_e32 v40, v40, v41
	v_mul_f32_e32 v41, v63, v52
	v_mul_f32_e32 v42, v75, v53
	v_cvt_pk_bf16_f32 v42, v41, v42
	v_mul_f32_e32 v41, v84, v54
	v_mul_f32_e32 v43, v86, v50
	v_cvt_pk_bf16_f32 v43, v41, v43
	v_mul_f32_e32 v41, v85, v48
	v_mul_f32_e32 v44, v88, v49
	v_cvt_pk_bf16_f32 v44, v41, v44
	v_mul_f32_e32 v41, v87, v51
	v_mul_f32_e32 v45, v71, v40
	v_cvt_pk_bf16_f32 v45, v41, v45
	v_mul_f32_e32 v41, v64, v52
	v_mul_f32_e32 v46, v60, v53
	v_cvt_pk_bf16_f32 v46, v41, v46
	v_mul_f32_e32 v41, v66, v54
	v_mul_f32_e32 v47, v68, v50
	v_cvt_pk_bf16_f32 v47, v41, v47
	v_mul_f32_e32 v41, v70, v48
	v_mul_f32_e32 v48, v72, v49
	v_cvt_pk_bf16_f32 v48, v41, v48
	v_mul_f32_e32 v41, v65, v51
	v_mul_f32_e32 v40, v67, v40
	s_mov_b64 s[0:1], 0x1200000
	v_cvt_pk_bf16_f32 v49, v41, v40
	v_lshl_add_u64 v[40:41], v[120:121], 0, s[0:1]
	s_mov_b32 s0, 0x1200000
	v_add_co_u32_e64 v50, s[4:5], s0, v120
	s_mov_b64 s[0:1], 0x3200000
	s_nop 0
	v_addc_co_u32_e64 v51, s[4:5], 0, v121, s[4:5]
	global_store_dwordx4 v[50:51], v[42:45], off
	s_nop 1
	v_lshl_add_u64 v[42:43], v[120:121], 0, s[0:1]
	s_mov_b32 s0, 0x3200000
	v_add_co_u32_e64 v44, s[4:5], s0, v120
	s_nop 1
	v_addc_co_u32_e64 v45, s[4:5], 0, v121, s[4:5]
	global_store_dwordx4 v[44:45], v[46:49], off
	global_load_dword v45, v[104:105], off
	s_nop 0
	global_load_dword v46, v[106:107], off
	ds_bpermute_b32 v47, v177, v36
	v_mov_b32_e32 v44, v36
	ds_bpermute_b32 v36, v177, v37
	ds_bpermute_b32 v50, v177, v38
	ds_bpermute_b32 v51, v177, v39
	s_waitcnt lgkmcnt(3)
	v_cndmask_b32_e64 v47, v47, -v47, vcc
	s_waitcnt vmcnt(0)
	v_pk_mul_f32 v[48:49], v[44:45], v[46:47]
	s_waitcnt lgkmcnt(2)
; __device__ __forceinline__ unsigned cvt_pk_bf16(float lo, float hi) { unsigned r; asm volatile("v_cvt_pk_bf16_f32 %0, %1, %2" : "=v"(r) : "v"(lo), "v"(hi)); return r; }
;     __device__ __forceinline__ void operator()(const AccT& acc, const Unit& u, int wr, int wc, int fr, int fq) const {
;     ...
;                 const int r = rbase + ai * 128 + m * 16;
;                 const int d = 4 * (2 * m + (fr >> 3)) + j;
; #pragma unroll
;                 for (int bj = 0; bj < 2; ++bj) {
;                     const int t0 = tb + bj * 128;
;                     float v[8];
; #pragma unroll
;                     for (int jj = 0; jj < 4; ++jj) { v[jj] = acc[ai][bj][m][0][jj]; v[4 + jj] = acc[ai][bj][m][1][jj]; }
;                     if constexpr (ROPE) {
;                         const int t = t0 & 2047;
; #pragma unroll
;                         for (int hf = 0; hf < 2; ++hf) {
;                             f32x4 cs, sn;
;                             if (m < 2) { const float c1 = ropeA[(t >> 6) * 16 + d], s1 = ropeA[1024 + (t >> 6) * 16 + d]; cs = (f32x4){c1, c1, c1, c1}; sn = (f32x4){s1, s1, s1, s1}; }
;                             else { const float* cb = ropeA + 2048 + (d - 16) * 64 + (t & 63) + 4 * hf; cs = *(const f32x4*)(cb); sn = *(const f32x4*)(cb + 1024); }
; #pragma unroll
;                             for (int jj = 0; jj < 4; ++jj) { const float pr = __shfl_xor(v[4 * hf + jj], 4); v[4 * hf + jj] = v[4 * hf + jj] * cs[jj] + sgn * pr * sn[jj]; }
;                             __builtin_amdgcn_sched_barrier(0);
;                         }
;                     }
;                     float zf[8], zb[8]; zf[0] = zf0; zb[0] = zb0;
; #pragma unroll
;                     for (int jj = 1; jj < 8; ++jj) { zf[jj] = zf[jj - 1] * zfs; zb[jj] = zb[jj - 1] * zbs; }
;                     u32x4 wf, wb;
;                     wf.x = cvt_pk_bf16(v[0] * zf[0], v[1] * zf[1]); wf.y = cvt_pk_bf16(v[2] * zf[2], v[3] * zf[3]); wf.z = cvt_pk_bf16(v[4] * zf[4], v[5] * zf[5]); wf.w = cvt_pk_bf16(v[6] * zf[6], v[7] * zf[7]);
;                     wb.x = cvt_pk_bf16(v[0] * zb[0], v[1] * zb[1]); wb.y = cvt_pk_bf16(v[2] * zb[2], v[3] * zb[3]); wb.z = cvt_pk_bf16(v[4] * zb[4], v[5] * zb[5]); wb.w = cvt_pk_bf16(v[6] * zb[6], v[7] * zb[7]);
;                     *(u32x4*)(KTZ + (size_t)r * NT + t0) = wf;
;                     *(u32x4*)(KTZ + (size_t)(256 + r) * NT + t0) = wb;
	v_cndmask_b32_e64 v47, v36, -v36, vcc
	v_mov_b32_e32 v44, v37
	v_pk_mul_f32 v[36:37], v[44:45], v[46:47]
	s_waitcnt lgkmcnt(1)
	v_cndmask_b32_e64 v47, v50, -v50, vcc
	v_mov_b32_e32 v44, v38
	v_add_f32_e32 v48, v48, v49
	v_add_f32_e32 v49, v36, v37
	v_pk_mul_f32 v[36:37], v[44:45], v[46:47]
	s_waitcnt lgkmcnt(0)
	v_cndmask_b32_e64 v47, v51, -v51, vcc
	v_mov_b32_e32 v44, v39
	v_add_f32_e32 v50, v36, v37
	v_pk_mul_f32 v[36:37], v[44:45], v[46:47]
	s_nop 0
	v_add_f32_e32 v46, v36, v37
	global_load_dword v37, v[104:105], off
	global_load_dword v38, v[106:107], off
	ds_bpermute_b32 v39, v177, v32
	v_mov_b32_e32 v36, v32
	ds_bpermute_b32 v32, v177, v33
	ds_bpermute_b32 v47, v177, v34
	ds_bpermute_b32 v51, v177, v35
	s_waitcnt lgkmcnt(3)
	v_cndmask_b32_e64 v39, v39, -v39, vcc
	s_waitcnt vmcnt(0)
	v_pk_mul_f32 v[44:45], v[36:37], v[38:39]
	s_waitcnt lgkmcnt(2)
	v_cndmask_b32_e64 v39, v32, -v32, vcc
	v_mov_b32_e32 v36, v33
	v_pk_mul_f32 v[32:33], v[36:37], v[38:39]
	s_waitcnt lgkmcnt(1)
	v_cndmask_b32_e64 v39, v47, -v47, vcc
	v_mov_b32_e32 v36, v34
	v_add_f32_e32 v44, v44, v45
	v_add_f32_e32 v45, v32, v33
	v_pk_mul_f32 v[32:33], v[36:37], v[38:39]
	s_waitcnt lgkmcnt(0)
	v_cndmask_b32_e64 v39, v51, -v51, vcc
	v_mov_b32_e32 v36, v35
	v_add_f32_e32 v47, v32, v33
	v_pk_mul_f32 v[32:33], v[36:37], v[38:39]
	s_nop 0
	v_add_f32_e32 v39, v32, v33
	v_mul_f32_e32 v32, v63, v48
	v_mul_f32_e32 v33, v75, v49
	v_cvt_pk_bf16_f32 v32, v32, v33
	v_mul_f32_e32 v33, v84, v50
	v_mul_f32_e32 v34, v86, v46
	v_cvt_pk_bf16_f32 v33, v33, v34
	v_mul_f32_e32 v34, v85, v44
	v_mul_f32_e32 v35, v88, v45
	v_cvt_pk_bf16_f32 v34, v34, v35
	v_mul_f32_e32 v35, v87, v47
	v_mul_f32_e32 v36, v71, v39
	v_cvt_pk_bf16_f32 v35, v35, v36
	v_mul_f32_e32 v36, v64, v48
	v_mul_f32_e32 v37, v60, v49
	v_cvt_pk_bf16_f32 v36, v36, v37
	v_mul_f32_e32 v37, v66, v50
	v_mul_f32_e32 v38, v68, v46
	v_cvt_pk_bf16_f32 v37, v37, v38
	v_mul_f32_e32 v38, v70, v44
	v_mul_f32_e32 v44, v72, v45
	v_mul_f32_e32 v39, v67, v39
	v_cvt_pk_bf16_f32 v38, v38, v44
	v_mul_f32_e32 v44, v65, v47
	v_cvt_pk_bf16_f32 v39, v44, v39
	global_store_dwordx4 v[40:41], v[32:35], off offset:256
	global_store_dwordx4 v[42:43], v[36:39], off offset:256
	global_load_dwordx4 v[32:35], v[98:99], off
	s_nop 0
	global_load_dwordx4 v[36:39], v[96:97], off
	ds_bpermute_b32 v41, v177, v28
	ds_bpermute_b32 v42, v177, v29
	ds_bpermute_b32 v44, v177, v30
	ds_bpermute_b32 v46, v177, v31
	v_mov_b32_e32 v40, v28
	v_mov_b32_e32 v28, v30
	s_waitcnt lgkmcnt(3)
	v_cndmask_b32_e64 v43, v41, -v41, vcc
	s_waitcnt lgkmcnt(2)
	v_cndmask_b32_e64 v45, v42, -v42, vcc
	s_waitcnt lgkmcnt(1)
	v_cndmask_b32_e64 v47, v44, -v44, vcc
	s_waitcnt lgkmcnt(0)
	v_cndmask_b32_e64 v49, v46, -v46, vcc
	s_waitcnt vmcnt(1)
	v_mov_b32_e32 v41, v32
	s_waitcnt vmcnt(0)
	v_mov_b32_e32 v42, v36
	v_mov_b32_e32 v32, v29
	v_mov_b32_e32 v44, v37
	v_mov_b32_e32 v29, v34
	v_mov_b32_e32 v46, v38
	v_mov_b32_e32 v34, v31
	v_mov_b32_e32 v48, v39
	v_pk_mul_f32 v[30:31], v[40:41], v[42:43]
	v_pk_mul_f32 v[32:33], v[32:33], v[44:45]
	v_pk_mul_f32 v[28:29], v[28:29], v[46:47]
	v_pk_mul_f32 v[34:35], v[34:35], v[48:49]
	v_add_f32_e32 v46, v30, v31
	v_add_f32_e32 v47, v32, v33
	v_add_f32_e32 v48, v28, v29
	v_add_f32_e32 v49, v34, v35
	global_load_dwordx4 v[28:31], v[92:93], off offset:16
	global_load_dwordx4 v[32:35], v[94:95], off offset:16
	ds_bpermute_b32 v37, v177, v24
	ds_bpermute_b32 v38, v177, v25
	ds_bpermute_b32 v40, v177, v26
	ds_bpermute_b32 v42, v177, v27
	v_mov_b32_e32 v36, v24
	v_mov_b32_e32 v24, v26
	s_waitcnt lgkmcnt(3)
	v_cndmask_b32_e64 v39, v37, -v37, vcc
	s_waitcnt lgkmcnt(2)
	v_cndmask_b32_e64 v41, v38, -v38, vcc
	s_waitcnt lgkmcnt(1)
	v_cndmask_b32_e64 v43, v40, -v40, vcc
	s_waitcnt lgkmcnt(0)
	v_cndmask_b32_e64 v45, v42, -v42, vcc
	s_waitcnt vmcnt(1)
	v_mov_b32_e32 v37, v28
	s_waitcnt vmcnt(0)
	v_mov_b32_e32 v38, v32
	v_mov_b32_e32 v28, v25
	v_mov_b32_e32 v40, v33
	v_mov_b32_e32 v25, v30
	v_mov_b32_e32 v42, v34
	v_mov_b32_e32 v30, v27
	v_mov_b32_e32 v44, v35
	v_pk_mul_f32 v[26:27], v[36:37], v[38:39]
	v_pk_mul_f32 v[28:29], v[28:29], v[40:41]
	v_pk_mul_f32 v[24:25], v[24:25], v[42:43]
	v_pk_mul_f32 v[30:31], v[30:31], v[44:45]
	v_add_f32_e32 v32, v26, v27
	v_add_f32_e32 v33, v28, v29
	v_add_f32_e32 v24, v24, v25
	v_add_f32_e32 v25, v30, v31
	v_mul_f32_e32 v26, v63, v46
	v_mul_f32_e32 v27, v75, v47
	v_cvt_pk_bf16_f32 v26, v26, v27
	v_mul_f32_e32 v27, v84, v48
	v_mul_f32_e32 v28, v86, v49
	v_cvt_pk_bf16_f32 v27, v27, v28
	v_mul_f32_e32 v28, v85, v32
	v_mul_f32_e32 v29, v88, v33
	v_cvt_pk_bf16_f32 v28, v28, v29
	v_mul_f32_e32 v29, v87, v24
	v_mul_f32_e32 v30, v71, v25
	v_cvt_pk_bf16_f32 v29, v29, v30
	v_mul_f32_e32 v30, v64, v46
	v_mul_f32_e32 v31, v60, v47
	v_cvt_pk_bf16_f32 v30, v30, v31
	v_mul_f32_e32 v31, v66, v48
	v_mul_f32_e32 v32, v70, v32
	v_mul_f32_e32 v33, v72, v33
	v_mul_f32_e32 v24, v65, v24
	v_mul_f32_e32 v25, v67, v25
	s_mov_b64 s[0:1], 0x1400000
	v_mul_f32_e32 v34, v68, v49
	v_cvt_pk_bf16_f32 v31, v31, v34
	v_cvt_pk_bf16_f32 v32, v32, v33
	v_cvt_pk_bf16_f32 v33, v24, v25
	v_lshl_add_u64 v[24:25], v[120:121], 0, s[0:1]
	s_mov_b32 s0, 0x1400000
	v_add_co_u32_e64 v34, s[4:5], s0, v120
	s_mov_b64 s[0:1], 0x3400000
	s_nop 0
	v_addc_co_u32_e64 v35, s[4:5], 0, v121, s[4:5]
	global_store_dwordx4 v[34:35], v[26:29], off
	s_nop 1
	v_lshl_add_u64 v[26:27], v[120:121], 0, s[0:1]
	s_mov_b32 s0, 0x3400000
	v_add_co_u32_e64 v28, s[4:5], s0, v120
	s_nop 1
	v_addc_co_u32_e64 v29, s[4:5], 0, v121, s[4:5]
	global_store_dwordx4 v[28:29], v[30:33], off
	global_load_dwordx4 v[28:31], v[98:99], off
	s_nop 0
	global_load_dwordx4 v[32:35], v[96:97], off
	ds_bpermute_b32 v37, v177, v20
	ds_bpermute_b32 v38, v177, v21
	ds_bpermute_b32 v40, v177, v22
	ds_bpermute_b32 v42, v177, v23
	v_mov_b32_e32 v36, v20
	v_mov_b32_e32 v20, v22
	s_waitcnt lgkmcnt(3)
; __device__ __forceinline__ unsigned cvt_pk_bf16(float lo, float hi) { unsigned r; asm volatile("v_cvt_pk_bf16_f32 %0, %1, %2" : "=v"(r) : "v"(lo), "v"(hi)); return r; }
;     __device__ __forceinline__ void operator()(const AccT& acc, const Unit& u, int wr, int wc, int fr, int fq) const {
;     ...
;                         const int t = t0 & 2047;
; #pragma unroll
;                         for (int hf = 0; hf < 2; ++hf) {
;                             f32x4 cs, sn;
;                             if (m < 2) { const float c1 = ropeA[(t >> 6) * 16 + d], s1 = ropeA[1024 + (t >> 6) * 16 + d]; cs = (f32x4){c1, c1, c1, c1}; sn = (f32x4){s1, s1, s1, s1}; }
;                             else { const float* cb = ropeA + 2048 + (d - 16) * 64 + (t & 63) + 4 * hf; cs = *(const f32x4*)(cb); sn = *(const f32x4*)(cb + 1024); }
; #pragma unroll
;                             for (int jj = 0; jj < 4; ++jj) { const float pr = __shfl_xor(v[4 * hf + jj], 4); v[4 * hf + jj] = v[4 * hf + jj] * cs[jj] + sgn * pr * sn[jj]; }
;                             __builtin_amdgcn_sched_barrier(0);
;                         }
;                     }
;                     float zf[8], zb[8]; zf[0] = zf0; zb[0] = zb0;
; #pragma unroll
;                     for (int jj = 1; jj < 8; ++jj) { zf[jj] = zf[jj - 1] * zfs; zb[jj] = zb[jj - 1] * zbs; }
;                     u32x4 wf, wb;
;                     wf.x = cvt_pk_bf16(v[0] * zf[0], v[1] * zf[1]); wf.y = cvt_pk_bf16(v[2] * zf[2], v[3] * zf[3]); wf.z = cvt_pk_bf16(v[4] * zf[4], v[5] * zf[5]); wf.w = cvt_pk_bf16(v[6] * zf[6], v[7] * zf[7]);
;                     wb.x = cvt_pk_bf16(v[0] * zb[0], v[1] * zb[1]); wb.y = cvt_pk_bf16(v[2] * zb[2], v[3] * zb[3]); wb.z = cvt_pk_bf16(v[4] * zb[4], v[5] * zb[5]); wb.w = cvt_pk_bf16(v[6] * zb[6], v[7] * zb[7]);
;                     *(u32x4*)(KTZ + (size_t)r * NT + t0) = wf;
;                     *(u32x4*)(KTZ + (size_t)(256 + r) * NT + t0) = wb;
	v_cndmask_b32_e64 v39, v37, -v37, vcc
	s_waitcnt lgkmcnt(2)
	v_cndmask_b32_e64 v41, v38, -v38, vcc
	s_waitcnt lgkmcnt(1)
	v_cndmask_b32_e64 v43, v40, -v40, vcc
	s_waitcnt lgkmcnt(0)
	v_cndmask_b32_e64 v45, v42, -v42, vcc
	s_waitcnt vmcnt(1)
	v_mov_b32_e32 v37, v28
	s_waitcnt vmcnt(0)
	v_mov_b32_e32 v38, v32
	v_mov_b32_e32 v28, v21
	v_mov_b32_e32 v40, v33
	v_mov_b32_e32 v21, v30
	v_mov_b32_e32 v42, v34
	v_mov_b32_e32 v30, v23
	v_mov_b32_e32 v44, v35
	v_pk_mul_f32 v[22:23], v[36:37], v[38:39]
	v_pk_mul_f32 v[28:29], v[28:29], v[40:41]
	v_pk_mul_f32 v[20:21], v[20:21], v[42:43]
	v_pk_mul_f32 v[30:31], v[30:31], v[44:45]
	v_add_f32_e32 v42, v22, v23
	v_add_f32_e32 v43, v28, v29
	v_add_f32_e32 v44, v20, v21
	v_add_f32_e32 v45, v30, v31
	global_load_dwordx4 v[20:23], v[92:93], off offset:16
	global_load_dwordx4 v[28:31], v[94:95], off offset:16
	ds_bpermute_b32 v33, v177, v16
	ds_bpermute_b32 v34, v177, v17
	ds_bpermute_b32 v36, v177, v18
	ds_bpermute_b32 v38, v177, v19
	v_mov_b32_e32 v32, v16
	v_mov_b32_e32 v16, v18
	s_waitcnt lgkmcnt(3)
	v_cndmask_b32_e64 v35, v33, -v33, vcc
	s_waitcnt lgkmcnt(2)
	v_cndmask_b32_e64 v37, v34, -v34, vcc
	s_waitcnt lgkmcnt(1)
	v_cndmask_b32_e64 v39, v36, -v36, vcc
	s_waitcnt lgkmcnt(0)
	v_cndmask_b32_e64 v41, v38, -v38, vcc
	s_waitcnt vmcnt(1)
	v_mov_b32_e32 v33, v20
	s_waitcnt vmcnt(0)
	v_mov_b32_e32 v34, v28
	v_mov_b32_e32 v20, v17
	v_mov_b32_e32 v36, v29
	v_mov_b32_e32 v17, v22
	v_mov_b32_e32 v38, v30
	v_mov_b32_e32 v22, v19
	v_mov_b32_e32 v40, v31
	v_pk_mul_f32 v[18:19], v[32:33], v[34:35]
	v_pk_mul_f32 v[20:21], v[20:21], v[36:37]
	v_pk_mul_f32 v[16:17], v[16:17], v[38:39]
	v_pk_mul_f32 v[22:23], v[22:23], v[40:41]
	v_add_f32_e32 v28, v18, v19
	v_add_f32_e32 v29, v20, v21
	v_add_f32_e32 v30, v16, v17
	v_add_f32_e32 v23, v22, v23
	v_mul_f32_e32 v16, v63, v42
	v_mul_f32_e32 v17, v75, v43
	v_cvt_pk_bf16_f32 v16, v16, v17
	v_mul_f32_e32 v17, v84, v44
	v_mul_f32_e32 v18, v86, v45
	v_cvt_pk_bf16_f32 v17, v17, v18
	v_mul_f32_e32 v18, v85, v28
	v_mul_f32_e32 v19, v88, v29
	v_cvt_pk_bf16_f32 v18, v18, v19
	v_mul_f32_e32 v19, v87, v30
	v_mul_f32_e32 v20, v71, v23
	v_cvt_pk_bf16_f32 v19, v19, v20
	v_mul_f32_e32 v20, v64, v42
	v_mul_f32_e32 v21, v60, v43
	v_cvt_pk_bf16_f32 v20, v20, v21
	v_mul_f32_e32 v21, v66, v44
	v_mul_f32_e32 v22, v68, v45
	v_cvt_pk_bf16_f32 v21, v21, v22
	v_mul_f32_e32 v22, v70, v28
	v_mul_f32_e32 v28, v72, v29
	v_mul_f32_e32 v23, v67, v23
	v_cvt_pk_bf16_f32 v22, v22, v28
	v_mul_f32_e32 v28, v65, v30
	v_cvt_pk_bf16_f32 v23, v28, v23
	global_store_dwordx4 v[24:25], v[16:19], off offset:256
	global_store_dwordx4 v[26:27], v[20:23], off offset:256
	global_load_dwordx4 v[16:19], v[82:83], off
	s_nop 0
	global_load_dwordx4 v[20:23], v[80:81], off
	ds_bpermute_b32 v25, v177, v12
	ds_bpermute_b32 v26, v177, v13
	ds_bpermute_b32 v28, v177, v14
	ds_bpermute_b32 v30, v177, v15
	v_mov_b32_e32 v24, v12
	v_mov_b32_e32 v12, v14
	s_waitcnt lgkmcnt(3)
	v_cndmask_b32_e64 v27, v25, -v25, vcc
	s_waitcnt lgkmcnt(2)
	v_cndmask_b32_e64 v29, v26, -v26, vcc
	s_waitcnt lgkmcnt(1)
	v_cndmask_b32_e64 v31, v28, -v28, vcc
	s_waitcnt lgkmcnt(0)
	v_cndmask_b32_e64 v33, v30, -v30, vcc
	s_waitcnt vmcnt(1)
	v_mov_b32_e32 v25, v16
	s_waitcnt vmcnt(0)
	v_mov_b32_e32 v26, v20
	v_mov_b32_e32 v16, v13
	v_mov_b32_e32 v28, v21
	v_mov_b32_e32 v13, v18
	v_mov_b32_e32 v30, v22
	v_mov_b32_e32 v18, v15
	v_mov_b32_e32 v32, v23
	v_pk_mul_f32 v[14:15], v[24:25], v[26:27]
	v_pk_mul_f32 v[16:17], v[16:17], v[28:29]
	v_pk_mul_f32 v[12:13], v[12:13], v[30:31]
	v_pk_mul_f32 v[18:19], v[18:19], v[32:33]
	v_add_f32_e32 v30, v14, v15
	v_add_f32_e32 v31, v16, v17
	v_add_f32_e32 v32, v12, v13
	v_add_f32_e32 v33, v18, v19
	global_load_dwordx4 v[12:15], v[76:77], off offset:16
	global_load_dwordx4 v[16:19], v[78:79], off offset:16
	ds_bpermute_b32 v21, v177, v8
	ds_bpermute_b32 v22, v177, v9
	ds_bpermute_b32 v24, v177, v10
	ds_bpermute_b32 v26, v177, v11
	v_mov_b32_e32 v20, v8
	v_mov_b32_e32 v8, v10
	s_waitcnt lgkmcnt(3)
	v_cndmask_b32_e64 v23, v21, -v21, vcc
	s_waitcnt lgkmcnt(2)
	v_cndmask_b32_e64 v25, v22, -v22, vcc
	s_waitcnt lgkmcnt(1)
	v_cndmask_b32_e64 v27, v24, -v24, vcc
	s_waitcnt lgkmcnt(0)
	v_cndmask_b32_e64 v29, v26, -v26, vcc
	s_waitcnt vmcnt(1)
	v_mov_b32_e32 v21, v12
	s_waitcnt vmcnt(0)
; template <class Epi, class Sched>
; __device__ __forceinline__ void gemm_phase(LAS unsigned char* lds, const Gemm g, const Sched& S, const Epi& E) {
;     ...
;         E(acc, cur, wr, wc, fr, fq);
;         if (!has_next) break;
; #pragma unroll
;         for (int a = 0; a < 2; ++a)
; #pragma unroll
;             for (int b = 0; b < 2; ++b)
; #pragma unroll
;                 for (int m = 0; m < 4; ++m)
; #pragma unroll
;                     for (int n = 0; n < 2; ++n) acc[a][b][m][n] = (f32x4){0.f, 0.f, 0.f, 0.f};
;         cur = nxt; cA = nA; cB = nB; ++ui;
;     }
;     PG8_WAIT_V(0);
;     __device__ __forceinline__ void operator()(const AccT& acc, const Unit& u, int wr, int wc, int fr, int fq) const {
;     ...
;                         const int t = t0 & 2047;
; #pragma unroll
;                         for (int hf = 0; hf < 2; ++hf) {
;                             f32x4 cs, sn;
;                             if (m < 2) { const float c1 = ropeA[(t >> 6) * 16 + d], s1 = ropeA[1024 + (t >> 6) * 16 + d]; cs = (f32x4){c1, c1, c1, c1}; sn = (f32x4){s1, s1, s1, s1}; }
;                             else { const float* cb = ropeA + 2048 + (d - 16) * 64 + (t & 63) + 4 * hf; cs = *(const f32x4*)(cb); sn = *(const f32x4*)(cb + 1024); }
; #pragma unroll
;                             for (int jj = 0; jj < 4; ++jj) { const float pr = __shfl_xor(v[4 * hf + jj], 4); v[4 * hf + jj] = v[4 * hf + jj] * cs[jj] + sgn * pr * sn[jj]; }
;                             __builtin_amdgcn_sched_barrier(0);
;                         }
;                     }
;                     float zf[8], zb[8]; zf[0] = zf0; zb[0] = zb0;
; #pragma unroll
;                     for (int jj = 1; jj < 8; ++jj) { zf[jj] = zf[jj - 1] * zfs; zb[jj] = zb[jj - 1] * zbs; }
;                     u32x4 wf, wb;
;                     wf.x = cvt_pk_bf16(v[0] * zf[0], v[1] * zf[1]); wf.y = cvt_pk_bf16(v[2] * zf[2], v[3] * zf[3]); wf.z = cvt_pk_bf16(v[4] * zf[4], v[5] * zf[5]); wf.w = cvt_pk_bf16(v[6] * zf[6], v[7] * zf[7]);
;                     wb.x = cvt_pk_bf16(v[0] * zb[0], v[1] * zb[1]); wb.y = cvt_pk_bf16(v[2] * zb[2], v[3] * zb[3]); wb.z = cvt_pk_bf16(v[4] * zb[4], v[5] * zb[5]); wb.w = cvt_pk_bf16(v[6] * zb[6], v[7] * zb[7]);
;                     *(u32x4*)(KTZ + (size_t)r * NT + t0) = wf;
;                     *(u32x4*)(KTZ + (size_t)(256 + r) * NT + t0) = wb;
;                     __builtin_amdgcn_sched_barrier(0);
	v_mov_b32_e32 v22, v16
	v_mov_b32_e32 v12, v9
	v_mov_b32_e32 v24, v17
	v_mov_b32_e32 v9, v14
	v_mov_b32_e32 v26, v18
	v_mov_b32_e32 v14, v11
	v_mov_b32_e32 v28, v19
	v_pk_mul_f32 v[10:11], v[20:21], v[22:23]
	v_pk_mul_f32 v[12:13], v[12:13], v[24:25]
	v_pk_mul_f32 v[8:9], v[8:9], v[26:27]
	v_pk_mul_f32 v[14:15], v[14:15], v[28:29]
	v_add_f32_e32 v16, v10, v11
	v_add_f32_e32 v17, v12, v13
	v_add_f32_e32 v8, v8, v9
	v_add_f32_e32 v9, v14, v15
	v_mul_f32_e32 v10, v63, v30
	v_mul_f32_e32 v11, v75, v31
	v_cvt_pk_bf16_f32 v10, v10, v11
	v_mul_f32_e32 v11, v84, v32
	v_mul_f32_e32 v12, v86, v33
	v_cvt_pk_bf16_f32 v11, v11, v12
	v_mul_f32_e32 v12, v85, v16
	v_mul_f32_e32 v13, v88, v17
	v_cvt_pk_bf16_f32 v12, v12, v13
	v_mul_f32_e32 v13, v87, v8
	v_mul_f32_e32 v14, v71, v9
	v_cvt_pk_bf16_f32 v13, v13, v14
	v_mul_f32_e32 v14, v64, v30
	v_mul_f32_e32 v15, v60, v31
	v_cvt_pk_bf16_f32 v14, v14, v15
	v_mul_f32_e32 v15, v66, v32
	v_mul_f32_e32 v18, v68, v33
	v_cvt_pk_bf16_f32 v15, v15, v18
	v_add_co_u32_e64 v18, s[4:5], s63, v120
	v_mul_f32_e32 v16, v70, v16
	v_mul_f32_e32 v17, v72, v17
	v_addc_co_u32_e64 v19, s[4:5], 0, v121, s[4:5]
	v_cvt_pk_bf16_f32 v16, v16, v17
	v_mul_f32_e32 v8, v65, v8
	v_mul_f32_e32 v9, v67, v9
	v_cvt_pk_bf16_f32 v17, v8, v9
	global_store_dwordx4 v[18:19], v[10:13], off
	v_lshl_add_u64 v[8:9], v[120:121], 0, s[26:27]
	s_nop 0
	v_add_co_u32_e64 v12, s[4:5], s64, v120
	v_lshl_add_u64 v[10:11], v[120:121], 0, s[28:29]
	s_nop 0
	v_addc_co_u32_e64 v13, s[4:5], 0, v121, s[4:5]
	global_store_dwordx4 v[12:13], v[14:17], off
	global_load_dwordx4 v[12:15], v[82:83], off
	s_nop 0
	global_load_dwordx4 v[16:19], v[80:81], off
	ds_bpermute_b32 v34, v177, v4
	ds_bpermute_b32 v32, v177, v5
	ds_bpermute_b32 v33, v177, v6
	ds_bpermute_b32 v28, v177, v7
	global_load_dwordx4 v[20:23], v[76:77], off offset:16
	global_load_dwordx4 v[24:27], v[78:79], off offset:16
	s_waitcnt lgkmcnt(0)
	v_cndmask_b32_e64 v29, v28, -v28, vcc
	v_mov_b32_e32 v30, v7
	s_waitcnt vmcnt(3)
	v_mov_b32_e32 v31, v15
	s_waitcnt vmcnt(2)
	v_mov_b32_e32 v28, v19
	v_cndmask_b32_e64 v19, v33, -v33, vcc
	v_mov_b32_e32 v7, v14
	v_cndmask_b32_e64 v15, v32, -v32, vcc
	v_mov_b32_e32 v32, v5
	v_mov_b32_e32 v33, v13
	v_mov_b32_e32 v14, v17
	v_cndmask_b32_e64 v17, v34, -v34, vcc
	v_mov_b32_e32 v5, v12
	ds_bpermute_b32 v13, v177, v0
	v_mov_b32_e32 v12, v0
	ds_bpermute_b32 v34, v177, v1
	ds_bpermute_b32 v35, v177, v2
	v_mov_b32_e32 v0, v2
	ds_bpermute_b32 v2, v177, v3
	v_pk_mul_f32 v[28:29], v[30:31], v[28:29]
	v_pk_mul_f32 v[6:7], v[6:7], v[18:19]
	v_pk_mul_f32 v[14:15], v[32:33], v[14:15]
	v_pk_mul_f32 v[4:5], v[4:5], v[16:17]
	v_add_f32_e32 v18, v28, v29
	v_add_f32_e32 v19, v6, v7
	v_add_f32_e32 v28, v14, v15
	v_add_f32_e32 v29, v4, v5
	s_waitcnt lgkmcnt(3)
	v_cndmask_b32_e64 v5, v13, -v13, vcc
	s_waitcnt lgkmcnt(2)
	v_cndmask_b32_e64 v7, v34, -v34, vcc
	s_waitcnt lgkmcnt(1)
	v_cndmask_b32_e64 v15, v35, -v35, vcc
	s_waitcnt lgkmcnt(0)
	v_cndmask_b32_e64 v17, v2, -v2, vcc
	s_waitcnt vmcnt(1)
	v_mov_b32_e32 v13, v20
	s_waitcnt vmcnt(0)
	v_mov_b32_e32 v4, v24
	v_mov_b32_e32 v20, v1
	v_mov_b32_e32 v6, v25
	v_mov_b32_e32 v1, v22
	v_mov_b32_e32 v14, v26
	v_mov_b32_e32 v22, v3
	v_mov_b32_e32 v16, v27
	v_pk_mul_f32 v[2:3], v[12:13], v[4:5]
	v_pk_mul_f32 v[4:5], v[20:21], v[6:7]
	v_pk_mul_f32 v[0:1], v[0:1], v[14:15]
	v_pk_mul_f32 v[6:7], v[22:23], v[16:17]
	v_add_f32_e32 v12, v2, v3
	v_add_f32_e32 v13, v4, v5
	v_add_f32_e32 v14, v0, v1
	v_add_f32_e32 v7, v6, v7
	v_mul_f32_e32 v0, v63, v29
	v_mul_f32_e32 v1, v75, v28
	v_cvt_pk_bf16_f32 v0, v0, v1
	v_mul_f32_e32 v1, v84, v19
	v_mul_f32_e32 v2, v86, v18
	v_cvt_pk_bf16_f32 v1, v1, v2
	v_mul_f32_e32 v2, v85, v12
	v_mul_f32_e32 v3, v88, v13
	v_cvt_pk_bf16_f32 v2, v2, v3
	v_mul_f32_e32 v3, v87, v14
	v_mul_f32_e32 v4, v71, v7
	v_cvt_pk_bf16_f32 v3, v3, v4
	v_mul_f32_e32 v4, v64, v29
	v_mul_f32_e32 v5, v60, v28
	v_cvt_pk_bf16_f32 v4, v4, v5
	v_mul_f32_e32 v5, v66, v19
	v_mul_f32_e32 v6, v68, v18
	v_cvt_pk_bf16_f32 v5, v5, v6
	v_mul_f32_e32 v6, v70, v12
	v_mul_f32_e32 v12, v72, v13
	v_mul_f32_e32 v7, v67, v7
	v_cvt_pk_bf16_f32 v6, v6, v12
	v_mul_f32_e32 v12, v65, v14
	v_cvt_pk_bf16_f32 v7, v12, v7
	global_store_dwordx4 v[8:9], v[0:3], off offset:256
	global_store_dwordx4 v[10:11], v[4:7], off offset:256
	s_and_b64 vcc, exec, s[2:3]
	s_mov_b32 s33, s30
	s_mov_b64 s[4:5], s[38:39]
	s_mov_b64 s[0:1], s[36:37]
	s_cbranch_vccz .LBB0_606
	s_waitcnt vmcnt(0)
	s_cmpk_gt_u32 s42, 0xff
	s_cbranch_scc1 .LBB0_617
	s_barrier

; #define PG8_STAGE(bufoff, gbase, voff) do { _Pragma("unroll") for (int _i = 0; _i < 2; ++_i) \
;         __builtin_amdgcn_global_load_lds((const unsigned*)((const char*)(gbase) + (voff)[_i]), (LAS unsigned*)(lds + (bufoff) + ldsw + _i * 8192), 16, 0, 0); } while (0)
; #define PG8_LDA(dst, b, h) do { _Pragma("unroll") for (int m = 0; m < 4; ++m) _Pragma("unroll") for (int k = 0; k < 2; ++k) dst[m][k] = *(const LAS bf16x8*)(lds + PG8_SA(b, h) + aoff + m * 2048 + k * 1024); } while (0)
; #define PG8_LDB(dst, b, h) do { _Pragma("unroll") for (int n = 0; n < 2; ++n) _Pragma("unroll") for (int k = 0; k < 2; ++k) dst[n][k] = *(const LAS bf16x8*)(lds + PG8_SB(b, h) + boff + n * 2048 + k * 1024); } while (0)
; #define PG8_MMA(ai, bj, At, Bt) do { __builtin_amdgcn_s_setprio(1); _Pragma("unroll") for (int m = 0; m < 4; ++m) _Pragma("unroll") for (int n = 0; n < 2; ++n) _Pragma("unroll") for (int k = 0; k < 2; ++k) \
;         acc[ai][bj][m][n] = __builtin_amdgcn_mfma_f32_16x16x32_bf16(Bt[n][k], At[m][k], acc[ai][bj][m][n], 0, 0, 0); __builtin_amdgcn_s_setprio(0); } while (0)
; #define PG8_WAIT_L(n) asm volatile("s_waitcnt lgkmcnt(" #n ")" ::: "memory")
; template <class Epi, class Sched>
; __device__ __forceinline__ void gemm_phase(LAS unsigned char* lds, const Gemm g, const Sched& S, const Epi& E) {
;     ...
;         const bool has_next = S.next(ui + 1, nxt);
;         const char* nA = has_next ? (const char*)g.A + (size_t)nxt.pm * tstep : cA; const char* nB = has_next ? (const char*)g.Bt + (size_t)nxt.pn * tstep : cB;
;         for (int t = 0; t < nt; t += 2) {
;             const bool last = (t == nt - 2);
;             const char* a1 = cA + (size_t)(t + 1) * kstep;
;             const char* a2 = last ? nA : cA + (size_t)(t + 2) * kstep; const char* b2 = last ? nB : cB + (size_t)(t + 2) * kstep;
;             const char* a3 = a2 + kstep; const char* b3 = b2 + kstep;
;             PG8_LDB(B0, 0, 0); PG8_SCHED; PG8_LDA(At, 0, 0); PG8_STAGE(PG8_SA(1, 1), a1 + hstep, voffA);
;             PG8_WAIT_L(8); PG8_BAR; PG8_WAIT_L(0); PG8_MMA(0, 0, At, B0); PG8_BAR; PG8_SCHED;
;             PG8_LDB(B1, 0, 1); PG8_STAGE(PG8_SB(0, 0), b2, voffB);
;             PG8_BAR; PG8_WAIT_L(0); PG8_MMA(0, 1, At, B1); PG8_BAR;
;             PG8_LDA(At, 0, 1); PG8_STAGE(PG8_SA(0, 0), a2, voffA);
;             PG8_BAR; PG8_WAIT_L(0); PG8_MMA(1, 0, At, B0); PG8_BAR; PG8_SCHED;
.LBB0_632:
	s_ashr_i32 s23, s22, 31
	v_cmp_lt_i64_e32 vcc, s[24:25], v[140:141]
	s_lshl_b64 s[24:25], s[22:23], 19
	s_add_u32 s24, s38, s24
	s_addc_u32 s25, s39, s25
	s_and_b64 s[26:27], vcc, exec
	s_cselect_b32 s23, s25, s31
	s_cselect_b32 s61, s24, s30
	s_ashr_i32 s21, s20, 31
	s_lshl_b64 s[26:27], s[20:21], 19
	s_add_u32 s26, s96, s26
	s_addc_u32 s27, s97, s27
	s_and_b64 s[36:37], vcc, exec
	s_cselect_b32 s21, s27, s35
	s_cselect_b32 s62, s26, s34
	s_add_u32 s30, s30, 0x40080
	s_addc_u32 s31, s31, 0
	s_add_u32 s63, s34, 0x100
	s_addc_u32 s64, s35, 0
	s_mov_b32 s65, -2
	s_waitcnt lgkmcnt(0)
	ds_read_b128 v[150:153], v147
	ds_read_b128 v[154:157], v147 offset:1024
	ds_read_b128 v[158:161], v147 offset:2048
	ds_read_b128 v[162:165], v147 offset:3072
	s_add_u32 s34, s30, 0xfffc0080
	s_addc_u32 s35, s31, -1
	s_cmp_eq_u32 s65, 12
	s_cselect_b32 s37, s23, s35
	s_cselect_b32 s36, s61, s34
	s_cselect_b32 s35, s21, s64
	s_cselect_b32 s34, s62, s63
	s_add_i32 m0, s29, 0xc000
	ds_read_b128 v[166:169], v148
	ds_read_b128 v[170:173], v148 offset:1024
	ds_read_b128 v[174:177], v148 offset:2048
	ds_read_b128 v[178:181], v148 offset:3072
	ds_read_b128 v[182:185], v148 offset:4096
	ds_read_b128 v[186:189], v148 offset:5120
	ds_read_b128 v[190:193], v148 offset:6144
	ds_read_b128 v[194:197], v148 offset:7168
	global_load_lds_dwordx4 v136, s[30:31]
	s_add_i32 m0, s29, 0xe000
	s_nop 0
	global_load_lds_dwordx4 v138, s[30:31]
	s_waitcnt lgkmcnt(8)
	s_waitcnt vmcnt(8)
	s_setprio 1
	s_barrier
	s_waitcnt lgkmcnt(0)
	v_mfma_f32_16x16x32_bf16 v[124:127], v[150:153], v[166:169], 0
	v_mfma_f32_16x16x32_bf16 v[120:123], v[158:161], v[166:169], 0
	v_mfma_f32_16x16x32_bf16 v[116:119], v[150:153], v[174:177], 0
	v_mfma_f32_16x16x32_bf16 v[108:111], v[158:161], v[174:177], 0
	v_mfma_f32_16x16x32_bf16 v[100:103], v[150:153], v[182:185], 0
	v_mfma_f32_16x16x32_bf16 v[92:95], v[158:161], v[182:185], 0
	v_mfma_f32_16x16x32_bf16 v[84:87], v[150:153], v[190:193], 0
	v_mfma_f32_16x16x32_bf16 v[76:79], v[158:161], v[190:193], 0
	v_mfma_f32_16x16x32_bf16 v[124:127], v[154:157], v[170:173], v[124:127]
	v_mfma_f32_16x16x32_bf16 v[120:123], v[162:165], v[170:173], v[120:123]
	v_mfma_f32_16x16x32_bf16 v[116:119], v[154:157], v[178:181], v[116:119]
	v_mfma_f32_16x16x32_bf16 v[108:111], v[162:165], v[178:181], v[108:111]
	v_mfma_f32_16x16x32_bf16 v[100:103], v[154:157], v[186:189], v[100:103]
	v_mfma_f32_16x16x32_bf16 v[92:95], v[162:165], v[186:189], v[92:95]
	v_mfma_f32_16x16x32_bf16 v[84:87], v[154:157], v[194:197], v[84:87]
	v_mfma_f32_16x16x32_bf16 v[76:79], v[162:165], v[194:197], v[76:79]
	s_setprio 0
	s_barrier
	s_add_i32 s66, s54, s43
	s_mov_b32 m0, s66
	ds_read_b128 v[202:205], v149
	ds_read_b128 v[206:209], v149 offset:1024
	ds_read_b128 v[210:213], v149 offset:2048
	ds_read_b128 v[214:217], v149 offset:3072
	global_load_lds_dwordx4 v130, s[34:35]
	s_add_i32 m0, s66, 0x2000
	s_nop 0
	global_load_lds_dwordx4 v134, s[34:35]
	s_waitcnt vmcnt(8)
	s_setprio 1
	s_barrier
	s_waitcnt lgkmcnt(0)
	v_mfma_f32_16x16x32_bf16 v[112:115], v[202:205], v[166:169], 0
	v_mfma_f32_16x16x32_bf16 v[104:107], v[210:213], v[166:169], 0
	v_mfma_f32_16x16x32_bf16 v[96:99], v[202:205], v[174:177], 0
	v_mfma_f32_16x16x32_bf16 v[88:91], v[210:213], v[174:177], 0
	v_mfma_f32_16x16x32_bf16 v[80:83], v[202:205], v[182:185], 0
	v_mfma_f32_16x16x32_bf16 v[72:75], v[210:213], v[182:185], 0
	v_mfma_f32_16x16x32_bf16 v[68:71], v[202:205], v[190:193], 0
	v_mfma_f32_16x16x32_bf16 v[64:67], v[210:213], v[190:193], 0
	v_mfma_f32_16x16x32_bf16 v[112:115], v[206:209], v[170:173], v[112:115]
	v_mfma_f32_16x16x32_bf16 v[104:107], v[214:217], v[170:173], v[104:107]
	v_mfma_f32_16x16x32_bf16 v[96:99], v[206:209], v[178:181], v[96:99]
	v_mfma_f32_16x16x32_bf16 v[88:91], v[214:217], v[178:181], v[88:91]
	v_mfma_f32_16x16x32_bf16 v[80:83], v[206:209], v[186:189], v[80:83]
	v_mfma_f32_16x16x32_bf16 v[72:75], v[214:217], v[186:189], v[72:75]
	v_mfma_f32_16x16x32_bf16 v[68:71], v[206:209], v[194:197], v[68:71]
	v_mfma_f32_16x16x32_bf16 v[64:67], v[214:217], v[194:197], v[64:67]
	s_setprio 0
	s_mov_b32 m0, s29
	v_lshl_add_u64 v[220:221], s[36:37], 0, v[128:129]
	s_barrier
	ds_read_b128 v[166:169], v148 offset:16384
	ds_read_b128 v[170:173], v148 offset:17408
	ds_read_b128 v[174:177], v148 offset:18432
	ds_read_b128 v[178:181], v148 offset:19456
	ds_read_b128 v[182:185], v148 offset:20480
	ds_read_b128 v[186:189], v148 offset:21504
	ds_read_b128 v[190:193], v148 offset:22528
	ds_read_b128 v[194:197], v148 offset:23552
	global_load_lds_dwordx4 v128, s[36:37]
	v_lshl_add_u64 v[222:223], s[36:37], 0, v[132:133]
	s_mov_b32 m0, s44
	s_nop 0
	global_load_lds_dwordx4 v132, s[36:37]
	s_setprio 1
	s_barrier
	s_waitcnt lgkmcnt(0)
	v_mfma_f32_16x16x32_bf16 v[60:63], v[150:153], v[166:169], 0
	v_mfma_f32_16x16x32_bf16 v[56:59], v[158:161], v[166:169], 0
	v_mfma_f32_16x16x32_bf16 v[52:55], v[150:153], v[174:177], 0
	v_mfma_f32_16x16x32_bf16 v[44:47], v[158:161], v[174:177], 0
	v_mfma_f32_16x16x32_bf16 v[36:39], v[150:153], v[182:185], 0
	v_mfma_f32_16x16x32_bf16 v[28:31], v[158:161], v[182:185], 0
	v_mfma_f32_16x16x32_bf16 v[20:23], v[150:153], v[190:193], 0
	v_mfma_f32_16x16x32_bf16 v[12:15], v[158:161], v[190:193], 0
	v_mfma_f32_16x16x32_bf16 v[60:63], v[154:157], v[170:173], v[60:63]
	v_mfma_f32_16x16x32_bf16 v[56:59], v[162:165], v[170:173], v[56:59]
	v_mfma_f32_16x16x32_bf16 v[52:55], v[154:157], v[178:181], v[52:55]
	v_mfma_f32_16x16x32_bf16 v[44:47], v[162:165], v[178:181], v[44:47]
	v_mfma_f32_16x16x32_bf16 v[36:39], v[154:157], v[186:189], v[36:39]
	v_mfma_f32_16x16x32_bf16 v[28:31], v[162:165], v[186:189], v[28:31]
	v_mfma_f32_16x16x32_bf16 v[20:23], v[154:157], v[194:197], v[20:23]
	v_mfma_f32_16x16x32_bf16 v[12:15], v[162:165], v[194:197], v[12:15]
	s_setprio 0
	s_barrier
; #define PG8_STAGE(bufoff, gbase, voff) do { _Pragma("unroll") for (int _i = 0; _i < 2; ++_i) \
;         __builtin_amdgcn_global_load_lds((const unsigned*)((const char*)(gbase) + (voff)[_i]), (LAS unsigned*)(lds + (bufoff) + ldsw + _i * 8192), 16, 0, 0); } while (0)
; #define PG8_LDA(dst, b, h) do { _Pragma("unroll") for (int m = 0; m < 4; ++m) _Pragma("unroll") for (int k = 0; k < 2; ++k) dst[m][k] = *(const LAS bf16x8*)(lds + PG8_SA(b, h) + aoff + m * 2048 + k * 1024); } while (0)
; #define PG8_LDB(dst, b, h) do { _Pragma("unroll") for (int n = 0; n < 2; ++n) _Pragma("unroll") for (int k = 0; k < 2; ++k) dst[n][k] = *(const LAS bf16x8*)(lds + PG8_SB(b, h) + boff + n * 2048 + k * 1024); } while (0)
; #define PG8_MMA(ai, bj, At, Bt) do { __builtin_amdgcn_s_setprio(1); _Pragma("unroll") for (int m = 0; m < 4; ++m) _Pragma("unroll") for (int n = 0; n < 2; ++n) _Pragma("unroll") for (int k = 0; k < 2; ++k) \
;         acc[ai][bj][m][n] = __builtin_amdgcn_mfma_f32_16x16x32_bf16(Bt[n][k], At[m][k], acc[ai][bj][m][n], 0, 0, 0); __builtin_amdgcn_s_setprio(0); } while (0)
; #define PG8_WAIT_V(n) asm volatile("s_waitcnt vmcnt(" #n ")" ::: "memory")
; #define PG8_WAIT_L(n) asm volatile("s_waitcnt lgkmcnt(" #n ")" ::: "memory")
; #define PG8_BAR __builtin_amdgcn_s_barrier()
; #define PG8_SCHED __builtin_amdgcn_sched_barrier(0)
; template <class Epi, class Sched>
; __device__ __forceinline__ void gemm_phase(LAS unsigned char* lds, const Gemm g, const Sched& S, const Epi& E) {
;     ...
;             PG8_STAGE(PG8_SB(0, 1), b2 + hstep, voffB);
;             PG8_WAIT_V(6); PG8_BAR; PG8_MMA(1, 1, At, B1); PG8_BAR;
;             PG8_LDB(B0, 1, 0); PG8_SCHED; PG8_LDA(At, 1, 0); PG8_STAGE(PG8_SA(0, 1), a2 + hstep, voffA);
;             PG8_WAIT_L(8); PG8_BAR; PG8_WAIT_L(0); PG8_MMA(0, 0, At, B0); PG8_BAR; PG8_SCHED;
;             PG8_LDB(B1, 1, 1); PG8_STAGE(PG8_SB(1, 0), b3, voffB);
;             PG8_BAR; PG8_WAIT_L(0); PG8_MMA(0, 1, At, B1); PG8_BAR;
;             PG8_LDA(At, 1, 1); PG8_STAGE(PG8_SA(1, 0), a3, voffA);
;             PG8_BAR; PG8_WAIT_L(0); PG8_MMA(1, 0, At, B0); PG8_BAR; PG8_SCHED;
	s_add_u32 s66, s34, 0x40000
	s_addc_u32 s67, s35, 0
	s_add_i32 s68, s55, s43
	s_mov_b32 m0, s68
	s_nop 0
	global_load_lds_dwordx4 v130, s[66:67]
	s_add_i32 m0, s68, 0x2000
	s_nop 0
	global_load_lds_dwordx4 v134, s[66:67]
	s_add_u32 s36, s36, 0x40000
	s_addc_u32 s37, s37, 0
	s_mov_b32 m0, s45
	s_nop 0
	global_load_lds_dwordx4 v128, s[36:37]
	s_mov_b32 m0, s46
	s_nop 0
	global_load_lds_dwordx4 v132, s[36:37]
	s_waitcnt vmcnt(10)
	s_setprio 1
	s_barrier
	v_mfma_f32_16x16x32_bf16 v[48:51], v[202:205], v[166:169], 0
	v_mfma_f32_16x16x32_bf16 v[40:43], v[210:213], v[166:169], 0
	v_mfma_f32_16x16x32_bf16 v[32:35], v[202:205], v[174:177], 0
	v_mfma_f32_16x16x32_bf16 v[24:27], v[210:213], v[174:177], 0
	v_mfma_f32_16x16x32_bf16 v[16:19], v[202:205], v[182:185], 0
	v_mfma_f32_16x16x32_bf16 v[8:11], v[210:213], v[182:185], 0
	v_mfma_f32_16x16x32_bf16 v[4:7], v[202:205], v[190:193], 0
	v_mfma_f32_16x16x32_bf16 v[0:3], v[210:213], v[190:193], 0
	v_mfma_f32_16x16x32_bf16 v[48:51], v[206:209], v[170:173], v[48:51]
	v_mfma_f32_16x16x32_bf16 v[40:43], v[214:217], v[170:173], v[40:43]
	v_mfma_f32_16x16x32_bf16 v[32:35], v[206:209], v[178:181], v[32:35]
	v_mfma_f32_16x16x32_bf16 v[24:27], v[214:217], v[178:181], v[24:27]
	v_mfma_f32_16x16x32_bf16 v[16:19], v[206:209], v[186:189], v[16:19]
	v_mfma_f32_16x16x32_bf16 v[8:11], v[214:217], v[186:189], v[8:11]
	v_mfma_f32_16x16x32_bf16 v[4:7], v[206:209], v[194:197], v[4:7]
	v_mfma_f32_16x16x32_bf16 v[0:3], v[214:217], v[194:197], v[0:3]
	s_setprio 0
	s_add_i32 s66, 0, 0x18000
	v_add_u32_e32 v162, s66, v146
	s_barrier
	ds_read_b128 v[150:153], v162
	ds_read_b128 v[154:157], v162 offset:1024
	ds_read_b128 v[158:161], v162 offset:2048
	ds_read_b128 v[162:165], v162 offset:3072
	ds_read_b128 v[166:169], v148 offset:32768
	ds_read_b128 v[170:173], v148 offset:33792
	ds_read_b128 v[174:177], v148 offset:34816
	ds_read_b128 v[178:181], v148 offset:35840
	ds_read_b128 v[182:185], v148 offset:36864
	ds_read_b128 v[186:189], v148 offset:37888
	ds_read_b128 v[190:193], v148 offset:38912
	ds_read_b128 v[194:197], v148 offset:39936
	s_waitcnt lgkmcnt(8)
	s_waitcnt vmcnt(8)
	s_setprio 1
	s_barrier
	s_waitcnt lgkmcnt(0)
	v_mfma_f32_16x16x32_bf16 v[124:127], v[150:153], v[166:169], v[124:127]
	v_mfma_f32_16x16x32_bf16 v[120:123], v[158:161], v[166:169], v[120:123]
	v_mfma_f32_16x16x32_bf16 v[116:119], v[150:153], v[174:177], v[116:119]
	v_mfma_f32_16x16x32_bf16 v[108:111], v[158:161], v[174:177], v[108:111]
	v_mfma_f32_16x16x32_bf16 v[100:103], v[150:153], v[182:185], v[100:103]
	v_mfma_f32_16x16x32_bf16 v[92:95], v[158:161], v[182:185], v[92:95]
	v_mfma_f32_16x16x32_bf16 v[84:87], v[150:153], v[190:193], v[84:87]
	v_mfma_f32_16x16x32_bf16 v[76:79], v[158:161], v[190:193], v[76:79]
	v_mfma_f32_16x16x32_bf16 v[124:127], v[154:157], v[170:173], v[124:127]
	v_mfma_f32_16x16x32_bf16 v[120:123], v[162:165], v[170:173], v[120:123]
	v_mfma_f32_16x16x32_bf16 v[116:119], v[154:157], v[178:181], v[116:119]
	v_mfma_f32_16x16x32_bf16 v[108:111], v[162:165], v[178:181], v[108:111]
	v_mfma_f32_16x16x32_bf16 v[100:103], v[154:157], v[186:189], v[100:103]
	v_mfma_f32_16x16x32_bf16 v[92:95], v[162:165], v[186:189], v[92:95]
	v_mfma_f32_16x16x32_bf16 v[84:87], v[154:157], v[194:197], v[84:87]
	v_mfma_f32_16x16x32_bf16 v[76:79], v[162:165], v[194:197], v[76:79]
	s_setprio 0
	s_barrier
	s_add_i32 s36, 0, 0x1c000
	s_add_i32 s37, s66, s43
	v_add_u32_e32 v214, s36, v146
	s_add_u32 s4, s34, 0x80
	s_addc_u32 s5, s35, 0
	s_mov_b32 m0, s37
	ds_read_b128 v[202:205], v214
	ds_read_b128 v[206:209], v214 offset:1024
	ds_read_b128 v[210:213], v214 offset:2048
	ds_read_b128 v[214:217], v214 offset:3072
	global_load_lds_dwordx4 v130, s[4:5]
	s_add_i32 m0, s37, 0x2000
	s_nop 0
	global_load_lds_dwordx4 v134, s[4:5]
	s_waitcnt vmcnt(8)
	s_setprio 1
	s_barrier
	s_waitcnt lgkmcnt(0)
	v_mfma_f32_16x16x32_bf16 v[112:115], v[202:205], v[166:169], v[112:115]
	v_mfma_f32_16x16x32_bf16 v[104:107], v[210:213], v[166:169], v[104:107]
	v_mfma_f32_16x16x32_bf16 v[96:99], v[202:205], v[174:177], v[96:99]
	v_mfma_f32_16x16x32_bf16 v[88:91], v[210:213], v[174:177], v[88:91]
	v_mfma_f32_16x16x32_bf16 v[80:83], v[202:205], v[182:185], v[80:83]
	v_mfma_f32_16x16x32_bf16 v[72:75], v[210:213], v[182:185], v[72:75]
	v_mfma_f32_16x16x32_bf16 v[68:71], v[202:205], v[190:193], v[68:71]
	v_mfma_f32_16x16x32_bf16 v[64:67], v[210:213], v[190:193], v[64:67]
	v_mfma_f32_16x16x32_bf16 v[112:115], v[206:209], v[170:173], v[112:115]
	v_mfma_f32_16x16x32_bf16 v[104:107], v[214:217], v[170:173], v[104:107]
	v_mfma_f32_16x16x32_bf16 v[96:99], v[206:209], v[178:181], v[96:99]
	v_mfma_f32_16x16x32_bf16 v[88:91], v[214:217], v[178:181], v[88:91]
	v_mfma_f32_16x16x32_bf16 v[80:83], v[206:209], v[186:189], v[80:83]
	v_mfma_f32_16x16x32_bf16 v[72:75], v[214:217], v[186:189], v[72:75]
	v_mfma_f32_16x16x32_bf16 v[68:71], v[206:209], v[194:197], v[68:71]
	v_mfma_f32_16x16x32_bf16 v[64:67], v[214:217], v[194:197], v[64:67]
	s_setprio 0
	s_mov_b32 m0, s51
	s_mov_b64 s[4:5], 0x80
	v_lshl_add_u64 v[198:199], v[220:221], 0, s[4:5]
	s_barrier
	ds_read_b128 v[166:169], v148 offset:49152
	ds_read_b128 v[170:173], v148 offset:50176
	ds_read_b128 v[174:177], v148 offset:51200
	ds_read_b128 v[178:181], v148 offset:52224
	ds_read_b128 v[182:185], v148 offset:53248
	ds_read_b128 v[186:189], v148 offset:54272
	ds_read_b128 v[190:193], v148 offset:55296
	ds_read_b128 v[194:197], v148 offset:56320
	global_load_lds_dwordx4 v[198:199], off
	v_lshl_add_u64 v[198:199], v[222:223], 0, s[4:5]
	s_mov_b32 m0, s52
	s_nop 0
	global_load_lds_dwordx4 v[198:199], off
	s_setprio 1
	s_barrier
; #define PG8_STAGE(bufoff, gbase, voff) do { _Pragma("unroll") for (int _i = 0; _i < 2; ++_i) \
;         __builtin_amdgcn_global_load_lds((const unsigned*)((const char*)(gbase) + (voff)[_i]), (LAS unsigned*)(lds + (bufoff) + ldsw + _i * 8192), 16, 0, 0); } while (0)
; #define PG8_LDA(dst, b, h) do { _Pragma("unroll") for (int m = 0; m < 4; ++m) _Pragma("unroll") for (int k = 0; k < 2; ++k) dst[m][k] = *(const LAS bf16x8*)(lds + PG8_SA(b, h) + aoff + m * 2048 + k * 1024); } while (0)
; #define PG8_LDB(dst, b, h) do { _Pragma("unroll") for (int n = 0; n < 2; ++n) _Pragma("unroll") for (int k = 0; k < 2; ++k) dst[n][k] = *(const LAS bf16x8*)(lds + PG8_SB(b, h) + boff + n * 2048 + k * 1024); } while (0)
; #define PG8_MMA(ai, bj, At, Bt) do { __builtin_amdgcn_s_setprio(1); _Pragma("unroll") for (int m = 0; m < 4; ++m) _Pragma("unroll") for (int n = 0; n < 2; ++n) _Pragma("unroll") for (int k = 0; k < 2; ++k) \
;         acc[ai][bj][m][n] = __builtin_amdgcn_mfma_f32_16x16x32_bf16(Bt[n][k], At[m][k], acc[ai][bj][m][n], 0, 0, 0); __builtin_amdgcn_s_setprio(0); } while (0)
; #define PG8_WAIT_V(n) asm volatile("s_waitcnt vmcnt(" #n ")" ::: "memory")
; #define PG8_WAIT_L(n) asm volatile("s_waitcnt lgkmcnt(" #n ")" ::: "memory")
; #define PG8_BAR __builtin_amdgcn_s_barrier()
; #define PG8_SCHED __builtin_amdgcn_sched_barrier(0)
; template <class Epi, class Sched>
; __device__ __forceinline__ void gemm_phase(LAS unsigned char* lds, const Gemm g, const Sched& S, const Epi& E) {
;     ...
;             PG8_LDB(B0, 0, 0); PG8_SCHED; PG8_LDA(At, 0, 0); PG8_STAGE(PG8_SA(1, 1), a1 + hstep, voffA);
;             PG8_WAIT_L(8); PG8_BAR; PG8_WAIT_L(0); PG8_MMA(0, 0, At, B0); PG8_BAR; PG8_SCHED;
;             PG8_LDB(B1, 0, 1); PG8_STAGE(PG8_SB(0, 0), b2, voffB);
;             PG8_BAR; PG8_WAIT_L(0); PG8_MMA(0, 1, At, B1); PG8_BAR;
;     ...
;             PG8_BAR; PG8_WAIT_L(0); PG8_MMA(1, 0, At, B0); PG8_BAR; PG8_SCHED;
;             PG8_STAGE(PG8_SB(1, 1), b3 + hstep, voffB);
;             PG8_WAIT_V(6); PG8_BAR; PG8_MMA(1, 1, At, B1); PG8_BAR;
	s_waitcnt lgkmcnt(0)
	v_mfma_f32_16x16x32_bf16 v[60:63], v[150:153], v[166:169], v[60:63]
	v_mfma_f32_16x16x32_bf16 v[56:59], v[158:161], v[166:169], v[56:59]
	v_mfma_f32_16x16x32_bf16 v[52:55], v[150:153], v[174:177], v[52:55]
	v_mfma_f32_16x16x32_bf16 v[44:47], v[158:161], v[174:177], v[44:47]
	v_mfma_f32_16x16x32_bf16 v[36:39], v[150:153], v[182:185], v[36:39]
	v_mfma_f32_16x16x32_bf16 v[28:31], v[158:161], v[182:185], v[28:31]
	v_mfma_f32_16x16x32_bf16 v[20:23], v[150:153], v[190:193], v[20:23]
	v_mfma_f32_16x16x32_bf16 v[12:15], v[158:161], v[190:193], v[12:15]
	v_mfma_f32_16x16x32_bf16 v[60:63], v[154:157], v[170:173], v[60:63]
	v_mfma_f32_16x16x32_bf16 v[56:59], v[162:165], v[170:173], v[56:59]
	v_mfma_f32_16x16x32_bf16 v[52:55], v[154:157], v[178:181], v[52:55]
	v_mfma_f32_16x16x32_bf16 v[44:47], v[162:165], v[178:181], v[44:47]
	v_mfma_f32_16x16x32_bf16 v[36:39], v[154:157], v[186:189], v[36:39]
	v_mfma_f32_16x16x32_bf16 v[28:31], v[162:165], v[186:189], v[28:31]
	v_mfma_f32_16x16x32_bf16 v[20:23], v[154:157], v[194:197], v[20:23]
	v_mfma_f32_16x16x32_bf16 v[12:15], v[162:165], v[194:197], v[12:15]
	s_setprio 0
	s_barrier
	s_add_u32 s34, s34, 0x40080
	s_addc_u32 s35, s35, 0
	s_add_i32 s36, s36, s43
	s_mov_b32 m0, s36
	s_nop 0
	global_load_lds_dwordx4 v130, s[34:35]
	s_add_i32 m0, s36, 0x2000
	s_nop 0
	global_load_lds_dwordx4 v134, s[34:35]
	s_waitcnt vmcnt(8)
	s_setprio 1
	s_barrier
	v_mfma_f32_16x16x32_bf16 v[48:51], v[202:205], v[166:169], v[48:51]
	v_mfma_f32_16x16x32_bf16 v[40:43], v[210:213], v[166:169], v[40:43]
	v_mfma_f32_16x16x32_bf16 v[32:35], v[202:205], v[174:177], v[32:35]
	v_mfma_f32_16x16x32_bf16 v[24:27], v[210:213], v[174:177], v[24:27]
	v_mfma_f32_16x16x32_bf16 v[16:19], v[202:205], v[182:185], v[16:19]
	v_mfma_f32_16x16x32_bf16 v[8:11], v[210:213], v[182:185], v[8:11]
	v_mfma_f32_16x16x32_bf16 v[4:7], v[202:205], v[190:193], v[4:7]
	v_mfma_f32_16x16x32_bf16 v[0:3], v[210:213], v[190:193], v[0:3]
	v_mfma_f32_16x16x32_bf16 v[48:51], v[206:209], v[170:173], v[48:51]
	v_mfma_f32_16x16x32_bf16 v[40:43], v[214:217], v[170:173], v[40:43]
	v_mfma_f32_16x16x32_bf16 v[32:35], v[206:209], v[178:181], v[32:35]
	v_mfma_f32_16x16x32_bf16 v[24:27], v[214:217], v[178:181], v[24:27]
	v_mfma_f32_16x16x32_bf16 v[16:19], v[206:209], v[186:189], v[16:19]
	v_mfma_f32_16x16x32_bf16 v[8:11], v[214:217], v[186:189], v[8:11]
	v_mfma_f32_16x16x32_bf16 v[4:7], v[206:209], v[194:197], v[4:7]
	v_mfma_f32_16x16x32_bf16 v[0:3], v[214:217], v[194:197], v[0:3]
	s_setprio 0
	s_add_i32 s65, s65, 2
	s_add_u32 s30, s30, 0x100
	s_addc_u32 s31, s31, 0
	s_add_u32 s63, s63, 0x100
	s_addc_u32 s64, s64, 0
	s_cmp_gt_u32 s65, 13
	s_barrier
.LBB0_633:
	ds_read_b128 v[150:153], v147
	ds_read_b128 v[154:157], v147 offset:1024
	ds_read_b128 v[158:161], v147 offset:2048
	ds_read_b128 v[162:165], v147 offset:3072
	s_add_u32 s34, s30, 0xfffc0080
	s_addc_u32 s35, s31, -1
	s_cmp_eq_u32 s65, 12
	s_cselect_b32 s37, s23, s35
	s_cselect_b32 s36, s61, s34
	s_cselect_b32 s35, s21, s64
	s_cselect_b32 s34, s62, s63
	s_add_i32 m0, s29, 0xc000
	ds_read_b128 v[166:169], v148
	ds_read_b128 v[170:173], v148 offset:1024
	ds_read_b128 v[174:177], v148 offset:2048
	ds_read_b128 v[178:181], v148 offset:3072
	ds_read_b128 v[182:185], v148 offset:4096
	ds_read_b128 v[186:189], v148 offset:5120
	ds_read_b128 v[190:193], v148 offset:6144
	ds_read_b128 v[194:197], v148 offset:7168
	global_load_lds_dwordx4 v136, s[30:31]
	s_add_i32 m0, s29, 0xe000
	s_nop 0
	global_load_lds_dwordx4 v138, s[30:31]
	s_waitcnt lgkmcnt(8)
	s_waitcnt vmcnt(8)
	s_setprio 1
	s_barrier
	s_waitcnt lgkmcnt(0)
	v_mfma_f32_16x16x32_bf16 v[124:127], v[150:153], v[166:169], v[124:127]
	v_mfma_f32_16x16x32_bf16 v[120:123], v[158:161], v[166:169], v[120:123]
	v_mfma_f32_16x16x32_bf16 v[116:119], v[150:153], v[174:177], v[116:119]
	v_mfma_f32_16x16x32_bf16 v[108:111], v[158:161], v[174:177], v[108:111]
	v_mfma_f32_16x16x32_bf16 v[100:103], v[150:153], v[182:185], v[100:103]
	v_mfma_f32_16x16x32_bf16 v[92:95], v[158:161], v[182:185], v[92:95]
	v_mfma_f32_16x16x32_bf16 v[84:87], v[150:153], v[190:193], v[84:87]
	v_mfma_f32_16x16x32_bf16 v[76:79], v[158:161], v[190:193], v[76:79]
	v_mfma_f32_16x16x32_bf16 v[124:127], v[154:157], v[170:173], v[124:127]
	v_mfma_f32_16x16x32_bf16 v[120:123], v[162:165], v[170:173], v[120:123]
	v_mfma_f32_16x16x32_bf16 v[116:119], v[154:157], v[178:181], v[116:119]
	v_mfma_f32_16x16x32_bf16 v[108:111], v[162:165], v[178:181], v[108:111]
	v_mfma_f32_16x16x32_bf16 v[100:103], v[154:157], v[186:189], v[100:103]
	v_mfma_f32_16x16x32_bf16 v[92:95], v[162:165], v[186:189], v[92:95]
	v_mfma_f32_16x16x32_bf16 v[84:87], v[154:157], v[194:197], v[84:87]
	v_mfma_f32_16x16x32_bf16 v[76:79], v[162:165], v[194:197], v[76:79]
	s_setprio 0
	s_barrier
	s_add_i32 s66, s54, s43
	s_mov_b32 m0, s66
	ds_read_b128 v[202:205], v149
	ds_read_b128 v[206:209], v149 offset:1024
	ds_read_b128 v[210:213], v149 offset:2048
	ds_read_b128 v[214:217], v149 offset:3072
	global_load_lds_dwordx4 v130, s[34:35]
	s_add_i32 m0, s66, 0x2000
	s_nop 0
	global_load_lds_dwordx4 v134, s[34:35]
	s_waitcnt vmcnt(8)
	s_setprio 1
	s_barrier
; #define PG8_STAGE(bufoff, gbase, voff) do { _Pragma("unroll") for (int _i = 0; _i < 2; ++_i) \
;         __builtin_amdgcn_global_load_lds((const unsigned*)((const char*)(gbase) + (voff)[_i]), (LAS unsigned*)(lds + (bufoff) + ldsw + _i * 8192), 16, 0, 0); } while (0)
; #define PG8_LDA(dst, b, h) do { _Pragma("unroll") for (int m = 0; m < 4; ++m) _Pragma("unroll") for (int k = 0; k < 2; ++k) dst[m][k] = *(const LAS bf16x8*)(lds + PG8_SA(b, h) + aoff + m * 2048 + k * 1024); } while (0)
; #define PG8_LDB(dst, b, h) do { _Pragma("unroll") for (int n = 0; n < 2; ++n) _Pragma("unroll") for (int k = 0; k < 2; ++k) dst[n][k] = *(const LAS bf16x8*)(lds + PG8_SB(b, h) + boff + n * 2048 + k * 1024); } while (0)
; #define PG8_MMA(ai, bj, At, Bt) do { __builtin_amdgcn_s_setprio(1); _Pragma("unroll") for (int m = 0; m < 4; ++m) _Pragma("unroll") for (int n = 0; n < 2; ++n) _Pragma("unroll") for (int k = 0; k < 2; ++k) \
;         acc[ai][bj][m][n] = __builtin_amdgcn_mfma_f32_16x16x32_bf16(Bt[n][k], At[m][k], acc[ai][bj][m][n], 0, 0, 0); __builtin_amdgcn_s_setprio(0); } while (0)
; #define PG8_WAIT_V(n) asm volatile("s_waitcnt vmcnt(" #n ")" ::: "memory")
; #define PG8_WAIT_L(n) asm volatile("s_waitcnt lgkmcnt(" #n ")" ::: "memory")
; #define PG8_BAR __builtin_amdgcn_s_barrier()
; #define PG8_SCHED __builtin_amdgcn_sched_barrier(0)
; template <class Epi, class Sched>
; __device__ __forceinline__ void gemm_phase(LAS unsigned char* lds, const Gemm g, const Sched& S, const Epi& E) {
;     ...
;             PG8_BAR; PG8_WAIT_L(0); PG8_MMA(0, 1, At, B1); PG8_BAR;
;             PG8_LDA(At, 0, 1); PG8_STAGE(PG8_SA(0, 0), a2, voffA);
;             PG8_BAR; PG8_WAIT_L(0); PG8_MMA(1, 0, At, B0); PG8_BAR; PG8_SCHED;
;             PG8_STAGE(PG8_SB(0, 1), b2 + hstep, voffB);
;             PG8_WAIT_V(6); PG8_BAR; PG8_MMA(1, 1, At, B1); PG8_BAR;
;             PG8_LDB(B0, 1, 0); PG8_SCHED; PG8_LDA(At, 1, 0); PG8_STAGE(PG8_SA(0, 1), a2 + hstep, voffA);
;             PG8_WAIT_L(8); PG8_BAR; PG8_WAIT_L(0); PG8_MMA(0, 0, At, B0); PG8_BAR; PG8_SCHED;
	s_waitcnt lgkmcnt(0)
	v_mfma_f32_16x16x32_bf16 v[112:115], v[202:205], v[166:169], v[112:115]
	v_mfma_f32_16x16x32_bf16 v[104:107], v[210:213], v[166:169], v[104:107]
	v_mfma_f32_16x16x32_bf16 v[96:99], v[202:205], v[174:177], v[96:99]
	v_mfma_f32_16x16x32_bf16 v[88:91], v[210:213], v[174:177], v[88:91]
	v_mfma_f32_16x16x32_bf16 v[80:83], v[202:205], v[182:185], v[80:83]
	v_mfma_f32_16x16x32_bf16 v[72:75], v[210:213], v[182:185], v[72:75]
	v_mfma_f32_16x16x32_bf16 v[68:71], v[202:205], v[190:193], v[68:71]
	v_mfma_f32_16x16x32_bf16 v[64:67], v[210:213], v[190:193], v[64:67]
	v_mfma_f32_16x16x32_bf16 v[112:115], v[206:209], v[170:173], v[112:115]
	v_mfma_f32_16x16x32_bf16 v[104:107], v[214:217], v[170:173], v[104:107]
	v_mfma_f32_16x16x32_bf16 v[96:99], v[206:209], v[178:181], v[96:99]
	v_mfma_f32_16x16x32_bf16 v[88:91], v[214:217], v[178:181], v[88:91]
	v_mfma_f32_16x16x32_bf16 v[80:83], v[206:209], v[186:189], v[80:83]
	v_mfma_f32_16x16x32_bf16 v[72:75], v[214:217], v[186:189], v[72:75]
	v_mfma_f32_16x16x32_bf16 v[68:71], v[206:209], v[194:197], v[68:71]
	v_mfma_f32_16x16x32_bf16 v[64:67], v[214:217], v[194:197], v[64:67]
	s_setprio 0
	s_mov_b32 m0, s29
	v_lshl_add_u64 v[220:221], s[36:37], 0, v[128:129]
	s_barrier
	ds_read_b128 v[166:169], v148 offset:16384
	ds_read_b128 v[170:173], v148 offset:17408
	ds_read_b128 v[174:177], v148 offset:18432
	ds_read_b128 v[178:181], v148 offset:19456
	ds_read_b128 v[182:185], v148 offset:20480
	ds_read_b128 v[186:189], v148 offset:21504
	ds_read_b128 v[190:193], v148 offset:22528
	ds_read_b128 v[194:197], v148 offset:23552
	global_load_lds_dwordx4 v128, s[36:37]
	v_lshl_add_u64 v[222:223], s[36:37], 0, v[132:133]
	s_mov_b32 m0, s44
	s_nop 0
	global_load_lds_dwordx4 v132, s[36:37]
	s_setprio 1
	s_barrier
	s_waitcnt lgkmcnt(0)
	v_mfma_f32_16x16x32_bf16 v[60:63], v[150:153], v[166:169], v[60:63]
	v_mfma_f32_16x16x32_bf16 v[56:59], v[158:161], v[166:169], v[56:59]
	v_mfma_f32_16x16x32_bf16 v[52:55], v[150:153], v[174:177], v[52:55]
	v_mfma_f32_16x16x32_bf16 v[44:47], v[158:161], v[174:177], v[44:47]
	v_mfma_f32_16x16x32_bf16 v[36:39], v[150:153], v[182:185], v[36:39]
	v_mfma_f32_16x16x32_bf16 v[28:31], v[158:161], v[182:185], v[28:31]
	v_mfma_f32_16x16x32_bf16 v[20:23], v[150:153], v[190:193], v[20:23]
	v_mfma_f32_16x16x32_bf16 v[12:15], v[158:161], v[190:193], v[12:15]
	v_mfma_f32_16x16x32_bf16 v[60:63], v[154:157], v[170:173], v[60:63]
	v_mfma_f32_16x16x32_bf16 v[56:59], v[162:165], v[170:173], v[56:59]
	v_mfma_f32_16x16x32_bf16 v[52:55], v[154:157], v[178:181], v[52:55]
	v_mfma_f32_16x16x32_bf16 v[44:47], v[162:165], v[178:181], v[44:47]
	v_mfma_f32_16x16x32_bf16 v[36:39], v[154:157], v[186:189], v[36:39]
	v_mfma_f32_16x16x32_bf16 v[28:31], v[162:165], v[186:189], v[28:31]
	v_mfma_f32_16x16x32_bf16 v[20:23], v[154:157], v[194:197], v[20:23]
	v_mfma_f32_16x16x32_bf16 v[12:15], v[162:165], v[194:197], v[12:15]
	s_setprio 0
	s_barrier
	s_add_u32 s66, s34, 0x40000
	s_addc_u32 s67, s35, 0
	s_add_i32 s68, s55, s43
	s_mov_b32 m0, s68
	s_nop 0
	global_load_lds_dwordx4 v130, s[66:67]
	s_add_i32 m0, s68, 0x2000
	s_nop 0
	global_load_lds_dwordx4 v134, s[66:67]
	s_add_u32 s36, s36, 0x40000
	s_addc_u32 s37, s37, 0
	s_mov_b32 m0, s45
	s_nop 0
	global_load_lds_dwordx4 v128, s[36:37]
	s_mov_b32 m0, s46
	s_nop 0
	global_load_lds_dwordx4 v132, s[36:37]
	s_waitcnt vmcnt(10)
	s_setprio 1
	s_barrier
	v_mfma_f32_16x16x32_bf16 v[48:51], v[202:205], v[166:169], v[48:51]
	v_mfma_f32_16x16x32_bf16 v[40:43], v[210:213], v[166:169], v[40:43]
	v_mfma_f32_16x16x32_bf16 v[32:35], v[202:205], v[174:177], v[32:35]
	v_mfma_f32_16x16x32_bf16 v[24:27], v[210:213], v[174:177], v[24:27]
	v_mfma_f32_16x16x32_bf16 v[16:19], v[202:205], v[182:185], v[16:19]
	v_mfma_f32_16x16x32_bf16 v[8:11], v[210:213], v[182:185], v[8:11]
	v_mfma_f32_16x16x32_bf16 v[4:7], v[202:205], v[190:193], v[4:7]
	v_mfma_f32_16x16x32_bf16 v[0:3], v[210:213], v[190:193], v[0:3]
	v_mfma_f32_16x16x32_bf16 v[48:51], v[206:209], v[170:173], v[48:51]
	v_mfma_f32_16x16x32_bf16 v[40:43], v[214:217], v[170:173], v[40:43]
	v_mfma_f32_16x16x32_bf16 v[32:35], v[206:209], v[178:181], v[32:35]
	v_mfma_f32_16x16x32_bf16 v[24:27], v[214:217], v[178:181], v[24:27]
	v_mfma_f32_16x16x32_bf16 v[16:19], v[206:209], v[186:189], v[16:19]
	v_mfma_f32_16x16x32_bf16 v[8:11], v[214:217], v[186:189], v[8:11]
	v_mfma_f32_16x16x32_bf16 v[4:7], v[206:209], v[194:197], v[4:7]
	v_mfma_f32_16x16x32_bf16 v[0:3], v[214:217], v[194:197], v[0:3]
	s_setprio 0
	s_add_i32 s66, 0, 0x18000
	v_add_u32_e32 v162, s66, v146
	s_barrier
	ds_read_b128 v[150:153], v162
	ds_read_b128 v[154:157], v162 offset:1024
	ds_read_b128 v[158:161], v162 offset:2048
	ds_read_b128 v[162:165], v162 offset:3072
	ds_read_b128 v[166:169], v148 offset:32768
	ds_read_b128 v[170:173], v148 offset:33792
	ds_read_b128 v[174:177], v148 offset:34816
	ds_read_b128 v[178:181], v148 offset:35840
	ds_read_b128 v[182:185], v148 offset:36864
	ds_read_b128 v[186:189], v148 offset:37888
	ds_read_b128 v[190:193], v148 offset:38912
	ds_read_b128 v[194:197], v148 offset:39936
	s_waitcnt lgkmcnt(8)
	s_waitcnt vmcnt(8)
	s_setprio 1
	s_barrier
; #define PG8_STAGE(bufoff, gbase, voff) do { _Pragma("unroll") for (int _i = 0; _i < 2; ++_i) \
;         __builtin_amdgcn_global_load_lds((const unsigned*)((const char*)(gbase) + (voff)[_i]), (LAS unsigned*)(lds + (bufoff) + ldsw + _i * 8192), 16, 0, 0); } while (0)
; #define PG8_LDA(dst, b, h) do { _Pragma("unroll") for (int m = 0; m < 4; ++m) _Pragma("unroll") for (int k = 0; k < 2; ++k) dst[m][k] = *(const LAS bf16x8*)(lds + PG8_SA(b, h) + aoff + m * 2048 + k * 1024); } while (0)
; #define PG8_LDB(dst, b, h) do { _Pragma("unroll") for (int n = 0; n < 2; ++n) _Pragma("unroll") for (int k = 0; k < 2; ++k) dst[n][k] = *(const LAS bf16x8*)(lds + PG8_SB(b, h) + boff + n * 2048 + k * 1024); } while (0)
; #define PG8_MMA(ai, bj, At, Bt) do { __builtin_amdgcn_s_setprio(1); _Pragma("unroll") for (int m = 0; m < 4; ++m) _Pragma("unroll") for (int n = 0; n < 2; ++n) _Pragma("unroll") for (int k = 0; k < 2; ++k) \
;         acc[ai][bj][m][n] = __builtin_amdgcn_mfma_f32_16x16x32_bf16(Bt[n][k], At[m][k], acc[ai][bj][m][n], 0, 0, 0); __builtin_amdgcn_s_setprio(0); } while (0)
; #define PG8_WAIT_V(n) asm volatile("s_waitcnt vmcnt(" #n ")" ::: "memory")
; #define PG8_WAIT_L(n) asm volatile("s_waitcnt lgkmcnt(" #n ")" ::: "memory")
; #define PG8_BAR __builtin_amdgcn_s_barrier()
; #define PG8_SCHED __builtin_amdgcn_sched_barrier(0)
; template <class Epi, class Sched>
; __device__ __forceinline__ void gemm_phase(LAS unsigned char* lds, const Gemm g, const Sched& S, const Epi& E) {
;     ...
;             PG8_WAIT_L(8); PG8_BAR; PG8_WAIT_L(0); PG8_MMA(0, 0, At, B0); PG8_BAR; PG8_SCHED;
;             PG8_LDB(B1, 1, 1); PG8_STAGE(PG8_SB(1, 0), b3, voffB);
;             PG8_BAR; PG8_WAIT_L(0); PG8_MMA(0, 1, At, B1); PG8_BAR;
;             PG8_LDA(At, 1, 1); PG8_STAGE(PG8_SA(1, 0), a3, voffA);
;             PG8_BAR; PG8_WAIT_L(0); PG8_MMA(1, 0, At, B0); PG8_BAR; PG8_SCHED;
;             PG8_STAGE(PG8_SB(1, 1), b3 + hstep, voffB);
;             PG8_WAIT_V(6); PG8_BAR; PG8_MMA(1, 1, At, B1); PG8_BAR;
	s_waitcnt lgkmcnt(0)
	v_mfma_f32_16x16x32_bf16 v[124:127], v[150:153], v[166:169], v[124:127]
	v_mfma_f32_16x16x32_bf16 v[120:123], v[158:161], v[166:169], v[120:123]
	v_mfma_f32_16x16x32_bf16 v[116:119], v[150:153], v[174:177], v[116:119]
	v_mfma_f32_16x16x32_bf16 v[108:111], v[158:161], v[174:177], v[108:111]
	v_mfma_f32_16x16x32_bf16 v[100:103], v[150:153], v[182:185], v[100:103]
	v_mfma_f32_16x16x32_bf16 v[92:95], v[158:161], v[182:185], v[92:95]
	v_mfma_f32_16x16x32_bf16 v[84:87], v[150:153], v[190:193], v[84:87]
	v_mfma_f32_16x16x32_bf16 v[76:79], v[158:161], v[190:193], v[76:79]
	v_mfma_f32_16x16x32_bf16 v[124:127], v[154:157], v[170:173], v[124:127]
	v_mfma_f32_16x16x32_bf16 v[120:123], v[162:165], v[170:173], v[120:123]
	v_mfma_f32_16x16x32_bf16 v[116:119], v[154:157], v[178:181], v[116:119]
	v_mfma_f32_16x16x32_bf16 v[108:111], v[162:165], v[178:181], v[108:111]
	v_mfma_f32_16x16x32_bf16 v[100:103], v[154:157], v[186:189], v[100:103]
	v_mfma_f32_16x16x32_bf16 v[92:95], v[162:165], v[186:189], v[92:95]
	v_mfma_f32_16x16x32_bf16 v[84:87], v[154:157], v[194:197], v[84:87]
	v_mfma_f32_16x16x32_bf16 v[76:79], v[162:165], v[194:197], v[76:79]
	s_setprio 0
	s_barrier
	s_add_i32 s36, 0, 0x1c000
	s_add_i32 s37, s66, s43
	v_add_u32_e32 v214, s36, v146
	s_add_u32 s4, s34, 0x80
	s_addc_u32 s5, s35, 0
	s_mov_b32 m0, s37
	ds_read_b128 v[202:205], v214
	ds_read_b128 v[206:209], v214 offset:1024
	ds_read_b128 v[210:213], v214 offset:2048
	ds_read_b128 v[214:217], v214 offset:3072
	global_load_lds_dwordx4 v130, s[4:5]
	s_add_i32 m0, s37, 0x2000
	s_nop 0
	global_load_lds_dwordx4 v134, s[4:5]
	s_waitcnt vmcnt(8)
	s_setprio 1
	s_barrier
	s_waitcnt lgkmcnt(0)
	v_mfma_f32_16x16x32_bf16 v[112:115], v[202:205], v[166:169], v[112:115]
	v_mfma_f32_16x16x32_bf16 v[104:107], v[210:213], v[166:169], v[104:107]
	v_mfma_f32_16x16x32_bf16 v[96:99], v[202:205], v[174:177], v[96:99]
	v_mfma_f32_16x16x32_bf16 v[88:91], v[210:213], v[174:177], v[88:91]
	v_mfma_f32_16x16x32_bf16 v[80:83], v[202:205], v[182:185], v[80:83]
	v_mfma_f32_16x16x32_bf16 v[72:75], v[210:213], v[182:185], v[72:75]
	v_mfma_f32_16x16x32_bf16 v[68:71], v[202:205], v[190:193], v[68:71]
	v_mfma_f32_16x16x32_bf16 v[64:67], v[210:213], v[190:193], v[64:67]
	v_mfma_f32_16x16x32_bf16 v[112:115], v[206:209], v[170:173], v[112:115]
	v_mfma_f32_16x16x32_bf16 v[104:107], v[214:217], v[170:173], v[104:107]
	v_mfma_f32_16x16x32_bf16 v[96:99], v[206:209], v[178:181], v[96:99]
	v_mfma_f32_16x16x32_bf16 v[88:91], v[214:217], v[178:181], v[88:91]
	v_mfma_f32_16x16x32_bf16 v[80:83], v[206:209], v[186:189], v[80:83]
	v_mfma_f32_16x16x32_bf16 v[72:75], v[214:217], v[186:189], v[72:75]
	v_mfma_f32_16x16x32_bf16 v[68:71], v[206:209], v[194:197], v[68:71]
	v_mfma_f32_16x16x32_bf16 v[64:67], v[214:217], v[194:197], v[64:67]
	s_setprio 0
	s_mov_b32 m0, s51
	s_mov_b64 s[4:5], 0x80
	v_lshl_add_u64 v[198:199], v[220:221], 0, s[4:5]
	s_barrier
	ds_read_b128 v[166:169], v148 offset:49152
	ds_read_b128 v[170:173], v148 offset:50176
	ds_read_b128 v[174:177], v148 offset:51200
	ds_read_b128 v[178:181], v148 offset:52224
	ds_read_b128 v[182:185], v148 offset:53248
	ds_read_b128 v[186:189], v148 offset:54272
	ds_read_b128 v[190:193], v148 offset:55296
	ds_read_b128 v[194:197], v148 offset:56320
	global_load_lds_dwordx4 v[198:199], off
	v_lshl_add_u64 v[198:199], v[222:223], 0, s[4:5]
	s_mov_b32 m0, s52
	s_nop 0
	global_load_lds_dwordx4 v[198:199], off
	s_setprio 1
	s_barrier
	s_waitcnt lgkmcnt(0)
	v_mfma_f32_16x16x32_bf16 v[60:63], v[150:153], v[166:169], v[60:63]
	v_mfma_f32_16x16x32_bf16 v[56:59], v[158:161], v[166:169], v[56:59]
	v_mfma_f32_16x16x32_bf16 v[52:55], v[150:153], v[174:177], v[52:55]
	v_mfma_f32_16x16x32_bf16 v[44:47], v[158:161], v[174:177], v[44:47]
	v_mfma_f32_16x16x32_bf16 v[36:39], v[150:153], v[182:185], v[36:39]
	v_mfma_f32_16x16x32_bf16 v[28:31], v[158:161], v[182:185], v[28:31]
	v_mfma_f32_16x16x32_bf16 v[20:23], v[150:153], v[190:193], v[20:23]
	v_mfma_f32_16x16x32_bf16 v[12:15], v[158:161], v[190:193], v[12:15]
	v_mfma_f32_16x16x32_bf16 v[60:63], v[154:157], v[170:173], v[60:63]
	v_mfma_f32_16x16x32_bf16 v[56:59], v[162:165], v[170:173], v[56:59]
	v_mfma_f32_16x16x32_bf16 v[52:55], v[154:157], v[178:181], v[52:55]
	v_mfma_f32_16x16x32_bf16 v[44:47], v[162:165], v[178:181], v[44:47]
	v_mfma_f32_16x16x32_bf16 v[36:39], v[154:157], v[186:189], v[36:39]
	v_mfma_f32_16x16x32_bf16 v[28:31], v[162:165], v[186:189], v[28:31]
	v_mfma_f32_16x16x32_bf16 v[20:23], v[154:157], v[194:197], v[20:23]
	v_mfma_f32_16x16x32_bf16 v[12:15], v[162:165], v[194:197], v[12:15]
	s_setprio 0
	s_barrier
	s_add_u32 s34, s34, 0x40080
	s_addc_u32 s35, s35, 0
	s_add_i32 s36, s36, s43
	s_mov_b32 m0, s36
	s_nop 0
	global_load_lds_dwordx4 v130, s[34:35]
	s_add_i32 m0, s36, 0x2000
	s_nop 0
	global_load_lds_dwordx4 v134, s[34:35]
	s_waitcnt vmcnt(8)
	s_setprio 1
	s_barrier
; __device__ __forceinline__ unsigned cvt_pk_bf16(float lo, float hi) { unsigned r; asm volatile("v_cvt_pk_bf16_f32 %0, %1, %2" : "=v"(r) : "v"(lo), "v"(hi)); return r; }
; #define PG8_MMA(ai, bj, At, Bt) do { __builtin_amdgcn_s_setprio(1); _Pragma("unroll") for (int m = 0; m < 4; ++m) _Pragma("unroll") for (int n = 0; n < 2; ++n) _Pragma("unroll") for (int k = 0; k < 2; ++k) \
;         acc[ai][bj][m][n] = __builtin_amdgcn_mfma_f32_16x16x32_bf16(Bt[n][k], At[m][k], acc[ai][bj][m][n], 0, 0, 0); __builtin_amdgcn_s_setprio(0); } while (0)
; #define PG8_WAIT_V(n) asm volatile("s_waitcnt vmcnt(" #n ")" ::: "memory")
; #define PG8_BAR __builtin_amdgcn_s_barrier()
; template <class Epi, class Sched>
; __device__ __forceinline__ void gemm_phase(LAS unsigned char* lds, const Gemm g, const Sched& S, const Epi& E) {
;     ...
;             PG8_WAIT_V(6); PG8_BAR; PG8_MMA(1, 1, At, B1); PG8_BAR;
;     __device__ __forceinline__ void operator()(const AccT& acc, const Unit& u, int wr, int wc, int fr, int fq) const {
;     ...
;         const int rbase = u.pm * 256 + wr * 64 + fr;
;         const int tb = u.pn * 256 + wc * 32 + 8 * fq;
; #pragma unroll
;         for (int ai = 0; ai < 2; ++ai)
; #pragma unroll
;             for (int m = 0; m < 4; ++m) {
;                 const int r = rbase + ai * 128 + m * 16;
; #pragma unroll
;                 for (int bj = 0; bj < 2; ++bj) {
;                     const int t0 = tb + bj * 128;
;                     const f32x4 v0 = acc[ai][bj][m][0], v1 = acc[ai][bj][m][1];
;                     u32x4 w; w.x = cvt_pk_bf16(v0[0], v0[1]); w.y = cvt_pk_bf16(v0[2], v0[3]); w.z = cvt_pk_bf16(v1[0], v1[1]); w.w = cvt_pk_bf16(v1[2], v1[3]);
;                     *(u32x4*)(VT + (size_t)r * NT + t0) = w;
;                 }
;             }
;     }
	v_mfma_f32_16x16x32_bf16 v[48:51], v[202:205], v[166:169], v[48:51]
	v_mfma_f32_16x16x32_bf16 v[40:43], v[210:213], v[166:169], v[40:43]
	v_mfma_f32_16x16x32_bf16 v[32:35], v[202:205], v[174:177], v[32:35]
	v_mfma_f32_16x16x32_bf16 v[24:27], v[210:213], v[174:177], v[24:27]
	v_mfma_f32_16x16x32_bf16 v[16:19], v[202:205], v[182:185], v[16:19]
	v_mfma_f32_16x16x32_bf16 v[8:11], v[210:213], v[182:185], v[8:11]
	v_mfma_f32_16x16x32_bf16 v[4:7], v[202:205], v[190:193], v[4:7]
	v_mfma_f32_16x16x32_bf16 v[0:3], v[210:213], v[190:193], v[0:3]
	v_mfma_f32_16x16x32_bf16 v[48:51], v[206:209], v[170:173], v[48:51]
	v_mfma_f32_16x16x32_bf16 v[40:43], v[214:217], v[170:173], v[40:43]
	v_mfma_f32_16x16x32_bf16 v[32:35], v[206:209], v[178:181], v[32:35]
	v_mfma_f32_16x16x32_bf16 v[24:27], v[214:217], v[178:181], v[24:27]
	v_mfma_f32_16x16x32_bf16 v[16:19], v[206:209], v[186:189], v[16:19]
	v_mfma_f32_16x16x32_bf16 v[8:11], v[214:217], v[186:189], v[8:11]
	v_mfma_f32_16x16x32_bf16 v[4:7], v[206:209], v[194:197], v[4:7]
	v_mfma_f32_16x16x32_bf16 v[0:3], v[214:217], v[194:197], v[0:3]
	s_setprio 0
	s_add_i32 s65, s65, 2
	s_add_u32 s30, s30, 0x100
	s_addc_u32 s31, s31, 0
	s_add_u32 s63, s63, 0x100
	s_addc_u32 s64, s64, 0
	s_cmp_gt_u32 s65, 13
	s_barrier
	s_cbranch_scc0 .LBB0_633
	v_mov_b32_e32 v150, v144
	v_mov_b32_e32 v151, v145
	s_lshl_b32 s21, s28, 8
	s_add_i32 s21, s21, s48
	v_add_u32_e32 v150, s21, v150
	s_lshl_b32 s21, s60, 8
	s_or_b32 s21, s21, s49
	v_lshl_add_u32 v152, v151, 3, s21
	v_ashrrev_i32_e32 v151, 31, v150
	v_cvt_pk_bf16_f32 v124, v124, v125
	v_cvt_pk_bf16_f32 v125, v126, v127
	v_cvt_pk_bf16_f32 v126, v120, v121
	v_lshlrev_b64 v[120:121], 17, v[150:151]
	v_lshl_add_u64 v[120:121], s[0:1], 0, v[120:121]
	v_ashrrev_i32_e32 v153, 31, v152
	v_lshl_add_u64 v[120:121], v[152:153], 1, v[120:121]
	s_mov_b32 s21, 0x200000
	v_cvt_pk_bf16_f32 v127, v122, v123
	global_store_dwordx4 v[120:121], v[124:127], off
	v_cvt_pk_bf16_f32 v112, v112, v113
	v_cvt_pk_bf16_f32 v113, v114, v115
	v_cvt_pk_bf16_f32 v114, v104, v105
	v_cvt_pk_bf16_f32 v115, v106, v107
	global_store_dwordx4 v[120:121], v[112:115], off offset:256
	v_cvt_pk_bf16_f32 v104, v116, v117
	v_cvt_pk_bf16_f32 v105, v118, v119
	v_cvt_pk_bf16_f32 v106, v108, v109
	v_cvt_pk_bf16_f32 v107, v110, v111
	s_mov_b64 s[30:31], 0x200000
	v_add_co_u32_e32 v110, vcc, s21, v120
	v_lshl_add_u64 v[108:109], v[120:121], 0, s[30:31]
	s_nop 0
	v_addc_co_u32_e32 v111, vcc, 0, v121, vcc
	s_mov_b32 s21, 0x400000
	global_store_dwordx4 v[110:111], v[104:107], off
	v_cvt_pk_bf16_f32 v96, v96, v97
	v_cvt_pk_bf16_f32 v97, v98, v99
	v_cvt_pk_bf16_f32 v98, v88, v89
	v_cvt_pk_bf16_f32 v99, v90, v91
	global_store_dwordx4 v[108:109], v[96:99], off offset:256
	v_cvt_pk_bf16_f32 v88, v100, v101
	v_cvt_pk_bf16_f32 v89, v102, v103
	v_cvt_pk_bf16_f32 v90, v92, v93
	v_cvt_pk_bf16_f32 v91, v94, v95
	s_mov_b64 s[30:31], 0x400000
	v_add_co_u32_e32 v94, vcc, s21, v120
	v_lshl_add_u64 v[92:93], v[120:121], 0, s[30:31]
	s_nop 0
	v_addc_co_u32_e32 v95, vcc, 0, v121, vcc
	s_mov_b32 s21, 0x600000
	global_store_dwordx4 v[94:95], v[88:91], off
	v_cvt_pk_bf16_f32 v80, v80, v81
	v_cvt_pk_bf16_f32 v81, v82, v83
	v_cvt_pk_bf16_f32 v82, v72, v73
	v_cvt_pk_bf16_f32 v83, v74, v75
	global_store_dwordx4 v[92:93], v[80:83], off offset:256
	v_cvt_pk_bf16_f32 v72, v84, v85
	v_cvt_pk_bf16_f32 v73, v86, v87
	v_cvt_pk_bf16_f32 v74, v76, v77
	v_cvt_pk_bf16_f32 v75, v78, v79
	s_mov_b64 s[30:31], 0x600000
	v_add_co_u32_e32 v78, vcc, s21, v120
	v_lshl_add_u64 v[76:77], v[120:121], 0, s[30:31]
	s_nop 0
	v_addc_co_u32_e32 v79, vcc, 0, v121, vcc
	global_store_dwordx4 v[78:79], v[72:75], off
	v_cvt_pk_bf16_f32 v68, v68, v69
	v_cvt_pk_bf16_f32 v69, v70, v71
	v_cvt_pk_bf16_f32 v70, v64, v65
	v_cvt_pk_bf16_f32 v71, v66, v67
	global_store_dwordx4 v[76:77], v[68:71], off offset:256
	v_cvt_pk_bf16_f32 v60, v60, v61
	v_cvt_pk_bf16_f32 v61, v62, v63
	v_cvt_pk_bf16_f32 v62, v56, v57
	v_cvt_pk_bf16_f32 v63, v58, v59
	s_mov_b64 s[30:31], 0x1000000
	v_add_co_u32_e32 v58, vcc, s56, v120
	v_lshl_add_u64 v[56:57], v[120:121], 0, s[30:31]
	s_nop 0
	v_addc_co_u32_e32 v59, vcc, 0, v121, vcc
	global_store_dwordx4 v[58:59], v[60:63], off
	v_cvt_pk_bf16_f32 v48, v48, v49
	v_cvt_pk_bf16_f32 v49, v50, v51
	v_cvt_pk_bf16_f32 v50, v40, v41
	v_cvt_pk_bf16_f32 v51, v42, v43
	global_store_dwordx4 v[56:57], v[48:51], off offset:256
	v_cvt_pk_bf16_f32 v40, v52, v53
	v_cvt_pk_bf16_f32 v41, v54, v55
	v_cvt_pk_bf16_f32 v42, v44, v45
	v_cvt_pk_bf16_f32 v43, v46, v47
	v_add_co_u32_e32 v46, vcc, s57, v120
	v_lshl_add_u64 v[44:45], v[120:121], 0, s[6:7]
	s_nop 0
	v_addc_co_u32_e32 v47, vcc, 0, v121, vcc
	global_store_dwordx4 v[46:47], v[40:43], off
	v_cvt_pk_bf16_f32 v32, v32, v33
	v_cvt_pk_bf16_f32 v33, v34, v35
	v_cvt_pk_bf16_f32 v34, v24, v25
	v_cvt_pk_bf16_f32 v35, v26, v27
	global_store_dwordx4 v[44:45], v[32:35], off offset:256
	v_cvt_pk_bf16_f32 v24, v36, v37
	v_cvt_pk_bf16_f32 v25, v38, v39
	v_cvt_pk_bf16_f32 v26, v28, v29
	v_cvt_pk_bf16_f32 v27, v30, v31
	v_add_co_u32_e32 v30, vcc, s58, v120
	v_lshl_add_u64 v[28:29], v[120:121], 0, s[8:9]
	s_nop 0
	v_addc_co_u32_e32 v31, vcc, 0, v121, vcc
	global_store_dwordx4 v[30:31], v[24:27], off
	v_cvt_pk_bf16_f32 v16, v16, v17
	v_cvt_pk_bf16_f32 v17, v18, v19
	v_cvt_pk_bf16_f32 v18, v8, v9
	v_cvt_pk_bf16_f32 v19, v10, v11
	global_store_dwordx4 v[28:29], v[16:19], off offset:256
	v_cvt_pk_bf16_f32 v8, v20, v21
	v_cvt_pk_bf16_f32 v9, v22, v23
	v_cvt_pk_bf16_f32 v10, v12, v13
	v_cvt_pk_bf16_f32 v11, v14, v15
	v_add_co_u32_e32 v14, vcc, s59, v120
	v_lshl_add_u64 v[12:13], v[120:121], 0, s[16:17]
	s_nop 0
	v_addc_co_u32_e32 v15, vcc, 0, v121, vcc
	s_and_b64 vcc, exec, s[2:3]
	s_mov_b32 s60, s20
	s_mov_b32 s28, s22
	s_mov_b64 s[34:35], s[26:27]
	s_mov_b64 s[30:31], s[24:25]
	global_store_dwordx4 v[14:15], v[8:11], off
	v_cvt_pk_bf16_f32 v4, v4, v5
	v_cvt_pk_bf16_f32 v5, v6, v7
	v_cvt_pk_bf16_f32 v6, v0, v1
	v_cvt_pk_bf16_f32 v7, v2, v3
	global_store_dwordx4 v[12:13], v[4:7], off offset:256
	s_cbranch_vccz .LBB0_626
	s_waitcnt vmcnt(0)
	s_cmpk_gt_u32 s33, 0xff
	s_cbranch_scc1 .LBB0_637
	s_barrier

; #define PG8_STAGE(bufoff, gbase, voff) do { _Pragma("unroll") for (int _i = 0; _i < 2; ++_i) \
;         __builtin_amdgcn_global_load_lds((const unsigned*)((const char*)(gbase) + (voff)[_i]), (LAS unsigned*)(lds + (bufoff) + ldsw + _i * 8192), 16, 0, 0); } while (0)
; #define PG8_LDA(dst, b, h) do { _Pragma("unroll") for (int m = 0; m < 4; ++m) _Pragma("unroll") for (int k = 0; k < 2; ++k) dst[m][k] = *(const LAS bf16x8*)(lds + PG8_SA(b, h) + aoff + m * 2048 + k * 1024); } while (0)
; #define PG8_LDB(dst, b, h) do { _Pragma("unroll") for (int n = 0; n < 2; ++n) _Pragma("unroll") for (int k = 0; k < 2; ++k) dst[n][k] = *(const LAS bf16x8*)(lds + PG8_SB(b, h) + boff + n * 2048 + k * 1024); } while (0)
; #define PG8_MMA(ai, bj, At, Bt) do { __builtin_amdgcn_s_setprio(1); _Pragma("unroll") for (int m = 0; m < 4; ++m) _Pragma("unroll") for (int n = 0; n < 2; ++n) _Pragma("unroll") for (int k = 0; k < 2; ++k) \
;         acc[ai][bj][m][n] = __builtin_amdgcn_mfma_f32_16x16x32_bf16(Bt[n][k], At[m][k], acc[ai][bj][m][n], 0, 0, 0); __builtin_amdgcn_s_setprio(0); } while (0)
; #define PG8_WAIT_L(n) asm volatile("s_waitcnt lgkmcnt(" #n ")" ::: "memory")
; template <class Epi, class Sched>
; __device__ __forceinline__ void gemm_phase(LAS unsigned char* lds, const Gemm g, const Sched& S, const Epi& E) {
;     ...
;         const bool has_next = S.next(ui + 1, nxt);
;         const char* nA = has_next ? (const char*)g.A + (size_t)nxt.pm * tstep : cA; const char* nB = has_next ? (const char*)g.Bt + (size_t)nxt.pn * tstep : cB;
;         for (int t = 0; t < nt; t += 2) {
;             const bool last = (t == nt - 2);
;             const char* a1 = cA + (size_t)(t + 1) * kstep;
;             const char* a2 = last ? nA : cA + (size_t)(t + 2) * kstep; const char* b2 = last ? nB : cB + (size_t)(t + 2) * kstep;
;             const char* a3 = a2 + kstep; const char* b3 = b2 + kstep;
;             PG8_LDB(B0, 0, 0); PG8_SCHED; PG8_LDA(At, 0, 0); PG8_STAGE(PG8_SA(1, 1), a1 + hstep, voffA);
;             PG8_WAIT_L(8); PG8_BAR; PG8_WAIT_L(0); PG8_MMA(0, 0, At, B0); PG8_BAR; PG8_SCHED;
;             PG8_LDB(B1, 0, 1); PG8_STAGE(PG8_SB(0, 0), b2, voffB);
;             PG8_BAR; PG8_WAIT_L(0); PG8_MMA(0, 1, At, B1); PG8_BAR;
;             PG8_LDA(At, 0, 1); PG8_STAGE(PG8_SA(0, 0), a2, voffA);
;             PG8_BAR; PG8_WAIT_L(0); PG8_MMA(1, 0, At, B0); PG8_BAR; PG8_SCHED;
.LBB0_652:
	s_ashr_i32 s9, s8, 31
	v_cmp_lt_i64_e32 vcc, s[16:17], v[142:143]
	s_lshl_b64 s[16:17], s[8:9], 19
	s_add_u32 s16, s14, s16
	s_addc_u32 s17, s15, s17
	s_and_b64 s[18:19], vcc, exec
	s_cselect_b32 s9, s17, s23
	s_cselect_b32 s48, s16, s22
	s_ashr_i32 s7, s6, 31
	s_lshl_b64 s[18:19], s[6:7], 19
	s_add_u32 s18, s12, s18
	s_addc_u32 s19, s13, s19
	s_and_b64 s[26:27], vcc, exec
	s_cselect_b32 s7, s19, s25
	s_cselect_b32 s49, s18, s24
	s_add_u32 s22, s22, 0x40080
	s_addc_u32 s23, s23, 0
	s_add_u32 s51, s24, 0x100
	s_addc_u32 s52, s25, 0
	s_mov_b32 s53, -2
	s_waitcnt lgkmcnt(0)
	ds_read_b128 v[152:155], v149
	ds_read_b128 v[156:159], v149 offset:1024
	ds_read_b128 v[160:163], v149 offset:2048
	ds_read_b128 v[164:167], v149 offset:3072
	s_add_u32 s24, s22, 0xfffc0080
	s_addc_u32 s25, s23, -1
	s_cmp_eq_u32 s53, 12
	s_cselect_b32 s27, s9, s25
	s_cselect_b32 s26, s48, s24
	s_cselect_b32 s25, s7, s52
	s_cselect_b32 s24, s49, s51
	s_add_i32 m0, s21, 0xc000
	ds_read_b128 v[168:171], v150
	ds_read_b128 v[172:175], v150 offset:1024
	ds_read_b128 v[176:179], v150 offset:2048
	ds_read_b128 v[180:183], v150 offset:3072
	ds_read_b128 v[184:187], v150 offset:4096
	ds_read_b128 v[188:191], v150 offset:5120
	ds_read_b128 v[192:195], v150 offset:6144
	ds_read_b128 v[196:199], v150 offset:7168
	global_load_lds_dwordx4 v138, s[22:23]
	s_add_i32 m0, s21, 0xe000
	s_nop 0
	global_load_lds_dwordx4 v140, s[22:23]
	s_waitcnt lgkmcnt(8)
	s_waitcnt vmcnt(8)
	s_setprio 1
	s_barrier
	s_waitcnt lgkmcnt(0)
	v_mfma_f32_16x16x32_bf16 v[124:127], v[152:155], v[168:171], 0
	v_mfma_f32_16x16x32_bf16 v[120:123], v[160:163], v[168:171], 0
	v_mfma_f32_16x16x32_bf16 v[112:115], v[152:155], v[176:179], 0
	v_mfma_f32_16x16x32_bf16 v[104:107], v[160:163], v[176:179], 0
	v_mfma_f32_16x16x32_bf16 v[96:99], v[152:155], v[184:187], 0
	v_mfma_f32_16x16x32_bf16 v[88:91], v[160:163], v[184:187], 0
	v_mfma_f32_16x16x32_bf16 v[80:83], v[152:155], v[192:195], 0
	v_mfma_f32_16x16x32_bf16 v[72:75], v[160:163], v[192:195], 0
	v_mfma_f32_16x16x32_bf16 v[124:127], v[156:159], v[172:175], v[124:127]
	v_mfma_f32_16x16x32_bf16 v[120:123], v[164:167], v[172:175], v[120:123]
	v_mfma_f32_16x16x32_bf16 v[112:115], v[156:159], v[180:183], v[112:115]
	v_mfma_f32_16x16x32_bf16 v[104:107], v[164:167], v[180:183], v[104:107]
	v_mfma_f32_16x16x32_bf16 v[96:99], v[156:159], v[188:191], v[96:99]
	v_mfma_f32_16x16x32_bf16 v[88:91], v[164:167], v[188:191], v[88:91]
	v_mfma_f32_16x16x32_bf16 v[80:83], v[156:159], v[196:199], v[80:83]
	v_mfma_f32_16x16x32_bf16 v[72:75], v[164:167], v[196:199], v[72:75]
	s_setprio 0
	s_barrier
	s_add_i32 s54, s45, s30
	s_mov_b32 m0, s54
	ds_read_b128 v[202:205], v151
	ds_read_b128 v[206:209], v151 offset:1024
	ds_read_b128 v[210:213], v151 offset:2048
	ds_read_b128 v[214:217], v151 offset:3072
	global_load_lds_dwordx4 v130, s[24:25]
	s_add_i32 m0, s54, 0x2000
	s_nop 0
	global_load_lds_dwordx4 v134, s[24:25]
	s_waitcnt vmcnt(8)
	s_setprio 1
	s_barrier
	s_waitcnt lgkmcnt(0)
	v_mfma_f32_16x16x32_bf16 v[116:119], v[202:205], v[168:171], 0
	v_mfma_f32_16x16x32_bf16 v[108:111], v[210:213], v[168:171], 0
	v_mfma_f32_16x16x32_bf16 v[100:103], v[202:205], v[176:179], 0
	v_mfma_f32_16x16x32_bf16 v[92:95], v[210:213], v[176:179], 0
	v_mfma_f32_16x16x32_bf16 v[84:87], v[202:205], v[184:187], 0
	v_mfma_f32_16x16x32_bf16 v[76:79], v[210:213], v[184:187], 0
	v_mfma_f32_16x16x32_bf16 v[68:71], v[202:205], v[192:195], 0
	v_mfma_f32_16x16x32_bf16 v[64:67], v[210:213], v[192:195], 0
	v_mfma_f32_16x16x32_bf16 v[116:119], v[206:209], v[172:175], v[116:119]
	v_mfma_f32_16x16x32_bf16 v[108:111], v[214:217], v[172:175], v[108:111]
	v_mfma_f32_16x16x32_bf16 v[100:103], v[206:209], v[180:183], v[100:103]
	v_mfma_f32_16x16x32_bf16 v[92:95], v[214:217], v[180:183], v[92:95]
	v_mfma_f32_16x16x32_bf16 v[84:87], v[206:209], v[188:191], v[84:87]
	v_mfma_f32_16x16x32_bf16 v[76:79], v[214:217], v[188:191], v[76:79]
	v_mfma_f32_16x16x32_bf16 v[68:71], v[206:209], v[196:199], v[68:71]
	v_mfma_f32_16x16x32_bf16 v[64:67], v[214:217], v[196:199], v[64:67]
	s_setprio 0
	s_mov_b32 m0, s21
	v_lshl_add_u64 v[222:223], s[26:27], 0, v[128:129]
	s_barrier
	ds_read_b128 v[168:171], v150 offset:16384
	ds_read_b128 v[172:175], v150 offset:17408
	ds_read_b128 v[176:179], v150 offset:18432
	ds_read_b128 v[180:183], v150 offset:19456
	ds_read_b128 v[184:187], v150 offset:20480
	ds_read_b128 v[188:191], v150 offset:21504
	ds_read_b128 v[192:195], v150 offset:22528
	ds_read_b128 v[196:199], v150 offset:23552
	global_load_lds_dwordx4 v128, s[26:27]
	v_lshl_add_u64 v[224:225], s[26:27], 0, v[132:133]
	s_mov_b32 m0, s31
	s_nop 0
	global_load_lds_dwordx4 v132, s[26:27]
	s_setprio 1
	s_barrier
	s_waitcnt lgkmcnt(0)
	v_mfma_f32_16x16x32_bf16 v[60:63], v[152:155], v[168:171], 0
	v_mfma_f32_16x16x32_bf16 v[56:59], v[160:163], v[168:171], 0
	v_mfma_f32_16x16x32_bf16 v[48:51], v[152:155], v[176:179], 0
	v_mfma_f32_16x16x32_bf16 v[40:43], v[160:163], v[176:179], 0
	v_mfma_f32_16x16x32_bf16 v[32:35], v[152:155], v[184:187], 0
	v_mfma_f32_16x16x32_bf16 v[24:27], v[160:163], v[184:187], 0
	v_mfma_f32_16x16x32_bf16 v[16:19], v[152:155], v[192:195], 0
	v_mfma_f32_16x16x32_bf16 v[8:11], v[160:163], v[192:195], 0
	v_mfma_f32_16x16x32_bf16 v[60:63], v[156:159], v[172:175], v[60:63]
	v_mfma_f32_16x16x32_bf16 v[56:59], v[164:167], v[172:175], v[56:59]
	v_mfma_f32_16x16x32_bf16 v[48:51], v[156:159], v[180:183], v[48:51]
	v_mfma_f32_16x16x32_bf16 v[40:43], v[164:167], v[180:183], v[40:43]
	v_mfma_f32_16x16x32_bf16 v[32:35], v[156:159], v[188:191], v[32:35]
	v_mfma_f32_16x16x32_bf16 v[24:27], v[164:167], v[188:191], v[24:27]
	v_mfma_f32_16x16x32_bf16 v[16:19], v[156:159], v[196:199], v[16:19]
	v_mfma_f32_16x16x32_bf16 v[8:11], v[164:167], v[196:199], v[8:11]
	s_setprio 0
	s_barrier
; #define PG8_STAGE(bufoff, gbase, voff) do { _Pragma("unroll") for (int _i = 0; _i < 2; ++_i) \
;         __builtin_amdgcn_global_load_lds((const unsigned*)((const char*)(gbase) + (voff)[_i]), (LAS unsigned*)(lds + (bufoff) + ldsw + _i * 8192), 16, 0, 0); } while (0)
; #define PG8_LDA(dst, b, h) do { _Pragma("unroll") for (int m = 0; m < 4; ++m) _Pragma("unroll") for (int k = 0; k < 2; ++k) dst[m][k] = *(const LAS bf16x8*)(lds + PG8_SA(b, h) + aoff + m * 2048 + k * 1024); } while (0)
; #define PG8_LDB(dst, b, h) do { _Pragma("unroll") for (int n = 0; n < 2; ++n) _Pragma("unroll") for (int k = 0; k < 2; ++k) dst[n][k] = *(const LAS bf16x8*)(lds + PG8_SB(b, h) + boff + n * 2048 + k * 1024); } while (0)
; #define PG8_MMA(ai, bj, At, Bt) do { __builtin_amdgcn_s_setprio(1); _Pragma("unroll") for (int m = 0; m < 4; ++m) _Pragma("unroll") for (int n = 0; n < 2; ++n) _Pragma("unroll") for (int k = 0; k < 2; ++k) \
;         acc[ai][bj][m][n] = __builtin_amdgcn_mfma_f32_16x16x32_bf16(Bt[n][k], At[m][k], acc[ai][bj][m][n], 0, 0, 0); __builtin_amdgcn_s_setprio(0); } while (0)
; #define PG8_WAIT_V(n) asm volatile("s_waitcnt vmcnt(" #n ")" ::: "memory")
; #define PG8_WAIT_L(n) asm volatile("s_waitcnt lgkmcnt(" #n ")" ::: "memory")
; #define PG8_BAR __builtin_amdgcn_s_barrier()
; #define PG8_SCHED __builtin_amdgcn_sched_barrier(0)
; template <class Epi, class Sched>
; __device__ __forceinline__ void gemm_phase(LAS unsigned char* lds, const Gemm g, const Sched& S, const Epi& E) {
;     ...
;             PG8_WAIT_V(6); PG8_BAR; PG8_MMA(1, 1, At, B1); PG8_BAR;
;             PG8_LDB(B0, 1, 0); PG8_SCHED; PG8_LDA(At, 1, 0); PG8_STAGE(PG8_SA(0, 1), a2 + hstep, voffA);
;             PG8_WAIT_L(8); PG8_BAR; PG8_WAIT_L(0); PG8_MMA(0, 0, At, B0); PG8_BAR; PG8_SCHED;
;             PG8_LDB(B1, 1, 1); PG8_STAGE(PG8_SB(1, 0), b3, voffB);
;             PG8_BAR; PG8_WAIT_L(0); PG8_MMA(0, 1, At, B1); PG8_BAR;
;             PG8_LDA(At, 1, 1); PG8_STAGE(PG8_SA(1, 0), a3, voffA);
;             PG8_BAR; PG8_WAIT_L(0); PG8_MMA(1, 0, At, B0); PG8_BAR; PG8_SCHED;
	s_add_u32 s54, s24, 0x40000
	s_addc_u32 s55, s25, 0
	s_add_i32 s56, s46, s30
	s_mov_b32 m0, s56
	s_nop 0
	global_load_lds_dwordx4 v130, s[54:55]
	s_add_i32 m0, s56, 0x2000
	s_nop 0
	global_load_lds_dwordx4 v134, s[54:55]
	s_add_u32 s26, s26, 0x40000
	s_addc_u32 s27, s27, 0
	s_mov_b32 m0, s33
	s_nop 0
	global_load_lds_dwordx4 v128, s[26:27]
	s_mov_b32 m0, s34
	s_nop 0
	global_load_lds_dwordx4 v132, s[26:27]
	s_waitcnt vmcnt(10)
	s_setprio 1
	s_barrier
	v_mfma_f32_16x16x32_bf16 v[52:55], v[202:205], v[168:171], 0
	v_mfma_f32_16x16x32_bf16 v[44:47], v[210:213], v[168:171], 0
	v_mfma_f32_16x16x32_bf16 v[36:39], v[202:205], v[176:179], 0
	v_mfma_f32_16x16x32_bf16 v[28:31], v[210:213], v[176:179], 0
	v_mfma_f32_16x16x32_bf16 v[20:23], v[202:205], v[184:187], 0
	v_mfma_f32_16x16x32_bf16 v[12:15], v[210:213], v[184:187], 0
	v_mfma_f32_16x16x32_bf16 v[4:7], v[202:205], v[192:195], 0
	v_mfma_f32_16x16x32_bf16 v[0:3], v[210:213], v[192:195], 0
	v_mfma_f32_16x16x32_bf16 v[52:55], v[206:209], v[172:175], v[52:55]
	v_mfma_f32_16x16x32_bf16 v[44:47], v[214:217], v[172:175], v[44:47]
	v_mfma_f32_16x16x32_bf16 v[36:39], v[206:209], v[180:183], v[36:39]
	v_mfma_f32_16x16x32_bf16 v[28:31], v[214:217], v[180:183], v[28:31]
	v_mfma_f32_16x16x32_bf16 v[20:23], v[206:209], v[188:191], v[20:23]
	v_mfma_f32_16x16x32_bf16 v[12:15], v[214:217], v[188:191], v[12:15]
	v_mfma_f32_16x16x32_bf16 v[4:7], v[206:209], v[196:199], v[4:7]
	v_mfma_f32_16x16x32_bf16 v[0:3], v[214:217], v[196:199], v[0:3]
	s_setprio 0
	s_add_i32 s54, 0, 0x18000
	v_add_u32_e32 v136, s54, v148
	s_barrier
	ds_read_b128 v[152:155], v136
	ds_read_b128 v[156:159], v136 offset:1024
	ds_read_b128 v[160:163], v136 offset:2048
	ds_read_b128 v[164:167], v136 offset:3072
	ds_read_b128 v[168:171], v150 offset:32768
	ds_read_b128 v[172:175], v150 offset:33792
	ds_read_b128 v[176:179], v150 offset:34816
	ds_read_b128 v[180:183], v150 offset:35840
	ds_read_b128 v[184:187], v150 offset:36864
	ds_read_b128 v[188:191], v150 offset:37888
	ds_read_b128 v[192:195], v150 offset:38912
	ds_read_b128 v[196:199], v150 offset:39936
	s_waitcnt lgkmcnt(8)
	s_waitcnt vmcnt(8)
	s_setprio 1
	s_barrier
	s_waitcnt lgkmcnt(0)
	v_mfma_f32_16x16x32_bf16 v[124:127], v[152:155], v[168:171], v[124:127]
	v_mfma_f32_16x16x32_bf16 v[120:123], v[160:163], v[168:171], v[120:123]
	v_mfma_f32_16x16x32_bf16 v[112:115], v[152:155], v[176:179], v[112:115]
	v_mfma_f32_16x16x32_bf16 v[104:107], v[160:163], v[176:179], v[104:107]
	v_mfma_f32_16x16x32_bf16 v[96:99], v[152:155], v[184:187], v[96:99]
	v_mfma_f32_16x16x32_bf16 v[88:91], v[160:163], v[184:187], v[88:91]
	v_mfma_f32_16x16x32_bf16 v[80:83], v[152:155], v[192:195], v[80:83]
	v_mfma_f32_16x16x32_bf16 v[72:75], v[160:163], v[192:195], v[72:75]
	v_mfma_f32_16x16x32_bf16 v[124:127], v[156:159], v[172:175], v[124:127]
	v_mfma_f32_16x16x32_bf16 v[120:123], v[164:167], v[172:175], v[120:123]
	v_mfma_f32_16x16x32_bf16 v[112:115], v[156:159], v[180:183], v[112:115]
	v_mfma_f32_16x16x32_bf16 v[104:107], v[164:167], v[180:183], v[104:107]
	v_mfma_f32_16x16x32_bf16 v[96:99], v[156:159], v[188:191], v[96:99]
	v_mfma_f32_16x16x32_bf16 v[88:91], v[164:167], v[188:191], v[88:91]
	v_mfma_f32_16x16x32_bf16 v[80:83], v[156:159], v[196:199], v[80:83]
	v_mfma_f32_16x16x32_bf16 v[72:75], v[164:167], v[196:199], v[72:75]
	s_setprio 0
	s_barrier
	s_add_i32 s26, 0, 0x1c000
	s_add_i32 s27, s54, s30
	v_add_u32_e32 v136, s26, v148
	s_add_u32 s0, s24, 0x80
	s_addc_u32 s1, s25, 0
	s_mov_b32 m0, s27
	ds_read_b128 v[202:205], v136
	ds_read_b128 v[206:209], v136 offset:1024
	ds_read_b128 v[210:213], v136 offset:2048
	ds_read_b128 v[214:217], v136 offset:3072
	global_load_lds_dwordx4 v130, s[0:1]
	s_add_i32 m0, s27, 0x2000
	s_nop 0
	global_load_lds_dwordx4 v134, s[0:1]
	s_waitcnt vmcnt(8)
	s_setprio 1
	s_barrier
	s_waitcnt lgkmcnt(0)
	v_mfma_f32_16x16x32_bf16 v[116:119], v[202:205], v[168:171], v[116:119]
	v_mfma_f32_16x16x32_bf16 v[108:111], v[210:213], v[168:171], v[108:111]
	v_mfma_f32_16x16x32_bf16 v[100:103], v[202:205], v[176:179], v[100:103]
	v_mfma_f32_16x16x32_bf16 v[92:95], v[210:213], v[176:179], v[92:95]
	v_mfma_f32_16x16x32_bf16 v[84:87], v[202:205], v[184:187], v[84:87]
	v_mfma_f32_16x16x32_bf16 v[76:79], v[210:213], v[184:187], v[76:79]
	v_mfma_f32_16x16x32_bf16 v[68:71], v[202:205], v[192:195], v[68:71]
	v_mfma_f32_16x16x32_bf16 v[64:67], v[210:213], v[192:195], v[64:67]
	v_mfma_f32_16x16x32_bf16 v[116:119], v[206:209], v[172:175], v[116:119]
	v_mfma_f32_16x16x32_bf16 v[108:111], v[214:217], v[172:175], v[108:111]
	v_mfma_f32_16x16x32_bf16 v[100:103], v[206:209], v[180:183], v[100:103]
	v_mfma_f32_16x16x32_bf16 v[92:95], v[214:217], v[180:183], v[92:95]
	v_mfma_f32_16x16x32_bf16 v[84:87], v[206:209], v[188:191], v[84:87]
	v_mfma_f32_16x16x32_bf16 v[76:79], v[214:217], v[188:191], v[76:79]
	v_mfma_f32_16x16x32_bf16 v[68:71], v[206:209], v[196:199], v[68:71]
	v_mfma_f32_16x16x32_bf16 v[64:67], v[214:217], v[196:199], v[64:67]
	s_setprio 0
	s_mov_b32 m0, s42
	s_mov_b64 s[0:1], 0x80
	v_lshl_add_u64 v[218:219], v[222:223], 0, s[0:1]
	s_barrier
	ds_read_b128 v[168:171], v150 offset:49152
	ds_read_b128 v[172:175], v150 offset:50176
	ds_read_b128 v[176:179], v150 offset:51200
	ds_read_b128 v[180:183], v150 offset:52224
	ds_read_b128 v[184:187], v150 offset:53248
	ds_read_b128 v[188:191], v150 offset:54272
	ds_read_b128 v[192:195], v150 offset:55296
	ds_read_b128 v[196:199], v150 offset:56320
	global_load_lds_dwordx4 v[218:219], off
	v_lshl_add_u64 v[218:219], v[224:225], 0, s[0:1]
	s_mov_b32 m0, s43
	s_nop 0
	global_load_lds_dwordx4 v[218:219], off
	s_setprio 1
	s_barrier
; #define PG8_STAGE(bufoff, gbase, voff) do { _Pragma("unroll") for (int _i = 0; _i < 2; ++_i) \
;         __builtin_amdgcn_global_load_lds((const unsigned*)((const char*)(gbase) + (voff)[_i]), (LAS unsigned*)(lds + (bufoff) + ldsw + _i * 8192), 16, 0, 0); } while (0)
; #define PG8_LDA(dst, b, h) do { _Pragma("unroll") for (int m = 0; m < 4; ++m) _Pragma("unroll") for (int k = 0; k < 2; ++k) dst[m][k] = *(const LAS bf16x8*)(lds + PG8_SA(b, h) + aoff + m * 2048 + k * 1024); } while (0)
; #define PG8_LDB(dst, b, h) do { _Pragma("unroll") for (int n = 0; n < 2; ++n) _Pragma("unroll") for (int k = 0; k < 2; ++k) dst[n][k] = *(const LAS bf16x8*)(lds + PG8_SB(b, h) + boff + n * 2048 + k * 1024); } while (0)
; #define PG8_MMA(ai, bj, At, Bt) do { __builtin_amdgcn_s_setprio(1); _Pragma("unroll") for (int m = 0; m < 4; ++m) _Pragma("unroll") for (int n = 0; n < 2; ++n) _Pragma("unroll") for (int k = 0; k < 2; ++k) \
;         acc[ai][bj][m][n] = __builtin_amdgcn_mfma_f32_16x16x32_bf16(Bt[n][k], At[m][k], acc[ai][bj][m][n], 0, 0, 0); __builtin_amdgcn_s_setprio(0); } while (0)
; #define PG8_WAIT_V(n) asm volatile("s_waitcnt vmcnt(" #n ")" ::: "memory")
; #define PG8_WAIT_L(n) asm volatile("s_waitcnt lgkmcnt(" #n ")" ::: "memory")
; #define PG8_BAR __builtin_amdgcn_s_barrier()
; #define PG8_SCHED __builtin_amdgcn_sched_barrier(0)
; template <class Epi, class Sched>
; __device__ __forceinline__ void gemm_phase(LAS unsigned char* lds, const Gemm g, const Sched& S, const Epi& E) {
;     ...
;         for (int t = 0; t < nt; t += 2) {
;             const bool last = (t == nt - 2);
;             const char* a1 = cA + (size_t)(t + 1) * kstep;
;             const char* a2 = last ? nA : cA + (size_t)(t + 2) * kstep; const char* b2 = last ? nB : cB + (size_t)(t + 2) * kstep;
;             const char* a3 = a2 + kstep; const char* b3 = b2 + kstep;
;             PG8_LDB(B0, 0, 0); PG8_SCHED; PG8_LDA(At, 0, 0); PG8_STAGE(PG8_SA(1, 1), a1 + hstep, voffA);
;             PG8_WAIT_L(8); PG8_BAR; PG8_WAIT_L(0); PG8_MMA(0, 0, At, B0); PG8_BAR; PG8_SCHED;
;             PG8_LDB(B1, 0, 1); PG8_STAGE(PG8_SB(0, 0), b2, voffB);
;             PG8_BAR; PG8_WAIT_L(0); PG8_MMA(0, 1, At, B1); PG8_BAR;
;     ...
;             PG8_BAR; PG8_WAIT_L(0); PG8_MMA(1, 0, At, B0); PG8_BAR; PG8_SCHED;
;             PG8_STAGE(PG8_SB(1, 1), b3 + hstep, voffB);
;             PG8_WAIT_V(6); PG8_BAR; PG8_MMA(1, 1, At, B1); PG8_BAR;
	s_waitcnt lgkmcnt(0)
	v_mfma_f32_16x16x32_bf16 v[60:63], v[152:155], v[168:171], v[60:63]
	v_mfma_f32_16x16x32_bf16 v[56:59], v[160:163], v[168:171], v[56:59]
	v_mfma_f32_16x16x32_bf16 v[48:51], v[152:155], v[176:179], v[48:51]
	v_mfma_f32_16x16x32_bf16 v[40:43], v[160:163], v[176:179], v[40:43]
	v_mfma_f32_16x16x32_bf16 v[32:35], v[152:155], v[184:187], v[32:35]
	v_mfma_f32_16x16x32_bf16 v[24:27], v[160:163], v[184:187], v[24:27]
	v_mfma_f32_16x16x32_bf16 v[16:19], v[152:155], v[192:195], v[16:19]
	v_mfma_f32_16x16x32_bf16 v[8:11], v[160:163], v[192:195], v[8:11]
	v_mfma_f32_16x16x32_bf16 v[60:63], v[156:159], v[172:175], v[60:63]
	v_mfma_f32_16x16x32_bf16 v[56:59], v[164:167], v[172:175], v[56:59]
	v_mfma_f32_16x16x32_bf16 v[48:51], v[156:159], v[180:183], v[48:51]
	v_mfma_f32_16x16x32_bf16 v[40:43], v[164:167], v[180:183], v[40:43]
	v_mfma_f32_16x16x32_bf16 v[32:35], v[156:159], v[188:191], v[32:35]
	v_mfma_f32_16x16x32_bf16 v[24:27], v[164:167], v[188:191], v[24:27]
	v_mfma_f32_16x16x32_bf16 v[16:19], v[156:159], v[196:199], v[16:19]
	v_mfma_f32_16x16x32_bf16 v[8:11], v[164:167], v[196:199], v[8:11]
	s_setprio 0
	s_barrier
	s_add_u32 s24, s24, 0x40080
	s_addc_u32 s25, s25, 0
	s_add_i32 s26, s26, s30
	s_mov_b32 m0, s26
	s_nop 0
	global_load_lds_dwordx4 v130, s[24:25]
	s_add_i32 m0, s26, 0x2000
	s_nop 0
	global_load_lds_dwordx4 v134, s[24:25]
	s_waitcnt vmcnt(8)
	s_setprio 1
	s_barrier
	v_mfma_f32_16x16x32_bf16 v[52:55], v[202:205], v[168:171], v[52:55]
	v_mfma_f32_16x16x32_bf16 v[44:47], v[210:213], v[168:171], v[44:47]
	v_mfma_f32_16x16x32_bf16 v[36:39], v[202:205], v[176:179], v[36:39]
	v_mfma_f32_16x16x32_bf16 v[28:31], v[210:213], v[176:179], v[28:31]
	v_mfma_f32_16x16x32_bf16 v[20:23], v[202:205], v[184:187], v[20:23]
	v_mfma_f32_16x16x32_bf16 v[12:15], v[210:213], v[184:187], v[12:15]
	v_mfma_f32_16x16x32_bf16 v[4:7], v[202:205], v[192:195], v[4:7]
	v_mfma_f32_16x16x32_bf16 v[0:3], v[210:213], v[192:195], v[0:3]
	v_mfma_f32_16x16x32_bf16 v[52:55], v[206:209], v[172:175], v[52:55]
	v_mfma_f32_16x16x32_bf16 v[44:47], v[214:217], v[172:175], v[44:47]
	v_mfma_f32_16x16x32_bf16 v[36:39], v[206:209], v[180:183], v[36:39]
	v_mfma_f32_16x16x32_bf16 v[28:31], v[214:217], v[180:183], v[28:31]
	v_mfma_f32_16x16x32_bf16 v[20:23], v[206:209], v[188:191], v[20:23]
	v_mfma_f32_16x16x32_bf16 v[12:15], v[214:217], v[188:191], v[12:15]
	v_mfma_f32_16x16x32_bf16 v[4:7], v[206:209], v[196:199], v[4:7]
	v_mfma_f32_16x16x32_bf16 v[0:3], v[214:217], v[196:199], v[0:3]
	s_setprio 0
	s_add_i32 s53, s53, 2
	s_add_u32 s22, s22, 0x100
	s_addc_u32 s23, s23, 0
	s_add_u32 s51, s51, 0x100
	s_addc_u32 s52, s52, 0
	s_cmp_gt_u32 s53, 13
	s_barrier
.LBB0_653:
	ds_read_b128 v[152:155], v149
	ds_read_b128 v[156:159], v149 offset:1024
	ds_read_b128 v[160:163], v149 offset:2048
	ds_read_b128 v[164:167], v149 offset:3072
	s_add_u32 s24, s22, 0xfffc0080
	s_addc_u32 s25, s23, -1
	s_cmp_eq_u32 s53, 12
	s_cselect_b32 s27, s9, s25
	s_cselect_b32 s26, s48, s24
	s_cselect_b32 s25, s7, s52
	s_cselect_b32 s24, s49, s51
	s_add_i32 m0, s21, 0xc000
	ds_read_b128 v[168:171], v150
	ds_read_b128 v[172:175], v150 offset:1024
	ds_read_b128 v[176:179], v150 offset:2048
	ds_read_b128 v[180:183], v150 offset:3072
	ds_read_b128 v[184:187], v150 offset:4096
	ds_read_b128 v[188:191], v150 offset:5120
	ds_read_b128 v[192:195], v150 offset:6144
	ds_read_b128 v[196:199], v150 offset:7168
	global_load_lds_dwordx4 v138, s[22:23]
	s_add_i32 m0, s21, 0xe000
	s_nop 0
	global_load_lds_dwordx4 v140, s[22:23]
	s_waitcnt lgkmcnt(8)
	s_waitcnt vmcnt(8)
	s_setprio 1
	s_barrier
	s_waitcnt lgkmcnt(0)
	v_mfma_f32_16x16x32_bf16 v[124:127], v[152:155], v[168:171], v[124:127]
	v_mfma_f32_16x16x32_bf16 v[120:123], v[160:163], v[168:171], v[120:123]
	v_mfma_f32_16x16x32_bf16 v[112:115], v[152:155], v[176:179], v[112:115]
	v_mfma_f32_16x16x32_bf16 v[104:107], v[160:163], v[176:179], v[104:107]
	v_mfma_f32_16x16x32_bf16 v[96:99], v[152:155], v[184:187], v[96:99]
	v_mfma_f32_16x16x32_bf16 v[88:91], v[160:163], v[184:187], v[88:91]
	v_mfma_f32_16x16x32_bf16 v[80:83], v[152:155], v[192:195], v[80:83]
	v_mfma_f32_16x16x32_bf16 v[72:75], v[160:163], v[192:195], v[72:75]
	v_mfma_f32_16x16x32_bf16 v[124:127], v[156:159], v[172:175], v[124:127]
	v_mfma_f32_16x16x32_bf16 v[120:123], v[164:167], v[172:175], v[120:123]
	v_mfma_f32_16x16x32_bf16 v[112:115], v[156:159], v[180:183], v[112:115]
	v_mfma_f32_16x16x32_bf16 v[104:107], v[164:167], v[180:183], v[104:107]
	v_mfma_f32_16x16x32_bf16 v[96:99], v[156:159], v[188:191], v[96:99]
	v_mfma_f32_16x16x32_bf16 v[88:91], v[164:167], v[188:191], v[88:91]
	v_mfma_f32_16x16x32_bf16 v[80:83], v[156:159], v[196:199], v[80:83]
	v_mfma_f32_16x16x32_bf16 v[72:75], v[164:167], v[196:199], v[72:75]
	s_setprio 0
	s_barrier
	s_add_i32 s54, s45, s30
	s_mov_b32 m0, s54
	ds_read_b128 v[202:205], v151
	ds_read_b128 v[206:209], v151 offset:1024
	ds_read_b128 v[210:213], v151 offset:2048
	ds_read_b128 v[214:217], v151 offset:3072
	global_load_lds_dwordx4 v130, s[24:25]
	s_add_i32 m0, s54, 0x2000
	s_nop 0
	global_load_lds_dwordx4 v134, s[24:25]
	s_waitcnt vmcnt(8)
	s_setprio 1
	s_barrier
; #define PG8_STAGE(bufoff, gbase, voff) do { _Pragma("unroll") for (int _i = 0; _i < 2; ++_i) \
;         __builtin_amdgcn_global_load_lds((const unsigned*)((const char*)(gbase) + (voff)[_i]), (LAS unsigned*)(lds + (bufoff) + ldsw + _i * 8192), 16, 0, 0); } while (0)
; #define PG8_LDA(dst, b, h) do { _Pragma("unroll") for (int m = 0; m < 4; ++m) _Pragma("unroll") for (int k = 0; k < 2; ++k) dst[m][k] = *(const LAS bf16x8*)(lds + PG8_SA(b, h) + aoff + m * 2048 + k * 1024); } while (0)
; #define PG8_LDB(dst, b, h) do { _Pragma("unroll") for (int n = 0; n < 2; ++n) _Pragma("unroll") for (int k = 0; k < 2; ++k) dst[n][k] = *(const LAS bf16x8*)(lds + PG8_SB(b, h) + boff + n * 2048 + k * 1024); } while (0)
; #define PG8_MMA(ai, bj, At, Bt) do { __builtin_amdgcn_s_setprio(1); _Pragma("unroll") for (int m = 0; m < 4; ++m) _Pragma("unroll") for (int n = 0; n < 2; ++n) _Pragma("unroll") for (int k = 0; k < 2; ++k) \
;         acc[ai][bj][m][n] = __builtin_amdgcn_mfma_f32_16x16x32_bf16(Bt[n][k], At[m][k], acc[ai][bj][m][n], 0, 0, 0); __builtin_amdgcn_s_setprio(0); } while (0)
; #define PG8_WAIT_V(n) asm volatile("s_waitcnt vmcnt(" #n ")" ::: "memory")
; #define PG8_WAIT_L(n) asm volatile("s_waitcnt lgkmcnt(" #n ")" ::: "memory")
; #define PG8_BAR __builtin_amdgcn_s_barrier()
; #define PG8_SCHED __builtin_amdgcn_sched_barrier(0)
; template <class Epi, class Sched>
; __device__ __forceinline__ void gemm_phase(LAS unsigned char* lds, const Gemm g, const Sched& S, const Epi& E) {
;     ...
;             PG8_LDA(At, 0, 1); PG8_STAGE(PG8_SA(0, 0), a2, voffA);
;             PG8_BAR; PG8_WAIT_L(0); PG8_MMA(1, 0, At, B0); PG8_BAR; PG8_SCHED;
;             PG8_STAGE(PG8_SB(0, 1), b2 + hstep, voffB);
;             PG8_WAIT_V(6); PG8_BAR; PG8_MMA(1, 1, At, B1); PG8_BAR;
;             PG8_LDB(B0, 1, 0); PG8_SCHED; PG8_LDA(At, 1, 0); PG8_STAGE(PG8_SA(0, 1), a2 + hstep, voffA);
;             PG8_WAIT_L(8); PG8_BAR; PG8_WAIT_L(0); PG8_MMA(0, 0, At, B0); PG8_BAR; PG8_SCHED;
;             PG8_LDB(B1, 1, 1); PG8_STAGE(PG8_SB(1, 0), b3, voffB);
;             PG8_BAR; PG8_WAIT_L(0); PG8_MMA(0, 1, At, B1); PG8_BAR;
	s_waitcnt lgkmcnt(0)
	v_mfma_f32_16x16x32_bf16 v[116:119], v[202:205], v[168:171], v[116:119]
	v_mfma_f32_16x16x32_bf16 v[108:111], v[210:213], v[168:171], v[108:111]
	v_mfma_f32_16x16x32_bf16 v[100:103], v[202:205], v[176:179], v[100:103]
	v_mfma_f32_16x16x32_bf16 v[92:95], v[210:213], v[176:179], v[92:95]
	v_mfma_f32_16x16x32_bf16 v[84:87], v[202:205], v[184:187], v[84:87]
	v_mfma_f32_16x16x32_bf16 v[76:79], v[210:213], v[184:187], v[76:79]
	v_mfma_f32_16x16x32_bf16 v[68:71], v[202:205], v[192:195], v[68:71]
	v_mfma_f32_16x16x32_bf16 v[64:67], v[210:213], v[192:195], v[64:67]
	v_mfma_f32_16x16x32_bf16 v[116:119], v[206:209], v[172:175], v[116:119]
	v_mfma_f32_16x16x32_bf16 v[108:111], v[214:217], v[172:175], v[108:111]
	v_mfma_f32_16x16x32_bf16 v[100:103], v[206:209], v[180:183], v[100:103]
	v_mfma_f32_16x16x32_bf16 v[92:95], v[214:217], v[180:183], v[92:95]
	v_mfma_f32_16x16x32_bf16 v[84:87], v[206:209], v[188:191], v[84:87]
	v_mfma_f32_16x16x32_bf16 v[76:79], v[214:217], v[188:191], v[76:79]
	v_mfma_f32_16x16x32_bf16 v[68:71], v[206:209], v[196:199], v[68:71]
	v_mfma_f32_16x16x32_bf16 v[64:67], v[214:217], v[196:199], v[64:67]
	s_setprio 0
	s_mov_b32 m0, s21
	v_lshl_add_u64 v[222:223], s[26:27], 0, v[128:129]
	s_barrier
	ds_read_b128 v[168:171], v150 offset:16384
	ds_read_b128 v[172:175], v150 offset:17408
	ds_read_b128 v[176:179], v150 offset:18432
	ds_read_b128 v[180:183], v150 offset:19456
	ds_read_b128 v[184:187], v150 offset:20480
	ds_read_b128 v[188:191], v150 offset:21504
	ds_read_b128 v[192:195], v150 offset:22528
	ds_read_b128 v[196:199], v150 offset:23552
	global_load_lds_dwordx4 v128, s[26:27]
	v_lshl_add_u64 v[224:225], s[26:27], 0, v[132:133]
	s_mov_b32 m0, s31
	s_nop 0
	global_load_lds_dwordx4 v132, s[26:27]
	s_setprio 1
	s_barrier
	s_waitcnt lgkmcnt(0)
	v_mfma_f32_16x16x32_bf16 v[60:63], v[152:155], v[168:171], v[60:63]
	v_mfma_f32_16x16x32_bf16 v[56:59], v[160:163], v[168:171], v[56:59]
	v_mfma_f32_16x16x32_bf16 v[48:51], v[152:155], v[176:179], v[48:51]
	v_mfma_f32_16x16x32_bf16 v[40:43], v[160:163], v[176:179], v[40:43]
	v_mfma_f32_16x16x32_bf16 v[32:35], v[152:155], v[184:187], v[32:35]
	v_mfma_f32_16x16x32_bf16 v[24:27], v[160:163], v[184:187], v[24:27]
	v_mfma_f32_16x16x32_bf16 v[16:19], v[152:155], v[192:195], v[16:19]
	v_mfma_f32_16x16x32_bf16 v[8:11], v[160:163], v[192:195], v[8:11]
	v_mfma_f32_16x16x32_bf16 v[60:63], v[156:159], v[172:175], v[60:63]
	v_mfma_f32_16x16x32_bf16 v[56:59], v[164:167], v[172:175], v[56:59]
	v_mfma_f32_16x16x32_bf16 v[48:51], v[156:159], v[180:183], v[48:51]
	v_mfma_f32_16x16x32_bf16 v[40:43], v[164:167], v[180:183], v[40:43]
	v_mfma_f32_16x16x32_bf16 v[32:35], v[156:159], v[188:191], v[32:35]
	v_mfma_f32_16x16x32_bf16 v[24:27], v[164:167], v[188:191], v[24:27]
	v_mfma_f32_16x16x32_bf16 v[16:19], v[156:159], v[196:199], v[16:19]
	v_mfma_f32_16x16x32_bf16 v[8:11], v[164:167], v[196:199], v[8:11]
	s_setprio 0
	s_barrier
	s_add_u32 s54, s24, 0x40000
	s_addc_u32 s55, s25, 0
	s_add_i32 s56, s46, s30
	s_mov_b32 m0, s56
	s_nop 0
	global_load_lds_dwordx4 v130, s[54:55]
	s_add_i32 m0, s56, 0x2000
	s_nop 0
	global_load_lds_dwordx4 v134, s[54:55]
	s_add_u32 s26, s26, 0x40000
	s_addc_u32 s27, s27, 0
	s_mov_b32 m0, s33
	s_nop 0
	global_load_lds_dwordx4 v128, s[26:27]
	s_mov_b32 m0, s34
	s_nop 0
	global_load_lds_dwordx4 v132, s[26:27]
	s_waitcnt vmcnt(10)
	s_setprio 1
	s_barrier
	v_mfma_f32_16x16x32_bf16 v[52:55], v[202:205], v[168:171], v[52:55]
	v_mfma_f32_16x16x32_bf16 v[44:47], v[210:213], v[168:171], v[44:47]
	v_mfma_f32_16x16x32_bf16 v[36:39], v[202:205], v[176:179], v[36:39]
	v_mfma_f32_16x16x32_bf16 v[28:31], v[210:213], v[176:179], v[28:31]
	v_mfma_f32_16x16x32_bf16 v[20:23], v[202:205], v[184:187], v[20:23]
	v_mfma_f32_16x16x32_bf16 v[12:15], v[210:213], v[184:187], v[12:15]
	v_mfma_f32_16x16x32_bf16 v[4:7], v[202:205], v[192:195], v[4:7]
	v_mfma_f32_16x16x32_bf16 v[0:3], v[210:213], v[192:195], v[0:3]
	v_mfma_f32_16x16x32_bf16 v[52:55], v[206:209], v[172:175], v[52:55]
	v_mfma_f32_16x16x32_bf16 v[44:47], v[214:217], v[172:175], v[44:47]
	v_mfma_f32_16x16x32_bf16 v[36:39], v[206:209], v[180:183], v[36:39]
	v_mfma_f32_16x16x32_bf16 v[28:31], v[214:217], v[180:183], v[28:31]
	v_mfma_f32_16x16x32_bf16 v[20:23], v[206:209], v[188:191], v[20:23]
	v_mfma_f32_16x16x32_bf16 v[12:15], v[214:217], v[188:191], v[12:15]
	v_mfma_f32_16x16x32_bf16 v[4:7], v[206:209], v[196:199], v[4:7]
	v_mfma_f32_16x16x32_bf16 v[0:3], v[214:217], v[196:199], v[0:3]
	s_setprio 0
	s_add_i32 s54, 0, 0x18000
	v_add_u32_e32 v136, s54, v148
	s_barrier
	ds_read_b128 v[152:155], v136
	ds_read_b128 v[156:159], v136 offset:1024
	ds_read_b128 v[160:163], v136 offset:2048
	ds_read_b128 v[164:167], v136 offset:3072
	ds_read_b128 v[168:171], v150 offset:32768
	ds_read_b128 v[172:175], v150 offset:33792
	ds_read_b128 v[176:179], v150 offset:34816
	ds_read_b128 v[180:183], v150 offset:35840
	ds_read_b128 v[184:187], v150 offset:36864
	ds_read_b128 v[188:191], v150 offset:37888
	ds_read_b128 v[192:195], v150 offset:38912
	ds_read_b128 v[196:199], v150 offset:39936
	s_waitcnt lgkmcnt(8)
	s_waitcnt vmcnt(8)
	s_setprio 1
	s_barrier
; #define PG8_STAGE(bufoff, gbase, voff) do { _Pragma("unroll") for (int _i = 0; _i < 2; ++_i) \
;         __builtin_amdgcn_global_load_lds((const unsigned*)((const char*)(gbase) + (voff)[_i]), (LAS unsigned*)(lds + (bufoff) + ldsw + _i * 8192), 16, 0, 0); } while (0)
; #define PG8_LDA(dst, b, h) do { _Pragma("unroll") for (int m = 0; m < 4; ++m) _Pragma("unroll") for (int k = 0; k < 2; ++k) dst[m][k] = *(const LAS bf16x8*)(lds + PG8_SA(b, h) + aoff + m * 2048 + k * 1024); } while (0)
; #define PG8_LDB(dst, b, h) do { _Pragma("unroll") for (int n = 0; n < 2; ++n) _Pragma("unroll") for (int k = 0; k < 2; ++k) dst[n][k] = *(const LAS bf16x8*)(lds + PG8_SB(b, h) + boff + n * 2048 + k * 1024); } while (0)
; #define PG8_MMA(ai, bj, At, Bt) do { __builtin_amdgcn_s_setprio(1); _Pragma("unroll") for (int m = 0; m < 4; ++m) _Pragma("unroll") for (int n = 0; n < 2; ++n) _Pragma("unroll") for (int k = 0; k < 2; ++k) \
;         acc[ai][bj][m][n] = __builtin_amdgcn_mfma_f32_16x16x32_bf16(Bt[n][k], At[m][k], acc[ai][bj][m][n], 0, 0, 0); __builtin_amdgcn_s_setprio(0); } while (0)
; #define PG8_WAIT_V(n) asm volatile("s_waitcnt vmcnt(" #n ")" ::: "memory")
; #define PG8_WAIT_L(n) asm volatile("s_waitcnt lgkmcnt(" #n ")" ::: "memory")
; #define PG8_BAR __builtin_amdgcn_s_barrier()
; #define PG8_SCHED __builtin_amdgcn_sched_barrier(0)
; template <class Epi, class Sched>
; __device__ __forceinline__ void gemm_phase(LAS unsigned char* lds, const Gemm g, const Sched& S, const Epi& E) {
;     ...
;             PG8_WAIT_L(8); PG8_BAR; PG8_WAIT_L(0); PG8_MMA(0, 0, At, B0); PG8_BAR; PG8_SCHED;
;             PG8_LDB(B1, 1, 1); PG8_STAGE(PG8_SB(1, 0), b3, voffB);
;             PG8_BAR; PG8_WAIT_L(0); PG8_MMA(0, 1, At, B1); PG8_BAR;
;             PG8_LDA(At, 1, 1); PG8_STAGE(PG8_SA(1, 0), a3, voffA);
;             PG8_BAR; PG8_WAIT_L(0); PG8_MMA(1, 0, At, B0); PG8_BAR; PG8_SCHED;
;             PG8_STAGE(PG8_SB(1, 1), b3 + hstep, voffB);
;             PG8_WAIT_V(6); PG8_BAR; PG8_MMA(1, 1, At, B1); PG8_BAR;
	s_waitcnt lgkmcnt(0)
	v_mfma_f32_16x16x32_bf16 v[124:127], v[152:155], v[168:171], v[124:127]
	v_mfma_f32_16x16x32_bf16 v[120:123], v[160:163], v[168:171], v[120:123]
	v_mfma_f32_16x16x32_bf16 v[112:115], v[152:155], v[176:179], v[112:115]
	v_mfma_f32_16x16x32_bf16 v[104:107], v[160:163], v[176:179], v[104:107]
	v_mfma_f32_16x16x32_bf16 v[96:99], v[152:155], v[184:187], v[96:99]
	v_mfma_f32_16x16x32_bf16 v[88:91], v[160:163], v[184:187], v[88:91]
	v_mfma_f32_16x16x32_bf16 v[80:83], v[152:155], v[192:195], v[80:83]
	v_mfma_f32_16x16x32_bf16 v[72:75], v[160:163], v[192:195], v[72:75]
	v_mfma_f32_16x16x32_bf16 v[124:127], v[156:159], v[172:175], v[124:127]
	v_mfma_f32_16x16x32_bf16 v[120:123], v[164:167], v[172:175], v[120:123]
	v_mfma_f32_16x16x32_bf16 v[112:115], v[156:159], v[180:183], v[112:115]
	v_mfma_f32_16x16x32_bf16 v[104:107], v[164:167], v[180:183], v[104:107]
	v_mfma_f32_16x16x32_bf16 v[96:99], v[156:159], v[188:191], v[96:99]
	v_mfma_f32_16x16x32_bf16 v[88:91], v[164:167], v[188:191], v[88:91]
	v_mfma_f32_16x16x32_bf16 v[80:83], v[156:159], v[196:199], v[80:83]
	v_mfma_f32_16x16x32_bf16 v[72:75], v[164:167], v[196:199], v[72:75]
	s_setprio 0
	s_barrier
	s_add_i32 s26, 0, 0x1c000
	s_add_i32 s27, s54, s30
	v_add_u32_e32 v136, s26, v148
	s_add_u32 s0, s24, 0x80
	s_addc_u32 s1, s25, 0
	s_mov_b32 m0, s27
	ds_read_b128 v[202:205], v136
	ds_read_b128 v[206:209], v136 offset:1024
	ds_read_b128 v[210:213], v136 offset:2048
	ds_read_b128 v[214:217], v136 offset:3072
	global_load_lds_dwordx4 v130, s[0:1]
	s_add_i32 m0, s27, 0x2000
	s_nop 0
	global_load_lds_dwordx4 v134, s[0:1]
	s_waitcnt vmcnt(8)
	s_setprio 1
	s_barrier
	s_waitcnt lgkmcnt(0)
	v_mfma_f32_16x16x32_bf16 v[116:119], v[202:205], v[168:171], v[116:119]
	v_mfma_f32_16x16x32_bf16 v[108:111], v[210:213], v[168:171], v[108:111]
	v_mfma_f32_16x16x32_bf16 v[100:103], v[202:205], v[176:179], v[100:103]
	v_mfma_f32_16x16x32_bf16 v[92:95], v[210:213], v[176:179], v[92:95]
	v_mfma_f32_16x16x32_bf16 v[84:87], v[202:205], v[184:187], v[84:87]
	v_mfma_f32_16x16x32_bf16 v[76:79], v[210:213], v[184:187], v[76:79]
	v_mfma_f32_16x16x32_bf16 v[68:71], v[202:205], v[192:195], v[68:71]
	v_mfma_f32_16x16x32_bf16 v[64:67], v[210:213], v[192:195], v[64:67]
	v_mfma_f32_16x16x32_bf16 v[116:119], v[206:209], v[172:175], v[116:119]
	v_mfma_f32_16x16x32_bf16 v[108:111], v[214:217], v[172:175], v[108:111]
	v_mfma_f32_16x16x32_bf16 v[100:103], v[206:209], v[180:183], v[100:103]
	v_mfma_f32_16x16x32_bf16 v[92:95], v[214:217], v[180:183], v[92:95]
	v_mfma_f32_16x16x32_bf16 v[84:87], v[206:209], v[188:191], v[84:87]
	v_mfma_f32_16x16x32_bf16 v[76:79], v[214:217], v[188:191], v[76:79]
	v_mfma_f32_16x16x32_bf16 v[68:71], v[206:209], v[196:199], v[68:71]
	v_mfma_f32_16x16x32_bf16 v[64:67], v[214:217], v[196:199], v[64:67]
	s_setprio 0
	s_mov_b32 m0, s42
	s_mov_b64 s[0:1], 0x80
	v_lshl_add_u64 v[218:219], v[222:223], 0, s[0:1]
	s_barrier
	ds_read_b128 v[168:171], v150 offset:49152
	ds_read_b128 v[172:175], v150 offset:50176
	ds_read_b128 v[176:179], v150 offset:51200
	ds_read_b128 v[180:183], v150 offset:52224
	ds_read_b128 v[184:187], v150 offset:53248
	ds_read_b128 v[188:191], v150 offset:54272
	ds_read_b128 v[192:195], v150 offset:55296
	ds_read_b128 v[196:199], v150 offset:56320
	global_load_lds_dwordx4 v[218:219], off
	v_lshl_add_u64 v[218:219], v[224:225], 0, s[0:1]
	s_mov_b32 m0, s43
	s_nop 0
	global_load_lds_dwordx4 v[218:219], off
	s_setprio 1
	s_barrier
	s_waitcnt lgkmcnt(0)
	v_mfma_f32_16x16x32_bf16 v[60:63], v[152:155], v[168:171], v[60:63]
	v_mfma_f32_16x16x32_bf16 v[56:59], v[160:163], v[168:171], v[56:59]
	v_mfma_f32_16x16x32_bf16 v[48:51], v[152:155], v[176:179], v[48:51]
	v_mfma_f32_16x16x32_bf16 v[40:43], v[160:163], v[176:179], v[40:43]
	v_mfma_f32_16x16x32_bf16 v[32:35], v[152:155], v[184:187], v[32:35]
	v_mfma_f32_16x16x32_bf16 v[24:27], v[160:163], v[184:187], v[24:27]
	v_mfma_f32_16x16x32_bf16 v[16:19], v[152:155], v[192:195], v[16:19]
	v_mfma_f32_16x16x32_bf16 v[8:11], v[160:163], v[192:195], v[8:11]
	v_mfma_f32_16x16x32_bf16 v[60:63], v[156:159], v[172:175], v[60:63]
	v_mfma_f32_16x16x32_bf16 v[56:59], v[164:167], v[172:175], v[56:59]
	v_mfma_f32_16x16x32_bf16 v[48:51], v[156:159], v[180:183], v[48:51]
	v_mfma_f32_16x16x32_bf16 v[40:43], v[164:167], v[180:183], v[40:43]
	v_mfma_f32_16x16x32_bf16 v[32:35], v[156:159], v[188:191], v[32:35]
	v_mfma_f32_16x16x32_bf16 v[24:27], v[164:167], v[188:191], v[24:27]
	v_mfma_f32_16x16x32_bf16 v[16:19], v[156:159], v[196:199], v[16:19]
	v_mfma_f32_16x16x32_bf16 v[8:11], v[164:167], v[196:199], v[8:11]
	s_setprio 0
	s_barrier
	s_add_u32 s24, s24, 0x40080
	s_addc_u32 s25, s25, 0
	s_add_i32 s26, s26, s30
	s_mov_b32 m0, s26
	s_nop 0
	global_load_lds_dwordx4 v130, s[24:25]
	s_add_i32 m0, s26, 0x2000
	s_nop 0
	global_load_lds_dwordx4 v134, s[24:25]
	s_waitcnt vmcnt(8)
	s_setprio 1
	s_barrier
	v_mfma_f32_16x16x32_bf16 v[52:55], v[202:205], v[168:171], v[52:55]
	v_mfma_f32_16x16x32_bf16 v[44:47], v[210:213], v[168:171], v[44:47]
	v_mfma_f32_16x16x32_bf16 v[36:39], v[202:205], v[176:179], v[36:39]
	v_mfma_f32_16x16x32_bf16 v[28:31], v[210:213], v[176:179], v[28:31]
	v_mfma_f32_16x16x32_bf16 v[20:23], v[202:205], v[184:187], v[20:23]
	v_mfma_f32_16x16x32_bf16 v[12:15], v[210:213], v[184:187], v[12:15]
	v_mfma_f32_16x16x32_bf16 v[4:7], v[202:205], v[192:195], v[4:7]
	v_mfma_f32_16x16x32_bf16 v[0:3], v[210:213], v[192:195], v[0:3]
	v_mfma_f32_16x16x32_bf16 v[52:55], v[206:209], v[172:175], v[52:55]
	v_mfma_f32_16x16x32_bf16 v[44:47], v[214:217], v[172:175], v[44:47]
	v_mfma_f32_16x16x32_bf16 v[36:39], v[206:209], v[180:183], v[36:39]
	v_mfma_f32_16x16x32_bf16 v[28:31], v[214:217], v[180:183], v[28:31]
	v_mfma_f32_16x16x32_bf16 v[20:23], v[206:209], v[188:191], v[20:23]
	v_mfma_f32_16x16x32_bf16 v[12:15], v[214:217], v[188:191], v[12:15]
	v_mfma_f32_16x16x32_bf16 v[4:7], v[206:209], v[196:199], v[4:7]
	v_mfma_f32_16x16x32_bf16 v[0:3], v[214:217], v[196:199], v[0:3]
	s_setprio 0
	s_add_i32 s53, s53, 2
	s_add_u32 s22, s22, 0x100
	s_addc_u32 s23, s23, 0
	s_add_u32 s51, s51, 0x100
	s_addc_u32 s52, s52, 0
	s_cmp_gt_u32 s53, 13
	s_barrier
; __device__ __forceinline__ unsigned cvt_pk_bf16(float lo, float hi) { unsigned r; asm volatile("v_cvt_pk_bf16_f32 %0, %1, %2" : "=v"(r) : "v"(lo), "v"(hi)); return r; }
;     __device__ __forceinline__ void operator()(const AccT& acc, const Unit& u, int wr, int wc, int fr, int fq) const {
;     ...
;         const int rbase = u.pm * 256 + wr * 64 + fr;
;         const int tb = u.pn * 256 + wc * 32 + 8 * fq;
; #pragma unroll
;         for (int ai = 0; ai < 2; ++ai)
; #pragma unroll
;             for (int m = 0; m < 4; ++m) {
;                 const int gm = rbase + ai * 128 + m * 16;
; #pragma unroll
;                 for (int bj = 0; bj < 2; ++bj) {
;                     const int t0 = tb + bj * 128;
;                     const f32x4 v0 = acc[ai][bj][m][0], v1 = acc[ai][bj][m][1];
;                     u32x4 w; w.x = cvt_pk_bf16(v0[0], v0[1]); w.y = cvt_pk_bf16(v0[2], v0[3]); w.z = cvt_pk_bf16(v1[0], v1[1]); w.w = cvt_pk_bf16(v1[2], v1[3]);
;                     *(u32x4*)(YT + ((size_t)((t0 >> 10) * 512 + gm)) * 2048 + part * 1024 + (t0 & 1023)) = w;
;                 }
;             }
	s_cbranch_scc0 .LBB0_653
	v_mov_b32_e32 v136, v147
	v_mov_b32_e32 v152, v146
	s_lshl_b32 s7, s20, 8
	s_add_i32 s7, s7, s36
	v_add_u32_e32 v152, s7, v152
	s_lshl_b32 s7, s47, 8
	s_or_b32 s7, s7, s37
	v_lshl_add_u32 v153, v136, 3, s7
	v_cvt_pk_bf16_f32 v124, v124, v125
	v_cvt_pk_bf16_f32 v125, v126, v127
	v_cvt_pk_bf16_f32 v126, v120, v121
	v_ashrrev_i32_e32 v120, 1, v153
	v_cvt_pk_bf16_f32 v127, v122, v123
	v_and_b32_e32 v122, 0xfffffe00, v120
	v_add_u32_e32 v120, v122, v152
	v_ashrrev_i32_e32 v121, 31, v120
	v_lshlrev_b64 v[120:121], 12, v[120:121]
	v_and_b32_e32 v123, 0x3f8, v153
	v_lshl_add_u64 v[120:121], s[68:69], 0, v[120:121]
	v_lshlrev_b32_e32 v136, 1, v123
	v_lshl_add_u64 v[120:121], v[120:121], 0, v[136:137]
	global_store_dwordx4 v[120:121], v[124:127], off
	v_add_u32_e32 v120, 0x80, v153
	v_cvt_pk_bf16_f32 v116, v116, v117
	v_cvt_pk_bf16_f32 v117, v118, v119
	v_cvt_pk_bf16_f32 v118, v108, v109
	v_ashrrev_i32_e32 v108, 1, v120
	v_and_b32_e32 v121, 0xfffffe00, v108
	v_add_u32_e32 v108, v121, v152
	v_ashrrev_i32_e32 v109, 31, v108
	v_lshlrev_b64 v[108:109], 12, v[108:109]
	v_cvt_pk_bf16_f32 v119, v110, v111
	v_lshl_add_u64 v[110:111], s[68:69], 0, v[108:109]
	v_and_b32_e32 v108, 0x3f8, v120
	v_lshlrev_b32_e32 v108, 1, v108
	v_mov_b32_e32 v109, v137
	v_lshl_add_u64 v[110:111], v[110:111], 0, v[108:109]
	global_store_dwordx4 v[110:111], v[116:119], off
	v_cvt_pk_bf16_f32 v110, v112, v113
	v_cvt_pk_bf16_f32 v111, v114, v115
	v_cvt_pk_bf16_f32 v112, v104, v105
	v_cvt_pk_bf16_f32 v113, v106, v107
	s_and_b64 vcc, exec, s[4:5]
	s_nop 0
	v_add_u32_e32 v116, 16, v152
	v_add_u32_e32 v104, v122, v116
	v_ashrrev_i32_e32 v105, 31, v104
	v_lshlrev_b64 v[104:105], 12, v[104:105]
	v_lshl_add_u64 v[104:105], s[68:69], 0, v[104:105]
	v_lshl_add_u64 v[104:105], v[104:105], 0, v[136:137]
	global_store_dwordx4 v[104:105], v[110:113], off
	v_cvt_pk_bf16_f32 v100, v100, v101
	v_cvt_pk_bf16_f32 v101, v102, v103
	v_cvt_pk_bf16_f32 v102, v92, v93
	v_add_u32_e32 v92, v121, v116
	v_ashrrev_i32_e32 v93, 31, v92
	v_lshlrev_b64 v[92:93], 12, v[92:93]
	v_lshl_add_u64 v[92:93], s[68:69], 0, v[92:93]
	v_lshl_add_u64 v[92:93], v[92:93], 0, v[108:109]
	v_cvt_pk_bf16_f32 v103, v94, v95
	global_store_dwordx4 v[92:93], v[100:103], off
	v_cvt_pk_bf16_f32 v92, v96, v97
	v_cvt_pk_bf16_f32 v93, v98, v99
	v_cvt_pk_bf16_f32 v94, v88, v89
	v_cvt_pk_bf16_f32 v95, v90, v91
	s_mov_b32 s47, s6
	s_nop 0
	v_add_u32_e32 v100, 32, v152
	v_add_u32_e32 v88, v122, v100
	v_ashrrev_i32_e32 v89, 31, v88
	v_lshlrev_b64 v[88:89], 12, v[88:89]
	v_lshl_add_u64 v[88:89], s[68:69], 0, v[88:89]
	v_lshl_add_u64 v[88:89], v[88:89], 0, v[136:137]
	global_store_dwordx4 v[88:89], v[92:95], off
	v_cvt_pk_bf16_f32 v84, v84, v85
	v_cvt_pk_bf16_f32 v85, v86, v87
	v_cvt_pk_bf16_f32 v86, v76, v77
	v_add_u32_e32 v76, v121, v100
	v_ashrrev_i32_e32 v77, 31, v76
	v_lshlrev_b64 v[76:77], 12, v[76:77]
	v_lshl_add_u64 v[76:77], s[68:69], 0, v[76:77]
	v_lshl_add_u64 v[76:77], v[76:77], 0, v[108:109]
	v_cvt_pk_bf16_f32 v87, v78, v79
	global_store_dwordx4 v[76:77], v[84:87], off
	v_cvt_pk_bf16_f32 v76, v80, v81
	v_cvt_pk_bf16_f32 v77, v82, v83
	v_cvt_pk_bf16_f32 v78, v72, v73
	v_cvt_pk_bf16_f32 v79, v74, v75
	s_mov_b32 s20, s8
	s_nop 0
	v_add_u32_e32 v84, 48, v152
	v_add_u32_e32 v72, v122, v84
	v_ashrrev_i32_e32 v73, 31, v72
	v_lshlrev_b64 v[72:73], 12, v[72:73]
	v_lshl_add_u64 v[72:73], s[68:69], 0, v[72:73]
	v_lshl_add_u64 v[72:73], v[72:73], 0, v[136:137]
	global_store_dwordx4 v[72:73], v[76:79], off
	v_cvt_pk_bf16_f32 v68, v68, v69
	v_cvt_pk_bf16_f32 v69, v70, v71
; __device__ __forceinline__ unsigned cvt_pk_bf16(float lo, float hi) { unsigned r; asm volatile("v_cvt_pk_bf16_f32 %0, %1, %2" : "=v"(r) : "v"(lo), "v"(hi)); return r; }
; #define PG8_WAIT_V(n) asm volatile("s_waitcnt vmcnt(" #n ")" ::: "memory")
; #define PG8_BAR __builtin_amdgcn_s_barrier()
; template <class Epi, class Sched>
; __device__ __forceinline__ void gemm_phase(LAS unsigned char* lds, const Gemm g, const Sched& S, const Epi& E) {
;     ...
;         if (!has_next) break;
; #pragma unroll
;         for (int a = 0; a < 2; ++a)
; #pragma unroll
;             for (int b = 0; b < 2; ++b)
; #pragma unroll
;                 for (int m = 0; m < 4; ++m)
; #pragma unroll
;                     for (int n = 0; n < 2; ++n) acc[a][b][m][n] = (f32x4){0.f, 0.f, 0.f, 0.f};
;         cur = nxt; cA = nA; cB = nB; ++ui;
;     }
;     PG8_WAIT_V(0);
;     if (wr == 0) PG8_BAR;
;     PG8_BAR;
;     __device__ __forceinline__ void operator()(const AccT& acc, const Unit& u, int wr, int wc, int fr, int fq) const {
;     ...
;                 const int gm = rbase + ai * 128 + m * 16;
; #pragma unroll
;                 for (int bj = 0; bj < 2; ++bj) {
;                     const int t0 = tb + bj * 128;
;                     const f32x4 v0 = acc[ai][bj][m][0], v1 = acc[ai][bj][m][1];
;                     u32x4 w; w.x = cvt_pk_bf16(v0[0], v0[1]); w.y = cvt_pk_bf16(v0[2], v0[3]); w.z = cvt_pk_bf16(v1[0], v1[1]); w.w = cvt_pk_bf16(v1[2], v1[3]);
;                     *(u32x4*)(YT + ((size_t)((t0 >> 10) * 512 + gm)) * 2048 + part * 1024 + (t0 & 1023)) = w;
;                 }
;             }
;     }
	v_cvt_pk_bf16_f32 v70, v64, v65
	v_add_u32_e32 v64, v121, v84
	v_ashrrev_i32_e32 v65, 31, v64
	v_lshlrev_b64 v[64:65], 12, v[64:65]
	v_lshl_add_u64 v[64:65], s[68:69], 0, v[64:65]
	v_lshl_add_u64 v[64:65], v[64:65], 0, v[108:109]
	v_cvt_pk_bf16_f32 v71, v66, v67
	global_store_dwordx4 v[64:65], v[68:71], off
	v_add_u32_e32 v64, 0x80, v152
	v_cvt_pk_bf16_f32 v60, v60, v61
	v_cvt_pk_bf16_f32 v61, v62, v63
	v_cvt_pk_bf16_f32 v62, v56, v57
	v_add_u32_e32 v56, v122, v64
	v_ashrrev_i32_e32 v57, 31, v56
	v_lshlrev_b64 v[56:57], 12, v[56:57]
	v_lshl_add_u64 v[56:57], s[68:69], 0, v[56:57]
	v_lshl_add_u64 v[56:57], v[56:57], 0, v[136:137]
	v_cvt_pk_bf16_f32 v63, v58, v59
	global_store_dwordx4 v[56:57], v[60:63], off
	v_cvt_pk_bf16_f32 v52, v52, v53
	v_cvt_pk_bf16_f32 v53, v54, v55
	v_cvt_pk_bf16_f32 v54, v44, v45
	v_add_u32_e32 v44, v121, v64
	v_ashrrev_i32_e32 v45, 31, v44
	v_lshlrev_b64 v[44:45], 12, v[44:45]
	v_lshl_add_u64 v[44:45], s[68:69], 0, v[44:45]
	v_lshl_add_u64 v[44:45], v[44:45], 0, v[108:109]
	v_cvt_pk_bf16_f32 v55, v46, v47
	global_store_dwordx4 v[44:45], v[52:55], off
	v_cvt_pk_bf16_f32 v44, v48, v49
	v_cvt_pk_bf16_f32 v45, v50, v51
	v_cvt_pk_bf16_f32 v46, v40, v41
	v_cvt_pk_bf16_f32 v47, v42, v43
	s_mov_b64 s[24:25], s[18:19]
	s_nop 0
	v_add_u32_e32 v52, 0x90, v152
	v_add_u32_e32 v40, v122, v52
	v_ashrrev_i32_e32 v41, 31, v40
	v_lshlrev_b64 v[40:41], 12, v[40:41]
	v_lshl_add_u64 v[40:41], s[68:69], 0, v[40:41]
	v_lshl_add_u64 v[40:41], v[40:41], 0, v[136:137]
	global_store_dwordx4 v[40:41], v[44:47], off
	v_cvt_pk_bf16_f32 v36, v36, v37
	v_cvt_pk_bf16_f32 v37, v38, v39
	v_cvt_pk_bf16_f32 v38, v28, v29
	v_add_u32_e32 v28, v121, v52
	v_ashrrev_i32_e32 v29, 31, v28
	v_lshlrev_b64 v[28:29], 12, v[28:29]
	v_lshl_add_u64 v[28:29], s[68:69], 0, v[28:29]
	v_lshl_add_u64 v[28:29], v[28:29], 0, v[108:109]
	v_cvt_pk_bf16_f32 v39, v30, v31
	global_store_dwordx4 v[28:29], v[36:39], off
	v_cvt_pk_bf16_f32 v28, v32, v33
	v_cvt_pk_bf16_f32 v29, v34, v35
	v_cvt_pk_bf16_f32 v30, v24, v25
	v_cvt_pk_bf16_f32 v31, v26, v27
	s_mov_b64 s[22:23], s[16:17]
	s_nop 0
	v_add_u32_e32 v36, 0xa0, v152
	v_add_u32_e32 v24, v122, v36
	v_ashrrev_i32_e32 v25, 31, v24
	v_lshlrev_b64 v[24:25], 12, v[24:25]
	v_lshl_add_u64 v[24:25], s[68:69], 0, v[24:25]
	v_lshl_add_u64 v[24:25], v[24:25], 0, v[136:137]
	global_store_dwordx4 v[24:25], v[28:31], off
	v_cvt_pk_bf16_f32 v20, v20, v21
	v_cvt_pk_bf16_f32 v21, v22, v23
	v_cvt_pk_bf16_f32 v22, v12, v13
	v_add_u32_e32 v12, v121, v36
	v_ashrrev_i32_e32 v13, 31, v12
	v_lshlrev_b64 v[12:13], 12, v[12:13]
	v_lshl_add_u64 v[12:13], s[68:69], 0, v[12:13]
	v_lshl_add_u64 v[12:13], v[12:13], 0, v[108:109]
	v_cvt_pk_bf16_f32 v23, v14, v15
	global_store_dwordx4 v[12:13], v[20:23], off
	v_cvt_pk_bf16_f32 v12, v16, v17
	v_cvt_pk_bf16_f32 v13, v18, v19
	v_cvt_pk_bf16_f32 v14, v8, v9
	v_cvt_pk_bf16_f32 v15, v10, v11
	s_nop 1
	v_add_u32_e32 v20, 0xb0, v152
	v_add_u32_e32 v8, v122, v20
	v_ashrrev_i32_e32 v9, 31, v8
	v_lshlrev_b64 v[8:9], 12, v[8:9]
	v_lshl_add_u64 v[8:9], s[68:69], 0, v[8:9]
	v_lshl_add_u64 v[8:9], v[8:9], 0, v[136:137]
	global_store_dwordx4 v[8:9], v[12:15], off
	v_cvt_pk_bf16_f32 v4, v4, v5
	v_cvt_pk_bf16_f32 v5, v6, v7
	v_cvt_pk_bf16_f32 v6, v0, v1
	v_add_u32_e32 v0, v121, v20
	v_ashrrev_i32_e32 v1, 31, v0
	v_lshlrev_b64 v[0:1], 12, v[0:1]
	v_lshl_add_u64 v[0:1], s[68:69], 0, v[0:1]
	v_lshl_add_u64 v[0:1], v[0:1], 0, v[108:109]
	v_cvt_pk_bf16_f32 v7, v2, v3
	global_store_dwordx4 v[0:1], v[4:7], off
	s_cbranch_vccz .LBB0_646
	s_waitcnt vmcnt(0)
	s_cmpk_gt_u32 s28, 0xff
	s_cbranch_scc1 .LBB0_657
	s_barrier

; #define PG8_STAGE(bufoff, gbase, voff) do { _Pragma("unroll") for (int _i = 0; _i < 2; ++_i) \
;         __builtin_amdgcn_global_load_lds((const unsigned*)((const char*)(gbase) + (voff)[_i]), (LAS unsigned*)(lds + (bufoff) + ldsw + _i * 8192), 16, 0, 0); } while (0)
; #define PG8_LDA(dst, b, h) do { _Pragma("unroll") for (int m = 0; m < 4; ++m) _Pragma("unroll") for (int k = 0; k < 2; ++k) dst[m][k] = *(const LAS bf16x8*)(lds + PG8_SA(b, h) + aoff + m * 2048 + k * 1024); } while (0)
; #define PG8_LDB(dst, b, h) do { _Pragma("unroll") for (int n = 0; n < 2; ++n) _Pragma("unroll") for (int k = 0; k < 2; ++k) dst[n][k] = *(const LAS bf16x8*)(lds + PG8_SB(b, h) + boff + n * 2048 + k * 1024); } while (0)
; #define PG8_MMA(ai, bj, At, Bt) do { __builtin_amdgcn_s_setprio(1); _Pragma("unroll") for (int m = 0; m < 4; ++m) _Pragma("unroll") for (int n = 0; n < 2; ++n) _Pragma("unroll") for (int k = 0; k < 2; ++k) \
;         acc[ai][bj][m][n] = __builtin_amdgcn_mfma_f32_16x16x32_bf16(Bt[n][k], At[m][k], acc[ai][bj][m][n], 0, 0, 0); __builtin_amdgcn_s_setprio(0); } while (0)
; #define PG8_WAIT_L(n) asm volatile("s_waitcnt lgkmcnt(" #n ")" ::: "memory")
; template <class Epi, class Sched>
; __device__ __forceinline__ void gemm_phase(LAS unsigned char* lds, const Gemm g, const Sched& S, const Epi& E) {
;     ...
;         const bool has_next = S.next(ui + 1, nxt);
;         const char* nA = has_next ? (const char*)g.A + (size_t)nxt.pm * tstep : cA; const char* nB = has_next ? (const char*)g.Bt + (size_t)nxt.pn * tstep : cB;
;         for (int t = 0; t < nt; t += 2) {
;             const bool last = (t == nt - 2);
;             const char* a1 = cA + (size_t)(t + 1) * kstep;
;             const char* a2 = last ? nA : cA + (size_t)(t + 2) * kstep; const char* b2 = last ? nB : cB + (size_t)(t + 2) * kstep;
;             const char* a3 = a2 + kstep; const char* b3 = b2 + kstep;
;             PG8_LDB(B0, 0, 0); PG8_SCHED; PG8_LDA(At, 0, 0); PG8_STAGE(PG8_SA(1, 1), a1 + hstep, voffA);
;             PG8_WAIT_L(8); PG8_BAR; PG8_WAIT_L(0); PG8_MMA(0, 0, At, B0); PG8_BAR; PG8_SCHED;
;             PG8_LDB(B1, 0, 1); PG8_STAGE(PG8_SB(0, 0), b2, voffB);
;             PG8_BAR; PG8_WAIT_L(0); PG8_MMA(0, 1, At, B1); PG8_BAR;
;             PG8_LDA(At, 0, 1); PG8_STAGE(PG8_SA(0, 0), a2, voffA);
;             PG8_BAR; PG8_WAIT_L(0); PG8_MMA(1, 0, At, B0); PG8_BAR; PG8_SCHED;
.LBB0_672:
	s_ashr_i32 s9, s8, 31
	v_cmp_lt_i64_e32 vcc, s[12:13], v[142:143]
	s_lshl_b64 s[12:13], s[8:9], 19
	s_add_u32 s12, s26, s12
	s_addc_u32 s13, s27, s13
	s_and_b64 s[14:15], vcc, exec
	s_cselect_b32 s9, s13, s19
	s_cselect_b32 s46, s12, s18
	s_ashr_i32 s7, s6, 31
	s_lshl_b64 s[14:15], s[6:7], 19
	s_add_u32 s14, s10, s14
	s_addc_u32 s15, s11, s15
	s_and_b64 s[22:23], vcc, exec
	s_cselect_b32 s7, s15, s21
	s_cselect_b32 s47, s14, s20
	s_add_u32 s18, s18, 0x40080
	s_addc_u32 s19, s19, 0
	s_add_u32 s48, s20, 0x100
	s_addc_u32 s49, s21, 0
	s_mov_b32 s51, -2
	s_waitcnt lgkmcnt(0)
	ds_read_b128 v[152:155], v149
	ds_read_b128 v[156:159], v149 offset:1024
	ds_read_b128 v[160:163], v149 offset:2048
	ds_read_b128 v[164:167], v149 offset:3072
	s_add_u32 s20, s18, 0xfffc0080
	s_addc_u32 s21, s19, -1
	s_cmp_eq_u32 s51, 12
	s_cselect_b32 s23, s9, s21
	s_cselect_b32 s22, s46, s20
	s_cselect_b32 s21, s7, s49
	s_cselect_b32 s20, s47, s48
	s_add_i32 m0, s17, 0xc000
	ds_read_b128 v[168:171], v150
	ds_read_b128 v[172:175], v150 offset:1024
	ds_read_b128 v[176:179], v150 offset:2048
	ds_read_b128 v[180:183], v150 offset:3072
	ds_read_b128 v[184:187], v150 offset:4096
	ds_read_b128 v[188:191], v150 offset:5120
	ds_read_b128 v[192:195], v150 offset:6144
	ds_read_b128 v[196:199], v150 offset:7168
	global_load_lds_dwordx4 v138, s[18:19]
	s_add_i32 m0, s17, 0xe000
	s_nop 0
	global_load_lds_dwordx4 v140, s[18:19]
	s_waitcnt lgkmcnt(8)
	s_waitcnt vmcnt(8)
	s_setprio 1
	s_barrier
	s_waitcnt lgkmcnt(0)
	v_mfma_f32_16x16x32_bf16 v[124:127], v[152:155], v[168:171], 0
	v_mfma_f32_16x16x32_bf16 v[120:123], v[160:163], v[168:171], 0
	v_mfma_f32_16x16x32_bf16 v[112:115], v[152:155], v[176:179], 0
	v_mfma_f32_16x16x32_bf16 v[104:107], v[160:163], v[176:179], 0
	v_mfma_f32_16x16x32_bf16 v[96:99], v[152:155], v[184:187], 0
	v_mfma_f32_16x16x32_bf16 v[88:91], v[160:163], v[184:187], 0
	v_mfma_f32_16x16x32_bf16 v[80:83], v[152:155], v[192:195], 0
	v_mfma_f32_16x16x32_bf16 v[72:75], v[160:163], v[192:195], 0
	v_mfma_f32_16x16x32_bf16 v[124:127], v[156:159], v[172:175], v[124:127]
	v_mfma_f32_16x16x32_bf16 v[120:123], v[164:167], v[172:175], v[120:123]
	v_mfma_f32_16x16x32_bf16 v[112:115], v[156:159], v[180:183], v[112:115]
	v_mfma_f32_16x16x32_bf16 v[104:107], v[164:167], v[180:183], v[104:107]
	v_mfma_f32_16x16x32_bf16 v[96:99], v[156:159], v[188:191], v[96:99]
	v_mfma_f32_16x16x32_bf16 v[88:91], v[164:167], v[188:191], v[88:91]
	v_mfma_f32_16x16x32_bf16 v[80:83], v[156:159], v[196:199], v[80:83]
	v_mfma_f32_16x16x32_bf16 v[72:75], v[164:167], v[196:199], v[72:75]
	s_setprio 0
	s_barrier
	s_add_i32 s52, s43, s28
	s_mov_b32 m0, s52
	ds_read_b128 v[202:205], v151
	ds_read_b128 v[206:209], v151 offset:1024
	ds_read_b128 v[210:213], v151 offset:2048
	ds_read_b128 v[214:217], v151 offset:3072
	global_load_lds_dwordx4 v130, s[20:21]
	s_add_i32 m0, s52, 0x2000
	s_nop 0
	global_load_lds_dwordx4 v134, s[20:21]
	s_waitcnt vmcnt(8)
	s_setprio 1
	s_barrier
	s_waitcnt lgkmcnt(0)
	v_mfma_f32_16x16x32_bf16 v[116:119], v[202:205], v[168:171], 0
	v_mfma_f32_16x16x32_bf16 v[108:111], v[210:213], v[168:171], 0
	v_mfma_f32_16x16x32_bf16 v[100:103], v[202:205], v[176:179], 0
	v_mfma_f32_16x16x32_bf16 v[92:95], v[210:213], v[176:179], 0
	v_mfma_f32_16x16x32_bf16 v[84:87], v[202:205], v[184:187], 0
	v_mfma_f32_16x16x32_bf16 v[76:79], v[210:213], v[184:187], 0
	v_mfma_f32_16x16x32_bf16 v[68:71], v[202:205], v[192:195], 0
	v_mfma_f32_16x16x32_bf16 v[64:67], v[210:213], v[192:195], 0
	v_mfma_f32_16x16x32_bf16 v[116:119], v[206:209], v[172:175], v[116:119]
	v_mfma_f32_16x16x32_bf16 v[108:111], v[214:217], v[172:175], v[108:111]
	v_mfma_f32_16x16x32_bf16 v[100:103], v[206:209], v[180:183], v[100:103]
	v_mfma_f32_16x16x32_bf16 v[92:95], v[214:217], v[180:183], v[92:95]
	v_mfma_f32_16x16x32_bf16 v[84:87], v[206:209], v[188:191], v[84:87]
	v_mfma_f32_16x16x32_bf16 v[76:79], v[214:217], v[188:191], v[76:79]
	v_mfma_f32_16x16x32_bf16 v[68:71], v[206:209], v[196:199], v[68:71]
	v_mfma_f32_16x16x32_bf16 v[64:67], v[214:217], v[196:199], v[64:67]
	s_setprio 0
	s_mov_b32 m0, s17
	v_lshl_add_u64 v[222:223], s[22:23], 0, v[128:129]
	s_barrier
	ds_read_b128 v[168:171], v150 offset:16384
	ds_read_b128 v[172:175], v150 offset:17408
	ds_read_b128 v[176:179], v150 offset:18432
	ds_read_b128 v[180:183], v150 offset:19456
	ds_read_b128 v[184:187], v150 offset:20480
	ds_read_b128 v[188:191], v150 offset:21504
	ds_read_b128 v[192:195], v150 offset:22528
	ds_read_b128 v[196:199], v150 offset:23552
	global_load_lds_dwordx4 v128, s[22:23]
	v_lshl_add_u64 v[224:225], s[22:23], 0, v[132:133]
	s_mov_b32 m0, s29
	s_nop 0
	global_load_lds_dwordx4 v132, s[22:23]
	s_setprio 1
	s_barrier
	s_waitcnt lgkmcnt(0)
	v_mfma_f32_16x16x32_bf16 v[60:63], v[152:155], v[168:171], 0
	v_mfma_f32_16x16x32_bf16 v[56:59], v[160:163], v[168:171], 0
	v_mfma_f32_16x16x32_bf16 v[48:51], v[152:155], v[176:179], 0
	v_mfma_f32_16x16x32_bf16 v[40:43], v[160:163], v[176:179], 0
	v_mfma_f32_16x16x32_bf16 v[32:35], v[152:155], v[184:187], 0
	v_mfma_f32_16x16x32_bf16 v[24:27], v[160:163], v[184:187], 0
	v_mfma_f32_16x16x32_bf16 v[16:19], v[152:155], v[192:195], 0
	v_mfma_f32_16x16x32_bf16 v[8:11], v[160:163], v[192:195], 0
	v_mfma_f32_16x16x32_bf16 v[60:63], v[156:159], v[172:175], v[60:63]
	v_mfma_f32_16x16x32_bf16 v[56:59], v[164:167], v[172:175], v[56:59]
	v_mfma_f32_16x16x32_bf16 v[48:51], v[156:159], v[180:183], v[48:51]
	v_mfma_f32_16x16x32_bf16 v[40:43], v[164:167], v[180:183], v[40:43]
	v_mfma_f32_16x16x32_bf16 v[32:35], v[156:159], v[188:191], v[32:35]
	v_mfma_f32_16x16x32_bf16 v[24:27], v[164:167], v[188:191], v[24:27]
	v_mfma_f32_16x16x32_bf16 v[16:19], v[156:159], v[196:199], v[16:19]
	v_mfma_f32_16x16x32_bf16 v[8:11], v[164:167], v[196:199], v[8:11]
	s_setprio 0
	s_barrier
; #define PG8_STAGE(bufoff, gbase, voff) do { _Pragma("unroll") for (int _i = 0; _i < 2; ++_i) \
;         __builtin_amdgcn_global_load_lds((const unsigned*)((const char*)(gbase) + (voff)[_i]), (LAS unsigned*)(lds + (bufoff) + ldsw + _i * 8192), 16, 0, 0); } while (0)
; #define PG8_LDA(dst, b, h) do { _Pragma("unroll") for (int m = 0; m < 4; ++m) _Pragma("unroll") for (int k = 0; k < 2; ++k) dst[m][k] = *(const LAS bf16x8*)(lds + PG8_SA(b, h) + aoff + m * 2048 + k * 1024); } while (0)
; #define PG8_LDB(dst, b, h) do { _Pragma("unroll") for (int n = 0; n < 2; ++n) _Pragma("unroll") for (int k = 0; k < 2; ++k) dst[n][k] = *(const LAS bf16x8*)(lds + PG8_SB(b, h) + boff + n * 2048 + k * 1024); } while (0)
; #define PG8_MMA(ai, bj, At, Bt) do { __builtin_amdgcn_s_setprio(1); _Pragma("unroll") for (int m = 0; m < 4; ++m) _Pragma("unroll") for (int n = 0; n < 2; ++n) _Pragma("unroll") for (int k = 0; k < 2; ++k) \
;         acc[ai][bj][m][n] = __builtin_amdgcn_mfma_f32_16x16x32_bf16(Bt[n][k], At[m][k], acc[ai][bj][m][n], 0, 0, 0); __builtin_amdgcn_s_setprio(0); } while (0)
; #define PG8_WAIT_V(n) asm volatile("s_waitcnt vmcnt(" #n ")" ::: "memory")
; #define PG8_WAIT_L(n) asm volatile("s_waitcnt lgkmcnt(" #n ")" ::: "memory")
; #define PG8_BAR __builtin_amdgcn_s_barrier()
; #define PG8_SCHED __builtin_amdgcn_sched_barrier(0)
; template <class Epi, class Sched>
; __device__ __forceinline__ void gemm_phase(LAS unsigned char* lds, const Gemm g, const Sched& S, const Epi& E) {
;     ...
;             PG8_STAGE(PG8_SB(0, 1), b2 + hstep, voffB);
;             PG8_WAIT_V(6); PG8_BAR; PG8_MMA(1, 1, At, B1); PG8_BAR;
;             PG8_LDB(B0, 1, 0); PG8_SCHED; PG8_LDA(At, 1, 0); PG8_STAGE(PG8_SA(0, 1), a2 + hstep, voffA);
;             PG8_WAIT_L(8); PG8_BAR; PG8_WAIT_L(0); PG8_MMA(0, 0, At, B0); PG8_BAR; PG8_SCHED;
;             PG8_LDB(B1, 1, 1); PG8_STAGE(PG8_SB(1, 0), b3, voffB);
;             PG8_BAR; PG8_WAIT_L(0); PG8_MMA(0, 1, At, B1); PG8_BAR;
;             PG8_LDA(At, 1, 1); PG8_STAGE(PG8_SA(1, 0), a3, voffA);
;             PG8_BAR; PG8_WAIT_L(0); PG8_MMA(1, 0, At, B0); PG8_BAR; PG8_SCHED;
	s_add_u32 s52, s20, 0x40000
	s_addc_u32 s53, s21, 0
	s_add_i32 s54, s44, s28
	s_mov_b32 m0, s54
	s_nop 0
	global_load_lds_dwordx4 v130, s[52:53]
	s_add_i32 m0, s54, 0x2000
	s_nop 0
	global_load_lds_dwordx4 v134, s[52:53]
	s_add_u32 s22, s22, 0x40000
	s_addc_u32 s23, s23, 0
	s_mov_b32 m0, s30
	s_nop 0
	global_load_lds_dwordx4 v128, s[22:23]
	s_mov_b32 m0, s31
	s_nop 0
	global_load_lds_dwordx4 v132, s[22:23]
	s_waitcnt vmcnt(10)
	s_setprio 1
	s_barrier
	v_mfma_f32_16x16x32_bf16 v[52:55], v[202:205], v[168:171], 0
	v_mfma_f32_16x16x32_bf16 v[44:47], v[210:213], v[168:171], 0
	v_mfma_f32_16x16x32_bf16 v[36:39], v[202:205], v[176:179], 0
	v_mfma_f32_16x16x32_bf16 v[28:31], v[210:213], v[176:179], 0
	v_mfma_f32_16x16x32_bf16 v[20:23], v[202:205], v[184:187], 0
	v_mfma_f32_16x16x32_bf16 v[12:15], v[210:213], v[184:187], 0
	v_mfma_f32_16x16x32_bf16 v[4:7], v[202:205], v[192:195], 0
	v_mfma_f32_16x16x32_bf16 v[0:3], v[210:213], v[192:195], 0
	v_mfma_f32_16x16x32_bf16 v[52:55], v[206:209], v[172:175], v[52:55]
	v_mfma_f32_16x16x32_bf16 v[44:47], v[214:217], v[172:175], v[44:47]
	v_mfma_f32_16x16x32_bf16 v[36:39], v[206:209], v[180:183], v[36:39]
	v_mfma_f32_16x16x32_bf16 v[28:31], v[214:217], v[180:183], v[28:31]
	v_mfma_f32_16x16x32_bf16 v[20:23], v[206:209], v[188:191], v[20:23]
	v_mfma_f32_16x16x32_bf16 v[12:15], v[214:217], v[188:191], v[12:15]
	v_mfma_f32_16x16x32_bf16 v[4:7], v[206:209], v[196:199], v[4:7]
	v_mfma_f32_16x16x32_bf16 v[0:3], v[214:217], v[196:199], v[0:3]
	s_setprio 0
	s_add_i32 s52, 0, 0x18000
	v_add_u32_e32 v136, s52, v148
	s_barrier
	ds_read_b128 v[152:155], v136
	ds_read_b128 v[156:159], v136 offset:1024
	ds_read_b128 v[160:163], v136 offset:2048
	ds_read_b128 v[164:167], v136 offset:3072
	ds_read_b128 v[168:171], v150 offset:32768
	ds_read_b128 v[172:175], v150 offset:33792
	ds_read_b128 v[176:179], v150 offset:34816
	ds_read_b128 v[180:183], v150 offset:35840
	ds_read_b128 v[184:187], v150 offset:36864
	ds_read_b128 v[188:191], v150 offset:37888
	ds_read_b128 v[192:195], v150 offset:38912
	ds_read_b128 v[196:199], v150 offset:39936
	s_waitcnt lgkmcnt(8)
	s_waitcnt vmcnt(8)
	s_setprio 1
	s_barrier
	s_waitcnt lgkmcnt(0)
	v_mfma_f32_16x16x32_bf16 v[124:127], v[152:155], v[168:171], v[124:127]
	v_mfma_f32_16x16x32_bf16 v[120:123], v[160:163], v[168:171], v[120:123]
	v_mfma_f32_16x16x32_bf16 v[112:115], v[152:155], v[176:179], v[112:115]
	v_mfma_f32_16x16x32_bf16 v[104:107], v[160:163], v[176:179], v[104:107]
	v_mfma_f32_16x16x32_bf16 v[96:99], v[152:155], v[184:187], v[96:99]
	v_mfma_f32_16x16x32_bf16 v[88:91], v[160:163], v[184:187], v[88:91]
	v_mfma_f32_16x16x32_bf16 v[80:83], v[152:155], v[192:195], v[80:83]
	v_mfma_f32_16x16x32_bf16 v[72:75], v[160:163], v[192:195], v[72:75]
	v_mfma_f32_16x16x32_bf16 v[124:127], v[156:159], v[172:175], v[124:127]
	v_mfma_f32_16x16x32_bf16 v[120:123], v[164:167], v[172:175], v[120:123]
	v_mfma_f32_16x16x32_bf16 v[112:115], v[156:159], v[180:183], v[112:115]
	v_mfma_f32_16x16x32_bf16 v[104:107], v[164:167], v[180:183], v[104:107]
	v_mfma_f32_16x16x32_bf16 v[96:99], v[156:159], v[188:191], v[96:99]
	v_mfma_f32_16x16x32_bf16 v[88:91], v[164:167], v[188:191], v[88:91]
	v_mfma_f32_16x16x32_bf16 v[80:83], v[156:159], v[196:199], v[80:83]
	v_mfma_f32_16x16x32_bf16 v[72:75], v[164:167], v[196:199], v[72:75]
	s_setprio 0
	s_barrier
	s_add_i32 s22, 0, 0x1c000
	s_add_i32 s23, s52, s28
	v_add_u32_e32 v136, s22, v148
	s_add_u32 s0, s20, 0x80
	s_addc_u32 s1, s21, 0
	s_mov_b32 m0, s23
	ds_read_b128 v[202:205], v136
	ds_read_b128 v[206:209], v136 offset:1024
	ds_read_b128 v[210:213], v136 offset:2048
	ds_read_b128 v[214:217], v136 offset:3072
	global_load_lds_dwordx4 v130, s[0:1]
	s_add_i32 m0, s23, 0x2000
	s_nop 0
	global_load_lds_dwordx4 v134, s[0:1]
	s_waitcnt vmcnt(8)
	s_setprio 1
	s_barrier
	s_waitcnt lgkmcnt(0)
	v_mfma_f32_16x16x32_bf16 v[116:119], v[202:205], v[168:171], v[116:119]
	v_mfma_f32_16x16x32_bf16 v[108:111], v[210:213], v[168:171], v[108:111]
	v_mfma_f32_16x16x32_bf16 v[100:103], v[202:205], v[176:179], v[100:103]
	v_mfma_f32_16x16x32_bf16 v[92:95], v[210:213], v[176:179], v[92:95]
	v_mfma_f32_16x16x32_bf16 v[84:87], v[202:205], v[184:187], v[84:87]
	v_mfma_f32_16x16x32_bf16 v[76:79], v[210:213], v[184:187], v[76:79]
	v_mfma_f32_16x16x32_bf16 v[68:71], v[202:205], v[192:195], v[68:71]
	v_mfma_f32_16x16x32_bf16 v[64:67], v[210:213], v[192:195], v[64:67]
	v_mfma_f32_16x16x32_bf16 v[116:119], v[206:209], v[172:175], v[116:119]
	v_mfma_f32_16x16x32_bf16 v[108:111], v[214:217], v[172:175], v[108:111]
	v_mfma_f32_16x16x32_bf16 v[100:103], v[206:209], v[180:183], v[100:103]
	v_mfma_f32_16x16x32_bf16 v[92:95], v[214:217], v[180:183], v[92:95]
	v_mfma_f32_16x16x32_bf16 v[84:87], v[206:209], v[188:191], v[84:87]
	v_mfma_f32_16x16x32_bf16 v[76:79], v[214:217], v[188:191], v[76:79]
	v_mfma_f32_16x16x32_bf16 v[68:71], v[206:209], v[196:199], v[68:71]
	v_mfma_f32_16x16x32_bf16 v[64:67], v[214:217], v[196:199], v[64:67]
	s_setprio 0
	s_mov_b32 m0, s36
	s_mov_b64 s[0:1], 0x80
	v_lshl_add_u64 v[218:219], v[222:223], 0, s[0:1]
	s_barrier
	ds_read_b128 v[168:171], v150 offset:49152
	ds_read_b128 v[172:175], v150 offset:50176
	ds_read_b128 v[176:179], v150 offset:51200
	ds_read_b128 v[180:183], v150 offset:52224
	ds_read_b128 v[184:187], v150 offset:53248
	ds_read_b128 v[188:191], v150 offset:54272
	ds_read_b128 v[192:195], v150 offset:55296
	ds_read_b128 v[196:199], v150 offset:56320
	global_load_lds_dwordx4 v[218:219], off
	v_lshl_add_u64 v[218:219], v[224:225], 0, s[0:1]
	s_mov_b32 m0, s37
	s_nop 0
	global_load_lds_dwordx4 v[218:219], off
	s_setprio 1
	s_barrier
; #define PG8_STAGE(bufoff, gbase, voff) do { _Pragma("unroll") for (int _i = 0; _i < 2; ++_i) \
;         __builtin_amdgcn_global_load_lds((const unsigned*)((const char*)(gbase) + (voff)[_i]), (LAS unsigned*)(lds + (bufoff) + ldsw + _i * 8192), 16, 0, 0); } while (0)
; #define PG8_LDA(dst, b, h) do { _Pragma("unroll") for (int m = 0; m < 4; ++m) _Pragma("unroll") for (int k = 0; k < 2; ++k) dst[m][k] = *(const LAS bf16x8*)(lds + PG8_SA(b, h) + aoff + m * 2048 + k * 1024); } while (0)
; #define PG8_LDB(dst, b, h) do { _Pragma("unroll") for (int n = 0; n < 2; ++n) _Pragma("unroll") for (int k = 0; k < 2; ++k) dst[n][k] = *(const LAS bf16x8*)(lds + PG8_SB(b, h) + boff + n * 2048 + k * 1024); } while (0)
; #define PG8_MMA(ai, bj, At, Bt) do { __builtin_amdgcn_s_setprio(1); _Pragma("unroll") for (int m = 0; m < 4; ++m) _Pragma("unroll") for (int n = 0; n < 2; ++n) _Pragma("unroll") for (int k = 0; k < 2; ++k) \
;         acc[ai][bj][m][n] = __builtin_amdgcn_mfma_f32_16x16x32_bf16(Bt[n][k], At[m][k], acc[ai][bj][m][n], 0, 0, 0); __builtin_amdgcn_s_setprio(0); } while (0)
; #define PG8_WAIT_V(n) asm volatile("s_waitcnt vmcnt(" #n ")" ::: "memory")
; #define PG8_WAIT_L(n) asm volatile("s_waitcnt lgkmcnt(" #n ")" ::: "memory")
; #define PG8_BAR __builtin_amdgcn_s_barrier()
; #define PG8_SCHED __builtin_amdgcn_sched_barrier(0)
; template <class Epi, class Sched>
; __device__ __forceinline__ void gemm_phase(LAS unsigned char* lds, const Gemm g, const Sched& S, const Epi& E) {
;     ...
;         for (int t = 0; t < nt; t += 2) {
;             const bool last = (t == nt - 2);
;             const char* a1 = cA + (size_t)(t + 1) * kstep;
;             const char* a2 = last ? nA : cA + (size_t)(t + 2) * kstep; const char* b2 = last ? nB : cB + (size_t)(t + 2) * kstep;
;             const char* a3 = a2 + kstep; const char* b3 = b2 + kstep;
;             PG8_LDB(B0, 0, 0); PG8_SCHED; PG8_LDA(At, 0, 0); PG8_STAGE(PG8_SA(1, 1), a1 + hstep, voffA);
;             PG8_WAIT_L(8); PG8_BAR; PG8_WAIT_L(0); PG8_MMA(0, 0, At, B0); PG8_BAR; PG8_SCHED;
;             PG8_LDB(B1, 0, 1); PG8_STAGE(PG8_SB(0, 0), b2, voffB);
;             PG8_BAR; PG8_WAIT_L(0); PG8_MMA(0, 1, At, B1); PG8_BAR;
;     ...
;             PG8_BAR; PG8_WAIT_L(0); PG8_MMA(1, 0, At, B0); PG8_BAR; PG8_SCHED;
;             PG8_STAGE(PG8_SB(1, 1), b3 + hstep, voffB);
;             PG8_WAIT_V(6); PG8_BAR; PG8_MMA(1, 1, At, B1); PG8_BAR;
	s_waitcnt lgkmcnt(0)
	v_mfma_f32_16x16x32_bf16 v[60:63], v[152:155], v[168:171], v[60:63]
	v_mfma_f32_16x16x32_bf16 v[56:59], v[160:163], v[168:171], v[56:59]
	v_mfma_f32_16x16x32_bf16 v[48:51], v[152:155], v[176:179], v[48:51]
	v_mfma_f32_16x16x32_bf16 v[40:43], v[160:163], v[176:179], v[40:43]
	v_mfma_f32_16x16x32_bf16 v[32:35], v[152:155], v[184:187], v[32:35]
	v_mfma_f32_16x16x32_bf16 v[24:27], v[160:163], v[184:187], v[24:27]
	v_mfma_f32_16x16x32_bf16 v[16:19], v[152:155], v[192:195], v[16:19]
	v_mfma_f32_16x16x32_bf16 v[8:11], v[160:163], v[192:195], v[8:11]
	v_mfma_f32_16x16x32_bf16 v[60:63], v[156:159], v[172:175], v[60:63]
	v_mfma_f32_16x16x32_bf16 v[56:59], v[164:167], v[172:175], v[56:59]
	v_mfma_f32_16x16x32_bf16 v[48:51], v[156:159], v[180:183], v[48:51]
	v_mfma_f32_16x16x32_bf16 v[40:43], v[164:167], v[180:183], v[40:43]
	v_mfma_f32_16x16x32_bf16 v[32:35], v[156:159], v[188:191], v[32:35]
	v_mfma_f32_16x16x32_bf16 v[24:27], v[164:167], v[188:191], v[24:27]
	v_mfma_f32_16x16x32_bf16 v[16:19], v[156:159], v[196:199], v[16:19]
	v_mfma_f32_16x16x32_bf16 v[8:11], v[164:167], v[196:199], v[8:11]
	s_setprio 0
	s_barrier
	s_add_u32 s20, s20, 0x40080
	s_addc_u32 s21, s21, 0
	s_add_i32 s22, s22, s28
	s_mov_b32 m0, s22
	s_nop 0
	global_load_lds_dwordx4 v130, s[20:21]
	s_add_i32 m0, s22, 0x2000
	s_nop 0
	global_load_lds_dwordx4 v134, s[20:21]
	s_waitcnt vmcnt(8)
	s_setprio 1
	s_barrier
	v_mfma_f32_16x16x32_bf16 v[52:55], v[202:205], v[168:171], v[52:55]
	v_mfma_f32_16x16x32_bf16 v[44:47], v[210:213], v[168:171], v[44:47]
	v_mfma_f32_16x16x32_bf16 v[36:39], v[202:205], v[176:179], v[36:39]
	v_mfma_f32_16x16x32_bf16 v[28:31], v[210:213], v[176:179], v[28:31]
	v_mfma_f32_16x16x32_bf16 v[20:23], v[202:205], v[184:187], v[20:23]
	v_mfma_f32_16x16x32_bf16 v[12:15], v[210:213], v[184:187], v[12:15]
	v_mfma_f32_16x16x32_bf16 v[4:7], v[202:205], v[192:195], v[4:7]
	v_mfma_f32_16x16x32_bf16 v[0:3], v[210:213], v[192:195], v[0:3]
	v_mfma_f32_16x16x32_bf16 v[52:55], v[206:209], v[172:175], v[52:55]
	v_mfma_f32_16x16x32_bf16 v[44:47], v[214:217], v[172:175], v[44:47]
	v_mfma_f32_16x16x32_bf16 v[36:39], v[206:209], v[180:183], v[36:39]
	v_mfma_f32_16x16x32_bf16 v[28:31], v[214:217], v[180:183], v[28:31]
	v_mfma_f32_16x16x32_bf16 v[20:23], v[206:209], v[188:191], v[20:23]
	v_mfma_f32_16x16x32_bf16 v[12:15], v[214:217], v[188:191], v[12:15]
	v_mfma_f32_16x16x32_bf16 v[4:7], v[206:209], v[196:199], v[4:7]
	v_mfma_f32_16x16x32_bf16 v[0:3], v[214:217], v[196:199], v[0:3]
	s_setprio 0
	s_add_i32 s51, s51, 2
	s_add_u32 s18, s18, 0x100
	s_addc_u32 s19, s19, 0
	s_add_u32 s48, s48, 0x100
	s_addc_u32 s49, s49, 0
	s_cmp_gt_u32 s51, 13
	s_barrier
.LBB0_673:
	ds_read_b128 v[152:155], v149
	ds_read_b128 v[156:159], v149 offset:1024
	ds_read_b128 v[160:163], v149 offset:2048
	ds_read_b128 v[164:167], v149 offset:3072
	s_add_u32 s20, s18, 0xfffc0080
	s_addc_u32 s21, s19, -1
	s_cmp_eq_u32 s51, 12
	s_cselect_b32 s23, s9, s21
	s_cselect_b32 s22, s46, s20
	s_cselect_b32 s21, s7, s49
	s_cselect_b32 s20, s47, s48
	s_add_i32 m0, s17, 0xc000
	ds_read_b128 v[168:171], v150
	ds_read_b128 v[172:175], v150 offset:1024
	ds_read_b128 v[176:179], v150 offset:2048
	ds_read_b128 v[180:183], v150 offset:3072
	ds_read_b128 v[184:187], v150 offset:4096
	ds_read_b128 v[188:191], v150 offset:5120
	ds_read_b128 v[192:195], v150 offset:6144
	ds_read_b128 v[196:199], v150 offset:7168
	global_load_lds_dwordx4 v138, s[18:19]
	s_add_i32 m0, s17, 0xe000
	s_nop 0
	global_load_lds_dwordx4 v140, s[18:19]
	s_waitcnt lgkmcnt(8)
	s_waitcnt vmcnt(8)
	s_setprio 1
	s_barrier
	s_waitcnt lgkmcnt(0)
	v_mfma_f32_16x16x32_bf16 v[124:127], v[152:155], v[168:171], v[124:127]
	v_mfma_f32_16x16x32_bf16 v[120:123], v[160:163], v[168:171], v[120:123]
	v_mfma_f32_16x16x32_bf16 v[112:115], v[152:155], v[176:179], v[112:115]
	v_mfma_f32_16x16x32_bf16 v[104:107], v[160:163], v[176:179], v[104:107]
	v_mfma_f32_16x16x32_bf16 v[96:99], v[152:155], v[184:187], v[96:99]
	v_mfma_f32_16x16x32_bf16 v[88:91], v[160:163], v[184:187], v[88:91]
	v_mfma_f32_16x16x32_bf16 v[80:83], v[152:155], v[192:195], v[80:83]
	v_mfma_f32_16x16x32_bf16 v[72:75], v[160:163], v[192:195], v[72:75]
	v_mfma_f32_16x16x32_bf16 v[124:127], v[156:159], v[172:175], v[124:127]
	v_mfma_f32_16x16x32_bf16 v[120:123], v[164:167], v[172:175], v[120:123]
	v_mfma_f32_16x16x32_bf16 v[112:115], v[156:159], v[180:183], v[112:115]
	v_mfma_f32_16x16x32_bf16 v[104:107], v[164:167], v[180:183], v[104:107]
	v_mfma_f32_16x16x32_bf16 v[96:99], v[156:159], v[188:191], v[96:99]
	v_mfma_f32_16x16x32_bf16 v[88:91], v[164:167], v[188:191], v[88:91]
	v_mfma_f32_16x16x32_bf16 v[80:83], v[156:159], v[196:199], v[80:83]
	v_mfma_f32_16x16x32_bf16 v[72:75], v[164:167], v[196:199], v[72:75]
	s_setprio 0
	s_barrier
	s_add_i32 s52, s43, s28
	s_mov_b32 m0, s52
	ds_read_b128 v[202:205], v151
	ds_read_b128 v[206:209], v151 offset:1024
	ds_read_b128 v[210:213], v151 offset:2048
	ds_read_b128 v[214:217], v151 offset:3072
	global_load_lds_dwordx4 v130, s[20:21]
	s_add_i32 m0, s52, 0x2000
	s_nop 0
	global_load_lds_dwordx4 v134, s[20:21]
	s_waitcnt vmcnt(8)
	s_setprio 1
	s_barrier
; #define PG8_STAGE(bufoff, gbase, voff) do { _Pragma("unroll") for (int _i = 0; _i < 2; ++_i) \
;         __builtin_amdgcn_global_load_lds((const unsigned*)((const char*)(gbase) + (voff)[_i]), (LAS unsigned*)(lds + (bufoff) + ldsw + _i * 8192), 16, 0, 0); } while (0)
; #define PG8_LDA(dst, b, h) do { _Pragma("unroll") for (int m = 0; m < 4; ++m) _Pragma("unroll") for (int k = 0; k < 2; ++k) dst[m][k] = *(const LAS bf16x8*)(lds + PG8_SA(b, h) + aoff + m * 2048 + k * 1024); } while (0)
; #define PG8_LDB(dst, b, h) do { _Pragma("unroll") for (int n = 0; n < 2; ++n) _Pragma("unroll") for (int k = 0; k < 2; ++k) dst[n][k] = *(const LAS bf16x8*)(lds + PG8_SB(b, h) + boff + n * 2048 + k * 1024); } while (0)
; #define PG8_MMA(ai, bj, At, Bt) do { __builtin_amdgcn_s_setprio(1); _Pragma("unroll") for (int m = 0; m < 4; ++m) _Pragma("unroll") for (int n = 0; n < 2; ++n) _Pragma("unroll") for (int k = 0; k < 2; ++k) \
;         acc[ai][bj][m][n] = __builtin_amdgcn_mfma_f32_16x16x32_bf16(Bt[n][k], At[m][k], acc[ai][bj][m][n], 0, 0, 0); __builtin_amdgcn_s_setprio(0); } while (0)
; #define PG8_WAIT_V(n) asm volatile("s_waitcnt vmcnt(" #n ")" ::: "memory")
; #define PG8_WAIT_L(n) asm volatile("s_waitcnt lgkmcnt(" #n ")" ::: "memory")
; #define PG8_BAR __builtin_amdgcn_s_barrier()
; #define PG8_SCHED __builtin_amdgcn_sched_barrier(0)
; template <class Epi, class Sched>
; __device__ __forceinline__ void gemm_phase(LAS unsigned char* lds, const Gemm g, const Sched& S, const Epi& E) {
;     ...
;             PG8_LDA(At, 0, 1); PG8_STAGE(PG8_SA(0, 0), a2, voffA);
;             PG8_BAR; PG8_WAIT_L(0); PG8_MMA(1, 0, At, B0); PG8_BAR; PG8_SCHED;
;             PG8_STAGE(PG8_SB(0, 1), b2 + hstep, voffB);
;             PG8_WAIT_V(6); PG8_BAR; PG8_MMA(1, 1, At, B1); PG8_BAR;
;             PG8_LDB(B0, 1, 0); PG8_SCHED; PG8_LDA(At, 1, 0); PG8_STAGE(PG8_SA(0, 1), a2 + hstep, voffA);
;             PG8_WAIT_L(8); PG8_BAR; PG8_WAIT_L(0); PG8_MMA(0, 0, At, B0); PG8_BAR; PG8_SCHED;
;             PG8_LDB(B1, 1, 1); PG8_STAGE(PG8_SB(1, 0), b3, voffB);
;             PG8_BAR; PG8_WAIT_L(0); PG8_MMA(0, 1, At, B1); PG8_BAR;
	s_waitcnt lgkmcnt(0)
	v_mfma_f32_16x16x32_bf16 v[116:119], v[202:205], v[168:171], v[116:119]
	v_mfma_f32_16x16x32_bf16 v[108:111], v[210:213], v[168:171], v[108:111]
	v_mfma_f32_16x16x32_bf16 v[100:103], v[202:205], v[176:179], v[100:103]
	v_mfma_f32_16x16x32_bf16 v[92:95], v[210:213], v[176:179], v[92:95]
	v_mfma_f32_16x16x32_bf16 v[84:87], v[202:205], v[184:187], v[84:87]
	v_mfma_f32_16x16x32_bf16 v[76:79], v[210:213], v[184:187], v[76:79]
	v_mfma_f32_16x16x32_bf16 v[68:71], v[202:205], v[192:195], v[68:71]
	v_mfma_f32_16x16x32_bf16 v[64:67], v[210:213], v[192:195], v[64:67]
	v_mfma_f32_16x16x32_bf16 v[116:119], v[206:209], v[172:175], v[116:119]
	v_mfma_f32_16x16x32_bf16 v[108:111], v[214:217], v[172:175], v[108:111]
	v_mfma_f32_16x16x32_bf16 v[100:103], v[206:209], v[180:183], v[100:103]
	v_mfma_f32_16x16x32_bf16 v[92:95], v[214:217], v[180:183], v[92:95]
	v_mfma_f32_16x16x32_bf16 v[84:87], v[206:209], v[188:191], v[84:87]
	v_mfma_f32_16x16x32_bf16 v[76:79], v[214:217], v[188:191], v[76:79]
	v_mfma_f32_16x16x32_bf16 v[68:71], v[206:209], v[196:199], v[68:71]
	v_mfma_f32_16x16x32_bf16 v[64:67], v[214:217], v[196:199], v[64:67]
	s_setprio 0
	s_mov_b32 m0, s17
	v_lshl_add_u64 v[222:223], s[22:23], 0, v[128:129]
	s_barrier
	ds_read_b128 v[168:171], v150 offset:16384
	ds_read_b128 v[172:175], v150 offset:17408
	ds_read_b128 v[176:179], v150 offset:18432
	ds_read_b128 v[180:183], v150 offset:19456
	ds_read_b128 v[184:187], v150 offset:20480
	ds_read_b128 v[188:191], v150 offset:21504
	ds_read_b128 v[192:195], v150 offset:22528
	ds_read_b128 v[196:199], v150 offset:23552
	global_load_lds_dwordx4 v128, s[22:23]
	v_lshl_add_u64 v[224:225], s[22:23], 0, v[132:133]
	s_mov_b32 m0, s29
	s_nop 0
	global_load_lds_dwordx4 v132, s[22:23]
	s_setprio 1
	s_barrier
	s_waitcnt lgkmcnt(0)
	v_mfma_f32_16x16x32_bf16 v[60:63], v[152:155], v[168:171], v[60:63]
	v_mfma_f32_16x16x32_bf16 v[56:59], v[160:163], v[168:171], v[56:59]
	v_mfma_f32_16x16x32_bf16 v[48:51], v[152:155], v[176:179], v[48:51]
	v_mfma_f32_16x16x32_bf16 v[40:43], v[160:163], v[176:179], v[40:43]
	v_mfma_f32_16x16x32_bf16 v[32:35], v[152:155], v[184:187], v[32:35]
	v_mfma_f32_16x16x32_bf16 v[24:27], v[160:163], v[184:187], v[24:27]
	v_mfma_f32_16x16x32_bf16 v[16:19], v[152:155], v[192:195], v[16:19]
	v_mfma_f32_16x16x32_bf16 v[8:11], v[160:163], v[192:195], v[8:11]
	v_mfma_f32_16x16x32_bf16 v[60:63], v[156:159], v[172:175], v[60:63]
	v_mfma_f32_16x16x32_bf16 v[56:59], v[164:167], v[172:175], v[56:59]
	v_mfma_f32_16x16x32_bf16 v[48:51], v[156:159], v[180:183], v[48:51]
	v_mfma_f32_16x16x32_bf16 v[40:43], v[164:167], v[180:183], v[40:43]
	v_mfma_f32_16x16x32_bf16 v[32:35], v[156:159], v[188:191], v[32:35]
	v_mfma_f32_16x16x32_bf16 v[24:27], v[164:167], v[188:191], v[24:27]
	v_mfma_f32_16x16x32_bf16 v[16:19], v[156:159], v[196:199], v[16:19]
	v_mfma_f32_16x16x32_bf16 v[8:11], v[164:167], v[196:199], v[8:11]
	s_setprio 0
	s_barrier
	s_add_u32 s52, s20, 0x40000
	s_addc_u32 s53, s21, 0
	s_add_i32 s54, s44, s28
	s_mov_b32 m0, s54
	s_nop 0
	global_load_lds_dwordx4 v130, s[52:53]
	s_add_i32 m0, s54, 0x2000
	s_nop 0
	global_load_lds_dwordx4 v134, s[52:53]
	s_add_u32 s22, s22, 0x40000
	s_addc_u32 s23, s23, 0
	s_mov_b32 m0, s30
	s_nop 0
	global_load_lds_dwordx4 v128, s[22:23]
	s_mov_b32 m0, s31
	s_nop 0
	global_load_lds_dwordx4 v132, s[22:23]
	s_waitcnt vmcnt(10)
	s_setprio 1
	s_barrier
	v_mfma_f32_16x16x32_bf16 v[52:55], v[202:205], v[168:171], v[52:55]
	v_mfma_f32_16x16x32_bf16 v[44:47], v[210:213], v[168:171], v[44:47]
	v_mfma_f32_16x16x32_bf16 v[36:39], v[202:205], v[176:179], v[36:39]
	v_mfma_f32_16x16x32_bf16 v[28:31], v[210:213], v[176:179], v[28:31]
	v_mfma_f32_16x16x32_bf16 v[20:23], v[202:205], v[184:187], v[20:23]
	v_mfma_f32_16x16x32_bf16 v[12:15], v[210:213], v[184:187], v[12:15]
	v_mfma_f32_16x16x32_bf16 v[4:7], v[202:205], v[192:195], v[4:7]
	v_mfma_f32_16x16x32_bf16 v[0:3], v[210:213], v[192:195], v[0:3]
	v_mfma_f32_16x16x32_bf16 v[52:55], v[206:209], v[172:175], v[52:55]
	v_mfma_f32_16x16x32_bf16 v[44:47], v[214:217], v[172:175], v[44:47]
	v_mfma_f32_16x16x32_bf16 v[36:39], v[206:209], v[180:183], v[36:39]
	v_mfma_f32_16x16x32_bf16 v[28:31], v[214:217], v[180:183], v[28:31]
	v_mfma_f32_16x16x32_bf16 v[20:23], v[206:209], v[188:191], v[20:23]
	v_mfma_f32_16x16x32_bf16 v[12:15], v[214:217], v[188:191], v[12:15]
	v_mfma_f32_16x16x32_bf16 v[4:7], v[206:209], v[196:199], v[4:7]
	v_mfma_f32_16x16x32_bf16 v[0:3], v[214:217], v[196:199], v[0:3]
	s_setprio 0
	s_add_i32 s52, 0, 0x18000
	v_add_u32_e32 v136, s52, v148
	s_barrier
	ds_read_b128 v[152:155], v136
	ds_read_b128 v[156:159], v136 offset:1024
	ds_read_b128 v[160:163], v136 offset:2048
	ds_read_b128 v[164:167], v136 offset:3072
	ds_read_b128 v[168:171], v150 offset:32768
	ds_read_b128 v[172:175], v150 offset:33792
	ds_read_b128 v[176:179], v150 offset:34816
	ds_read_b128 v[180:183], v150 offset:35840
	ds_read_b128 v[184:187], v150 offset:36864
	ds_read_b128 v[188:191], v150 offset:37888
	ds_read_b128 v[192:195], v150 offset:38912
	ds_read_b128 v[196:199], v150 offset:39936
	s_waitcnt lgkmcnt(8)
	s_waitcnt vmcnt(8)
	s_setprio 1
	s_barrier
; #define PG8_STAGE(bufoff, gbase, voff) do { _Pragma("unroll") for (int _i = 0; _i < 2; ++_i) \
;         __builtin_amdgcn_global_load_lds((const unsigned*)((const char*)(gbase) + (voff)[_i]), (LAS unsigned*)(lds + (bufoff) + ldsw + _i * 8192), 16, 0, 0); } while (0)
; #define PG8_LDA(dst, b, h) do { _Pragma("unroll") for (int m = 0; m < 4; ++m) _Pragma("unroll") for (int k = 0; k < 2; ++k) dst[m][k] = *(const LAS bf16x8*)(lds + PG8_SA(b, h) + aoff + m * 2048 + k * 1024); } while (0)
; #define PG8_LDB(dst, b, h) do { _Pragma("unroll") for (int n = 0; n < 2; ++n) _Pragma("unroll") for (int k = 0; k < 2; ++k) dst[n][k] = *(const LAS bf16x8*)(lds + PG8_SB(b, h) + boff + n * 2048 + k * 1024); } while (0)
; #define PG8_MMA(ai, bj, At, Bt) do { __builtin_amdgcn_s_setprio(1); _Pragma("unroll") for (int m = 0; m < 4; ++m) _Pragma("unroll") for (int n = 0; n < 2; ++n) _Pragma("unroll") for (int k = 0; k < 2; ++k) \
;         acc[ai][bj][m][n] = __builtin_amdgcn_mfma_f32_16x16x32_bf16(Bt[n][k], At[m][k], acc[ai][bj][m][n], 0, 0, 0); __builtin_amdgcn_s_setprio(0); } while (0)
; #define PG8_WAIT_V(n) asm volatile("s_waitcnt vmcnt(" #n ")" ::: "memory")
; #define PG8_WAIT_L(n) asm volatile("s_waitcnt lgkmcnt(" #n ")" ::: "memory")
; #define PG8_BAR __builtin_amdgcn_s_barrier()
; #define PG8_SCHED __builtin_amdgcn_sched_barrier(0)
; template <class Epi, class Sched>
; __device__ __forceinline__ void gemm_phase(LAS unsigned char* lds, const Gemm g, const Sched& S, const Epi& E) {
;     ...
;             PG8_WAIT_L(8); PG8_BAR; PG8_WAIT_L(0); PG8_MMA(0, 0, At, B0); PG8_BAR; PG8_SCHED;
;             PG8_LDB(B1, 1, 1); PG8_STAGE(PG8_SB(1, 0), b3, voffB);
;             PG8_BAR; PG8_WAIT_L(0); PG8_MMA(0, 1, At, B1); PG8_BAR;
;             PG8_LDA(At, 1, 1); PG8_STAGE(PG8_SA(1, 0), a3, voffA);
;             PG8_BAR; PG8_WAIT_L(0); PG8_MMA(1, 0, At, B0); PG8_BAR; PG8_SCHED;
;             PG8_STAGE(PG8_SB(1, 1), b3 + hstep, voffB);
;             PG8_WAIT_V(6); PG8_BAR; PG8_MMA(1, 1, At, B1); PG8_BAR;
	s_waitcnt lgkmcnt(0)
	v_mfma_f32_16x16x32_bf16 v[124:127], v[152:155], v[168:171], v[124:127]
	v_mfma_f32_16x16x32_bf16 v[120:123], v[160:163], v[168:171], v[120:123]
	v_mfma_f32_16x16x32_bf16 v[112:115], v[152:155], v[176:179], v[112:115]
	v_mfma_f32_16x16x32_bf16 v[104:107], v[160:163], v[176:179], v[104:107]
	v_mfma_f32_16x16x32_bf16 v[96:99], v[152:155], v[184:187], v[96:99]
	v_mfma_f32_16x16x32_bf16 v[88:91], v[160:163], v[184:187], v[88:91]
	v_mfma_f32_16x16x32_bf16 v[80:83], v[152:155], v[192:195], v[80:83]
	v_mfma_f32_16x16x32_bf16 v[72:75], v[160:163], v[192:195], v[72:75]
	v_mfma_f32_16x16x32_bf16 v[124:127], v[156:159], v[172:175], v[124:127]
	v_mfma_f32_16x16x32_bf16 v[120:123], v[164:167], v[172:175], v[120:123]
	v_mfma_f32_16x16x32_bf16 v[112:115], v[156:159], v[180:183], v[112:115]
	v_mfma_f32_16x16x32_bf16 v[104:107], v[164:167], v[180:183], v[104:107]
	v_mfma_f32_16x16x32_bf16 v[96:99], v[156:159], v[188:191], v[96:99]
	v_mfma_f32_16x16x32_bf16 v[88:91], v[164:167], v[188:191], v[88:91]
	v_mfma_f32_16x16x32_bf16 v[80:83], v[156:159], v[196:199], v[80:83]
	v_mfma_f32_16x16x32_bf16 v[72:75], v[164:167], v[196:199], v[72:75]
	s_setprio 0
	s_barrier
	s_add_i32 s22, 0, 0x1c000
	s_add_i32 s23, s52, s28
	v_add_u32_e32 v136, s22, v148
	s_add_u32 s0, s20, 0x80
	s_addc_u32 s1, s21, 0
	s_mov_b32 m0, s23
	ds_read_b128 v[202:205], v136
	ds_read_b128 v[206:209], v136 offset:1024
	ds_read_b128 v[210:213], v136 offset:2048
	ds_read_b128 v[214:217], v136 offset:3072
	global_load_lds_dwordx4 v130, s[0:1]
	s_add_i32 m0, s23, 0x2000
	s_nop 0
	global_load_lds_dwordx4 v134, s[0:1]
	s_waitcnt vmcnt(8)
	s_setprio 1
	s_barrier
	s_waitcnt lgkmcnt(0)
	v_mfma_f32_16x16x32_bf16 v[116:119], v[202:205], v[168:171], v[116:119]
	v_mfma_f32_16x16x32_bf16 v[108:111], v[210:213], v[168:171], v[108:111]
	v_mfma_f32_16x16x32_bf16 v[100:103], v[202:205], v[176:179], v[100:103]
	v_mfma_f32_16x16x32_bf16 v[92:95], v[210:213], v[176:179], v[92:95]
	v_mfma_f32_16x16x32_bf16 v[84:87], v[202:205], v[184:187], v[84:87]
	v_mfma_f32_16x16x32_bf16 v[76:79], v[210:213], v[184:187], v[76:79]
	v_mfma_f32_16x16x32_bf16 v[68:71], v[202:205], v[192:195], v[68:71]
	v_mfma_f32_16x16x32_bf16 v[64:67], v[210:213], v[192:195], v[64:67]
	v_mfma_f32_16x16x32_bf16 v[116:119], v[206:209], v[172:175], v[116:119]
	v_mfma_f32_16x16x32_bf16 v[108:111], v[214:217], v[172:175], v[108:111]
	v_mfma_f32_16x16x32_bf16 v[100:103], v[206:209], v[180:183], v[100:103]
	v_mfma_f32_16x16x32_bf16 v[92:95], v[214:217], v[180:183], v[92:95]
	v_mfma_f32_16x16x32_bf16 v[84:87], v[206:209], v[188:191], v[84:87]
	v_mfma_f32_16x16x32_bf16 v[76:79], v[214:217], v[188:191], v[76:79]
	v_mfma_f32_16x16x32_bf16 v[68:71], v[206:209], v[196:199], v[68:71]
	v_mfma_f32_16x16x32_bf16 v[64:67], v[214:217], v[196:199], v[64:67]
	s_setprio 0
	s_mov_b32 m0, s36
	s_mov_b64 s[0:1], 0x80
	v_lshl_add_u64 v[218:219], v[222:223], 0, s[0:1]
	s_barrier
	ds_read_b128 v[168:171], v150 offset:49152
	ds_read_b128 v[172:175], v150 offset:50176
	ds_read_b128 v[176:179], v150 offset:51200
	ds_read_b128 v[180:183], v150 offset:52224
	ds_read_b128 v[184:187], v150 offset:53248
	ds_read_b128 v[188:191], v150 offset:54272
	ds_read_b128 v[192:195], v150 offset:55296
	ds_read_b128 v[196:199], v150 offset:56320
	global_load_lds_dwordx4 v[218:219], off
	v_lshl_add_u64 v[218:219], v[224:225], 0, s[0:1]
	s_mov_b32 m0, s37
	s_nop 0
	global_load_lds_dwordx4 v[218:219], off
	s_setprio 1
	s_barrier
	s_waitcnt lgkmcnt(0)
	v_mfma_f32_16x16x32_bf16 v[60:63], v[152:155], v[168:171], v[60:63]
	v_mfma_f32_16x16x32_bf16 v[56:59], v[160:163], v[168:171], v[56:59]
	v_mfma_f32_16x16x32_bf16 v[48:51], v[152:155], v[176:179], v[48:51]
	v_mfma_f32_16x16x32_bf16 v[40:43], v[160:163], v[176:179], v[40:43]
	v_mfma_f32_16x16x32_bf16 v[32:35], v[152:155], v[184:187], v[32:35]
	v_mfma_f32_16x16x32_bf16 v[24:27], v[160:163], v[184:187], v[24:27]
	v_mfma_f32_16x16x32_bf16 v[16:19], v[152:155], v[192:195], v[16:19]
	v_mfma_f32_16x16x32_bf16 v[8:11], v[160:163], v[192:195], v[8:11]
	v_mfma_f32_16x16x32_bf16 v[60:63], v[156:159], v[172:175], v[60:63]
	v_mfma_f32_16x16x32_bf16 v[56:59], v[164:167], v[172:175], v[56:59]
	v_mfma_f32_16x16x32_bf16 v[48:51], v[156:159], v[180:183], v[48:51]
	v_mfma_f32_16x16x32_bf16 v[40:43], v[164:167], v[180:183], v[40:43]
	v_mfma_f32_16x16x32_bf16 v[32:35], v[156:159], v[188:191], v[32:35]
	v_mfma_f32_16x16x32_bf16 v[24:27], v[164:167], v[188:191], v[24:27]
	v_mfma_f32_16x16x32_bf16 v[16:19], v[156:159], v[196:199], v[16:19]
	v_mfma_f32_16x16x32_bf16 v[8:11], v[164:167], v[196:199], v[8:11]
	s_setprio 0
	s_barrier
	s_add_u32 s20, s20, 0x40080
	s_addc_u32 s21, s21, 0
	s_add_i32 s22, s22, s28
	s_mov_b32 m0, s22
	s_nop 0
	global_load_lds_dwordx4 v130, s[20:21]
	s_add_i32 m0, s22, 0x2000
	s_nop 0
	global_load_lds_dwordx4 v134, s[20:21]
	s_waitcnt vmcnt(8)
	s_setprio 1
	s_barrier
	v_mfma_f32_16x16x32_bf16 v[52:55], v[202:205], v[168:171], v[52:55]
	v_mfma_f32_16x16x32_bf16 v[44:47], v[210:213], v[168:171], v[44:47]
	v_mfma_f32_16x16x32_bf16 v[36:39], v[202:205], v[176:179], v[36:39]
	v_mfma_f32_16x16x32_bf16 v[28:31], v[210:213], v[176:179], v[28:31]
	v_mfma_f32_16x16x32_bf16 v[20:23], v[202:205], v[184:187], v[20:23]
	v_mfma_f32_16x16x32_bf16 v[12:15], v[210:213], v[184:187], v[12:15]
	v_mfma_f32_16x16x32_bf16 v[4:7], v[202:205], v[192:195], v[4:7]
	v_mfma_f32_16x16x32_bf16 v[0:3], v[210:213], v[192:195], v[0:3]
	v_mfma_f32_16x16x32_bf16 v[52:55], v[206:209], v[172:175], v[52:55]
	v_mfma_f32_16x16x32_bf16 v[44:47], v[214:217], v[172:175], v[44:47]
	v_mfma_f32_16x16x32_bf16 v[36:39], v[206:209], v[180:183], v[36:39]
	v_mfma_f32_16x16x32_bf16 v[28:31], v[214:217], v[180:183], v[28:31]
	v_mfma_f32_16x16x32_bf16 v[20:23], v[206:209], v[188:191], v[20:23]
	v_mfma_f32_16x16x32_bf16 v[12:15], v[214:217], v[188:191], v[12:15]
	v_mfma_f32_16x16x32_bf16 v[4:7], v[206:209], v[196:199], v[4:7]
	v_mfma_f32_16x16x32_bf16 v[0:3], v[214:217], v[196:199], v[0:3]
	s_setprio 0
	s_add_i32 s51, s51, 2
	s_add_u32 s18, s18, 0x100
	s_addc_u32 s19, s19, 0
	s_add_u32 s48, s48, 0x100
	s_addc_u32 s49, s49, 0
	s_cmp_gt_u32 s51, 13
	s_barrier
; __device__ __forceinline__ unsigned cvt_pk_bf16(float lo, float hi) { unsigned r; asm volatile("v_cvt_pk_bf16_f32 %0, %1, %2" : "=v"(r) : "v"(lo), "v"(hi)); return r; }
;     __device__ __forceinline__ void operator()(const AccT& acc, const Unit& u, int wr, int wc, int fr, int fq) const {
;     ...
;         const int rbase = u.pm * 256 + wr * 64 + fr;
;         const int tb = u.pn * 256 + wc * 32 + 8 * fq;
; #pragma unroll
;         for (int ai = 0; ai < 2; ++ai)
; #pragma unroll
;             for (int m = 0; m < 4; ++m) {
;                 const int gm = rbase + ai * 128 + m * 16;
; #pragma unroll
;                 for (int bj = 0; bj < 2; ++bj) {
;                     const int t0 = tb + bj * 128;
;                     const f32x4 v0 = acc[ai][bj][m][0], v1 = acc[ai][bj][m][1];
;                     u32x4 w; w.x = cvt_pk_bf16(v0[0], v0[1]); w.y = cvt_pk_bf16(v0[2], v0[3]); w.z = cvt_pk_bf16(v1[0], v1[1]); w.w = cvt_pk_bf16(v1[2], v1[3]);
;                     *(u32x4*)(YT + ((size_t)((t0 >> 10) * 512 + gm)) * 2048 + part * 1024 + (t0 & 1023)) = w;
;                 }
;             }
;     }
	s_cbranch_scc0 .LBB0_673
	v_mov_b32_e32 v136, v147
	v_mov_b32_e32 v152, v146
	s_lshl_b32 s7, s16, 8
	s_add_i32 s7, s7, s34
	v_add_u32_e32 v152, s7, v152
	s_lshl_b32 s7, s45, 8
	s_or_b32 s7, s7, s35
	v_lshl_add_u32 v153, v136, 3, s7
	v_cvt_pk_bf16_f32 v124, v124, v125
	v_cvt_pk_bf16_f32 v125, v126, v127
	v_cvt_pk_bf16_f32 v126, v120, v121
	v_ashrrev_i32_e32 v120, 1, v153
	v_cvt_pk_bf16_f32 v127, v122, v123
	v_and_b32_e32 v122, 0xfffffe00, v120
	v_add_u32_e32 v120, v122, v152
	v_ashrrev_i32_e32 v121, 31, v120
	v_lshlrev_b64 v[120:121], 12, v[120:121]
	v_and_b32_e32 v123, 0x3f8, v153
	v_lshl_add_u64 v[120:121], s[4:5], 0, v[120:121]
	v_lshlrev_b32_e32 v136, 1, v123
	v_lshl_add_u64 v[120:121], v[120:121], 0, v[136:137]
	global_store_dwordx4 v[120:121], v[124:127], off
	v_add_u32_e32 v120, 0x80, v153
	v_cvt_pk_bf16_f32 v116, v116, v117
	v_cvt_pk_bf16_f32 v117, v118, v119
	v_cvt_pk_bf16_f32 v118, v108, v109
	v_ashrrev_i32_e32 v108, 1, v120
	v_and_b32_e32 v121, 0xfffffe00, v108
	v_add_u32_e32 v108, v121, v152
	v_ashrrev_i32_e32 v109, 31, v108
	v_lshlrev_b64 v[108:109], 12, v[108:109]
	v_cvt_pk_bf16_f32 v119, v110, v111
	v_lshl_add_u64 v[110:111], s[4:5], 0, v[108:109]
	v_and_b32_e32 v108, 0x3f8, v120
	v_lshlrev_b32_e32 v108, 1, v108
	v_mov_b32_e32 v109, v137
	v_lshl_add_u64 v[110:111], v[110:111], 0, v[108:109]
	global_store_dwordx4 v[110:111], v[116:119], off
	v_cvt_pk_bf16_f32 v110, v112, v113
	v_cvt_pk_bf16_f32 v111, v114, v115
	v_cvt_pk_bf16_f32 v112, v104, v105
	v_cvt_pk_bf16_f32 v113, v106, v107
	s_and_b64 vcc, exec, s[2:3]
	s_nop 0
	v_add_u32_e32 v116, 16, v152
	v_add_u32_e32 v104, v122, v116
	v_ashrrev_i32_e32 v105, 31, v104
	v_lshlrev_b64 v[104:105], 12, v[104:105]
	v_lshl_add_u64 v[104:105], s[4:5], 0, v[104:105]
	v_lshl_add_u64 v[104:105], v[104:105], 0, v[136:137]
	global_store_dwordx4 v[104:105], v[110:113], off
	v_cvt_pk_bf16_f32 v100, v100, v101
	v_cvt_pk_bf16_f32 v101, v102, v103
	v_cvt_pk_bf16_f32 v102, v92, v93
	v_add_u32_e32 v92, v121, v116
	v_ashrrev_i32_e32 v93, 31, v92
	v_lshlrev_b64 v[92:93], 12, v[92:93]
	v_lshl_add_u64 v[92:93], s[4:5], 0, v[92:93]
	v_lshl_add_u64 v[92:93], v[92:93], 0, v[108:109]
	v_cvt_pk_bf16_f32 v103, v94, v95
	global_store_dwordx4 v[92:93], v[100:103], off
	v_cvt_pk_bf16_f32 v92, v96, v97
	v_cvt_pk_bf16_f32 v93, v98, v99
	v_cvt_pk_bf16_f32 v94, v88, v89
	v_cvt_pk_bf16_f32 v95, v90, v91
	s_mov_b32 s45, s6
	s_nop 0
	v_add_u32_e32 v100, 32, v152
	v_add_u32_e32 v88, v122, v100
	v_ashrrev_i32_e32 v89, 31, v88
	v_lshlrev_b64 v[88:89], 12, v[88:89]
	v_lshl_add_u64 v[88:89], s[4:5], 0, v[88:89]
	v_lshl_add_u64 v[88:89], v[88:89], 0, v[136:137]
	global_store_dwordx4 v[88:89], v[92:95], off
	v_cvt_pk_bf16_f32 v84, v84, v85
	v_cvt_pk_bf16_f32 v85, v86, v87
	v_cvt_pk_bf16_f32 v86, v76, v77
	v_add_u32_e32 v76, v121, v100
	v_ashrrev_i32_e32 v77, 31, v76
	v_lshlrev_b64 v[76:77], 12, v[76:77]
	v_lshl_add_u64 v[76:77], s[4:5], 0, v[76:77]
	v_lshl_add_u64 v[76:77], v[76:77], 0, v[108:109]
	v_cvt_pk_bf16_f32 v87, v78, v79
	global_store_dwordx4 v[76:77], v[84:87], off
	v_cvt_pk_bf16_f32 v76, v80, v81
	v_cvt_pk_bf16_f32 v77, v82, v83
	v_cvt_pk_bf16_f32 v78, v72, v73
	v_cvt_pk_bf16_f32 v79, v74, v75
	s_mov_b32 s16, s8
	s_nop 0
	v_add_u32_e32 v84, 48, v152
	v_add_u32_e32 v72, v122, v84
	v_ashrrev_i32_e32 v73, 31, v72
	v_lshlrev_b64 v[72:73], 12, v[72:73]
	v_lshl_add_u64 v[72:73], s[4:5], 0, v[72:73]
	v_lshl_add_u64 v[72:73], v[72:73], 0, v[136:137]
	global_store_dwordx4 v[72:73], v[76:79], off
	v_cvt_pk_bf16_f32 v68, v68, v69
	v_cvt_pk_bf16_f32 v69, v70, v71
	v_cvt_pk_bf16_f32 v70, v64, v65
	v_add_u32_e32 v64, v121, v84
	v_ashrrev_i32_e32 v65, 31, v64
	v_lshlrev_b64 v[64:65], 12, v[64:65]
	v_lshl_add_u64 v[64:65], s[4:5], 0, v[64:65]
	v_lshl_add_u64 v[64:65], v[64:65], 0, v[108:109]
	v_cvt_pk_bf16_f32 v71, v66, v67
	global_store_dwordx4 v[64:65], v[68:71], off
	v_add_u32_e32 v64, 0x80, v152
	v_cvt_pk_bf16_f32 v60, v60, v61
	v_cvt_pk_bf16_f32 v61, v62, v63
	v_cvt_pk_bf16_f32 v62, v56, v57
	v_add_u32_e32 v56, v122, v64
	v_ashrrev_i32_e32 v57, 31, v56
	v_lshlrev_b64 v[56:57], 12, v[56:57]
	v_lshl_add_u64 v[56:57], s[4:5], 0, v[56:57]
	v_lshl_add_u64 v[56:57], v[56:57], 0, v[136:137]
	v_cvt_pk_bf16_f32 v63, v58, v59
	global_store_dwordx4 v[56:57], v[60:63], off
	v_cvt_pk_bf16_f32 v52, v52, v53
	v_cvt_pk_bf16_f32 v53, v54, v55
	v_cvt_pk_bf16_f32 v54, v44, v45
	v_add_u32_e32 v44, v121, v64
	v_ashrrev_i32_e32 v45, 31, v44
	v_lshlrev_b64 v[44:45], 12, v[44:45]
	v_lshl_add_u64 v[44:45], s[4:5], 0, v[44:45]
	v_lshl_add_u64 v[44:45], v[44:45], 0, v[108:109]
	v_cvt_pk_bf16_f32 v55, v46, v47
	global_store_dwordx4 v[44:45], v[52:55], off
	v_cvt_pk_bf16_f32 v44, v48, v49
	v_cvt_pk_bf16_f32 v45, v50, v51
	v_cvt_pk_bf16_f32 v46, v40, v41
	v_cvt_pk_bf16_f32 v47, v42, v43
	s_mov_b64 s[20:21], s[14:15]
	s_nop 0
	v_add_u32_e32 v52, 0x90, v152
	v_add_u32_e32 v40, v122, v52
	v_ashrrev_i32_e32 v41, 31, v40
	v_lshlrev_b64 v[40:41], 12, v[40:41]
	v_lshl_add_u64 v[40:41], s[4:5], 0, v[40:41]
	v_lshl_add_u64 v[40:41], v[40:41], 0, v[136:137]
	global_store_dwordx4 v[40:41], v[44:47], off
	v_cvt_pk_bf16_f32 v36, v36, v37
	v_cvt_pk_bf16_f32 v37, v38, v39
	v_cvt_pk_bf16_f32 v38, v28, v29
	v_add_u32_e32 v28, v121, v52
	v_ashrrev_i32_e32 v29, 31, v28
	v_lshlrev_b64 v[28:29], 12, v[28:29]
	v_lshl_add_u64 v[28:29], s[4:5], 0, v[28:29]
	v_lshl_add_u64 v[28:29], v[28:29], 0, v[108:109]
	v_cvt_pk_bf16_f32 v39, v30, v31
	global_store_dwordx4 v[28:29], v[36:39], off
	v_cvt_pk_bf16_f32 v28, v32, v33
	v_cvt_pk_bf16_f32 v29, v34, v35
	v_cvt_pk_bf16_f32 v30, v24, v25
	v_cvt_pk_bf16_f32 v31, v26, v27
	s_mov_b64 s[18:19], s[12:13]
	s_nop 0
	v_add_u32_e32 v36, 0xa0, v152
	v_add_u32_e32 v24, v122, v36
	v_ashrrev_i32_e32 v25, 31, v24
	v_lshlrev_b64 v[24:25], 12, v[24:25]
	v_lshl_add_u64 v[24:25], s[4:5], 0, v[24:25]
	v_lshl_add_u64 v[24:25], v[24:25], 0, v[136:137]
	global_store_dwordx4 v[24:25], v[28:31], off
	v_cvt_pk_bf16_f32 v20, v20, v21
	v_cvt_pk_bf16_f32 v21, v22, v23
	v_cvt_pk_bf16_f32 v22, v12, v13
	v_add_u32_e32 v12, v121, v36
	v_ashrrev_i32_e32 v13, 31, v12
	v_lshlrev_b64 v[12:13], 12, v[12:13]
	v_lshl_add_u64 v[12:13], s[4:5], 0, v[12:13]
	v_lshl_add_u64 v[12:13], v[12:13], 0, v[108:109]
	v_cvt_pk_bf16_f32 v23, v14, v15
	global_store_dwordx4 v[12:13], v[20:23], off
	v_cvt_pk_bf16_f32 v12, v16, v17
	v_cvt_pk_bf16_f32 v13, v18, v19
	v_cvt_pk_bf16_f32 v14, v8, v9
	v_cvt_pk_bf16_f32 v15, v10, v11
	s_nop 1
	v_add_u32_e32 v20, 0xb0, v152
	v_add_u32_e32 v8, v122, v20
	v_ashrrev_i32_e32 v9, 31, v8
	v_lshlrev_b64 v[8:9], 12, v[8:9]
	v_lshl_add_u64 v[8:9], s[4:5], 0, v[8:9]
	v_lshl_add_u64 v[8:9], v[8:9], 0, v[136:137]
	global_store_dwordx4 v[8:9], v[12:15], off
	v_cvt_pk_bf16_f32 v4, v4, v5
	v_cvt_pk_bf16_f32 v5, v6, v7
	v_cvt_pk_bf16_f32 v6, v0, v1
	v_add_u32_e32 v0, v121, v20
	v_ashrrev_i32_e32 v1, 31, v0
	v_lshlrev_b64 v[0:1], 12, v[0:1]
	v_lshl_add_u64 v[0:1], s[4:5], 0, v[0:1]
	v_lshl_add_u64 v[0:1], v[0:1], 0, v[108:109]
	v_cvt_pk_bf16_f32 v7, v2, v3
	global_store_dwordx4 v[0:1], v[4:7], off
	s_cbranch_vccz .LBB0_666
; #define PG8_WAIT_V(n) asm volatile("s_waitcnt vmcnt(" #n ")" ::: "memory")
; #define PG8_BAR __builtin_amdgcn_s_barrier()
; template <class Epi, class Sched>
; __device__ __forceinline__ void gemm_phase(LAS unsigned char* lds, const Gemm g, const Sched& S, const Epi& E) {
;     ...
;     PG8_WAIT_V(0);
;     if (wr == 0) PG8_BAR;
;     PG8_BAR;
	s_waitcnt vmcnt(0)
	s_cmpk_gt_u32 s24, 0xff
	s_cbranch_scc1 .LBB0_677
	s_barrier

; #define PG8_STAGE(bufoff, gbase, voff) do { _Pragma("unroll") for (int _i = 0; _i < 2; ++_i) \
;         __builtin_amdgcn_global_load_lds((const unsigned*)((const char*)(gbase) + (voff)[_i]), (LAS unsigned*)(lds + (bufoff) + ldsw + _i * 8192), 16, 0, 0); } while (0)
; #define PG8_LDA(dst, b, h) do { _Pragma("unroll") for (int m = 0; m < 4; ++m) _Pragma("unroll") for (int k = 0; k < 2; ++k) dst[m][k] = *(const LAS bf16x8*)(lds + PG8_SA(b, h) + aoff + m * 2048 + k * 1024); } while (0)
; #define PG8_LDB(dst, b, h) do { _Pragma("unroll") for (int n = 0; n < 2; ++n) _Pragma("unroll") for (int k = 0; k < 2; ++k) dst[n][k] = *(const LAS bf16x8*)(lds + PG8_SB(b, h) + boff + n * 2048 + k * 1024); } while (0)
; #define PG8_MMA(ai, bj, At, Bt) do { __builtin_amdgcn_s_setprio(1); _Pragma("unroll") for (int m = 0; m < 4; ++m) _Pragma("unroll") for (int n = 0; n < 2; ++n) _Pragma("unroll") for (int k = 0; k < 2; ++k) \
;         acc[ai][bj][m][n] = __builtin_amdgcn_mfma_f32_16x16x32_bf16(Bt[n][k], At[m][k], acc[ai][bj][m][n], 0, 0, 0); __builtin_amdgcn_s_setprio(0); } while (0)
; #define PG8_WAIT_L(n) asm volatile("s_waitcnt lgkmcnt(" #n ")" ::: "memory")
; template <class Epi, class Sched>
; __device__ __forceinline__ void gemm_phase(LAS unsigned char* lds, const Gemm g, const Sched& S, const Epi& E) {
;     ...
;         const bool has_next = S.next(ui + 1, nxt);
;         const char* nA = has_next ? (const char*)g.A + (size_t)nxt.pm * tstep : cA; const char* nB = has_next ? (const char*)g.Bt + (size_t)nxt.pn * tstep : cB;
;         for (int t = 0; t < nt; t += 2) {
;             const bool last = (t == nt - 2);
;             const char* a1 = cA + (size_t)(t + 1) * kstep;
;             const char* a2 = last ? nA : cA + (size_t)(t + 2) * kstep; const char* b2 = last ? nB : cB + (size_t)(t + 2) * kstep;
;             const char* a3 = a2 + kstep; const char* b3 = b2 + kstep;
;             PG8_LDB(B0, 0, 0); PG8_SCHED; PG8_LDA(At, 0, 0); PG8_STAGE(PG8_SA(1, 1), a1 + hstep, voffA);
;             PG8_WAIT_L(8); PG8_BAR; PG8_WAIT_L(0); PG8_MMA(0, 0, At, B0); PG8_BAR; PG8_SCHED;
;             PG8_LDB(B1, 0, 1); PG8_STAGE(PG8_SB(0, 0), b2, voffB);
;             PG8_BAR; PG8_WAIT_L(0); PG8_MMA(0, 1, At, B1); PG8_BAR;
;             PG8_LDA(At, 0, 1); PG8_STAGE(PG8_SA(0, 0), a2, voffA);
;             PG8_BAR; PG8_WAIT_L(0); PG8_MMA(1, 0, At, B0); PG8_BAR; PG8_SCHED;
.LBB0_692:
	s_ashr_i32 s19, s18, 31
	v_cmp_lt_i64_e64 s[24:25], s[20:21], 32
	s_lshl_b64 s[20:21], s[18:19], 19
	s_add_u32 s20, s40, s20
	s_addc_u32 s21, s41, s21
	s_and_b64 s[22:23], s[24:25], exec
	s_cselect_b32 s19, s21, s3
	s_cselect_b32 s57, s20, s2
	s_ashr_i32 s17, s16, 31
	s_lshl_b64 s[22:23], s[16:17], 19
	s_add_u32 s22, s28, s22
	s_addc_u32 s23, s29, s23
	s_and_b64 s[24:25], s[24:25], exec
	s_cselect_b32 s17, s23, s5
	s_cselect_b32 s58, s22, s4
	s_add_u32 s2, s2, 0x40080
	s_addc_u32 s3, s3, 0
	s_add_u32 s59, s4, 0x100
	s_addc_u32 s60, s5, 0
	s_mov_b32 s61, -2
	s_waitcnt lgkmcnt(0)
	ds_read_b128 v[140:143], v149
	ds_read_b128 v[154:157], v149 offset:1024
	ds_read_b128 v[158:161], v149 offset:2048
	ds_read_b128 v[162:165], v149 offset:3072
	s_add_u32 s4, s2, 0xfffc0080
	s_addc_u32 s5, s3, -1
	s_cmp_eq_u32 s61, 12
	s_cselect_b32 s25, s19, s5
	s_cselect_b32 s24, s57, s4
	s_cselect_b32 s5, s17, s60
	s_cselect_b32 s4, s58, s59
	s_add_i32 m0, s33, 0xc000
	ds_read_b128 v[166:169], v150
	ds_read_b128 v[170:173], v150 offset:1024
	ds_read_b128 v[174:177], v150 offset:2048
	ds_read_b128 v[178:181], v150 offset:3072
	ds_read_b128 v[182:185], v150 offset:4096
	ds_read_b128 v[186:189], v150 offset:5120
	ds_read_b128 v[190:193], v150 offset:6144
	ds_read_b128 v[194:197], v150 offset:7168
	global_load_lds_dwordx4 v136, s[2:3]
	s_add_i32 m0, s33, 0xe000
	s_nop 0
	global_load_lds_dwordx4 v138, s[2:3]
	s_waitcnt lgkmcnt(8)
	s_waitcnt vmcnt(8)
	s_setprio 1
	s_barrier
	s_waitcnt lgkmcnt(0)
	v_mfma_f32_16x16x32_bf16 v[124:127], v[140:143], v[166:169], 0
	v_mfma_f32_16x16x32_bf16 v[120:123], v[158:161], v[166:169], 0
	v_mfma_f32_16x16x32_bf16 v[108:111], v[140:143], v[174:177], 0
	v_mfma_f32_16x16x32_bf16 v[104:107], v[158:161], v[174:177], 0
	v_mfma_f32_16x16x32_bf16 v[92:95], v[140:143], v[182:185], 0
	v_mfma_f32_16x16x32_bf16 v[88:91], v[158:161], v[182:185], 0
	v_mfma_f32_16x16x32_bf16 v[76:79], v[140:143], v[190:193], 0
	v_mfma_f32_16x16x32_bf16 v[72:75], v[158:161], v[190:193], 0
	v_mfma_f32_16x16x32_bf16 v[124:127], v[154:157], v[170:173], v[124:127]
	v_mfma_f32_16x16x32_bf16 v[120:123], v[162:165], v[170:173], v[120:123]
	v_mfma_f32_16x16x32_bf16 v[108:111], v[154:157], v[178:181], v[108:111]
	v_mfma_f32_16x16x32_bf16 v[104:107], v[162:165], v[178:181], v[104:107]
	v_mfma_f32_16x16x32_bf16 v[92:95], v[154:157], v[186:189], v[92:95]
	v_mfma_f32_16x16x32_bf16 v[88:91], v[162:165], v[186:189], v[88:91]
	v_mfma_f32_16x16x32_bf16 v[76:79], v[154:157], v[194:197], v[76:79]
	v_mfma_f32_16x16x32_bf16 v[72:75], v[162:165], v[194:197], v[72:75]
	s_setprio 0
	s_barrier
	s_add_i32 s62, s47, s31
	s_mov_b32 m0, s62
	ds_read_b128 v[202:205], v151
	ds_read_b128 v[206:209], v151 offset:1024
	ds_read_b128 v[210:213], v151 offset:2048
	ds_read_b128 v[214:217], v151 offset:3072
	global_load_lds_dwordx4 v130, s[4:5]
	s_add_i32 m0, s62, 0x2000
	s_nop 0
	global_load_lds_dwordx4 v134, s[4:5]
	s_waitcnt vmcnt(8)
	s_setprio 1
	s_barrier
	s_waitcnt lgkmcnt(0)
	v_mfma_f32_16x16x32_bf16 v[116:119], v[202:205], v[166:169], 0
	v_mfma_f32_16x16x32_bf16 v[112:115], v[210:213], v[166:169], 0
	v_mfma_f32_16x16x32_bf16 v[100:103], v[202:205], v[174:177], 0
	v_mfma_f32_16x16x32_bf16 v[96:99], v[210:213], v[174:177], 0
	v_mfma_f32_16x16x32_bf16 v[84:87], v[202:205], v[182:185], 0
	v_mfma_f32_16x16x32_bf16 v[80:83], v[210:213], v[182:185], 0
	v_mfma_f32_16x16x32_bf16 v[68:71], v[202:205], v[190:193], 0
	v_mfma_f32_16x16x32_bf16 v[64:67], v[210:213], v[190:193], 0
	v_mfma_f32_16x16x32_bf16 v[116:119], v[206:209], v[170:173], v[116:119]
	v_mfma_f32_16x16x32_bf16 v[112:115], v[214:217], v[170:173], v[112:115]
	v_mfma_f32_16x16x32_bf16 v[100:103], v[206:209], v[178:181], v[100:103]
	v_mfma_f32_16x16x32_bf16 v[96:99], v[214:217], v[178:181], v[96:99]
	v_mfma_f32_16x16x32_bf16 v[84:87], v[206:209], v[186:189], v[84:87]
	v_mfma_f32_16x16x32_bf16 v[80:83], v[214:217], v[186:189], v[80:83]
	v_mfma_f32_16x16x32_bf16 v[68:71], v[206:209], v[194:197], v[68:71]
	v_mfma_f32_16x16x32_bf16 v[64:67], v[214:217], v[194:197], v[64:67]
	s_setprio 0
	s_mov_b32 m0, s33
	v_lshl_add_u64 v[218:219], s[24:25], 0, v[128:129]
	s_barrier
	ds_read_b128 v[166:169], v150 offset:16384
	ds_read_b128 v[170:173], v150 offset:17408
	ds_read_b128 v[174:177], v150 offset:18432
	ds_read_b128 v[178:181], v150 offset:19456
	ds_read_b128 v[182:185], v150 offset:20480
	ds_read_b128 v[186:189], v150 offset:21504
	ds_read_b128 v[190:193], v150 offset:22528
	ds_read_b128 v[194:197], v150 offset:23552
	global_load_lds_dwordx4 v128, s[24:25]
	v_lshl_add_u64 v[220:221], s[24:25], 0, v[132:133]
	s_mov_b32 m0, s34
	s_nop 0
	global_load_lds_dwordx4 v132, s[24:25]
	s_setprio 1
	s_barrier
	s_waitcnt lgkmcnt(0)
	v_mfma_f32_16x16x32_bf16 v[60:63], v[140:143], v[166:169], 0
	v_mfma_f32_16x16x32_bf16 v[56:59], v[158:161], v[166:169], 0
	v_mfma_f32_16x16x32_bf16 v[44:47], v[140:143], v[174:177], 0
	v_mfma_f32_16x16x32_bf16 v[40:43], v[158:161], v[174:177], 0
	v_mfma_f32_16x16x32_bf16 v[28:31], v[140:143], v[182:185], 0
	v_mfma_f32_16x16x32_bf16 v[24:27], v[158:161], v[182:185], 0
	v_mfma_f32_16x16x32_bf16 v[12:15], v[140:143], v[190:193], 0
	v_mfma_f32_16x16x32_bf16 v[8:11], v[158:161], v[190:193], 0
	v_mfma_f32_16x16x32_bf16 v[60:63], v[154:157], v[170:173], v[60:63]
	v_mfma_f32_16x16x32_bf16 v[56:59], v[162:165], v[170:173], v[56:59]
	v_mfma_f32_16x16x32_bf16 v[44:47], v[154:157], v[178:181], v[44:47]
	v_mfma_f32_16x16x32_bf16 v[40:43], v[162:165], v[178:181], v[40:43]
	v_mfma_f32_16x16x32_bf16 v[28:31], v[154:157], v[186:189], v[28:31]
	v_mfma_f32_16x16x32_bf16 v[24:27], v[162:165], v[186:189], v[24:27]
	v_mfma_f32_16x16x32_bf16 v[12:15], v[154:157], v[194:197], v[12:15]
	v_mfma_f32_16x16x32_bf16 v[8:11], v[162:165], v[194:197], v[8:11]
	s_setprio 0
	s_barrier
; #define PG8_STAGE(bufoff, gbase, voff) do { _Pragma("unroll") for (int _i = 0; _i < 2; ++_i) \
;         __builtin_amdgcn_global_load_lds((const unsigned*)((const char*)(gbase) + (voff)[_i]), (LAS unsigned*)(lds + (bufoff) + ldsw + _i * 8192), 16, 0, 0); } while (0)
; #define PG8_LDA(dst, b, h) do { _Pragma("unroll") for (int m = 0; m < 4; ++m) _Pragma("unroll") for (int k = 0; k < 2; ++k) dst[m][k] = *(const LAS bf16x8*)(lds + PG8_SA(b, h) + aoff + m * 2048 + k * 1024); } while (0)
; #define PG8_LDB(dst, b, h) do { _Pragma("unroll") for (int n = 0; n < 2; ++n) _Pragma("unroll") for (int k = 0; k < 2; ++k) dst[n][k] = *(const LAS bf16x8*)(lds + PG8_SB(b, h) + boff + n * 2048 + k * 1024); } while (0)
; #define PG8_MMA(ai, bj, At, Bt) do { __builtin_amdgcn_s_setprio(1); _Pragma("unroll") for (int m = 0; m < 4; ++m) _Pragma("unroll") for (int n = 0; n < 2; ++n) _Pragma("unroll") for (int k = 0; k < 2; ++k) \
;         acc[ai][bj][m][n] = __builtin_amdgcn_mfma_f32_16x16x32_bf16(Bt[n][k], At[m][k], acc[ai][bj][m][n], 0, 0, 0); __builtin_amdgcn_s_setprio(0); } while (0)
; #define PG8_WAIT_V(n) asm volatile("s_waitcnt vmcnt(" #n ")" ::: "memory")
; #define PG8_WAIT_L(n) asm volatile("s_waitcnt lgkmcnt(" #n ")" ::: "memory")
; #define PG8_BAR __builtin_amdgcn_s_barrier()
; #define PG8_SCHED __builtin_amdgcn_sched_barrier(0)
; template <class Epi, class Sched>
; __device__ __forceinline__ void gemm_phase(LAS unsigned char* lds, const Gemm g, const Sched& S, const Epi& E) {
;     ...
;             PG8_STAGE(PG8_SB(0, 1), b2 + hstep, voffB);
;             PG8_WAIT_V(6); PG8_BAR; PG8_MMA(1, 1, At, B1); PG8_BAR;
;             PG8_LDB(B0, 1, 0); PG8_SCHED; PG8_LDA(At, 1, 0); PG8_STAGE(PG8_SA(0, 1), a2 + hstep, voffA);
;             PG8_WAIT_L(8); PG8_BAR; PG8_WAIT_L(0); PG8_MMA(0, 0, At, B0); PG8_BAR; PG8_SCHED;
;             PG8_LDB(B1, 1, 1); PG8_STAGE(PG8_SB(1, 0), b3, voffB);
;             PG8_BAR; PG8_WAIT_L(0); PG8_MMA(0, 1, At, B1); PG8_BAR;
;             PG8_LDA(At, 1, 1); PG8_STAGE(PG8_SA(1, 0), a3, voffA);
;             PG8_BAR; PG8_WAIT_L(0); PG8_MMA(1, 0, At, B0); PG8_BAR; PG8_SCHED;
	s_add_u32 s62, s4, 0x40000
	s_addc_u32 s63, s5, 0
	s_add_i32 s64, s48, s31
	s_mov_b32 m0, s64
	s_nop 0
	global_load_lds_dwordx4 v130, s[62:63]
	s_add_i32 m0, s64, 0x2000
	s_nop 0
	global_load_lds_dwordx4 v134, s[62:63]
	s_add_u32 s24, s24, 0x40000
	s_addc_u32 s25, s25, 0
	s_mov_b32 m0, s35
	s_nop 0
	global_load_lds_dwordx4 v128, s[24:25]
	s_mov_b32 m0, s36
	s_nop 0
	global_load_lds_dwordx4 v132, s[24:25]
	s_waitcnt vmcnt(10)
	s_setprio 1
	s_barrier
	v_mfma_f32_16x16x32_bf16 v[52:55], v[202:205], v[166:169], 0
	v_mfma_f32_16x16x32_bf16 v[48:51], v[210:213], v[166:169], 0
	v_mfma_f32_16x16x32_bf16 v[36:39], v[202:205], v[174:177], 0
	v_mfma_f32_16x16x32_bf16 v[32:35], v[210:213], v[174:177], 0
	v_mfma_f32_16x16x32_bf16 v[20:23], v[202:205], v[182:185], 0
	v_mfma_f32_16x16x32_bf16 v[16:19], v[210:213], v[182:185], 0
	v_mfma_f32_16x16x32_bf16 v[4:7], v[202:205], v[190:193], 0
	v_mfma_f32_16x16x32_bf16 v[0:3], v[210:213], v[190:193], 0
	v_mfma_f32_16x16x32_bf16 v[52:55], v[206:209], v[170:173], v[52:55]
	v_mfma_f32_16x16x32_bf16 v[48:51], v[214:217], v[170:173], v[48:51]
	v_mfma_f32_16x16x32_bf16 v[36:39], v[206:209], v[178:181], v[36:39]
	v_mfma_f32_16x16x32_bf16 v[32:35], v[214:217], v[178:181], v[32:35]
	v_mfma_f32_16x16x32_bf16 v[20:23], v[206:209], v[186:189], v[20:23]
	v_mfma_f32_16x16x32_bf16 v[16:19], v[214:217], v[186:189], v[16:19]
	v_mfma_f32_16x16x32_bf16 v[4:7], v[206:209], v[194:197], v[4:7]
	v_mfma_f32_16x16x32_bf16 v[0:3], v[214:217], v[194:197], v[0:3]
	s_setprio 0
	s_add_i32 s62, 0, 0x18000
	v_add_u32_e32 v162, s62, v148
	s_barrier
	ds_read_b128 v[140:143], v162
	ds_read_b128 v[154:157], v162 offset:1024
	ds_read_b128 v[158:161], v162 offset:2048
	ds_read_b128 v[162:165], v162 offset:3072
	ds_read_b128 v[166:169], v150 offset:32768
	ds_read_b128 v[170:173], v150 offset:33792
	ds_read_b128 v[174:177], v150 offset:34816
	ds_read_b128 v[178:181], v150 offset:35840
	ds_read_b128 v[182:185], v150 offset:36864
	ds_read_b128 v[186:189], v150 offset:37888
	ds_read_b128 v[190:193], v150 offset:38912
	ds_read_b128 v[194:197], v150 offset:39936
	s_waitcnt lgkmcnt(8)
	s_waitcnt vmcnt(8)
	s_setprio 1
	s_barrier
	s_waitcnt lgkmcnt(0)
	v_mfma_f32_16x16x32_bf16 v[124:127], v[140:143], v[166:169], v[124:127]
	v_mfma_f32_16x16x32_bf16 v[120:123], v[158:161], v[166:169], v[120:123]
	v_mfma_f32_16x16x32_bf16 v[108:111], v[140:143], v[174:177], v[108:111]
	v_mfma_f32_16x16x32_bf16 v[104:107], v[158:161], v[174:177], v[104:107]
	v_mfma_f32_16x16x32_bf16 v[92:95], v[140:143], v[182:185], v[92:95]
	v_mfma_f32_16x16x32_bf16 v[88:91], v[158:161], v[182:185], v[88:91]
	v_mfma_f32_16x16x32_bf16 v[76:79], v[140:143], v[190:193], v[76:79]
	v_mfma_f32_16x16x32_bf16 v[72:75], v[158:161], v[190:193], v[72:75]
	v_mfma_f32_16x16x32_bf16 v[124:127], v[154:157], v[170:173], v[124:127]
	v_mfma_f32_16x16x32_bf16 v[120:123], v[162:165], v[170:173], v[120:123]
	v_mfma_f32_16x16x32_bf16 v[108:111], v[154:157], v[178:181], v[108:111]
	v_mfma_f32_16x16x32_bf16 v[104:107], v[162:165], v[178:181], v[104:107]
	v_mfma_f32_16x16x32_bf16 v[92:95], v[154:157], v[186:189], v[92:95]
	v_mfma_f32_16x16x32_bf16 v[88:91], v[162:165], v[186:189], v[88:91]
	v_mfma_f32_16x16x32_bf16 v[76:79], v[154:157], v[194:197], v[76:79]
	v_mfma_f32_16x16x32_bf16 v[72:75], v[162:165], v[194:197], v[72:75]
	s_setprio 0
	s_barrier
	s_add_i32 s24, 0, 0x1c000
	s_add_i32 s25, s62, s31
	v_add_u32_e32 v214, s24, v148
	s_add_u32 s0, s4, 0x80
	s_addc_u32 s1, s5, 0
	s_mov_b32 m0, s25
	ds_read_b128 v[202:205], v214
	ds_read_b128 v[206:209], v214 offset:1024
	ds_read_b128 v[210:213], v214 offset:2048
	ds_read_b128 v[214:217], v214 offset:3072
	global_load_lds_dwordx4 v130, s[0:1]
	s_add_i32 m0, s25, 0x2000
	s_nop 0
	global_load_lds_dwordx4 v134, s[0:1]
	s_waitcnt vmcnt(8)
	s_setprio 1
	s_barrier
	s_waitcnt lgkmcnt(0)
	v_mfma_f32_16x16x32_bf16 v[116:119], v[202:205], v[166:169], v[116:119]
	v_mfma_f32_16x16x32_bf16 v[112:115], v[210:213], v[166:169], v[112:115]
	v_mfma_f32_16x16x32_bf16 v[100:103], v[202:205], v[174:177], v[100:103]
	v_mfma_f32_16x16x32_bf16 v[96:99], v[210:213], v[174:177], v[96:99]
	v_mfma_f32_16x16x32_bf16 v[84:87], v[202:205], v[182:185], v[84:87]
	v_mfma_f32_16x16x32_bf16 v[80:83], v[210:213], v[182:185], v[80:83]
	v_mfma_f32_16x16x32_bf16 v[68:71], v[202:205], v[190:193], v[68:71]
	v_mfma_f32_16x16x32_bf16 v[64:67], v[210:213], v[190:193], v[64:67]
	v_mfma_f32_16x16x32_bf16 v[116:119], v[206:209], v[170:173], v[116:119]
	v_mfma_f32_16x16x32_bf16 v[112:115], v[214:217], v[170:173], v[112:115]
	v_mfma_f32_16x16x32_bf16 v[100:103], v[206:209], v[178:181], v[100:103]
	v_mfma_f32_16x16x32_bf16 v[96:99], v[214:217], v[178:181], v[96:99]
	v_mfma_f32_16x16x32_bf16 v[84:87], v[206:209], v[186:189], v[84:87]
	v_mfma_f32_16x16x32_bf16 v[80:83], v[214:217], v[186:189], v[80:83]
	v_mfma_f32_16x16x32_bf16 v[68:71], v[206:209], v[194:197], v[68:71]
	v_mfma_f32_16x16x32_bf16 v[64:67], v[214:217], v[194:197], v[64:67]
	s_setprio 0
	s_mov_b32 m0, s44
	s_mov_b64 s[0:1], 0x80
	v_lshl_add_u64 v[144:145], v[218:219], 0, s[0:1]
	s_barrier
	ds_read_b128 v[166:169], v150 offset:49152
	ds_read_b128 v[170:173], v150 offset:50176
	ds_read_b128 v[174:177], v150 offset:51200
	ds_read_b128 v[178:181], v150 offset:52224
	ds_read_b128 v[182:185], v150 offset:53248
	ds_read_b128 v[186:189], v150 offset:54272
	ds_read_b128 v[190:193], v150 offset:55296
	ds_read_b128 v[194:197], v150 offset:56320
	global_load_lds_dwordx4 v[144:145], off
	v_lshl_add_u64 v[144:145], v[220:221], 0, s[0:1]
	s_mov_b32 m0, s45
	s_nop 0
	global_load_lds_dwordx4 v[144:145], off
	s_setprio 1
	s_barrier
; #define PG8_STAGE(bufoff, gbase, voff) do { _Pragma("unroll") for (int _i = 0; _i < 2; ++_i) \
;         __builtin_amdgcn_global_load_lds((const unsigned*)((const char*)(gbase) + (voff)[_i]), (LAS unsigned*)(lds + (bufoff) + ldsw + _i * 8192), 16, 0, 0); } while (0)
; #define PG8_LDA(dst, b, h) do { _Pragma("unroll") for (int m = 0; m < 4; ++m) _Pragma("unroll") for (int k = 0; k < 2; ++k) dst[m][k] = *(const LAS bf16x8*)(lds + PG8_SA(b, h) + aoff + m * 2048 + k * 1024); } while (0)
; #define PG8_LDB(dst, b, h) do { _Pragma("unroll") for (int n = 0; n < 2; ++n) _Pragma("unroll") for (int k = 0; k < 2; ++k) dst[n][k] = *(const LAS bf16x8*)(lds + PG8_SB(b, h) + boff + n * 2048 + k * 1024); } while (0)
; #define PG8_MMA(ai, bj, At, Bt) do { __builtin_amdgcn_s_setprio(1); _Pragma("unroll") for (int m = 0; m < 4; ++m) _Pragma("unroll") for (int n = 0; n < 2; ++n) _Pragma("unroll") for (int k = 0; k < 2; ++k) \
;         acc[ai][bj][m][n] = __builtin_amdgcn_mfma_f32_16x16x32_bf16(Bt[n][k], At[m][k], acc[ai][bj][m][n], 0, 0, 0); __builtin_amdgcn_s_setprio(0); } while (0)
; #define PG8_WAIT_V(n) asm volatile("s_waitcnt vmcnt(" #n ")" ::: "memory")
; #define PG8_WAIT_L(n) asm volatile("s_waitcnt lgkmcnt(" #n ")" ::: "memory")
; #define PG8_BAR __builtin_amdgcn_s_barrier()
; #define PG8_SCHED __builtin_amdgcn_sched_barrier(0)
; template <class Epi, class Sched>
; __device__ __forceinline__ void gemm_phase(LAS unsigned char* lds, const Gemm g, const Sched& S, const Epi& E) {
;     ...
;         for (int t = 0; t < nt; t += 2) {
;             const bool last = (t == nt - 2);
;             const char* a1 = cA + (size_t)(t + 1) * kstep;
;             const char* a2 = last ? nA : cA + (size_t)(t + 2) * kstep; const char* b2 = last ? nB : cB + (size_t)(t + 2) * kstep;
;             const char* a3 = a2 + kstep; const char* b3 = b2 + kstep;
;             PG8_LDB(B0, 0, 0); PG8_SCHED; PG8_LDA(At, 0, 0); PG8_STAGE(PG8_SA(1, 1), a1 + hstep, voffA);
;             PG8_WAIT_L(8); PG8_BAR; PG8_WAIT_L(0); PG8_MMA(0, 0, At, B0); PG8_BAR; PG8_SCHED;
;             PG8_LDB(B1, 0, 1); PG8_STAGE(PG8_SB(0, 0), b2, voffB);
;             PG8_BAR; PG8_WAIT_L(0); PG8_MMA(0, 1, At, B1); PG8_BAR;
;     ...
;             PG8_BAR; PG8_WAIT_L(0); PG8_MMA(1, 0, At, B0); PG8_BAR; PG8_SCHED;
;             PG8_STAGE(PG8_SB(1, 1), b3 + hstep, voffB);
;             PG8_WAIT_V(6); PG8_BAR; PG8_MMA(1, 1, At, B1); PG8_BAR;
	s_waitcnt lgkmcnt(0)
	v_mfma_f32_16x16x32_bf16 v[60:63], v[140:143], v[166:169], v[60:63]
	v_mfma_f32_16x16x32_bf16 v[56:59], v[158:161], v[166:169], v[56:59]
	v_mfma_f32_16x16x32_bf16 v[44:47], v[140:143], v[174:177], v[44:47]
	v_mfma_f32_16x16x32_bf16 v[40:43], v[158:161], v[174:177], v[40:43]
	v_mfma_f32_16x16x32_bf16 v[28:31], v[140:143], v[182:185], v[28:31]
	v_mfma_f32_16x16x32_bf16 v[24:27], v[158:161], v[182:185], v[24:27]
	v_mfma_f32_16x16x32_bf16 v[12:15], v[140:143], v[190:193], v[12:15]
	v_mfma_f32_16x16x32_bf16 v[8:11], v[158:161], v[190:193], v[8:11]
	v_mfma_f32_16x16x32_bf16 v[60:63], v[154:157], v[170:173], v[60:63]
	v_mfma_f32_16x16x32_bf16 v[56:59], v[162:165], v[170:173], v[56:59]
	v_mfma_f32_16x16x32_bf16 v[44:47], v[154:157], v[178:181], v[44:47]
	v_mfma_f32_16x16x32_bf16 v[40:43], v[162:165], v[178:181], v[40:43]
	v_mfma_f32_16x16x32_bf16 v[28:31], v[154:157], v[186:189], v[28:31]
	v_mfma_f32_16x16x32_bf16 v[24:27], v[162:165], v[186:189], v[24:27]
	v_mfma_f32_16x16x32_bf16 v[12:15], v[154:157], v[194:197], v[12:15]
	v_mfma_f32_16x16x32_bf16 v[8:11], v[162:165], v[194:197], v[8:11]
	s_setprio 0
	s_barrier
	s_add_u32 s4, s4, 0x40080
	s_addc_u32 s5, s5, 0
	s_add_i32 s24, s24, s31
	s_mov_b32 m0, s24
	s_nop 0
	global_load_lds_dwordx4 v130, s[4:5]
	s_add_i32 m0, s24, 0x2000
	s_nop 0
	global_load_lds_dwordx4 v134, s[4:5]
	s_waitcnt vmcnt(8)
	s_setprio 1
	s_barrier
	v_mfma_f32_16x16x32_bf16 v[52:55], v[202:205], v[166:169], v[52:55]
	v_mfma_f32_16x16x32_bf16 v[48:51], v[210:213], v[166:169], v[48:51]
	v_mfma_f32_16x16x32_bf16 v[36:39], v[202:205], v[174:177], v[36:39]
	v_mfma_f32_16x16x32_bf16 v[32:35], v[210:213], v[174:177], v[32:35]
	v_mfma_f32_16x16x32_bf16 v[20:23], v[202:205], v[182:185], v[20:23]
	v_mfma_f32_16x16x32_bf16 v[16:19], v[210:213], v[182:185], v[16:19]
	v_mfma_f32_16x16x32_bf16 v[4:7], v[202:205], v[190:193], v[4:7]
	v_mfma_f32_16x16x32_bf16 v[0:3], v[210:213], v[190:193], v[0:3]
	v_mfma_f32_16x16x32_bf16 v[52:55], v[206:209], v[170:173], v[52:55]
	v_mfma_f32_16x16x32_bf16 v[48:51], v[214:217], v[170:173], v[48:51]
	v_mfma_f32_16x16x32_bf16 v[36:39], v[206:209], v[178:181], v[36:39]
	v_mfma_f32_16x16x32_bf16 v[32:35], v[214:217], v[178:181], v[32:35]
	v_mfma_f32_16x16x32_bf16 v[20:23], v[206:209], v[186:189], v[20:23]
	v_mfma_f32_16x16x32_bf16 v[16:19], v[214:217], v[186:189], v[16:19]
	v_mfma_f32_16x16x32_bf16 v[4:7], v[206:209], v[194:197], v[4:7]
	v_mfma_f32_16x16x32_bf16 v[0:3], v[214:217], v[194:197], v[0:3]
	s_setprio 0
	s_add_i32 s61, s61, 2
	s_add_u32 s2, s2, 0x100
	s_addc_u32 s3, s3, 0
	s_add_u32 s59, s59, 0x100
	s_addc_u32 s60, s60, 0
	s_cmp_gt_u32 s61, 13
	s_barrier
.LBB0_693:
	ds_read_b128 v[140:143], v149
	ds_read_b128 v[154:157], v149 offset:1024
	ds_read_b128 v[158:161], v149 offset:2048
	ds_read_b128 v[162:165], v149 offset:3072
	s_add_u32 s4, s2, 0xfffc0080
	s_addc_u32 s5, s3, -1
	s_cmp_eq_u32 s61, 12
	s_cselect_b32 s25, s19, s5
	s_cselect_b32 s24, s57, s4
	s_cselect_b32 s5, s17, s60
	s_cselect_b32 s4, s58, s59
	s_add_i32 m0, s33, 0xc000
	ds_read_b128 v[166:169], v150
	ds_read_b128 v[170:173], v150 offset:1024
	ds_read_b128 v[174:177], v150 offset:2048
	ds_read_b128 v[178:181], v150 offset:3072
	ds_read_b128 v[182:185], v150 offset:4096
	ds_read_b128 v[186:189], v150 offset:5120
	ds_read_b128 v[190:193], v150 offset:6144
	ds_read_b128 v[194:197], v150 offset:7168
	global_load_lds_dwordx4 v136, s[2:3]
	s_add_i32 m0, s33, 0xe000
	s_nop 0
	global_load_lds_dwordx4 v138, s[2:3]
	s_waitcnt lgkmcnt(8)
	s_waitcnt vmcnt(8)
	s_setprio 1
	s_barrier
	s_waitcnt lgkmcnt(0)
	v_mfma_f32_16x16x32_bf16 v[124:127], v[140:143], v[166:169], v[124:127]
	v_mfma_f32_16x16x32_bf16 v[120:123], v[158:161], v[166:169], v[120:123]
	v_mfma_f32_16x16x32_bf16 v[108:111], v[140:143], v[174:177], v[108:111]
	v_mfma_f32_16x16x32_bf16 v[104:107], v[158:161], v[174:177], v[104:107]
	v_mfma_f32_16x16x32_bf16 v[92:95], v[140:143], v[182:185], v[92:95]
	v_mfma_f32_16x16x32_bf16 v[88:91], v[158:161], v[182:185], v[88:91]
	v_mfma_f32_16x16x32_bf16 v[76:79], v[140:143], v[190:193], v[76:79]
	v_mfma_f32_16x16x32_bf16 v[72:75], v[158:161], v[190:193], v[72:75]
	v_mfma_f32_16x16x32_bf16 v[124:127], v[154:157], v[170:173], v[124:127]
	v_mfma_f32_16x16x32_bf16 v[120:123], v[162:165], v[170:173], v[120:123]
	v_mfma_f32_16x16x32_bf16 v[108:111], v[154:157], v[178:181], v[108:111]
	v_mfma_f32_16x16x32_bf16 v[104:107], v[162:165], v[178:181], v[104:107]
	v_mfma_f32_16x16x32_bf16 v[92:95], v[154:157], v[186:189], v[92:95]
	v_mfma_f32_16x16x32_bf16 v[88:91], v[162:165], v[186:189], v[88:91]
	v_mfma_f32_16x16x32_bf16 v[76:79], v[154:157], v[194:197], v[76:79]
	v_mfma_f32_16x16x32_bf16 v[72:75], v[162:165], v[194:197], v[72:75]
	s_setprio 0
	s_barrier
	s_add_i32 s62, s47, s31
	s_mov_b32 m0, s62
	ds_read_b128 v[202:205], v151
	ds_read_b128 v[206:209], v151 offset:1024
	ds_read_b128 v[210:213], v151 offset:2048
	ds_read_b128 v[214:217], v151 offset:3072
	global_load_lds_dwordx4 v130, s[4:5]
	s_add_i32 m0, s62, 0x2000
	s_nop 0
	global_load_lds_dwordx4 v134, s[4:5]
	s_waitcnt vmcnt(8)
	s_setprio 1
	s_barrier
; #define PG8_STAGE(bufoff, gbase, voff) do { _Pragma("unroll") for (int _i = 0; _i < 2; ++_i) \
;         __builtin_amdgcn_global_load_lds((const unsigned*)((const char*)(gbase) + (voff)[_i]), (LAS unsigned*)(lds + (bufoff) + ldsw + _i * 8192), 16, 0, 0); } while (0)
; #define PG8_LDA(dst, b, h) do { _Pragma("unroll") for (int m = 0; m < 4; ++m) _Pragma("unroll") for (int k = 0; k < 2; ++k) dst[m][k] = *(const LAS bf16x8*)(lds + PG8_SA(b, h) + aoff + m * 2048 + k * 1024); } while (0)
; #define PG8_LDB(dst, b, h) do { _Pragma("unroll") for (int n = 0; n < 2; ++n) _Pragma("unroll") for (int k = 0; k < 2; ++k) dst[n][k] = *(const LAS bf16x8*)(lds + PG8_SB(b, h) + boff + n * 2048 + k * 1024); } while (0)
; #define PG8_MMA(ai, bj, At, Bt) do { __builtin_amdgcn_s_setprio(1); _Pragma("unroll") for (int m = 0; m < 4; ++m) _Pragma("unroll") for (int n = 0; n < 2; ++n) _Pragma("unroll") for (int k = 0; k < 2; ++k) \
;         acc[ai][bj][m][n] = __builtin_amdgcn_mfma_f32_16x16x32_bf16(Bt[n][k], At[m][k], acc[ai][bj][m][n], 0, 0, 0); __builtin_amdgcn_s_setprio(0); } while (0)
; #define PG8_WAIT_V(n) asm volatile("s_waitcnt vmcnt(" #n ")" ::: "memory")
; #define PG8_WAIT_L(n) asm volatile("s_waitcnt lgkmcnt(" #n ")" ::: "memory")
; #define PG8_BAR __builtin_amdgcn_s_barrier()
; #define PG8_SCHED __builtin_amdgcn_sched_barrier(0)
; template <class Epi, class Sched>
; __device__ __forceinline__ void gemm_phase(LAS unsigned char* lds, const Gemm g, const Sched& S, const Epi& E) {
;     ...
;             PG8_LDA(At, 0, 1); PG8_STAGE(PG8_SA(0, 0), a2, voffA);
;             PG8_BAR; PG8_WAIT_L(0); PG8_MMA(1, 0, At, B0); PG8_BAR; PG8_SCHED;
;             PG8_STAGE(PG8_SB(0, 1), b2 + hstep, voffB);
;             PG8_WAIT_V(6); PG8_BAR; PG8_MMA(1, 1, At, B1); PG8_BAR;
;             PG8_LDB(B0, 1, 0); PG8_SCHED; PG8_LDA(At, 1, 0); PG8_STAGE(PG8_SA(0, 1), a2 + hstep, voffA);
;             PG8_WAIT_L(8); PG8_BAR; PG8_WAIT_L(0); PG8_MMA(0, 0, At, B0); PG8_BAR; PG8_SCHED;
;             PG8_LDB(B1, 1, 1); PG8_STAGE(PG8_SB(1, 0), b3, voffB);
;             PG8_BAR; PG8_WAIT_L(0); PG8_MMA(0, 1, At, B1); PG8_BAR;
	s_waitcnt lgkmcnt(0)
	v_mfma_f32_16x16x32_bf16 v[116:119], v[202:205], v[166:169], v[116:119]
	v_mfma_f32_16x16x32_bf16 v[112:115], v[210:213], v[166:169], v[112:115]
	v_mfma_f32_16x16x32_bf16 v[100:103], v[202:205], v[174:177], v[100:103]
	v_mfma_f32_16x16x32_bf16 v[96:99], v[210:213], v[174:177], v[96:99]
	v_mfma_f32_16x16x32_bf16 v[84:87], v[202:205], v[182:185], v[84:87]
	v_mfma_f32_16x16x32_bf16 v[80:83], v[210:213], v[182:185], v[80:83]
	v_mfma_f32_16x16x32_bf16 v[68:71], v[202:205], v[190:193], v[68:71]
	v_mfma_f32_16x16x32_bf16 v[64:67], v[210:213], v[190:193], v[64:67]
	v_mfma_f32_16x16x32_bf16 v[116:119], v[206:209], v[170:173], v[116:119]
	v_mfma_f32_16x16x32_bf16 v[112:115], v[214:217], v[170:173], v[112:115]
	v_mfma_f32_16x16x32_bf16 v[100:103], v[206:209], v[178:181], v[100:103]
	v_mfma_f32_16x16x32_bf16 v[96:99], v[214:217], v[178:181], v[96:99]
	v_mfma_f32_16x16x32_bf16 v[84:87], v[206:209], v[186:189], v[84:87]
	v_mfma_f32_16x16x32_bf16 v[80:83], v[214:217], v[186:189], v[80:83]
	v_mfma_f32_16x16x32_bf16 v[68:71], v[206:209], v[194:197], v[68:71]
	v_mfma_f32_16x16x32_bf16 v[64:67], v[214:217], v[194:197], v[64:67]
	s_setprio 0
	s_mov_b32 m0, s33
	v_lshl_add_u64 v[218:219], s[24:25], 0, v[128:129]
	s_barrier
	ds_read_b128 v[166:169], v150 offset:16384
	ds_read_b128 v[170:173], v150 offset:17408
	ds_read_b128 v[174:177], v150 offset:18432
	ds_read_b128 v[178:181], v150 offset:19456
	ds_read_b128 v[182:185], v150 offset:20480
	ds_read_b128 v[186:189], v150 offset:21504
	ds_read_b128 v[190:193], v150 offset:22528
	ds_read_b128 v[194:197], v150 offset:23552
	global_load_lds_dwordx4 v128, s[24:25]
	v_lshl_add_u64 v[220:221], s[24:25], 0, v[132:133]
	s_mov_b32 m0, s34
	s_nop 0
	global_load_lds_dwordx4 v132, s[24:25]
	s_setprio 1
	s_barrier
	s_waitcnt lgkmcnt(0)
	v_mfma_f32_16x16x32_bf16 v[60:63], v[140:143], v[166:169], v[60:63]
	v_mfma_f32_16x16x32_bf16 v[56:59], v[158:161], v[166:169], v[56:59]
	v_mfma_f32_16x16x32_bf16 v[44:47], v[140:143], v[174:177], v[44:47]
	v_mfma_f32_16x16x32_bf16 v[40:43], v[158:161], v[174:177], v[40:43]
	v_mfma_f32_16x16x32_bf16 v[28:31], v[140:143], v[182:185], v[28:31]
	v_mfma_f32_16x16x32_bf16 v[24:27], v[158:161], v[182:185], v[24:27]
	v_mfma_f32_16x16x32_bf16 v[12:15], v[140:143], v[190:193], v[12:15]
	v_mfma_f32_16x16x32_bf16 v[8:11], v[158:161], v[190:193], v[8:11]
	v_mfma_f32_16x16x32_bf16 v[60:63], v[154:157], v[170:173], v[60:63]
	v_mfma_f32_16x16x32_bf16 v[56:59], v[162:165], v[170:173], v[56:59]
	v_mfma_f32_16x16x32_bf16 v[44:47], v[154:157], v[178:181], v[44:47]
	v_mfma_f32_16x16x32_bf16 v[40:43], v[162:165], v[178:181], v[40:43]
	v_mfma_f32_16x16x32_bf16 v[28:31], v[154:157], v[186:189], v[28:31]
	v_mfma_f32_16x16x32_bf16 v[24:27], v[162:165], v[186:189], v[24:27]
	v_mfma_f32_16x16x32_bf16 v[12:15], v[154:157], v[194:197], v[12:15]
	v_mfma_f32_16x16x32_bf16 v[8:11], v[162:165], v[194:197], v[8:11]
	s_setprio 0
	s_barrier
	s_add_u32 s62, s4, 0x40000
	s_addc_u32 s63, s5, 0
	s_add_i32 s64, s48, s31
	s_mov_b32 m0, s64
	s_nop 0
	global_load_lds_dwordx4 v130, s[62:63]
	s_add_i32 m0, s64, 0x2000
	s_nop 0
	global_load_lds_dwordx4 v134, s[62:63]
	s_add_u32 s24, s24, 0x40000
	s_addc_u32 s25, s25, 0
	s_mov_b32 m0, s35
	s_nop 0
	global_load_lds_dwordx4 v128, s[24:25]
	s_mov_b32 m0, s36
	s_nop 0
	global_load_lds_dwordx4 v132, s[24:25]
	s_waitcnt vmcnt(10)
	s_setprio 1
	s_barrier
	v_mfma_f32_16x16x32_bf16 v[52:55], v[202:205], v[166:169], v[52:55]
	v_mfma_f32_16x16x32_bf16 v[48:51], v[210:213], v[166:169], v[48:51]
	v_mfma_f32_16x16x32_bf16 v[36:39], v[202:205], v[174:177], v[36:39]
	v_mfma_f32_16x16x32_bf16 v[32:35], v[210:213], v[174:177], v[32:35]
	v_mfma_f32_16x16x32_bf16 v[20:23], v[202:205], v[182:185], v[20:23]
	v_mfma_f32_16x16x32_bf16 v[16:19], v[210:213], v[182:185], v[16:19]
	v_mfma_f32_16x16x32_bf16 v[4:7], v[202:205], v[190:193], v[4:7]
	v_mfma_f32_16x16x32_bf16 v[0:3], v[210:213], v[190:193], v[0:3]
	v_mfma_f32_16x16x32_bf16 v[52:55], v[206:209], v[170:173], v[52:55]
	v_mfma_f32_16x16x32_bf16 v[48:51], v[214:217], v[170:173], v[48:51]
	v_mfma_f32_16x16x32_bf16 v[36:39], v[206:209], v[178:181], v[36:39]
	v_mfma_f32_16x16x32_bf16 v[32:35], v[214:217], v[178:181], v[32:35]
	v_mfma_f32_16x16x32_bf16 v[20:23], v[206:209], v[186:189], v[20:23]
	v_mfma_f32_16x16x32_bf16 v[16:19], v[214:217], v[186:189], v[16:19]
	v_mfma_f32_16x16x32_bf16 v[4:7], v[206:209], v[194:197], v[4:7]
	v_mfma_f32_16x16x32_bf16 v[0:3], v[214:217], v[194:197], v[0:3]
	s_setprio 0
	s_add_i32 s62, 0, 0x18000
	v_add_u32_e32 v162, s62, v148
	s_barrier
	ds_read_b128 v[140:143], v162
	ds_read_b128 v[154:157], v162 offset:1024
	ds_read_b128 v[158:161], v162 offset:2048
	ds_read_b128 v[162:165], v162 offset:3072
	ds_read_b128 v[166:169], v150 offset:32768
	ds_read_b128 v[170:173], v150 offset:33792
	ds_read_b128 v[174:177], v150 offset:34816
	ds_read_b128 v[178:181], v150 offset:35840
	ds_read_b128 v[182:185], v150 offset:36864
	ds_read_b128 v[186:189], v150 offset:37888
	ds_read_b128 v[190:193], v150 offset:38912
	ds_read_b128 v[194:197], v150 offset:39936
	s_waitcnt lgkmcnt(8)
	s_waitcnt vmcnt(8)
	s_setprio 1
	s_barrier
; #define PG8_STAGE(bufoff, gbase, voff) do { _Pragma("unroll") for (int _i = 0; _i < 2; ++_i) \
;         __builtin_amdgcn_global_load_lds((const unsigned*)((const char*)(gbase) + (voff)[_i]), (LAS unsigned*)(lds + (bufoff) + ldsw + _i * 8192), 16, 0, 0); } while (0)
; #define PG8_LDA(dst, b, h) do { _Pragma("unroll") for (int m = 0; m < 4; ++m) _Pragma("unroll") for (int k = 0; k < 2; ++k) dst[m][k] = *(const LAS bf16x8*)(lds + PG8_SA(b, h) + aoff + m * 2048 + k * 1024); } while (0)
; #define PG8_LDB(dst, b, h) do { _Pragma("unroll") for (int n = 0; n < 2; ++n) _Pragma("unroll") for (int k = 0; k < 2; ++k) dst[n][k] = *(const LAS bf16x8*)(lds + PG8_SB(b, h) + boff + n * 2048 + k * 1024); } while (0)
; #define PG8_MMA(ai, bj, At, Bt) do { __builtin_amdgcn_s_setprio(1); _Pragma("unroll") for (int m = 0; m < 4; ++m) _Pragma("unroll") for (int n = 0; n < 2; ++n) _Pragma("unroll") for (int k = 0; k < 2; ++k) \
;         acc[ai][bj][m][n] = __builtin_amdgcn_mfma_f32_16x16x32_bf16(Bt[n][k], At[m][k], acc[ai][bj][m][n], 0, 0, 0); __builtin_amdgcn_s_setprio(0); } while (0)
; #define PG8_WAIT_V(n) asm volatile("s_waitcnt vmcnt(" #n ")" ::: "memory")
; #define PG8_WAIT_L(n) asm volatile("s_waitcnt lgkmcnt(" #n ")" ::: "memory")
; #define PG8_BAR __builtin_amdgcn_s_barrier()
; #define PG8_SCHED __builtin_amdgcn_sched_barrier(0)
; template <class Epi, class Sched>
; __device__ __forceinline__ void gemm_phase(LAS unsigned char* lds, const Gemm g, const Sched& S, const Epi& E) {
;     ...
;             PG8_WAIT_L(8); PG8_BAR; PG8_WAIT_L(0); PG8_MMA(0, 0, At, B0); PG8_BAR; PG8_SCHED;
;             PG8_LDB(B1, 1, 1); PG8_STAGE(PG8_SB(1, 0), b3, voffB);
;             PG8_BAR; PG8_WAIT_L(0); PG8_MMA(0, 1, At, B1); PG8_BAR;
;             PG8_LDA(At, 1, 1); PG8_STAGE(PG8_SA(1, 0), a3, voffA);
;             PG8_BAR; PG8_WAIT_L(0); PG8_MMA(1, 0, At, B0); PG8_BAR; PG8_SCHED;
;             PG8_STAGE(PG8_SB(1, 1), b3 + hstep, voffB);
;             PG8_WAIT_V(6); PG8_BAR; PG8_MMA(1, 1, At, B1); PG8_BAR;
	s_waitcnt lgkmcnt(0)
	v_mfma_f32_16x16x32_bf16 v[124:127], v[140:143], v[166:169], v[124:127]
	v_mfma_f32_16x16x32_bf16 v[120:123], v[158:161], v[166:169], v[120:123]
	v_mfma_f32_16x16x32_bf16 v[108:111], v[140:143], v[174:177], v[108:111]
	v_mfma_f32_16x16x32_bf16 v[104:107], v[158:161], v[174:177], v[104:107]
	v_mfma_f32_16x16x32_bf16 v[92:95], v[140:143], v[182:185], v[92:95]
	v_mfma_f32_16x16x32_bf16 v[88:91], v[158:161], v[182:185], v[88:91]
	v_mfma_f32_16x16x32_bf16 v[76:79], v[140:143], v[190:193], v[76:79]
	v_mfma_f32_16x16x32_bf16 v[72:75], v[158:161], v[190:193], v[72:75]
	v_mfma_f32_16x16x32_bf16 v[124:127], v[154:157], v[170:173], v[124:127]
	v_mfma_f32_16x16x32_bf16 v[120:123], v[162:165], v[170:173], v[120:123]
	v_mfma_f32_16x16x32_bf16 v[108:111], v[154:157], v[178:181], v[108:111]
	v_mfma_f32_16x16x32_bf16 v[104:107], v[162:165], v[178:181], v[104:107]
	v_mfma_f32_16x16x32_bf16 v[92:95], v[154:157], v[186:189], v[92:95]
	v_mfma_f32_16x16x32_bf16 v[88:91], v[162:165], v[186:189], v[88:91]
	v_mfma_f32_16x16x32_bf16 v[76:79], v[154:157], v[194:197], v[76:79]
	v_mfma_f32_16x16x32_bf16 v[72:75], v[162:165], v[194:197], v[72:75]
	s_setprio 0
	s_barrier
	s_add_i32 s24, 0, 0x1c000
	s_add_i32 s25, s62, s31
	v_add_u32_e32 v214, s24, v148
	s_add_u32 s0, s4, 0x80
	s_addc_u32 s1, s5, 0
	s_mov_b32 m0, s25
	ds_read_b128 v[202:205], v214
	ds_read_b128 v[206:209], v214 offset:1024
	ds_read_b128 v[210:213], v214 offset:2048
	ds_read_b128 v[214:217], v214 offset:3072
	global_load_lds_dwordx4 v130, s[0:1]
	s_add_i32 m0, s25, 0x2000
	s_nop 0
	global_load_lds_dwordx4 v134, s[0:1]
	s_waitcnt vmcnt(8)
	s_setprio 1
	s_barrier
	s_waitcnt lgkmcnt(0)
	v_mfma_f32_16x16x32_bf16 v[116:119], v[202:205], v[166:169], v[116:119]
	v_mfma_f32_16x16x32_bf16 v[112:115], v[210:213], v[166:169], v[112:115]
	v_mfma_f32_16x16x32_bf16 v[100:103], v[202:205], v[174:177], v[100:103]
	v_mfma_f32_16x16x32_bf16 v[96:99], v[210:213], v[174:177], v[96:99]
	v_mfma_f32_16x16x32_bf16 v[84:87], v[202:205], v[182:185], v[84:87]
	v_mfma_f32_16x16x32_bf16 v[80:83], v[210:213], v[182:185], v[80:83]
	v_mfma_f32_16x16x32_bf16 v[68:71], v[202:205], v[190:193], v[68:71]
	v_mfma_f32_16x16x32_bf16 v[64:67], v[210:213], v[190:193], v[64:67]
	v_mfma_f32_16x16x32_bf16 v[116:119], v[206:209], v[170:173], v[116:119]
	v_mfma_f32_16x16x32_bf16 v[112:115], v[214:217], v[170:173], v[112:115]
	v_mfma_f32_16x16x32_bf16 v[100:103], v[206:209], v[178:181], v[100:103]
	v_mfma_f32_16x16x32_bf16 v[96:99], v[214:217], v[178:181], v[96:99]
	v_mfma_f32_16x16x32_bf16 v[84:87], v[206:209], v[186:189], v[84:87]
	v_mfma_f32_16x16x32_bf16 v[80:83], v[214:217], v[186:189], v[80:83]
	v_mfma_f32_16x16x32_bf16 v[68:71], v[206:209], v[194:197], v[68:71]
	v_mfma_f32_16x16x32_bf16 v[64:67], v[214:217], v[194:197], v[64:67]
	s_setprio 0
	s_mov_b32 m0, s44
	s_mov_b64 s[0:1], 0x80
	v_lshl_add_u64 v[144:145], v[218:219], 0, s[0:1]
	s_barrier
	ds_read_b128 v[166:169], v150 offset:49152
	ds_read_b128 v[170:173], v150 offset:50176
	ds_read_b128 v[174:177], v150 offset:51200
	ds_read_b128 v[178:181], v150 offset:52224
	ds_read_b128 v[182:185], v150 offset:53248
	ds_read_b128 v[186:189], v150 offset:54272
	ds_read_b128 v[190:193], v150 offset:55296
	ds_read_b128 v[194:197], v150 offset:56320
	global_load_lds_dwordx4 v[144:145], off
	v_lshl_add_u64 v[144:145], v[220:221], 0, s[0:1]
	s_mov_b32 m0, s45
	s_nop 0
	global_load_lds_dwordx4 v[144:145], off
	s_setprio 1
	s_barrier
	s_waitcnt lgkmcnt(0)
	v_mfma_f32_16x16x32_bf16 v[60:63], v[140:143], v[166:169], v[60:63]
	v_mfma_f32_16x16x32_bf16 v[56:59], v[158:161], v[166:169], v[56:59]
	v_mfma_f32_16x16x32_bf16 v[44:47], v[140:143], v[174:177], v[44:47]
	v_mfma_f32_16x16x32_bf16 v[40:43], v[158:161], v[174:177], v[40:43]
	v_mfma_f32_16x16x32_bf16 v[28:31], v[140:143], v[182:185], v[28:31]
	v_mfma_f32_16x16x32_bf16 v[24:27], v[158:161], v[182:185], v[24:27]
	v_mfma_f32_16x16x32_bf16 v[12:15], v[140:143], v[190:193], v[12:15]
	v_mfma_f32_16x16x32_bf16 v[8:11], v[158:161], v[190:193], v[8:11]
	v_mfma_f32_16x16x32_bf16 v[60:63], v[154:157], v[170:173], v[60:63]
	v_mfma_f32_16x16x32_bf16 v[56:59], v[162:165], v[170:173], v[56:59]
	v_mfma_f32_16x16x32_bf16 v[44:47], v[154:157], v[178:181], v[44:47]
	v_mfma_f32_16x16x32_bf16 v[40:43], v[162:165], v[178:181], v[40:43]
	v_mfma_f32_16x16x32_bf16 v[28:31], v[154:157], v[186:189], v[28:31]
	v_mfma_f32_16x16x32_bf16 v[24:27], v[162:165], v[186:189], v[24:27]
	v_mfma_f32_16x16x32_bf16 v[12:15], v[154:157], v[194:197], v[12:15]
	v_mfma_f32_16x16x32_bf16 v[8:11], v[162:165], v[194:197], v[8:11]
	s_setprio 0
	s_barrier
	s_add_u32 s4, s4, 0x40080
	s_addc_u32 s5, s5, 0
	s_add_i32 s24, s24, s31
	s_mov_b32 m0, s24
	s_nop 0
	global_load_lds_dwordx4 v130, s[4:5]
	s_add_i32 m0, s24, 0x2000
	s_nop 0
	global_load_lds_dwordx4 v134, s[4:5]
	s_waitcnt vmcnt(8)
	s_setprio 1
	s_barrier
	v_mfma_f32_16x16x32_bf16 v[52:55], v[202:205], v[166:169], v[52:55]
	v_mfma_f32_16x16x32_bf16 v[48:51], v[210:213], v[166:169], v[48:51]
	v_mfma_f32_16x16x32_bf16 v[36:39], v[202:205], v[174:177], v[36:39]
	v_mfma_f32_16x16x32_bf16 v[32:35], v[210:213], v[174:177], v[32:35]
	v_mfma_f32_16x16x32_bf16 v[20:23], v[202:205], v[182:185], v[20:23]
	v_mfma_f32_16x16x32_bf16 v[16:19], v[210:213], v[182:185], v[16:19]
	v_mfma_f32_16x16x32_bf16 v[4:7], v[202:205], v[190:193], v[4:7]
	v_mfma_f32_16x16x32_bf16 v[0:3], v[210:213], v[190:193], v[0:3]
	v_mfma_f32_16x16x32_bf16 v[52:55], v[206:209], v[170:173], v[52:55]
	v_mfma_f32_16x16x32_bf16 v[48:51], v[214:217], v[170:173], v[48:51]
	v_mfma_f32_16x16x32_bf16 v[36:39], v[206:209], v[178:181], v[36:39]
	v_mfma_f32_16x16x32_bf16 v[32:35], v[214:217], v[178:181], v[32:35]
	v_mfma_f32_16x16x32_bf16 v[20:23], v[206:209], v[186:189], v[20:23]
	v_mfma_f32_16x16x32_bf16 v[16:19], v[214:217], v[186:189], v[16:19]
	v_mfma_f32_16x16x32_bf16 v[4:7], v[206:209], v[194:197], v[4:7]
	v_mfma_f32_16x16x32_bf16 v[0:3], v[214:217], v[194:197], v[0:3]
	s_setprio 0
	s_add_i32 s61, s61, 2
	s_add_u32 s2, s2, 0x100
	s_addc_u32 s3, s3, 0
	s_add_u32 s59, s59, 0x100
	s_addc_u32 s60, s60, 0
	s_cmp_gt_u32 s61, 13
	s_barrier
;     __device__ __forceinline__ void operator()(const AccT& acc, const Unit& u, int wr, int wc, int fr, int fq) const {
;     ...
;         const int rbase = wr * 64 + fr;
;         const int tb = u.pn * 256 + wc * 32 + 8 * fq;
;         const int o0 = wc * 32 + 8 * fq;
;         const int j = fr & 3; const float sgn = ((fr >> 2) & 1) ? 1.0f : -1.0f;
; #pragma unroll
;         for (int ai = 0; ai < 2; ++ai) {
;             const int hh = 2 * ai + wr;
;             const float l2f = lgd[hh] * 1.4426950408889634f, l2b = lgd[4 + hh] * 1.4426950408889634f;
;             const float zf0 = exp2f((float)(127 - o0) * l2f), zfs = exp2f(-l2f), zb0 = exp2f((float)o0 * l2b), zbs = exp2f(l2b);
; #pragma unroll
;             for (int m = 0; m < 4; ++m) {
;                 const int r = rbase + ai * 128 + m * 16;
;                 const int d = 4 * (2 * m + (fr >> 3)) + j;
; #pragma unroll
;                 for (int bj = 0; bj < 2; ++bj) {
;                     const int t0 = tb + bj * 128;
;                     float v[8];
; #pragma unroll
;                     for (int jj = 0; jj < 4; ++jj) { v[jj] = acc[ai][bj][m][0][jj]; v[4 + jj] = acc[ai][bj][m][1][jj]; }
;                     if constexpr (ROPE) {
;                         const int t = t0 & 2047;
; #pragma unroll
;                         for (int hf = 0; hf < 2; ++hf) {
;                             f32x4 cs, sn;
;                             if (m < 2) { const float c1 = ropeA[(t >> 6) * 16 + d], s1 = ropeA[1024 + (t >> 6) * 16 + d]; cs = (f32x4){c1, c1, c1, c1}; sn = (f32x4){s1, s1, s1, s1}; }
;                             else { const float* cb = ropeA + 2048 + (d - 16) * 64 + (t & 63) + 4 * hf; cs = *(const f32x4*)(cb); sn = *(const f32x4*)(cb + 1024); }
; #pragma unroll
;                             for (int jj = 0; jj < 4; ++jj) { const float pr = __shfl_xor(v[4 * hf + jj], 4); v[4 * hf + jj] = v[4 * hf + jj] * cs[jj] + sgn * pr * sn[jj]; }
;                             __builtin_amdgcn_sched_barrier(0);
;                         }
;                     }
;                     float zf[8], zb[8]; zf[0] = zf0; zb[0] = zb0;
; #pragma unroll
;                     for (int jj = 1; jj < 8; ++jj) { zf[jj] = zf[jj - 1] * zfs; zb[jj] = zb[jj - 1] * zbs; }
;                     u32x4 wf, wb;
	s_cbranch_scc0 .LBB0_693
	v_mov_b32_e32 v141, v147
	v_mov_b32_e32 v140, v146
	global_load_dword v156, v131, s[6:7]
	global_load_dword v157, v131, s[6:7] offset:16
	s_lshl_b32 s2, s56, 8
	s_or_b32 s2, s2, s43
	v_add_u32_e32 v140, s42, v140
	v_lshlrev_b32_e32 v141, 3, v141
	v_add_u32_e32 v142, s2, v141
	v_add_u32_e32 v143, s43, v141
	v_ashrrev_i32_e32 v141, 31, v140
	v_sub_u32_e32 v144, 0x7f, v143
	v_lshlrev_b64 v[140:141], 14, v[140:141]
	v_cvt_f32_i32_e32 v154, v143
	v_ashrrev_i32_e32 v143, 31, v142
	v_cvt_f32_i32_e32 v155, v144
	v_lshl_add_u64 v[140:141], s[70:71], 0, v[140:141]
	s_mov_b32 s3, 0x400000
	v_lshl_add_u64 v[140:141], v[142:143], 1, v[140:141]
	v_add_co_u32_e32 v144, vcc, s3, v140
	s_mov_b64 s[4:5], 0x400000
	s_nop 0
	v_addc_co_u32_e32 v145, vcc, 0, v141, vcc
	v_lshl_add_u64 v[142:143], v[140:141], 0, s[4:5]
	s_waitcnt vmcnt(0)
	v_mul_f32_e32 v158, 0x3fb8aa3b, v156
	v_mul_f32_e32 v159, 0x3fb8aa3b, v157
	v_mul_f32_e32 v160, v158, v155
	v_cmp_lt_f32_e32 vcc, s51, v158
	v_mul_f32_e32 v162, v159, v154
	v_cmp_gt_f32_e64 s[2:3], s49, v159
	v_cndmask_b32_e32 v161, 0, v153, vcc
	v_cmp_gt_f32_e64 s[4:5], s49, v160
	v_cndmask_b32_e64 v163, 0, v153, s[2:3]
	s_and_b64 s[24:25], vcc, exec
	v_cmp_gt_f32_e32 vcc, s49, v162
	v_fmac_f32_e32 v163, 0x3fb8aa3b, v157
	v_cndmask_b32_e64 v157, 0, v153, s[4:5]
	v_cndmask_b32_e32 v162, 0, v153, vcc
	v_fmac_f32_e32 v161, 0xbfb8aa3b, v156
	v_fmac_f32_e32 v157, v158, v155
	v_fmac_f32_e32 v162, v159, v154
	v_exp_f32_e32 v161, v161
	v_exp_f32_e32 v163, v163
	v_exp_f32_e32 v157, v157
	v_exp_f32_e32 v158, v162
	v_cndmask_b32_e64 v160, 0, v152, s[4:5]
	s_cselect_b32 s4, 0xffffffc0, 0
	s_and_b64 s[2:3], s[2:3], exec
	v_cndmask_b32_e32 v156, 0, v152, vcc
	s_cselect_b32 s2, 0xffffffc0, 0
	v_ldexp_f32 v161, v161, s4
	v_ldexp_f32 v162, v163, s2
	v_ldexp_f32 v163, v157, v160
	v_ldexp_f32 v156, v158, v156
	v_mul_f32_e32 v164, v161, v163
	v_mul_f32_e32 v157, v162, v156
	v_mul_f32_e32 v158, v124, v163
	v_mul_f32_e32 v165, v124, v156
	v_mul_f32_e32 v166, v161, v164
	v_mul_f32_e32 v124, v162, v157
	v_mul_f32_e32 v159, v125, v164
	v_mul_f32_e32 v167, v125, v157
	v_mul_f32_e32 v168, v161, v166
	v_mul_f32_e32 v125, v162, v124
	v_cvt_pk_bf16_f32 v158, v158, v159
	v_mul_f32_e32 v159, v126, v166
	v_mul_f32_e32 v169, v126, v124
	v_mul_f32_e32 v170, v161, v168
	v_mul_f32_e32 v126, v162, v125
	v_mul_f32_e32 v171, v161, v170
	v_mul_f32_e32 v172, v162, v126
	v_mul_f32_e32 v160, v127, v168
	v_mul_f32_e32 v174, v161, v171
	v_mul_f32_e32 v175, v162, v172
	v_cvt_pk_bf16_f32 v159, v159, v160
	v_mul_f32_e32 v160, v120, v170
	v_mul_f32_e32 v173, v120, v126
	v_mul_f32_e32 v120, v121, v171
	v_mul_f32_e32 v177, v161, v174
	v_mul_f32_e32 v162, v162, v175
	v_mul_f32_e32 v176, v121, v172
	v_cvt_pk_bf16_f32 v160, v160, v120
	v_mul_f32_e32 v120, v122, v174
	v_mul_f32_e32 v121, v123, v177
	v_mul_f32_e32 v123, v123, v162
	v_cvt_pk_bf16_f32 v161, v120, v121
	v_mul_f32_e32 v127, v127, v125
	v_mul_f32_e32 v178, v122, v175
	v_cvt_pk_bf16_f32 v120, v165, v167
	v_cvt_pk_bf16_f32 v121, v169, v127
	v_cvt_pk_bf16_f32 v122, v173, v176
	v_cvt_pk_bf16_f32 v123, v178, v123
	global_store_dwordx4 v[140:141], v[158:161], off
	global_store_dwordx4 v[144:145], v[120:123], off
	s_nop 1
	v_mul_f32_e32 v120, v116, v163
	v_mul_f32_e32 v121, v117, v164
	v_cvt_pk_bf16_f32 v120, v120, v121
	v_mul_f32_e32 v121, v118, v166
	v_mul_f32_e32 v122, v119, v168
	v_cvt_pk_bf16_f32 v121, v121, v122
	v_mul_f32_e32 v122, v112, v170
	v_mul_f32_e32 v123, v113, v171
	v_cvt_pk_bf16_f32 v122, v122, v123
	v_mul_f32_e32 v123, v114, v174
	v_mul_f32_e32 v116, v116, v156
	v_mul_f32_e32 v117, v117, v157
	v_mul_f32_e32 v127, v115, v177
	v_cvt_pk_bf16_f32 v123, v123, v127
	v_cvt_pk_bf16_f32 v116, v116, v117
	v_mul_f32_e32 v117, v118, v124
	v_mul_f32_e32 v118, v119, v125
	v_mul_f32_e32 v112, v112, v126
	v_mul_f32_e32 v113, v113, v172
	v_cvt_pk_bf16_f32 v117, v117, v118
	v_cvt_pk_bf16_f32 v118, v112, v113
	v_mul_f32_e32 v112, v114, v175
	v_mul_f32_e32 v113, v115, v162
	v_cvt_pk_bf16_f32 v119, v112, v113
	global_store_dwordx4 v[140:141], v[120:123], off offset:256
	global_store_dwordx4 v[142:143], v[116:119], off offset:256
	v_mul_f32_e32 v112, v108, v163
	v_mul_f32_e32 v113, v109, v164
	v_cvt_pk_bf16_f32 v112, v112, v113
	v_mul_f32_e32 v113, v110, v166
	v_mul_f32_e32 v114, v111, v168
	v_cvt_pk_bf16_f32 v113, v113, v114
	v_mul_f32_e32 v114, v104, v170
	v_mul_f32_e32 v115, v105, v171
	v_cvt_pk_bf16_f32 v114, v114, v115
	v_mul_f32_e32 v115, v106, v174
	v_mul_f32_e32 v108, v108, v156
	v_mul_f32_e32 v109, v109, v157
	v_mul_f32_e32 v116, v107, v177
	v_cvt_pk_bf16_f32 v115, v115, v116
	v_cvt_pk_bf16_f32 v108, v108, v109
	v_mul_f32_e32 v109, v110, v124
	v_mul_f32_e32 v110, v111, v125
	v_mul_f32_e32 v104, v104, v126
	s_mov_b64 s[2:3], 0x40000
	v_cvt_pk_bf16_f32 v109, v109, v110
	v_mul_f32_e32 v105, v105, v172
	v_cvt_pk_bf16_f32 v110, v104, v105
	v_mul_f32_e32 v104, v106, v175
	v_lshl_add_u64 v[116:117], v[140:141], 0, s[2:3]
	s_mov_b32 s2, 0x40000
	v_mul_f32_e32 v105, v107, v162
	v_cvt_pk_bf16_f32 v111, v104, v105
	v_add_co_u32_e32 v104, vcc, s2, v140
	s_mov_b64 s[2:3], 0x440000
	s_nop 0
	v_addc_co_u32_e32 v105, vcc, 0, v141, vcc
	global_store_dwordx4 v[104:105], v[112:115], off
	s_nop 1
	v_lshl_add_u64 v[112:113], v[140:141], 0, s[2:3]
	s_mov_b32 s2, 0x440000
	v_add_co_u32_e32 v104, vcc, s2, v140
	s_nop 1
	v_addc_co_u32_e32 v105, vcc, 0, v141, vcc
	global_store_dwordx4 v[104:105], v[108:111], off
	v_mul_f32_e32 v104, v100, v163
	v_mul_f32_e32 v105, v101, v164
	v_cvt_pk_bf16_f32 v104, v104, v105
	v_mul_f32_e32 v105, v102, v166
	v_mul_f32_e32 v106, v103, v168
	v_cvt_pk_bf16_f32 v105, v105, v106
;     __device__ __forceinline__ void operator()(const AccT& acc, const Unit& u, int wr, int wc, int fr, int fq) const {
;     ...
; #pragma unroll
;         for (int ai = 0; ai < 2; ++ai) {
;             const int hh = 2 * ai + wr;
;             const float l2f = lgd[hh] * 1.4426950408889634f, l2b = lgd[4 + hh] * 1.4426950408889634f;
;             const float zf0 = exp2f((float)(127 - o0) * l2f), zfs = exp2f(-l2f), zb0 = exp2f((float)o0 * l2b), zbs = exp2f(l2b);
; #pragma unroll
;             for (int m = 0; m < 4; ++m) {
;                 const int r = rbase + ai * 128 + m * 16;
;                 const int d = 4 * (2 * m + (fr >> 3)) + j;
; #pragma unroll
;                 for (int bj = 0; bj < 2; ++bj) {
;                     const int t0 = tb + bj * 128;
;                     float v[8];
; #pragma unroll
;                     for (int jj = 0; jj < 4; ++jj) { v[jj] = acc[ai][bj][m][0][jj]; v[4 + jj] = acc[ai][bj][m][1][jj]; }
;                     if constexpr (ROPE) {
;                         const int t = t0 & 2047;
; #pragma unroll
;                         for (int hf = 0; hf < 2; ++hf) {
;                             f32x4 cs, sn;
;                             if (m < 2) { const float c1 = ropeA[(t >> 6) * 16 + d], s1 = ropeA[1024 + (t >> 6) * 16 + d]; cs = (f32x4){c1, c1, c1, c1}; sn = (f32x4){s1, s1, s1, s1}; }
;                             else { const float* cb = ropeA + 2048 + (d - 16) * 64 + (t & 63) + 4 * hf; cs = *(const f32x4*)(cb); sn = *(const f32x4*)(cb + 1024); }
; #pragma unroll
;                             for (int jj = 0; jj < 4; ++jj) { const float pr = __shfl_xor(v[4 * hf + jj], 4); v[4 * hf + jj] = v[4 * hf + jj] * cs[jj] + sgn * pr * sn[jj]; }
;                             __builtin_amdgcn_sched_barrier(0);
;                         }
;                     }
;                     float zf[8], zb[8]; zf[0] = zf0; zb[0] = zb0;
; #pragma unroll
;                     for (int jj = 1; jj < 8; ++jj) { zf[jj] = zf[jj - 1] * zfs; zb[jj] = zb[jj - 1] * zbs; }
;                     u32x4 wf, wb;
;                     wf.x = cvt_pk_bf16(v[0] * zf[0], v[1] * zf[1]); wf.y = cvt_pk_bf16(v[2] * zf[2], v[3] * zf[3]); wf.z = cvt_pk_bf16(v[4] * zf[4], v[5] * zf[5]); wf.w = cvt_pk_bf16(v[6] * zf[6], v[7] * zf[7]);
	v_mul_f32_e32 v106, v96, v170
	v_mul_f32_e32 v107, v97, v171
	v_cvt_pk_bf16_f32 v106, v106, v107
	v_mul_f32_e32 v107, v98, v174
	v_mul_f32_e32 v100, v100, v156
	v_mul_f32_e32 v101, v101, v157
	v_mul_f32_e32 v108, v99, v177
	v_cvt_pk_bf16_f32 v107, v107, v108
	v_cvt_pk_bf16_f32 v100, v100, v101
	v_mul_f32_e32 v101, v102, v124
	v_mul_f32_e32 v102, v103, v125
	v_mul_f32_e32 v96, v96, v126
	v_mul_f32_e32 v97, v97, v172
	v_cvt_pk_bf16_f32 v101, v101, v102
	v_cvt_pk_bf16_f32 v102, v96, v97
	v_mul_f32_e32 v96, v98, v175
	v_mul_f32_e32 v97, v99, v162
	v_cvt_pk_bf16_f32 v103, v96, v97
	global_store_dwordx4 v[116:117], v[104:107], off offset:256
	global_store_dwordx4 v[112:113], v[100:103], off offset:256
	v_mul_f32_e32 v96, v92, v163
	v_mul_f32_e32 v97, v93, v164
	v_cvt_pk_bf16_f32 v96, v96, v97
	v_mul_f32_e32 v97, v94, v166
	v_mul_f32_e32 v98, v95, v168
	v_cvt_pk_bf16_f32 v97, v97, v98
	v_mul_f32_e32 v98, v88, v170
	v_mul_f32_e32 v99, v89, v171
	v_cvt_pk_bf16_f32 v98, v98, v99
	v_mul_f32_e32 v99, v90, v174
	v_mul_f32_e32 v92, v92, v156
	v_mul_f32_e32 v93, v93, v157
	v_mul_f32_e32 v100, v91, v177
	v_cvt_pk_bf16_f32 v99, v99, v100
	v_cvt_pk_bf16_f32 v92, v92, v93
	v_mul_f32_e32 v93, v94, v124
	v_mul_f32_e32 v94, v95, v125
	v_mul_f32_e32 v88, v88, v126
	s_mov_b64 s[2:3], 0x80000
	v_cvt_pk_bf16_f32 v93, v93, v94
	v_mul_f32_e32 v89, v89, v172
	v_cvt_pk_bf16_f32 v94, v88, v89
	v_mul_f32_e32 v88, v90, v175
	v_lshl_add_u64 v[100:101], v[140:141], 0, s[2:3]
	s_mov_b32 s2, 0x80000
	v_mul_f32_e32 v89, v91, v162
	v_cvt_pk_bf16_f32 v95, v88, v89
	v_add_co_u32_e32 v88, vcc, s2, v140
	s_mov_b64 s[2:3], 0x480000
	s_nop 0
	v_addc_co_u32_e32 v89, vcc, 0, v141, vcc
	global_store_dwordx4 v[88:89], v[96:99], off
	s_nop 1
	v_lshl_add_u64 v[96:97], v[140:141], 0, s[2:3]
	s_mov_b32 s2, 0x480000
	v_add_co_u32_e32 v88, vcc, s2, v140
	s_nop 1
	v_addc_co_u32_e32 v89, vcc, 0, v141, vcc
	global_store_dwordx4 v[88:89], v[92:95], off
	v_mul_f32_e32 v88, v84, v163
	v_mul_f32_e32 v89, v85, v164
	v_cvt_pk_bf16_f32 v88, v88, v89
	v_mul_f32_e32 v89, v86, v166
	v_mul_f32_e32 v90, v87, v168
	v_cvt_pk_bf16_f32 v89, v89, v90
	v_mul_f32_e32 v90, v80, v170
	v_mul_f32_e32 v91, v81, v171
	v_cvt_pk_bf16_f32 v90, v90, v91
	v_mul_f32_e32 v91, v82, v174
	v_mul_f32_e32 v84, v84, v156
	v_mul_f32_e32 v85, v85, v157
	v_mul_f32_e32 v92, v83, v177
	v_cvt_pk_bf16_f32 v91, v91, v92
	v_cvt_pk_bf16_f32 v84, v84, v85
	v_mul_f32_e32 v85, v86, v124
	v_mul_f32_e32 v86, v87, v125
	v_mul_f32_e32 v80, v80, v126
	v_mul_f32_e32 v81, v81, v172
	v_cvt_pk_bf16_f32 v85, v85, v86
	v_cvt_pk_bf16_f32 v86, v80, v81
	v_mul_f32_e32 v80, v82, v175
	v_mul_f32_e32 v81, v83, v162
	v_cvt_pk_bf16_f32 v87, v80, v81
	global_store_dwordx4 v[100:101], v[88:91], off offset:256
	global_store_dwordx4 v[96:97], v[84:87], off offset:256
	v_mul_f32_e32 v80, v76, v163
	v_mul_f32_e32 v81, v77, v164
	v_cvt_pk_bf16_f32 v80, v80, v81
	v_mul_f32_e32 v81, v78, v166
	v_mul_f32_e32 v82, v79, v168
	v_cvt_pk_bf16_f32 v81, v81, v82
	v_mul_f32_e32 v82, v72, v170
	v_mul_f32_e32 v83, v73, v171
	v_cvt_pk_bf16_f32 v82, v82, v83
	v_mul_f32_e32 v83, v74, v174
	v_mul_f32_e32 v76, v76, v156
	v_mul_f32_e32 v77, v77, v157
	v_mul_f32_e32 v84, v75, v177
	v_cvt_pk_bf16_f32 v83, v83, v84
	v_cvt_pk_bf16_f32 v76, v76, v77
	v_mul_f32_e32 v77, v78, v124
	v_mul_f32_e32 v78, v79, v125
	v_mul_f32_e32 v72, v72, v126
	s_mov_b64 s[2:3], 0xc0000
	v_cvt_pk_bf16_f32 v77, v77, v78
	v_mul_f32_e32 v73, v73, v172
	v_cvt_pk_bf16_f32 v78, v72, v73
	v_mul_f32_e32 v72, v74, v175
	v_lshl_add_u64 v[84:85], v[140:141], 0, s[2:3]
	s_mov_b32 s2, 0xc0000
	v_mul_f32_e32 v73, v75, v162
	v_cvt_pk_bf16_f32 v79, v72, v73
	v_add_co_u32_e32 v72, vcc, s2, v140
	s_mov_b64 s[2:3], 0x4c0000
	s_nop 0
	v_addc_co_u32_e32 v73, vcc, 0, v141, vcc
	global_store_dwordx4 v[72:73], v[80:83], off
	s_nop 1
	v_lshl_add_u64 v[80:81], v[140:141], 0, s[2:3]
	s_mov_b32 s2, 0x4c0000
	v_add_co_u32_e32 v72, vcc, s2, v140
	s_nop 1
	v_addc_co_u32_e32 v73, vcc, 0, v141, vcc
	global_store_dwordx4 v[72:73], v[76:79], off
	v_mul_f32_e32 v72, v68, v163
	v_mul_f32_e32 v73, v69, v164
	v_cvt_pk_bf16_f32 v72, v72, v73
	v_mul_f32_e32 v73, v70, v166
	v_mul_f32_e32 v74, v71, v168
	v_cvt_pk_bf16_f32 v73, v73, v74
	v_mul_f32_e32 v74, v64, v170
	v_mul_f32_e32 v75, v65, v171
	v_cvt_pk_bf16_f32 v74, v74, v75
	v_mul_f32_e32 v75, v66, v174
	v_mul_f32_e32 v68, v68, v156
	v_mul_f32_e32 v69, v69, v157
	v_mul_f32_e32 v76, v67, v177
	v_cvt_pk_bf16_f32 v75, v75, v76
	v_cvt_pk_bf16_f32 v68, v68, v69
	v_mul_f32_e32 v69, v70, v124
	v_mul_f32_e32 v70, v71, v125
	v_mul_f32_e32 v64, v64, v126
	v_mul_f32_e32 v65, v65, v172
	v_cvt_pk_bf16_f32 v69, v69, v70
	v_cvt_pk_bf16_f32 v70, v64, v65
	v_mul_f32_e32 v64, v66, v175
	v_mul_f32_e32 v65, v67, v162
	v_cvt_pk_bf16_f32 v71, v64, v65
	global_store_dwordx4 v[84:85], v[72:75], off offset:256
	global_store_dwordx4 v[80:81], v[68:71], off offset:256
	global_load_dword v70, v131, s[6:7] offset:8
	s_nop 0
	global_load_dword v71, v131, s[6:7] offset:24
	s_mov_b32 s17, 0x200000
	v_add_co_u32_e32 v76, vcc, s17, v140
	s_mov_b32 s19, 0x600000
	s_nop 0
	v_addc_co_u32_e32 v77, vcc, 0, v141, vcc
	v_add_co_u32_e32 v68, vcc, s19, v140
	s_mov_b64 s[2:3], 0x200000
	s_nop 0
	v_addc_co_u32_e32 v69, vcc, 0, v141, vcc
	s_mov_b64 s[4:5], 0x600000
	v_lshl_add_u64 v[64:65], v[140:141], 0, s[2:3]
	v_lshl_add_u64 v[66:67], v[140:141], 0, s[4:5]
	s_waitcnt vmcnt(0)
;     __device__ __forceinline__ void operator()(const AccT& acc, const Unit& u, int wr, int wc, int fr, int fq) const {
;     ...
;             const float l2f = lgd[hh] * 1.4426950408889634f, l2b = lgd[4 + hh] * 1.4426950408889634f;
;             const float zf0 = exp2f((float)(127 - o0) * l2f), zfs = exp2f(-l2f), zb0 = exp2f((float)o0 * l2b), zbs = exp2f(l2b);
; #pragma unroll
;             for (int m = 0; m < 4; ++m) {
;                 const int r = rbase + ai * 128 + m * 16;
;                 const int d = 4 * (2 * m + (fr >> 3)) + j;
; #pragma unroll
;                 for (int bj = 0; bj < 2; ++bj) {
;                     const int t0 = tb + bj * 128;
;                     float v[8];
; #pragma unroll
;                     for (int jj = 0; jj < 4; ++jj) { v[jj] = acc[ai][bj][m][0][jj]; v[4 + jj] = acc[ai][bj][m][1][jj]; }
;                     if constexpr (ROPE) {
;                         const int t = t0 & 2047;
; #pragma unroll
;                         for (int hf = 0; hf < 2; ++hf) {
;                             f32x4 cs, sn;
;                             if (m < 2) { const float c1 = ropeA[(t >> 6) * 16 + d], s1 = ropeA[1024 + (t >> 6) * 16 + d]; cs = (f32x4){c1, c1, c1, c1}; sn = (f32x4){s1, s1, s1, s1}; }
;                             else { const float* cb = ropeA + 2048 + (d - 16) * 64 + (t & 63) + 4 * hf; cs = *(const f32x4*)(cb); sn = *(const f32x4*)(cb + 1024); }
; #pragma unroll
;                             for (int jj = 0; jj < 4; ++jj) { const float pr = __shfl_xor(v[4 * hf + jj], 4); v[4 * hf + jj] = v[4 * hf + jj] * cs[jj] + sgn * pr * sn[jj]; }
;                             __builtin_amdgcn_sched_barrier(0);
;                         }
;                     }
;                     float zf[8], zb[8]; zf[0] = zf0; zb[0] = zb0;
; #pragma unroll
;                     for (int jj = 1; jj < 8; ++jj) { zf[jj] = zf[jj - 1] * zfs; zb[jj] = zb[jj - 1] * zbs; }
;                     u32x4 wf, wb;
;                     wf.x = cvt_pk_bf16(v[0] * zf[0], v[1] * zf[1]); wf.y = cvt_pk_bf16(v[2] * zf[2], v[3] * zf[3]); wf.z = cvt_pk_bf16(v[4] * zf[4], v[5] * zf[5]); wf.w = cvt_pk_bf16(v[6] * zf[6], v[7] * zf[7]);
;                     wb.x = cvt_pk_bf16(v[0] * zb[0], v[1] * zb[1]); wb.y = cvt_pk_bf16(v[2] * zb[2], v[3] * zb[3]); wb.z = cvt_pk_bf16(v[4] * zb[4], v[5] * zb[5]); wb.w = cvt_pk_bf16(v[6] * zb[6], v[7] * zb[7]);
	v_mul_f32_e32 v72, 0x3fb8aa3b, v70
	v_mul_f32_e32 v73, 0x3fb8aa3b, v71
	v_mul_f32_e32 v74, v72, v155
	v_cmp_lt_f32_e32 vcc, s51, v72
	v_mul_f32_e32 v78, v73, v154
	v_cmp_gt_f32_e64 s[2:3], s49, v73
	v_cndmask_b32_e32 v75, 0, v153, vcc
	v_cmp_gt_f32_e64 s[4:5], s49, v74
	v_cndmask_b32_e64 v79, 0, v153, s[2:3]
	s_and_b64 s[24:25], vcc, exec
	v_cmp_gt_f32_e32 vcc, s49, v78
	v_fmac_f32_e32 v79, 0x3fb8aa3b, v71
	v_cndmask_b32_e64 v71, 0, v153, s[4:5]
	v_cndmask_b32_e32 v78, 0, v153, vcc
	v_fmac_f32_e32 v75, 0xbfb8aa3b, v70
	v_fmac_f32_e32 v71, v72, v155
	v_fmac_f32_e32 v78, v73, v154
	v_exp_f32_e32 v75, v75
	v_exp_f32_e32 v79, v79
	v_exp_f32_e32 v71, v71
	v_exp_f32_e32 v72, v78
	v_cndmask_b32_e64 v74, 0, v152, s[4:5]
	s_cselect_b32 s4, 0xffffffc0, 0
	s_and_b64 s[2:3], s[2:3], exec
	v_cndmask_b32_e32 v70, 0, v152, vcc
	s_cselect_b32 s2, 0xffffffc0, 0
	v_ldexp_f32 v75, v75, s4
	v_ldexp_f32 v78, v79, s2
	v_ldexp_f32 v79, v71, v74
	v_ldexp_f32 v70, v72, v70
	v_mul_f32_e32 v80, v75, v79
	v_mul_f32_e32 v71, v78, v70
	v_mul_f32_e32 v72, v60, v79
	v_mul_f32_e32 v81, v60, v70
	v_mul_f32_e32 v82, v75, v80
	v_mul_f32_e32 v60, v78, v71
	v_mul_f32_e32 v83, v75, v82
	v_mul_f32_e32 v84, v78, v60
	v_mul_f32_e32 v85, v75, v83
	v_mul_f32_e32 v86, v78, v84
	v_mul_f32_e32 v73, v61, v80
	v_mul_f32_e32 v87, v75, v85
	v_mul_f32_e32 v88, v78, v86
	v_cvt_pk_bf16_f32 v72, v72, v73
	v_mul_f32_e32 v73, v62, v82
	v_mul_f32_e32 v74, v63, v83
	v_mul_f32_e32 v90, v75, v87
	v_mul_f32_e32 v91, v78, v88
	v_cvt_pk_bf16_f32 v73, v73, v74
	v_mul_f32_e32 v74, v56, v85
	v_mul_f32_e32 v89, v56, v86
	v_mul_f32_e32 v56, v57, v87
	v_mul_f32_e32 v93, v75, v90
	v_mul_f32_e32 v78, v78, v91
	v_mul_f32_e32 v92, v57, v88
	v_cvt_pk_bf16_f32 v74, v74, v56
	v_mul_f32_e32 v56, v58, v90
	v_mul_f32_e32 v57, v59, v93
	v_mul_f32_e32 v59, v59, v78
	v_cvt_pk_bf16_f32 v75, v56, v57
	v_mul_f32_e32 v61, v61, v71
	v_mul_f32_e32 v62, v62, v60
	v_mul_f32_e32 v63, v63, v84
	v_mul_f32_e32 v94, v58, v91
	v_cvt_pk_bf16_f32 v56, v81, v61
	v_cvt_pk_bf16_f32 v57, v62, v63
	v_cvt_pk_bf16_f32 v58, v89, v92
	v_cvt_pk_bf16_f32 v59, v94, v59
	global_store_dwordx4 v[76:77], v[72:75], off
	global_store_dwordx4 v[68:69], v[56:59], off
	s_nop 1
	v_mul_f32_e32 v56, v52, v79
	v_mul_f32_e32 v57, v53, v80
	v_cvt_pk_bf16_f32 v56, v56, v57
	v_mul_f32_e32 v57, v54, v82
	v_mul_f32_e32 v58, v55, v83
	v_cvt_pk_bf16_f32 v57, v57, v58
	v_mul_f32_e32 v58, v48, v85
	v_mul_f32_e32 v59, v49, v87
	v_cvt_pk_bf16_f32 v58, v58, v59
	v_mul_f32_e32 v59, v50, v90
	v_mul_f32_e32 v52, v52, v70
	v_mul_f32_e32 v53, v53, v71
	v_mul_f32_e32 v61, v51, v93
	v_cvt_pk_bf16_f32 v59, v59, v61
	v_cvt_pk_bf16_f32 v52, v52, v53
	v_mul_f32_e32 v53, v54, v60
	v_mul_f32_e32 v54, v55, v84
	v_mul_f32_e32 v48, v48, v86
	v_mul_f32_e32 v49, v49, v88
	v_cvt_pk_bf16_f32 v53, v53, v54
	v_cvt_pk_bf16_f32 v54, v48, v49
	v_mul_f32_e32 v48, v50, v91
	v_mul_f32_e32 v49, v51, v78
	v_cvt_pk_bf16_f32 v55, v48, v49
	global_store_dwordx4 v[64:65], v[56:59], off offset:256
	global_store_dwordx4 v[66:67], v[52:55], off offset:256
	v_mul_f32_e32 v48, v44, v79
	v_mul_f32_e32 v49, v45, v80
	v_cvt_pk_bf16_f32 v48, v48, v49
	v_mul_f32_e32 v49, v46, v82
	v_mul_f32_e32 v50, v47, v83
	v_cvt_pk_bf16_f32 v49, v49, v50
	v_mul_f32_e32 v50, v40, v85
	v_mul_f32_e32 v51, v41, v87
	v_cvt_pk_bf16_f32 v50, v50, v51
	v_mul_f32_e32 v51, v42, v90
	v_mul_f32_e32 v44, v44, v70
	v_mul_f32_e32 v45, v45, v71
	v_mul_f32_e32 v52, v43, v93
	v_cvt_pk_bf16_f32 v51, v51, v52
	v_cvt_pk_bf16_f32 v44, v44, v45
	v_mul_f32_e32 v45, v46, v60
	v_mul_f32_e32 v46, v47, v84
	v_mul_f32_e32 v40, v40, v86
	s_mov_b64 s[2:3], 0x240000
	v_cvt_pk_bf16_f32 v45, v45, v46
	v_mul_f32_e32 v41, v41, v88
	v_cvt_pk_bf16_f32 v46, v40, v41
	v_mul_f32_e32 v40, v42, v91
	v_lshl_add_u64 v[52:53], v[140:141], 0, s[2:3]
	s_mov_b32 s2, 0x240000
	v_mul_f32_e32 v41, v43, v78
	v_cvt_pk_bf16_f32 v47, v40, v41
	v_add_co_u32_e32 v40, vcc, s2, v140
	s_mov_b64 s[2:3], 0x640000
	s_nop 0
	v_addc_co_u32_e32 v41, vcc, 0, v141, vcc
	global_store_dwordx4 v[40:41], v[48:51], off
	s_nop 1
	v_lshl_add_u64 v[48:49], v[140:141], 0, s[2:3]
	s_mov_b32 s2, 0x640000
	v_add_co_u32_e32 v40, vcc, s2, v140
	s_nop 1
	v_addc_co_u32_e32 v41, vcc, 0, v141, vcc
	global_store_dwordx4 v[40:41], v[44:47], off
	v_mul_f32_e32 v40, v36, v79
	v_mul_f32_e32 v41, v37, v80
	v_cvt_pk_bf16_f32 v40, v40, v41
	v_mul_f32_e32 v41, v38, v82
	v_mul_f32_e32 v42, v39, v83
	v_cvt_pk_bf16_f32 v41, v41, v42
	v_mul_f32_e32 v42, v32, v85
	v_mul_f32_e32 v43, v33, v87
	v_cvt_pk_bf16_f32 v42, v42, v43
	v_mul_f32_e32 v43, v34, v90
	v_mul_f32_e32 v36, v36, v70
; __device__ __forceinline__ unsigned cvt_pk_bf16(float lo, float hi) { unsigned r; asm volatile("v_cvt_pk_bf16_f32 %0, %1, %2" : "=v"(r) : "v"(lo), "v"(hi)); return r; }
; #define PG8_WAIT_V(n) asm volatile("s_waitcnt vmcnt(" #n ")" ::: "memory")
; #define PG8_BAR __builtin_amdgcn_s_barrier()
; template <class Epi, class Sched>
; __device__ __forceinline__ void gemm_phase(LAS unsigned char* lds, const Gemm g, const Sched& S, const Epi& E) {
;     ...
;         if (!has_next) break;
; #pragma unroll
;         for (int a = 0; a < 2; ++a)
; #pragma unroll
;             for (int b = 0; b < 2; ++b)
; #pragma unroll
;                 for (int m = 0; m < 4; ++m)
; #pragma unroll
;                     for (int n = 0; n < 2; ++n) acc[a][b][m][n] = (f32x4){0.f, 0.f, 0.f, 0.f};
;         cur = nxt; cA = nA; cB = nB; ++ui;
;     }
;     PG8_WAIT_V(0);
;     if (wr == 0) PG8_BAR;
;     PG8_BAR;
;     __device__ __forceinline__ void operator()(const AccT& acc, const Unit& u, int wr, int wc, int fr, int fq) const {
;     ...
;                     float zf[8], zb[8]; zf[0] = zf0; zb[0] = zb0;
; #pragma unroll
;                     for (int jj = 1; jj < 8; ++jj) { zf[jj] = zf[jj - 1] * zfs; zb[jj] = zb[jj - 1] * zbs; }
;                     u32x4 wf, wb;
;                     wf.x = cvt_pk_bf16(v[0] * zf[0], v[1] * zf[1]); wf.y = cvt_pk_bf16(v[2] * zf[2], v[3] * zf[3]); wf.z = cvt_pk_bf16(v[4] * zf[4], v[5] * zf[5]); wf.w = cvt_pk_bf16(v[6] * zf[6], v[7] * zf[7]);
;                     wb.x = cvt_pk_bf16(v[0] * zb[0], v[1] * zb[1]); wb.y = cvt_pk_bf16(v[2] * zb[2], v[3] * zb[3]); wb.z = cvt_pk_bf16(v[4] * zb[4], v[5] * zb[5]); wb.w = cvt_pk_bf16(v[6] * zb[6], v[7] * zb[7]);
;                     *(u32x4*)(KTZ + (size_t)r * NT + t0) = wf;
;                     *(u32x4*)(KTZ + (size_t)(256 + r) * NT + t0) = wb;
;                     __builtin_amdgcn_sched_barrier(0);
;                 }
	v_mul_f32_e32 v37, v37, v71
	v_mul_f32_e32 v44, v35, v93
	v_cvt_pk_bf16_f32 v43, v43, v44
	v_cvt_pk_bf16_f32 v36, v36, v37
	v_mul_f32_e32 v37, v38, v60
	v_mul_f32_e32 v38, v39, v84
	v_mul_f32_e32 v32, v32, v86
	v_mul_f32_e32 v33, v33, v88
	v_cvt_pk_bf16_f32 v37, v37, v38
	v_cvt_pk_bf16_f32 v38, v32, v33
	v_mul_f32_e32 v32, v34, v91
	v_mul_f32_e32 v33, v35, v78
	v_cvt_pk_bf16_f32 v39, v32, v33
	global_store_dwordx4 v[52:53], v[40:43], off offset:256
	global_store_dwordx4 v[48:49], v[36:39], off offset:256
	v_mul_f32_e32 v32, v28, v79
	v_mul_f32_e32 v33, v29, v80
	v_cvt_pk_bf16_f32 v32, v32, v33
	v_mul_f32_e32 v33, v30, v82
	v_mul_f32_e32 v34, v31, v83
	v_cvt_pk_bf16_f32 v33, v33, v34
	v_mul_f32_e32 v34, v24, v85
	v_mul_f32_e32 v35, v25, v87
	v_cvt_pk_bf16_f32 v34, v34, v35
	v_mul_f32_e32 v35, v26, v90
	v_mul_f32_e32 v28, v28, v70
	v_mul_f32_e32 v29, v29, v71
	v_mul_f32_e32 v36, v27, v93
	v_cvt_pk_bf16_f32 v35, v35, v36
	v_cvt_pk_bf16_f32 v28, v28, v29
	v_mul_f32_e32 v29, v30, v60
	v_mul_f32_e32 v30, v31, v84
	v_mul_f32_e32 v24, v24, v86
	v_cvt_pk_bf16_f32 v29, v29, v30
	v_mul_f32_e32 v25, v25, v88
	v_cvt_pk_bf16_f32 v30, v24, v25
	v_mul_f32_e32 v24, v26, v91
	v_mul_f32_e32 v25, v27, v78
	v_cvt_pk_bf16_f32 v31, v24, v25
	v_add_co_u32_e32 v24, vcc, s52, v140
	s_mov_b64 s[2:3], 0x280000
	s_nop 0
	v_addc_co_u32_e32 v25, vcc, 0, v141, vcc
	global_store_dwordx4 v[24:25], v[32:35], off
	v_add_co_u32_e32 v24, vcc, s53, v140
	v_lshl_add_u64 v[36:37], v[140:141], 0, s[2:3]
	s_nop 0
	v_addc_co_u32_e32 v25, vcc, 0, v141, vcc
	v_lshl_add_u64 v[32:33], v[140:141], 0, s[8:9]
	global_store_dwordx4 v[24:25], v[28:31], off
	v_mul_f32_e32 v24, v20, v79
	v_mul_f32_e32 v25, v21, v80
	v_cvt_pk_bf16_f32 v24, v24, v25
	v_mul_f32_e32 v25, v22, v82
	v_mul_f32_e32 v26, v23, v83
	v_cvt_pk_bf16_f32 v25, v25, v26
	v_mul_f32_e32 v26, v16, v85
	v_mul_f32_e32 v27, v17, v87
	v_cvt_pk_bf16_f32 v26, v26, v27
	v_mul_f32_e32 v27, v18, v90
	v_mul_f32_e32 v20, v20, v70
	v_mul_f32_e32 v21, v21, v71
	v_mul_f32_e32 v28, v19, v93
	v_cvt_pk_bf16_f32 v27, v27, v28
	v_cvt_pk_bf16_f32 v20, v20, v21
	v_mul_f32_e32 v21, v22, v60
	v_mul_f32_e32 v22, v23, v84
	v_mul_f32_e32 v16, v16, v86
	v_mul_f32_e32 v17, v17, v88
	v_cvt_pk_bf16_f32 v21, v21, v22
	v_cvt_pk_bf16_f32 v22, v16, v17
	v_mul_f32_e32 v16, v18, v91
	v_mul_f32_e32 v17, v19, v78
	v_cvt_pk_bf16_f32 v23, v16, v17
	global_store_dwordx4 v[36:37], v[24:27], off offset:256
	global_store_dwordx4 v[32:33], v[20:23], off offset:256
	v_mul_f32_e32 v16, v12, v79
	v_mul_f32_e32 v17, v13, v80
	v_cvt_pk_bf16_f32 v16, v16, v17
	v_mul_f32_e32 v17, v14, v82
	v_mul_f32_e32 v18, v15, v83
	v_cvt_pk_bf16_f32 v17, v17, v18
	v_mul_f32_e32 v18, v8, v85
	v_mul_f32_e32 v19, v9, v87
	v_cvt_pk_bf16_f32 v18, v18, v19
	v_mul_f32_e32 v19, v10, v90
	v_mul_f32_e32 v12, v12, v70
	v_mul_f32_e32 v13, v13, v71
	v_mul_f32_e32 v20, v11, v93
	v_cvt_pk_bf16_f32 v19, v19, v20
	v_cvt_pk_bf16_f32 v12, v12, v13
	v_mul_f32_e32 v13, v14, v60
	v_mul_f32_e32 v14, v15, v84
	v_mul_f32_e32 v8, v8, v86
	v_cvt_pk_bf16_f32 v13, v13, v14
	v_mul_f32_e32 v9, v9, v88
	v_cvt_pk_bf16_f32 v14, v8, v9
	v_mul_f32_e32 v8, v10, v91
	v_mul_f32_e32 v9, v11, v78
	v_cvt_pk_bf16_f32 v15, v8, v9
	v_add_co_u32_e32 v8, vcc, s54, v140
	v_lshl_add_u64 v[20:21], v[140:141], 0, s[10:11]
	s_nop 0
	v_addc_co_u32_e32 v9, vcc, 0, v141, vcc
	global_store_dwordx4 v[8:9], v[16:19], off
	v_add_co_u32_e32 v8, vcc, s55, v140
	s_nop 0
	v_lshl_add_u64 v[16:17], v[140:141], 0, s[12:13]
	v_addc_co_u32_e32 v9, vcc, 0, v141, vcc
	global_store_dwordx4 v[8:9], v[12:15], off
	v_mul_f32_e32 v8, v4, v79
	v_mul_f32_e32 v9, v5, v80
	v_cvt_pk_bf16_f32 v8, v8, v9
	v_mul_f32_e32 v9, v6, v82
	v_mul_f32_e32 v10, v7, v83
	v_cvt_pk_bf16_f32 v9, v9, v10
	v_mul_f32_e32 v10, v0, v85
	v_mul_f32_e32 v11, v1, v87
	v_cvt_pk_bf16_f32 v10, v10, v11
	v_mul_f32_e32 v11, v2, v90
	v_mul_f32_e32 v4, v4, v70
	v_mul_f32_e32 v5, v5, v71
	v_mul_f32_e32 v12, v3, v93
	v_cvt_pk_bf16_f32 v11, v11, v12
	v_cvt_pk_bf16_f32 v4, v4, v5
	v_mul_f32_e32 v5, v6, v60
	v_mul_f32_e32 v6, v7, v84
	v_mul_f32_e32 v0, v0, v86
	v_mul_f32_e32 v1, v1, v88
	v_cvt_pk_bf16_f32 v5, v5, v6
	v_cvt_pk_bf16_f32 v6, v0, v1
	v_mul_f32_e32 v0, v2, v91
	v_mul_f32_e32 v1, v3, v78
	v_cvt_pk_bf16_f32 v7, v0, v1
	global_store_dwordx4 v[20:21], v[8:11], off offset:256
	global_store_dwordx4 v[16:17], v[4:7], off offset:256
	s_and_b64 vcc, exec, s[14:15]
	s_mov_b32 s56, s16
	s_mov_b64 s[4:5], s[22:23]
	s_mov_b64 s[2:3], s[20:21]
	s_cbranch_vccz .LBB0_686
	s_waitcnt vmcnt(0)
	s_cmpk_gt_u32 s27, 0xff
	s_cbranch_scc1 .LBB0_697
	s_barrier

; #define PG8_STAGE(bufoff, gbase, voff) do { _Pragma("unroll") for (int _i = 0; _i < 2; ++_i) \
;         __builtin_amdgcn_global_load_lds((const unsigned*)((const char*)(gbase) + (voff)[_i]), (LAS unsigned*)(lds + (bufoff) + ldsw + _i * 8192), 16, 0, 0); } while (0)
; #define PG8_LDA(dst, b, h) do { _Pragma("unroll") for (int m = 0; m < 4; ++m) _Pragma("unroll") for (int k = 0; k < 2; ++k) dst[m][k] = *(const LAS bf16x8*)(lds + PG8_SA(b, h) + aoff + m * 2048 + k * 1024); } while (0)
; #define PG8_LDB(dst, b, h) do { _Pragma("unroll") for (int n = 0; n < 2; ++n) _Pragma("unroll") for (int k = 0; k < 2; ++k) dst[n][k] = *(const LAS bf16x8*)(lds + PG8_SB(b, h) + boff + n * 2048 + k * 1024); } while (0)
; #define PG8_MMA(ai, bj, At, Bt) do { __builtin_amdgcn_s_setprio(1); _Pragma("unroll") for (int m = 0; m < 4; ++m) _Pragma("unroll") for (int n = 0; n < 2; ++n) _Pragma("unroll") for (int k = 0; k < 2; ++k) \
;         acc[ai][bj][m][n] = __builtin_amdgcn_mfma_f32_16x16x32_bf16(Bt[n][k], At[m][k], acc[ai][bj][m][n], 0, 0, 0); __builtin_amdgcn_s_setprio(0); } while (0)
; #define PG8_WAIT_L(n) asm volatile("s_waitcnt lgkmcnt(" #n ")" ::: "memory")
; template <class Epi, class Sched>
; __device__ __forceinline__ void gemm_phase(LAS unsigned char* lds, const Gemm g, const Sched& S, const Epi& E) {
;     ...
;         const bool has_next = S.next(ui + 1, nxt);
;         const char* nA = has_next ? (const char*)g.A + (size_t)nxt.pm * tstep : cA; const char* nB = has_next ? (const char*)g.Bt + (size_t)nxt.pn * tstep : cB;
;         for (int t = 0; t < nt; t += 2) {
;             const bool last = (t == nt - 2);
;             const char* a1 = cA + (size_t)(t + 1) * kstep;
;             const char* a2 = last ? nA : cA + (size_t)(t + 2) * kstep; const char* b2 = last ? nB : cB + (size_t)(t + 2) * kstep;
;             const char* a3 = a2 + kstep; const char* b3 = b2 + kstep;
;             PG8_LDB(B0, 0, 0); PG8_SCHED; PG8_LDA(At, 0, 0); PG8_STAGE(PG8_SA(1, 1), a1 + hstep, voffA);
;             PG8_WAIT_L(8); PG8_BAR; PG8_WAIT_L(0); PG8_MMA(0, 0, At, B0); PG8_BAR; PG8_SCHED;
;             PG8_LDB(B1, 0, 1); PG8_STAGE(PG8_SB(0, 0), b2, voffB);
;             PG8_BAR; PG8_WAIT_L(0); PG8_MMA(0, 1, At, B1); PG8_BAR;
;             PG8_LDA(At, 0, 1); PG8_STAGE(PG8_SA(0, 0), a2, voffA);
;             PG8_BAR; PG8_WAIT_L(0); PG8_MMA(1, 0, At, B0); PG8_BAR; PG8_SCHED;
.LBB0_712:
	s_ashr_i32 s15, s14, 31
	v_cmp_lt_i64_e64 s[26:27], s[16:17], 64
	s_lshl_b64 s[16:17], s[14:15], 19
	s_add_u32 s16, s38, s16
	s_addc_u32 s17, s39, s17
	s_and_b64 s[18:19], s[26:27], exec
	s_cselect_b32 s15, s17, s23
	s_cselect_b32 s54, s16, s22
	s_ashr_i32 s13, s12, 31
	s_lshl_b64 s[18:19], s[12:13], 19
	s_add_u32 s18, s28, s18
	s_addc_u32 s19, s29, s19
	s_and_b64 s[26:27], s[26:27], exec
	s_cselect_b32 s13, s19, s25
	s_cselect_b32 s55, s18, s24
	s_add_u32 s22, s22, 0x40080
	s_addc_u32 s23, s23, 0
	s_add_u32 s56, s24, 0x100
	s_addc_u32 s57, s25, 0
	s_mov_b32 s58, -2
	s_waitcnt lgkmcnt(0)
	ds_read_b128 v[146:149], v143
	ds_read_b128 v[150:153], v143 offset:1024
	ds_read_b128 v[154:157], v143 offset:2048
	ds_read_b128 v[158:161], v143 offset:3072
	s_add_u32 s24, s22, 0xfffc0080
	s_addc_u32 s25, s23, -1
	s_cmp_eq_u32 s58, 12
	s_cselect_b32 s27, s15, s25
	s_cselect_b32 s26, s54, s24
	s_cselect_b32 s25, s13, s57
	s_cselect_b32 s24, s55, s56
	s_add_i32 m0, s21, 0xc000
	ds_read_b128 v[162:165], v144
	ds_read_b128 v[166:169], v144 offset:1024
	ds_read_b128 v[170:173], v144 offset:2048
	ds_read_b128 v[174:177], v144 offset:3072
	ds_read_b128 v[178:181], v144 offset:4096
	ds_read_b128 v[182:185], v144 offset:5120
	ds_read_b128 v[186:189], v144 offset:6144
	ds_read_b128 v[190:193], v144 offset:7168
	global_load_lds_dwordx4 v136, s[22:23]
	s_add_i32 m0, s21, 0xe000
	s_nop 0
	global_load_lds_dwordx4 v138, s[22:23]
	s_waitcnt lgkmcnt(8)
	s_waitcnt vmcnt(8)
	s_setprio 1
	s_barrier
	s_waitcnt lgkmcnt(0)
	v_mfma_f32_16x16x32_bf16 v[124:127], v[146:149], v[162:165], 0
	v_mfma_f32_16x16x32_bf16 v[120:123], v[154:157], v[162:165], 0
	v_mfma_f32_16x16x32_bf16 v[116:119], v[146:149], v[170:173], 0
	v_mfma_f32_16x16x32_bf16 v[108:111], v[154:157], v[170:173], 0
	v_mfma_f32_16x16x32_bf16 v[100:103], v[146:149], v[178:181], 0
	v_mfma_f32_16x16x32_bf16 v[92:95], v[154:157], v[178:181], 0
	v_mfma_f32_16x16x32_bf16 v[84:87], v[146:149], v[186:189], 0
	v_mfma_f32_16x16x32_bf16 v[76:79], v[154:157], v[186:189], 0
	v_mfma_f32_16x16x32_bf16 v[124:127], v[150:153], v[166:169], v[124:127]
	v_mfma_f32_16x16x32_bf16 v[120:123], v[158:161], v[166:169], v[120:123]
	v_mfma_f32_16x16x32_bf16 v[116:119], v[150:153], v[174:177], v[116:119]
	v_mfma_f32_16x16x32_bf16 v[108:111], v[158:161], v[174:177], v[108:111]
	v_mfma_f32_16x16x32_bf16 v[100:103], v[150:153], v[182:185], v[100:103]
	v_mfma_f32_16x16x32_bf16 v[92:95], v[158:161], v[182:185], v[92:95]
	v_mfma_f32_16x16x32_bf16 v[84:87], v[150:153], v[190:193], v[84:87]
	v_mfma_f32_16x16x32_bf16 v[76:79], v[158:161], v[190:193], v[76:79]
	s_setprio 0
	s_barrier
	s_add_i32 s59, s46, s34
	s_mov_b32 m0, s59
	ds_read_b128 v[194:197], v145
	ds_read_b128 v[202:205], v145 offset:1024
	ds_read_b128 v[206:209], v145 offset:2048
	ds_read_b128 v[210:213], v145 offset:3072
	global_load_lds_dwordx4 v130, s[24:25]
	s_add_i32 m0, s59, 0x2000
	s_nop 0
	global_load_lds_dwordx4 v134, s[24:25]
	s_waitcnt vmcnt(8)
	s_setprio 1
	s_barrier
	s_waitcnt lgkmcnt(0)
	v_mfma_f32_16x16x32_bf16 v[112:115], v[194:197], v[162:165], 0
	v_mfma_f32_16x16x32_bf16 v[104:107], v[206:209], v[162:165], 0
	v_mfma_f32_16x16x32_bf16 v[96:99], v[194:197], v[170:173], 0
	v_mfma_f32_16x16x32_bf16 v[88:91], v[206:209], v[170:173], 0
	v_mfma_f32_16x16x32_bf16 v[80:83], v[194:197], v[178:181], 0
	v_mfma_f32_16x16x32_bf16 v[72:75], v[206:209], v[178:181], 0
	v_mfma_f32_16x16x32_bf16 v[68:71], v[194:197], v[186:189], 0
	v_mfma_f32_16x16x32_bf16 v[64:67], v[206:209], v[186:189], 0
	v_mfma_f32_16x16x32_bf16 v[112:115], v[202:205], v[166:169], v[112:115]
	v_mfma_f32_16x16x32_bf16 v[104:107], v[210:213], v[166:169], v[104:107]
	v_mfma_f32_16x16x32_bf16 v[96:99], v[202:205], v[174:177], v[96:99]
	v_mfma_f32_16x16x32_bf16 v[88:91], v[210:213], v[174:177], v[88:91]
	v_mfma_f32_16x16x32_bf16 v[80:83], v[202:205], v[182:185], v[80:83]
	v_mfma_f32_16x16x32_bf16 v[72:75], v[210:213], v[182:185], v[72:75]
	v_mfma_f32_16x16x32_bf16 v[68:71], v[202:205], v[190:193], v[68:71]
	v_mfma_f32_16x16x32_bf16 v[64:67], v[210:213], v[190:193], v[64:67]
	s_setprio 0
	s_mov_b32 m0, s21
	v_lshl_add_u64 v[216:217], s[26:27], 0, v[128:129]
	s_barrier
	ds_read_b128 v[162:165], v144 offset:16384
	ds_read_b128 v[166:169], v144 offset:17408
	ds_read_b128 v[170:173], v144 offset:18432
	ds_read_b128 v[174:177], v144 offset:19456
	ds_read_b128 v[178:181], v144 offset:20480
	ds_read_b128 v[182:185], v144 offset:21504
	ds_read_b128 v[186:189], v144 offset:22528
	ds_read_b128 v[190:193], v144 offset:23552
	global_load_lds_dwordx4 v128, s[26:27]
	v_lshl_add_u64 v[218:219], s[26:27], 0, v[132:133]
	s_mov_b32 m0, s35
	s_nop 0
	global_load_lds_dwordx4 v132, s[26:27]
	s_setprio 1
	s_barrier
	s_waitcnt lgkmcnt(0)
	v_mfma_f32_16x16x32_bf16 v[60:63], v[146:149], v[162:165], 0
	v_mfma_f32_16x16x32_bf16 v[56:59], v[154:157], v[162:165], 0
	v_mfma_f32_16x16x32_bf16 v[52:55], v[146:149], v[170:173], 0
	v_mfma_f32_16x16x32_bf16 v[44:47], v[154:157], v[170:173], 0
	v_mfma_f32_16x16x32_bf16 v[36:39], v[146:149], v[178:181], 0
	v_mfma_f32_16x16x32_bf16 v[28:31], v[154:157], v[178:181], 0
	v_mfma_f32_16x16x32_bf16 v[20:23], v[146:149], v[186:189], 0
	v_mfma_f32_16x16x32_bf16 v[12:15], v[154:157], v[186:189], 0
	v_mfma_f32_16x16x32_bf16 v[60:63], v[150:153], v[166:169], v[60:63]
	v_mfma_f32_16x16x32_bf16 v[56:59], v[158:161], v[166:169], v[56:59]
	v_mfma_f32_16x16x32_bf16 v[52:55], v[150:153], v[174:177], v[52:55]
	v_mfma_f32_16x16x32_bf16 v[44:47], v[158:161], v[174:177], v[44:47]
	v_mfma_f32_16x16x32_bf16 v[36:39], v[150:153], v[182:185], v[36:39]
	v_mfma_f32_16x16x32_bf16 v[28:31], v[158:161], v[182:185], v[28:31]
	v_mfma_f32_16x16x32_bf16 v[20:23], v[150:153], v[190:193], v[20:23]
	v_mfma_f32_16x16x32_bf16 v[12:15], v[158:161], v[190:193], v[12:15]
	s_setprio 0
	s_barrier
; #define PG8_STAGE(bufoff, gbase, voff) do { _Pragma("unroll") for (int _i = 0; _i < 2; ++_i) \
;         __builtin_amdgcn_global_load_lds((const unsigned*)((const char*)(gbase) + (voff)[_i]), (LAS unsigned*)(lds + (bufoff) + ldsw + _i * 8192), 16, 0, 0); } while (0)
; #define PG8_LDA(dst, b, h) do { _Pragma("unroll") for (int m = 0; m < 4; ++m) _Pragma("unroll") for (int k = 0; k < 2; ++k) dst[m][k] = *(const LAS bf16x8*)(lds + PG8_SA(b, h) + aoff + m * 2048 + k * 1024); } while (0)
; #define PG8_LDB(dst, b, h) do { _Pragma("unroll") for (int n = 0; n < 2; ++n) _Pragma("unroll") for (int k = 0; k < 2; ++k) dst[n][k] = *(const LAS bf16x8*)(lds + PG8_SB(b, h) + boff + n * 2048 + k * 1024); } while (0)
; #define PG8_MMA(ai, bj, At, Bt) do { __builtin_amdgcn_s_setprio(1); _Pragma("unroll") for (int m = 0; m < 4; ++m) _Pragma("unroll") for (int n = 0; n < 2; ++n) _Pragma("unroll") for (int k = 0; k < 2; ++k) \
;         acc[ai][bj][m][n] = __builtin_amdgcn_mfma_f32_16x16x32_bf16(Bt[n][k], At[m][k], acc[ai][bj][m][n], 0, 0, 0); __builtin_amdgcn_s_setprio(0); } while (0)
; #define PG8_WAIT_V(n) asm volatile("s_waitcnt vmcnt(" #n ")" ::: "memory")
; #define PG8_WAIT_L(n) asm volatile("s_waitcnt lgkmcnt(" #n ")" ::: "memory")
; #define PG8_BAR __builtin_amdgcn_s_barrier()
; #define PG8_SCHED __builtin_amdgcn_sched_barrier(0)
; template <class Epi, class Sched>
; __device__ __forceinline__ void gemm_phase(LAS unsigned char* lds, const Gemm g, const Sched& S, const Epi& E) {
;     ...
;             PG8_STAGE(PG8_SB(0, 1), b2 + hstep, voffB);
;             PG8_WAIT_V(6); PG8_BAR; PG8_MMA(1, 1, At, B1); PG8_BAR;
;             PG8_LDB(B0, 1, 0); PG8_SCHED; PG8_LDA(At, 1, 0); PG8_STAGE(PG8_SA(0, 1), a2 + hstep, voffA);
;             PG8_WAIT_L(8); PG8_BAR; PG8_WAIT_L(0); PG8_MMA(0, 0, At, B0); PG8_BAR; PG8_SCHED;
;             PG8_LDB(B1, 1, 1); PG8_STAGE(PG8_SB(1, 0), b3, voffB);
;             PG8_BAR; PG8_WAIT_L(0); PG8_MMA(0, 1, At, B1); PG8_BAR;
;             PG8_LDA(At, 1, 1); PG8_STAGE(PG8_SA(1, 0), a3, voffA);
;             PG8_BAR; PG8_WAIT_L(0); PG8_MMA(1, 0, At, B0); PG8_BAR; PG8_SCHED;
;             PG8_STAGE(PG8_SB(1, 1), b3 + hstep, voffB);
;             PG8_WAIT_V(6); PG8_BAR; PG8_MMA(1, 1, At, B1); PG8_BAR;
	s_add_u32 s60, s24, 0x40000
	s_addc_u32 s61, s25, 0
	s_add_i32 s59, s47, s34
	s_mov_b32 m0, s59
	s_nop 0
	global_load_lds_dwordx4 v130, s[60:61]
	s_add_i32 m0, s59, 0x2000
	s_nop 0
	global_load_lds_dwordx4 v134, s[60:61]
	s_add_u32 s26, s26, 0x40000
	s_addc_u32 s27, s27, 0
	s_mov_b32 m0, s36
	s_nop 0
	global_load_lds_dwordx4 v128, s[26:27]
	s_mov_b32 m0, s37
	s_nop 0
	global_load_lds_dwordx4 v132, s[26:27]
	s_waitcnt vmcnt(10)
	s_setprio 1
	s_barrier
	v_mfma_f32_16x16x32_bf16 v[48:51], v[194:197], v[162:165], 0
	v_mfma_f32_16x16x32_bf16 v[40:43], v[206:209], v[162:165], 0
	v_mfma_f32_16x16x32_bf16 v[32:35], v[194:197], v[170:173], 0
	v_mfma_f32_16x16x32_bf16 v[24:27], v[206:209], v[170:173], 0
	v_mfma_f32_16x16x32_bf16 v[16:19], v[194:197], v[178:181], 0
	v_mfma_f32_16x16x32_bf16 v[8:11], v[206:209], v[178:181], 0
	v_mfma_f32_16x16x32_bf16 v[4:7], v[194:197], v[186:189], 0
	v_mfma_f32_16x16x32_bf16 v[0:3], v[206:209], v[186:189], 0
	v_mfma_f32_16x16x32_bf16 v[48:51], v[202:205], v[166:169], v[48:51]
	v_mfma_f32_16x16x32_bf16 v[40:43], v[210:213], v[166:169], v[40:43]
	v_mfma_f32_16x16x32_bf16 v[32:35], v[202:205], v[174:177], v[32:35]
	v_mfma_f32_16x16x32_bf16 v[24:27], v[210:213], v[174:177], v[24:27]
	v_mfma_f32_16x16x32_bf16 v[16:19], v[202:205], v[182:185], v[16:19]
	v_mfma_f32_16x16x32_bf16 v[8:11], v[210:213], v[182:185], v[8:11]
	v_mfma_f32_16x16x32_bf16 v[4:7], v[202:205], v[190:193], v[4:7]
	v_mfma_f32_16x16x32_bf16 v[0:3], v[210:213], v[190:193], v[0:3]
	s_setprio 0
	s_add_i32 s59, 0, 0x18000
	v_add_u32_e32 v158, s59, v142
	s_barrier
	ds_read_b128 v[146:149], v158
	ds_read_b128 v[150:153], v158 offset:1024
	ds_read_b128 v[154:157], v158 offset:2048
	ds_read_b128 v[158:161], v158 offset:3072
	ds_read_b128 v[162:165], v144 offset:32768
	ds_read_b128 v[166:169], v144 offset:33792
	ds_read_b128 v[170:173], v144 offset:34816
	ds_read_b128 v[174:177], v144 offset:35840
	ds_read_b128 v[178:181], v144 offset:36864
	ds_read_b128 v[182:185], v144 offset:37888
	ds_read_b128 v[186:189], v144 offset:38912
	ds_read_b128 v[190:193], v144 offset:39936
	s_waitcnt lgkmcnt(8)
	s_waitcnt vmcnt(8)
	s_setprio 1
	s_barrier
	s_waitcnt lgkmcnt(0)
	v_mfma_f32_16x16x32_bf16 v[124:127], v[146:149], v[162:165], v[124:127]
	v_mfma_f32_16x16x32_bf16 v[120:123], v[154:157], v[162:165], v[120:123]
	v_mfma_f32_16x16x32_bf16 v[116:119], v[146:149], v[170:173], v[116:119]
	v_mfma_f32_16x16x32_bf16 v[108:111], v[154:157], v[170:173], v[108:111]
	v_mfma_f32_16x16x32_bf16 v[100:103], v[146:149], v[178:181], v[100:103]
	v_mfma_f32_16x16x32_bf16 v[92:95], v[154:157], v[178:181], v[92:95]
	v_mfma_f32_16x16x32_bf16 v[84:87], v[146:149], v[186:189], v[84:87]
	v_mfma_f32_16x16x32_bf16 v[76:79], v[154:157], v[186:189], v[76:79]
	v_mfma_f32_16x16x32_bf16 v[124:127], v[150:153], v[166:169], v[124:127]
	v_mfma_f32_16x16x32_bf16 v[120:123], v[158:161], v[166:169], v[120:123]
	v_mfma_f32_16x16x32_bf16 v[116:119], v[150:153], v[174:177], v[116:119]
	v_mfma_f32_16x16x32_bf16 v[108:111], v[158:161], v[174:177], v[108:111]
	v_mfma_f32_16x16x32_bf16 v[100:103], v[150:153], v[182:185], v[100:103]
	v_mfma_f32_16x16x32_bf16 v[92:95], v[158:161], v[182:185], v[92:95]
	v_mfma_f32_16x16x32_bf16 v[84:87], v[150:153], v[190:193], v[84:87]
	v_mfma_f32_16x16x32_bf16 v[76:79], v[158:161], v[190:193], v[76:79]
	s_setprio 0
	s_barrier
	s_add_i32 s26, 0, 0x1c000
	s_add_i32 s27, s59, s34
	v_add_u32_e32 v210, s26, v142
	s_add_u32 s0, s24, 0x80
	s_addc_u32 s1, s25, 0
	s_mov_b32 m0, s27
	ds_read_b128 v[194:197], v210
	ds_read_b128 v[202:205], v210 offset:1024
	ds_read_b128 v[206:209], v210 offset:2048
	ds_read_b128 v[210:213], v210 offset:3072
	global_load_lds_dwordx4 v130, s[0:1]
	s_add_i32 m0, s27, 0x2000
	s_nop 0
	global_load_lds_dwordx4 v134, s[0:1]
	s_waitcnt vmcnt(8)
	s_setprio 1
	s_barrier
	s_waitcnt lgkmcnt(0)
	v_mfma_f32_16x16x32_bf16 v[112:115], v[194:197], v[162:165], v[112:115]
	v_mfma_f32_16x16x32_bf16 v[104:107], v[206:209], v[162:165], v[104:107]
	v_mfma_f32_16x16x32_bf16 v[96:99], v[194:197], v[170:173], v[96:99]
	v_mfma_f32_16x16x32_bf16 v[88:91], v[206:209], v[170:173], v[88:91]
	v_mfma_f32_16x16x32_bf16 v[80:83], v[194:197], v[178:181], v[80:83]
	v_mfma_f32_16x16x32_bf16 v[72:75], v[206:209], v[178:181], v[72:75]
	v_mfma_f32_16x16x32_bf16 v[68:71], v[194:197], v[186:189], v[68:71]
	v_mfma_f32_16x16x32_bf16 v[64:67], v[206:209], v[186:189], v[64:67]
	v_mfma_f32_16x16x32_bf16 v[112:115], v[202:205], v[166:169], v[112:115]
	v_mfma_f32_16x16x32_bf16 v[104:107], v[210:213], v[166:169], v[104:107]
	v_mfma_f32_16x16x32_bf16 v[96:99], v[202:205], v[174:177], v[96:99]
	v_mfma_f32_16x16x32_bf16 v[88:91], v[210:213], v[174:177], v[88:91]
	v_mfma_f32_16x16x32_bf16 v[80:83], v[202:205], v[182:185], v[80:83]
	v_mfma_f32_16x16x32_bf16 v[72:75], v[210:213], v[182:185], v[72:75]
	v_mfma_f32_16x16x32_bf16 v[68:71], v[202:205], v[190:193], v[68:71]
	v_mfma_f32_16x16x32_bf16 v[64:67], v[210:213], v[190:193], v[64:67]
	s_setprio 0
	s_mov_b32 m0, s43
	s_mov_b64 s[0:1], 0x80
	v_lshl_add_u64 v[198:199], v[216:217], 0, s[0:1]
	s_barrier
	ds_read_b128 v[162:165], v144 offset:49152
	ds_read_b128 v[166:169], v144 offset:50176
	ds_read_b128 v[170:173], v144 offset:51200
	ds_read_b128 v[174:177], v144 offset:52224
	ds_read_b128 v[178:181], v144 offset:53248
	ds_read_b128 v[182:185], v144 offset:54272
	ds_read_b128 v[186:189], v144 offset:55296
	ds_read_b128 v[190:193], v144 offset:56320
	global_load_lds_dwordx4 v[198:199], off
	v_lshl_add_u64 v[198:199], v[218:219], 0, s[0:1]
	s_mov_b32 m0, s44
	s_nop 0
	global_load_lds_dwordx4 v[198:199], off
	s_setprio 1
	s_barrier
; #define PG8_STAGE(bufoff, gbase, voff) do { _Pragma("unroll") for (int _i = 0; _i < 2; ++_i) \
;         __builtin_amdgcn_global_load_lds((const unsigned*)((const char*)(gbase) + (voff)[_i]), (LAS unsigned*)(lds + (bufoff) + ldsw + _i * 8192), 16, 0, 0); } while (0)
; #define PG8_LDA(dst, b, h) do { _Pragma("unroll") for (int m = 0; m < 4; ++m) _Pragma("unroll") for (int k = 0; k < 2; ++k) dst[m][k] = *(const LAS bf16x8*)(lds + PG8_SA(b, h) + aoff + m * 2048 + k * 1024); } while (0)
; #define PG8_LDB(dst, b, h) do { _Pragma("unroll") for (int n = 0; n < 2; ++n) _Pragma("unroll") for (int k = 0; k < 2; ++k) dst[n][k] = *(const LAS bf16x8*)(lds + PG8_SB(b, h) + boff + n * 2048 + k * 1024); } while (0)
; #define PG8_WAIT_V(n) asm volatile("s_waitcnt vmcnt(" #n ")" ::: "memory")
; #define PG8_WAIT_L(n) asm volatile("s_waitcnt lgkmcnt(" #n ")" ::: "memory")
; #define PG8_BAR __builtin_amdgcn_s_barrier()
; #define PG8_SCHED __builtin_amdgcn_sched_barrier(0)
; template <class Epi, class Sched>
; __device__ __forceinline__ void gemm_phase(LAS unsigned char* lds, const Gemm g, const Sched& S, const Epi& E) {
;     ...
;             PG8_LDB(B0, 0, 0); PG8_SCHED; PG8_LDA(At, 0, 0); PG8_STAGE(PG8_SA(1, 1), a1 + hstep, voffA);
;             PG8_WAIT_L(8); PG8_BAR; PG8_WAIT_L(0); PG8_MMA(0, 0, At, B0); PG8_BAR; PG8_SCHED;
;             PG8_LDB(B1, 0, 1); PG8_STAGE(PG8_SB(0, 0), b2, voffB);
;             PG8_BAR; PG8_WAIT_L(0); PG8_MMA(0, 1, At, B1); PG8_BAR;
;             PG8_LDA(At, 0, 1); PG8_STAGE(PG8_SA(0, 0), a2, voffA);
;             PG8_BAR; PG8_WAIT_L(0); PG8_MMA(1, 0, At, B0); PG8_BAR; PG8_SCHED;
;             PG8_STAGE(PG8_SB(0, 1), b2 + hstep, voffB);
;             PG8_WAIT_V(6); PG8_BAR; PG8_MMA(1, 1, At, B1); PG8_BAR;
;             PG8_LDB(B0, 1, 0); PG8_SCHED; PG8_LDA(At, 1, 0); PG8_STAGE(PG8_SA(0, 1), a2 + hstep, voffA);
;             PG8_WAIT_L(8); PG8_BAR; PG8_WAIT_L(0); PG8_MMA(0, 0, At, B0); PG8_BAR; PG8_SCHED;
;             PG8_LDB(B1, 1, 1); PG8_STAGE(PG8_SB(1, 0), b3, voffB);
;             PG8_BAR; PG8_WAIT_L(0); PG8_MMA(0, 1, At, B1); PG8_BAR;
;             PG8_LDA(At, 1, 1); PG8_STAGE(PG8_SA(1, 0), a3, voffA);
;             PG8_BAR; PG8_WAIT_L(0); PG8_MMA(1, 0, At, B0); PG8_BAR; PG8_SCHED;
;             PG8_STAGE(PG8_SB(1, 1), b3 + hstep, voffB);
;             PG8_WAIT_V(6); PG8_BAR; PG8_MMA(1, 1, At, B1); PG8_BAR;
	s_waitcnt lgkmcnt(0)
	v_mfma_f32_16x16x32_bf16 v[60:63], v[146:149], v[162:165], v[60:63]
	v_mfma_f32_16x16x32_bf16 v[56:59], v[154:157], v[162:165], v[56:59]
	v_mfma_f32_16x16x32_bf16 v[52:55], v[146:149], v[170:173], v[52:55]
	v_mfma_f32_16x16x32_bf16 v[44:47], v[154:157], v[170:173], v[44:47]
	v_mfma_f32_16x16x32_bf16 v[36:39], v[146:149], v[178:181], v[36:39]
	v_mfma_f32_16x16x32_bf16 v[28:31], v[154:157], v[178:181], v[28:31]
	v_mfma_f32_16x16x32_bf16 v[20:23], v[146:149], v[186:189], v[20:23]
	v_mfma_f32_16x16x32_bf16 v[12:15], v[154:157], v[186:189], v[12:15]
	v_mfma_f32_16x16x32_bf16 v[60:63], v[150:153], v[166:169], v[60:63]
	v_mfma_f32_16x16x32_bf16 v[56:59], v[158:161], v[166:169], v[56:59]
	v_mfma_f32_16x16x32_bf16 v[52:55], v[150:153], v[174:177], v[52:55]
	v_mfma_f32_16x16x32_bf16 v[44:47], v[158:161], v[174:177], v[44:47]
	v_mfma_f32_16x16x32_bf16 v[36:39], v[150:153], v[182:185], v[36:39]
	v_mfma_f32_16x16x32_bf16 v[28:31], v[158:161], v[182:185], v[28:31]
	v_mfma_f32_16x16x32_bf16 v[20:23], v[150:153], v[190:193], v[20:23]
	v_mfma_f32_16x16x32_bf16 v[12:15], v[158:161], v[190:193], v[12:15]
	s_setprio 0
	s_barrier
	s_add_u32 s24, s24, 0x40080
	s_addc_u32 s25, s25, 0
	s_add_i32 s26, s26, s34
	s_mov_b32 m0, s26
	s_nop 0
	global_load_lds_dwordx4 v130, s[24:25]
	s_add_i32 m0, s26, 0x2000
	s_nop 0
	global_load_lds_dwordx4 v134, s[24:25]
	s_waitcnt vmcnt(8)
	s_setprio 1
	s_barrier
	v_mfma_f32_16x16x32_bf16 v[48:51], v[194:197], v[162:165], v[48:51]
	v_mfma_f32_16x16x32_bf16 v[40:43], v[206:209], v[162:165], v[40:43]
	v_mfma_f32_16x16x32_bf16 v[32:35], v[194:197], v[170:173], v[32:35]
	v_mfma_f32_16x16x32_bf16 v[24:27], v[206:209], v[170:173], v[24:27]
	v_mfma_f32_16x16x32_bf16 v[16:19], v[194:197], v[178:181], v[16:19]
	v_mfma_f32_16x16x32_bf16 v[8:11], v[206:209], v[178:181], v[8:11]
	v_mfma_f32_16x16x32_bf16 v[4:7], v[194:197], v[186:189], v[4:7]
	v_mfma_f32_16x16x32_bf16 v[0:3], v[206:209], v[186:189], v[0:3]
	v_mfma_f32_16x16x32_bf16 v[48:51], v[202:205], v[166:169], v[48:51]
	v_mfma_f32_16x16x32_bf16 v[40:43], v[210:213], v[166:169], v[40:43]
	v_mfma_f32_16x16x32_bf16 v[32:35], v[202:205], v[174:177], v[32:35]
	v_mfma_f32_16x16x32_bf16 v[24:27], v[210:213], v[174:177], v[24:27]
	v_mfma_f32_16x16x32_bf16 v[16:19], v[202:205], v[182:185], v[16:19]
	v_mfma_f32_16x16x32_bf16 v[8:11], v[210:213], v[182:185], v[8:11]
	v_mfma_f32_16x16x32_bf16 v[4:7], v[202:205], v[190:193], v[4:7]
	v_mfma_f32_16x16x32_bf16 v[0:3], v[210:213], v[190:193], v[0:3]
	s_setprio 0
	s_add_i32 s58, s58, 2
	s_add_u32 s22, s22, 0x100
	s_addc_u32 s23, s23, 0
	s_add_u32 s56, s56, 0x100
	s_addc_u32 s57, s57, 0
	s_cmp_gt_u32 s58, 13
	s_barrier
.LBB0_713:
	ds_read_b128 v[146:149], v143
	ds_read_b128 v[150:153], v143 offset:1024
	ds_read_b128 v[154:157], v143 offset:2048
	ds_read_b128 v[158:161], v143 offset:3072
	s_add_u32 s24, s22, 0xfffc0080
	s_addc_u32 s25, s23, -1
	s_cmp_eq_u32 s58, 12
	s_cselect_b32 s27, s15, s25
	s_cselect_b32 s26, s54, s24
	s_cselect_b32 s25, s13, s57
	s_cselect_b32 s24, s55, s56
	s_add_i32 m0, s21, 0xc000
	ds_read_b128 v[162:165], v144
	ds_read_b128 v[166:169], v144 offset:1024
	ds_read_b128 v[170:173], v144 offset:2048
	ds_read_b128 v[174:177], v144 offset:3072
	ds_read_b128 v[178:181], v144 offset:4096
	ds_read_b128 v[182:185], v144 offset:5120
	ds_read_b128 v[186:189], v144 offset:6144
	ds_read_b128 v[190:193], v144 offset:7168
	global_load_lds_dwordx4 v136, s[22:23]
	s_add_i32 m0, s21, 0xe000
	s_nop 0
	global_load_lds_dwordx4 v138, s[22:23]
	s_waitcnt lgkmcnt(8)
	s_waitcnt vmcnt(8)
	s_setprio 1
	s_barrier
	s_waitcnt lgkmcnt(0)
	v_mfma_f32_16x16x32_bf16 v[124:127], v[146:149], v[162:165], v[124:127]
	v_mfma_f32_16x16x32_bf16 v[120:123], v[154:157], v[162:165], v[120:123]
	v_mfma_f32_16x16x32_bf16 v[116:119], v[146:149], v[170:173], v[116:119]
	v_mfma_f32_16x16x32_bf16 v[108:111], v[154:157], v[170:173], v[108:111]
	v_mfma_f32_16x16x32_bf16 v[100:103], v[146:149], v[178:181], v[100:103]
	v_mfma_f32_16x16x32_bf16 v[92:95], v[154:157], v[178:181], v[92:95]
	v_mfma_f32_16x16x32_bf16 v[84:87], v[146:149], v[186:189], v[84:87]
	v_mfma_f32_16x16x32_bf16 v[76:79], v[154:157], v[186:189], v[76:79]
	v_mfma_f32_16x16x32_bf16 v[124:127], v[150:153], v[166:169], v[124:127]
	v_mfma_f32_16x16x32_bf16 v[120:123], v[158:161], v[166:169], v[120:123]
	v_mfma_f32_16x16x32_bf16 v[116:119], v[150:153], v[174:177], v[116:119]
	v_mfma_f32_16x16x32_bf16 v[108:111], v[158:161], v[174:177], v[108:111]
	v_mfma_f32_16x16x32_bf16 v[100:103], v[150:153], v[182:185], v[100:103]
	v_mfma_f32_16x16x32_bf16 v[92:95], v[158:161], v[182:185], v[92:95]
	v_mfma_f32_16x16x32_bf16 v[84:87], v[150:153], v[190:193], v[84:87]
	v_mfma_f32_16x16x32_bf16 v[76:79], v[158:161], v[190:193], v[76:79]
	s_setprio 0
	s_barrier
	s_add_i32 s59, s46, s34
	s_mov_b32 m0, s59
	ds_read_b128 v[194:197], v145
	ds_read_b128 v[202:205], v145 offset:1024
	ds_read_b128 v[206:209], v145 offset:2048
	ds_read_b128 v[210:213], v145 offset:3072
	global_load_lds_dwordx4 v130, s[24:25]
	s_add_i32 m0, s59, 0x2000
	s_nop 0
	global_load_lds_dwordx4 v134, s[24:25]
	s_waitcnt vmcnt(8)
	s_setprio 1
	s_barrier
; #define PG8_STAGE(bufoff, gbase, voff) do { _Pragma("unroll") for (int _i = 0; _i < 2; ++_i) \
;         __builtin_amdgcn_global_load_lds((const unsigned*)((const char*)(gbase) + (voff)[_i]), (LAS unsigned*)(lds + (bufoff) + ldsw + _i * 8192), 16, 0, 0); } while (0)
; #define PG8_LDA(dst, b, h) do { _Pragma("unroll") for (int m = 0; m < 4; ++m) _Pragma("unroll") for (int k = 0; k < 2; ++k) dst[m][k] = *(const LAS bf16x8*)(lds + PG8_SA(b, h) + aoff + m * 2048 + k * 1024); } while (0)
; #define PG8_LDB(dst, b, h) do { _Pragma("unroll") for (int n = 0; n < 2; ++n) _Pragma("unroll") for (int k = 0; k < 2; ++k) dst[n][k] = *(const LAS bf16x8*)(lds + PG8_SB(b, h) + boff + n * 2048 + k * 1024); } while (0)
; #define PG8_MMA(ai, bj, At, Bt) do { __builtin_amdgcn_s_setprio(1); _Pragma("unroll") for (int m = 0; m < 4; ++m) _Pragma("unroll") for (int n = 0; n < 2; ++n) _Pragma("unroll") for (int k = 0; k < 2; ++k) \
;         acc[ai][bj][m][n] = __builtin_amdgcn_mfma_f32_16x16x32_bf16(Bt[n][k], At[m][k], acc[ai][bj][m][n], 0, 0, 0); __builtin_amdgcn_s_setprio(0); } while (0)
; #define PG8_WAIT_V(n) asm volatile("s_waitcnt vmcnt(" #n ")" ::: "memory")
; #define PG8_WAIT_L(n) asm volatile("s_waitcnt lgkmcnt(" #n ")" ::: "memory")
; #define PG8_BAR __builtin_amdgcn_s_barrier()
; #define PG8_SCHED __builtin_amdgcn_sched_barrier(0)
; template <class Epi, class Sched>
; __device__ __forceinline__ void gemm_phase(LAS unsigned char* lds, const Gemm g, const Sched& S, const Epi& E) {
;     ...
;             PG8_BAR; PG8_WAIT_L(0); PG8_MMA(0, 1, At, B1); PG8_BAR;
;             PG8_LDA(At, 0, 1); PG8_STAGE(PG8_SA(0, 0), a2, voffA);
;             PG8_BAR; PG8_WAIT_L(0); PG8_MMA(1, 0, At, B0); PG8_BAR; PG8_SCHED;
;             PG8_STAGE(PG8_SB(0, 1), b2 + hstep, voffB);
;             PG8_WAIT_V(6); PG8_BAR; PG8_MMA(1, 1, At, B1); PG8_BAR;
;             PG8_LDB(B0, 1, 0); PG8_SCHED; PG8_LDA(At, 1, 0); PG8_STAGE(PG8_SA(0, 1), a2 + hstep, voffA);
;             PG8_WAIT_L(8); PG8_BAR; PG8_WAIT_L(0); PG8_MMA(0, 0, At, B0); PG8_BAR; PG8_SCHED;
	s_waitcnt lgkmcnt(0)
	v_mfma_f32_16x16x32_bf16 v[112:115], v[194:197], v[162:165], v[112:115]
	v_mfma_f32_16x16x32_bf16 v[104:107], v[206:209], v[162:165], v[104:107]
	v_mfma_f32_16x16x32_bf16 v[96:99], v[194:197], v[170:173], v[96:99]
	v_mfma_f32_16x16x32_bf16 v[88:91], v[206:209], v[170:173], v[88:91]
	v_mfma_f32_16x16x32_bf16 v[80:83], v[194:197], v[178:181], v[80:83]
	v_mfma_f32_16x16x32_bf16 v[72:75], v[206:209], v[178:181], v[72:75]
	v_mfma_f32_16x16x32_bf16 v[68:71], v[194:197], v[186:189], v[68:71]
	v_mfma_f32_16x16x32_bf16 v[64:67], v[206:209], v[186:189], v[64:67]
	v_mfma_f32_16x16x32_bf16 v[112:115], v[202:205], v[166:169], v[112:115]
	v_mfma_f32_16x16x32_bf16 v[104:107], v[210:213], v[166:169], v[104:107]
	v_mfma_f32_16x16x32_bf16 v[96:99], v[202:205], v[174:177], v[96:99]
	v_mfma_f32_16x16x32_bf16 v[88:91], v[210:213], v[174:177], v[88:91]
	v_mfma_f32_16x16x32_bf16 v[80:83], v[202:205], v[182:185], v[80:83]
	v_mfma_f32_16x16x32_bf16 v[72:75], v[210:213], v[182:185], v[72:75]
	v_mfma_f32_16x16x32_bf16 v[68:71], v[202:205], v[190:193], v[68:71]
	v_mfma_f32_16x16x32_bf16 v[64:67], v[210:213], v[190:193], v[64:67]
	s_setprio 0
	s_mov_b32 m0, s21
	v_lshl_add_u64 v[216:217], s[26:27], 0, v[128:129]
	s_barrier
	ds_read_b128 v[162:165], v144 offset:16384
	ds_read_b128 v[166:169], v144 offset:17408
	ds_read_b128 v[170:173], v144 offset:18432
	ds_read_b128 v[174:177], v144 offset:19456
	ds_read_b128 v[178:181], v144 offset:20480
	ds_read_b128 v[182:185], v144 offset:21504
	ds_read_b128 v[186:189], v144 offset:22528
	ds_read_b128 v[190:193], v144 offset:23552
	global_load_lds_dwordx4 v128, s[26:27]
	v_lshl_add_u64 v[218:219], s[26:27], 0, v[132:133]
	s_mov_b32 m0, s35
	s_nop 0
	global_load_lds_dwordx4 v132, s[26:27]
	s_setprio 1
	s_barrier
	s_waitcnt lgkmcnt(0)
	v_mfma_f32_16x16x32_bf16 v[60:63], v[146:149], v[162:165], v[60:63]
	v_mfma_f32_16x16x32_bf16 v[56:59], v[154:157], v[162:165], v[56:59]
	v_mfma_f32_16x16x32_bf16 v[52:55], v[146:149], v[170:173], v[52:55]
	v_mfma_f32_16x16x32_bf16 v[44:47], v[154:157], v[170:173], v[44:47]
	v_mfma_f32_16x16x32_bf16 v[36:39], v[146:149], v[178:181], v[36:39]
	v_mfma_f32_16x16x32_bf16 v[28:31], v[154:157], v[178:181], v[28:31]
	v_mfma_f32_16x16x32_bf16 v[20:23], v[146:149], v[186:189], v[20:23]
	v_mfma_f32_16x16x32_bf16 v[12:15], v[154:157], v[186:189], v[12:15]
	v_mfma_f32_16x16x32_bf16 v[60:63], v[150:153], v[166:169], v[60:63]
	v_mfma_f32_16x16x32_bf16 v[56:59], v[158:161], v[166:169], v[56:59]
	v_mfma_f32_16x16x32_bf16 v[52:55], v[150:153], v[174:177], v[52:55]
	v_mfma_f32_16x16x32_bf16 v[44:47], v[158:161], v[174:177], v[44:47]
	v_mfma_f32_16x16x32_bf16 v[36:39], v[150:153], v[182:185], v[36:39]
	v_mfma_f32_16x16x32_bf16 v[28:31], v[158:161], v[182:185], v[28:31]
	v_mfma_f32_16x16x32_bf16 v[20:23], v[150:153], v[190:193], v[20:23]
	v_mfma_f32_16x16x32_bf16 v[12:15], v[158:161], v[190:193], v[12:15]
	s_setprio 0
	s_barrier
	s_add_u32 s60, s24, 0x40000
	s_addc_u32 s61, s25, 0
	s_add_i32 s59, s47, s34
	s_mov_b32 m0, s59
	s_nop 0
	global_load_lds_dwordx4 v130, s[60:61]
	s_add_i32 m0, s59, 0x2000
	s_nop 0
	global_load_lds_dwordx4 v134, s[60:61]
	s_add_u32 s26, s26, 0x40000
	s_addc_u32 s27, s27, 0
	s_mov_b32 m0, s36
	s_nop 0
	global_load_lds_dwordx4 v128, s[26:27]
	s_mov_b32 m0, s37
	s_nop 0
	global_load_lds_dwordx4 v132, s[26:27]
	s_waitcnt vmcnt(10)
	s_setprio 1
	s_barrier
	v_mfma_f32_16x16x32_bf16 v[48:51], v[194:197], v[162:165], v[48:51]
	v_mfma_f32_16x16x32_bf16 v[40:43], v[206:209], v[162:165], v[40:43]
	v_mfma_f32_16x16x32_bf16 v[32:35], v[194:197], v[170:173], v[32:35]
	v_mfma_f32_16x16x32_bf16 v[24:27], v[206:209], v[170:173], v[24:27]
	v_mfma_f32_16x16x32_bf16 v[16:19], v[194:197], v[178:181], v[16:19]
	v_mfma_f32_16x16x32_bf16 v[8:11], v[206:209], v[178:181], v[8:11]
	v_mfma_f32_16x16x32_bf16 v[4:7], v[194:197], v[186:189], v[4:7]
	v_mfma_f32_16x16x32_bf16 v[0:3], v[206:209], v[186:189], v[0:3]
	v_mfma_f32_16x16x32_bf16 v[48:51], v[202:205], v[166:169], v[48:51]
	v_mfma_f32_16x16x32_bf16 v[40:43], v[210:213], v[166:169], v[40:43]
	v_mfma_f32_16x16x32_bf16 v[32:35], v[202:205], v[174:177], v[32:35]
	v_mfma_f32_16x16x32_bf16 v[24:27], v[210:213], v[174:177], v[24:27]
	v_mfma_f32_16x16x32_bf16 v[16:19], v[202:205], v[182:185], v[16:19]
	v_mfma_f32_16x16x32_bf16 v[8:11], v[210:213], v[182:185], v[8:11]
	v_mfma_f32_16x16x32_bf16 v[4:7], v[202:205], v[190:193], v[4:7]
	v_mfma_f32_16x16x32_bf16 v[0:3], v[210:213], v[190:193], v[0:3]
	s_setprio 0
	s_add_i32 s59, 0, 0x18000
	v_add_u32_e32 v158, s59, v142
	s_barrier
	ds_read_b128 v[146:149], v158
	ds_read_b128 v[150:153], v158 offset:1024
	ds_read_b128 v[154:157], v158 offset:2048
	ds_read_b128 v[158:161], v158 offset:3072
	ds_read_b128 v[162:165], v144 offset:32768
	ds_read_b128 v[166:169], v144 offset:33792
	ds_read_b128 v[170:173], v144 offset:34816
	ds_read_b128 v[174:177], v144 offset:35840
	ds_read_b128 v[178:181], v144 offset:36864
	ds_read_b128 v[182:185], v144 offset:37888
	ds_read_b128 v[186:189], v144 offset:38912
	ds_read_b128 v[190:193], v144 offset:39936
	s_waitcnt lgkmcnt(8)
	s_waitcnt vmcnt(8)
	s_setprio 1
	s_barrier
; #define PG8_STAGE(bufoff, gbase, voff) do { _Pragma("unroll") for (int _i = 0; _i < 2; ++_i) \
;         __builtin_amdgcn_global_load_lds((const unsigned*)((const char*)(gbase) + (voff)[_i]), (LAS unsigned*)(lds + (bufoff) + ldsw + _i * 8192), 16, 0, 0); } while (0)
; #define PG8_LDA(dst, b, h) do { _Pragma("unroll") for (int m = 0; m < 4; ++m) _Pragma("unroll") for (int k = 0; k < 2; ++k) dst[m][k] = *(const LAS bf16x8*)(lds + PG8_SA(b, h) + aoff + m * 2048 + k * 1024); } while (0)
; #define PG8_LDB(dst, b, h) do { _Pragma("unroll") for (int n = 0; n < 2; ++n) _Pragma("unroll") for (int k = 0; k < 2; ++k) dst[n][k] = *(const LAS bf16x8*)(lds + PG8_SB(b, h) + boff + n * 2048 + k * 1024); } while (0)
; #define PG8_MMA(ai, bj, At, Bt) do { __builtin_amdgcn_s_setprio(1); _Pragma("unroll") for (int m = 0; m < 4; ++m) _Pragma("unroll") for (int n = 0; n < 2; ++n) _Pragma("unroll") for (int k = 0; k < 2; ++k) \
;         acc[ai][bj][m][n] = __builtin_amdgcn_mfma_f32_16x16x32_bf16(Bt[n][k], At[m][k], acc[ai][bj][m][n], 0, 0, 0); __builtin_amdgcn_s_setprio(0); } while (0)
; #define PG8_WAIT_V(n) asm volatile("s_waitcnt vmcnt(" #n ")" ::: "memory")
; #define PG8_WAIT_L(n) asm volatile("s_waitcnt lgkmcnt(" #n ")" ::: "memory")
; #define PG8_BAR __builtin_amdgcn_s_barrier()
; #define PG8_SCHED __builtin_amdgcn_sched_barrier(0)
; template <class Epi, class Sched>
; __device__ __forceinline__ void gemm_phase(LAS unsigned char* lds, const Gemm g, const Sched& S, const Epi& E) {
;     ...
;             PG8_WAIT_L(8); PG8_BAR; PG8_WAIT_L(0); PG8_MMA(0, 0, At, B0); PG8_BAR; PG8_SCHED;
;             PG8_LDB(B1, 1, 1); PG8_STAGE(PG8_SB(1, 0), b3, voffB);
;             PG8_BAR; PG8_WAIT_L(0); PG8_MMA(0, 1, At, B1); PG8_BAR;
;             PG8_LDA(At, 1, 1); PG8_STAGE(PG8_SA(1, 0), a3, voffA);
;             PG8_BAR; PG8_WAIT_L(0); PG8_MMA(1, 0, At, B0); PG8_BAR; PG8_SCHED;
;             PG8_STAGE(PG8_SB(1, 1), b3 + hstep, voffB);
;             PG8_WAIT_V(6); PG8_BAR; PG8_MMA(1, 1, At, B1); PG8_BAR;
	s_waitcnt lgkmcnt(0)
	v_mfma_f32_16x16x32_bf16 v[124:127], v[146:149], v[162:165], v[124:127]
	v_mfma_f32_16x16x32_bf16 v[120:123], v[154:157], v[162:165], v[120:123]
	v_mfma_f32_16x16x32_bf16 v[116:119], v[146:149], v[170:173], v[116:119]
	v_mfma_f32_16x16x32_bf16 v[108:111], v[154:157], v[170:173], v[108:111]
	v_mfma_f32_16x16x32_bf16 v[100:103], v[146:149], v[178:181], v[100:103]
	v_mfma_f32_16x16x32_bf16 v[92:95], v[154:157], v[178:181], v[92:95]
	v_mfma_f32_16x16x32_bf16 v[84:87], v[146:149], v[186:189], v[84:87]
	v_mfma_f32_16x16x32_bf16 v[76:79], v[154:157], v[186:189], v[76:79]
	v_mfma_f32_16x16x32_bf16 v[124:127], v[150:153], v[166:169], v[124:127]
	v_mfma_f32_16x16x32_bf16 v[120:123], v[158:161], v[166:169], v[120:123]
	v_mfma_f32_16x16x32_bf16 v[116:119], v[150:153], v[174:177], v[116:119]
	v_mfma_f32_16x16x32_bf16 v[108:111], v[158:161], v[174:177], v[108:111]
	v_mfma_f32_16x16x32_bf16 v[100:103], v[150:153], v[182:185], v[100:103]
	v_mfma_f32_16x16x32_bf16 v[92:95], v[158:161], v[182:185], v[92:95]
	v_mfma_f32_16x16x32_bf16 v[84:87], v[150:153], v[190:193], v[84:87]
	v_mfma_f32_16x16x32_bf16 v[76:79], v[158:161], v[190:193], v[76:79]
	s_setprio 0
	s_barrier
	s_add_i32 s26, 0, 0x1c000
	s_add_i32 s27, s59, s34
	v_add_u32_e32 v210, s26, v142
	s_add_u32 s0, s24, 0x80
	s_addc_u32 s1, s25, 0
	s_mov_b32 m0, s27
	ds_read_b128 v[194:197], v210
	ds_read_b128 v[202:205], v210 offset:1024
	ds_read_b128 v[206:209], v210 offset:2048
	ds_read_b128 v[210:213], v210 offset:3072
	global_load_lds_dwordx4 v130, s[0:1]
	s_add_i32 m0, s27, 0x2000
	s_nop 0
	global_load_lds_dwordx4 v134, s[0:1]
	s_waitcnt vmcnt(8)
	s_setprio 1
	s_barrier
	s_waitcnt lgkmcnt(0)
	v_mfma_f32_16x16x32_bf16 v[112:115], v[194:197], v[162:165], v[112:115]
	v_mfma_f32_16x16x32_bf16 v[104:107], v[206:209], v[162:165], v[104:107]
	v_mfma_f32_16x16x32_bf16 v[96:99], v[194:197], v[170:173], v[96:99]
	v_mfma_f32_16x16x32_bf16 v[88:91], v[206:209], v[170:173], v[88:91]
	v_mfma_f32_16x16x32_bf16 v[80:83], v[194:197], v[178:181], v[80:83]
	v_mfma_f32_16x16x32_bf16 v[72:75], v[206:209], v[178:181], v[72:75]
	v_mfma_f32_16x16x32_bf16 v[68:71], v[194:197], v[186:189], v[68:71]
	v_mfma_f32_16x16x32_bf16 v[64:67], v[206:209], v[186:189], v[64:67]
	v_mfma_f32_16x16x32_bf16 v[112:115], v[202:205], v[166:169], v[112:115]
	v_mfma_f32_16x16x32_bf16 v[104:107], v[210:213], v[166:169], v[104:107]
	v_mfma_f32_16x16x32_bf16 v[96:99], v[202:205], v[174:177], v[96:99]
	v_mfma_f32_16x16x32_bf16 v[88:91], v[210:213], v[174:177], v[88:91]
	v_mfma_f32_16x16x32_bf16 v[80:83], v[202:205], v[182:185], v[80:83]
	v_mfma_f32_16x16x32_bf16 v[72:75], v[210:213], v[182:185], v[72:75]
	v_mfma_f32_16x16x32_bf16 v[68:71], v[202:205], v[190:193], v[68:71]
	v_mfma_f32_16x16x32_bf16 v[64:67], v[210:213], v[190:193], v[64:67]
	s_setprio 0
	s_mov_b32 m0, s43
	s_mov_b64 s[0:1], 0x80
	v_lshl_add_u64 v[198:199], v[216:217], 0, s[0:1]
	s_barrier
	ds_read_b128 v[162:165], v144 offset:49152
	ds_read_b128 v[166:169], v144 offset:50176
	ds_read_b128 v[170:173], v144 offset:51200
	ds_read_b128 v[174:177], v144 offset:52224
	ds_read_b128 v[178:181], v144 offset:53248
	ds_read_b128 v[182:185], v144 offset:54272
	ds_read_b128 v[186:189], v144 offset:55296
	ds_read_b128 v[190:193], v144 offset:56320
	global_load_lds_dwordx4 v[198:199], off
	v_lshl_add_u64 v[198:199], v[218:219], 0, s[0:1]
	s_mov_b32 m0, s44
	s_nop 0
	global_load_lds_dwordx4 v[198:199], off
	s_setprio 1
	s_barrier
	s_waitcnt lgkmcnt(0)
	v_mfma_f32_16x16x32_bf16 v[60:63], v[146:149], v[162:165], v[60:63]
	v_mfma_f32_16x16x32_bf16 v[56:59], v[154:157], v[162:165], v[56:59]
	v_mfma_f32_16x16x32_bf16 v[52:55], v[146:149], v[170:173], v[52:55]
	v_mfma_f32_16x16x32_bf16 v[44:47], v[154:157], v[170:173], v[44:47]
	v_mfma_f32_16x16x32_bf16 v[36:39], v[146:149], v[178:181], v[36:39]
	v_mfma_f32_16x16x32_bf16 v[28:31], v[154:157], v[178:181], v[28:31]
	v_mfma_f32_16x16x32_bf16 v[20:23], v[146:149], v[186:189], v[20:23]
	v_mfma_f32_16x16x32_bf16 v[12:15], v[154:157], v[186:189], v[12:15]
	v_mfma_f32_16x16x32_bf16 v[60:63], v[150:153], v[166:169], v[60:63]
	v_mfma_f32_16x16x32_bf16 v[56:59], v[158:161], v[166:169], v[56:59]
	v_mfma_f32_16x16x32_bf16 v[52:55], v[150:153], v[174:177], v[52:55]
	v_mfma_f32_16x16x32_bf16 v[44:47], v[158:161], v[174:177], v[44:47]
	v_mfma_f32_16x16x32_bf16 v[36:39], v[150:153], v[182:185], v[36:39]
	v_mfma_f32_16x16x32_bf16 v[28:31], v[158:161], v[182:185], v[28:31]
	v_mfma_f32_16x16x32_bf16 v[20:23], v[150:153], v[190:193], v[20:23]
	v_mfma_f32_16x16x32_bf16 v[12:15], v[158:161], v[190:193], v[12:15]
	s_setprio 0
	s_barrier
	s_add_u32 s24, s24, 0x40080
	s_addc_u32 s25, s25, 0
	s_add_i32 s26, s26, s34
	s_mov_b32 m0, s26
	s_nop 0
	global_load_lds_dwordx4 v130, s[24:25]
	s_add_i32 m0, s26, 0x2000
	s_nop 0
	global_load_lds_dwordx4 v134, s[24:25]
	s_waitcnt vmcnt(8)
	s_setprio 1
	s_barrier
; __device__ __forceinline__ unsigned cvt_pk_bf16(float lo, float hi) { unsigned r; asm volatile("v_cvt_pk_bf16_f32 %0, %1, %2" : "=v"(r) : "v"(lo), "v"(hi)); return r; }
; #define PG8_MMA(ai, bj, At, Bt) do { __builtin_amdgcn_s_setprio(1); _Pragma("unroll") for (int m = 0; m < 4; ++m) _Pragma("unroll") for (int n = 0; n < 2; ++n) _Pragma("unroll") for (int k = 0; k < 2; ++k) \
;         acc[ai][bj][m][n] = __builtin_amdgcn_mfma_f32_16x16x32_bf16(Bt[n][k], At[m][k], acc[ai][bj][m][n], 0, 0, 0); __builtin_amdgcn_s_setprio(0); } while (0)
; #define PG8_WAIT_V(n) asm volatile("s_waitcnt vmcnt(" #n ")" ::: "memory")
; #define PG8_BAR __builtin_amdgcn_s_barrier()
; template <class Epi, class Sched>
; __device__ __forceinline__ void gemm_phase(LAS unsigned char* lds, const Gemm g, const Sched& S, const Epi& E) {
;     ...
;             PG8_WAIT_V(6); PG8_BAR; PG8_MMA(1, 1, At, B1); PG8_BAR;
;         }
;         E(acc, cur, wr, wc, fr, fq);
;         if (!has_next) break;
; #pragma unroll
;         for (int a = 0; a < 2; ++a)
; #pragma unroll
;             for (int b = 0; b < 2; ++b)
; #pragma unroll
;                 for (int m = 0; m < 4; ++m)
; #pragma unroll
;                     for (int n = 0; n < 2; ++n) acc[a][b][m][n] = (f32x4){0.f, 0.f, 0.f, 0.f};
;         cur = nxt; cA = nA; cB = nB; ++ui;
;     }
;     PG8_WAIT_V(0);
;     if (wr == 0) PG8_BAR;
;     PG8_BAR;
;     __device__ __forceinline__ void operator()(const AccT& acc, const Unit& u, int wr, int wc, int fr, int fq) const {
;         asm volatile("" : "+v"(fr), "+v"(fq));
;         const int rbase = u.pm * 256 + wr * 64 + fr;
;         const int tb = u.pn * 256 + wc * 32 + 8 * fq;
; #pragma unroll
;         for (int ai = 0; ai < 2; ++ai)
; #pragma unroll
;             for (int m = 0; m < 4; ++m) {
;                 const int r = rbase + ai * 128 + m * 16;
; #pragma unroll
;                 for (int bj = 0; bj < 2; ++bj) {
;                     const int t0 = tb + bj * 128;
;                     const f32x4 v0 = acc[ai][bj][m][0], v1 = acc[ai][bj][m][1];
;                     u32x4 w; w.x = cvt_pk_bf16(v0[0], v0[1]); w.y = cvt_pk_bf16(v0[2], v0[3]); w.z = cvt_pk_bf16(v1[0], v1[1]); w.w = cvt_pk_bf16(v1[2], v1[3]);
;                     *(u32x4*)(VT + (size_t)r * NT + t0) = w;
;                 }
;             }
;     }
	v_mfma_f32_16x16x32_bf16 v[48:51], v[194:197], v[162:165], v[48:51]
	v_mfma_f32_16x16x32_bf16 v[40:43], v[206:209], v[162:165], v[40:43]
	v_mfma_f32_16x16x32_bf16 v[32:35], v[194:197], v[170:173], v[32:35]
	v_mfma_f32_16x16x32_bf16 v[24:27], v[206:209], v[170:173], v[24:27]
	v_mfma_f32_16x16x32_bf16 v[16:19], v[194:197], v[178:181], v[16:19]
	v_mfma_f32_16x16x32_bf16 v[8:11], v[206:209], v[178:181], v[8:11]
	v_mfma_f32_16x16x32_bf16 v[4:7], v[194:197], v[186:189], v[4:7]
	v_mfma_f32_16x16x32_bf16 v[0:3], v[206:209], v[186:189], v[0:3]
	v_mfma_f32_16x16x32_bf16 v[48:51], v[202:205], v[166:169], v[48:51]
	v_mfma_f32_16x16x32_bf16 v[40:43], v[210:213], v[166:169], v[40:43]
	v_mfma_f32_16x16x32_bf16 v[32:35], v[202:205], v[174:177], v[32:35]
	v_mfma_f32_16x16x32_bf16 v[24:27], v[210:213], v[174:177], v[24:27]
	v_mfma_f32_16x16x32_bf16 v[16:19], v[202:205], v[182:185], v[16:19]
	v_mfma_f32_16x16x32_bf16 v[8:11], v[210:213], v[182:185], v[8:11]
	v_mfma_f32_16x16x32_bf16 v[4:7], v[202:205], v[190:193], v[4:7]
	v_mfma_f32_16x16x32_bf16 v[0:3], v[210:213], v[190:193], v[0:3]
	s_setprio 0
	s_add_i32 s58, s58, 2
	s_add_u32 s22, s22, 0x100
	s_addc_u32 s23, s23, 0
	s_add_u32 s56, s56, 0x100
	s_addc_u32 s57, s57, 0
	s_cmp_gt_u32 s58, 13
	s_barrier
	s_cbranch_scc0 .LBB0_713
	v_mov_b32_e32 v146, v140
	v_mov_b32_e32 v147, v141
	s_lshl_b32 s13, s20, 8
	s_add_i32 s13, s13, s41
	v_add_u32_e32 v146, s13, v146
	s_lshl_b32 s13, s53, 8
	s_or_b32 s13, s13, s42
	v_lshl_add_u32 v148, v147, 3, s13
	v_ashrrev_i32_e32 v147, 31, v146
	v_cvt_pk_bf16_f32 v124, v124, v125
	v_cvt_pk_bf16_f32 v125, v126, v127
	v_cvt_pk_bf16_f32 v126, v120, v121
	v_lshlrev_b64 v[120:121], 14, v[146:147]
	v_lshl_add_u64 v[120:121], s[62:63], 0, v[120:121]
	v_ashrrev_i32_e32 v149, 31, v148
	v_lshl_add_u64 v[120:121], v[148:149], 1, v[120:121]
	s_mov_b32 s13, 0x40000
	v_cvt_pk_bf16_f32 v127, v122, v123
	global_store_dwordx4 v[120:121], v[124:127], off
	v_cvt_pk_bf16_f32 v112, v112, v113
	v_cvt_pk_bf16_f32 v113, v114, v115
	v_cvt_pk_bf16_f32 v114, v104, v105
	v_cvt_pk_bf16_f32 v115, v106, v107
	global_store_dwordx4 v[120:121], v[112:115], off offset:256
	v_cvt_pk_bf16_f32 v104, v116, v117
	v_cvt_pk_bf16_f32 v105, v118, v119
	v_cvt_pk_bf16_f32 v106, v108, v109
	v_cvt_pk_bf16_f32 v107, v110, v111
	s_mov_b64 s[22:23], 0x40000
	v_add_co_u32_e32 v110, vcc, s13, v120
	v_lshl_add_u64 v[108:109], v[120:121], 0, s[22:23]
	s_nop 0
	v_addc_co_u32_e32 v111, vcc, 0, v121, vcc
	s_mov_b32 s13, 0x80000
	global_store_dwordx4 v[110:111], v[104:107], off
	v_cvt_pk_bf16_f32 v96, v96, v97
	v_cvt_pk_bf16_f32 v97, v98, v99
	v_cvt_pk_bf16_f32 v98, v88, v89
	v_cvt_pk_bf16_f32 v99, v90, v91
	global_store_dwordx4 v[108:109], v[96:99], off offset:256
	v_cvt_pk_bf16_f32 v88, v100, v101
	v_cvt_pk_bf16_f32 v89, v102, v103
	v_cvt_pk_bf16_f32 v90, v92, v93
	v_cvt_pk_bf16_f32 v91, v94, v95
	s_mov_b64 s[22:23], 0x80000
	v_add_co_u32_e32 v94, vcc, s13, v120
	v_lshl_add_u64 v[92:93], v[120:121], 0, s[22:23]
	s_nop 0
	v_addc_co_u32_e32 v95, vcc, 0, v121, vcc
	global_store_dwordx4 v[94:95], v[88:91], off
	v_cvt_pk_bf16_f32 v80, v80, v81
	v_cvt_pk_bf16_f32 v81, v82, v83
	v_cvt_pk_bf16_f32 v82, v72, v73
	v_cvt_pk_bf16_f32 v83, v74, v75
	global_store_dwordx4 v[92:93], v[80:83], off offset:256
	v_cvt_pk_bf16_f32 v72, v84, v85
	v_cvt_pk_bf16_f32 v73, v86, v87
	v_cvt_pk_bf16_f32 v74, v76, v77
	v_cvt_pk_bf16_f32 v75, v78, v79
	s_mov_b64 s[22:23], 0xc0000
	v_add_co_u32_e32 v78, vcc, s48, v120
	v_lshl_add_u64 v[76:77], v[120:121], 0, s[22:23]
	s_nop 0
	v_addc_co_u32_e32 v79, vcc, 0, v121, vcc
	global_store_dwordx4 v[78:79], v[72:75], off
	v_cvt_pk_bf16_f32 v68, v68, v69
	v_cvt_pk_bf16_f32 v69, v70, v71
	v_cvt_pk_bf16_f32 v70, v64, v65
	v_cvt_pk_bf16_f32 v71, v66, v67
	global_store_dwordx4 v[76:77], v[68:71], off offset:256
	v_cvt_pk_bf16_f32 v60, v60, v61
	v_cvt_pk_bf16_f32 v61, v62, v63
	v_cvt_pk_bf16_f32 v62, v56, v57
	v_cvt_pk_bf16_f32 v63, v58, v59
	v_add_co_u32_e32 v58, vcc, s49, v120
	v_lshl_add_u64 v[56:57], v[120:121], 0, s[2:3]
	s_nop 0
	v_addc_co_u32_e32 v59, vcc, 0, v121, vcc
	global_store_dwordx4 v[58:59], v[60:63], off
	v_cvt_pk_bf16_f32 v48, v48, v49
	v_cvt_pk_bf16_f32 v49, v50, v51
	v_cvt_pk_bf16_f32 v50, v40, v41
	v_cvt_pk_bf16_f32 v51, v42, v43
	global_store_dwordx4 v[56:57], v[48:51], off offset:256
	v_cvt_pk_bf16_f32 v40, v52, v53
	v_cvt_pk_bf16_f32 v41, v54, v55
	v_cvt_pk_bf16_f32 v42, v44, v45
	v_cvt_pk_bf16_f32 v43, v46, v47
	v_add_co_u32_e32 v46, vcc, s50, v120
	v_lshl_add_u64 v[44:45], v[120:121], 0, s[4:5]
	s_nop 0
	v_addc_co_u32_e32 v47, vcc, 0, v121, vcc
	global_store_dwordx4 v[46:47], v[40:43], off
	v_cvt_pk_bf16_f32 v32, v32, v33
	v_cvt_pk_bf16_f32 v33, v34, v35
	v_cvt_pk_bf16_f32 v34, v24, v25
	v_cvt_pk_bf16_f32 v35, v26, v27
	global_store_dwordx4 v[44:45], v[32:35], off offset:256
	v_cvt_pk_bf16_f32 v24, v36, v37
	v_cvt_pk_bf16_f32 v25, v38, v39
	v_cvt_pk_bf16_f32 v26, v28, v29
	v_cvt_pk_bf16_f32 v27, v30, v31
	v_add_co_u32_e32 v30, vcc, s51, v120
	v_lshl_add_u64 v[28:29], v[120:121], 0, s[6:7]
	s_nop 0
	v_addc_co_u32_e32 v31, vcc, 0, v121, vcc
	global_store_dwordx4 v[30:31], v[24:27], off
	v_cvt_pk_bf16_f32 v16, v16, v17
	v_cvt_pk_bf16_f32 v17, v18, v19
	v_cvt_pk_bf16_f32 v18, v8, v9
	v_cvt_pk_bf16_f32 v19, v10, v11
	global_store_dwordx4 v[28:29], v[16:19], off offset:256
	v_cvt_pk_bf16_f32 v8, v20, v21
	v_cvt_pk_bf16_f32 v9, v22, v23
	v_cvt_pk_bf16_f32 v10, v12, v13
	v_cvt_pk_bf16_f32 v11, v14, v15
	v_add_co_u32_e32 v14, vcc, s52, v120
	v_lshl_add_u64 v[12:13], v[120:121], 0, s[8:9]
	s_nop 0
	v_addc_co_u32_e32 v15, vcc, 0, v121, vcc
	s_and_b64 vcc, exec, s[10:11]
	s_mov_b32 s53, s12
	s_mov_b32 s20, s14
	s_mov_b64 s[24:25], s[18:19]
	s_mov_b64 s[22:23], s[16:17]
	global_store_dwordx4 v[14:15], v[8:11], off
	v_cvt_pk_bf16_f32 v4, v4, v5
	v_cvt_pk_bf16_f32 v5, v6, v7
	v_cvt_pk_bf16_f32 v6, v0, v1
	v_cvt_pk_bf16_f32 v7, v2, v3
	global_store_dwordx4 v[12:13], v[4:7], off offset:256
	s_cbranch_vccz .LBB0_706
	s_waitcnt vmcnt(0)
	s_cmpk_gt_u32 s31, 0xff
	s_cbranch_scc1 .LBB0_717
	s_barrier

; #define PG8_STAGE(bufoff, gbase, voff) do { _Pragma("unroll") for (int _i = 0; _i < 2; ++_i) \
;         __builtin_amdgcn_global_load_lds((const unsigned*)((const char*)(gbase) + (voff)[_i]), (LAS unsigned*)(lds + (bufoff) + ldsw + _i * 8192), 16, 0, 0); } while (0)
; #define PG8_LDA(dst, b, h) do { _Pragma("unroll") for (int m = 0; m < 4; ++m) _Pragma("unroll") for (int k = 0; k < 2; ++k) dst[m][k] = *(const LAS bf16x8*)(lds + PG8_SA(b, h) + aoff + m * 2048 + k * 1024); } while (0)
; #define PG8_LDB(dst, b, h) do { _Pragma("unroll") for (int n = 0; n < 2; ++n) _Pragma("unroll") for (int k = 0; k < 2; ++k) dst[n][k] = *(const LAS bf16x8*)(lds + PG8_SB(b, h) + boff + n * 2048 + k * 1024); } while (0)
; #define PG8_MMA(ai, bj, At, Bt) do { __builtin_amdgcn_s_setprio(1); _Pragma("unroll") for (int m = 0; m < 4; ++m) _Pragma("unroll") for (int n = 0; n < 2; ++n) _Pragma("unroll") for (int k = 0; k < 2; ++k) \
;         acc[ai][bj][m][n] = __builtin_amdgcn_mfma_f32_16x16x32_bf16(Bt[n][k], At[m][k], acc[ai][bj][m][n], 0, 0, 0); __builtin_amdgcn_s_setprio(0); } while (0)
; #define PG8_WAIT_L(n) asm volatile("s_waitcnt lgkmcnt(" #n ")" ::: "memory")
; template <class Epi, class Sched>
; __device__ __forceinline__ void gemm_phase(LAS unsigned char* lds, const Gemm g, const Sched& S, const Epi& E) {
;     ...
;         const bool has_next = S.next(ui + 1, nxt);
;         const char* nA = has_next ? (const char*)g.A + (size_t)nxt.pm * tstep : cA; const char* nB = has_next ? (const char*)g.Bt + (size_t)nxt.pn * tstep : cB;
;         for (int t = 0; t < nt; t += 2) {
;             const bool last = (t == nt - 2);
;             const char* a1 = cA + (size_t)(t + 1) * kstep;
;             const char* a2 = last ? nA : cA + (size_t)(t + 2) * kstep; const char* b2 = last ? nB : cB + (size_t)(t + 2) * kstep;
;             const char* a3 = a2 + kstep; const char* b3 = b2 + kstep;
;             PG8_LDB(B0, 0, 0); PG8_SCHED; PG8_LDA(At, 0, 0); PG8_STAGE(PG8_SA(1, 1), a1 + hstep, voffA);
;             PG8_WAIT_L(8); PG8_BAR; PG8_WAIT_L(0); PG8_MMA(0, 0, At, B0); PG8_BAR; PG8_SCHED;
;             PG8_LDB(B1, 0, 1); PG8_STAGE(PG8_SB(0, 0), b2, voffB);
;             PG8_BAR; PG8_WAIT_L(0); PG8_MMA(0, 1, At, B1); PG8_BAR;
;             PG8_LDA(At, 0, 1); PG8_STAGE(PG8_SA(0, 0), a2, voffA);
;             PG8_BAR; PG8_WAIT_L(0); PG8_MMA(1, 0, At, B0); PG8_BAR; PG8_SCHED;
.LBB0_825:
	s_ashr_i32 s7, s6, 31
	v_cmp_lt_i64_e32 vcc, s[8:9], v[156:157]
	s_lshl_b64 s[8:9], s[6:7], 20
	s_add_u32 s8, s22, s8
	s_addc_u32 s9, s23, s9
	s_and_b64 s[10:11], vcc, exec
	s_cselect_b32 s7, s9, s15
	s_cselect_b32 s39, s8, s14
	s_ashr_i32 s5, s4, 31
	s_lshl_b64 s[10:11], s[4:5], 20
	s_add_u32 s10, s50, s10
	s_addc_u32 s11, s51, s11
	s_and_b64 s[18:19], vcc, exec
	s_cselect_b32 s5, s11, s17
	s_cselect_b32 s40, s10, s16
	s_add_u32 s14, s14, 0x80080
	s_addc_u32 s15, s15, 0
	s_add_u32 s41, s16, 0x100
	s_addc_u32 s42, s17, 0
	s_mov_b32 s43, -2
	ds_read_b128 v[128:131], v168
	ds_read_b128 v[132:135], v168 offset:1024
	ds_read_b128 v[136:139], v168 offset:2048
	ds_read_b128 v[140:143], v168 offset:3072
	s_add_u32 s16, s14, 0xfff80080
	s_addc_u32 s17, s15, -1
	s_cmp_eq_u32 s43, 28
	s_cselect_b32 s19, s7, s17
	s_cselect_b32 s18, s39, s16
	s_cselect_b32 s17, s5, s42
	s_cselect_b32 s16, s40, s41
	s_add_i32 m0, s13, 0xc000
	ds_read_b128 v[162:165], v169
	ds_read_b128 v[172:175], v169 offset:1024
	ds_read_b128 v[176:179], v169 offset:2048
	ds_read_b128 v[180:183], v169 offset:3072
	ds_read_b128 v[184:187], v169 offset:4096
	ds_read_b128 v[188:191], v169 offset:5120
	ds_read_b128 v[192:195], v169 offset:6144
	ds_read_b128 v[196:199], v169 offset:7168
	global_load_lds_dwordx4 v152, s[14:15]
	s_add_i32 m0, s13, 0xe000
	s_nop 0
	global_load_lds_dwordx4 v154, s[14:15]
	s_waitcnt lgkmcnt(8)
	s_waitcnt vmcnt(8)
	s_setprio 1
	s_barrier
	s_waitcnt lgkmcnt(0)
	v_mfma_f32_16x16x32_bf16 v[124:127], v[128:131], v[162:165], 0
	v_mfma_f32_16x16x32_bf16 v[120:123], v[136:139], v[162:165], 0
	v_mfma_f32_16x16x32_bf16 v[116:119], v[128:131], v[176:179], 0
	v_mfma_f32_16x16x32_bf16 v[112:115], v[136:139], v[176:179], 0
	v_mfma_f32_16x16x32_bf16 v[108:111], v[128:131], v[184:187], 0
	v_mfma_f32_16x16x32_bf16 v[100:103], v[136:139], v[184:187], 0
	v_mfma_f32_16x16x32_bf16 v[76:79], v[128:131], v[192:195], 0
	v_mfma_f32_16x16x32_bf16 v[72:75], v[136:139], v[192:195], 0
	v_mfma_f32_16x16x32_bf16 v[124:127], v[132:135], v[172:175], v[124:127]
	v_mfma_f32_16x16x32_bf16 v[120:123], v[140:143], v[172:175], v[120:123]
	v_mfma_f32_16x16x32_bf16 v[116:119], v[132:135], v[180:183], v[116:119]
	v_mfma_f32_16x16x32_bf16 v[112:115], v[140:143], v[180:183], v[112:115]
	v_mfma_f32_16x16x32_bf16 v[108:111], v[132:135], v[188:191], v[108:111]
	v_mfma_f32_16x16x32_bf16 v[100:103], v[140:143], v[188:191], v[100:103]
	v_mfma_f32_16x16x32_bf16 v[76:79], v[132:135], v[196:199], v[76:79]
	v_mfma_f32_16x16x32_bf16 v[72:75], v[140:143], v[196:199], v[72:75]
	s_setprio 0
	s_barrier
	s_add_i32 s44, s35, s24
	s_mov_b32 m0, s44
	ds_read_b128 v[202:205], v170
	ds_read_b128 v[206:209], v170 offset:1024
	ds_read_b128 v[210:213], v170 offset:2048
	ds_read_b128 v[214:217], v170 offset:3072
	global_load_lds_dwordx4 v146, s[16:17]
	s_add_i32 m0, s44, 0x2000
	s_nop 0
	global_load_lds_dwordx4 v150, s[16:17]
	s_waitcnt vmcnt(8)
	s_setprio 1
	s_barrier
	s_waitcnt lgkmcnt(0)
	v_mfma_f32_16x16x32_bf16 v[104:107], v[202:205], v[162:165], 0
	v_mfma_f32_16x16x32_bf16 v[96:99], v[210:213], v[162:165], 0
	v_mfma_f32_16x16x32_bf16 v[92:95], v[202:205], v[176:179], 0
	v_mfma_f32_16x16x32_bf16 v[88:91], v[210:213], v[176:179], 0
	v_mfma_f32_16x16x32_bf16 v[84:87], v[202:205], v[184:187], 0
	v_mfma_f32_16x16x32_bf16 v[80:83], v[210:213], v[184:187], 0
	v_mfma_f32_16x16x32_bf16 v[68:71], v[202:205], v[192:195], 0
	v_mfma_f32_16x16x32_bf16 v[64:67], v[210:213], v[192:195], 0
	v_mfma_f32_16x16x32_bf16 v[104:107], v[206:209], v[172:175], v[104:107]
	v_mfma_f32_16x16x32_bf16 v[96:99], v[214:217], v[172:175], v[96:99]
	v_mfma_f32_16x16x32_bf16 v[92:95], v[206:209], v[180:183], v[92:95]
	v_mfma_f32_16x16x32_bf16 v[88:91], v[214:217], v[180:183], v[88:91]
	v_mfma_f32_16x16x32_bf16 v[84:87], v[206:209], v[188:191], v[84:87]
	v_mfma_f32_16x16x32_bf16 v[80:83], v[214:217], v[188:191], v[80:83]
	v_mfma_f32_16x16x32_bf16 v[68:71], v[206:209], v[196:199], v[68:71]
	v_mfma_f32_16x16x32_bf16 v[64:67], v[214:217], v[196:199], v[64:67]
	s_setprio 0
	s_mov_b32 m0, s13
	v_lshl_add_u64 v[222:223], s[18:19], 0, v[144:145]
	s_barrier
	ds_read_b128 v[162:165], v169 offset:16384
	ds_read_b128 v[172:175], v169 offset:17408
	ds_read_b128 v[176:179], v169 offset:18432
	ds_read_b128 v[180:183], v169 offset:19456
	ds_read_b128 v[184:187], v169 offset:20480
	ds_read_b128 v[188:191], v169 offset:21504
	ds_read_b128 v[192:195], v169 offset:22528
	ds_read_b128 v[196:199], v169 offset:23552
	global_load_lds_dwordx4 v144, s[18:19]
	v_lshl_add_u64 v[224:225], s[18:19], 0, v[148:149]
	s_mov_b32 m0, s25
	s_nop 0
	global_load_lds_dwordx4 v148, s[18:19]
	s_setprio 1
	s_barrier
	s_waitcnt lgkmcnt(0)
	v_mfma_f32_16x16x32_bf16 v[60:63], v[128:131], v[162:165], 0
	v_mfma_f32_16x16x32_bf16 v[56:59], v[136:139], v[162:165], 0
	v_mfma_f32_16x16x32_bf16 v[48:51], v[128:131], v[176:179], 0
	v_mfma_f32_16x16x32_bf16 v[40:43], v[136:139], v[176:179], 0
	v_mfma_f32_16x16x32_bf16 v[32:35], v[128:131], v[184:187], 0
	v_mfma_f32_16x16x32_bf16 v[24:27], v[136:139], v[184:187], 0
	v_mfma_f32_16x16x32_bf16 v[16:19], v[128:131], v[192:195], 0
	v_mfma_f32_16x16x32_bf16 v[8:11], v[136:139], v[192:195], 0
	v_mfma_f32_16x16x32_bf16 v[60:63], v[132:135], v[172:175], v[60:63]
	v_mfma_f32_16x16x32_bf16 v[56:59], v[140:143], v[172:175], v[56:59]
	v_mfma_f32_16x16x32_bf16 v[48:51], v[132:135], v[180:183], v[48:51]
	v_mfma_f32_16x16x32_bf16 v[40:43], v[140:143], v[180:183], v[40:43]
	v_mfma_f32_16x16x32_bf16 v[32:35], v[132:135], v[188:191], v[32:35]
	v_mfma_f32_16x16x32_bf16 v[24:27], v[140:143], v[188:191], v[24:27]
	v_mfma_f32_16x16x32_bf16 v[16:19], v[132:135], v[196:199], v[16:19]
	v_mfma_f32_16x16x32_bf16 v[8:11], v[140:143], v[196:199], v[8:11]
	s_setprio 0
	s_barrier
; #define PG8_STAGE(bufoff, gbase, voff) do { _Pragma("unroll") for (int _i = 0; _i < 2; ++_i) \
;         __builtin_amdgcn_global_load_lds((const unsigned*)((const char*)(gbase) + (voff)[_i]), (LAS unsigned*)(lds + (bufoff) + ldsw + _i * 8192), 16, 0, 0); } while (0)
; #define PG8_LDA(dst, b, h) do { _Pragma("unroll") for (int m = 0; m < 4; ++m) _Pragma("unroll") for (int k = 0; k < 2; ++k) dst[m][k] = *(const LAS bf16x8*)(lds + PG8_SA(b, h) + aoff + m * 2048 + k * 1024); } while (0)
; #define PG8_LDB(dst, b, h) do { _Pragma("unroll") for (int n = 0; n < 2; ++n) _Pragma("unroll") for (int k = 0; k < 2; ++k) dst[n][k] = *(const LAS bf16x8*)(lds + PG8_SB(b, h) + boff + n * 2048 + k * 1024); } while (0)
; #define PG8_MMA(ai, bj, At, Bt) do { __builtin_amdgcn_s_setprio(1); _Pragma("unroll") for (int m = 0; m < 4; ++m) _Pragma("unroll") for (int n = 0; n < 2; ++n) _Pragma("unroll") for (int k = 0; k < 2; ++k) \
;         acc[ai][bj][m][n] = __builtin_amdgcn_mfma_f32_16x16x32_bf16(Bt[n][k], At[m][k], acc[ai][bj][m][n], 0, 0, 0); __builtin_amdgcn_s_setprio(0); } while (0)
; #define PG8_WAIT_V(n) asm volatile("s_waitcnt vmcnt(" #n ")" ::: "memory")
; #define PG8_WAIT_L(n) asm volatile("s_waitcnt lgkmcnt(" #n ")" ::: "memory")
; #define PG8_BAR __builtin_amdgcn_s_barrier()
; #define PG8_SCHED __builtin_amdgcn_sched_barrier(0)
; template <class Epi, class Sched>
; __device__ __forceinline__ void gemm_phase(LAS unsigned char* lds, const Gemm g, const Sched& S, const Epi& E) {
;     ...
;             PG8_STAGE(PG8_SB(0, 1), b2 + hstep, voffB);
;             PG8_WAIT_V(6); PG8_BAR; PG8_MMA(1, 1, At, B1); PG8_BAR;
;             PG8_LDB(B0, 1, 0); PG8_SCHED; PG8_LDA(At, 1, 0); PG8_STAGE(PG8_SA(0, 1), a2 + hstep, voffA);
;             PG8_WAIT_L(8); PG8_BAR; PG8_WAIT_L(0); PG8_MMA(0, 0, At, B0); PG8_BAR; PG8_SCHED;
;             PG8_LDB(B1, 1, 1); PG8_STAGE(PG8_SB(1, 0), b3, voffB);
;             PG8_BAR; PG8_WAIT_L(0); PG8_MMA(0, 1, At, B1); PG8_BAR;
;             PG8_LDA(At, 1, 1); PG8_STAGE(PG8_SA(1, 0), a3, voffA);
	s_add_u32 s44, s16, 0x80000
	s_addc_u32 s45, s17, 0
	s_add_i32 s46, s36, s24
	s_mov_b32 m0, s46
	s_nop 0
	global_load_lds_dwordx4 v146, s[44:45]
	s_add_i32 m0, s46, 0x2000
	s_nop 0
	global_load_lds_dwordx4 v150, s[44:45]
	s_add_u32 s18, s18, 0x80000
	s_addc_u32 s19, s19, 0
	s_mov_b32 m0, s26
	s_nop 0
	global_load_lds_dwordx4 v144, s[18:19]
	s_mov_b32 m0, s27
	s_nop 0
	global_load_lds_dwordx4 v148, s[18:19]
	s_waitcnt vmcnt(10)
	s_setprio 1
	s_barrier
	v_mfma_f32_16x16x32_bf16 v[52:55], v[202:205], v[162:165], 0
	v_mfma_f32_16x16x32_bf16 v[44:47], v[210:213], v[162:165], 0
	v_mfma_f32_16x16x32_bf16 v[36:39], v[202:205], v[176:179], 0
	v_mfma_f32_16x16x32_bf16 v[28:31], v[210:213], v[176:179], 0
	v_mfma_f32_16x16x32_bf16 v[20:23], v[202:205], v[184:187], 0
	v_mfma_f32_16x16x32_bf16 v[12:15], v[210:213], v[184:187], 0
	v_mfma_f32_16x16x32_bf16 v[4:7], v[202:205], v[192:195], 0
	v_mfma_f32_16x16x32_bf16 v[0:3], v[210:213], v[192:195], 0
	v_mfma_f32_16x16x32_bf16 v[52:55], v[206:209], v[172:175], v[52:55]
	v_mfma_f32_16x16x32_bf16 v[44:47], v[214:217], v[172:175], v[44:47]
	v_mfma_f32_16x16x32_bf16 v[36:39], v[206:209], v[180:183], v[36:39]
	v_mfma_f32_16x16x32_bf16 v[28:31], v[214:217], v[180:183], v[28:31]
	v_mfma_f32_16x16x32_bf16 v[20:23], v[206:209], v[188:191], v[20:23]
	v_mfma_f32_16x16x32_bf16 v[12:15], v[214:217], v[188:191], v[12:15]
	v_mfma_f32_16x16x32_bf16 v[4:7], v[206:209], v[196:199], v[4:7]
	v_mfma_f32_16x16x32_bf16 v[0:3], v[214:217], v[196:199], v[0:3]
	s_setprio 0
	s_add_i32 s44, 0, 0x18000
	v_add_u32_e32 v140, s44, v167
	s_barrier
	ds_read_b128 v[128:131], v140
	ds_read_b128 v[132:135], v140 offset:1024
	ds_read_b128 v[136:139], v140 offset:2048
	ds_read_b128 v[140:143], v140 offset:3072
	ds_read_b128 v[162:165], v169 offset:32768
	ds_read_b128 v[172:175], v169 offset:33792
	ds_read_b128 v[176:179], v169 offset:34816
	ds_read_b128 v[180:183], v169 offset:35840
	ds_read_b128 v[184:187], v169 offset:36864
	ds_read_b128 v[188:191], v169 offset:37888
	ds_read_b128 v[192:195], v169 offset:38912
	ds_read_b128 v[196:199], v169 offset:39936
	s_waitcnt lgkmcnt(8)
	s_waitcnt vmcnt(8)
	s_setprio 1
	s_barrier
	s_waitcnt lgkmcnt(0)
	v_mfma_f32_16x16x32_bf16 v[124:127], v[128:131], v[162:165], v[124:127]
	v_mfma_f32_16x16x32_bf16 v[120:123], v[136:139], v[162:165], v[120:123]
	v_mfma_f32_16x16x32_bf16 v[116:119], v[128:131], v[176:179], v[116:119]
	v_mfma_f32_16x16x32_bf16 v[112:115], v[136:139], v[176:179], v[112:115]
	v_mfma_f32_16x16x32_bf16 v[108:111], v[128:131], v[184:187], v[108:111]
	v_mfma_f32_16x16x32_bf16 v[100:103], v[136:139], v[184:187], v[100:103]
	v_mfma_f32_16x16x32_bf16 v[76:79], v[128:131], v[192:195], v[76:79]
	v_mfma_f32_16x16x32_bf16 v[72:75], v[136:139], v[192:195], v[72:75]
	v_mfma_f32_16x16x32_bf16 v[124:127], v[132:135], v[172:175], v[124:127]
	v_mfma_f32_16x16x32_bf16 v[120:123], v[140:143], v[172:175], v[120:123]
	v_mfma_f32_16x16x32_bf16 v[116:119], v[132:135], v[180:183], v[116:119]
	v_mfma_f32_16x16x32_bf16 v[112:115], v[140:143], v[180:183], v[112:115]
	v_mfma_f32_16x16x32_bf16 v[108:111], v[132:135], v[188:191], v[108:111]
	v_mfma_f32_16x16x32_bf16 v[100:103], v[140:143], v[188:191], v[100:103]
	v_mfma_f32_16x16x32_bf16 v[76:79], v[132:135], v[196:199], v[76:79]
	v_mfma_f32_16x16x32_bf16 v[72:75], v[140:143], v[196:199], v[72:75]
	s_setprio 0
	s_barrier
	s_add_i32 s18, 0, 0x1c000
	s_add_i32 s19, s44, s24
	v_add_u32_e32 v160, s18, v167
	s_add_u32 s0, s16, 0x80
	s_addc_u32 s1, s17, 0
	s_mov_b32 m0, s19
	ds_read_b128 v[202:205], v160
	ds_read_b128 v[206:209], v160 offset:1024
	ds_read_b128 v[210:213], v160 offset:2048
	ds_read_b128 v[214:217], v160 offset:3072
	global_load_lds_dwordx4 v146, s[0:1]
	s_add_i32 m0, s19, 0x2000
	s_nop 0
	global_load_lds_dwordx4 v150, s[0:1]
	s_waitcnt vmcnt(8)
	s_setprio 1
	s_barrier
	s_waitcnt lgkmcnt(0)
	v_mfma_f32_16x16x32_bf16 v[104:107], v[202:205], v[162:165], v[104:107]
	v_mfma_f32_16x16x32_bf16 v[96:99], v[210:213], v[162:165], v[96:99]
	v_mfma_f32_16x16x32_bf16 v[92:95], v[202:205], v[176:179], v[92:95]
	v_mfma_f32_16x16x32_bf16 v[88:91], v[210:213], v[176:179], v[88:91]
	v_mfma_f32_16x16x32_bf16 v[84:87], v[202:205], v[184:187], v[84:87]
	v_mfma_f32_16x16x32_bf16 v[80:83], v[210:213], v[184:187], v[80:83]
	v_mfma_f32_16x16x32_bf16 v[68:71], v[202:205], v[192:195], v[68:71]
	v_mfma_f32_16x16x32_bf16 v[64:67], v[210:213], v[192:195], v[64:67]
	v_mfma_f32_16x16x32_bf16 v[104:107], v[206:209], v[172:175], v[104:107]
	v_mfma_f32_16x16x32_bf16 v[96:99], v[214:217], v[172:175], v[96:99]
	v_mfma_f32_16x16x32_bf16 v[92:95], v[206:209], v[180:183], v[92:95]
	v_mfma_f32_16x16x32_bf16 v[88:91], v[214:217], v[180:183], v[88:91]
	v_mfma_f32_16x16x32_bf16 v[84:87], v[206:209], v[188:191], v[84:87]
	v_mfma_f32_16x16x32_bf16 v[80:83], v[214:217], v[188:191], v[80:83]
	v_mfma_f32_16x16x32_bf16 v[68:71], v[206:209], v[196:199], v[68:71]
	v_mfma_f32_16x16x32_bf16 v[64:67], v[214:217], v[196:199], v[64:67]
	s_setprio 0
	s_mov_b32 m0, s31
	s_mov_b64 s[0:1], 0x80
	v_lshl_add_u64 v[218:219], v[222:223], 0, s[0:1]
	s_barrier
	ds_read_b128 v[162:165], v169 offset:49152
	ds_read_b128 v[172:175], v169 offset:50176
	ds_read_b128 v[176:179], v169 offset:51200
	ds_read_b128 v[180:183], v169 offset:52224
	ds_read_b128 v[184:187], v169 offset:53248
	ds_read_b128 v[188:191], v169 offset:54272
	ds_read_b128 v[192:195], v169 offset:55296
	ds_read_b128 v[196:199], v169 offset:56320
	global_load_lds_dwordx4 v[218:219], off
	v_lshl_add_u64 v[218:219], v[224:225], 0, s[0:1]
	s_mov_b32 m0, s33
	s_nop 0
	global_load_lds_dwordx4 v[218:219], off
	s_setprio 1
	s_barrier
; #define PG8_STAGE(bufoff, gbase, voff) do { _Pragma("unroll") for (int _i = 0; _i < 2; ++_i) \
;         __builtin_amdgcn_global_load_lds((const unsigned*)((const char*)(gbase) + (voff)[_i]), (LAS unsigned*)(lds + (bufoff) + ldsw + _i * 8192), 16, 0, 0); } while (0)
; #define PG8_LDA(dst, b, h) do { _Pragma("unroll") for (int m = 0; m < 4; ++m) _Pragma("unroll") for (int k = 0; k < 2; ++k) dst[m][k] = *(const LAS bf16x8*)(lds + PG8_SA(b, h) + aoff + m * 2048 + k * 1024); } while (0)
; #define PG8_LDB(dst, b, h) do { _Pragma("unroll") for (int n = 0; n < 2; ++n) _Pragma("unroll") for (int k = 0; k < 2; ++k) dst[n][k] = *(const LAS bf16x8*)(lds + PG8_SB(b, h) + boff + n * 2048 + k * 1024); } while (0)
; #define PG8_WAIT_V(n) asm volatile("s_waitcnt vmcnt(" #n ")" ::: "memory")
; #define PG8_WAIT_L(n) asm volatile("s_waitcnt lgkmcnt(" #n ")" ::: "memory")
; #define PG8_BAR __builtin_amdgcn_s_barrier()
; #define PG8_SCHED __builtin_amdgcn_sched_barrier(0)
; template <class Epi, class Sched>
; __device__ __forceinline__ void gemm_phase(LAS unsigned char* lds, const Gemm g, const Sched& S, const Epi& E) {
;     ...
;             PG8_LDB(B0, 0, 0); PG8_SCHED; PG8_LDA(At, 0, 0); PG8_STAGE(PG8_SA(1, 1), a1 + hstep, voffA);
;             PG8_WAIT_L(8); PG8_BAR; PG8_WAIT_L(0); PG8_MMA(0, 0, At, B0); PG8_BAR; PG8_SCHED;
;             PG8_LDB(B1, 0, 1); PG8_STAGE(PG8_SB(0, 0), b2, voffB);
;             PG8_BAR; PG8_WAIT_L(0); PG8_MMA(0, 1, At, B1); PG8_BAR;
;             PG8_LDA(At, 0, 1); PG8_STAGE(PG8_SA(0, 0), a2, voffA);
;             PG8_BAR; PG8_WAIT_L(0); PG8_MMA(1, 0, At, B0); PG8_BAR; PG8_SCHED;
;             PG8_STAGE(PG8_SB(0, 1), b2 + hstep, voffB);
;             PG8_WAIT_V(6); PG8_BAR; PG8_MMA(1, 1, At, B1); PG8_BAR;
;             PG8_LDB(B0, 1, 0); PG8_SCHED; PG8_LDA(At, 1, 0); PG8_STAGE(PG8_SA(0, 1), a2 + hstep, voffA);
;             PG8_WAIT_L(8); PG8_BAR; PG8_WAIT_L(0); PG8_MMA(0, 0, At, B0); PG8_BAR; PG8_SCHED;
;             PG8_LDB(B1, 1, 1); PG8_STAGE(PG8_SB(1, 0), b3, voffB);
;             PG8_BAR; PG8_WAIT_L(0); PG8_MMA(0, 1, At, B1); PG8_BAR;
;             PG8_LDA(At, 1, 1); PG8_STAGE(PG8_SA(1, 0), a3, voffA);
;             PG8_BAR; PG8_WAIT_L(0); PG8_MMA(1, 0, At, B0); PG8_BAR; PG8_SCHED;
;             PG8_STAGE(PG8_SB(1, 1), b3 + hstep, voffB);
;             PG8_WAIT_V(6); PG8_BAR; PG8_MMA(1, 1, At, B1); PG8_BAR;
	s_waitcnt lgkmcnt(0)
	v_mfma_f32_16x16x32_bf16 v[60:63], v[128:131], v[162:165], v[60:63]
	v_mfma_f32_16x16x32_bf16 v[56:59], v[136:139], v[162:165], v[56:59]
	v_mfma_f32_16x16x32_bf16 v[48:51], v[128:131], v[176:179], v[48:51]
	v_mfma_f32_16x16x32_bf16 v[40:43], v[136:139], v[176:179], v[40:43]
	v_mfma_f32_16x16x32_bf16 v[32:35], v[128:131], v[184:187], v[32:35]
	v_mfma_f32_16x16x32_bf16 v[24:27], v[136:139], v[184:187], v[24:27]
	v_mfma_f32_16x16x32_bf16 v[16:19], v[128:131], v[192:195], v[16:19]
	v_mfma_f32_16x16x32_bf16 v[8:11], v[136:139], v[192:195], v[8:11]
	v_mfma_f32_16x16x32_bf16 v[60:63], v[132:135], v[172:175], v[60:63]
	v_mfma_f32_16x16x32_bf16 v[56:59], v[140:143], v[172:175], v[56:59]
	v_mfma_f32_16x16x32_bf16 v[48:51], v[132:135], v[180:183], v[48:51]
	v_mfma_f32_16x16x32_bf16 v[40:43], v[140:143], v[180:183], v[40:43]
	v_mfma_f32_16x16x32_bf16 v[32:35], v[132:135], v[188:191], v[32:35]
	v_mfma_f32_16x16x32_bf16 v[24:27], v[140:143], v[188:191], v[24:27]
	v_mfma_f32_16x16x32_bf16 v[16:19], v[132:135], v[196:199], v[16:19]
	v_mfma_f32_16x16x32_bf16 v[8:11], v[140:143], v[196:199], v[8:11]
	s_setprio 0
	s_barrier
	s_add_u32 s16, s16, 0x80080
	s_addc_u32 s17, s17, 0
	s_add_i32 s18, s18, s24
	s_mov_b32 m0, s18
	s_nop 0
	global_load_lds_dwordx4 v146, s[16:17]
	s_add_i32 m0, s18, 0x2000
	s_nop 0
	global_load_lds_dwordx4 v150, s[16:17]
	s_waitcnt vmcnt(8)
	s_setprio 1
	s_barrier
	v_mfma_f32_16x16x32_bf16 v[52:55], v[202:205], v[162:165], v[52:55]
	v_mfma_f32_16x16x32_bf16 v[44:47], v[210:213], v[162:165], v[44:47]
	v_mfma_f32_16x16x32_bf16 v[36:39], v[202:205], v[176:179], v[36:39]
	v_mfma_f32_16x16x32_bf16 v[28:31], v[210:213], v[176:179], v[28:31]
	v_mfma_f32_16x16x32_bf16 v[20:23], v[202:205], v[184:187], v[20:23]
	v_mfma_f32_16x16x32_bf16 v[12:15], v[210:213], v[184:187], v[12:15]
	v_mfma_f32_16x16x32_bf16 v[4:7], v[202:205], v[192:195], v[4:7]
	v_mfma_f32_16x16x32_bf16 v[0:3], v[210:213], v[192:195], v[0:3]
	v_mfma_f32_16x16x32_bf16 v[52:55], v[206:209], v[172:175], v[52:55]
	v_mfma_f32_16x16x32_bf16 v[44:47], v[214:217], v[172:175], v[44:47]
	v_mfma_f32_16x16x32_bf16 v[36:39], v[206:209], v[180:183], v[36:39]
	v_mfma_f32_16x16x32_bf16 v[28:31], v[214:217], v[180:183], v[28:31]
	v_mfma_f32_16x16x32_bf16 v[20:23], v[206:209], v[188:191], v[20:23]
	v_mfma_f32_16x16x32_bf16 v[12:15], v[214:217], v[188:191], v[12:15]
	v_mfma_f32_16x16x32_bf16 v[4:7], v[206:209], v[196:199], v[4:7]
	v_mfma_f32_16x16x32_bf16 v[0:3], v[214:217], v[196:199], v[0:3]
	s_setprio 0
	s_add_i32 s43, s43, 2
	s_add_u32 s14, s14, 0x100
	s_addc_u32 s15, s15, 0
	s_add_u32 s41, s41, 0x100
	s_addc_u32 s42, s42, 0
	s_cmp_gt_u32 s43, 29
	s_barrier
.LBB0_826:
	ds_read_b128 v[128:131], v168
	ds_read_b128 v[132:135], v168 offset:1024
	ds_read_b128 v[136:139], v168 offset:2048
	ds_read_b128 v[140:143], v168 offset:3072
	s_add_u32 s16, s14, 0xfff80080
	s_addc_u32 s17, s15, -1
	s_cmp_eq_u32 s43, 28
	s_cselect_b32 s19, s7, s17
	s_cselect_b32 s18, s39, s16
	s_cselect_b32 s17, s5, s42
	s_cselect_b32 s16, s40, s41
	s_add_i32 m0, s13, 0xc000
	ds_read_b128 v[162:165], v169
	ds_read_b128 v[172:175], v169 offset:1024
	ds_read_b128 v[176:179], v169 offset:2048
	ds_read_b128 v[180:183], v169 offset:3072
	ds_read_b128 v[184:187], v169 offset:4096
	ds_read_b128 v[188:191], v169 offset:5120
	ds_read_b128 v[192:195], v169 offset:6144
	ds_read_b128 v[196:199], v169 offset:7168
	global_load_lds_dwordx4 v152, s[14:15]
	s_add_i32 m0, s13, 0xe000
	s_nop 0
	global_load_lds_dwordx4 v154, s[14:15]
	s_waitcnt lgkmcnt(8)
	s_waitcnt vmcnt(8)
	s_setprio 1
	s_barrier
	s_waitcnt lgkmcnt(0)
	v_mfma_f32_16x16x32_bf16 v[124:127], v[128:131], v[162:165], v[124:127]
	v_mfma_f32_16x16x32_bf16 v[120:123], v[136:139], v[162:165], v[120:123]
	v_mfma_f32_16x16x32_bf16 v[116:119], v[128:131], v[176:179], v[116:119]
	v_mfma_f32_16x16x32_bf16 v[112:115], v[136:139], v[176:179], v[112:115]
	v_mfma_f32_16x16x32_bf16 v[108:111], v[128:131], v[184:187], v[108:111]
	v_mfma_f32_16x16x32_bf16 v[100:103], v[136:139], v[184:187], v[100:103]
	v_mfma_f32_16x16x32_bf16 v[76:79], v[128:131], v[192:195], v[76:79]
	v_mfma_f32_16x16x32_bf16 v[72:75], v[136:139], v[192:195], v[72:75]
	v_mfma_f32_16x16x32_bf16 v[124:127], v[132:135], v[172:175], v[124:127]
	v_mfma_f32_16x16x32_bf16 v[120:123], v[140:143], v[172:175], v[120:123]
	v_mfma_f32_16x16x32_bf16 v[116:119], v[132:135], v[180:183], v[116:119]
	v_mfma_f32_16x16x32_bf16 v[112:115], v[140:143], v[180:183], v[112:115]
	v_mfma_f32_16x16x32_bf16 v[108:111], v[132:135], v[188:191], v[108:111]
	v_mfma_f32_16x16x32_bf16 v[100:103], v[140:143], v[188:191], v[100:103]
	v_mfma_f32_16x16x32_bf16 v[76:79], v[132:135], v[196:199], v[76:79]
	v_mfma_f32_16x16x32_bf16 v[72:75], v[140:143], v[196:199], v[72:75]
	s_setprio 0
	s_barrier
	s_add_i32 s44, s35, s24
	s_mov_b32 m0, s44
	ds_read_b128 v[202:205], v170
	ds_read_b128 v[206:209], v170 offset:1024
	ds_read_b128 v[210:213], v170 offset:2048
	ds_read_b128 v[214:217], v170 offset:3072
	global_load_lds_dwordx4 v146, s[16:17]
	s_add_i32 m0, s44, 0x2000
	s_nop 0
	global_load_lds_dwordx4 v150, s[16:17]
	s_waitcnt vmcnt(8)
	s_setprio 1
	s_barrier
; #define PG8_STAGE(bufoff, gbase, voff) do { _Pragma("unroll") for (int _i = 0; _i < 2; ++_i) \
;         __builtin_amdgcn_global_load_lds((const unsigned*)((const char*)(gbase) + (voff)[_i]), (LAS unsigned*)(lds + (bufoff) + ldsw + _i * 8192), 16, 0, 0); } while (0)
; #define PG8_LDA(dst, b, h) do { _Pragma("unroll") for (int m = 0; m < 4; ++m) _Pragma("unroll") for (int k = 0; k < 2; ++k) dst[m][k] = *(const LAS bf16x8*)(lds + PG8_SA(b, h) + aoff + m * 2048 + k * 1024); } while (0)
; #define PG8_LDB(dst, b, h) do { _Pragma("unroll") for (int n = 0; n < 2; ++n) _Pragma("unroll") for (int k = 0; k < 2; ++k) dst[n][k] = *(const LAS bf16x8*)(lds + PG8_SB(b, h) + boff + n * 2048 + k * 1024); } while (0)
; #define PG8_MMA(ai, bj, At, Bt) do { __builtin_amdgcn_s_setprio(1); _Pragma("unroll") for (int m = 0; m < 4; ++m) _Pragma("unroll") for (int n = 0; n < 2; ++n) _Pragma("unroll") for (int k = 0; k < 2; ++k) \
;         acc[ai][bj][m][n] = __builtin_amdgcn_mfma_f32_16x16x32_bf16(Bt[n][k], At[m][k], acc[ai][bj][m][n], 0, 0, 0); __builtin_amdgcn_s_setprio(0); } while (0)
; #define PG8_WAIT_V(n) asm volatile("s_waitcnt vmcnt(" #n ")" ::: "memory")
; #define PG8_WAIT_L(n) asm volatile("s_waitcnt lgkmcnt(" #n ")" ::: "memory")
; #define PG8_BAR __builtin_amdgcn_s_barrier()
; #define PG8_SCHED __builtin_amdgcn_sched_barrier(0)
; template <class Epi, class Sched>
; __device__ __forceinline__ void gemm_phase(LAS unsigned char* lds, const Gemm g, const Sched& S, const Epi& E) {
;     ...
;             PG8_BAR; PG8_WAIT_L(0); PG8_MMA(0, 1, At, B1); PG8_BAR;
;             PG8_LDA(At, 0, 1); PG8_STAGE(PG8_SA(0, 0), a2, voffA);
;             PG8_BAR; PG8_WAIT_L(0); PG8_MMA(1, 0, At, B0); PG8_BAR; PG8_SCHED;
;             PG8_STAGE(PG8_SB(0, 1), b2 + hstep, voffB);
;             PG8_WAIT_V(6); PG8_BAR; PG8_MMA(1, 1, At, B1); PG8_BAR;
;             PG8_LDB(B0, 1, 0); PG8_SCHED; PG8_LDA(At, 1, 0); PG8_STAGE(PG8_SA(0, 1), a2 + hstep, voffA);
;             PG8_WAIT_L(8); PG8_BAR; PG8_WAIT_L(0); PG8_MMA(0, 0, At, B0); PG8_BAR; PG8_SCHED;
	s_waitcnt lgkmcnt(0)
	v_mfma_f32_16x16x32_bf16 v[104:107], v[202:205], v[162:165], v[104:107]
	v_mfma_f32_16x16x32_bf16 v[96:99], v[210:213], v[162:165], v[96:99]
	v_mfma_f32_16x16x32_bf16 v[92:95], v[202:205], v[176:179], v[92:95]
	v_mfma_f32_16x16x32_bf16 v[88:91], v[210:213], v[176:179], v[88:91]
	v_mfma_f32_16x16x32_bf16 v[84:87], v[202:205], v[184:187], v[84:87]
	v_mfma_f32_16x16x32_bf16 v[80:83], v[210:213], v[184:187], v[80:83]
	v_mfma_f32_16x16x32_bf16 v[68:71], v[202:205], v[192:195], v[68:71]
	v_mfma_f32_16x16x32_bf16 v[64:67], v[210:213], v[192:195], v[64:67]
	v_mfma_f32_16x16x32_bf16 v[104:107], v[206:209], v[172:175], v[104:107]
	v_mfma_f32_16x16x32_bf16 v[96:99], v[214:217], v[172:175], v[96:99]
	v_mfma_f32_16x16x32_bf16 v[92:95], v[206:209], v[180:183], v[92:95]
	v_mfma_f32_16x16x32_bf16 v[88:91], v[214:217], v[180:183], v[88:91]
	v_mfma_f32_16x16x32_bf16 v[84:87], v[206:209], v[188:191], v[84:87]
	v_mfma_f32_16x16x32_bf16 v[80:83], v[214:217], v[188:191], v[80:83]
	v_mfma_f32_16x16x32_bf16 v[68:71], v[206:209], v[196:199], v[68:71]
	v_mfma_f32_16x16x32_bf16 v[64:67], v[214:217], v[196:199], v[64:67]
	s_setprio 0
	s_mov_b32 m0, s13
	v_lshl_add_u64 v[222:223], s[18:19], 0, v[144:145]
	s_barrier
	ds_read_b128 v[162:165], v169 offset:16384
	ds_read_b128 v[172:175], v169 offset:17408
	ds_read_b128 v[176:179], v169 offset:18432
	ds_read_b128 v[180:183], v169 offset:19456
	ds_read_b128 v[184:187], v169 offset:20480
	ds_read_b128 v[188:191], v169 offset:21504
	ds_read_b128 v[192:195], v169 offset:22528
	ds_read_b128 v[196:199], v169 offset:23552
	global_load_lds_dwordx4 v144, s[18:19]
	v_lshl_add_u64 v[224:225], s[18:19], 0, v[148:149]
	s_mov_b32 m0, s25
	s_nop 0
	global_load_lds_dwordx4 v148, s[18:19]
	s_setprio 1
	s_barrier
	s_waitcnt lgkmcnt(0)
	v_mfma_f32_16x16x32_bf16 v[60:63], v[128:131], v[162:165], v[60:63]
	v_mfma_f32_16x16x32_bf16 v[56:59], v[136:139], v[162:165], v[56:59]
	v_mfma_f32_16x16x32_bf16 v[48:51], v[128:131], v[176:179], v[48:51]
	v_mfma_f32_16x16x32_bf16 v[40:43], v[136:139], v[176:179], v[40:43]
	v_mfma_f32_16x16x32_bf16 v[32:35], v[128:131], v[184:187], v[32:35]
	v_mfma_f32_16x16x32_bf16 v[24:27], v[136:139], v[184:187], v[24:27]
	v_mfma_f32_16x16x32_bf16 v[16:19], v[128:131], v[192:195], v[16:19]
	v_mfma_f32_16x16x32_bf16 v[8:11], v[136:139], v[192:195], v[8:11]
	v_mfma_f32_16x16x32_bf16 v[60:63], v[132:135], v[172:175], v[60:63]
	v_mfma_f32_16x16x32_bf16 v[56:59], v[140:143], v[172:175], v[56:59]
	v_mfma_f32_16x16x32_bf16 v[48:51], v[132:135], v[180:183], v[48:51]
	v_mfma_f32_16x16x32_bf16 v[40:43], v[140:143], v[180:183], v[40:43]
	v_mfma_f32_16x16x32_bf16 v[32:35], v[132:135], v[188:191], v[32:35]
	v_mfma_f32_16x16x32_bf16 v[24:27], v[140:143], v[188:191], v[24:27]
	v_mfma_f32_16x16x32_bf16 v[16:19], v[132:135], v[196:199], v[16:19]
	v_mfma_f32_16x16x32_bf16 v[8:11], v[140:143], v[196:199], v[8:11]
	s_setprio 0
	s_barrier
	s_add_u32 s44, s16, 0x80000
	s_addc_u32 s45, s17, 0
	s_add_i32 s46, s36, s24
	s_mov_b32 m0, s46
	s_nop 0
	global_load_lds_dwordx4 v146, s[44:45]
	s_add_i32 m0, s46, 0x2000
	s_nop 0
	global_load_lds_dwordx4 v150, s[44:45]
	s_add_u32 s18, s18, 0x80000
	s_addc_u32 s19, s19, 0
	s_mov_b32 m0, s26
	s_nop 0
	global_load_lds_dwordx4 v144, s[18:19]
	s_mov_b32 m0, s27
	s_nop 0
	global_load_lds_dwordx4 v148, s[18:19]
	s_waitcnt vmcnt(10)
	s_setprio 1
	s_barrier
	v_mfma_f32_16x16x32_bf16 v[52:55], v[202:205], v[162:165], v[52:55]
	v_mfma_f32_16x16x32_bf16 v[44:47], v[210:213], v[162:165], v[44:47]
	v_mfma_f32_16x16x32_bf16 v[36:39], v[202:205], v[176:179], v[36:39]
	v_mfma_f32_16x16x32_bf16 v[28:31], v[210:213], v[176:179], v[28:31]
	v_mfma_f32_16x16x32_bf16 v[20:23], v[202:205], v[184:187], v[20:23]
	v_mfma_f32_16x16x32_bf16 v[12:15], v[210:213], v[184:187], v[12:15]
	v_mfma_f32_16x16x32_bf16 v[4:7], v[202:205], v[192:195], v[4:7]
	v_mfma_f32_16x16x32_bf16 v[0:3], v[210:213], v[192:195], v[0:3]
	v_mfma_f32_16x16x32_bf16 v[52:55], v[206:209], v[172:175], v[52:55]
	v_mfma_f32_16x16x32_bf16 v[44:47], v[214:217], v[172:175], v[44:47]
	v_mfma_f32_16x16x32_bf16 v[36:39], v[206:209], v[180:183], v[36:39]
	v_mfma_f32_16x16x32_bf16 v[28:31], v[214:217], v[180:183], v[28:31]
	v_mfma_f32_16x16x32_bf16 v[20:23], v[206:209], v[188:191], v[20:23]
	v_mfma_f32_16x16x32_bf16 v[12:15], v[214:217], v[188:191], v[12:15]
	v_mfma_f32_16x16x32_bf16 v[4:7], v[206:209], v[196:199], v[4:7]
	v_mfma_f32_16x16x32_bf16 v[0:3], v[214:217], v[196:199], v[0:3]
	s_setprio 0
	s_add_i32 s44, 0, 0x18000
	v_add_u32_e32 v140, s44, v167
	s_barrier
	ds_read_b128 v[128:131], v140
	ds_read_b128 v[132:135], v140 offset:1024
	ds_read_b128 v[136:139], v140 offset:2048
	ds_read_b128 v[140:143], v140 offset:3072
	ds_read_b128 v[162:165], v169 offset:32768
	ds_read_b128 v[172:175], v169 offset:33792
	ds_read_b128 v[176:179], v169 offset:34816
	ds_read_b128 v[180:183], v169 offset:35840
	ds_read_b128 v[184:187], v169 offset:36864
	ds_read_b128 v[188:191], v169 offset:37888
	ds_read_b128 v[192:195], v169 offset:38912
	ds_read_b128 v[196:199], v169 offset:39936
	s_waitcnt lgkmcnt(8)
	s_waitcnt vmcnt(8)
	s_setprio 1
	s_barrier
; #define PG8_STAGE(bufoff, gbase, voff) do { _Pragma("unroll") for (int _i = 0; _i < 2; ++_i) \
;         __builtin_amdgcn_global_load_lds((const unsigned*)((const char*)(gbase) + (voff)[_i]), (LAS unsigned*)(lds + (bufoff) + ldsw + _i * 8192), 16, 0, 0); } while (0)
; #define PG8_LDA(dst, b, h) do { _Pragma("unroll") for (int m = 0; m < 4; ++m) _Pragma("unroll") for (int k = 0; k < 2; ++k) dst[m][k] = *(const LAS bf16x8*)(lds + PG8_SA(b, h) + aoff + m * 2048 + k * 1024); } while (0)
; #define PG8_LDB(dst, b, h) do { _Pragma("unroll") for (int n = 0; n < 2; ++n) _Pragma("unroll") for (int k = 0; k < 2; ++k) dst[n][k] = *(const LAS bf16x8*)(lds + PG8_SB(b, h) + boff + n * 2048 + k * 1024); } while (0)
; #define PG8_MMA(ai, bj, At, Bt) do { __builtin_amdgcn_s_setprio(1); _Pragma("unroll") for (int m = 0; m < 4; ++m) _Pragma("unroll") for (int n = 0; n < 2; ++n) _Pragma("unroll") for (int k = 0; k < 2; ++k) \
;         acc[ai][bj][m][n] = __builtin_amdgcn_mfma_f32_16x16x32_bf16(Bt[n][k], At[m][k], acc[ai][bj][m][n], 0, 0, 0); __builtin_amdgcn_s_setprio(0); } while (0)
; #define PG8_WAIT_V(n) asm volatile("s_waitcnt vmcnt(" #n ")" ::: "memory")
; #define PG8_WAIT_L(n) asm volatile("s_waitcnt lgkmcnt(" #n ")" ::: "memory")
; #define PG8_BAR __builtin_amdgcn_s_barrier()
; #define PG8_SCHED __builtin_amdgcn_sched_barrier(0)
; template <class Epi, class Sched>
; __device__ __forceinline__ void gemm_phase(LAS unsigned char* lds, const Gemm g, const Sched& S, const Epi& E) {
;     ...
;             PG8_WAIT_L(8); PG8_BAR; PG8_WAIT_L(0); PG8_MMA(0, 0, At, B0); PG8_BAR; PG8_SCHED;
;             PG8_LDB(B1, 1, 1); PG8_STAGE(PG8_SB(1, 0), b3, voffB);
;             PG8_BAR; PG8_WAIT_L(0); PG8_MMA(0, 1, At, B1); PG8_BAR;
;             PG8_LDA(At, 1, 1); PG8_STAGE(PG8_SA(1, 0), a3, voffA);
;             PG8_BAR; PG8_WAIT_L(0); PG8_MMA(1, 0, At, B0); PG8_BAR; PG8_SCHED;
;             PG8_STAGE(PG8_SB(1, 1), b3 + hstep, voffB);
;             PG8_WAIT_V(6); PG8_BAR; PG8_MMA(1, 1, At, B1); PG8_BAR;
	s_waitcnt lgkmcnt(0)
	v_mfma_f32_16x16x32_bf16 v[124:127], v[128:131], v[162:165], v[124:127]
	v_mfma_f32_16x16x32_bf16 v[120:123], v[136:139], v[162:165], v[120:123]
	v_mfma_f32_16x16x32_bf16 v[116:119], v[128:131], v[176:179], v[116:119]
	v_mfma_f32_16x16x32_bf16 v[112:115], v[136:139], v[176:179], v[112:115]
	v_mfma_f32_16x16x32_bf16 v[108:111], v[128:131], v[184:187], v[108:111]
	v_mfma_f32_16x16x32_bf16 v[100:103], v[136:139], v[184:187], v[100:103]
	v_mfma_f32_16x16x32_bf16 v[76:79], v[128:131], v[192:195], v[76:79]
	v_mfma_f32_16x16x32_bf16 v[72:75], v[136:139], v[192:195], v[72:75]
	v_mfma_f32_16x16x32_bf16 v[124:127], v[132:135], v[172:175], v[124:127]
	v_mfma_f32_16x16x32_bf16 v[120:123], v[140:143], v[172:175], v[120:123]
	v_mfma_f32_16x16x32_bf16 v[116:119], v[132:135], v[180:183], v[116:119]
	v_mfma_f32_16x16x32_bf16 v[112:115], v[140:143], v[180:183], v[112:115]
	v_mfma_f32_16x16x32_bf16 v[108:111], v[132:135], v[188:191], v[108:111]
	v_mfma_f32_16x16x32_bf16 v[100:103], v[140:143], v[188:191], v[100:103]
	v_mfma_f32_16x16x32_bf16 v[76:79], v[132:135], v[196:199], v[76:79]
	v_mfma_f32_16x16x32_bf16 v[72:75], v[140:143], v[196:199], v[72:75]
	s_setprio 0
	s_barrier
	s_add_i32 s18, 0, 0x1c000
	s_add_i32 s19, s44, s24
	v_add_u32_e32 v160, s18, v167
	s_add_u32 s0, s16, 0x80
	s_addc_u32 s1, s17, 0
	s_mov_b32 m0, s19
	ds_read_b128 v[202:205], v160
	ds_read_b128 v[206:209], v160 offset:1024
	ds_read_b128 v[210:213], v160 offset:2048
	ds_read_b128 v[214:217], v160 offset:3072
	global_load_lds_dwordx4 v146, s[0:1]
	s_add_i32 m0, s19, 0x2000
	s_nop 0
	global_load_lds_dwordx4 v150, s[0:1]
	s_waitcnt vmcnt(8)
	s_setprio 1
	s_barrier
	s_waitcnt lgkmcnt(0)
	v_mfma_f32_16x16x32_bf16 v[104:107], v[202:205], v[162:165], v[104:107]
	v_mfma_f32_16x16x32_bf16 v[96:99], v[210:213], v[162:165], v[96:99]
	v_mfma_f32_16x16x32_bf16 v[92:95], v[202:205], v[176:179], v[92:95]
	v_mfma_f32_16x16x32_bf16 v[88:91], v[210:213], v[176:179], v[88:91]
	v_mfma_f32_16x16x32_bf16 v[84:87], v[202:205], v[184:187], v[84:87]
	v_mfma_f32_16x16x32_bf16 v[80:83], v[210:213], v[184:187], v[80:83]
	v_mfma_f32_16x16x32_bf16 v[68:71], v[202:205], v[192:195], v[68:71]
	v_mfma_f32_16x16x32_bf16 v[64:67], v[210:213], v[192:195], v[64:67]
	v_mfma_f32_16x16x32_bf16 v[104:107], v[206:209], v[172:175], v[104:107]
	v_mfma_f32_16x16x32_bf16 v[96:99], v[214:217], v[172:175], v[96:99]
	v_mfma_f32_16x16x32_bf16 v[92:95], v[206:209], v[180:183], v[92:95]
	v_mfma_f32_16x16x32_bf16 v[88:91], v[214:217], v[180:183], v[88:91]
	v_mfma_f32_16x16x32_bf16 v[84:87], v[206:209], v[188:191], v[84:87]
	v_mfma_f32_16x16x32_bf16 v[80:83], v[214:217], v[188:191], v[80:83]
	v_mfma_f32_16x16x32_bf16 v[68:71], v[206:209], v[196:199], v[68:71]
	v_mfma_f32_16x16x32_bf16 v[64:67], v[214:217], v[196:199], v[64:67]
	s_setprio 0
	s_mov_b32 m0, s31
	s_mov_b64 s[0:1], 0x80
	v_lshl_add_u64 v[218:219], v[222:223], 0, s[0:1]
	s_barrier
	ds_read_b128 v[162:165], v169 offset:49152
	ds_read_b128 v[172:175], v169 offset:50176
	ds_read_b128 v[176:179], v169 offset:51200
	ds_read_b128 v[180:183], v169 offset:52224
	ds_read_b128 v[184:187], v169 offset:53248
	ds_read_b128 v[188:191], v169 offset:54272
	ds_read_b128 v[192:195], v169 offset:55296
	ds_read_b128 v[196:199], v169 offset:56320
	global_load_lds_dwordx4 v[218:219], off
	v_lshl_add_u64 v[218:219], v[224:225], 0, s[0:1]
	s_mov_b32 m0, s33
	s_nop 0
	global_load_lds_dwordx4 v[218:219], off
	s_setprio 1
	s_barrier
	s_waitcnt lgkmcnt(0)
	v_mfma_f32_16x16x32_bf16 v[60:63], v[128:131], v[162:165], v[60:63]
	v_mfma_f32_16x16x32_bf16 v[56:59], v[136:139], v[162:165], v[56:59]
	v_mfma_f32_16x16x32_bf16 v[48:51], v[128:131], v[176:179], v[48:51]
	v_mfma_f32_16x16x32_bf16 v[40:43], v[136:139], v[176:179], v[40:43]
	v_mfma_f32_16x16x32_bf16 v[32:35], v[128:131], v[184:187], v[32:35]
	v_mfma_f32_16x16x32_bf16 v[24:27], v[136:139], v[184:187], v[24:27]
	v_mfma_f32_16x16x32_bf16 v[16:19], v[128:131], v[192:195], v[16:19]
	v_mfma_f32_16x16x32_bf16 v[8:11], v[136:139], v[192:195], v[8:11]
	v_mfma_f32_16x16x32_bf16 v[60:63], v[132:135], v[172:175], v[60:63]
	v_mfma_f32_16x16x32_bf16 v[56:59], v[140:143], v[172:175], v[56:59]
	v_mfma_f32_16x16x32_bf16 v[48:51], v[132:135], v[180:183], v[48:51]
	v_mfma_f32_16x16x32_bf16 v[40:43], v[140:143], v[180:183], v[40:43]
	v_mfma_f32_16x16x32_bf16 v[32:35], v[132:135], v[188:191], v[32:35]
	v_mfma_f32_16x16x32_bf16 v[24:27], v[140:143], v[188:191], v[24:27]
	v_mfma_f32_16x16x32_bf16 v[16:19], v[132:135], v[196:199], v[16:19]
	v_mfma_f32_16x16x32_bf16 v[8:11], v[140:143], v[196:199], v[8:11]
	s_setprio 0
	s_barrier
	s_add_u32 s16, s16, 0x80080
	s_addc_u32 s17, s17, 0
	s_add_i32 s18, s18, s24
	s_mov_b32 m0, s18
	s_nop 0
	global_load_lds_dwordx4 v146, s[16:17]
	s_add_i32 m0, s18, 0x2000
	s_nop 0
	global_load_lds_dwordx4 v150, s[16:17]
	s_waitcnt vmcnt(8)
	s_setprio 1
	s_barrier
	v_mfma_f32_16x16x32_bf16 v[52:55], v[202:205], v[162:165], v[52:55]
	v_mfma_f32_16x16x32_bf16 v[44:47], v[210:213], v[162:165], v[44:47]
	v_mfma_f32_16x16x32_bf16 v[36:39], v[202:205], v[176:179], v[36:39]
	v_mfma_f32_16x16x32_bf16 v[28:31], v[210:213], v[176:179], v[28:31]
	v_mfma_f32_16x16x32_bf16 v[20:23], v[202:205], v[184:187], v[20:23]
	v_mfma_f32_16x16x32_bf16 v[12:15], v[210:213], v[184:187], v[12:15]
	v_mfma_f32_16x16x32_bf16 v[4:7], v[202:205], v[192:195], v[4:7]
	v_mfma_f32_16x16x32_bf16 v[0:3], v[210:213], v[192:195], v[0:3]
	v_mfma_f32_16x16x32_bf16 v[52:55], v[206:209], v[172:175], v[52:55]
	v_mfma_f32_16x16x32_bf16 v[44:47], v[214:217], v[172:175], v[44:47]
	v_mfma_f32_16x16x32_bf16 v[36:39], v[206:209], v[180:183], v[36:39]
	v_mfma_f32_16x16x32_bf16 v[28:31], v[214:217], v[180:183], v[28:31]
	v_mfma_f32_16x16x32_bf16 v[20:23], v[206:209], v[188:191], v[20:23]
	v_mfma_f32_16x16x32_bf16 v[12:15], v[214:217], v[188:191], v[12:15]
	v_mfma_f32_16x16x32_bf16 v[4:7], v[206:209], v[196:199], v[4:7]
	v_mfma_f32_16x16x32_bf16 v[0:3], v[214:217], v[196:199], v[0:3]
	s_setprio 0
	s_add_i32 s43, s43, 2
	s_add_u32 s14, s14, 0x100
	s_addc_u32 s15, s15, 0
	s_add_u32 s41, s41, 0x100
	s_addc_u32 s42, s42, 0
	s_cmp_gt_u32 s43, 29
	s_barrier
; __device__ __forceinline__ unsigned cvt_pk_bf16(float lo, float hi) { unsigned r; asm volatile("v_cvt_pk_bf16_f32 %0, %1, %2" : "=v"(r) : "v"(lo), "v"(hi)); return r; }
;     __device__ __forceinline__ void operator()(const AccT& acc, const Unit& u, int wr, int wc, int fr, int fq) const {
;         asm volatile("" : "+v"(fr), "+v"(fq));
;         const int row0 = u.pm * 256 + wr * 64 + fr; const int b = u.pn >> 1, ch0 = (u.pn & 1) * 256 + wc * 32 + 8 * fq;
;         const float sg = (fr & 1) ? -1.0f : 1.0f;
;         f32x4 yh[2][2];
; #pragma unroll
;         for (int bj = 0; bj < 2; ++bj)
; #pragma unroll
;             for (int n = 0; n < 2; ++n) yh[bj][n] = *(const f32x4*)(YCH + b * 512 + ch0 + bj * 128 + 4 * n) * sg;
; #pragma unroll
;         for (int ai = 0; ai < 2; ++ai)
; #pragma unroll
;             for (int m = 0; m < 4; ++m) {
;                 const int k = row0 + ai * 128 + m * 16;
; #pragma unroll
;                 for (int bj = 0; bj < 2; ++bj) {
;                     const f32x4 v0 = acc[ai][bj][m][0] + yh[bj][0], v1 = acc[ai][bj][m][1] + yh[bj][1];
;                     u32x4 w; w.x = cvt_pk_bf16(v0[0], v0[1]); w.y = cvt_pk_bf16(v0[2], v0[3]); w.z = cvt_pk_bf16(v1[0], v1[1]); w.w = cvt_pk_bf16(v1[2], v1[3]);
;                     *(u32x4*)(CAT + (size_t)(b * 2048 + k) * CATW + 1024 + ch0 + bj * 128) = w;
;                 }
	s_cbranch_scc0 .LBB0_826
	s_ashr_i32 s5, s38, 1
	s_lshl_b32 s7, s38, 8
	s_lshl_b32 s14, s5, 9
	s_and_b32 s7, s7, 0x100
	s_ashr_i32 s15, s14, 31
	v_mov_b32_e32 v171, v161
	v_mov_b32_e32 v128, v166
	s_or_b32 s7, s7, s30
	s_lshl_b64 s[14:15], s[14:15], 2
	s_add_u32 s14, s48, s14
	v_lshl_add_u32 v164, v128, 3, s7
	s_addc_u32 s15, s49, s15
	v_ashrrev_i32_e32 v165, 31, v164
	v_lshl_add_u64 v[128:129], v[164:165], 2, s[14:15]
	global_load_dwordx4 v[140:143], v[128:129], off
	global_load_dwordx4 v[136:139], v[128:129], off offset:16
	global_load_dwordx4 v[132:135], v[128:129], off offset:512
	s_nop 0
	global_load_dwordx4 v[128:131], v[128:129], off offset:528
	s_lshl_b32 s7, s12, 8
	s_lshl_b32 s5, s5, 11
	s_add_i32 s7, s7, s29
	v_and_b32_e32 v160, 1, v171
	s_add_i32 s7, s7, s5
	v_mov_b64_e32 v[162:163], s[96:97]
	v_cmp_eq_u32_e32 vcc, 0, v160
	v_add_u32_e32 v171, s7, v171
	v_lshlrev_b64 v[164:165], 1, v[164:165]
	v_cndmask_b32_e64 v160, -1.0, 1.0, vcc
	v_mad_i64_i32 v[172:173], s[14:15], v171, s37, v[162:163]
	v_add_u32_e32 v174, 16, v171
	v_lshl_add_u64 v[172:173], v[172:173], 0, v[164:165]
	v_mad_i64_i32 v[174:175], s[14:15], v174, s37, v[162:163]
	v_add_u32_e32 v176, 32, v171
	v_lshl_add_u64 v[174:175], v[174:175], 0, v[164:165]
	v_mad_i64_i32 v[176:177], s[14:15], v176, s37, v[162:163]
	v_lshl_add_u64 v[176:177], v[176:177], 0, v[164:165]
	v_add_u32_e32 v182, 48, v171
	s_and_b64 vcc, exec, s[2:3]
	s_mov_b32 s38, s4
	s_mov_b32 s12, s6
	s_mov_b64 s[16:17], s[10:11]
	s_waitcnt vmcnt(0)
	v_pk_fma_f32 v[126:127], v[142:143], v[160:161], v[126:127] op_sel_hi:[1,0,1]
	v_pk_fma_f32 v[124:125], v[140:141], v[160:161], v[124:125] op_sel_hi:[1,0,1]
	v_pk_fma_f32 v[122:123], v[138:139], v[160:161], v[122:123] op_sel_hi:[1,0,1]
	v_pk_fma_f32 v[180:181], v[128:129], v[160:161], v[80:81] op_sel_hi:[1,0,1]
	v_cvt_pk_bf16_f32 v80, v124, v125
	v_cvt_pk_bf16_f32 v81, v126, v127
	v_pk_fma_f32 v[120:121], v[136:137], v[160:161], v[120:121] op_sel_hi:[1,0,1]
	v_pk_fma_f32 v[106:107], v[134:135], v[160:161], v[106:107] op_sel_hi:[1,0,1]
	v_pk_fma_f32 v[104:105], v[132:133], v[160:161], v[104:105] op_sel_hi:[1,0,1]
	v_pk_fma_f32 v[178:179], v[130:131], v[160:161], v[82:83] op_sel_hi:[1,0,1]
	v_cvt_pk_bf16_f32 v82, v120, v121
	v_cvt_pk_bf16_f32 v83, v122, v123
	global_store_dwordx4 v[172:173], v[80:83], off offset:2048
	v_pk_fma_f32 v[98:99], v[130:131], v[160:161], v[98:99] op_sel_hi:[1,0,1]
	v_pk_fma_f32 v[96:97], v[128:129], v[160:161], v[96:97] op_sel_hi:[1,0,1]
	v_cvt_pk_bf16_f32 v80, v104, v105
	v_cvt_pk_bf16_f32 v81, v106, v107
	v_pk_fma_f32 v[118:119], v[142:143], v[160:161], v[118:119] op_sel_hi:[1,0,1]
	v_pk_fma_f32 v[116:117], v[140:141], v[160:161], v[116:117] op_sel_hi:[1,0,1]
	v_cvt_pk_bf16_f32 v82, v96, v97
	v_cvt_pk_bf16_f32 v83, v98, v99
	global_store_dwordx4 v[172:173], v[80:83], off offset:2304
	v_pk_fma_f32 v[114:115], v[138:139], v[160:161], v[114:115] op_sel_hi:[1,0,1]
	v_pk_fma_f32 v[112:113], v[136:137], v[160:161], v[112:113] op_sel_hi:[1,0,1]
	v_cvt_pk_bf16_f32 v80, v116, v117
	v_cvt_pk_bf16_f32 v81, v118, v119
	v_pk_fma_f32 v[94:95], v[134:135], v[160:161], v[94:95] op_sel_hi:[1,0,1]
	v_pk_fma_f32 v[92:93], v[132:133], v[160:161], v[92:93] op_sel_hi:[1,0,1]
	v_cvt_pk_bf16_f32 v82, v112, v113
	v_cvt_pk_bf16_f32 v83, v114, v115
	global_store_dwordx4 v[174:175], v[80:83], off offset:2048
	v_pk_fma_f32 v[90:91], v[130:131], v[160:161], v[90:91] op_sel_hi:[1,0,1]
	v_pk_fma_f32 v[88:89], v[128:129], v[160:161], v[88:89] op_sel_hi:[1,0,1]
	v_cvt_pk_bf16_f32 v80, v92, v93
	v_cvt_pk_bf16_f32 v81, v94, v95
	v_pk_fma_f32 v[110:111], v[142:143], v[160:161], v[110:111] op_sel_hi:[1,0,1]
	v_pk_fma_f32 v[108:109], v[140:141], v[160:161], v[108:109] op_sel_hi:[1,0,1]
	v_cvt_pk_bf16_f32 v82, v88, v89
	v_cvt_pk_bf16_f32 v83, v90, v91
	global_store_dwordx4 v[174:175], v[80:83], off offset:2304
	v_pk_fma_f32 v[102:103], v[138:139], v[160:161], v[102:103] op_sel_hi:[1,0,1]
	v_pk_fma_f32 v[100:101], v[136:137], v[160:161], v[100:101] op_sel_hi:[1,0,1]
	v_cvt_pk_bf16_f32 v80, v108, v109
	v_cvt_pk_bf16_f32 v81, v110, v111
	v_pk_fma_f32 v[86:87], v[134:135], v[160:161], v[86:87] op_sel_hi:[1,0,1]
	v_pk_fma_f32 v[84:85], v[132:133], v[160:161], v[84:85] op_sel_hi:[1,0,1]
	v_cvt_pk_bf16_f32 v82, v100, v101
	v_cvt_pk_bf16_f32 v83, v102, v103
	global_store_dwordx4 v[176:177], v[80:83], off offset:2048
	v_pk_fma_f32 v[76:77], v[140:141], v[160:161], v[76:77] op_sel_hi:[1,0,1]
	v_pk_fma_f32 v[78:79], v[142:143], v[160:161], v[78:79] op_sel_hi:[1,0,1]
	v_cvt_pk_bf16_f32 v80, v84, v85
	v_cvt_pk_bf16_f32 v81, v86, v87
	v_cvt_pk_bf16_f32 v82, v180, v181
	v_cvt_pk_bf16_f32 v83, v178, v179
	global_store_dwordx4 v[176:177], v[80:83], off offset:2304
	v_pk_fma_f32 v[70:71], v[134:135], v[160:161], v[70:71] op_sel_hi:[1,0,1]
	v_pk_fma_f32 v[68:69], v[132:133], v[160:161], v[68:69] op_sel_hi:[1,0,1]
	v_pk_fma_f32 v[80:81], v[138:139], v[160:161], v[74:75] op_sel_hi:[1,0,1]
	v_pk_fma_f32 v[74:75], v[136:137], v[160:161], v[72:73] op_sel_hi:[1,0,1]
	v_cvt_pk_bf16_f32 v72, v76, v77
	v_mad_i64_i32 v[76:77], s[14:15], v182, s37, v[162:163]
	v_cvt_pk_bf16_f32 v73, v78, v79
; __device__ __forceinline__ unsigned cvt_pk_bf16(float lo, float hi) { unsigned r; asm volatile("v_cvt_pk_bf16_f32 %0, %1, %2" : "=v"(r) : "v"(lo), "v"(hi)); return r; }
; #define PG8_WAIT_V(n) asm volatile("s_waitcnt vmcnt(" #n ")" ::: "memory")
; #define PG8_BAR __builtin_amdgcn_s_barrier()
; template <class Epi, class Sched>
; __device__ __forceinline__ void gemm_phase(LAS unsigned char* lds, const Gemm g, const Sched& S, const Epi& E) {
;     ...
;         E(acc, cur, wr, wc, fr, fq);
;         if (!has_next) break;
; #pragma unroll
;         for (int a = 0; a < 2; ++a)
; #pragma unroll
;             for (int b = 0; b < 2; ++b)
; #pragma unroll
;                 for (int m = 0; m < 4; ++m)
; #pragma unroll
;                     for (int n = 0; n < 2; ++n) acc[a][b][m][n] = (f32x4){0.f, 0.f, 0.f, 0.f};
;         cur = nxt; cA = nA; cB = nB; ++ui;
;     }
;     PG8_WAIT_V(0);
;     if (wr == 0) PG8_BAR;
;     PG8_BAR;
;     __device__ __forceinline__ void operator()(const AccT& acc, const Unit& u, int wr, int wc, int fr, int fq) const {
;     ...
;         for (int ai = 0; ai < 2; ++ai)
; #pragma unroll
;             for (int m = 0; m < 4; ++m) {
;                 const int k = row0 + ai * 128 + m * 16;
; #pragma unroll
;                 for (int bj = 0; bj < 2; ++bj) {
;                     const f32x4 v0 = acc[ai][bj][m][0] + yh[bj][0], v1 = acc[ai][bj][m][1] + yh[bj][1];
;                     u32x4 w; w.x = cvt_pk_bf16(v0[0], v0[1]); w.y = cvt_pk_bf16(v0[2], v0[3]); w.z = cvt_pk_bf16(v1[0], v1[1]); w.w = cvt_pk_bf16(v1[2], v1[3]);
;                     *(u32x4*)(CAT + (size_t)(b * 2048 + k) * CATW + 1024 + ch0 + bj * 128) = w;
;                 }
	v_lshl_add_u64 v[76:77], v[76:77], 0, v[164:165]
	v_cvt_pk_bf16_f32 v74, v74, v75
	v_cvt_pk_bf16_f32 v75, v80, v81
	global_store_dwordx4 v[76:77], v[72:75], off offset:2048
	v_pk_fma_f32 v[60:61], v[140:141], v[160:161], v[60:61] op_sel_hi:[1,0,1]
	v_pk_fma_f32 v[62:63], v[142:143], v[160:161], v[62:63] op_sel_hi:[1,0,1]
	v_pk_fma_f32 v[72:73], v[130:131], v[160:161], v[66:67] op_sel_hi:[1,0,1]
	v_pk_fma_f32 v[66:67], v[128:129], v[160:161], v[64:65] op_sel_hi:[1,0,1]
	v_cvt_pk_bf16_f32 v64, v68, v69
	v_cvt_pk_bf16_f32 v65, v70, v71
	v_pk_fma_f32 v[54:55], v[134:135], v[160:161], v[54:55] op_sel_hi:[1,0,1]
	v_cvt_pk_bf16_f32 v66, v66, v67
	v_cvt_pk_bf16_f32 v67, v72, v73
	global_store_dwordx4 v[76:77], v[64:67], off offset:2304
	v_pk_fma_f32 v[52:53], v[132:133], v[160:161], v[52:53] op_sel_hi:[1,0,1]
	v_pk_fma_f32 v[38:39], v[134:135], v[160:161], v[38:39] op_sel_hi:[1,0,1]
	v_add_u32_e32 v66, 0x80, v171
	v_pk_fma_f32 v[64:65], v[138:139], v[160:161], v[58:59] op_sel_hi:[1,0,1]
	v_pk_fma_f32 v[58:59], v[136:137], v[160:161], v[56:57] op_sel_hi:[1,0,1]
	v_cvt_pk_bf16_f32 v56, v60, v61
	v_mad_i64_i32 v[60:61], s[14:15], v66, s37, v[162:163]
	v_cvt_pk_bf16_f32 v57, v62, v63
	v_lshl_add_u64 v[60:61], v[60:61], 0, v[164:165]
	v_cvt_pk_bf16_f32 v58, v58, v59
	v_cvt_pk_bf16_f32 v59, v64, v65
	global_store_dwordx4 v[60:61], v[56:59], off offset:2048
	v_pk_fma_f32 v[36:37], v[132:133], v[160:161], v[36:37] op_sel_hi:[1,0,1]
	v_pk_fma_f32 v[22:23], v[134:135], v[160:161], v[22:23] op_sel_hi:[1,0,1]
	v_pk_fma_f32 v[56:57], v[130:131], v[160:161], v[46:47] op_sel_hi:[1,0,1]
	v_pk_fma_f32 v[46:47], v[128:129], v[160:161], v[44:45] op_sel_hi:[1,0,1]
	v_cvt_pk_bf16_f32 v44, v52, v53
	v_cvt_pk_bf16_f32 v45, v54, v55
	v_add_u32_e32 v52, 0x90, v171
	v_cvt_pk_bf16_f32 v46, v46, v47
	v_cvt_pk_bf16_f32 v47, v56, v57
	global_store_dwordx4 v[60:61], v[44:47], off offset:2304
	v_pk_fma_f32 v[20:21], v[132:133], v[160:161], v[20:21] op_sel_hi:[1,0,1]
	v_pk_fma_f32 v[6:7], v[134:135], v[160:161], v[6:7] op_sel_hi:[1,0,1]
	v_pk_fma_f32 v[44:45], v[142:143], v[160:161], v[50:51] op_sel_hi:[1,0,1]
	v_pk_fma_f32 v[46:47], v[140:141], v[160:161], v[48:49] op_sel_hi:[1,0,1]
	v_pk_fma_f32 v[48:49], v[138:139], v[160:161], v[42:43] op_sel_hi:[1,0,1]
	v_pk_fma_f32 v[42:43], v[136:137], v[160:161], v[40:41] op_sel_hi:[1,0,1]
	v_cvt_pk_bf16_f32 v40, v46, v47
	v_cvt_pk_bf16_f32 v41, v44, v45
	v_mad_i64_i32 v[44:45], s[14:15], v52, s37, v[162:163]
	v_lshl_add_u64 v[44:45], v[44:45], 0, v[164:165]
	v_cvt_pk_bf16_f32 v42, v42, v43
	v_cvt_pk_bf16_f32 v43, v48, v49
	global_store_dwordx4 v[44:45], v[40:43], off offset:2048
	v_pk_fma_f32 v[4:5], v[132:133], v[160:161], v[4:5] op_sel_hi:[1,0,1]
	s_nop 0
	v_pk_fma_f32 v[40:41], v[130:131], v[160:161], v[30:31] op_sel_hi:[1,0,1]
	v_pk_fma_f32 v[30:31], v[128:129], v[160:161], v[28:29] op_sel_hi:[1,0,1]
	v_cvt_pk_bf16_f32 v28, v36, v37
	v_cvt_pk_bf16_f32 v29, v38, v39
	v_add_u32_e32 v36, 0xa0, v171
	v_cvt_pk_bf16_f32 v30, v30, v31
	v_cvt_pk_bf16_f32 v31, v40, v41
	global_store_dwordx4 v[44:45], v[28:31], off offset:2304
	s_nop 1
	v_pk_fma_f32 v[28:29], v[142:143], v[160:161], v[34:35] op_sel_hi:[1,0,1]
	v_pk_fma_f32 v[30:31], v[140:141], v[160:161], v[32:33] op_sel_hi:[1,0,1]
	v_pk_fma_f32 v[32:33], v[138:139], v[160:161], v[26:27] op_sel_hi:[1,0,1]
	v_pk_fma_f32 v[26:27], v[136:137], v[160:161], v[24:25] op_sel_hi:[1,0,1]
	v_cvt_pk_bf16_f32 v24, v30, v31
	v_cvt_pk_bf16_f32 v25, v28, v29
	v_mad_i64_i32 v[28:29], s[14:15], v36, s37, v[162:163]
	v_lshl_add_u64 v[28:29], v[28:29], 0, v[164:165]
	v_cvt_pk_bf16_f32 v26, v26, v27
	v_cvt_pk_bf16_f32 v27, v32, v33
	global_store_dwordx4 v[28:29], v[24:27], off offset:2048
	s_nop 1
	v_pk_fma_f32 v[24:25], v[130:131], v[160:161], v[14:15] op_sel_hi:[1,0,1]
	v_pk_fma_f32 v[14:15], v[128:129], v[160:161], v[12:13] op_sel_hi:[1,0,1]
	v_cvt_pk_bf16_f32 v12, v20, v21
	v_cvt_pk_bf16_f32 v13, v22, v23
	v_add_u32_e32 v20, 0xb0, v171
	v_cvt_pk_bf16_f32 v14, v14, v15
	v_cvt_pk_bf16_f32 v15, v24, v25
	global_store_dwordx4 v[28:29], v[12:15], off offset:2304
	s_nop 1
	v_pk_fma_f32 v[12:13], v[142:143], v[160:161], v[18:19] op_sel_hi:[1,0,1]
	v_pk_fma_f32 v[14:15], v[140:141], v[160:161], v[16:17] op_sel_hi:[1,0,1]
	v_pk_fma_f32 v[16:17], v[138:139], v[160:161], v[10:11] op_sel_hi:[1,0,1]
	v_pk_fma_f32 v[10:11], v[136:137], v[160:161], v[8:9] op_sel_hi:[1,0,1]
	v_cvt_pk_bf16_f32 v8, v14, v15
	v_cvt_pk_bf16_f32 v9, v12, v13
	v_mad_i64_i32 v[12:13], s[14:15], v20, s37, v[162:163]
	v_lshl_add_u64 v[12:13], v[12:13], 0, v[164:165]
	v_cvt_pk_bf16_f32 v10, v10, v11
	v_cvt_pk_bf16_f32 v11, v16, v17
	global_store_dwordx4 v[12:13], v[8:11], off offset:2048
	s_mov_b64 s[14:15], s[8:9]
	s_nop 0
	v_pk_fma_f32 v[8:9], v[130:131], v[160:161], v[2:3] op_sel_hi:[1,0,1]
	v_pk_fma_f32 v[2:3], v[128:129], v[160:161], v[0:1] op_sel_hi:[1,0,1]
	v_cvt_pk_bf16_f32 v0, v4, v5
	v_cvt_pk_bf16_f32 v1, v6, v7
	s_nop 0
	v_cvt_pk_bf16_f32 v2, v2, v3
	v_cvt_pk_bf16_f32 v3, v8, v9
	global_store_dwordx4 v[12:13], v[0:3], off offset:2304
	s_cbranch_vccz .LBB0_819
	s_waitcnt vmcnt(0)
	s_cmpk_gt_u32 s20, 0xff
	s_cbranch_scc1 .LBB0_830
	s_barrier

; #define PG8_STAGE(bufoff, gbase, voff) do { _Pragma("unroll") for (int _i = 0; _i < 2; ++_i) \
;         __builtin_amdgcn_global_load_lds((const unsigned*)((const char*)(gbase) + (voff)[_i]), (LAS unsigned*)(lds + (bufoff) + ldsw + _i * 8192), 16, 0, 0); } while (0)
; #define PG8_LDA(dst, b, h) do { _Pragma("unroll") for (int m = 0; m < 4; ++m) _Pragma("unroll") for (int k = 0; k < 2; ++k) dst[m][k] = *(const LAS bf16x8*)(lds + PG8_SA(b, h) + aoff + m * 2048 + k * 1024); } while (0)
; #define PG8_LDB(dst, b, h) do { _Pragma("unroll") for (int n = 0; n < 2; ++n) _Pragma("unroll") for (int k = 0; k < 2; ++k) dst[n][k] = *(const LAS bf16x8*)(lds + PG8_SB(b, h) + boff + n * 2048 + k * 1024); } while (0)
; #define PG8_WAIT_V(n) asm volatile("s_waitcnt vmcnt(" #n ")" ::: "memory")
; #define PG8_WAIT_L(n) asm volatile("s_waitcnt lgkmcnt(" #n ")" ::: "memory")
; #define PG8_BAR __builtin_amdgcn_s_barrier()
; template <class Epi, class Sched>
; __device__ __forceinline__ void gemm_phase(LAS unsigned char* lds, const Gemm g, const Sched& S, const Epi& E) {
;     ...
;         const bool has_next = S.next(ui + 1, nxt);
;         const char* nA = has_next ? (const char*)g.A + (size_t)nxt.pm * tstep : cA; const char* nB = has_next ? (const char*)g.Bt + (size_t)nxt.pn * tstep : cB;
;         for (int t = 0; t < nt; t += 2) {
;             const bool last = (t == nt - 2);
;             const char* a1 = cA + (size_t)(t + 1) * kstep;
;             const char* a2 = last ? nA : cA + (size_t)(t + 2) * kstep; const char* b2 = last ? nB : cB + (size_t)(t + 2) * kstep;
;             const char* a3 = a2 + kstep; const char* b3 = b2 + kstep;
;             PG8_LDB(B0, 0, 0); PG8_SCHED; PG8_LDA(At, 0, 0); PG8_STAGE(PG8_SA(1, 1), a1 + hstep, voffA);
;             PG8_WAIT_L(8); PG8_BAR; PG8_WAIT_L(0); PG8_MMA(0, 0, At, B0); PG8_BAR; PG8_SCHED;
;             PG8_LDB(B1, 0, 1); PG8_STAGE(PG8_SB(0, 0), b2, voffB);
;             PG8_BAR; PG8_WAIT_L(0); PG8_MMA(0, 1, At, B1); PG8_BAR;
;             PG8_LDA(At, 0, 1); PG8_STAGE(PG8_SA(0, 0), a2, voffA);
;             PG8_BAR; PG8_WAIT_L(0); PG8_MMA(1, 0, At, B0); PG8_BAR; PG8_SCHED;
;             PG8_STAGE(PG8_SB(0, 1), b2 + hstep, voffB);
;             PG8_WAIT_V(6); PG8_BAR; PG8_MMA(1, 1, At, B1); PG8_BAR;
;             PG8_LDB(B0, 1, 0); PG8_SCHED; PG8_LDA(At, 1, 0); PG8_STAGE(PG8_SA(0, 1), a2 + hstep, voffA);
.LBB0_901:
	s_add_u32 s56, s26, 0x100
	s_addc_u32 s57, s27, 0
	s_mov_b32 s58, -2
	s_waitcnt vmcnt(0)
	ds_read_b128 v[128:131], v237
	ds_read_b128 v[132:135], v237 offset:1024
	ds_read_b128 v[136:139], v237 offset:2048
	ds_read_b128 v[140:143], v237 offset:3072
	s_add_u32 s26, s24, 0x100
	s_addc_u32 s27, s25, 0
	s_cmp_eq_u32 s58, 20
	s_cselect_b32 s31, s5, s27
	s_cselect_b32 s30, s4, s26
	s_cselect_b32 s29, s7, s57
	s_cselect_b32 s28, s6, s56
	v_lshl_add_u64 v[176:177], s[24:25], 0, v[210:211]
	s_add_i32 m0, s38, 0xc000
	ds_read_b128 v[144:147], v238
	ds_read_b128 v[148:151], v238 offset:1024
	ds_read_b128 v[152:155], v238 offset:2048
	ds_read_b128 v[156:159], v238 offset:3072
	ds_read_b128 v[160:163], v238 offset:4096
	ds_read_b128 v[164:167], v238 offset:5120
	ds_read_b128 v[168:171], v238 offset:6144
	ds_read_b128 v[172:175], v238 offset:7168
	global_load_lds_dwordx4 v[176:177], off
	v_lshl_add_u64 v[176:177], s[24:25], 0, v[212:213]
	s_add_i32 m0, s38, 0xe000
	s_nop 0
	global_load_lds_dwordx4 v[176:177], off
	s_waitcnt lgkmcnt(8)
	s_waitcnt vmcnt(8)
	s_setprio 1
	s_barrier
	s_waitcnt lgkmcnt(0)
	v_mfma_f32_16x16x32_bf16 v[124:127], v[128:131], v[144:147], 0
	v_mfma_f32_16x16x32_bf16 v[120:123], v[136:139], v[144:147], 0
	v_mfma_f32_16x16x32_bf16 v[108:111], v[128:131], v[152:155], 0
	v_mfma_f32_16x16x32_bf16 v[104:107], v[136:139], v[152:155], 0
	v_mfma_f32_16x16x32_bf16 v[92:95], v[128:131], v[160:163], 0
	v_mfma_f32_16x16x32_bf16 v[88:91], v[136:139], v[160:163], 0
	v_mfma_f32_16x16x32_bf16 v[76:79], v[128:131], v[168:171], 0
	v_mfma_f32_16x16x32_bf16 v[72:75], v[136:139], v[168:171], 0
	v_mfma_f32_16x16x32_bf16 v[124:127], v[132:135], v[148:151], v[124:127]
	v_mfma_f32_16x16x32_bf16 v[120:123], v[140:143], v[148:151], v[120:123]
	v_mfma_f32_16x16x32_bf16 v[108:111], v[132:135], v[156:159], v[108:111]
	v_mfma_f32_16x16x32_bf16 v[104:107], v[140:143], v[156:159], v[104:107]
	v_mfma_f32_16x16x32_bf16 v[92:95], v[132:135], v[164:167], v[92:95]
	v_mfma_f32_16x16x32_bf16 v[88:91], v[140:143], v[164:167], v[88:91]
	v_mfma_f32_16x16x32_bf16 v[76:79], v[132:135], v[172:175], v[76:79]
	v_mfma_f32_16x16x32_bf16 v[72:75], v[140:143], v[172:175], v[72:75]
	s_setprio 0
	s_barrier
	s_add_i32 s24, s50, s37
	s_mov_b32 m0, s24
	ds_read_b128 v[176:179], v239
	ds_read_b128 v[180:183], v239 offset:1024
	ds_read_b128 v[184:187], v239 offset:2048
	ds_read_b128 v[188:191], v239 offset:3072
	global_load_lds_dwordx4 v204, s[28:29]
	s_add_i32 m0, s24, 0x2000
	s_nop 0
	global_load_lds_dwordx4 v208, s[28:29]
	s_waitcnt vmcnt(8)
	s_setprio 1
	s_barrier
	s_waitcnt lgkmcnt(0)
	v_mfma_f32_16x16x32_bf16 v[116:119], v[176:179], v[144:147], 0
	v_mfma_f32_16x16x32_bf16 v[112:115], v[184:187], v[144:147], 0
	v_mfma_f32_16x16x32_bf16 v[100:103], v[176:179], v[152:155], 0
	v_mfma_f32_16x16x32_bf16 v[96:99], v[184:187], v[152:155], 0
	v_mfma_f32_16x16x32_bf16 v[84:87], v[176:179], v[160:163], 0
	v_mfma_f32_16x16x32_bf16 v[80:83], v[184:187], v[160:163], 0
	v_mfma_f32_16x16x32_bf16 v[68:71], v[176:179], v[168:171], 0
	v_mfma_f32_16x16x32_bf16 v[64:67], v[184:187], v[168:171], 0
	v_mfma_f32_16x16x32_bf16 v[116:119], v[180:183], v[148:151], v[116:119]
	v_mfma_f32_16x16x32_bf16 v[112:115], v[188:191], v[148:151], v[112:115]
	v_mfma_f32_16x16x32_bf16 v[100:103], v[180:183], v[156:159], v[100:103]
	v_mfma_f32_16x16x32_bf16 v[96:99], v[188:191], v[156:159], v[96:99]
	v_mfma_f32_16x16x32_bf16 v[84:87], v[180:183], v[164:167], v[84:87]
	v_mfma_f32_16x16x32_bf16 v[80:83], v[188:191], v[164:167], v[80:83]
	v_mfma_f32_16x16x32_bf16 v[68:71], v[180:183], v[172:175], v[68:71]
	v_mfma_f32_16x16x32_bf16 v[64:67], v[188:191], v[172:175], v[64:67]
	s_setprio 0
	s_mov_b32 m0, s38
	v_lshl_add_u64 v[196:197], s[30:31], 0, v[202:203]
	s_barrier
	ds_read_b128 v[144:147], v238 offset:16384
	ds_read_b128 v[148:151], v238 offset:17408
	ds_read_b128 v[152:155], v238 offset:18432
	ds_read_b128 v[156:159], v238 offset:19456
	ds_read_b128 v[160:163], v238 offset:20480
	ds_read_b128 v[164:167], v238 offset:21504
	ds_read_b128 v[168:171], v238 offset:22528
	ds_read_b128 v[172:175], v238 offset:23552
	global_load_lds_dwordx4 v202, s[30:31]
	v_lshl_add_u64 v[198:199], s[30:31], 0, v[206:207]
	s_mov_b32 m0, s39
	s_nop 0
	global_load_lds_dwordx4 v206, s[30:31]
	s_setprio 1
	s_barrier
	s_waitcnt lgkmcnt(0)
	v_mfma_f32_16x16x32_bf16 v[60:63], v[128:131], v[144:147], 0
	v_mfma_f32_16x16x32_bf16 v[56:59], v[136:139], v[144:147], 0
	v_mfma_f32_16x16x32_bf16 v[44:47], v[128:131], v[152:155], 0
	v_mfma_f32_16x16x32_bf16 v[40:43], v[136:139], v[152:155], 0
	v_mfma_f32_16x16x32_bf16 v[28:31], v[128:131], v[160:163], 0
	v_mfma_f32_16x16x32_bf16 v[24:27], v[136:139], v[160:163], 0
	v_mfma_f32_16x16x32_bf16 v[12:15], v[128:131], v[168:171], 0
	v_mfma_f32_16x16x32_bf16 v[8:11], v[136:139], v[168:171], 0
	v_mfma_f32_16x16x32_bf16 v[60:63], v[132:135], v[148:151], v[60:63]
	v_mfma_f32_16x16x32_bf16 v[56:59], v[140:143], v[148:151], v[56:59]
	v_mfma_f32_16x16x32_bf16 v[44:47], v[132:135], v[156:159], v[44:47]
	v_mfma_f32_16x16x32_bf16 v[40:43], v[140:143], v[156:159], v[40:43]
	v_mfma_f32_16x16x32_bf16 v[28:31], v[132:135], v[164:167], v[28:31]
	v_mfma_f32_16x16x32_bf16 v[24:27], v[140:143], v[164:167], v[24:27]
	v_mfma_f32_16x16x32_bf16 v[12:15], v[132:135], v[172:175], v[12:15]
	v_mfma_f32_16x16x32_bf16 v[8:11], v[140:143], v[172:175], v[8:11]
	s_setprio 0
	s_barrier
	s_add_u32 s24, s28, 0x60000
	s_addc_u32 s25, s29, 0
	s_add_i32 s59, s51, s37
	s_mov_b32 m0, s59
	s_nop 0
	global_load_lds_dwordx4 v204, s[24:25]
	s_add_i32 m0, s59, 0x2000
	s_nop 0
	global_load_lds_dwordx4 v208, s[24:25]
	s_add_u32 s24, s30, 0x60000
	s_addc_u32 s25, s31, 0
	s_mov_b32 m0, s40
	s_nop 0
	global_load_lds_dwordx4 v202, s[24:25]
	s_mov_b32 m0, s41
	s_nop 0
	global_load_lds_dwordx4 v206, s[24:25]
	s_waitcnt vmcnt(10)
	s_setprio 1
	s_barrier
; #define PG8_STAGE(bufoff, gbase, voff) do { _Pragma("unroll") for (int _i = 0; _i < 2; ++_i) \
;         __builtin_amdgcn_global_load_lds((const unsigned*)((const char*)(gbase) + (voff)[_i]), (LAS unsigned*)(lds + (bufoff) + ldsw + _i * 8192), 16, 0, 0); } while (0)
; #define PG8_LDA(dst, b, h) do { _Pragma("unroll") for (int m = 0; m < 4; ++m) _Pragma("unroll") for (int k = 0; k < 2; ++k) dst[m][k] = *(const LAS bf16x8*)(lds + PG8_SA(b, h) + aoff + m * 2048 + k * 1024); } while (0)
; #define PG8_LDB(dst, b, h) do { _Pragma("unroll") for (int n = 0; n < 2; ++n) _Pragma("unroll") for (int k = 0; k < 2; ++k) dst[n][k] = *(const LAS bf16x8*)(lds + PG8_SB(b, h) + boff + n * 2048 + k * 1024); } while (0)
; #define PG8_MMA(ai, bj, At, Bt) do { __builtin_amdgcn_s_setprio(1); _Pragma("unroll") for (int m = 0; m < 4; ++m) _Pragma("unroll") for (int n = 0; n < 2; ++n) _Pragma("unroll") for (int k = 0; k < 2; ++k) \
;         acc[ai][bj][m][n] = __builtin_amdgcn_mfma_f32_16x16x32_bf16(Bt[n][k], At[m][k], acc[ai][bj][m][n], 0, 0, 0); __builtin_amdgcn_s_setprio(0); } while (0)
; #define PG8_WAIT_V(n) asm volatile("s_waitcnt vmcnt(" #n ")" ::: "memory")
; #define PG8_WAIT_L(n) asm volatile("s_waitcnt lgkmcnt(" #n ")" ::: "memory")
; #define PG8_BAR __builtin_amdgcn_s_barrier()
; #define PG8_SCHED __builtin_amdgcn_sched_barrier(0)
; template <class Epi, class Sched>
; __device__ __forceinline__ void gemm_phase(LAS unsigned char* lds, const Gemm g, const Sched& S, const Epi& E) {
;     ...
;             PG8_WAIT_V(6); PG8_BAR; PG8_MMA(1, 1, At, B1); PG8_BAR;
;             PG8_LDB(B0, 1, 0); PG8_SCHED; PG8_LDA(At, 1, 0); PG8_STAGE(PG8_SA(0, 1), a2 + hstep, voffA);
;             PG8_WAIT_L(8); PG8_BAR; PG8_WAIT_L(0); PG8_MMA(0, 0, At, B0); PG8_BAR; PG8_SCHED;
;             PG8_LDB(B1, 1, 1); PG8_STAGE(PG8_SB(1, 0), b3, voffB);
;             PG8_BAR; PG8_WAIT_L(0); PG8_MMA(0, 1, At, B1); PG8_BAR;
;             PG8_LDA(At, 1, 1); PG8_STAGE(PG8_SA(1, 0), a3, voffA);
	v_mfma_f32_16x16x32_bf16 v[52:55], v[176:179], v[144:147], 0
	v_mfma_f32_16x16x32_bf16 v[48:51], v[184:187], v[144:147], 0
	v_mfma_f32_16x16x32_bf16 v[36:39], v[176:179], v[152:155], 0
	v_mfma_f32_16x16x32_bf16 v[32:35], v[184:187], v[152:155], 0
	v_mfma_f32_16x16x32_bf16 v[20:23], v[176:179], v[160:163], 0
	v_mfma_f32_16x16x32_bf16 v[16:19], v[184:187], v[160:163], 0
	v_mfma_f32_16x16x32_bf16 v[4:7], v[176:179], v[168:171], 0
	v_mfma_f32_16x16x32_bf16 v[0:3], v[184:187], v[168:171], 0
	v_mfma_f32_16x16x32_bf16 v[52:55], v[180:183], v[148:151], v[52:55]
	v_mfma_f32_16x16x32_bf16 v[48:51], v[188:191], v[148:151], v[48:51]
	v_mfma_f32_16x16x32_bf16 v[36:39], v[180:183], v[156:159], v[36:39]
	v_mfma_f32_16x16x32_bf16 v[32:35], v[188:191], v[156:159], v[32:35]
	v_mfma_f32_16x16x32_bf16 v[20:23], v[180:183], v[164:167], v[20:23]
	v_mfma_f32_16x16x32_bf16 v[16:19], v[188:191], v[164:167], v[16:19]
	v_mfma_f32_16x16x32_bf16 v[4:7], v[180:183], v[172:175], v[4:7]
	v_mfma_f32_16x16x32_bf16 v[0:3], v[188:191], v[172:175], v[0:3]
	s_setprio 0
	s_add_i32 s59, 0, 0x18000
	v_add_u32_e32 v140, s59, v236
	s_barrier
	ds_read_b128 v[128:131], v140
	ds_read_b128 v[132:135], v140 offset:1024
	ds_read_b128 v[136:139], v140 offset:2048
	ds_read_b128 v[140:143], v140 offset:3072
	ds_read_b128 v[144:147], v238 offset:32768
	ds_read_b128 v[148:151], v238 offset:33792
	ds_read_b128 v[152:155], v238 offset:34816
	ds_read_b128 v[156:159], v238 offset:35840
	ds_read_b128 v[160:163], v238 offset:36864
	ds_read_b128 v[164:167], v238 offset:37888
	ds_read_b128 v[168:171], v238 offset:38912
	ds_read_b128 v[172:175], v238 offset:39936
	s_waitcnt lgkmcnt(8)
	s_waitcnt vmcnt(8)
	s_setprio 1
	s_barrier
	s_waitcnt lgkmcnt(0)
	v_mfma_f32_16x16x32_bf16 v[124:127], v[128:131], v[144:147], v[124:127]
	v_mfma_f32_16x16x32_bf16 v[120:123], v[136:139], v[144:147], v[120:123]
	v_mfma_f32_16x16x32_bf16 v[108:111], v[128:131], v[152:155], v[108:111]
	v_mfma_f32_16x16x32_bf16 v[104:107], v[136:139], v[152:155], v[104:107]
	v_mfma_f32_16x16x32_bf16 v[92:95], v[128:131], v[160:163], v[92:95]
	v_mfma_f32_16x16x32_bf16 v[88:91], v[136:139], v[160:163], v[88:91]
	v_mfma_f32_16x16x32_bf16 v[76:79], v[128:131], v[168:171], v[76:79]
	v_mfma_f32_16x16x32_bf16 v[72:75], v[136:139], v[168:171], v[72:75]
	v_mfma_f32_16x16x32_bf16 v[124:127], v[132:135], v[148:151], v[124:127]
	v_mfma_f32_16x16x32_bf16 v[120:123], v[140:143], v[148:151], v[120:123]
	v_mfma_f32_16x16x32_bf16 v[108:111], v[132:135], v[156:159], v[108:111]
	v_mfma_f32_16x16x32_bf16 v[104:107], v[140:143], v[156:159], v[104:107]
	v_mfma_f32_16x16x32_bf16 v[92:95], v[132:135], v[164:167], v[92:95]
	v_mfma_f32_16x16x32_bf16 v[88:91], v[140:143], v[164:167], v[88:91]
	v_mfma_f32_16x16x32_bf16 v[76:79], v[132:135], v[172:175], v[76:79]
	v_mfma_f32_16x16x32_bf16 v[72:75], v[140:143], v[172:175], v[72:75]
	s_setprio 0
	s_barrier
	s_add_i32 s30, 0, 0x1c000
	s_add_i32 s24, s59, s37
	v_add_u32_e32 v188, s30, v236
	s_add_u32 s0, s28, 0x80
	s_addc_u32 s1, s29, 0
	s_mov_b32 m0, s24
	ds_read_b128 v[176:179], v188
	ds_read_b128 v[180:183], v188 offset:1024
	ds_read_b128 v[184:187], v188 offset:2048
	ds_read_b128 v[188:191], v188 offset:3072
	global_load_lds_dwordx4 v204, s[0:1]
	s_add_i32 m0, s24, 0x2000
	s_nop 0
	global_load_lds_dwordx4 v208, s[0:1]
	s_waitcnt vmcnt(8)
	s_setprio 1
	s_barrier
	s_waitcnt lgkmcnt(0)
	v_mfma_f32_16x16x32_bf16 v[116:119], v[176:179], v[144:147], v[116:119]
	v_mfma_f32_16x16x32_bf16 v[112:115], v[184:187], v[144:147], v[112:115]
	v_mfma_f32_16x16x32_bf16 v[100:103], v[176:179], v[152:155], v[100:103]
	v_mfma_f32_16x16x32_bf16 v[96:99], v[184:187], v[152:155], v[96:99]
	v_mfma_f32_16x16x32_bf16 v[84:87], v[176:179], v[160:163], v[84:87]
	v_mfma_f32_16x16x32_bf16 v[80:83], v[184:187], v[160:163], v[80:83]
	v_mfma_f32_16x16x32_bf16 v[68:71], v[176:179], v[168:171], v[68:71]
	v_mfma_f32_16x16x32_bf16 v[64:67], v[184:187], v[168:171], v[64:67]
	v_mfma_f32_16x16x32_bf16 v[116:119], v[180:183], v[148:151], v[116:119]
	v_mfma_f32_16x16x32_bf16 v[112:115], v[188:191], v[148:151], v[112:115]
	v_mfma_f32_16x16x32_bf16 v[100:103], v[180:183], v[156:159], v[100:103]
	v_mfma_f32_16x16x32_bf16 v[96:99], v[188:191], v[156:159], v[96:99]
	v_mfma_f32_16x16x32_bf16 v[84:87], v[180:183], v[164:167], v[84:87]
	v_mfma_f32_16x16x32_bf16 v[80:83], v[188:191], v[164:167], v[80:83]
	v_mfma_f32_16x16x32_bf16 v[68:71], v[180:183], v[172:175], v[68:71]
	v_mfma_f32_16x16x32_bf16 v[64:67], v[188:191], v[172:175], v[64:67]
	s_setprio 0
	s_mov_b32 m0, s47
	s_mov_b64 s[0:1], 0x80
	v_lshl_add_u64 v[192:193], v[196:197], 0, s[0:1]
	s_barrier
	ds_read_b128 v[144:147], v238 offset:49152
	ds_read_b128 v[148:151], v238 offset:50176
	ds_read_b128 v[152:155], v238 offset:51200
	ds_read_b128 v[156:159], v238 offset:52224
	ds_read_b128 v[160:163], v238 offset:53248
	ds_read_b128 v[164:167], v238 offset:54272
	ds_read_b128 v[168:171], v238 offset:55296
	ds_read_b128 v[172:175], v238 offset:56320
	global_load_lds_dwordx4 v[192:193], off
	v_lshl_add_u64 v[192:193], v[198:199], 0, s[0:1]
	s_mov_b32 m0, s48
	s_nop 0
	global_load_lds_dwordx4 v[192:193], off
	s_setprio 1
	s_barrier
; #define PG8_STAGE(bufoff, gbase, voff) do { _Pragma("unroll") for (int _i = 0; _i < 2; ++_i) \
;         __builtin_amdgcn_global_load_lds((const unsigned*)((const char*)(gbase) + (voff)[_i]), (LAS unsigned*)(lds + (bufoff) + ldsw + _i * 8192), 16, 0, 0); } while (0)
; #define PG8_LDA(dst, b, h) do { _Pragma("unroll") for (int m = 0; m < 4; ++m) _Pragma("unroll") for (int k = 0; k < 2; ++k) dst[m][k] = *(const LAS bf16x8*)(lds + PG8_SA(b, h) + aoff + m * 2048 + k * 1024); } while (0)
; #define PG8_LDB(dst, b, h) do { _Pragma("unroll") for (int n = 0; n < 2; ++n) _Pragma("unroll") for (int k = 0; k < 2; ++k) dst[n][k] = *(const LAS bf16x8*)(lds + PG8_SB(b, h) + boff + n * 2048 + k * 1024); } while (0)
; #define PG8_WAIT_V(n) asm volatile("s_waitcnt vmcnt(" #n ")" ::: "memory")
; #define PG8_WAIT_L(n) asm volatile("s_waitcnt lgkmcnt(" #n ")" ::: "memory")
; #define PG8_BAR __builtin_amdgcn_s_barrier()
; #define PG8_SCHED __builtin_amdgcn_sched_barrier(0)
; template <class Epi, class Sched>
; __device__ __forceinline__ void gemm_phase(LAS unsigned char* lds, const Gemm g, const Sched& S, const Epi& E) {
;     ...
;             PG8_LDB(B0, 0, 0); PG8_SCHED; PG8_LDA(At, 0, 0); PG8_STAGE(PG8_SA(1, 1), a1 + hstep, voffA);
;             PG8_WAIT_L(8); PG8_BAR; PG8_WAIT_L(0); PG8_MMA(0, 0, At, B0); PG8_BAR; PG8_SCHED;
;             PG8_LDB(B1, 0, 1); PG8_STAGE(PG8_SB(0, 0), b2, voffB);
;             PG8_BAR; PG8_WAIT_L(0); PG8_MMA(0, 1, At, B1); PG8_BAR;
;             PG8_LDA(At, 0, 1); PG8_STAGE(PG8_SA(0, 0), a2, voffA);
;             PG8_BAR; PG8_WAIT_L(0); PG8_MMA(1, 0, At, B0); PG8_BAR; PG8_SCHED;
;             PG8_STAGE(PG8_SB(0, 1), b2 + hstep, voffB);
;             PG8_WAIT_V(6); PG8_BAR; PG8_MMA(1, 1, At, B1); PG8_BAR;
;             PG8_LDB(B0, 1, 0); PG8_SCHED; PG8_LDA(At, 1, 0); PG8_STAGE(PG8_SA(0, 1), a2 + hstep, voffA);
;             PG8_WAIT_L(8); PG8_BAR; PG8_WAIT_L(0); PG8_MMA(0, 0, At, B0); PG8_BAR; PG8_SCHED;
;             PG8_LDB(B1, 1, 1); PG8_STAGE(PG8_SB(1, 0), b3, voffB);
;             PG8_BAR; PG8_WAIT_L(0); PG8_MMA(0, 1, At, B1); PG8_BAR;
;             PG8_LDA(At, 1, 1); PG8_STAGE(PG8_SA(1, 0), a3, voffA);
;             PG8_BAR; PG8_WAIT_L(0); PG8_MMA(1, 0, At, B0); PG8_BAR; PG8_SCHED;
;             PG8_STAGE(PG8_SB(1, 1), b3 + hstep, voffB);
;             PG8_WAIT_V(6); PG8_BAR; PG8_MMA(1, 1, At, B1); PG8_BAR;
	s_waitcnt lgkmcnt(0)
	v_mfma_f32_16x16x32_bf16 v[60:63], v[128:131], v[144:147], v[60:63]
	v_mfma_f32_16x16x32_bf16 v[56:59], v[136:139], v[144:147], v[56:59]
	v_mfma_f32_16x16x32_bf16 v[44:47], v[128:131], v[152:155], v[44:47]
	v_mfma_f32_16x16x32_bf16 v[40:43], v[136:139], v[152:155], v[40:43]
	v_mfma_f32_16x16x32_bf16 v[28:31], v[128:131], v[160:163], v[28:31]
	v_mfma_f32_16x16x32_bf16 v[24:27], v[136:139], v[160:163], v[24:27]
	v_mfma_f32_16x16x32_bf16 v[12:15], v[128:131], v[168:171], v[12:15]
	v_mfma_f32_16x16x32_bf16 v[8:11], v[136:139], v[168:171], v[8:11]
	v_mfma_f32_16x16x32_bf16 v[60:63], v[132:135], v[148:151], v[60:63]
	v_mfma_f32_16x16x32_bf16 v[56:59], v[140:143], v[148:151], v[56:59]
	v_mfma_f32_16x16x32_bf16 v[44:47], v[132:135], v[156:159], v[44:47]
	v_mfma_f32_16x16x32_bf16 v[40:43], v[140:143], v[156:159], v[40:43]
	v_mfma_f32_16x16x32_bf16 v[28:31], v[132:135], v[164:167], v[28:31]
	v_mfma_f32_16x16x32_bf16 v[24:27], v[140:143], v[164:167], v[24:27]
	v_mfma_f32_16x16x32_bf16 v[12:15], v[132:135], v[172:175], v[12:15]
	v_mfma_f32_16x16x32_bf16 v[8:11], v[140:143], v[172:175], v[8:11]
	s_setprio 0
	s_barrier
	s_add_u32 s24, s28, 0x60080
	s_addc_u32 s25, s29, 0
	s_add_i32 s28, s30, s37
	s_mov_b32 m0, s28
	s_nop 0
	global_load_lds_dwordx4 v204, s[24:25]
	s_add_i32 m0, s28, 0x2000
	s_nop 0
	global_load_lds_dwordx4 v208, s[24:25]
	s_waitcnt vmcnt(8)
	s_setprio 1
	s_barrier
	v_mfma_f32_16x16x32_bf16 v[52:55], v[176:179], v[144:147], v[52:55]
	v_mfma_f32_16x16x32_bf16 v[48:51], v[184:187], v[144:147], v[48:51]
	v_mfma_f32_16x16x32_bf16 v[36:39], v[176:179], v[152:155], v[36:39]
	v_mfma_f32_16x16x32_bf16 v[32:35], v[184:187], v[152:155], v[32:35]
	v_mfma_f32_16x16x32_bf16 v[20:23], v[176:179], v[160:163], v[20:23]
	v_mfma_f32_16x16x32_bf16 v[16:19], v[184:187], v[160:163], v[16:19]
	v_mfma_f32_16x16x32_bf16 v[4:7], v[176:179], v[168:171], v[4:7]
	v_mfma_f32_16x16x32_bf16 v[0:3], v[184:187], v[168:171], v[0:3]
	v_mfma_f32_16x16x32_bf16 v[52:55], v[180:183], v[148:151], v[52:55]
	v_mfma_f32_16x16x32_bf16 v[48:51], v[188:191], v[148:151], v[48:51]
	v_mfma_f32_16x16x32_bf16 v[36:39], v[180:183], v[156:159], v[36:39]
	v_mfma_f32_16x16x32_bf16 v[32:35], v[188:191], v[156:159], v[32:35]
	v_mfma_f32_16x16x32_bf16 v[20:23], v[180:183], v[164:167], v[20:23]
	v_mfma_f32_16x16x32_bf16 v[16:19], v[188:191], v[164:167], v[16:19]
	v_mfma_f32_16x16x32_bf16 v[4:7], v[180:183], v[172:175], v[4:7]
	v_mfma_f32_16x16x32_bf16 v[0:3], v[188:191], v[172:175], v[0:3]
	s_setprio 0
	s_add_i32 s58, s58, 2
	s_add_u32 s56, s56, 0x100
	s_addc_u32 s57, s57, 0
	s_cmp_gt_u32 s58, 21
	s_mov_b64 s[24:25], s[26:27]
	s_barrier
.LBB0_902:
	ds_read_b128 v[128:131], v237
	ds_read_b128 v[132:135], v237 offset:1024
	ds_read_b128 v[136:139], v237 offset:2048
	ds_read_b128 v[140:143], v237 offset:3072
	s_add_u32 s26, s24, 0x100
	s_addc_u32 s27, s25, 0
	s_cmp_eq_u32 s58, 20
	s_cselect_b32 s31, s5, s27
	s_cselect_b32 s30, s4, s26
	s_cselect_b32 s29, s7, s57
	s_cselect_b32 s28, s6, s56
	v_lshl_add_u64 v[176:177], s[24:25], 0, v[210:211]
	s_add_i32 m0, s38, 0xc000
	ds_read_b128 v[144:147], v238
	ds_read_b128 v[148:151], v238 offset:1024
	ds_read_b128 v[152:155], v238 offset:2048
	ds_read_b128 v[156:159], v238 offset:3072
	ds_read_b128 v[160:163], v238 offset:4096
	ds_read_b128 v[164:167], v238 offset:5120
	ds_read_b128 v[168:171], v238 offset:6144
	ds_read_b128 v[172:175], v238 offset:7168
	global_load_lds_dwordx4 v[176:177], off
	v_lshl_add_u64 v[176:177], s[24:25], 0, v[212:213]
	s_add_i32 m0, s38, 0xe000
	s_nop 0
	global_load_lds_dwordx4 v[176:177], off
	s_waitcnt lgkmcnt(8)
	s_waitcnt vmcnt(8)
	s_setprio 1
	s_barrier
	s_waitcnt lgkmcnt(0)
	v_mfma_f32_16x16x32_bf16 v[124:127], v[128:131], v[144:147], v[124:127]
	v_mfma_f32_16x16x32_bf16 v[120:123], v[136:139], v[144:147], v[120:123]
	v_mfma_f32_16x16x32_bf16 v[108:111], v[128:131], v[152:155], v[108:111]
	v_mfma_f32_16x16x32_bf16 v[104:107], v[136:139], v[152:155], v[104:107]
	v_mfma_f32_16x16x32_bf16 v[92:95], v[128:131], v[160:163], v[92:95]
	v_mfma_f32_16x16x32_bf16 v[88:91], v[136:139], v[160:163], v[88:91]
	v_mfma_f32_16x16x32_bf16 v[76:79], v[128:131], v[168:171], v[76:79]
	v_mfma_f32_16x16x32_bf16 v[72:75], v[136:139], v[168:171], v[72:75]
	v_mfma_f32_16x16x32_bf16 v[124:127], v[132:135], v[148:151], v[124:127]
	v_mfma_f32_16x16x32_bf16 v[120:123], v[140:143], v[148:151], v[120:123]
	v_mfma_f32_16x16x32_bf16 v[108:111], v[132:135], v[156:159], v[108:111]
	v_mfma_f32_16x16x32_bf16 v[104:107], v[140:143], v[156:159], v[104:107]
	v_mfma_f32_16x16x32_bf16 v[92:95], v[132:135], v[164:167], v[92:95]
	v_mfma_f32_16x16x32_bf16 v[88:91], v[140:143], v[164:167], v[88:91]
	v_mfma_f32_16x16x32_bf16 v[76:79], v[132:135], v[172:175], v[76:79]
	v_mfma_f32_16x16x32_bf16 v[72:75], v[140:143], v[172:175], v[72:75]
	s_setprio 0
	s_barrier
	s_add_i32 s24, s50, s37
	s_mov_b32 m0, s24
	ds_read_b128 v[176:179], v239
	ds_read_b128 v[180:183], v239 offset:1024
	ds_read_b128 v[184:187], v239 offset:2048
	ds_read_b128 v[188:191], v239 offset:3072
	global_load_lds_dwordx4 v204, s[28:29]
	s_add_i32 m0, s24, 0x2000
	s_nop 0
	global_load_lds_dwordx4 v208, s[28:29]
	s_waitcnt vmcnt(8)
	s_setprio 1
	s_barrier
; #define PG8_STAGE(bufoff, gbase, voff) do { _Pragma("unroll") for (int _i = 0; _i < 2; ++_i) \
;         __builtin_amdgcn_global_load_lds((const unsigned*)((const char*)(gbase) + (voff)[_i]), (LAS unsigned*)(lds + (bufoff) + ldsw + _i * 8192), 16, 0, 0); } while (0)
; #define PG8_LDA(dst, b, h) do { _Pragma("unroll") for (int m = 0; m < 4; ++m) _Pragma("unroll") for (int k = 0; k < 2; ++k) dst[m][k] = *(const LAS bf16x8*)(lds + PG8_SA(b, h) + aoff + m * 2048 + k * 1024); } while (0)
; #define PG8_LDB(dst, b, h) do { _Pragma("unroll") for (int n = 0; n < 2; ++n) _Pragma("unroll") for (int k = 0; k < 2; ++k) dst[n][k] = *(const LAS bf16x8*)(lds + PG8_SB(b, h) + boff + n * 2048 + k * 1024); } while (0)
; #define PG8_MMA(ai, bj, At, Bt) do { __builtin_amdgcn_s_setprio(1); _Pragma("unroll") for (int m = 0; m < 4; ++m) _Pragma("unroll") for (int n = 0; n < 2; ++n) _Pragma("unroll") for (int k = 0; k < 2; ++k) \
;         acc[ai][bj][m][n] = __builtin_amdgcn_mfma_f32_16x16x32_bf16(Bt[n][k], At[m][k], acc[ai][bj][m][n], 0, 0, 0); __builtin_amdgcn_s_setprio(0); } while (0)
; #define PG8_WAIT_V(n) asm volatile("s_waitcnt vmcnt(" #n ")" ::: "memory")
; #define PG8_WAIT_L(n) asm volatile("s_waitcnt lgkmcnt(" #n ")" ::: "memory")
; #define PG8_BAR __builtin_amdgcn_s_barrier()
; #define PG8_SCHED __builtin_amdgcn_sched_barrier(0)
; template <class Epi, class Sched>
; __device__ __forceinline__ void gemm_phase(LAS unsigned char* lds, const Gemm g, const Sched& S, const Epi& E) {
;     ...
;             PG8_BAR; PG8_WAIT_L(0); PG8_MMA(0, 1, At, B1); PG8_BAR;
;             PG8_LDA(At, 0, 1); PG8_STAGE(PG8_SA(0, 0), a2, voffA);
;             PG8_BAR; PG8_WAIT_L(0); PG8_MMA(1, 0, At, B0); PG8_BAR; PG8_SCHED;
;             PG8_STAGE(PG8_SB(0, 1), b2 + hstep, voffB);
;             PG8_WAIT_V(6); PG8_BAR; PG8_MMA(1, 1, At, B1); PG8_BAR;
;             PG8_LDB(B0, 1, 0); PG8_SCHED; PG8_LDA(At, 1, 0); PG8_STAGE(PG8_SA(0, 1), a2 + hstep, voffA);
;             PG8_WAIT_L(8); PG8_BAR; PG8_WAIT_L(0); PG8_MMA(0, 0, At, B0); PG8_BAR; PG8_SCHED;
	s_waitcnt lgkmcnt(0)
	v_mfma_f32_16x16x32_bf16 v[116:119], v[176:179], v[144:147], v[116:119]
	v_mfma_f32_16x16x32_bf16 v[112:115], v[184:187], v[144:147], v[112:115]
	v_mfma_f32_16x16x32_bf16 v[100:103], v[176:179], v[152:155], v[100:103]
	v_mfma_f32_16x16x32_bf16 v[96:99], v[184:187], v[152:155], v[96:99]
	v_mfma_f32_16x16x32_bf16 v[84:87], v[176:179], v[160:163], v[84:87]
	v_mfma_f32_16x16x32_bf16 v[80:83], v[184:187], v[160:163], v[80:83]
	v_mfma_f32_16x16x32_bf16 v[68:71], v[176:179], v[168:171], v[68:71]
	v_mfma_f32_16x16x32_bf16 v[64:67], v[184:187], v[168:171], v[64:67]
	v_mfma_f32_16x16x32_bf16 v[116:119], v[180:183], v[148:151], v[116:119]
	v_mfma_f32_16x16x32_bf16 v[112:115], v[188:191], v[148:151], v[112:115]
	v_mfma_f32_16x16x32_bf16 v[100:103], v[180:183], v[156:159], v[100:103]
	v_mfma_f32_16x16x32_bf16 v[96:99], v[188:191], v[156:159], v[96:99]
	v_mfma_f32_16x16x32_bf16 v[84:87], v[180:183], v[164:167], v[84:87]
	v_mfma_f32_16x16x32_bf16 v[80:83], v[188:191], v[164:167], v[80:83]
	v_mfma_f32_16x16x32_bf16 v[68:71], v[180:183], v[172:175], v[68:71]
	v_mfma_f32_16x16x32_bf16 v[64:67], v[188:191], v[172:175], v[64:67]
	s_setprio 0
	s_mov_b32 m0, s38
	v_lshl_add_u64 v[196:197], s[30:31], 0, v[202:203]
	s_barrier
	ds_read_b128 v[144:147], v238 offset:16384
	ds_read_b128 v[148:151], v238 offset:17408
	ds_read_b128 v[152:155], v238 offset:18432
	ds_read_b128 v[156:159], v238 offset:19456
	ds_read_b128 v[160:163], v238 offset:20480
	ds_read_b128 v[164:167], v238 offset:21504
	ds_read_b128 v[168:171], v238 offset:22528
	ds_read_b128 v[172:175], v238 offset:23552
	global_load_lds_dwordx4 v202, s[30:31]
	v_lshl_add_u64 v[198:199], s[30:31], 0, v[206:207]
	s_mov_b32 m0, s39
	s_nop 0
	global_load_lds_dwordx4 v206, s[30:31]
	s_setprio 1
	s_barrier
	s_waitcnt lgkmcnt(0)
	v_mfma_f32_16x16x32_bf16 v[60:63], v[128:131], v[144:147], v[60:63]
	v_mfma_f32_16x16x32_bf16 v[56:59], v[136:139], v[144:147], v[56:59]
	v_mfma_f32_16x16x32_bf16 v[44:47], v[128:131], v[152:155], v[44:47]
	v_mfma_f32_16x16x32_bf16 v[40:43], v[136:139], v[152:155], v[40:43]
	v_mfma_f32_16x16x32_bf16 v[28:31], v[128:131], v[160:163], v[28:31]
	v_mfma_f32_16x16x32_bf16 v[24:27], v[136:139], v[160:163], v[24:27]
	v_mfma_f32_16x16x32_bf16 v[12:15], v[128:131], v[168:171], v[12:15]
	v_mfma_f32_16x16x32_bf16 v[8:11], v[136:139], v[168:171], v[8:11]
	v_mfma_f32_16x16x32_bf16 v[60:63], v[132:135], v[148:151], v[60:63]
	v_mfma_f32_16x16x32_bf16 v[56:59], v[140:143], v[148:151], v[56:59]
	v_mfma_f32_16x16x32_bf16 v[44:47], v[132:135], v[156:159], v[44:47]
	v_mfma_f32_16x16x32_bf16 v[40:43], v[140:143], v[156:159], v[40:43]
	v_mfma_f32_16x16x32_bf16 v[28:31], v[132:135], v[164:167], v[28:31]
	v_mfma_f32_16x16x32_bf16 v[24:27], v[140:143], v[164:167], v[24:27]
	v_mfma_f32_16x16x32_bf16 v[12:15], v[132:135], v[172:175], v[12:15]
	v_mfma_f32_16x16x32_bf16 v[8:11], v[140:143], v[172:175], v[8:11]
	s_setprio 0
	s_barrier
	s_add_u32 s24, s28, 0x60000
	s_addc_u32 s25, s29, 0
	s_add_i32 s59, s51, s37
	s_mov_b32 m0, s59
	s_nop 0
	global_load_lds_dwordx4 v204, s[24:25]
	s_add_i32 m0, s59, 0x2000
	s_nop 0
	global_load_lds_dwordx4 v208, s[24:25]
	s_add_u32 s24, s30, 0x60000
	s_addc_u32 s25, s31, 0
	s_mov_b32 m0, s40
	s_nop 0
	global_load_lds_dwordx4 v202, s[24:25]
	s_mov_b32 m0, s41
	s_nop 0
	global_load_lds_dwordx4 v206, s[24:25]
	s_waitcnt vmcnt(10)
	s_setprio 1
	s_barrier
	v_mfma_f32_16x16x32_bf16 v[52:55], v[176:179], v[144:147], v[52:55]
	v_mfma_f32_16x16x32_bf16 v[48:51], v[184:187], v[144:147], v[48:51]
	v_mfma_f32_16x16x32_bf16 v[36:39], v[176:179], v[152:155], v[36:39]
	v_mfma_f32_16x16x32_bf16 v[32:35], v[184:187], v[152:155], v[32:35]
	v_mfma_f32_16x16x32_bf16 v[20:23], v[176:179], v[160:163], v[20:23]
	v_mfma_f32_16x16x32_bf16 v[16:19], v[184:187], v[160:163], v[16:19]
	v_mfma_f32_16x16x32_bf16 v[4:7], v[176:179], v[168:171], v[4:7]
	v_mfma_f32_16x16x32_bf16 v[0:3], v[184:187], v[168:171], v[0:3]
	v_mfma_f32_16x16x32_bf16 v[52:55], v[180:183], v[148:151], v[52:55]
	v_mfma_f32_16x16x32_bf16 v[48:51], v[188:191], v[148:151], v[48:51]
	v_mfma_f32_16x16x32_bf16 v[36:39], v[180:183], v[156:159], v[36:39]
	v_mfma_f32_16x16x32_bf16 v[32:35], v[188:191], v[156:159], v[32:35]
	v_mfma_f32_16x16x32_bf16 v[20:23], v[180:183], v[164:167], v[20:23]
	v_mfma_f32_16x16x32_bf16 v[16:19], v[188:191], v[164:167], v[16:19]
	v_mfma_f32_16x16x32_bf16 v[4:7], v[180:183], v[172:175], v[4:7]
	v_mfma_f32_16x16x32_bf16 v[0:3], v[188:191], v[172:175], v[0:3]
	s_setprio 0
	s_add_i32 s59, 0, 0x18000
	v_add_u32_e32 v140, s59, v236
	s_barrier
	ds_read_b128 v[128:131], v140
	ds_read_b128 v[132:135], v140 offset:1024
	ds_read_b128 v[136:139], v140 offset:2048
	ds_read_b128 v[140:143], v140 offset:3072
	ds_read_b128 v[144:147], v238 offset:32768
	ds_read_b128 v[148:151], v238 offset:33792
	ds_read_b128 v[152:155], v238 offset:34816
	ds_read_b128 v[156:159], v238 offset:35840
	ds_read_b128 v[160:163], v238 offset:36864
	ds_read_b128 v[164:167], v238 offset:37888
	ds_read_b128 v[168:171], v238 offset:38912
	ds_read_b128 v[172:175], v238 offset:39936
	s_waitcnt lgkmcnt(8)
	s_waitcnt vmcnt(8)
	s_setprio 1
	s_barrier
; #define PG8_STAGE(bufoff, gbase, voff) do { _Pragma("unroll") for (int _i = 0; _i < 2; ++_i) \
;         __builtin_amdgcn_global_load_lds((const unsigned*)((const char*)(gbase) + (voff)[_i]), (LAS unsigned*)(lds + (bufoff) + ldsw + _i * 8192), 16, 0, 0); } while (0)
; #define PG8_LDA(dst, b, h) do { _Pragma("unroll") for (int m = 0; m < 4; ++m) _Pragma("unroll") for (int k = 0; k < 2; ++k) dst[m][k] = *(const LAS bf16x8*)(lds + PG8_SA(b, h) + aoff + m * 2048 + k * 1024); } while (0)
; #define PG8_LDB(dst, b, h) do { _Pragma("unroll") for (int n = 0; n < 2; ++n) _Pragma("unroll") for (int k = 0; k < 2; ++k) dst[n][k] = *(const LAS bf16x8*)(lds + PG8_SB(b, h) + boff + n * 2048 + k * 1024); } while (0)
; #define PG8_MMA(ai, bj, At, Bt) do { __builtin_amdgcn_s_setprio(1); _Pragma("unroll") for (int m = 0; m < 4; ++m) _Pragma("unroll") for (int n = 0; n < 2; ++n) _Pragma("unroll") for (int k = 0; k < 2; ++k) \
;         acc[ai][bj][m][n] = __builtin_amdgcn_mfma_f32_16x16x32_bf16(Bt[n][k], At[m][k], acc[ai][bj][m][n], 0, 0, 0); __builtin_amdgcn_s_setprio(0); } while (0)
; #define PG8_WAIT_V(n) asm volatile("s_waitcnt vmcnt(" #n ")" ::: "memory")
; #define PG8_WAIT_L(n) asm volatile("s_waitcnt lgkmcnt(" #n ")" ::: "memory")
; #define PG8_BAR __builtin_amdgcn_s_barrier()
; #define PG8_SCHED __builtin_amdgcn_sched_barrier(0)
; template <class Epi, class Sched>
; __device__ __forceinline__ void gemm_phase(LAS unsigned char* lds, const Gemm g, const Sched& S, const Epi& E) {
;     ...
;             PG8_WAIT_L(8); PG8_BAR; PG8_WAIT_L(0); PG8_MMA(0, 0, At, B0); PG8_BAR; PG8_SCHED;
;             PG8_LDB(B1, 1, 1); PG8_STAGE(PG8_SB(1, 0), b3, voffB);
;             PG8_BAR; PG8_WAIT_L(0); PG8_MMA(0, 1, At, B1); PG8_BAR;
;             PG8_LDA(At, 1, 1); PG8_STAGE(PG8_SA(1, 0), a3, voffA);
;             PG8_BAR; PG8_WAIT_L(0); PG8_MMA(1, 0, At, B0); PG8_BAR; PG8_SCHED;
;             PG8_STAGE(PG8_SB(1, 1), b3 + hstep, voffB);
;             PG8_WAIT_V(6); PG8_BAR; PG8_MMA(1, 1, At, B1); PG8_BAR;
	s_waitcnt lgkmcnt(0)
	v_mfma_f32_16x16x32_bf16 v[124:127], v[128:131], v[144:147], v[124:127]
	v_mfma_f32_16x16x32_bf16 v[120:123], v[136:139], v[144:147], v[120:123]
	v_mfma_f32_16x16x32_bf16 v[108:111], v[128:131], v[152:155], v[108:111]
	v_mfma_f32_16x16x32_bf16 v[104:107], v[136:139], v[152:155], v[104:107]
	v_mfma_f32_16x16x32_bf16 v[92:95], v[128:131], v[160:163], v[92:95]
	v_mfma_f32_16x16x32_bf16 v[88:91], v[136:139], v[160:163], v[88:91]
	v_mfma_f32_16x16x32_bf16 v[76:79], v[128:131], v[168:171], v[76:79]
	v_mfma_f32_16x16x32_bf16 v[72:75], v[136:139], v[168:171], v[72:75]
	v_mfma_f32_16x16x32_bf16 v[124:127], v[132:135], v[148:151], v[124:127]
	v_mfma_f32_16x16x32_bf16 v[120:123], v[140:143], v[148:151], v[120:123]
	v_mfma_f32_16x16x32_bf16 v[108:111], v[132:135], v[156:159], v[108:111]
	v_mfma_f32_16x16x32_bf16 v[104:107], v[140:143], v[156:159], v[104:107]
	v_mfma_f32_16x16x32_bf16 v[92:95], v[132:135], v[164:167], v[92:95]
	v_mfma_f32_16x16x32_bf16 v[88:91], v[140:143], v[164:167], v[88:91]
	v_mfma_f32_16x16x32_bf16 v[76:79], v[132:135], v[172:175], v[76:79]
	v_mfma_f32_16x16x32_bf16 v[72:75], v[140:143], v[172:175], v[72:75]
	s_setprio 0
	s_barrier
	s_add_i32 s30, 0, 0x1c000
	s_add_i32 s24, s59, s37
	v_add_u32_e32 v188, s30, v236
	s_add_u32 s0, s28, 0x80
	s_addc_u32 s1, s29, 0
	s_mov_b32 m0, s24
	ds_read_b128 v[176:179], v188
	ds_read_b128 v[180:183], v188 offset:1024
	ds_read_b128 v[184:187], v188 offset:2048
	ds_read_b128 v[188:191], v188 offset:3072
	global_load_lds_dwordx4 v204, s[0:1]
	s_add_i32 m0, s24, 0x2000
	s_nop 0
	global_load_lds_dwordx4 v208, s[0:1]
	s_waitcnt vmcnt(8)
	s_setprio 1
	s_barrier
	s_waitcnt lgkmcnt(0)
	v_mfma_f32_16x16x32_bf16 v[116:119], v[176:179], v[144:147], v[116:119]
	v_mfma_f32_16x16x32_bf16 v[112:115], v[184:187], v[144:147], v[112:115]
	v_mfma_f32_16x16x32_bf16 v[100:103], v[176:179], v[152:155], v[100:103]
	v_mfma_f32_16x16x32_bf16 v[96:99], v[184:187], v[152:155], v[96:99]
	v_mfma_f32_16x16x32_bf16 v[84:87], v[176:179], v[160:163], v[84:87]
	v_mfma_f32_16x16x32_bf16 v[80:83], v[184:187], v[160:163], v[80:83]
	v_mfma_f32_16x16x32_bf16 v[68:71], v[176:179], v[168:171], v[68:71]
	v_mfma_f32_16x16x32_bf16 v[64:67], v[184:187], v[168:171], v[64:67]
	v_mfma_f32_16x16x32_bf16 v[116:119], v[180:183], v[148:151], v[116:119]
	v_mfma_f32_16x16x32_bf16 v[112:115], v[188:191], v[148:151], v[112:115]
	v_mfma_f32_16x16x32_bf16 v[100:103], v[180:183], v[156:159], v[100:103]
	v_mfma_f32_16x16x32_bf16 v[96:99], v[188:191], v[156:159], v[96:99]
	v_mfma_f32_16x16x32_bf16 v[84:87], v[180:183], v[164:167], v[84:87]
	v_mfma_f32_16x16x32_bf16 v[80:83], v[188:191], v[164:167], v[80:83]
	v_mfma_f32_16x16x32_bf16 v[68:71], v[180:183], v[172:175], v[68:71]
	v_mfma_f32_16x16x32_bf16 v[64:67], v[188:191], v[172:175], v[64:67]
	s_setprio 0
	s_mov_b32 m0, s47
	s_mov_b64 s[0:1], 0x80
	v_lshl_add_u64 v[192:193], v[196:197], 0, s[0:1]
	s_barrier
	ds_read_b128 v[144:147], v238 offset:49152
	ds_read_b128 v[148:151], v238 offset:50176
	ds_read_b128 v[152:155], v238 offset:51200
	ds_read_b128 v[156:159], v238 offset:52224
	ds_read_b128 v[160:163], v238 offset:53248
	ds_read_b128 v[164:167], v238 offset:54272
	ds_read_b128 v[168:171], v238 offset:55296
	ds_read_b128 v[172:175], v238 offset:56320
	global_load_lds_dwordx4 v[192:193], off
	v_lshl_add_u64 v[192:193], v[198:199], 0, s[0:1]
	s_mov_b32 m0, s48
	s_nop 0
	global_load_lds_dwordx4 v[192:193], off
	s_setprio 1
	s_barrier
	s_waitcnt lgkmcnt(0)
	v_mfma_f32_16x16x32_bf16 v[60:63], v[128:131], v[144:147], v[60:63]
	v_mfma_f32_16x16x32_bf16 v[56:59], v[136:139], v[144:147], v[56:59]
	v_mfma_f32_16x16x32_bf16 v[44:47], v[128:131], v[152:155], v[44:47]
	v_mfma_f32_16x16x32_bf16 v[40:43], v[136:139], v[152:155], v[40:43]
	v_mfma_f32_16x16x32_bf16 v[28:31], v[128:131], v[160:163], v[28:31]
	v_mfma_f32_16x16x32_bf16 v[24:27], v[136:139], v[160:163], v[24:27]
	v_mfma_f32_16x16x32_bf16 v[12:15], v[128:131], v[168:171], v[12:15]
	v_mfma_f32_16x16x32_bf16 v[8:11], v[136:139], v[168:171], v[8:11]
	v_mfma_f32_16x16x32_bf16 v[60:63], v[132:135], v[148:151], v[60:63]
	v_mfma_f32_16x16x32_bf16 v[56:59], v[140:143], v[148:151], v[56:59]
	v_mfma_f32_16x16x32_bf16 v[44:47], v[132:135], v[156:159], v[44:47]
	v_mfma_f32_16x16x32_bf16 v[40:43], v[140:143], v[156:159], v[40:43]
	v_mfma_f32_16x16x32_bf16 v[28:31], v[132:135], v[164:167], v[28:31]
	v_mfma_f32_16x16x32_bf16 v[24:27], v[140:143], v[164:167], v[24:27]
	v_mfma_f32_16x16x32_bf16 v[12:15], v[132:135], v[172:175], v[12:15]
	v_mfma_f32_16x16x32_bf16 v[8:11], v[140:143], v[172:175], v[8:11]
	s_setprio 0
	s_barrier
	s_add_u32 s24, s28, 0x60080
	s_addc_u32 s25, s29, 0
	s_add_i32 s28, s30, s37
	s_mov_b32 m0, s28
	s_nop 0
	global_load_lds_dwordx4 v204, s[24:25]
	s_add_i32 m0, s28, 0x2000
	s_nop 0
	global_load_lds_dwordx4 v208, s[24:25]
	s_waitcnt vmcnt(8)
	s_setprio 1
	s_barrier
	v_mfma_f32_16x16x32_bf16 v[52:55], v[176:179], v[144:147], v[52:55]
	v_mfma_f32_16x16x32_bf16 v[48:51], v[184:187], v[144:147], v[48:51]
	v_mfma_f32_16x16x32_bf16 v[36:39], v[176:179], v[152:155], v[36:39]
	v_mfma_f32_16x16x32_bf16 v[32:35], v[184:187], v[152:155], v[32:35]
	v_mfma_f32_16x16x32_bf16 v[20:23], v[176:179], v[160:163], v[20:23]
	v_mfma_f32_16x16x32_bf16 v[16:19], v[184:187], v[160:163], v[16:19]
	v_mfma_f32_16x16x32_bf16 v[4:7], v[176:179], v[168:171], v[4:7]
	v_mfma_f32_16x16x32_bf16 v[0:3], v[184:187], v[168:171], v[0:3]
	v_mfma_f32_16x16x32_bf16 v[52:55], v[180:183], v[148:151], v[52:55]
	v_mfma_f32_16x16x32_bf16 v[48:51], v[188:191], v[148:151], v[48:51]
	v_mfma_f32_16x16x32_bf16 v[36:39], v[180:183], v[156:159], v[36:39]
	v_mfma_f32_16x16x32_bf16 v[32:35], v[188:191], v[156:159], v[32:35]
	v_mfma_f32_16x16x32_bf16 v[20:23], v[180:183], v[164:167], v[20:23]
	v_mfma_f32_16x16x32_bf16 v[16:19], v[188:191], v[164:167], v[16:19]
	v_mfma_f32_16x16x32_bf16 v[4:7], v[180:183], v[172:175], v[4:7]
	v_mfma_f32_16x16x32_bf16 v[0:3], v[188:191], v[172:175], v[0:3]
	s_setprio 0
	s_add_i32 s58, s58, 2
	s_add_u32 s56, s56, 0x100
	s_addc_u32 s57, s57, 0
	s_cmp_gt_u32 s58, 21
	s_mov_b64 s[24:25], s[26:27]
	s_barrier
; __device__ __forceinline__ unsigned cvt_pk_bf16(float lo, float hi) { unsigned r; asm volatile("v_cvt_pk_bf16_f32 %0, %1, %2" : "=v"(r) : "v"(lo), "v"(hi)); return r; }
; __device__ __forceinline__ float bf_lo(unsigned u) { return __uint_as_float(u << 16); }
; __device__ __forceinline__ float bf_hi(unsigned u) { return __uint_as_float(u & 0xffff0000u); }
;     __device__ __forceinline__ void operator()(const AccT& acc, const Unit& u, int wr, int wc, int fr, int fq) const {
;         asm volatile("" : "+v"(fr), "+v"(fq));
;         const int rowt = u.pm * 256; const int b = rowt >> 11;
;         const bf16_t* res = res_b + (size_t)rowt * DM; bf16_t* out = hb + (size_t)rowt * DM;
;         const int col0 = u.pn * 256 + wc * 32 + 8 * fq;
;         f32x4 gv[2][2];
; #pragma unroll
;         for (int bj = 0; bj < 2; ++bj)
; #pragma unroll
;             for (int n = 0; n < 2; ++n) gv[bj][n] = *(const f32x4*)(gate + (size_t)b * NMOD + col0 + bj * 128 + n * 4) * gs;
;         u32x4 r[2][4][2];
; #pragma unroll
;         for (int ai = 0; ai < 2; ++ai)
; #pragma unroll
;             for (int m = 0; m < 4; ++m)
; #pragma unroll
;                 for (int bj = 0; bj < 2; ++bj) r[ai][m][bj] = *(const u32x4*)(res + (size_t)(wr * 64 + fr + ai * 128 + m * 16) * DM + col0 + bj * 128);
; #pragma unroll
;         for (int ai = 0; ai < 2; ++ai)
; #pragma unroll
;             for (int m = 0; m < 4; ++m)
; #pragma unroll
;                 for (int bj = 0; bj < 2; ++bj) {
;                     const u32x4 q = r[ai][m][bj];
;                     const f32x4 r0 = {bf_lo(q.x), bf_hi(q.x), bf_lo(q.y), bf_hi(q.y)}, r1 = {bf_lo(q.z), bf_hi(q.z), bf_lo(q.w), bf_hi(q.w)};
;                     const f32x4 h0 = r0 + gv[bj][0] * acc[ai][bj][m][0], h1 = r1 + gv[bj][1] * acc[ai][bj][m][1];
;                     u32x4 w; w.x = cvt_pk_bf16(h0[0], h0[1]); w.y = cvt_pk_bf16(h0[2], h0[3]); w.z = cvt_pk_bf16(h1[0], h1[1]); w.w = cvt_pk_bf16(h1[2], h1[3]);
;                     *(u32x4*)(out + (size_t)(wr * 64 + fr + ai * 128 + m * 16) * DM + col0 + bj * 128) = w;
;                 }
	s_cbranch_scc0 .LBB0_902
	s_lshl_b32 s27, s55, 8
	v_mov_b32_e32 v146, v235
	v_mov_b32_e32 v128, v234
	s_lshl_b32 s24, s54, 8
	s_ashr_i32 s26, s54, 3
	s_or_b32 s27, s27, s46
	s_ashr_i32 s25, s24, 31
	v_lshl_add_u32 v144, v128, 3, s27
	s_mul_hi_i32 s27, s26, 0x9000
	s_mul_i32 s26, s26, 0x9000
	s_add_u32 s26, s43, s26
	s_addc_u32 s27, s44, s27
	v_ashrrev_i32_e32 v145, 31, v144
	s_lshl_b64 s[24:25], s[24:25], 11
	v_lshl_add_u64 v[132:133], v[144:145], 2, s[26:27]
	s_add_u32 s26, s62, s24
	v_add_u32_e32 v146, s45, v146
	s_addc_u32 s27, s63, s25
	v_lshlrev_b64 v[222:223], 1, v[144:145]
	v_ashrrev_i32_e32 v147, 31, v146
	v_lshl_add_u64 v[144:145], s[26:27], 0, v[222:223]
	v_lshlrev_b64 v[248:249], 11, v[146:147]
	v_lshl_add_u64 v[146:147], v[144:145], 0, v[248:249]
	global_load_dwordx4 v[136:139], v[132:133], off offset:16
	global_load_dwordx4 v[140:143], v[132:133], off
	global_load_dwordx4 v[128:131], v[132:133], off offset:528
	s_nop 0
	global_load_dwordx4 v[132:135], v[132:133], off offset:512
	s_nop 0
	global_load_dwordx4 v[240:243], v[146:147], off
	global_load_dwordx4 v[244:247], v[146:147], off offset:256
	v_lshl_add_u64 v[232:233], v[248:249], 0, s[10:11]
	v_lshl_add_u64 v[146:147], v[144:145], 0, v[232:233]
	global_load_dwordx4 v[196:199], v[146:147], off
	global_load_dwordx4 v[192:195], v[146:147], off offset:256
	v_lshl_add_u64 v[230:231], v[248:249], 0, s[12:13]
	v_lshl_add_u64 v[146:147], v[144:145], 0, v[230:231]
	global_load_dwordx4 v[188:191], v[146:147], off
	global_load_dwordx4 v[184:187], v[146:147], off offset:256
	v_lshl_add_u64 v[228:229], v[248:249], 0, s[14:15]
	v_lshl_add_u64 v[146:147], v[144:145], 0, v[228:229]
	global_load_dwordx4 v[180:183], v[146:147], off
	global_load_dwordx4 v[176:179], v[146:147], off offset:256
	v_lshl_add_u64 v[226:227], v[248:249], 0, s[16:17]
	v_lshl_add_u64 v[146:147], v[144:145], 0, v[226:227]
	global_load_dwordx4 v[172:175], v[146:147], off
	global_load_dwordx4 v[168:171], v[146:147], off offset:256
	v_lshl_add_u64 v[224:225], v[248:249], 0, s[18:19]
	v_lshl_add_u64 v[146:147], v[144:145], 0, v[224:225]
	global_load_dwordx4 v[164:167], v[146:147], off
	global_load_dwordx4 v[160:163], v[146:147], off offset:256
	v_lshl_add_u64 v[220:221], v[248:249], 0, s[20:21]
	v_lshl_add_u64 v[146:147], v[144:145], 0, v[220:221]
	global_load_dwordx4 v[156:159], v[146:147], off
	global_load_dwordx4 v[152:155], v[146:147], off offset:256
	v_lshl_add_u64 v[218:219], v[248:249], 0, s[22:23]
	v_lshl_add_u64 v[144:145], v[144:145], 0, v[218:219]
	global_load_dwordx4 v[148:151], v[144:145], off
	s_nop 0
	global_load_dwordx4 v[144:147], v[144:145], off offset:256
	s_add_u32 s24, s80, s24
	s_addc_u32 s25, s81, s25
	v_lshl_add_u64 v[222:223], s[24:25], 0, v[222:223]
	v_lshl_add_u64 v[248:249], v[222:223], 0, v[248:249]
	s_and_b64 vcc, exec, s[2:3]
	s_mov_b32 s55, s52
	s_mov_b32 s54, s53
	s_mov_b64 s[26:27], s[6:7]
	s_mov_b64 s[24:25], s[4:5]
	s_waitcnt vmcnt(0)
	v_lshlrev_b32_e32 v250, 16, v240
	v_and_b32_e32 v251, 0xffff0000, v240
	v_lshlrev_b32_e32 v240, 16, v241
	v_and_b32_e32 v241, 0xffff0000, v241
	v_lshlrev_b32_e32 v252, 16, v242
	v_and_b32_e32 v253, 0xffff0000, v242
	v_lshlrev_b32_e32 v242, 16, v243
	v_and_b32_e32 v243, 0xffff0000, v243
	v_pk_fma_f32 v[126:127], v[126:127], v[142:143], v[240:241]
	v_pk_fma_f32 v[124:125], v[124:125], v[140:141], v[250:251]
	v_pk_fma_f32 v[240:241], v[122:123], v[138:139], v[242:243]
	v_pk_fma_f32 v[122:123], v[120:121], v[136:137], v[252:253]
	v_cvt_pk_bf16_f32 v120, v124, v125
	v_cvt_pk_bf16_f32 v121, v126, v127
	v_lshlrev_b32_e32 v124, 16, v246
	v_cvt_pk_bf16_f32 v122, v122, v123
	v_cvt_pk_bf16_f32 v123, v240, v241
	global_store_dwordx4 v[248:249], v[120:123], off
	v_and_b32_e32 v125, 0xffff0000, v246
	v_lshlrev_b32_e32 v126, 16, v247
	v_lshlrev_b32_e32 v120, 16, v244
	v_and_b32_e32 v121, 0xffff0000, v244
	v_and_b32_e32 v127, 0xffff0000, v247
	v_lshlrev_b32_e32 v122, 16, v245
	v_and_b32_e32 v123, 0xffff0000, v245
	v_pk_fma_f32 v[116:117], v[116:117], v[132:133], v[120:121]
	v_pk_fma_f32 v[120:121], v[114:115], v[130:131], v[126:127]
	v_pk_fma_f32 v[114:115], v[112:113], v[128:129], v[124:125]
	v_pk_fma_f32 v[118:119], v[118:119], v[134:135], v[122:123]
	v_cvt_pk_bf16_f32 v112, v116, v117
	v_lshlrev_b32_e32 v116, 16, v197
	v_cvt_pk_bf16_f32 v113, v118, v119
	v_cvt_pk_bf16_f32 v114, v114, v115
	v_cvt_pk_bf16_f32 v115, v120, v121
	global_store_dwordx4 v[248:249], v[112:115], off offset:256
	v_and_b32_e32 v117, 0xffff0000, v197
	v_lshlrev_b32_e32 v118, 16, v198
	v_lshlrev_b32_e32 v114, 16, v196
	v_and_b32_e32 v115, 0xffff0000, v196
	v_and_b32_e32 v119, 0xffff0000, v198
	v_lshlrev_b32_e32 v120, 16, v199
	v_and_b32_e32 v121, 0xffff0000, v199
	v_lshl_add_u64 v[112:113], v[222:223], 0, v[232:233]
	v_pk_fma_f32 v[110:111], v[110:111], v[142:143], v[116:117]
	v_pk_fma_f32 v[108:109], v[108:109], v[140:141], v[114:115]
	v_pk_fma_f32 v[114:115], v[106:107], v[138:139], v[120:121]
	v_pk_fma_f32 v[106:107], v[104:105], v[136:137], v[118:119]
	v_cvt_pk_bf16_f32 v104, v108, v109
	v_cvt_pk_bf16_f32 v105, v110, v111
	v_lshlrev_b32_e32 v108, 16, v194
	v_cvt_pk_bf16_f32 v106, v106, v107
	v_cvt_pk_bf16_f32 v107, v114, v115
	global_store_dwordx4 v[112:113], v[104:107], off
	v_and_b32_e32 v109, 0xffff0000, v194
	v_lshlrev_b32_e32 v110, 16, v195
	v_lshlrev_b32_e32 v104, 16, v192
	v_and_b32_e32 v105, 0xffff0000, v192
	v_and_b32_e32 v111, 0xffff0000, v195
	v_lshlrev_b32_e32 v106, 16, v193
	v_and_b32_e32 v107, 0xffff0000, v193
	v_pk_fma_f32 v[100:101], v[100:101], v[132:133], v[104:105]
	v_pk_fma_f32 v[104:105], v[98:99], v[130:131], v[110:111]
	v_pk_fma_f32 v[98:99], v[96:97], v[128:129], v[108:109]
; __device__ __forceinline__ unsigned cvt_pk_bf16(float lo, float hi) { unsigned r; asm volatile("v_cvt_pk_bf16_f32 %0, %1, %2" : "=v"(r) : "v"(lo), "v"(hi)); return r; }
; __device__ __forceinline__ float bf_lo(unsigned u) { return __uint_as_float(u << 16); }
; __device__ __forceinline__ float bf_hi(unsigned u) { return __uint_as_float(u & 0xffff0000u); }
;     __device__ __forceinline__ void operator()(const AccT& acc, const Unit& u, int wr, int wc, int fr, int fq) const {
;     ...
;                 for (int bj = 0; bj < 2; ++bj) {
;                     const u32x4 q = r[ai][m][bj];
;                     const f32x4 r0 = {bf_lo(q.x), bf_hi(q.x), bf_lo(q.y), bf_hi(q.y)}, r1 = {bf_lo(q.z), bf_hi(q.z), bf_lo(q.w), bf_hi(q.w)};
;                     const f32x4 h0 = r0 + gv[bj][0] * acc[ai][bj][m][0], h1 = r1 + gv[bj][1] * acc[ai][bj][m][1];
;                     u32x4 w; w.x = cvt_pk_bf16(h0[0], h0[1]); w.y = cvt_pk_bf16(h0[2], h0[3]); w.z = cvt_pk_bf16(h1[0], h1[1]); w.w = cvt_pk_bf16(h1[2], h1[3]);
;                     *(u32x4*)(out + (size_t)(wr * 64 + fr + ai * 128 + m * 16) * DM + col0 + bj * 128) = w;
;                 }
	v_pk_fma_f32 v[102:103], v[102:103], v[134:135], v[106:107]
	v_cvt_pk_bf16_f32 v96, v100, v101
	v_lshlrev_b32_e32 v100, 16, v189
	v_cvt_pk_bf16_f32 v97, v102, v103
	v_cvt_pk_bf16_f32 v98, v98, v99
	v_cvt_pk_bf16_f32 v99, v104, v105
	global_store_dwordx4 v[112:113], v[96:99], off offset:256
	v_and_b32_e32 v101, 0xffff0000, v189
	v_lshlrev_b32_e32 v102, 16, v190
	v_lshlrev_b32_e32 v98, 16, v188
	v_and_b32_e32 v99, 0xffff0000, v188
	v_and_b32_e32 v103, 0xffff0000, v190
	v_lshlrev_b32_e32 v104, 16, v191
	v_and_b32_e32 v105, 0xffff0000, v191
	v_lshl_add_u64 v[96:97], v[222:223], 0, v[230:231]
	v_pk_fma_f32 v[94:95], v[94:95], v[142:143], v[100:101]
	v_pk_fma_f32 v[92:93], v[92:93], v[140:141], v[98:99]
	v_pk_fma_f32 v[98:99], v[90:91], v[138:139], v[104:105]
	v_pk_fma_f32 v[90:91], v[88:89], v[136:137], v[102:103]
	v_cvt_pk_bf16_f32 v88, v92, v93
	v_cvt_pk_bf16_f32 v89, v94, v95
	v_lshlrev_b32_e32 v92, 16, v186
	v_cvt_pk_bf16_f32 v90, v90, v91
	v_cvt_pk_bf16_f32 v91, v98, v99
	global_store_dwordx4 v[96:97], v[88:91], off
	v_and_b32_e32 v93, 0xffff0000, v186
	v_lshlrev_b32_e32 v94, 16, v187
	v_lshlrev_b32_e32 v88, 16, v184
	v_and_b32_e32 v89, 0xffff0000, v184
	v_and_b32_e32 v95, 0xffff0000, v187
	v_lshlrev_b32_e32 v90, 16, v185
	v_and_b32_e32 v91, 0xffff0000, v185
	v_pk_fma_f32 v[84:85], v[84:85], v[132:133], v[88:89]
	v_pk_fma_f32 v[88:89], v[82:83], v[130:131], v[94:95]
	v_pk_fma_f32 v[82:83], v[80:81], v[128:129], v[92:93]
	v_pk_fma_f32 v[86:87], v[86:87], v[134:135], v[90:91]
	v_cvt_pk_bf16_f32 v80, v84, v85
	v_lshlrev_b32_e32 v84, 16, v181
	v_cvt_pk_bf16_f32 v81, v86, v87
	v_cvt_pk_bf16_f32 v82, v82, v83
	v_cvt_pk_bf16_f32 v83, v88, v89
	global_store_dwordx4 v[96:97], v[80:83], off offset:256
	v_and_b32_e32 v85, 0xffff0000, v181
	v_lshlrev_b32_e32 v86, 16, v182
	v_lshlrev_b32_e32 v82, 16, v180
	v_and_b32_e32 v83, 0xffff0000, v180
	v_and_b32_e32 v87, 0xffff0000, v182
	v_lshlrev_b32_e32 v88, 16, v183
	v_and_b32_e32 v89, 0xffff0000, v183
	v_lshl_add_u64 v[80:81], v[222:223], 0, v[228:229]
	v_pk_fma_f32 v[78:79], v[78:79], v[142:143], v[84:85]
	v_pk_fma_f32 v[76:77], v[76:77], v[140:141], v[82:83]
	v_pk_fma_f32 v[82:83], v[74:75], v[138:139], v[88:89]
	v_pk_fma_f32 v[74:75], v[72:73], v[136:137], v[86:87]
	v_cvt_pk_bf16_f32 v72, v76, v77
	v_cvt_pk_bf16_f32 v73, v78, v79
	v_lshlrev_b32_e32 v76, 16, v178
	v_cvt_pk_bf16_f32 v74, v74, v75
	v_cvt_pk_bf16_f32 v75, v82, v83
	global_store_dwordx4 v[80:81], v[72:75], off
	v_and_b32_e32 v77, 0xffff0000, v178
	v_lshlrev_b32_e32 v78, 16, v179
	v_lshlrev_b32_e32 v72, 16, v176
	v_and_b32_e32 v73, 0xffff0000, v176
	v_and_b32_e32 v79, 0xffff0000, v179
	v_lshlrev_b32_e32 v74, 16, v177
	v_and_b32_e32 v75, 0xffff0000, v177
	v_pk_fma_f32 v[68:69], v[68:69], v[132:133], v[72:73]
	v_pk_fma_f32 v[72:73], v[66:67], v[130:131], v[78:79]
	v_pk_fma_f32 v[66:67], v[64:65], v[128:129], v[76:77]
	v_pk_fma_f32 v[70:71], v[70:71], v[134:135], v[74:75]
	v_cvt_pk_bf16_f32 v64, v68, v69
	v_lshlrev_b32_e32 v68, 16, v173
	v_cvt_pk_bf16_f32 v65, v70, v71
	v_cvt_pk_bf16_f32 v66, v66, v67
	v_cvt_pk_bf16_f32 v67, v72, v73
	global_store_dwordx4 v[80:81], v[64:67], off offset:256
	v_and_b32_e32 v69, 0xffff0000, v173
	v_lshlrev_b32_e32 v70, 16, v174
	v_lshlrev_b32_e32 v66, 16, v172
	v_and_b32_e32 v67, 0xffff0000, v172
	v_and_b32_e32 v71, 0xffff0000, v174
	v_lshlrev_b32_e32 v72, 16, v175
	v_and_b32_e32 v73, 0xffff0000, v175
	v_lshl_add_u64 v[64:65], v[222:223], 0, v[226:227]
	v_pk_fma_f32 v[62:63], v[62:63], v[142:143], v[68:69]
	v_pk_fma_f32 v[60:61], v[60:61], v[140:141], v[66:67]
	v_pk_fma_f32 v[66:67], v[58:59], v[138:139], v[72:73]
	v_pk_fma_f32 v[58:59], v[56:57], v[136:137], v[70:71]
	v_cvt_pk_bf16_f32 v56, v60, v61
	v_cvt_pk_bf16_f32 v57, v62, v63
	v_lshlrev_b32_e32 v60, 16, v170
	v_cvt_pk_bf16_f32 v58, v58, v59
	v_cvt_pk_bf16_f32 v59, v66, v67
	global_store_dwordx4 v[64:65], v[56:59], off
	v_and_b32_e32 v61, 0xffff0000, v170
	v_lshlrev_b32_e32 v62, 16, v171
	v_lshlrev_b32_e32 v56, 16, v168
	v_and_b32_e32 v57, 0xffff0000, v168
	v_and_b32_e32 v63, 0xffff0000, v171
	v_lshlrev_b32_e32 v58, 16, v169
	v_and_b32_e32 v59, 0xffff0000, v169
	v_pk_fma_f32 v[52:53], v[52:53], v[132:133], v[56:57]
	v_pk_fma_f32 v[56:57], v[50:51], v[130:131], v[62:63]
	v_pk_fma_f32 v[50:51], v[48:49], v[128:129], v[60:61]
	v_pk_fma_f32 v[54:55], v[54:55], v[134:135], v[58:59]
	v_cvt_pk_bf16_f32 v48, v52, v53
	v_lshlrev_b32_e32 v52, 16, v165
	v_cvt_pk_bf16_f32 v49, v54, v55
; __device__ __forceinline__ unsigned cvt_pk_bf16(float lo, float hi) { unsigned r; asm volatile("v_cvt_pk_bf16_f32 %0, %1, %2" : "=v"(r) : "v"(lo), "v"(hi)); return r; }
; __device__ __forceinline__ float bf_lo(unsigned u) { return __uint_as_float(u << 16); }
; __device__ __forceinline__ float bf_hi(unsigned u) { return __uint_as_float(u & 0xffff0000u); }
; #define PG8_WAIT_V(n) asm volatile("s_waitcnt vmcnt(" #n ")" ::: "memory")
; #define PG8_BAR __builtin_amdgcn_s_barrier()
; template <class Epi, class Sched>
; __device__ __forceinline__ void gemm_phase(LAS unsigned char* lds, const Gemm g, const Sched& S, const Epi& E) {
;     ...
;         E(acc, cur, wr, wc, fr, fq);
;         if (!has_next) break;
; #pragma unroll
;         for (int a = 0; a < 2; ++a)
; #pragma unroll
;             for (int b = 0; b < 2; ++b)
; #pragma unroll
;                 for (int m = 0; m < 4; ++m)
; #pragma unroll
;                     for (int n = 0; n < 2; ++n) acc[a][b][m][n] = (f32x4){0.f, 0.f, 0.f, 0.f};
;         cur = nxt; cA = nA; cB = nB; ++ui;
;     }
;     PG8_WAIT_V(0);
;     if (wr == 0) PG8_BAR;
;     PG8_BAR;
;     __device__ __forceinline__ void operator()(const AccT& acc, const Unit& u, int wr, int wc, int fr, int fq) const {
;     ...
;                 for (int bj = 0; bj < 2; ++bj) {
;                     const u32x4 q = r[ai][m][bj];
;                     const f32x4 r0 = {bf_lo(q.x), bf_hi(q.x), bf_lo(q.y), bf_hi(q.y)}, r1 = {bf_lo(q.z), bf_hi(q.z), bf_lo(q.w), bf_hi(q.w)};
;                     const f32x4 h0 = r0 + gv[bj][0] * acc[ai][bj][m][0], h1 = r1 + gv[bj][1] * acc[ai][bj][m][1];
;                     u32x4 w; w.x = cvt_pk_bf16(h0[0], h0[1]); w.y = cvt_pk_bf16(h0[2], h0[3]); w.z = cvt_pk_bf16(h1[0], h1[1]); w.w = cvt_pk_bf16(h1[2], h1[3]);
;                     *(u32x4*)(out + (size_t)(wr * 64 + fr + ai * 128 + m * 16) * DM + col0 + bj * 128) = w;
;                 }
	v_cvt_pk_bf16_f32 v50, v50, v51
	v_cvt_pk_bf16_f32 v51, v56, v57
	global_store_dwordx4 v[64:65], v[48:51], off offset:256
	v_and_b32_e32 v53, 0xffff0000, v165
	v_lshlrev_b32_e32 v54, 16, v166
	v_lshlrev_b32_e32 v50, 16, v164
	v_and_b32_e32 v51, 0xffff0000, v164
	v_and_b32_e32 v55, 0xffff0000, v166
	v_lshlrev_b32_e32 v56, 16, v167
	v_and_b32_e32 v57, 0xffff0000, v167
	v_lshl_add_u64 v[48:49], v[222:223], 0, v[224:225]
	v_pk_fma_f32 v[46:47], v[46:47], v[142:143], v[52:53]
	v_pk_fma_f32 v[44:45], v[44:45], v[140:141], v[50:51]
	v_pk_fma_f32 v[50:51], v[42:43], v[138:139], v[56:57]
	v_pk_fma_f32 v[42:43], v[40:41], v[136:137], v[54:55]
	v_cvt_pk_bf16_f32 v40, v44, v45
	v_cvt_pk_bf16_f32 v41, v46, v47
	v_lshlrev_b32_e32 v44, 16, v162
	v_cvt_pk_bf16_f32 v42, v42, v43
	v_cvt_pk_bf16_f32 v43, v50, v51
	global_store_dwordx4 v[48:49], v[40:43], off
	v_and_b32_e32 v45, 0xffff0000, v162
	v_lshlrev_b32_e32 v46, 16, v163
	v_lshlrev_b32_e32 v40, 16, v160
	v_and_b32_e32 v41, 0xffff0000, v160
	v_and_b32_e32 v47, 0xffff0000, v163
	v_lshlrev_b32_e32 v42, 16, v161
	v_and_b32_e32 v43, 0xffff0000, v161
	v_pk_fma_f32 v[36:37], v[36:37], v[132:133], v[40:41]
	v_pk_fma_f32 v[40:41], v[34:35], v[130:131], v[46:47]
	v_pk_fma_f32 v[34:35], v[32:33], v[128:129], v[44:45]
	v_pk_fma_f32 v[38:39], v[38:39], v[134:135], v[42:43]
	v_cvt_pk_bf16_f32 v32, v36, v37
	v_lshlrev_b32_e32 v36, 16, v157
	v_cvt_pk_bf16_f32 v33, v38, v39
	v_cvt_pk_bf16_f32 v34, v34, v35
	v_cvt_pk_bf16_f32 v35, v40, v41
	global_store_dwordx4 v[48:49], v[32:35], off offset:256
	v_and_b32_e32 v37, 0xffff0000, v157
	v_lshlrev_b32_e32 v38, 16, v158
	v_lshlrev_b32_e32 v34, 16, v156
	v_and_b32_e32 v35, 0xffff0000, v156
	v_and_b32_e32 v39, 0xffff0000, v158
	v_lshlrev_b32_e32 v40, 16, v159
	v_and_b32_e32 v41, 0xffff0000, v159
	v_lshl_add_u64 v[32:33], v[222:223], 0, v[220:221]
	v_pk_fma_f32 v[30:31], v[30:31], v[142:143], v[36:37]
	v_pk_fma_f32 v[28:29], v[28:29], v[140:141], v[34:35]
	v_pk_fma_f32 v[34:35], v[26:27], v[138:139], v[40:41]
	v_pk_fma_f32 v[26:27], v[24:25], v[136:137], v[38:39]
	v_cvt_pk_bf16_f32 v24, v28, v29
	v_cvt_pk_bf16_f32 v25, v30, v31
	v_lshlrev_b32_e32 v28, 16, v154
	v_cvt_pk_bf16_f32 v26, v26, v27
	v_cvt_pk_bf16_f32 v27, v34, v35
	global_store_dwordx4 v[32:33], v[24:27], off
	v_and_b32_e32 v29, 0xffff0000, v154
	v_lshlrev_b32_e32 v30, 16, v155
	v_lshlrev_b32_e32 v24, 16, v152
	v_and_b32_e32 v25, 0xffff0000, v152
	v_and_b32_e32 v31, 0xffff0000, v155
	v_lshlrev_b32_e32 v26, 16, v153
	v_and_b32_e32 v27, 0xffff0000, v153
	v_pk_fma_f32 v[20:21], v[20:21], v[132:133], v[24:25]
	v_pk_fma_f32 v[24:25], v[18:19], v[130:131], v[30:31]
	v_pk_fma_f32 v[18:19], v[16:17], v[128:129], v[28:29]
	v_pk_fma_f32 v[22:23], v[22:23], v[134:135], v[26:27]
	v_cvt_pk_bf16_f32 v16, v20, v21
	v_lshlrev_b32_e32 v20, 16, v149
	v_cvt_pk_bf16_f32 v17, v22, v23
	v_cvt_pk_bf16_f32 v18, v18, v19
	v_cvt_pk_bf16_f32 v19, v24, v25
	global_store_dwordx4 v[32:33], v[16:19], off offset:256
	v_and_b32_e32 v21, 0xffff0000, v149
	v_lshlrev_b32_e32 v22, 16, v150
	v_lshlrev_b32_e32 v18, 16, v148
	v_and_b32_e32 v19, 0xffff0000, v148
	v_and_b32_e32 v23, 0xffff0000, v150
	v_lshlrev_b32_e32 v24, 16, v151
	v_and_b32_e32 v25, 0xffff0000, v151
	v_lshl_add_u64 v[16:17], v[222:223], 0, v[218:219]
	v_pk_fma_f32 v[14:15], v[14:15], v[142:143], v[20:21]
	v_pk_fma_f32 v[12:13], v[12:13], v[140:141], v[18:19]
	v_pk_fma_f32 v[18:19], v[10:11], v[138:139], v[24:25]
	v_pk_fma_f32 v[10:11], v[8:9], v[136:137], v[22:23]
	v_cvt_pk_bf16_f32 v8, v12, v13
	v_cvt_pk_bf16_f32 v9, v14, v15
	v_lshlrev_b32_e32 v12, 16, v146
	v_cvt_pk_bf16_f32 v10, v10, v11
	v_cvt_pk_bf16_f32 v11, v18, v19
	global_store_dwordx4 v[16:17], v[8:11], off
	v_and_b32_e32 v13, 0xffff0000, v146
	v_lshlrev_b32_e32 v14, 16, v147
	v_lshlrev_b32_e32 v8, 16, v144
	v_and_b32_e32 v9, 0xffff0000, v144
	v_and_b32_e32 v15, 0xffff0000, v147
	v_lshlrev_b32_e32 v10, 16, v145
	v_and_b32_e32 v11, 0xffff0000, v145
	v_pk_fma_f32 v[4:5], v[4:5], v[132:133], v[8:9]
	v_pk_fma_f32 v[8:9], v[2:3], v[130:131], v[14:15]
	v_pk_fma_f32 v[2:3], v[0:1], v[128:129], v[12:13]
	v_pk_fma_f32 v[6:7], v[6:7], v[134:135], v[10:11]
	v_cvt_pk_bf16_f32 v0, v4, v5
	s_nop 0
	v_cvt_pk_bf16_f32 v1, v6, v7
	v_cvt_pk_bf16_f32 v2, v2, v3
	v_cvt_pk_bf16_f32 v3, v8, v9
	global_store_dwordx4 v[16:17], v[0:3], off offset:256
	s_cbranch_vccz .LBB0_891
	s_waitcnt vmcnt(0)
	s_cmpk_gt_u32 s33, 0xff
	s_cbranch_scc1 .LBB0_906
	s_barrier

; #define PG8_STAGE(bufoff, gbase, voff) do { _Pragma("unroll") for (int _i = 0; _i < 2; ++_i) \
;         __builtin_amdgcn_global_load_lds((const unsigned*)((const char*)(gbase) + (voff)[_i]), (LAS unsigned*)(lds + (bufoff) + ldsw + _i * 8192), 16, 0, 0); } while (0)
; #define PG8_LDA(dst, b, h) do { _Pragma("unroll") for (int m = 0; m < 4; ++m) _Pragma("unroll") for (int k = 0; k < 2; ++k) dst[m][k] = *(const LAS bf16x8*)(lds + PG8_SA(b, h) + aoff + m * 2048 + k * 1024); } while (0)
; #define PG8_LDB(dst, b, h) do { _Pragma("unroll") for (int n = 0; n < 2; ++n) _Pragma("unroll") for (int k = 0; k < 2; ++k) dst[n][k] = *(const LAS bf16x8*)(lds + PG8_SB(b, h) + boff + n * 2048 + k * 1024); } while (0)
; #define PG8_WAIT_V(n) asm volatile("s_waitcnt vmcnt(" #n ")" ::: "memory")
; #define PG8_WAIT_L(n) asm volatile("s_waitcnt lgkmcnt(" #n ")" ::: "memory")
; #define PG8_BAR __builtin_amdgcn_s_barrier()
; #define PG8_SCHED __builtin_amdgcn_sched_barrier(0)
; template <class Epi, class Sched>
; __device__ __forceinline__ void gemm_phase(LAS unsigned char* lds, const Gemm g, const Sched& S, const Epi& E) {
;     ...
;         const bool has_next = S.next(ui + 1, nxt);
;         const char* nA = has_next ? (const char*)g.A + (size_t)nxt.pm * tstep : cA; const char* nB = has_next ? (const char*)g.Bt + (size_t)nxt.pn * tstep : cB;
;         for (int t = 0; t < nt; t += 2) {
;             const bool last = (t == nt - 2);
;             const char* a1 = cA + (size_t)(t + 1) * kstep;
;             const char* a2 = last ? nA : cA + (size_t)(t + 2) * kstep; const char* b2 = last ? nB : cB + (size_t)(t + 2) * kstep;
;             const char* a3 = a2 + kstep; const char* b3 = b2 + kstep;
;             PG8_LDB(B0, 0, 0); PG8_SCHED; PG8_LDA(At, 0, 0); PG8_STAGE(PG8_SA(1, 1), a1 + hstep, voffA);
;             PG8_WAIT_L(8); PG8_BAR; PG8_WAIT_L(0); PG8_MMA(0, 0, At, B0); PG8_BAR; PG8_SCHED;
;             PG8_LDB(B1, 0, 1); PG8_STAGE(PG8_SB(0, 0), b2, voffB);
;             PG8_BAR; PG8_WAIT_L(0); PG8_MMA(0, 1, At, B1); PG8_BAR;
;             PG8_LDA(At, 0, 1); PG8_STAGE(PG8_SA(0, 0), a2, voffA);
;             PG8_BAR; PG8_WAIT_L(0); PG8_MMA(1, 0, At, B0); PG8_BAR; PG8_SCHED;
;             PG8_STAGE(PG8_SB(0, 1), b2 + hstep, voffB);
;             PG8_WAIT_V(6); PG8_BAR; PG8_MMA(1, 1, At, B1); PG8_BAR;
.LBB0_1020:
	s_ashr_i32 s7, s6, 31
	v_cmp_lt_i64_e32 vcc, s[10:11], v[140:141]
	s_lshl_b64 s[10:11], s[6:7], 19
	s_add_u32 s10, s96, s10
	s_addc_u32 s11, s97, s11
	s_and_b64 s[12:13], vcc, exec
	s_cselect_b32 s7, s11, s17
	s_cselect_b32 s42, s10, s16
	s_ashr_i32 s5, s4, 31
	s_lshl_b64 s[12:13], s[4:5], 19
	s_add_u32 s12, s23, s12
	s_addc_u32 s13, s24, s13
	s_and_b64 s[20:21], vcc, exec
	s_cselect_b32 s5, s13, s19
	s_cselect_b32 s43, s12, s18
	s_add_u32 s16, s16, 0x40080
	s_addc_u32 s17, s17, 0
	s_add_u32 s44, s18, 0x100
	s_addc_u32 s45, s19, 0
	s_mov_b32 s46, -2
	ds_read_b128 v[150:153], v147
	ds_read_b128 v[154:157], v147 offset:1024
	ds_read_b128 v[158:161], v147 offset:2048
	ds_read_b128 v[162:165], v147 offset:3072
	s_add_u32 s18, s16, 0xfffc0080
	s_addc_u32 s19, s17, -1
	s_cmp_eq_u32 s46, 12
	s_cselect_b32 s21, s7, s19
	s_cselect_b32 s20, s42, s18
	s_cselect_b32 s19, s5, s45
	s_cselect_b32 s18, s43, s44
	s_add_i32 m0, s15, 0xc000
	ds_read_b128 v[166:169], v148
	ds_read_b128 v[170:173], v148 offset:1024
	ds_read_b128 v[174:177], v148 offset:2048
	ds_read_b128 v[178:181], v148 offset:3072
	ds_read_b128 v[182:185], v148 offset:4096
	ds_read_b128 v[186:189], v148 offset:5120
	ds_read_b128 v[190:193], v148 offset:6144
	ds_read_b128 v[194:197], v148 offset:7168
	global_load_lds_dwordx4 v136, s[16:17]
	s_add_i32 m0, s15, 0xe000
	s_nop 0
	global_load_lds_dwordx4 v138, s[16:17]
	s_waitcnt lgkmcnt(8)
	s_waitcnt vmcnt(8)
	s_setprio 1
	s_barrier
	s_waitcnt lgkmcnt(0)
	v_mfma_f32_16x16x32_bf16 v[124:127], v[150:153], v[166:169], 0
	v_mfma_f32_16x16x32_bf16 v[116:119], v[158:161], v[166:169], 0
	v_mfma_f32_16x16x32_bf16 v[108:111], v[150:153], v[174:177], 0
	v_mfma_f32_16x16x32_bf16 v[100:103], v[158:161], v[174:177], 0
	v_mfma_f32_16x16x32_bf16 v[92:95], v[150:153], v[182:185], 0
	v_mfma_f32_16x16x32_bf16 v[84:87], v[158:161], v[182:185], 0
	v_mfma_f32_16x16x32_bf16 v[76:79], v[150:153], v[190:193], 0
	v_mfma_f32_16x16x32_bf16 v[68:71], v[158:161], v[190:193], 0
	v_mfma_f32_16x16x32_bf16 v[124:127], v[154:157], v[170:173], v[124:127]
	v_mfma_f32_16x16x32_bf16 v[116:119], v[162:165], v[170:173], v[116:119]
	v_mfma_f32_16x16x32_bf16 v[108:111], v[154:157], v[178:181], v[108:111]
	v_mfma_f32_16x16x32_bf16 v[100:103], v[162:165], v[178:181], v[100:103]
	v_mfma_f32_16x16x32_bf16 v[92:95], v[154:157], v[186:189], v[92:95]
	v_mfma_f32_16x16x32_bf16 v[84:87], v[162:165], v[186:189], v[84:87]
	v_mfma_f32_16x16x32_bf16 v[76:79], v[154:157], v[194:197], v[76:79]
	v_mfma_f32_16x16x32_bf16 v[68:71], v[162:165], v[194:197], v[68:71]
	s_setprio 0
	s_barrier
	s_add_i32 s47, s38, s25
	s_mov_b32 m0, s47
	ds_read_b128 v[202:205], v149
	ds_read_b128 v[206:209], v149 offset:1024
	ds_read_b128 v[210:213], v149 offset:2048
	ds_read_b128 v[214:217], v149 offset:3072
	global_load_lds_dwordx4 v132, s[18:19]
	s_add_i32 m0, s47, 0x2000
	s_nop 0
	global_load_lds_dwordx4 v128, s[18:19]
	s_waitcnt vmcnt(8)
	s_setprio 1
	s_barrier
	s_waitcnt lgkmcnt(0)
	v_mfma_f32_16x16x32_bf16 v[120:123], v[202:205], v[166:169], 0
	v_mfma_f32_16x16x32_bf16 v[112:115], v[210:213], v[166:169], 0
	v_mfma_f32_16x16x32_bf16 v[104:107], v[202:205], v[174:177], 0
	v_mfma_f32_16x16x32_bf16 v[96:99], v[210:213], v[174:177], 0
	v_mfma_f32_16x16x32_bf16 v[88:91], v[202:205], v[182:185], 0
	v_mfma_f32_16x16x32_bf16 v[80:83], v[210:213], v[182:185], 0
	v_mfma_f32_16x16x32_bf16 v[72:75], v[202:205], v[190:193], 0
	v_mfma_f32_16x16x32_bf16 v[64:67], v[210:213], v[190:193], 0
	v_mfma_f32_16x16x32_bf16 v[120:123], v[206:209], v[170:173], v[120:123]
	v_mfma_f32_16x16x32_bf16 v[112:115], v[214:217], v[170:173], v[112:115]
	v_mfma_f32_16x16x32_bf16 v[104:107], v[206:209], v[178:181], v[104:107]
	v_mfma_f32_16x16x32_bf16 v[96:99], v[214:217], v[178:181], v[96:99]
	v_mfma_f32_16x16x32_bf16 v[88:91], v[206:209], v[186:189], v[88:91]
	v_mfma_f32_16x16x32_bf16 v[80:83], v[214:217], v[186:189], v[80:83]
	v_mfma_f32_16x16x32_bf16 v[72:75], v[206:209], v[194:197], v[72:75]
	v_mfma_f32_16x16x32_bf16 v[64:67], v[214:217], v[194:197], v[64:67]
	s_setprio 0
	s_mov_b32 m0, s15
	v_lshl_add_u64 v[220:221], s[20:21], 0, v[134:135]
	s_barrier
	ds_read_b128 v[166:169], v148 offset:16384
	ds_read_b128 v[170:173], v148 offset:17408
	ds_read_b128 v[174:177], v148 offset:18432
	ds_read_b128 v[178:181], v148 offset:19456
	ds_read_b128 v[182:185], v148 offset:20480
	ds_read_b128 v[186:189], v148 offset:21504
	ds_read_b128 v[190:193], v148 offset:22528
	ds_read_b128 v[194:197], v148 offset:23552
	global_load_lds_dwordx4 v134, s[20:21]
	v_lshl_add_u64 v[222:223], s[20:21], 0, v[130:131]
	s_mov_b32 m0, s28
	s_nop 0
	global_load_lds_dwordx4 v130, s[20:21]
	s_setprio 1
	s_barrier
	s_waitcnt lgkmcnt(0)
	v_mfma_f32_16x16x32_bf16 v[60:63], v[150:153], v[166:169], 0
	v_mfma_f32_16x16x32_bf16 v[56:59], v[158:161], v[166:169], 0
	v_mfma_f32_16x16x32_bf16 v[44:47], v[150:153], v[174:177], 0
	v_mfma_f32_16x16x32_bf16 v[40:43], v[158:161], v[174:177], 0
	v_mfma_f32_16x16x32_bf16 v[28:31], v[150:153], v[182:185], 0
	v_mfma_f32_16x16x32_bf16 v[24:27], v[158:161], v[182:185], 0
	v_mfma_f32_16x16x32_bf16 v[12:15], v[150:153], v[190:193], 0
	v_mfma_f32_16x16x32_bf16 v[8:11], v[158:161], v[190:193], 0
	v_mfma_f32_16x16x32_bf16 v[60:63], v[154:157], v[170:173], v[60:63]
	v_mfma_f32_16x16x32_bf16 v[56:59], v[162:165], v[170:173], v[56:59]
	v_mfma_f32_16x16x32_bf16 v[44:47], v[154:157], v[178:181], v[44:47]
	v_mfma_f32_16x16x32_bf16 v[40:43], v[162:165], v[178:181], v[40:43]
	v_mfma_f32_16x16x32_bf16 v[28:31], v[154:157], v[186:189], v[28:31]
	v_mfma_f32_16x16x32_bf16 v[24:27], v[162:165], v[186:189], v[24:27]
	v_mfma_f32_16x16x32_bf16 v[12:15], v[154:157], v[194:197], v[12:15]
	v_mfma_f32_16x16x32_bf16 v[8:11], v[162:165], v[194:197], v[8:11]
	s_setprio 0
	s_barrier
; #define PG8_STAGE(bufoff, gbase, voff) do { _Pragma("unroll") for (int _i = 0; _i < 2; ++_i) \
;         __builtin_amdgcn_global_load_lds((const unsigned*)((const char*)(gbase) + (voff)[_i]), (LAS unsigned*)(lds + (bufoff) + ldsw + _i * 8192), 16, 0, 0); } while (0)
; #define PG8_LDA(dst, b, h) do { _Pragma("unroll") for (int m = 0; m < 4; ++m) _Pragma("unroll") for (int k = 0; k < 2; ++k) dst[m][k] = *(const LAS bf16x8*)(lds + PG8_SA(b, h) + aoff + m * 2048 + k * 1024); } while (0)
; #define PG8_LDB(dst, b, h) do { _Pragma("unroll") for (int n = 0; n < 2; ++n) _Pragma("unroll") for (int k = 0; k < 2; ++k) dst[n][k] = *(const LAS bf16x8*)(lds + PG8_SB(b, h) + boff + n * 2048 + k * 1024); } while (0)
; #define PG8_MMA(ai, bj, At, Bt) do { __builtin_amdgcn_s_setprio(1); _Pragma("unroll") for (int m = 0; m < 4; ++m) _Pragma("unroll") for (int n = 0; n < 2; ++n) _Pragma("unroll") for (int k = 0; k < 2; ++k) \
;         acc[ai][bj][m][n] = __builtin_amdgcn_mfma_f32_16x16x32_bf16(Bt[n][k], At[m][k], acc[ai][bj][m][n], 0, 0, 0); __builtin_amdgcn_s_setprio(0); } while (0)
; #define PG8_WAIT_V(n) asm volatile("s_waitcnt vmcnt(" #n ")" ::: "memory")
; #define PG8_WAIT_L(n) asm volatile("s_waitcnt lgkmcnt(" #n ")" ::: "memory")
; #define PG8_BAR __builtin_amdgcn_s_barrier()
; #define PG8_SCHED __builtin_amdgcn_sched_barrier(0)
; template <class Epi, class Sched>
; __device__ __forceinline__ void gemm_phase(LAS unsigned char* lds, const Gemm g, const Sched& S, const Epi& E) {
;     ...
;             PG8_STAGE(PG8_SB(0, 1), b2 + hstep, voffB);
;             PG8_WAIT_V(6); PG8_BAR; PG8_MMA(1, 1, At, B1); PG8_BAR;
;             PG8_LDB(B0, 1, 0); PG8_SCHED; PG8_LDA(At, 1, 0); PG8_STAGE(PG8_SA(0, 1), a2 + hstep, voffA);
;             PG8_WAIT_L(8); PG8_BAR; PG8_WAIT_L(0); PG8_MMA(0, 0, At, B0); PG8_BAR; PG8_SCHED;
;             PG8_LDB(B1, 1, 1); PG8_STAGE(PG8_SB(1, 0), b3, voffB);
;             PG8_BAR; PG8_WAIT_L(0); PG8_MMA(0, 1, At, B1); PG8_BAR;
;             PG8_LDA(At, 1, 1); PG8_STAGE(PG8_SA(1, 0), a3, voffA);
	s_add_u32 s48, s18, 0x40000
	s_addc_u32 s49, s19, 0
	s_add_i32 s47, s39, s25
	s_mov_b32 m0, s47
	s_nop 0
	global_load_lds_dwordx4 v132, s[48:49]
	s_add_i32 m0, s47, 0x2000
	s_nop 0
	global_load_lds_dwordx4 v128, s[48:49]
	s_add_u32 s20, s20, 0x40000
	s_addc_u32 s21, s21, 0
	s_mov_b32 m0, s29
	s_nop 0
	global_load_lds_dwordx4 v134, s[20:21]
	s_mov_b32 m0, s30
	s_nop 0
	global_load_lds_dwordx4 v130, s[20:21]
	s_waitcnt vmcnt(10)
	s_setprio 1
	s_barrier
	v_mfma_f32_16x16x32_bf16 v[52:55], v[202:205], v[166:169], 0
	v_mfma_f32_16x16x32_bf16 v[48:51], v[210:213], v[166:169], 0
	v_mfma_f32_16x16x32_bf16 v[36:39], v[202:205], v[174:177], 0
	v_mfma_f32_16x16x32_bf16 v[32:35], v[210:213], v[174:177], 0
	v_mfma_f32_16x16x32_bf16 v[20:23], v[202:205], v[182:185], 0
	v_mfma_f32_16x16x32_bf16 v[16:19], v[210:213], v[182:185], 0
	v_mfma_f32_16x16x32_bf16 v[4:7], v[202:205], v[190:193], 0
	v_mfma_f32_16x16x32_bf16 v[0:3], v[210:213], v[190:193], 0
	v_mfma_f32_16x16x32_bf16 v[52:55], v[206:209], v[170:173], v[52:55]
	v_mfma_f32_16x16x32_bf16 v[48:51], v[214:217], v[170:173], v[48:51]
	v_mfma_f32_16x16x32_bf16 v[36:39], v[206:209], v[178:181], v[36:39]
	v_mfma_f32_16x16x32_bf16 v[32:35], v[214:217], v[178:181], v[32:35]
	v_mfma_f32_16x16x32_bf16 v[20:23], v[206:209], v[186:189], v[20:23]
	v_mfma_f32_16x16x32_bf16 v[16:19], v[214:217], v[186:189], v[16:19]
	v_mfma_f32_16x16x32_bf16 v[4:7], v[206:209], v[194:197], v[4:7]
	v_mfma_f32_16x16x32_bf16 v[0:3], v[214:217], v[194:197], v[0:3]
	s_setprio 0
	s_add_i32 s47, 0, 0x18000
	v_add_u32_e32 v162, s47, v146
	s_barrier
	ds_read_b128 v[150:153], v162
	ds_read_b128 v[154:157], v162 offset:1024
	ds_read_b128 v[158:161], v162 offset:2048
	ds_read_b128 v[162:165], v162 offset:3072
	ds_read_b128 v[166:169], v148 offset:32768
	ds_read_b128 v[170:173], v148 offset:33792
	ds_read_b128 v[174:177], v148 offset:34816
	ds_read_b128 v[178:181], v148 offset:35840
	ds_read_b128 v[182:185], v148 offset:36864
	ds_read_b128 v[186:189], v148 offset:37888
	ds_read_b128 v[190:193], v148 offset:38912
	ds_read_b128 v[194:197], v148 offset:39936
	s_waitcnt lgkmcnt(8)
	s_waitcnt vmcnt(8)
	s_setprio 1
	s_barrier
	s_waitcnt lgkmcnt(0)
	v_mfma_f32_16x16x32_bf16 v[124:127], v[150:153], v[166:169], v[124:127]
	v_mfma_f32_16x16x32_bf16 v[116:119], v[158:161], v[166:169], v[116:119]
	v_mfma_f32_16x16x32_bf16 v[108:111], v[150:153], v[174:177], v[108:111]
	v_mfma_f32_16x16x32_bf16 v[100:103], v[158:161], v[174:177], v[100:103]
	v_mfma_f32_16x16x32_bf16 v[92:95], v[150:153], v[182:185], v[92:95]
	v_mfma_f32_16x16x32_bf16 v[84:87], v[158:161], v[182:185], v[84:87]
	v_mfma_f32_16x16x32_bf16 v[76:79], v[150:153], v[190:193], v[76:79]
	v_mfma_f32_16x16x32_bf16 v[68:71], v[158:161], v[190:193], v[68:71]
	v_mfma_f32_16x16x32_bf16 v[124:127], v[154:157], v[170:173], v[124:127]
	v_mfma_f32_16x16x32_bf16 v[116:119], v[162:165], v[170:173], v[116:119]
	v_mfma_f32_16x16x32_bf16 v[108:111], v[154:157], v[178:181], v[108:111]
	v_mfma_f32_16x16x32_bf16 v[100:103], v[162:165], v[178:181], v[100:103]
	v_mfma_f32_16x16x32_bf16 v[92:95], v[154:157], v[186:189], v[92:95]
	v_mfma_f32_16x16x32_bf16 v[84:87], v[162:165], v[186:189], v[84:87]
	v_mfma_f32_16x16x32_bf16 v[76:79], v[154:157], v[194:197], v[76:79]
	v_mfma_f32_16x16x32_bf16 v[68:71], v[162:165], v[194:197], v[68:71]
	s_setprio 0
	s_barrier
	s_add_i32 s20, 0, 0x1c000
	s_add_i32 s21, s47, s25
	v_add_u32_e32 v214, s20, v146
	s_add_u32 s0, s18, 0x80
	s_addc_u32 s1, s19, 0
	s_mov_b32 m0, s21
	ds_read_b128 v[202:205], v214
	ds_read_b128 v[206:209], v214 offset:1024
	ds_read_b128 v[210:213], v214 offset:2048
	ds_read_b128 v[214:217], v214 offset:3072
	global_load_lds_dwordx4 v132, s[0:1]
	s_add_i32 m0, s21, 0x2000
	s_nop 0
	global_load_lds_dwordx4 v128, s[0:1]
	s_waitcnt vmcnt(8)
	s_setprio 1
	s_barrier
	s_waitcnt lgkmcnt(0)
	v_mfma_f32_16x16x32_bf16 v[120:123], v[202:205], v[166:169], v[120:123]
	v_mfma_f32_16x16x32_bf16 v[112:115], v[210:213], v[166:169], v[112:115]
	v_mfma_f32_16x16x32_bf16 v[104:107], v[202:205], v[174:177], v[104:107]
	v_mfma_f32_16x16x32_bf16 v[96:99], v[210:213], v[174:177], v[96:99]
	v_mfma_f32_16x16x32_bf16 v[88:91], v[202:205], v[182:185], v[88:91]
	v_mfma_f32_16x16x32_bf16 v[80:83], v[210:213], v[182:185], v[80:83]
	v_mfma_f32_16x16x32_bf16 v[72:75], v[202:205], v[190:193], v[72:75]
	v_mfma_f32_16x16x32_bf16 v[64:67], v[210:213], v[190:193], v[64:67]
	v_mfma_f32_16x16x32_bf16 v[120:123], v[206:209], v[170:173], v[120:123]
	v_mfma_f32_16x16x32_bf16 v[112:115], v[214:217], v[170:173], v[112:115]
	v_mfma_f32_16x16x32_bf16 v[104:107], v[206:209], v[178:181], v[104:107]
	v_mfma_f32_16x16x32_bf16 v[96:99], v[214:217], v[178:181], v[96:99]
	v_mfma_f32_16x16x32_bf16 v[88:91], v[206:209], v[186:189], v[88:91]
	v_mfma_f32_16x16x32_bf16 v[80:83], v[214:217], v[186:189], v[80:83]
	v_mfma_f32_16x16x32_bf16 v[72:75], v[206:209], v[194:197], v[72:75]
	v_mfma_f32_16x16x32_bf16 v[64:67], v[214:217], v[194:197], v[64:67]
	s_setprio 0
	s_mov_b32 m0, s35
	s_mov_b64 s[0:1], 0x80
	v_lshl_add_u64 v[198:199], v[220:221], 0, s[0:1]
	s_barrier
	ds_read_b128 v[166:169], v148 offset:49152
	ds_read_b128 v[170:173], v148 offset:50176
	ds_read_b128 v[174:177], v148 offset:51200
	ds_read_b128 v[178:181], v148 offset:52224
	ds_read_b128 v[182:185], v148 offset:53248
	ds_read_b128 v[186:189], v148 offset:54272
	ds_read_b128 v[190:193], v148 offset:55296
	ds_read_b128 v[194:197], v148 offset:56320
	global_load_lds_dwordx4 v[198:199], off
	v_lshl_add_u64 v[198:199], v[222:223], 0, s[0:1]
	s_mov_b32 m0, s36
	s_nop 0
	global_load_lds_dwordx4 v[198:199], off
	s_setprio 1
	s_barrier
; #define PG8_STAGE(bufoff, gbase, voff) do { _Pragma("unroll") for (int _i = 0; _i < 2; ++_i) \
;         __builtin_amdgcn_global_load_lds((const unsigned*)((const char*)(gbase) + (voff)[_i]), (LAS unsigned*)(lds + (bufoff) + ldsw + _i * 8192), 16, 0, 0); } while (0)
; #define PG8_LDA(dst, b, h) do { _Pragma("unroll") for (int m = 0; m < 4; ++m) _Pragma("unroll") for (int k = 0; k < 2; ++k) dst[m][k] = *(const LAS bf16x8*)(lds + PG8_SA(b, h) + aoff + m * 2048 + k * 1024); } while (0)
; #define PG8_LDB(dst, b, h) do { _Pragma("unroll") for (int n = 0; n < 2; ++n) _Pragma("unroll") for (int k = 0; k < 2; ++k) dst[n][k] = *(const LAS bf16x8*)(lds + PG8_SB(b, h) + boff + n * 2048 + k * 1024); } while (0)
; #define PG8_WAIT_V(n) asm volatile("s_waitcnt vmcnt(" #n ")" ::: "memory")
; #define PG8_WAIT_L(n) asm volatile("s_waitcnt lgkmcnt(" #n ")" ::: "memory")
; #define PG8_BAR __builtin_amdgcn_s_barrier()
; #define PG8_SCHED __builtin_amdgcn_sched_barrier(0)
; template <class Epi, class Sched>
; __device__ __forceinline__ void gemm_phase(LAS unsigned char* lds, const Gemm g, const Sched& S, const Epi& E) {
;     ...
;             PG8_LDB(B0, 0, 0); PG8_SCHED; PG8_LDA(At, 0, 0); PG8_STAGE(PG8_SA(1, 1), a1 + hstep, voffA);
;             PG8_WAIT_L(8); PG8_BAR; PG8_WAIT_L(0); PG8_MMA(0, 0, At, B0); PG8_BAR; PG8_SCHED;
;             PG8_LDB(B1, 0, 1); PG8_STAGE(PG8_SB(0, 0), b2, voffB);
;             PG8_BAR; PG8_WAIT_L(0); PG8_MMA(0, 1, At, B1); PG8_BAR;
;             PG8_LDA(At, 0, 1); PG8_STAGE(PG8_SA(0, 0), a2, voffA);
;             PG8_BAR; PG8_WAIT_L(0); PG8_MMA(1, 0, At, B0); PG8_BAR; PG8_SCHED;
;             PG8_STAGE(PG8_SB(0, 1), b2 + hstep, voffB);
;             PG8_WAIT_V(6); PG8_BAR; PG8_MMA(1, 1, At, B1); PG8_BAR;
;             PG8_LDB(B0, 1, 0); PG8_SCHED; PG8_LDA(At, 1, 0); PG8_STAGE(PG8_SA(0, 1), a2 + hstep, voffA);
;             PG8_WAIT_L(8); PG8_BAR; PG8_WAIT_L(0); PG8_MMA(0, 0, At, B0); PG8_BAR; PG8_SCHED;
;             PG8_LDB(B1, 1, 1); PG8_STAGE(PG8_SB(1, 0), b3, voffB);
;             PG8_BAR; PG8_WAIT_L(0); PG8_MMA(0, 1, At, B1); PG8_BAR;
;             PG8_LDA(At, 1, 1); PG8_STAGE(PG8_SA(1, 0), a3, voffA);
;             PG8_BAR; PG8_WAIT_L(0); PG8_MMA(1, 0, At, B0); PG8_BAR; PG8_SCHED;
;             PG8_STAGE(PG8_SB(1, 1), b3 + hstep, voffB);
;             PG8_WAIT_V(6); PG8_BAR; PG8_MMA(1, 1, At, B1); PG8_BAR;
	s_waitcnt lgkmcnt(0)
	v_mfma_f32_16x16x32_bf16 v[60:63], v[150:153], v[166:169], v[60:63]
	v_mfma_f32_16x16x32_bf16 v[56:59], v[158:161], v[166:169], v[56:59]
	v_mfma_f32_16x16x32_bf16 v[44:47], v[150:153], v[174:177], v[44:47]
	v_mfma_f32_16x16x32_bf16 v[40:43], v[158:161], v[174:177], v[40:43]
	v_mfma_f32_16x16x32_bf16 v[28:31], v[150:153], v[182:185], v[28:31]
	v_mfma_f32_16x16x32_bf16 v[24:27], v[158:161], v[182:185], v[24:27]
	v_mfma_f32_16x16x32_bf16 v[12:15], v[150:153], v[190:193], v[12:15]
	v_mfma_f32_16x16x32_bf16 v[8:11], v[158:161], v[190:193], v[8:11]
	v_mfma_f32_16x16x32_bf16 v[60:63], v[154:157], v[170:173], v[60:63]
	v_mfma_f32_16x16x32_bf16 v[56:59], v[162:165], v[170:173], v[56:59]
	v_mfma_f32_16x16x32_bf16 v[44:47], v[154:157], v[178:181], v[44:47]
	v_mfma_f32_16x16x32_bf16 v[40:43], v[162:165], v[178:181], v[40:43]
	v_mfma_f32_16x16x32_bf16 v[28:31], v[154:157], v[186:189], v[28:31]
	v_mfma_f32_16x16x32_bf16 v[24:27], v[162:165], v[186:189], v[24:27]
	v_mfma_f32_16x16x32_bf16 v[12:15], v[154:157], v[194:197], v[12:15]
	v_mfma_f32_16x16x32_bf16 v[8:11], v[162:165], v[194:197], v[8:11]
	s_setprio 0
	s_barrier
	s_add_u32 s18, s18, 0x40080
	s_addc_u32 s19, s19, 0
	s_add_i32 s20, s20, s25
	s_mov_b32 m0, s20
	s_nop 0
	global_load_lds_dwordx4 v132, s[18:19]
	s_add_i32 m0, s20, 0x2000
	s_nop 0
	global_load_lds_dwordx4 v128, s[18:19]
	s_waitcnt vmcnt(8)
	s_setprio 1
	s_barrier
	v_mfma_f32_16x16x32_bf16 v[52:55], v[202:205], v[166:169], v[52:55]
	v_mfma_f32_16x16x32_bf16 v[48:51], v[210:213], v[166:169], v[48:51]
	v_mfma_f32_16x16x32_bf16 v[36:39], v[202:205], v[174:177], v[36:39]
	v_mfma_f32_16x16x32_bf16 v[32:35], v[210:213], v[174:177], v[32:35]
	v_mfma_f32_16x16x32_bf16 v[20:23], v[202:205], v[182:185], v[20:23]
	v_mfma_f32_16x16x32_bf16 v[16:19], v[210:213], v[182:185], v[16:19]
	v_mfma_f32_16x16x32_bf16 v[4:7], v[202:205], v[190:193], v[4:7]
	v_mfma_f32_16x16x32_bf16 v[0:3], v[210:213], v[190:193], v[0:3]
	v_mfma_f32_16x16x32_bf16 v[52:55], v[206:209], v[170:173], v[52:55]
	v_mfma_f32_16x16x32_bf16 v[48:51], v[214:217], v[170:173], v[48:51]
	v_mfma_f32_16x16x32_bf16 v[36:39], v[206:209], v[178:181], v[36:39]
	v_mfma_f32_16x16x32_bf16 v[32:35], v[214:217], v[178:181], v[32:35]
	v_mfma_f32_16x16x32_bf16 v[20:23], v[206:209], v[186:189], v[20:23]
	v_mfma_f32_16x16x32_bf16 v[16:19], v[214:217], v[186:189], v[16:19]
	v_mfma_f32_16x16x32_bf16 v[4:7], v[206:209], v[194:197], v[4:7]
	v_mfma_f32_16x16x32_bf16 v[0:3], v[214:217], v[194:197], v[0:3]
	s_setprio 0
	s_add_i32 s46, s46, 2
	s_add_u32 s16, s16, 0x100
	s_addc_u32 s17, s17, 0
	s_add_u32 s44, s44, 0x100
	s_addc_u32 s45, s45, 0
	s_cmp_gt_u32 s46, 13
	s_barrier
.LBB0_1021:
	ds_read_b128 v[150:153], v147
	ds_read_b128 v[154:157], v147 offset:1024
	ds_read_b128 v[158:161], v147 offset:2048
	ds_read_b128 v[162:165], v147 offset:3072
	s_add_u32 s18, s16, 0xfffc0080
	s_addc_u32 s19, s17, -1
	s_cmp_eq_u32 s46, 12
	s_cselect_b32 s21, s7, s19
	s_cselect_b32 s20, s42, s18
	s_cselect_b32 s19, s5, s45
	s_cselect_b32 s18, s43, s44
	s_add_i32 m0, s15, 0xc000
	ds_read_b128 v[166:169], v148
	ds_read_b128 v[170:173], v148 offset:1024
	ds_read_b128 v[174:177], v148 offset:2048
	ds_read_b128 v[178:181], v148 offset:3072
	ds_read_b128 v[182:185], v148 offset:4096
	ds_read_b128 v[186:189], v148 offset:5120
	ds_read_b128 v[190:193], v148 offset:6144
	ds_read_b128 v[194:197], v148 offset:7168
	global_load_lds_dwordx4 v136, s[16:17]
	s_add_i32 m0, s15, 0xe000
	s_nop 0
	global_load_lds_dwordx4 v138, s[16:17]
	s_waitcnt lgkmcnt(8)
	s_waitcnt vmcnt(8)
	s_setprio 1
	s_barrier
	s_waitcnt lgkmcnt(0)
	v_mfma_f32_16x16x32_bf16 v[124:127], v[150:153], v[166:169], v[124:127]
	v_mfma_f32_16x16x32_bf16 v[116:119], v[158:161], v[166:169], v[116:119]
	v_mfma_f32_16x16x32_bf16 v[108:111], v[150:153], v[174:177], v[108:111]
	v_mfma_f32_16x16x32_bf16 v[100:103], v[158:161], v[174:177], v[100:103]
	v_mfma_f32_16x16x32_bf16 v[92:95], v[150:153], v[182:185], v[92:95]
	v_mfma_f32_16x16x32_bf16 v[84:87], v[158:161], v[182:185], v[84:87]
	v_mfma_f32_16x16x32_bf16 v[76:79], v[150:153], v[190:193], v[76:79]
	v_mfma_f32_16x16x32_bf16 v[68:71], v[158:161], v[190:193], v[68:71]
	v_mfma_f32_16x16x32_bf16 v[124:127], v[154:157], v[170:173], v[124:127]
	v_mfma_f32_16x16x32_bf16 v[116:119], v[162:165], v[170:173], v[116:119]
	v_mfma_f32_16x16x32_bf16 v[108:111], v[154:157], v[178:181], v[108:111]
	v_mfma_f32_16x16x32_bf16 v[100:103], v[162:165], v[178:181], v[100:103]
	v_mfma_f32_16x16x32_bf16 v[92:95], v[154:157], v[186:189], v[92:95]
	v_mfma_f32_16x16x32_bf16 v[84:87], v[162:165], v[186:189], v[84:87]
	v_mfma_f32_16x16x32_bf16 v[76:79], v[154:157], v[194:197], v[76:79]
	v_mfma_f32_16x16x32_bf16 v[68:71], v[162:165], v[194:197], v[68:71]
	s_setprio 0
	s_barrier
	s_add_i32 s47, s38, s25
	s_mov_b32 m0, s47
	ds_read_b128 v[202:205], v149
	ds_read_b128 v[206:209], v149 offset:1024
	ds_read_b128 v[210:213], v149 offset:2048
	ds_read_b128 v[214:217], v149 offset:3072
	global_load_lds_dwordx4 v132, s[18:19]
	s_add_i32 m0, s47, 0x2000
	s_nop 0
	global_load_lds_dwordx4 v128, s[18:19]
	s_waitcnt vmcnt(8)
	s_setprio 1
	s_barrier
; #define PG8_STAGE(bufoff, gbase, voff) do { _Pragma("unroll") for (int _i = 0; _i < 2; ++_i) \
;         __builtin_amdgcn_global_load_lds((const unsigned*)((const char*)(gbase) + (voff)[_i]), (LAS unsigned*)(lds + (bufoff) + ldsw + _i * 8192), 16, 0, 0); } while (0)
; #define PG8_LDA(dst, b, h) do { _Pragma("unroll") for (int m = 0; m < 4; ++m) _Pragma("unroll") for (int k = 0; k < 2; ++k) dst[m][k] = *(const LAS bf16x8*)(lds + PG8_SA(b, h) + aoff + m * 2048 + k * 1024); } while (0)
; #define PG8_LDB(dst, b, h) do { _Pragma("unroll") for (int n = 0; n < 2; ++n) _Pragma("unroll") for (int k = 0; k < 2; ++k) dst[n][k] = *(const LAS bf16x8*)(lds + PG8_SB(b, h) + boff + n * 2048 + k * 1024); } while (0)
; #define PG8_WAIT_V(n) asm volatile("s_waitcnt vmcnt(" #n ")" ::: "memory")
; #define PG8_WAIT_L(n) asm volatile("s_waitcnt lgkmcnt(" #n ")" ::: "memory")
; #define PG8_BAR __builtin_amdgcn_s_barrier()
; #define PG8_SCHED __builtin_amdgcn_sched_barrier(0)
; template <class Epi, class Sched>
; __device__ __forceinline__ void gemm_phase(LAS unsigned char* lds, const Gemm g, const Sched& S, const Epi& E) {
;     ...
;             PG8_LDB(B0, 0, 0); PG8_SCHED; PG8_LDA(At, 0, 0); PG8_STAGE(PG8_SA(1, 1), a1 + hstep, voffA);
;             PG8_WAIT_L(8); PG8_BAR; PG8_WAIT_L(0); PG8_MMA(0, 0, At, B0); PG8_BAR; PG8_SCHED;
;             PG8_LDB(B1, 0, 1); PG8_STAGE(PG8_SB(0, 0), b2, voffB);
;             PG8_BAR; PG8_WAIT_L(0); PG8_MMA(0, 1, At, B1); PG8_BAR;
;             PG8_LDA(At, 0, 1); PG8_STAGE(PG8_SA(0, 0), a2, voffA);
;             PG8_BAR; PG8_WAIT_L(0); PG8_MMA(1, 0, At, B0); PG8_BAR; PG8_SCHED;
;             PG8_STAGE(PG8_SB(0, 1), b2 + hstep, voffB);
;             PG8_WAIT_V(6); PG8_BAR; PG8_MMA(1, 1, At, B1); PG8_BAR;
;             PG8_LDB(B0, 1, 0); PG8_SCHED; PG8_LDA(At, 1, 0); PG8_STAGE(PG8_SA(0, 1), a2 + hstep, voffA);
;             PG8_WAIT_L(8); PG8_BAR; PG8_WAIT_L(0); PG8_MMA(0, 0, At, B0); PG8_BAR; PG8_SCHED;
;             PG8_LDB(B1, 1, 1); PG8_STAGE(PG8_SB(1, 0), b3, voffB);
;             PG8_BAR; PG8_WAIT_L(0); PG8_MMA(0, 1, At, B1); PG8_BAR;
;             PG8_LDA(At, 1, 1); PG8_STAGE(PG8_SA(1, 0), a3, voffA);
;             PG8_BAR; PG8_WAIT_L(0); PG8_MMA(1, 0, At, B0); PG8_BAR; PG8_SCHED;
;             PG8_STAGE(PG8_SB(1, 1), b3 + hstep, voffB);
;             PG8_WAIT_V(6); PG8_BAR; PG8_MMA(1, 1, At, B1); PG8_BAR;
	s_waitcnt lgkmcnt(0)
	v_mfma_f32_16x16x32_bf16 v[120:123], v[202:205], v[166:169], v[120:123]
	v_mfma_f32_16x16x32_bf16 v[112:115], v[210:213], v[166:169], v[112:115]
	v_mfma_f32_16x16x32_bf16 v[104:107], v[202:205], v[174:177], v[104:107]
	v_mfma_f32_16x16x32_bf16 v[96:99], v[210:213], v[174:177], v[96:99]
	v_mfma_f32_16x16x32_bf16 v[88:91], v[202:205], v[182:185], v[88:91]
	v_mfma_f32_16x16x32_bf16 v[80:83], v[210:213], v[182:185], v[80:83]
	v_mfma_f32_16x16x32_bf16 v[72:75], v[202:205], v[190:193], v[72:75]
	v_mfma_f32_16x16x32_bf16 v[64:67], v[210:213], v[190:193], v[64:67]
	v_mfma_f32_16x16x32_bf16 v[120:123], v[206:209], v[170:173], v[120:123]
	v_mfma_f32_16x16x32_bf16 v[112:115], v[214:217], v[170:173], v[112:115]
	v_mfma_f32_16x16x32_bf16 v[104:107], v[206:209], v[178:181], v[104:107]
	v_mfma_f32_16x16x32_bf16 v[96:99], v[214:217], v[178:181], v[96:99]
	v_mfma_f32_16x16x32_bf16 v[88:91], v[206:209], v[186:189], v[88:91]
	v_mfma_f32_16x16x32_bf16 v[80:83], v[214:217], v[186:189], v[80:83]
	v_mfma_f32_16x16x32_bf16 v[72:75], v[206:209], v[194:197], v[72:75]
	v_mfma_f32_16x16x32_bf16 v[64:67], v[214:217], v[194:197], v[64:67]
	s_setprio 0
	s_mov_b32 m0, s15
	v_lshl_add_u64 v[220:221], s[20:21], 0, v[134:135]
	s_barrier
	ds_read_b128 v[166:169], v148 offset:16384
	ds_read_b128 v[170:173], v148 offset:17408
	ds_read_b128 v[174:177], v148 offset:18432
	ds_read_b128 v[178:181], v148 offset:19456
	ds_read_b128 v[182:185], v148 offset:20480
	ds_read_b128 v[186:189], v148 offset:21504
	ds_read_b128 v[190:193], v148 offset:22528
	ds_read_b128 v[194:197], v148 offset:23552
	global_load_lds_dwordx4 v134, s[20:21]
	v_lshl_add_u64 v[222:223], s[20:21], 0, v[130:131]
	s_mov_b32 m0, s28
	s_nop 0
	global_load_lds_dwordx4 v130, s[20:21]
	s_setprio 1
	s_barrier
	s_waitcnt lgkmcnt(0)
	v_mfma_f32_16x16x32_bf16 v[60:63], v[150:153], v[166:169], v[60:63]
	v_mfma_f32_16x16x32_bf16 v[56:59], v[158:161], v[166:169], v[56:59]
	v_mfma_f32_16x16x32_bf16 v[44:47], v[150:153], v[174:177], v[44:47]
	v_mfma_f32_16x16x32_bf16 v[40:43], v[158:161], v[174:177], v[40:43]
	v_mfma_f32_16x16x32_bf16 v[28:31], v[150:153], v[182:185], v[28:31]
	v_mfma_f32_16x16x32_bf16 v[24:27], v[158:161], v[182:185], v[24:27]
	v_mfma_f32_16x16x32_bf16 v[12:15], v[150:153], v[190:193], v[12:15]
	v_mfma_f32_16x16x32_bf16 v[8:11], v[158:161], v[190:193], v[8:11]
	v_mfma_f32_16x16x32_bf16 v[60:63], v[154:157], v[170:173], v[60:63]
	v_mfma_f32_16x16x32_bf16 v[56:59], v[162:165], v[170:173], v[56:59]
	v_mfma_f32_16x16x32_bf16 v[44:47], v[154:157], v[178:181], v[44:47]
	v_mfma_f32_16x16x32_bf16 v[40:43], v[162:165], v[178:181], v[40:43]
	v_mfma_f32_16x16x32_bf16 v[28:31], v[154:157], v[186:189], v[28:31]
	v_mfma_f32_16x16x32_bf16 v[24:27], v[162:165], v[186:189], v[24:27]
	v_mfma_f32_16x16x32_bf16 v[12:15], v[154:157], v[194:197], v[12:15]
	v_mfma_f32_16x16x32_bf16 v[8:11], v[162:165], v[194:197], v[8:11]
	s_setprio 0
	s_barrier
	s_add_u32 s48, s18, 0x40000
	s_addc_u32 s49, s19, 0
	s_add_i32 s47, s39, s25
	s_mov_b32 m0, s47
	s_nop 0
	global_load_lds_dwordx4 v132, s[48:49]
	s_add_i32 m0, s47, 0x2000
	s_nop 0
	global_load_lds_dwordx4 v128, s[48:49]
	s_add_u32 s20, s20, 0x40000
	s_addc_u32 s21, s21, 0
	s_mov_b32 m0, s29
	s_nop 0
	global_load_lds_dwordx4 v134, s[20:21]
	s_mov_b32 m0, s30
	s_nop 0
	global_load_lds_dwordx4 v130, s[20:21]
	s_waitcnt vmcnt(10)
	s_setprio 1
	s_barrier
	v_mfma_f32_16x16x32_bf16 v[52:55], v[202:205], v[166:169], v[52:55]
	v_mfma_f32_16x16x32_bf16 v[48:51], v[210:213], v[166:169], v[48:51]
	v_mfma_f32_16x16x32_bf16 v[36:39], v[202:205], v[174:177], v[36:39]
	v_mfma_f32_16x16x32_bf16 v[32:35], v[210:213], v[174:177], v[32:35]
	v_mfma_f32_16x16x32_bf16 v[20:23], v[202:205], v[182:185], v[20:23]
	v_mfma_f32_16x16x32_bf16 v[16:19], v[210:213], v[182:185], v[16:19]
	v_mfma_f32_16x16x32_bf16 v[4:7], v[202:205], v[190:193], v[4:7]
	v_mfma_f32_16x16x32_bf16 v[0:3], v[210:213], v[190:193], v[0:3]
	v_mfma_f32_16x16x32_bf16 v[52:55], v[206:209], v[170:173], v[52:55]
	v_mfma_f32_16x16x32_bf16 v[48:51], v[214:217], v[170:173], v[48:51]
	v_mfma_f32_16x16x32_bf16 v[36:39], v[206:209], v[178:181], v[36:39]
	v_mfma_f32_16x16x32_bf16 v[32:35], v[214:217], v[178:181], v[32:35]
	v_mfma_f32_16x16x32_bf16 v[20:23], v[206:209], v[186:189], v[20:23]
	v_mfma_f32_16x16x32_bf16 v[16:19], v[214:217], v[186:189], v[16:19]
	v_mfma_f32_16x16x32_bf16 v[4:7], v[206:209], v[194:197], v[4:7]
	v_mfma_f32_16x16x32_bf16 v[0:3], v[214:217], v[194:197], v[0:3]
	s_setprio 0
	s_add_i32 s47, 0, 0x18000
	v_add_u32_e32 v162, s47, v146
	s_barrier
	ds_read_b128 v[150:153], v162
	ds_read_b128 v[154:157], v162 offset:1024
	ds_read_b128 v[158:161], v162 offset:2048
	ds_read_b128 v[162:165], v162 offset:3072
	ds_read_b128 v[166:169], v148 offset:32768
	ds_read_b128 v[170:173], v148 offset:33792
	ds_read_b128 v[174:177], v148 offset:34816
	ds_read_b128 v[178:181], v148 offset:35840
	ds_read_b128 v[182:185], v148 offset:36864
	ds_read_b128 v[186:189], v148 offset:37888
	ds_read_b128 v[190:193], v148 offset:38912
	ds_read_b128 v[194:197], v148 offset:39936
	s_waitcnt lgkmcnt(8)
	s_waitcnt vmcnt(8)
	s_setprio 1
	s_barrier
; #define PG8_STAGE(bufoff, gbase, voff) do { _Pragma("unroll") for (int _i = 0; _i < 2; ++_i) \
;         __builtin_amdgcn_global_load_lds((const unsigned*)((const char*)(gbase) + (voff)[_i]), (LAS unsigned*)(lds + (bufoff) + ldsw + _i * 8192), 16, 0, 0); } while (0)
; #define PG8_LDA(dst, b, h) do { _Pragma("unroll") for (int m = 0; m < 4; ++m) _Pragma("unroll") for (int k = 0; k < 2; ++k) dst[m][k] = *(const LAS bf16x8*)(lds + PG8_SA(b, h) + aoff + m * 2048 + k * 1024); } while (0)
; #define PG8_LDB(dst, b, h) do { _Pragma("unroll") for (int n = 0; n < 2; ++n) _Pragma("unroll") for (int k = 0; k < 2; ++k) dst[n][k] = *(const LAS bf16x8*)(lds + PG8_SB(b, h) + boff + n * 2048 + k * 1024); } while (0)
; #define PG8_WAIT_V(n) asm volatile("s_waitcnt vmcnt(" #n ")" ::: "memory")
; #define PG8_WAIT_L(n) asm volatile("s_waitcnt lgkmcnt(" #n ")" ::: "memory")
; #define PG8_BAR __builtin_amdgcn_s_barrier()
; #define PG8_SCHED __builtin_amdgcn_sched_barrier(0)
; template <class Epi, class Sched>
; __device__ __forceinline__ void gemm_phase(LAS unsigned char* lds, const Gemm g, const Sched& S, const Epi& E) {
;     ...
;             PG8_LDB(B0, 0, 0); PG8_SCHED; PG8_LDA(At, 0, 0); PG8_STAGE(PG8_SA(1, 1), a1 + hstep, voffA);
;             PG8_WAIT_L(8); PG8_BAR; PG8_WAIT_L(0); PG8_MMA(0, 0, At, B0); PG8_BAR; PG8_SCHED;
;             PG8_LDB(B1, 0, 1); PG8_STAGE(PG8_SB(0, 0), b2, voffB);
;             PG8_BAR; PG8_WAIT_L(0); PG8_MMA(0, 1, At, B1); PG8_BAR;
;             PG8_LDA(At, 0, 1); PG8_STAGE(PG8_SA(0, 0), a2, voffA);
;             PG8_BAR; PG8_WAIT_L(0); PG8_MMA(1, 0, At, B0); PG8_BAR; PG8_SCHED;
;             PG8_STAGE(PG8_SB(0, 1), b2 + hstep, voffB);
;             PG8_WAIT_V(6); PG8_BAR; PG8_MMA(1, 1, At, B1); PG8_BAR;
;             PG8_LDB(B0, 1, 0); PG8_SCHED; PG8_LDA(At, 1, 0); PG8_STAGE(PG8_SA(0, 1), a2 + hstep, voffA);
;             PG8_WAIT_L(8); PG8_BAR; PG8_WAIT_L(0); PG8_MMA(0, 0, At, B0); PG8_BAR; PG8_SCHED;
;             PG8_LDB(B1, 1, 1); PG8_STAGE(PG8_SB(1, 0), b3, voffB);
;             PG8_BAR; PG8_WAIT_L(0); PG8_MMA(0, 1, At, B1); PG8_BAR;
;             PG8_LDA(At, 1, 1); PG8_STAGE(PG8_SA(1, 0), a3, voffA);
;             PG8_BAR; PG8_WAIT_L(0); PG8_MMA(1, 0, At, B0); PG8_BAR; PG8_SCHED;
;             PG8_STAGE(PG8_SB(1, 1), b3 + hstep, voffB);
;             PG8_WAIT_V(6); PG8_BAR; PG8_MMA(1, 1, At, B1); PG8_BAR;
	s_waitcnt lgkmcnt(0)
	v_mfma_f32_16x16x32_bf16 v[124:127], v[150:153], v[166:169], v[124:127]
	v_mfma_f32_16x16x32_bf16 v[116:119], v[158:161], v[166:169], v[116:119]
	v_mfma_f32_16x16x32_bf16 v[108:111], v[150:153], v[174:177], v[108:111]
	v_mfma_f32_16x16x32_bf16 v[100:103], v[158:161], v[174:177], v[100:103]
	v_mfma_f32_16x16x32_bf16 v[92:95], v[150:153], v[182:185], v[92:95]
	v_mfma_f32_16x16x32_bf16 v[84:87], v[158:161], v[182:185], v[84:87]
	v_mfma_f32_16x16x32_bf16 v[76:79], v[150:153], v[190:193], v[76:79]
	v_mfma_f32_16x16x32_bf16 v[68:71], v[158:161], v[190:193], v[68:71]
	v_mfma_f32_16x16x32_bf16 v[124:127], v[154:157], v[170:173], v[124:127]
	v_mfma_f32_16x16x32_bf16 v[116:119], v[162:165], v[170:173], v[116:119]
	v_mfma_f32_16x16x32_bf16 v[108:111], v[154:157], v[178:181], v[108:111]
	v_mfma_f32_16x16x32_bf16 v[100:103], v[162:165], v[178:181], v[100:103]
	v_mfma_f32_16x16x32_bf16 v[92:95], v[154:157], v[186:189], v[92:95]
	v_mfma_f32_16x16x32_bf16 v[84:87], v[162:165], v[186:189], v[84:87]
	v_mfma_f32_16x16x32_bf16 v[76:79], v[154:157], v[194:197], v[76:79]
	v_mfma_f32_16x16x32_bf16 v[68:71], v[162:165], v[194:197], v[68:71]
	s_setprio 0
	s_barrier
	s_add_i32 s20, 0, 0x1c000
	s_add_i32 s21, s47, s25
	v_add_u32_e32 v214, s20, v146
	s_add_u32 s0, s18, 0x80
	s_addc_u32 s1, s19, 0
	s_mov_b32 m0, s21
	ds_read_b128 v[202:205], v214
	ds_read_b128 v[206:209], v214 offset:1024
	ds_read_b128 v[210:213], v214 offset:2048
	ds_read_b128 v[214:217], v214 offset:3072
	global_load_lds_dwordx4 v132, s[0:1]
	s_add_i32 m0, s21, 0x2000
	s_nop 0
	global_load_lds_dwordx4 v128, s[0:1]
	s_waitcnt vmcnt(8)
	s_setprio 1
	s_barrier
	s_waitcnt lgkmcnt(0)
	v_mfma_f32_16x16x32_bf16 v[120:123], v[202:205], v[166:169], v[120:123]
	v_mfma_f32_16x16x32_bf16 v[112:115], v[210:213], v[166:169], v[112:115]
	v_mfma_f32_16x16x32_bf16 v[104:107], v[202:205], v[174:177], v[104:107]
	v_mfma_f32_16x16x32_bf16 v[96:99], v[210:213], v[174:177], v[96:99]
	v_mfma_f32_16x16x32_bf16 v[88:91], v[202:205], v[182:185], v[88:91]
	v_mfma_f32_16x16x32_bf16 v[80:83], v[210:213], v[182:185], v[80:83]
	v_mfma_f32_16x16x32_bf16 v[72:75], v[202:205], v[190:193], v[72:75]
	v_mfma_f32_16x16x32_bf16 v[64:67], v[210:213], v[190:193], v[64:67]
	v_mfma_f32_16x16x32_bf16 v[120:123], v[206:209], v[170:173], v[120:123]
	v_mfma_f32_16x16x32_bf16 v[112:115], v[214:217], v[170:173], v[112:115]
	v_mfma_f32_16x16x32_bf16 v[104:107], v[206:209], v[178:181], v[104:107]
	v_mfma_f32_16x16x32_bf16 v[96:99], v[214:217], v[178:181], v[96:99]
	v_mfma_f32_16x16x32_bf16 v[88:91], v[206:209], v[186:189], v[88:91]
	v_mfma_f32_16x16x32_bf16 v[80:83], v[214:217], v[186:189], v[80:83]
	v_mfma_f32_16x16x32_bf16 v[72:75], v[206:209], v[194:197], v[72:75]
	v_mfma_f32_16x16x32_bf16 v[64:67], v[214:217], v[194:197], v[64:67]
	s_setprio 0
	s_mov_b32 m0, s35
	s_mov_b64 s[0:1], 0x80
	v_lshl_add_u64 v[198:199], v[220:221], 0, s[0:1]
	s_barrier
	ds_read_b128 v[166:169], v148 offset:49152
	ds_read_b128 v[170:173], v148 offset:50176
	ds_read_b128 v[174:177], v148 offset:51200
	ds_read_b128 v[178:181], v148 offset:52224
	ds_read_b128 v[182:185], v148 offset:53248
	ds_read_b128 v[186:189], v148 offset:54272
	ds_read_b128 v[190:193], v148 offset:55296
	ds_read_b128 v[194:197], v148 offset:56320
	global_load_lds_dwordx4 v[198:199], off
	v_lshl_add_u64 v[198:199], v[222:223], 0, s[0:1]
	s_mov_b32 m0, s36
	s_nop 0
	global_load_lds_dwordx4 v[198:199], off
	s_setprio 1
	s_barrier
	s_waitcnt lgkmcnt(0)
	v_mfma_f32_16x16x32_bf16 v[60:63], v[150:153], v[166:169], v[60:63]
	v_mfma_f32_16x16x32_bf16 v[56:59], v[158:161], v[166:169], v[56:59]
	v_mfma_f32_16x16x32_bf16 v[44:47], v[150:153], v[174:177], v[44:47]
	v_mfma_f32_16x16x32_bf16 v[40:43], v[158:161], v[174:177], v[40:43]
	v_mfma_f32_16x16x32_bf16 v[28:31], v[150:153], v[182:185], v[28:31]
	v_mfma_f32_16x16x32_bf16 v[24:27], v[158:161], v[182:185], v[24:27]
	v_mfma_f32_16x16x32_bf16 v[12:15], v[150:153], v[190:193], v[12:15]
	v_mfma_f32_16x16x32_bf16 v[8:11], v[158:161], v[190:193], v[8:11]
	v_mfma_f32_16x16x32_bf16 v[60:63], v[154:157], v[170:173], v[60:63]
	v_mfma_f32_16x16x32_bf16 v[56:59], v[162:165], v[170:173], v[56:59]
	v_mfma_f32_16x16x32_bf16 v[44:47], v[154:157], v[178:181], v[44:47]
	v_mfma_f32_16x16x32_bf16 v[40:43], v[162:165], v[178:181], v[40:43]
	v_mfma_f32_16x16x32_bf16 v[28:31], v[154:157], v[186:189], v[28:31]
	v_mfma_f32_16x16x32_bf16 v[24:27], v[162:165], v[186:189], v[24:27]
	v_mfma_f32_16x16x32_bf16 v[12:15], v[154:157], v[194:197], v[12:15]
	v_mfma_f32_16x16x32_bf16 v[8:11], v[162:165], v[194:197], v[8:11]
	s_setprio 0
	s_barrier
	s_add_u32 s18, s18, 0x40080
	s_addc_u32 s19, s19, 0
	s_add_i32 s20, s20, s25
	s_mov_b32 m0, s20
	s_nop 0
	global_load_lds_dwordx4 v132, s[18:19]
	s_add_i32 m0, s20, 0x2000
	s_nop 0
	global_load_lds_dwordx4 v128, s[18:19]
	s_waitcnt vmcnt(8)
	s_setprio 1
	s_barrier
	v_mfma_f32_16x16x32_bf16 v[52:55], v[202:205], v[166:169], v[52:55]
	v_mfma_f32_16x16x32_bf16 v[48:51], v[210:213], v[166:169], v[48:51]
	v_mfma_f32_16x16x32_bf16 v[36:39], v[202:205], v[174:177], v[36:39]
	v_mfma_f32_16x16x32_bf16 v[32:35], v[210:213], v[174:177], v[32:35]
	v_mfma_f32_16x16x32_bf16 v[20:23], v[202:205], v[182:185], v[20:23]
	v_mfma_f32_16x16x32_bf16 v[16:19], v[210:213], v[182:185], v[16:19]
	v_mfma_f32_16x16x32_bf16 v[4:7], v[202:205], v[190:193], v[4:7]
	v_mfma_f32_16x16x32_bf16 v[0:3], v[210:213], v[190:193], v[0:3]
	v_mfma_f32_16x16x32_bf16 v[52:55], v[206:209], v[170:173], v[52:55]
	v_mfma_f32_16x16x32_bf16 v[48:51], v[214:217], v[170:173], v[48:51]
	v_mfma_f32_16x16x32_bf16 v[36:39], v[206:209], v[178:181], v[36:39]
	v_mfma_f32_16x16x32_bf16 v[32:35], v[214:217], v[178:181], v[32:35]
	v_mfma_f32_16x16x32_bf16 v[20:23], v[206:209], v[186:189], v[20:23]
	v_mfma_f32_16x16x32_bf16 v[16:19], v[214:217], v[186:189], v[16:19]
	v_mfma_f32_16x16x32_bf16 v[4:7], v[206:209], v[194:197], v[4:7]
	v_mfma_f32_16x16x32_bf16 v[0:3], v[214:217], v[194:197], v[0:3]
	s_setprio 0
	s_add_i32 s46, s46, 2
	s_add_u32 s16, s16, 0x100
	s_addc_u32 s17, s17, 0
	s_add_u32 s44, s44, 0x100
	s_addc_u32 s45, s45, 0
	s_cmp_gt_u32 s46, 13
	s_cbranch_scc1 .Lconc_last_g11
	s_barrier
	s_branch .LBB0_1021

; #define PG8_STAGE(bufoff, gbase, voff) do { _Pragma("unroll") for (int _i = 0; _i < 2; ++_i) \
;         __builtin_amdgcn_global_load_lds((const unsigned*)((const char*)(gbase) + (voff)[_i]), (LAS unsigned*)(lds + (bufoff) + ldsw + _i * 8192), 16, 0, 0); } while (0)
; #define PG8_WAIT_V(n) asm volatile("s_waitcnt vmcnt(" #n ")" ::: "memory")
; #define PG8_WAIT_L(n) asm volatile("s_waitcnt lgkmcnt(" #n ")" ::: "memory")
; template <class Epi, class Sched>
; __device__ __forceinline__ void gemm_phase(LAS unsigned char* lds, const Gemm g, const Sched& S, const Epi& E) {
;     ...
;         const bool has_next = S.next(ui + 1, nxt);
;         const char* nA = has_next ? (const char*)g.A + (size_t)nxt.pm * tstep : cA; const char* nB = has_next ? (const char*)g.Bt + (size_t)nxt.pn * tstep : cB;
;         for (int t = 0; t < nt; t += 2) {
;             const bool last = (t == nt - 2);
;             const char* a1 = cA + (size_t)(t + 1) * kstep;
;             const char* a2 = last ? nA : cA + (size_t)(t + 2) * kstep; const char* b2 = last ? nB : cB + (size_t)(t + 2) * kstep;
;             const char* a3 = a2 + kstep; const char* b3 = b2 + kstep;
;             PG8_LDB(B0, 0, 0); PG8_SCHED; PG8_LDA(At, 0, 0); PG8_STAGE(PG8_SA(1, 1), a1 + hstep, voffA);
;             PG8_WAIT_L(8); PG8_BAR; PG8_WAIT_L(0); PG8_MMA(0, 0, At, B0); PG8_BAR; PG8_SCHED;
;             PG8_LDB(B1, 0, 1); PG8_STAGE(PG8_SB(0, 0), b2, voffB);
;             PG8_BAR; PG8_WAIT_L(0); PG8_MMA(0, 1, At, B1); PG8_BAR;
;             PG8_LDA(At, 0, 1); PG8_STAGE(PG8_SA(0, 0), a2, voffA);
;             PG8_BAR; PG8_WAIT_L(0); PG8_MMA(1, 0, At, B0); PG8_BAR; PG8_SCHED;
;             PG8_STAGE(PG8_SB(0, 1), b2 + hstep, voffB);
;             PG8_WAIT_V(6); PG8_BAR; PG8_MMA(1, 1, At, B1); PG8_BAR;
;             PG8_LDB(B0, 1, 0); PG8_SCHED; PG8_LDA(At, 1, 0); PG8_STAGE(PG8_SA(0, 1), a2 + hstep, voffA);
;             PG8_WAIT_L(8); PG8_BAR; PG8_WAIT_L(0); PG8_MMA(0, 0, At, B0); PG8_BAR; PG8_SCHED;
;             PG8_LDB(B1, 1, 1); PG8_STAGE(PG8_SB(1, 0), b3, voffB);
;             PG8_BAR; PG8_WAIT_L(0); PG8_MMA(0, 1, At, B1); PG8_BAR;
;             PG8_LDA(At, 1, 1); PG8_STAGE(PG8_SA(1, 0), a3, voffA);
;             PG8_BAR; PG8_WAIT_L(0); PG8_MMA(1, 0, At, B0); PG8_BAR; PG8_SCHED;
;             PG8_STAGE(PG8_SB(1, 1), b3 + hstep, voffB);
;             PG8_WAIT_V(6); PG8_BAR; PG8_MMA(1, 1, At, B1); PG8_BAR;
.LBB0_1096:
	s_add_u32 s54, s24, 0x100
	s_addc_u32 s55, s25, 0
	s_mov_b32 s56, -2
	ds_read_b128 v[128:131], v241
	ds_read_b128 v[132:135], v241 offset:1024
	ds_read_b128 v[136:139], v241 offset:2048
	ds_read_b128 v[140:143], v241 offset:3072
	s_add_u32 s24, s22, 0x100
	s_addc_u32 s25, s23, 0
	s_cmp_eq_u32 s56, 40
	s_cselect_b32 s29, s5, s25
	s_cselect_b32 s28, s4, s24
	s_cselect_b32 s27, s7, s55
	s_cselect_b32 s26, s6, s54
	v_lshl_add_u64 v[176:177], s[22:23], 0, v[196:197]
	s_add_i32 m0, s35, 0xc000
	ds_read_b128 v[144:147], v242
	ds_read_b128 v[148:151], v242 offset:1024
	ds_read_b128 v[152:155], v242 offset:2048
	ds_read_b128 v[156:159], v242 offset:3072
	ds_read_b128 v[160:163], v242 offset:4096
	ds_read_b128 v[164:167], v242 offset:5120
	ds_read_b128 v[168:171], v242 offset:6144
	ds_read_b128 v[172:175], v242 offset:7168
	global_load_lds_dwordx4 v[176:177], off
	v_lshl_add_u64 v[176:177], s[22:23], 0, v[198:199]
	s_add_i32 m0, s35, 0xe000
	s_nop 0
	global_load_lds_dwordx4 v[176:177], off
	s_waitcnt lgkmcnt(8)
	s_waitcnt vmcnt(8)
	s_setprio 1
	s_barrier
	s_waitcnt lgkmcnt(0)
	v_mfma_f32_16x16x32_bf16 v[124:127], v[128:131], v[144:147], 0
	v_mfma_f32_16x16x32_bf16 v[120:123], v[136:139], v[144:147], 0
	v_mfma_f32_16x16x32_bf16 v[108:111], v[128:131], v[152:155], 0
	v_mfma_f32_16x16x32_bf16 v[104:107], v[136:139], v[152:155], 0
	v_mfma_f32_16x16x32_bf16 v[92:95], v[128:131], v[160:163], 0
	v_mfma_f32_16x16x32_bf16 v[88:91], v[136:139], v[160:163], 0
	v_mfma_f32_16x16x32_bf16 v[76:79], v[128:131], v[168:171], 0
	v_mfma_f32_16x16x32_bf16 v[72:75], v[136:139], v[168:171], 0
	v_mfma_f32_16x16x32_bf16 v[124:127], v[132:135], v[148:151], v[124:127]
	v_mfma_f32_16x16x32_bf16 v[120:123], v[140:143], v[148:151], v[120:123]
	v_mfma_f32_16x16x32_bf16 v[108:111], v[132:135], v[156:159], v[108:111]
	v_mfma_f32_16x16x32_bf16 v[104:107], v[140:143], v[156:159], v[104:107]
	v_mfma_f32_16x16x32_bf16 v[92:95], v[132:135], v[164:167], v[92:95]
	v_mfma_f32_16x16x32_bf16 v[88:91], v[140:143], v[164:167], v[88:91]
	v_mfma_f32_16x16x32_bf16 v[76:79], v[132:135], v[172:175], v[76:79]
	v_mfma_f32_16x16x32_bf16 v[72:75], v[140:143], v[172:175], v[72:75]
	s_setprio 0
	s_barrier
	s_add_i32 s22, s48, s34
	s_mov_b32 m0, s22
	ds_read_b128 v[176:179], v243
	ds_read_b128 v[180:183], v243 offset:1024
	ds_read_b128 v[184:187], v243 offset:2048
	ds_read_b128 v[206:209], v243 offset:3072
	global_load_lds_dwordx4 v190, s[26:27]
	s_add_i32 m0, s22, 0x2000
	s_nop 0
	global_load_lds_dwordx4 v194, s[26:27]
	s_waitcnt vmcnt(8)
	s_setprio 1
	s_barrier
	s_waitcnt lgkmcnt(0)
	v_mfma_f32_16x16x32_bf16 v[116:119], v[176:179], v[144:147], 0
	v_mfma_f32_16x16x32_bf16 v[112:115], v[184:187], v[144:147], 0
	v_mfma_f32_16x16x32_bf16 v[100:103], v[176:179], v[152:155], 0
	v_mfma_f32_16x16x32_bf16 v[96:99], v[184:187], v[152:155], 0
	v_mfma_f32_16x16x32_bf16 v[84:87], v[176:179], v[160:163], 0
	v_mfma_f32_16x16x32_bf16 v[80:83], v[184:187], v[160:163], 0
	v_mfma_f32_16x16x32_bf16 v[68:71], v[176:179], v[168:171], 0
	v_mfma_f32_16x16x32_bf16 v[64:67], v[184:187], v[168:171], 0
	v_mfma_f32_16x16x32_bf16 v[116:119], v[180:183], v[148:151], v[116:119]
	v_mfma_f32_16x16x32_bf16 v[112:115], v[206:209], v[148:151], v[112:115]
	v_mfma_f32_16x16x32_bf16 v[100:103], v[180:183], v[156:159], v[100:103]
	v_mfma_f32_16x16x32_bf16 v[96:99], v[206:209], v[156:159], v[96:99]
	v_mfma_f32_16x16x32_bf16 v[84:87], v[180:183], v[164:167], v[84:87]
	v_mfma_f32_16x16x32_bf16 v[80:83], v[206:209], v[164:167], v[80:83]
	v_mfma_f32_16x16x32_bf16 v[68:71], v[180:183], v[172:175], v[68:71]
	v_mfma_f32_16x16x32_bf16 v[64:67], v[206:209], v[172:175], v[64:67]
	s_setprio 0
	s_mov_b32 m0, s35
	v_lshl_add_u64 v[214:215], s[28:29], 0, v[188:189]
	s_barrier
	ds_read_b128 v[144:147], v242 offset:16384
	ds_read_b128 v[148:151], v242 offset:17408
	ds_read_b128 v[152:155], v242 offset:18432
	ds_read_b128 v[156:159], v242 offset:19456
	ds_read_b128 v[160:163], v242 offset:20480
	ds_read_b128 v[164:167], v242 offset:21504
	ds_read_b128 v[168:171], v242 offset:22528
	ds_read_b128 v[172:175], v242 offset:23552
	global_load_lds_dwordx4 v188, s[28:29]
	v_lshl_add_u64 v[216:217], s[28:29], 0, v[192:193]
	s_mov_b32 m0, s36
	s_nop 0
	global_load_lds_dwordx4 v192, s[28:29]
	s_setprio 1
	s_barrier
	s_waitcnt lgkmcnt(0)
	v_mfma_f32_16x16x32_bf16 v[60:63], v[128:131], v[144:147], 0
	v_mfma_f32_16x16x32_bf16 v[56:59], v[136:139], v[144:147], 0
	v_mfma_f32_16x16x32_bf16 v[44:47], v[128:131], v[152:155], 0
	v_mfma_f32_16x16x32_bf16 v[40:43], v[136:139], v[152:155], 0
	v_mfma_f32_16x16x32_bf16 v[28:31], v[128:131], v[160:163], 0
	v_mfma_f32_16x16x32_bf16 v[24:27], v[136:139], v[160:163], 0
	v_mfma_f32_16x16x32_bf16 v[12:15], v[128:131], v[168:171], 0
	v_mfma_f32_16x16x32_bf16 v[8:11], v[136:139], v[168:171], 0
	v_mfma_f32_16x16x32_bf16 v[60:63], v[132:135], v[148:151], v[60:63]
	v_mfma_f32_16x16x32_bf16 v[56:59], v[140:143], v[148:151], v[56:59]
	v_mfma_f32_16x16x32_bf16 v[44:47], v[132:135], v[156:159], v[44:47]
	v_mfma_f32_16x16x32_bf16 v[40:43], v[140:143], v[156:159], v[40:43]
	v_mfma_f32_16x16x32_bf16 v[28:31], v[132:135], v[164:167], v[28:31]
	v_mfma_f32_16x16x32_bf16 v[24:27], v[140:143], v[164:167], v[24:27]
	v_mfma_f32_16x16x32_bf16 v[12:15], v[132:135], v[172:175], v[12:15]
	v_mfma_f32_16x16x32_bf16 v[8:11], v[140:143], v[172:175], v[8:11]
	s_setprio 0
	s_barrier
	s_add_u32 s22, s26, 0xb0000
	s_addc_u32 s23, s27, 0
	s_add_i32 s57, s49, s34
	s_mov_b32 m0, s57
	s_nop 0
	global_load_lds_dwordx4 v190, s[22:23]
	s_add_i32 m0, s57, 0x2000
	s_nop 0
	global_load_lds_dwordx4 v194, s[22:23]
	s_add_u32 s22, s28, 0xb0000
	s_addc_u32 s23, s29, 0
	s_mov_b32 m0, s37
	s_nop 0
	global_load_lds_dwordx4 v188, s[22:23]
	s_mov_b32 m0, s38
	s_nop 0
	global_load_lds_dwordx4 v192, s[22:23]
	s_waitcnt vmcnt(10)
	s_setprio 1
	s_barrier
; #define PG8_STAGE(bufoff, gbase, voff) do { _Pragma("unroll") for (int _i = 0; _i < 2; ++_i) \
;         __builtin_amdgcn_global_load_lds((const unsigned*)((const char*)(gbase) + (voff)[_i]), (LAS unsigned*)(lds + (bufoff) + ldsw + _i * 8192), 16, 0, 0); } while (0)
; #define PG8_LDA(dst, b, h) do { _Pragma("unroll") for (int m = 0; m < 4; ++m) _Pragma("unroll") for (int k = 0; k < 2; ++k) dst[m][k] = *(const LAS bf16x8*)(lds + PG8_SA(b, h) + aoff + m * 2048 + k * 1024); } while (0)
; #define PG8_LDB(dst, b, h) do { _Pragma("unroll") for (int n = 0; n < 2; ++n) _Pragma("unroll") for (int k = 0; k < 2; ++k) dst[n][k] = *(const LAS bf16x8*)(lds + PG8_SB(b, h) + boff + n * 2048 + k * 1024); } while (0)
; #define PG8_WAIT_V(n) asm volatile("s_waitcnt vmcnt(" #n ")" ::: "memory")
; #define PG8_WAIT_L(n) asm volatile("s_waitcnt lgkmcnt(" #n ")" ::: "memory")
; #define PG8_BAR __builtin_amdgcn_s_barrier()
; #define PG8_SCHED __builtin_amdgcn_sched_barrier(0)
; template <class Epi, class Sched>
; __device__ __forceinline__ void gemm_phase(LAS unsigned char* lds, const Gemm g, const Sched& S, const Epi& E) {
;     ...
;             PG8_LDB(B0, 0, 0); PG8_SCHED; PG8_LDA(At, 0, 0); PG8_STAGE(PG8_SA(1, 1), a1 + hstep, voffA);
;             PG8_WAIT_L(8); PG8_BAR; PG8_WAIT_L(0); PG8_MMA(0, 0, At, B0); PG8_BAR; PG8_SCHED;
;             PG8_LDB(B1, 0, 1); PG8_STAGE(PG8_SB(0, 0), b2, voffB);
;             PG8_BAR; PG8_WAIT_L(0); PG8_MMA(0, 1, At, B1); PG8_BAR;
;             PG8_LDA(At, 0, 1); PG8_STAGE(PG8_SA(0, 0), a2, voffA);
;             PG8_BAR; PG8_WAIT_L(0); PG8_MMA(1, 0, At, B0); PG8_BAR; PG8_SCHED;
;             PG8_STAGE(PG8_SB(0, 1), b2 + hstep, voffB);
;             PG8_WAIT_V(6); PG8_BAR; PG8_MMA(1, 1, At, B1); PG8_BAR;
;             PG8_LDB(B0, 1, 0); PG8_SCHED; PG8_LDA(At, 1, 0); PG8_STAGE(PG8_SA(0, 1), a2 + hstep, voffA);
;             PG8_WAIT_L(8); PG8_BAR; PG8_WAIT_L(0); PG8_MMA(0, 0, At, B0); PG8_BAR; PG8_SCHED;
;             PG8_LDB(B1, 1, 1); PG8_STAGE(PG8_SB(1, 0), b3, voffB);
;             PG8_BAR; PG8_WAIT_L(0); PG8_MMA(0, 1, At, B1); PG8_BAR;
;             PG8_LDA(At, 1, 1); PG8_STAGE(PG8_SA(1, 0), a3, voffA);
;             PG8_BAR; PG8_WAIT_L(0); PG8_MMA(1, 0, At, B0); PG8_BAR; PG8_SCHED;
;             PG8_STAGE(PG8_SB(1, 1), b3 + hstep, voffB);
;             PG8_WAIT_V(6); PG8_BAR; PG8_MMA(1, 1, At, B1); PG8_BAR;
	v_mfma_f32_16x16x32_bf16 v[52:55], v[176:179], v[144:147], 0
	v_mfma_f32_16x16x32_bf16 v[48:51], v[184:187], v[144:147], 0
	v_mfma_f32_16x16x32_bf16 v[36:39], v[176:179], v[152:155], 0
	v_mfma_f32_16x16x32_bf16 v[32:35], v[184:187], v[152:155], 0
	v_mfma_f32_16x16x32_bf16 v[20:23], v[176:179], v[160:163], 0
	v_mfma_f32_16x16x32_bf16 v[16:19], v[184:187], v[160:163], 0
	v_mfma_f32_16x16x32_bf16 v[4:7], v[176:179], v[168:171], 0
	v_mfma_f32_16x16x32_bf16 v[0:3], v[184:187], v[168:171], 0
	v_mfma_f32_16x16x32_bf16 v[52:55], v[180:183], v[148:151], v[52:55]
	v_mfma_f32_16x16x32_bf16 v[48:51], v[206:209], v[148:151], v[48:51]
	v_mfma_f32_16x16x32_bf16 v[36:39], v[180:183], v[156:159], v[36:39]
	v_mfma_f32_16x16x32_bf16 v[32:35], v[206:209], v[156:159], v[32:35]
	v_mfma_f32_16x16x32_bf16 v[20:23], v[180:183], v[164:167], v[20:23]
	v_mfma_f32_16x16x32_bf16 v[16:19], v[206:209], v[164:167], v[16:19]
	v_mfma_f32_16x16x32_bf16 v[4:7], v[180:183], v[172:175], v[4:7]
	v_mfma_f32_16x16x32_bf16 v[0:3], v[206:209], v[172:175], v[0:3]
	s_setprio 0
	s_add_i32 s57, 0, 0x18000
	v_add_u32_e32 v140, s57, v240
	s_barrier
	ds_read_b128 v[128:131], v140
	ds_read_b128 v[132:135], v140 offset:1024
	ds_read_b128 v[136:139], v140 offset:2048
	ds_read_b128 v[140:143], v140 offset:3072
	ds_read_b128 v[144:147], v242 offset:32768
	ds_read_b128 v[148:151], v242 offset:33792
	ds_read_b128 v[152:155], v242 offset:34816
	ds_read_b128 v[156:159], v242 offset:35840
	ds_read_b128 v[160:163], v242 offset:36864
	ds_read_b128 v[164:167], v242 offset:37888
	ds_read_b128 v[168:171], v242 offset:38912
	ds_read_b128 v[172:175], v242 offset:39936
	s_waitcnt lgkmcnt(8)
	s_waitcnt vmcnt(8)
	s_setprio 1
	s_barrier
	s_waitcnt lgkmcnt(0)
	v_mfma_f32_16x16x32_bf16 v[124:127], v[128:131], v[144:147], v[124:127]
	v_mfma_f32_16x16x32_bf16 v[120:123], v[136:139], v[144:147], v[120:123]
	v_mfma_f32_16x16x32_bf16 v[108:111], v[128:131], v[152:155], v[108:111]
	v_mfma_f32_16x16x32_bf16 v[104:107], v[136:139], v[152:155], v[104:107]
	v_mfma_f32_16x16x32_bf16 v[92:95], v[128:131], v[160:163], v[92:95]
	v_mfma_f32_16x16x32_bf16 v[88:91], v[136:139], v[160:163], v[88:91]
	v_mfma_f32_16x16x32_bf16 v[76:79], v[128:131], v[168:171], v[76:79]
	v_mfma_f32_16x16x32_bf16 v[72:75], v[136:139], v[168:171], v[72:75]
	v_mfma_f32_16x16x32_bf16 v[124:127], v[132:135], v[148:151], v[124:127]
	v_mfma_f32_16x16x32_bf16 v[120:123], v[140:143], v[148:151], v[120:123]
	v_mfma_f32_16x16x32_bf16 v[108:111], v[132:135], v[156:159], v[108:111]
	v_mfma_f32_16x16x32_bf16 v[104:107], v[140:143], v[156:159], v[104:107]
	v_mfma_f32_16x16x32_bf16 v[92:95], v[132:135], v[164:167], v[92:95]
	v_mfma_f32_16x16x32_bf16 v[88:91], v[140:143], v[164:167], v[88:91]
	v_mfma_f32_16x16x32_bf16 v[76:79], v[132:135], v[172:175], v[76:79]
	v_mfma_f32_16x16x32_bf16 v[72:75], v[140:143], v[172:175], v[72:75]
	s_setprio 0
	s_barrier
	s_add_i32 s28, 0, 0x1c000
	s_add_i32 s22, s57, s34
	v_add_u32_e32 v206, s28, v240
	s_add_u32 s0, s26, 0x80
	s_addc_u32 s1, s27, 0
	s_mov_b32 m0, s22
	ds_read_b128 v[176:179], v206
	ds_read_b128 v[180:183], v206 offset:1024
	ds_read_b128 v[184:187], v206 offset:2048
	ds_read_b128 v[206:209], v206 offset:3072
	global_load_lds_dwordx4 v190, s[0:1]
	s_add_i32 m0, s22, 0x2000
	s_nop 0
	global_load_lds_dwordx4 v194, s[0:1]
	s_waitcnt vmcnt(8)
	s_setprio 1
	s_barrier
	s_waitcnt lgkmcnt(0)
	v_mfma_f32_16x16x32_bf16 v[116:119], v[176:179], v[144:147], v[116:119]
	v_mfma_f32_16x16x32_bf16 v[112:115], v[184:187], v[144:147], v[112:115]
	v_mfma_f32_16x16x32_bf16 v[100:103], v[176:179], v[152:155], v[100:103]
	v_mfma_f32_16x16x32_bf16 v[96:99], v[184:187], v[152:155], v[96:99]
	v_mfma_f32_16x16x32_bf16 v[84:87], v[176:179], v[160:163], v[84:87]
	v_mfma_f32_16x16x32_bf16 v[80:83], v[184:187], v[160:163], v[80:83]
	v_mfma_f32_16x16x32_bf16 v[68:71], v[176:179], v[168:171], v[68:71]
	v_mfma_f32_16x16x32_bf16 v[64:67], v[184:187], v[168:171], v[64:67]
	v_mfma_f32_16x16x32_bf16 v[116:119], v[180:183], v[148:151], v[116:119]
	v_mfma_f32_16x16x32_bf16 v[112:115], v[206:209], v[148:151], v[112:115]
	v_mfma_f32_16x16x32_bf16 v[100:103], v[180:183], v[156:159], v[100:103]
	v_mfma_f32_16x16x32_bf16 v[96:99], v[206:209], v[156:159], v[96:99]
	v_mfma_f32_16x16x32_bf16 v[84:87], v[180:183], v[164:167], v[84:87]
	v_mfma_f32_16x16x32_bf16 v[80:83], v[206:209], v[164:167], v[80:83]
	v_mfma_f32_16x16x32_bf16 v[68:71], v[180:183], v[172:175], v[68:71]
	v_mfma_f32_16x16x32_bf16 v[64:67], v[206:209], v[172:175], v[64:67]
	s_setprio 0
	s_mov_b32 m0, s44
	s_mov_b64 s[0:1], 0x80
	v_lshl_add_u64 v[210:211], v[214:215], 0, s[0:1]
	s_barrier
	ds_read_b128 v[144:147], v242 offset:49152
	ds_read_b128 v[148:151], v242 offset:50176
	ds_read_b128 v[152:155], v242 offset:51200
	ds_read_b128 v[156:159], v242 offset:52224
	ds_read_b128 v[160:163], v242 offset:53248
	ds_read_b128 v[164:167], v242 offset:54272
	ds_read_b128 v[168:171], v242 offset:55296
	ds_read_b128 v[172:175], v242 offset:56320
	global_load_lds_dwordx4 v[210:211], off
	v_lshl_add_u64 v[210:211], v[216:217], 0, s[0:1]
	s_mov_b32 m0, s45
	s_nop 0
	global_load_lds_dwordx4 v[210:211], off
	s_setprio 1
	s_barrier
; #define PG8_STAGE(bufoff, gbase, voff) do { _Pragma("unroll") for (int _i = 0; _i < 2; ++_i) \
;         __builtin_amdgcn_global_load_lds((const unsigned*)((const char*)(gbase) + (voff)[_i]), (LAS unsigned*)(lds + (bufoff) + ldsw + _i * 8192), 16, 0, 0); } while (0)
; #define PG8_LDA(dst, b, h) do { _Pragma("unroll") for (int m = 0; m < 4; ++m) _Pragma("unroll") for (int k = 0; k < 2; ++k) dst[m][k] = *(const LAS bf16x8*)(lds + PG8_SA(b, h) + aoff + m * 2048 + k * 1024); } while (0)
; #define PG8_WAIT_V(n) asm volatile("s_waitcnt vmcnt(" #n ")" ::: "memory")
; #define PG8_WAIT_L(n) asm volatile("s_waitcnt lgkmcnt(" #n ")" ::: "memory")
; template <class Epi, class Sched>
; __device__ __forceinline__ void gemm_phase(LAS unsigned char* lds, const Gemm g, const Sched& S, const Epi& E) {
;     ...
;         for (int t = 0; t < nt; t += 2) {
;             const bool last = (t == nt - 2);
;             const char* a1 = cA + (size_t)(t + 1) * kstep;
;             const char* a2 = last ? nA : cA + (size_t)(t + 2) * kstep; const char* b2 = last ? nB : cB + (size_t)(t + 2) * kstep;
;             const char* a3 = a2 + kstep; const char* b3 = b2 + kstep;
;             PG8_LDB(B0, 0, 0); PG8_SCHED; PG8_LDA(At, 0, 0); PG8_STAGE(PG8_SA(1, 1), a1 + hstep, voffA);
;             PG8_WAIT_L(8); PG8_BAR; PG8_WAIT_L(0); PG8_MMA(0, 0, At, B0); PG8_BAR; PG8_SCHED;
;             PG8_LDB(B1, 0, 1); PG8_STAGE(PG8_SB(0, 0), b2, voffB);
;             PG8_BAR; PG8_WAIT_L(0); PG8_MMA(0, 1, At, B1); PG8_BAR;
;             PG8_LDA(At, 0, 1); PG8_STAGE(PG8_SA(0, 0), a2, voffA);
;             PG8_BAR; PG8_WAIT_L(0); PG8_MMA(1, 0, At, B0); PG8_BAR; PG8_SCHED;
;             PG8_STAGE(PG8_SB(0, 1), b2 + hstep, voffB);
;             PG8_WAIT_V(6); PG8_BAR; PG8_MMA(1, 1, At, B1); PG8_BAR;
;             PG8_LDB(B0, 1, 0); PG8_SCHED; PG8_LDA(At, 1, 0); PG8_STAGE(PG8_SA(0, 1), a2 + hstep, voffA);
;             PG8_WAIT_L(8); PG8_BAR; PG8_WAIT_L(0); PG8_MMA(0, 0, At, B0); PG8_BAR; PG8_SCHED;
;             PG8_LDB(B1, 1, 1); PG8_STAGE(PG8_SB(1, 0), b3, voffB);
;             PG8_BAR; PG8_WAIT_L(0); PG8_MMA(0, 1, At, B1); PG8_BAR;
;             PG8_LDA(At, 1, 1); PG8_STAGE(PG8_SA(1, 0), a3, voffA);
;             PG8_BAR; PG8_WAIT_L(0); PG8_MMA(1, 0, At, B0); PG8_BAR; PG8_SCHED;
;             PG8_STAGE(PG8_SB(1, 1), b3 + hstep, voffB);
;             PG8_WAIT_V(6); PG8_BAR; PG8_MMA(1, 1, At, B1); PG8_BAR;
	s_waitcnt lgkmcnt(0)
	v_mfma_f32_16x16x32_bf16 v[60:63], v[128:131], v[144:147], v[60:63]
	v_mfma_f32_16x16x32_bf16 v[56:59], v[136:139], v[144:147], v[56:59]
	v_mfma_f32_16x16x32_bf16 v[44:47], v[128:131], v[152:155], v[44:47]
	v_mfma_f32_16x16x32_bf16 v[40:43], v[136:139], v[152:155], v[40:43]
	v_mfma_f32_16x16x32_bf16 v[28:31], v[128:131], v[160:163], v[28:31]
	v_mfma_f32_16x16x32_bf16 v[24:27], v[136:139], v[160:163], v[24:27]
	v_mfma_f32_16x16x32_bf16 v[12:15], v[128:131], v[168:171], v[12:15]
	v_mfma_f32_16x16x32_bf16 v[8:11], v[136:139], v[168:171], v[8:11]
	v_mfma_f32_16x16x32_bf16 v[60:63], v[132:135], v[148:151], v[60:63]
	v_mfma_f32_16x16x32_bf16 v[56:59], v[140:143], v[148:151], v[56:59]
	v_mfma_f32_16x16x32_bf16 v[44:47], v[132:135], v[156:159], v[44:47]
	v_mfma_f32_16x16x32_bf16 v[40:43], v[140:143], v[156:159], v[40:43]
	v_mfma_f32_16x16x32_bf16 v[28:31], v[132:135], v[164:167], v[28:31]
	v_mfma_f32_16x16x32_bf16 v[24:27], v[140:143], v[164:167], v[24:27]
	v_mfma_f32_16x16x32_bf16 v[12:15], v[132:135], v[172:175], v[12:15]
	v_mfma_f32_16x16x32_bf16 v[8:11], v[140:143], v[172:175], v[8:11]
	s_setprio 0
	s_barrier
	s_add_u32 s22, s26, 0xb0080
	s_addc_u32 s23, s27, 0
	s_add_i32 s26, s28, s34
	s_mov_b32 m0, s26
	s_nop 0
	global_load_lds_dwordx4 v190, s[22:23]
	s_add_i32 m0, s26, 0x2000
	s_nop 0
	global_load_lds_dwordx4 v194, s[22:23]
	s_waitcnt vmcnt(8)
	s_setprio 1
	s_barrier
	v_mfma_f32_16x16x32_bf16 v[52:55], v[176:179], v[144:147], v[52:55]
	v_mfma_f32_16x16x32_bf16 v[48:51], v[184:187], v[144:147], v[48:51]
	v_mfma_f32_16x16x32_bf16 v[36:39], v[176:179], v[152:155], v[36:39]
	v_mfma_f32_16x16x32_bf16 v[32:35], v[184:187], v[152:155], v[32:35]
	v_mfma_f32_16x16x32_bf16 v[20:23], v[176:179], v[160:163], v[20:23]
	v_mfma_f32_16x16x32_bf16 v[16:19], v[184:187], v[160:163], v[16:19]
	v_mfma_f32_16x16x32_bf16 v[4:7], v[176:179], v[168:171], v[4:7]
	v_mfma_f32_16x16x32_bf16 v[0:3], v[184:187], v[168:171], v[0:3]
	v_mfma_f32_16x16x32_bf16 v[52:55], v[180:183], v[148:151], v[52:55]
	v_mfma_f32_16x16x32_bf16 v[48:51], v[206:209], v[148:151], v[48:51]
	v_mfma_f32_16x16x32_bf16 v[36:39], v[180:183], v[156:159], v[36:39]
	v_mfma_f32_16x16x32_bf16 v[32:35], v[206:209], v[156:159], v[32:35]
	v_mfma_f32_16x16x32_bf16 v[20:23], v[180:183], v[164:167], v[20:23]
	v_mfma_f32_16x16x32_bf16 v[16:19], v[206:209], v[164:167], v[16:19]
	v_mfma_f32_16x16x32_bf16 v[4:7], v[180:183], v[172:175], v[4:7]
	v_mfma_f32_16x16x32_bf16 v[0:3], v[206:209], v[172:175], v[0:3]
	s_setprio 0
	s_add_i32 s56, s56, 2
	s_add_u32 s54, s54, 0x100
	s_addc_u32 s55, s55, 0
	s_cmp_gt_u32 s56, 41
	s_mov_b64 s[22:23], s[24:25]
	s_barrier
.LBB0_1097:
	ds_read_b128 v[128:131], v241
	ds_read_b128 v[132:135], v241 offset:1024
	ds_read_b128 v[136:139], v241 offset:2048
	ds_read_b128 v[140:143], v241 offset:3072
	s_add_u32 s24, s22, 0x100
	s_addc_u32 s25, s23, 0
	s_cmp_eq_u32 s56, 40
	s_cselect_b32 s29, s5, s25
	s_cselect_b32 s28, s4, s24
	s_cselect_b32 s27, s7, s55
	s_cselect_b32 s26, s6, s54
	v_lshl_add_u64 v[176:177], s[22:23], 0, v[196:197]
	s_add_i32 m0, s35, 0xc000
	ds_read_b128 v[144:147], v242
	ds_read_b128 v[148:151], v242 offset:1024
	ds_read_b128 v[152:155], v242 offset:2048
	ds_read_b128 v[156:159], v242 offset:3072
	ds_read_b128 v[160:163], v242 offset:4096
	ds_read_b128 v[164:167], v242 offset:5120
	ds_read_b128 v[168:171], v242 offset:6144
	ds_read_b128 v[172:175], v242 offset:7168
	global_load_lds_dwordx4 v[176:177], off
	v_lshl_add_u64 v[176:177], s[22:23], 0, v[198:199]
	s_add_i32 m0, s35, 0xe000
	s_nop 0
	global_load_lds_dwordx4 v[176:177], off
	s_waitcnt lgkmcnt(8)
	s_waitcnt vmcnt(8)
	s_setprio 1
	s_barrier
	s_waitcnt lgkmcnt(0)
	v_mfma_f32_16x16x32_bf16 v[124:127], v[128:131], v[144:147], v[124:127]
	v_mfma_f32_16x16x32_bf16 v[120:123], v[136:139], v[144:147], v[120:123]
	v_mfma_f32_16x16x32_bf16 v[108:111], v[128:131], v[152:155], v[108:111]
	v_mfma_f32_16x16x32_bf16 v[104:107], v[136:139], v[152:155], v[104:107]
	v_mfma_f32_16x16x32_bf16 v[92:95], v[128:131], v[160:163], v[92:95]
	v_mfma_f32_16x16x32_bf16 v[88:91], v[136:139], v[160:163], v[88:91]
	v_mfma_f32_16x16x32_bf16 v[76:79], v[128:131], v[168:171], v[76:79]
	v_mfma_f32_16x16x32_bf16 v[72:75], v[136:139], v[168:171], v[72:75]
	v_mfma_f32_16x16x32_bf16 v[124:127], v[132:135], v[148:151], v[124:127]
	v_mfma_f32_16x16x32_bf16 v[120:123], v[140:143], v[148:151], v[120:123]
	v_mfma_f32_16x16x32_bf16 v[108:111], v[132:135], v[156:159], v[108:111]
	v_mfma_f32_16x16x32_bf16 v[104:107], v[140:143], v[156:159], v[104:107]
	v_mfma_f32_16x16x32_bf16 v[92:95], v[132:135], v[164:167], v[92:95]
	v_mfma_f32_16x16x32_bf16 v[88:91], v[140:143], v[164:167], v[88:91]
	v_mfma_f32_16x16x32_bf16 v[76:79], v[132:135], v[172:175], v[76:79]
	v_mfma_f32_16x16x32_bf16 v[72:75], v[140:143], v[172:175], v[72:75]
	s_setprio 0
	s_barrier
	s_add_i32 s22, s48, s34
	s_mov_b32 m0, s22
	ds_read_b128 v[176:179], v243
	ds_read_b128 v[180:183], v243 offset:1024
	ds_read_b128 v[184:187], v243 offset:2048
	ds_read_b128 v[206:209], v243 offset:3072
	global_load_lds_dwordx4 v190, s[26:27]
	s_add_i32 m0, s22, 0x2000
	s_nop 0
	global_load_lds_dwordx4 v194, s[26:27]
	s_waitcnt vmcnt(8)
	s_setprio 1
	s_barrier
; #define PG8_STAGE(bufoff, gbase, voff) do { _Pragma("unroll") for (int _i = 0; _i < 2; ++_i) \
;         __builtin_amdgcn_global_load_lds((const unsigned*)((const char*)(gbase) + (voff)[_i]), (LAS unsigned*)(lds + (bufoff) + ldsw + _i * 8192), 16, 0, 0); } while (0)
; #define PG8_LDA(dst, b, h) do { _Pragma("unroll") for (int m = 0; m < 4; ++m) _Pragma("unroll") for (int k = 0; k < 2; ++k) dst[m][k] = *(const LAS bf16x8*)(lds + PG8_SA(b, h) + aoff + m * 2048 + k * 1024); } while (0)
; #define PG8_LDB(dst, b, h) do { _Pragma("unroll") for (int n = 0; n < 2; ++n) _Pragma("unroll") for (int k = 0; k < 2; ++k) dst[n][k] = *(const LAS bf16x8*)(lds + PG8_SB(b, h) + boff + n * 2048 + k * 1024); } while (0)
; #define PG8_MMA(ai, bj, At, Bt) do { __builtin_amdgcn_s_setprio(1); _Pragma("unroll") for (int m = 0; m < 4; ++m) _Pragma("unroll") for (int n = 0; n < 2; ++n) _Pragma("unroll") for (int k = 0; k < 2; ++k) \
;         acc[ai][bj][m][n] = __builtin_amdgcn_mfma_f32_16x16x32_bf16(Bt[n][k], At[m][k], acc[ai][bj][m][n], 0, 0, 0); __builtin_amdgcn_s_setprio(0); } while (0)
; #define PG8_WAIT_V(n) asm volatile("s_waitcnt vmcnt(" #n ")" ::: "memory")
; #define PG8_WAIT_L(n) asm volatile("s_waitcnt lgkmcnt(" #n ")" ::: "memory")
; #define PG8_BAR __builtin_amdgcn_s_barrier()
; #define PG8_SCHED __builtin_amdgcn_sched_barrier(0)
; template <class Epi, class Sched>
; __device__ __forceinline__ void gemm_phase(LAS unsigned char* lds, const Gemm g, const Sched& S, const Epi& E) {
;     ...
;             PG8_WAIT_V(6); PG8_BAR; PG8_MMA(1, 1, At, B1); PG8_BAR;
;             PG8_LDB(B0, 1, 0); PG8_SCHED; PG8_LDA(At, 1, 0); PG8_STAGE(PG8_SA(0, 1), a2 + hstep, voffA);
;             PG8_WAIT_L(8); PG8_BAR; PG8_WAIT_L(0); PG8_MMA(0, 0, At, B0); PG8_BAR; PG8_SCHED;
;             PG8_LDB(B1, 1, 1); PG8_STAGE(PG8_SB(1, 0), b3, voffB);
;             PG8_BAR; PG8_WAIT_L(0); PG8_MMA(0, 1, At, B1); PG8_BAR;
;             PG8_LDA(At, 1, 1); PG8_STAGE(PG8_SA(1, 0), a3, voffA);
;             PG8_BAR; PG8_WAIT_L(0); PG8_MMA(1, 0, At, B0); PG8_BAR; PG8_SCHED;
	s_waitcnt lgkmcnt(0)
	v_mfma_f32_16x16x32_bf16 v[116:119], v[176:179], v[144:147], v[116:119]
	v_mfma_f32_16x16x32_bf16 v[112:115], v[184:187], v[144:147], v[112:115]
	v_mfma_f32_16x16x32_bf16 v[100:103], v[176:179], v[152:155], v[100:103]
	v_mfma_f32_16x16x32_bf16 v[96:99], v[184:187], v[152:155], v[96:99]
	v_mfma_f32_16x16x32_bf16 v[84:87], v[176:179], v[160:163], v[84:87]
	v_mfma_f32_16x16x32_bf16 v[80:83], v[184:187], v[160:163], v[80:83]
	v_mfma_f32_16x16x32_bf16 v[68:71], v[176:179], v[168:171], v[68:71]
	v_mfma_f32_16x16x32_bf16 v[64:67], v[184:187], v[168:171], v[64:67]
	v_mfma_f32_16x16x32_bf16 v[116:119], v[180:183], v[148:151], v[116:119]
	v_mfma_f32_16x16x32_bf16 v[112:115], v[206:209], v[148:151], v[112:115]
	v_mfma_f32_16x16x32_bf16 v[100:103], v[180:183], v[156:159], v[100:103]
	v_mfma_f32_16x16x32_bf16 v[96:99], v[206:209], v[156:159], v[96:99]
	v_mfma_f32_16x16x32_bf16 v[84:87], v[180:183], v[164:167], v[84:87]
	v_mfma_f32_16x16x32_bf16 v[80:83], v[206:209], v[164:167], v[80:83]
	v_mfma_f32_16x16x32_bf16 v[68:71], v[180:183], v[172:175], v[68:71]
	v_mfma_f32_16x16x32_bf16 v[64:67], v[206:209], v[172:175], v[64:67]
	s_setprio 0
	s_mov_b32 m0, s35
	v_lshl_add_u64 v[214:215], s[28:29], 0, v[188:189]
	s_barrier
	ds_read_b128 v[144:147], v242 offset:16384
	ds_read_b128 v[148:151], v242 offset:17408
	ds_read_b128 v[152:155], v242 offset:18432
	ds_read_b128 v[156:159], v242 offset:19456
	ds_read_b128 v[160:163], v242 offset:20480
	ds_read_b128 v[164:167], v242 offset:21504
	ds_read_b128 v[168:171], v242 offset:22528
	ds_read_b128 v[172:175], v242 offset:23552
	global_load_lds_dwordx4 v188, s[28:29]
	v_lshl_add_u64 v[216:217], s[28:29], 0, v[192:193]
	s_mov_b32 m0, s36
	s_nop 0
	global_load_lds_dwordx4 v192, s[28:29]
	s_setprio 1
	s_barrier
	s_waitcnt lgkmcnt(0)
	v_mfma_f32_16x16x32_bf16 v[60:63], v[128:131], v[144:147], v[60:63]
	v_mfma_f32_16x16x32_bf16 v[56:59], v[136:139], v[144:147], v[56:59]
	v_mfma_f32_16x16x32_bf16 v[44:47], v[128:131], v[152:155], v[44:47]
	v_mfma_f32_16x16x32_bf16 v[40:43], v[136:139], v[152:155], v[40:43]
	v_mfma_f32_16x16x32_bf16 v[28:31], v[128:131], v[160:163], v[28:31]
	v_mfma_f32_16x16x32_bf16 v[24:27], v[136:139], v[160:163], v[24:27]
	v_mfma_f32_16x16x32_bf16 v[12:15], v[128:131], v[168:171], v[12:15]
	v_mfma_f32_16x16x32_bf16 v[8:11], v[136:139], v[168:171], v[8:11]
	v_mfma_f32_16x16x32_bf16 v[60:63], v[132:135], v[148:151], v[60:63]
	v_mfma_f32_16x16x32_bf16 v[56:59], v[140:143], v[148:151], v[56:59]
	v_mfma_f32_16x16x32_bf16 v[44:47], v[132:135], v[156:159], v[44:47]
	v_mfma_f32_16x16x32_bf16 v[40:43], v[140:143], v[156:159], v[40:43]
	v_mfma_f32_16x16x32_bf16 v[28:31], v[132:135], v[164:167], v[28:31]
	v_mfma_f32_16x16x32_bf16 v[24:27], v[140:143], v[164:167], v[24:27]
	v_mfma_f32_16x16x32_bf16 v[12:15], v[132:135], v[172:175], v[12:15]
	v_mfma_f32_16x16x32_bf16 v[8:11], v[140:143], v[172:175], v[8:11]
	s_setprio 0
	s_barrier
	s_add_u32 s22, s26, 0xb0000
	s_addc_u32 s23, s27, 0
	s_add_i32 s57, s49, s34
	s_mov_b32 m0, s57
	s_nop 0
	global_load_lds_dwordx4 v190, s[22:23]
	s_add_i32 m0, s57, 0x2000
	s_nop 0
	global_load_lds_dwordx4 v194, s[22:23]
	s_add_u32 s22, s28, 0xb0000
	s_addc_u32 s23, s29, 0
	s_mov_b32 m0, s37
	s_nop 0
	global_load_lds_dwordx4 v188, s[22:23]
	s_mov_b32 m0, s38
	s_nop 0
	global_load_lds_dwordx4 v192, s[22:23]
	s_waitcnt vmcnt(10)
	s_setprio 1
	s_barrier
	v_mfma_f32_16x16x32_bf16 v[52:55], v[176:179], v[144:147], v[52:55]
	v_mfma_f32_16x16x32_bf16 v[48:51], v[184:187], v[144:147], v[48:51]
	v_mfma_f32_16x16x32_bf16 v[36:39], v[176:179], v[152:155], v[36:39]
	v_mfma_f32_16x16x32_bf16 v[32:35], v[184:187], v[152:155], v[32:35]
	v_mfma_f32_16x16x32_bf16 v[20:23], v[176:179], v[160:163], v[20:23]
	v_mfma_f32_16x16x32_bf16 v[16:19], v[184:187], v[160:163], v[16:19]
	v_mfma_f32_16x16x32_bf16 v[4:7], v[176:179], v[168:171], v[4:7]
	v_mfma_f32_16x16x32_bf16 v[0:3], v[184:187], v[168:171], v[0:3]
	v_mfma_f32_16x16x32_bf16 v[52:55], v[180:183], v[148:151], v[52:55]
	v_mfma_f32_16x16x32_bf16 v[48:51], v[206:209], v[148:151], v[48:51]
	v_mfma_f32_16x16x32_bf16 v[36:39], v[180:183], v[156:159], v[36:39]
	v_mfma_f32_16x16x32_bf16 v[32:35], v[206:209], v[156:159], v[32:35]
	v_mfma_f32_16x16x32_bf16 v[20:23], v[180:183], v[164:167], v[20:23]
	v_mfma_f32_16x16x32_bf16 v[16:19], v[206:209], v[164:167], v[16:19]
	v_mfma_f32_16x16x32_bf16 v[4:7], v[180:183], v[172:175], v[4:7]
	v_mfma_f32_16x16x32_bf16 v[0:3], v[206:209], v[172:175], v[0:3]
	s_setprio 0
	s_add_i32 s57, 0, 0x18000
	v_add_u32_e32 v140, s57, v240
	s_barrier
	ds_read_b128 v[128:131], v140
	ds_read_b128 v[132:135], v140 offset:1024
	ds_read_b128 v[136:139], v140 offset:2048
	ds_read_b128 v[140:143], v140 offset:3072
	ds_read_b128 v[144:147], v242 offset:32768
	ds_read_b128 v[148:151], v242 offset:33792
	ds_read_b128 v[152:155], v242 offset:34816
	ds_read_b128 v[156:159], v242 offset:35840
	ds_read_b128 v[160:163], v242 offset:36864
	ds_read_b128 v[164:167], v242 offset:37888
	ds_read_b128 v[168:171], v242 offset:38912
	ds_read_b128 v[172:175], v242 offset:39936
	s_waitcnt lgkmcnt(8)
	s_waitcnt vmcnt(8)
	s_setprio 1
	s_barrier
; #define PG8_STAGE(bufoff, gbase, voff) do { _Pragma("unroll") for (int _i = 0; _i < 2; ++_i) \
;         __builtin_amdgcn_global_load_lds((const unsigned*)((const char*)(gbase) + (voff)[_i]), (LAS unsigned*)(lds + (bufoff) + ldsw + _i * 8192), 16, 0, 0); } while (0)
; #define PG8_LDA(dst, b, h) do { _Pragma("unroll") for (int m = 0; m < 4; ++m) _Pragma("unroll") for (int k = 0; k < 2; ++k) dst[m][k] = *(const LAS bf16x8*)(lds + PG8_SA(b, h) + aoff + m * 2048 + k * 1024); } while (0)
; #define PG8_LDB(dst, b, h) do { _Pragma("unroll") for (int n = 0; n < 2; ++n) _Pragma("unroll") for (int k = 0; k < 2; ++k) dst[n][k] = *(const LAS bf16x8*)(lds + PG8_SB(b, h) + boff + n * 2048 + k * 1024); } while (0)
; #define PG8_MMA(ai, bj, At, Bt) do { __builtin_amdgcn_s_setprio(1); _Pragma("unroll") for (int m = 0; m < 4; ++m) _Pragma("unroll") for (int n = 0; n < 2; ++n) _Pragma("unroll") for (int k = 0; k < 2; ++k) \
;         acc[ai][bj][m][n] = __builtin_amdgcn_mfma_f32_16x16x32_bf16(Bt[n][k], At[m][k], acc[ai][bj][m][n], 0, 0, 0); __builtin_amdgcn_s_setprio(0); } while (0)
; #define PG8_WAIT_V(n) asm volatile("s_waitcnt vmcnt(" #n ")" ::: "memory")
; #define PG8_WAIT_L(n) asm volatile("s_waitcnt lgkmcnt(" #n ")" ::: "memory")
; #define PG8_BAR __builtin_amdgcn_s_barrier()
; #define PG8_SCHED __builtin_amdgcn_sched_barrier(0)
; template <class Epi, class Sched>
; __device__ __forceinline__ void gemm_phase(LAS unsigned char* lds, const Gemm g, const Sched& S, const Epi& E) {
;     ...
;             PG8_LDB(B0, 1, 0); PG8_SCHED; PG8_LDA(At, 1, 0); PG8_STAGE(PG8_SA(0, 1), a2 + hstep, voffA);
;             PG8_WAIT_L(8); PG8_BAR; PG8_WAIT_L(0); PG8_MMA(0, 0, At, B0); PG8_BAR; PG8_SCHED;
;             PG8_LDB(B1, 1, 1); PG8_STAGE(PG8_SB(1, 0), b3, voffB);
;             PG8_BAR; PG8_WAIT_L(0); PG8_MMA(0, 1, At, B1); PG8_BAR;
;             PG8_LDA(At, 1, 1); PG8_STAGE(PG8_SA(1, 0), a3, voffA);
;             PG8_BAR; PG8_WAIT_L(0); PG8_MMA(1, 0, At, B0); PG8_BAR; PG8_SCHED;
;             PG8_STAGE(PG8_SB(1, 1), b3 + hstep, voffB);
;             PG8_WAIT_V(6); PG8_BAR; PG8_MMA(1, 1, At, B1); PG8_BAR;
	s_waitcnt lgkmcnt(0)
	v_mfma_f32_16x16x32_bf16 v[124:127], v[128:131], v[144:147], v[124:127]
	v_mfma_f32_16x16x32_bf16 v[120:123], v[136:139], v[144:147], v[120:123]
	v_mfma_f32_16x16x32_bf16 v[108:111], v[128:131], v[152:155], v[108:111]
	v_mfma_f32_16x16x32_bf16 v[104:107], v[136:139], v[152:155], v[104:107]
	v_mfma_f32_16x16x32_bf16 v[92:95], v[128:131], v[160:163], v[92:95]
	v_mfma_f32_16x16x32_bf16 v[88:91], v[136:139], v[160:163], v[88:91]
	v_mfma_f32_16x16x32_bf16 v[76:79], v[128:131], v[168:171], v[76:79]
	v_mfma_f32_16x16x32_bf16 v[72:75], v[136:139], v[168:171], v[72:75]
	v_mfma_f32_16x16x32_bf16 v[124:127], v[132:135], v[148:151], v[124:127]
	v_mfma_f32_16x16x32_bf16 v[120:123], v[140:143], v[148:151], v[120:123]
	v_mfma_f32_16x16x32_bf16 v[108:111], v[132:135], v[156:159], v[108:111]
	v_mfma_f32_16x16x32_bf16 v[104:107], v[140:143], v[156:159], v[104:107]
	v_mfma_f32_16x16x32_bf16 v[92:95], v[132:135], v[164:167], v[92:95]
	v_mfma_f32_16x16x32_bf16 v[88:91], v[140:143], v[164:167], v[88:91]
	v_mfma_f32_16x16x32_bf16 v[76:79], v[132:135], v[172:175], v[76:79]
	v_mfma_f32_16x16x32_bf16 v[72:75], v[140:143], v[172:175], v[72:75]
	s_setprio 0
	s_barrier
	s_add_i32 s28, 0, 0x1c000
	s_add_i32 s22, s57, s34
	v_add_u32_e32 v206, s28, v240
	s_add_u32 s0, s26, 0x80
	s_addc_u32 s1, s27, 0
	s_mov_b32 m0, s22
	ds_read_b128 v[176:179], v206
	ds_read_b128 v[180:183], v206 offset:1024
	ds_read_b128 v[184:187], v206 offset:2048
	ds_read_b128 v[206:209], v206 offset:3072
	global_load_lds_dwordx4 v190, s[0:1]
	s_add_i32 m0, s22, 0x2000
	s_nop 0
	global_load_lds_dwordx4 v194, s[0:1]
	s_waitcnt vmcnt(8)
	s_setprio 1
	s_barrier
	s_waitcnt lgkmcnt(0)
	v_mfma_f32_16x16x32_bf16 v[116:119], v[176:179], v[144:147], v[116:119]
	v_mfma_f32_16x16x32_bf16 v[112:115], v[184:187], v[144:147], v[112:115]
	v_mfma_f32_16x16x32_bf16 v[100:103], v[176:179], v[152:155], v[100:103]
	v_mfma_f32_16x16x32_bf16 v[96:99], v[184:187], v[152:155], v[96:99]
	v_mfma_f32_16x16x32_bf16 v[84:87], v[176:179], v[160:163], v[84:87]
	v_mfma_f32_16x16x32_bf16 v[80:83], v[184:187], v[160:163], v[80:83]
	v_mfma_f32_16x16x32_bf16 v[68:71], v[176:179], v[168:171], v[68:71]
	v_mfma_f32_16x16x32_bf16 v[64:67], v[184:187], v[168:171], v[64:67]
	v_mfma_f32_16x16x32_bf16 v[116:119], v[180:183], v[148:151], v[116:119]
	v_mfma_f32_16x16x32_bf16 v[112:115], v[206:209], v[148:151], v[112:115]
	v_mfma_f32_16x16x32_bf16 v[100:103], v[180:183], v[156:159], v[100:103]
	v_mfma_f32_16x16x32_bf16 v[96:99], v[206:209], v[156:159], v[96:99]
	v_mfma_f32_16x16x32_bf16 v[84:87], v[180:183], v[164:167], v[84:87]
	v_mfma_f32_16x16x32_bf16 v[80:83], v[206:209], v[164:167], v[80:83]
	v_mfma_f32_16x16x32_bf16 v[68:71], v[180:183], v[172:175], v[68:71]
	v_mfma_f32_16x16x32_bf16 v[64:67], v[206:209], v[172:175], v[64:67]
	s_setprio 0
	s_mov_b32 m0, s44
	s_mov_b64 s[0:1], 0x80
	v_lshl_add_u64 v[210:211], v[214:215], 0, s[0:1]
	s_barrier
	ds_read_b128 v[144:147], v242 offset:49152
	ds_read_b128 v[148:151], v242 offset:50176
	ds_read_b128 v[152:155], v242 offset:51200
	ds_read_b128 v[156:159], v242 offset:52224
	ds_read_b128 v[160:163], v242 offset:53248
	ds_read_b128 v[164:167], v242 offset:54272
	ds_read_b128 v[168:171], v242 offset:55296
	ds_read_b128 v[172:175], v242 offset:56320
	global_load_lds_dwordx4 v[210:211], off
	v_lshl_add_u64 v[210:211], v[216:217], 0, s[0:1]
	s_mov_b32 m0, s45
	s_nop 0
	global_load_lds_dwordx4 v[210:211], off
	s_setprio 1
	s_barrier
	s_waitcnt lgkmcnt(0)
	v_mfma_f32_16x16x32_bf16 v[60:63], v[128:131], v[144:147], v[60:63]
	v_mfma_f32_16x16x32_bf16 v[56:59], v[136:139], v[144:147], v[56:59]
	v_mfma_f32_16x16x32_bf16 v[44:47], v[128:131], v[152:155], v[44:47]
	v_mfma_f32_16x16x32_bf16 v[40:43], v[136:139], v[152:155], v[40:43]
	v_mfma_f32_16x16x32_bf16 v[28:31], v[128:131], v[160:163], v[28:31]
	v_mfma_f32_16x16x32_bf16 v[24:27], v[136:139], v[160:163], v[24:27]
	v_mfma_f32_16x16x32_bf16 v[12:15], v[128:131], v[168:171], v[12:15]
	v_mfma_f32_16x16x32_bf16 v[8:11], v[136:139], v[168:171], v[8:11]
	v_mfma_f32_16x16x32_bf16 v[60:63], v[132:135], v[148:151], v[60:63]
	v_mfma_f32_16x16x32_bf16 v[56:59], v[140:143], v[148:151], v[56:59]
	v_mfma_f32_16x16x32_bf16 v[44:47], v[132:135], v[156:159], v[44:47]
	v_mfma_f32_16x16x32_bf16 v[40:43], v[140:143], v[156:159], v[40:43]
	v_mfma_f32_16x16x32_bf16 v[28:31], v[132:135], v[164:167], v[28:31]
	v_mfma_f32_16x16x32_bf16 v[24:27], v[140:143], v[164:167], v[24:27]
	v_mfma_f32_16x16x32_bf16 v[12:15], v[132:135], v[172:175], v[12:15]
	v_mfma_f32_16x16x32_bf16 v[8:11], v[140:143], v[172:175], v[8:11]
	s_setprio 0
	s_barrier
	s_add_u32 s22, s26, 0xb0080
	s_addc_u32 s23, s27, 0
	s_add_i32 s26, s28, s34
	s_mov_b32 m0, s26
	s_nop 0
	global_load_lds_dwordx4 v190, s[22:23]
	s_add_i32 m0, s26, 0x2000
	s_nop 0
	global_load_lds_dwordx4 v194, s[22:23]
	s_waitcnt vmcnt(8)
	s_setprio 1
	s_barrier
	v_mfma_f32_16x16x32_bf16 v[52:55], v[176:179], v[144:147], v[52:55]
	v_mfma_f32_16x16x32_bf16 v[48:51], v[184:187], v[144:147], v[48:51]
	v_mfma_f32_16x16x32_bf16 v[36:39], v[176:179], v[152:155], v[36:39]
	v_mfma_f32_16x16x32_bf16 v[32:35], v[184:187], v[152:155], v[32:35]
	v_mfma_f32_16x16x32_bf16 v[20:23], v[176:179], v[160:163], v[20:23]
	v_mfma_f32_16x16x32_bf16 v[16:19], v[184:187], v[160:163], v[16:19]
	v_mfma_f32_16x16x32_bf16 v[4:7], v[176:179], v[168:171], v[4:7]
	v_mfma_f32_16x16x32_bf16 v[0:3], v[184:187], v[168:171], v[0:3]
	v_mfma_f32_16x16x32_bf16 v[52:55], v[180:183], v[148:151], v[52:55]
	v_mfma_f32_16x16x32_bf16 v[48:51], v[206:209], v[148:151], v[48:51]
	v_mfma_f32_16x16x32_bf16 v[36:39], v[180:183], v[156:159], v[36:39]
	v_mfma_f32_16x16x32_bf16 v[32:35], v[206:209], v[156:159], v[32:35]
	v_mfma_f32_16x16x32_bf16 v[20:23], v[180:183], v[164:167], v[20:23]
	v_mfma_f32_16x16x32_bf16 v[16:19], v[206:209], v[164:167], v[16:19]
	v_mfma_f32_16x16x32_bf16 v[4:7], v[180:183], v[172:175], v[4:7]
	v_mfma_f32_16x16x32_bf16 v[0:3], v[206:209], v[172:175], v[0:3]
	s_setprio 0
	s_add_i32 s56, s56, 2
	s_add_u32 s54, s54, 0x100
	s_addc_u32 s55, s55, 0
	s_cmp_gt_u32 s56, 41
	s_mov_b64 s[22:23], s[24:25]
	s_barrier
; __device__ __forceinline__ unsigned cvt_pk_bf16(float lo, float hi) { unsigned r; asm volatile("v_cvt_pk_bf16_f32 %0, %1, %2" : "=v"(r) : "v"(lo), "v"(hi)); return r; }
; __device__ __forceinline__ float bf_lo(unsigned u) { return __uint_as_float(u << 16); }
; __device__ __forceinline__ float bf_hi(unsigned u) { return __uint_as_float(u & 0xffff0000u); }
;     __device__ __forceinline__ void operator()(const AccT& acc, const Unit& u, int wr, int wc, int fr, int fq) const {
;     ...
;         f32x4 gv[2][2];
; #pragma unroll
;         for (int bj = 0; bj < 2; ++bj)
; #pragma unroll
;             for (int n = 0; n < 2; ++n) gv[bj][n] = *(const f32x4*)(gate + (size_t)b * NMOD + col0 + bj * 128 + n * 4) * gs;
;         u32x4 r[2][4][2];
; #pragma unroll
;         for (int ai = 0; ai < 2; ++ai)
; #pragma unroll
;             for (int m = 0; m < 4; ++m)
; #pragma unroll
;                 for (int bj = 0; bj < 2; ++bj) r[ai][m][bj] = *(const u32x4*)(res + (size_t)(wr * 64 + fr + ai * 128 + m * 16) * DM + col0 + bj * 128);
; #pragma unroll
;         for (int ai = 0; ai < 2; ++ai)
; #pragma unroll
;             for (int m = 0; m < 4; ++m)
; #pragma unroll
;                 for (int bj = 0; bj < 2; ++bj) {
;                     const u32x4 q = r[ai][m][bj];
;                     const f32x4 r0 = {bf_lo(q.x), bf_hi(q.x), bf_lo(q.y), bf_hi(q.y)}, r1 = {bf_lo(q.z), bf_hi(q.z), bf_lo(q.w), bf_hi(q.w)};
;                     const f32x4 h0 = r0 + gv[bj][0] * acc[ai][bj][m][0], h1 = r1 + gv[bj][1] * acc[ai][bj][m][1];
;                     u32x4 w; w.x = cvt_pk_bf16(h0[0], h0[1]); w.y = cvt_pk_bf16(h0[2], h0[3]); w.z = cvt_pk_bf16(h1[0], h1[1]); w.w = cvt_pk_bf16(h1[2], h1[3]);
;                     *(u32x4*)(out + (size_t)(wr * 64 + fr + ai * 128 + m * 16) * DM + col0 + bj * 128) = w;
	s_cbranch_scc0 .LBB0_1097
	s_lshl_b32 s25, s52, 8
	v_mov_b32_e32 v140, v239
	v_mov_b32_e32 v128, v238
	s_lshl_b32 s22, s53, 8
	s_ashr_i32 s24, s53, 3
	s_or_b32 s25, s25, s43
	s_ashr_i32 s23, s22, 31
	v_lshl_add_u32 v136, v128, 3, s25
	s_mul_hi_i32 s25, s24, 0x9000
	s_mul_i32 s24, s24, 0x9000
	s_add_u32 s24, s40, s24
	s_addc_u32 s25, s41, s25
	v_ashrrev_i32_e32 v137, 31, v136
	v_lshl_add_u64 v[138:139], v[136:137], 2, s[24:25]
	global_load_dwordx4 v[128:131], v[138:139], off offset:16
	global_load_dwordx4 v[132:135], v[138:139], off
	s_lshl_b64 s[22:23], s[22:23], 11
	s_add_u32 s24, s80, s22
	s_addc_u32 s25, s81, s23
	v_lshlrev_b64 v[226:227], 1, v[136:137]
	s_add_u32 s22, s96, s22
	s_addc_u32 s23, s97, s23
	s_and_b64 vcc, exec, s[2:3]
	s_mov_b32 s52, s50
	s_mov_b32 s53, s51
	s_waitcnt vmcnt(0)
	v_pk_mul_f32 v[216:217], v[130:131], 0.5 op_sel_hi:[1,0]
	v_pk_mul_f32 v[220:221], v[134:135], 0.5 op_sel_hi:[1,0]
	v_pk_mul_f32 v[218:219], v[132:133], 0.5 op_sel_hi:[1,0]
	v_pk_mul_f32 v[214:215], v[128:129], 0.5 op_sel_hi:[1,0]
	global_load_dwordx4 v[128:131], v[138:139], off offset:528
	global_load_dwordx4 v[132:135], v[138:139], off offset:512
	s_waitcnt vmcnt(0)
	v_pk_mul_f32 v[206:207], v[128:129], 0.5 op_sel_hi:[1,0]
	v_add_u32_e32 v128, s42, v140
	v_ashrrev_i32_e32 v129, 31, v128
	v_pk_mul_f32 v[208:209], v[130:131], 0.5 op_sel_hi:[1,0]
	v_lshl_add_u64 v[130:131], s[24:25], 0, v[226:227]
	v_lshlrev_b64 v[248:249], 11, v[128:129]
	v_lshl_add_u64 v[128:129], v[130:131], 0, v[248:249]
	global_load_dwordx4 v[244:247], v[128:129], off
	global_load_dwordx4 v[184:187], v[128:129], off offset:256
	v_lshl_add_u64 v[236:237], v[248:249], 0, s[8:9]
	v_lshl_add_u64 v[128:129], v[130:131], 0, v[236:237]
	global_load_dwordx4 v[180:183], v[128:129], off
	global_load_dwordx4 v[176:179], v[128:129], off offset:256
	v_lshl_add_u64 v[234:235], v[248:249], 0, s[10:11]
	v_lshl_add_u64 v[128:129], v[130:131], 0, v[234:235]
	global_load_dwordx4 v[172:175], v[128:129], off
	global_load_dwordx4 v[168:171], v[128:129], off offset:256
	v_lshl_add_u64 v[232:233], v[248:249], 0, s[12:13]
	v_lshl_add_u64 v[128:129], v[130:131], 0, v[232:233]
	global_load_dwordx4 v[164:167], v[128:129], off
	global_load_dwordx4 v[160:163], v[128:129], off offset:256
	v_lshl_add_u64 v[230:231], v[248:249], 0, s[14:15]
	v_lshl_add_u64 v[128:129], v[130:131], 0, v[230:231]
	global_load_dwordx4 v[156:159], v[128:129], off
	global_load_dwordx4 v[152:155], v[128:129], off offset:256
	v_lshl_add_u64 v[228:229], v[248:249], 0, s[16:17]
	v_lshl_add_u64 v[128:129], v[130:131], 0, v[228:229]
	global_load_dwordx4 v[148:151], v[128:129], off
	global_load_dwordx4 v[144:147], v[128:129], off offset:256
	v_lshl_add_u64 v[224:225], v[248:249], 0, s[18:19]
	v_lshl_add_u64 v[128:129], v[130:131], 0, v[224:225]
	global_load_dwordx4 v[140:143], v[128:129], off
	global_load_dwordx4 v[136:139], v[128:129], off offset:256
	v_lshl_add_u64 v[222:223], v[248:249], 0, s[20:21]
	v_lshl_add_u64 v[128:129], v[130:131], 0, v[222:223]
	v_pk_mul_f32 v[212:213], v[134:135], 0.5 op_sel_hi:[1,0]
	v_pk_mul_f32 v[210:211], v[132:133], 0.5 op_sel_hi:[1,0]
	global_load_dwordx4 v[132:135], v[128:129], off
	s_nop 0
	global_load_dwordx4 v[128:131], v[128:129], off offset:256
	v_lshl_add_u64 v[226:227], s[22:23], 0, v[226:227]
	v_lshl_add_u64 v[248:249], v[226:227], 0, v[248:249]
	s_mov_b64 s[24:25], s[6:7]
	s_mov_b64 s[22:23], s[4:5]
	s_waitcnt vmcnt(0)
	v_lshlrev_b32_e32 v250, 16, v244
	v_and_b32_e32 v251, 0xffff0000, v244
	v_lshlrev_b32_e32 v244, 16, v245
	v_and_b32_e32 v245, 0xffff0000, v245
	v_lshlrev_b32_e32 v252, 16, v246
	v_and_b32_e32 v253, 0xffff0000, v246
	v_lshlrev_b32_e32 v246, 16, v247
	v_and_b32_e32 v247, 0xffff0000, v247
	v_pk_fma_f32 v[126:127], v[126:127], v[220:221], v[244:245]
	v_pk_fma_f32 v[124:125], v[124:125], v[218:219], v[250:251]
	v_pk_fma_f32 v[244:245], v[122:123], v[216:217], v[246:247]
	v_pk_fma_f32 v[122:123], v[120:121], v[214:215], v[252:253]
	v_cvt_pk_bf16_f32 v120, v124, v125
	v_cvt_pk_bf16_f32 v121, v126, v127
	v_lshlrev_b32_e32 v124, 16, v186
	v_cvt_pk_bf16_f32 v122, v122, v123
	v_cvt_pk_bf16_f32 v123, v244, v245
	global_store_dwordx4 v[248:249], v[120:123], off
	v_and_b32_e32 v125, 0xffff0000, v186
	v_lshlrev_b32_e32 v126, 16, v187
	v_lshlrev_b32_e32 v120, 16, v184
	v_and_b32_e32 v121, 0xffff0000, v184
	v_and_b32_e32 v127, 0xffff0000, v187
	v_lshlrev_b32_e32 v122, 16, v185
	v_and_b32_e32 v123, 0xffff0000, v185
	v_pk_fma_f32 v[116:117], v[116:117], v[210:211], v[120:121]
	v_pk_fma_f32 v[120:121], v[114:115], v[208:209], v[126:127]
	v_pk_fma_f32 v[114:115], v[112:113], v[206:207], v[124:125]
	v_pk_fma_f32 v[118:119], v[118:119], v[212:213], v[122:123]
	v_cvt_pk_bf16_f32 v112, v116, v117
	v_lshlrev_b32_e32 v116, 16, v181
	v_cvt_pk_bf16_f32 v113, v118, v119
	v_cvt_pk_bf16_f32 v114, v114, v115
	v_cvt_pk_bf16_f32 v115, v120, v121
	global_store_dwordx4 v[248:249], v[112:115], off offset:256
	v_and_b32_e32 v117, 0xffff0000, v181
	v_lshlrev_b32_e32 v118, 16, v182
	v_lshlrev_b32_e32 v114, 16, v180
	v_and_b32_e32 v115, 0xffff0000, v180
	v_and_b32_e32 v119, 0xffff0000, v182
	v_lshlrev_b32_e32 v120, 16, v183
	v_and_b32_e32 v121, 0xffff0000, v183
	v_lshl_add_u64 v[112:113], v[226:227], 0, v[236:237]
	v_pk_fma_f32 v[110:111], v[110:111], v[220:221], v[116:117]
	v_pk_fma_f32 v[108:109], v[108:109], v[218:219], v[114:115]
	v_pk_fma_f32 v[114:115], v[106:107], v[216:217], v[120:121]
	v_pk_fma_f32 v[106:107], v[104:105], v[214:215], v[118:119]
	v_cvt_pk_bf16_f32 v104, v108, v109
	v_cvt_pk_bf16_f32 v105, v110, v111
	v_lshlrev_b32_e32 v108, 16, v178
	v_cvt_pk_bf16_f32 v106, v106, v107
	v_cvt_pk_bf16_f32 v107, v114, v115
; __device__ __forceinline__ unsigned cvt_pk_bf16(float lo, float hi) { unsigned r; asm volatile("v_cvt_pk_bf16_f32 %0, %1, %2" : "=v"(r) : "v"(lo), "v"(hi)); return r; }
; __device__ __forceinline__ float bf_lo(unsigned u) { return __uint_as_float(u << 16); }
; __device__ __forceinline__ float bf_hi(unsigned u) { return __uint_as_float(u & 0xffff0000u); }
;     __device__ __forceinline__ void operator()(const AccT& acc, const Unit& u, int wr, int wc, int fr, int fq) const {
;     ...
;         for (int ai = 0; ai < 2; ++ai)
; #pragma unroll
;             for (int m = 0; m < 4; ++m)
; #pragma unroll
;                 for (int bj = 0; bj < 2; ++bj) {
;                     const u32x4 q = r[ai][m][bj];
;                     const f32x4 r0 = {bf_lo(q.x), bf_hi(q.x), bf_lo(q.y), bf_hi(q.y)}, r1 = {bf_lo(q.z), bf_hi(q.z), bf_lo(q.w), bf_hi(q.w)};
;                     const f32x4 h0 = r0 + gv[bj][0] * acc[ai][bj][m][0], h1 = r1 + gv[bj][1] * acc[ai][bj][m][1];
;                     u32x4 w; w.x = cvt_pk_bf16(h0[0], h0[1]); w.y = cvt_pk_bf16(h0[2], h0[3]); w.z = cvt_pk_bf16(h1[0], h1[1]); w.w = cvt_pk_bf16(h1[2], h1[3]);
;                     *(u32x4*)(out + (size_t)(wr * 64 + fr + ai * 128 + m * 16) * DM + col0 + bj * 128) = w;
;                 }
	global_store_dwordx4 v[112:113], v[104:107], off
	v_and_b32_e32 v109, 0xffff0000, v178
	v_lshlrev_b32_e32 v110, 16, v179
	v_lshlrev_b32_e32 v104, 16, v176
	v_and_b32_e32 v105, 0xffff0000, v176
	v_and_b32_e32 v111, 0xffff0000, v179
	v_lshlrev_b32_e32 v106, 16, v177
	v_and_b32_e32 v107, 0xffff0000, v177
	v_pk_fma_f32 v[100:101], v[100:101], v[210:211], v[104:105]
	v_pk_fma_f32 v[104:105], v[98:99], v[208:209], v[110:111]
	v_pk_fma_f32 v[98:99], v[96:97], v[206:207], v[108:109]
	v_pk_fma_f32 v[102:103], v[102:103], v[212:213], v[106:107]
	v_cvt_pk_bf16_f32 v96, v100, v101
	v_lshlrev_b32_e32 v100, 16, v173
	v_cvt_pk_bf16_f32 v97, v102, v103
	v_cvt_pk_bf16_f32 v98, v98, v99
	v_cvt_pk_bf16_f32 v99, v104, v105
	global_store_dwordx4 v[112:113], v[96:99], off offset:256
	v_and_b32_e32 v101, 0xffff0000, v173
	v_lshlrev_b32_e32 v102, 16, v174
	v_lshlrev_b32_e32 v98, 16, v172
	v_and_b32_e32 v99, 0xffff0000, v172
	v_and_b32_e32 v103, 0xffff0000, v174
	v_lshlrev_b32_e32 v104, 16, v175
	v_and_b32_e32 v105, 0xffff0000, v175
	v_lshl_add_u64 v[96:97], v[226:227], 0, v[234:235]
	v_pk_fma_f32 v[94:95], v[94:95], v[220:221], v[100:101]
	v_pk_fma_f32 v[92:93], v[92:93], v[218:219], v[98:99]
	v_pk_fma_f32 v[98:99], v[90:91], v[216:217], v[104:105]
	v_pk_fma_f32 v[90:91], v[88:89], v[214:215], v[102:103]
	v_cvt_pk_bf16_f32 v88, v92, v93
	v_cvt_pk_bf16_f32 v89, v94, v95
	v_lshlrev_b32_e32 v92, 16, v170
	v_cvt_pk_bf16_f32 v90, v90, v91
	v_cvt_pk_bf16_f32 v91, v98, v99
	global_store_dwordx4 v[96:97], v[88:91], off
	v_and_b32_e32 v93, 0xffff0000, v170
	v_lshlrev_b32_e32 v94, 16, v171
	v_lshlrev_b32_e32 v88, 16, v168
	v_and_b32_e32 v89, 0xffff0000, v168
	v_and_b32_e32 v95, 0xffff0000, v171
	v_lshlrev_b32_e32 v90, 16, v169
	v_and_b32_e32 v91, 0xffff0000, v169
	v_pk_fma_f32 v[84:85], v[84:85], v[210:211], v[88:89]
	v_pk_fma_f32 v[88:89], v[82:83], v[208:209], v[94:95]
	v_pk_fma_f32 v[82:83], v[80:81], v[206:207], v[92:93]
	v_pk_fma_f32 v[86:87], v[86:87], v[212:213], v[90:91]
	v_cvt_pk_bf16_f32 v80, v84, v85
	v_lshlrev_b32_e32 v84, 16, v165
	v_cvt_pk_bf16_f32 v81, v86, v87
	v_cvt_pk_bf16_f32 v82, v82, v83
	v_cvt_pk_bf16_f32 v83, v88, v89
	global_store_dwordx4 v[96:97], v[80:83], off offset:256
	v_and_b32_e32 v85, 0xffff0000, v165
	v_lshlrev_b32_e32 v86, 16, v166
	v_lshlrev_b32_e32 v82, 16, v164
	v_and_b32_e32 v83, 0xffff0000, v164
	v_and_b32_e32 v87, 0xffff0000, v166
	v_lshlrev_b32_e32 v88, 16, v167
	v_and_b32_e32 v89, 0xffff0000, v167
	v_lshl_add_u64 v[80:81], v[226:227], 0, v[232:233]
	v_pk_fma_f32 v[78:79], v[78:79], v[220:221], v[84:85]
	v_pk_fma_f32 v[76:77], v[76:77], v[218:219], v[82:83]
	v_pk_fma_f32 v[82:83], v[74:75], v[216:217], v[88:89]
	v_pk_fma_f32 v[74:75], v[72:73], v[214:215], v[86:87]
	v_cvt_pk_bf16_f32 v72, v76, v77
	v_cvt_pk_bf16_f32 v73, v78, v79
	v_lshlrev_b32_e32 v76, 16, v162
	v_cvt_pk_bf16_f32 v74, v74, v75
	v_cvt_pk_bf16_f32 v75, v82, v83
	global_store_dwordx4 v[80:81], v[72:75], off
	v_and_b32_e32 v77, 0xffff0000, v162
	v_lshlrev_b32_e32 v78, 16, v163
	v_lshlrev_b32_e32 v72, 16, v160
	v_and_b32_e32 v73, 0xffff0000, v160
	v_and_b32_e32 v79, 0xffff0000, v163
	v_lshlrev_b32_e32 v74, 16, v161
	v_and_b32_e32 v75, 0xffff0000, v161
	v_pk_fma_f32 v[68:69], v[68:69], v[210:211], v[72:73]
	v_pk_fma_f32 v[72:73], v[66:67], v[208:209], v[78:79]
	v_pk_fma_f32 v[66:67], v[64:65], v[206:207], v[76:77]
	v_pk_fma_f32 v[70:71], v[70:71], v[212:213], v[74:75]
	v_cvt_pk_bf16_f32 v64, v68, v69
	v_lshlrev_b32_e32 v68, 16, v157
	v_cvt_pk_bf16_f32 v65, v70, v71
	v_cvt_pk_bf16_f32 v66, v66, v67
	v_cvt_pk_bf16_f32 v67, v72, v73
	global_store_dwordx4 v[80:81], v[64:67], off offset:256
	v_and_b32_e32 v69, 0xffff0000, v157
	v_lshlrev_b32_e32 v70, 16, v158
	v_lshlrev_b32_e32 v66, 16, v156
	v_and_b32_e32 v67, 0xffff0000, v156
	v_and_b32_e32 v71, 0xffff0000, v158
	v_lshlrev_b32_e32 v72, 16, v159
	v_and_b32_e32 v73, 0xffff0000, v159
	v_lshl_add_u64 v[64:65], v[226:227], 0, v[230:231]
	v_pk_fma_f32 v[62:63], v[62:63], v[220:221], v[68:69]
	v_pk_fma_f32 v[60:61], v[60:61], v[218:219], v[66:67]
	v_pk_fma_f32 v[66:67], v[58:59], v[216:217], v[72:73]
	v_pk_fma_f32 v[58:59], v[56:57], v[214:215], v[70:71]
	v_cvt_pk_bf16_f32 v56, v60, v61
	v_cvt_pk_bf16_f32 v57, v62, v63
	v_lshlrev_b32_e32 v60, 16, v154
	v_cvt_pk_bf16_f32 v58, v58, v59
	v_cvt_pk_bf16_f32 v59, v66, v67
	global_store_dwordx4 v[64:65], v[56:59], off
	v_and_b32_e32 v61, 0xffff0000, v154
	v_lshlrev_b32_e32 v62, 16, v155
	v_lshlrev_b32_e32 v56, 16, v152
	v_and_b32_e32 v57, 0xffff0000, v152
	v_and_b32_e32 v63, 0xffff0000, v155
	v_lshlrev_b32_e32 v58, 16, v153
	v_and_b32_e32 v59, 0xffff0000, v153
	v_pk_fma_f32 v[52:53], v[52:53], v[210:211], v[56:57]
; __device__ __forceinline__ unsigned cvt_pk_bf16(float lo, float hi) { unsigned r; asm volatile("v_cvt_pk_bf16_f32 %0, %1, %2" : "=v"(r) : "v"(lo), "v"(hi)); return r; }
; __device__ __forceinline__ float bf_lo(unsigned u) { return __uint_as_float(u << 16); }
; __device__ __forceinline__ float bf_hi(unsigned u) { return __uint_as_float(u & 0xffff0000u); }
;     __device__ __forceinline__ void operator()(const AccT& acc, const Unit& u, int wr, int wc, int fr, int fq) const {
;     ...
;         for (int ai = 0; ai < 2; ++ai)
; #pragma unroll
;             for (int m = 0; m < 4; ++m)
; #pragma unroll
;                 for (int bj = 0; bj < 2; ++bj) {
;                     const u32x4 q = r[ai][m][bj];
;                     const f32x4 r0 = {bf_lo(q.x), bf_hi(q.x), bf_lo(q.y), bf_hi(q.y)}, r1 = {bf_lo(q.z), bf_hi(q.z), bf_lo(q.w), bf_hi(q.w)};
;                     const f32x4 h0 = r0 + gv[bj][0] * acc[ai][bj][m][0], h1 = r1 + gv[bj][1] * acc[ai][bj][m][1];
;                     u32x4 w; w.x = cvt_pk_bf16(h0[0], h0[1]); w.y = cvt_pk_bf16(h0[2], h0[3]); w.z = cvt_pk_bf16(h1[0], h1[1]); w.w = cvt_pk_bf16(h1[2], h1[3]);
;                     *(u32x4*)(out + (size_t)(wr * 64 + fr + ai * 128 + m * 16) * DM + col0 + bj * 128) = w;
;                 }
	v_pk_fma_f32 v[56:57], v[50:51], v[208:209], v[62:63]
	v_pk_fma_f32 v[50:51], v[48:49], v[206:207], v[60:61]
	v_pk_fma_f32 v[54:55], v[54:55], v[212:213], v[58:59]
	v_cvt_pk_bf16_f32 v48, v52, v53
	v_lshlrev_b32_e32 v52, 16, v149
	v_cvt_pk_bf16_f32 v49, v54, v55
	v_cvt_pk_bf16_f32 v50, v50, v51
	v_cvt_pk_bf16_f32 v51, v56, v57
	global_store_dwordx4 v[64:65], v[48:51], off offset:256
	v_and_b32_e32 v53, 0xffff0000, v149
	v_lshlrev_b32_e32 v54, 16, v150
	v_lshlrev_b32_e32 v50, 16, v148
	v_and_b32_e32 v51, 0xffff0000, v148
	v_and_b32_e32 v55, 0xffff0000, v150
	v_lshlrev_b32_e32 v56, 16, v151
	v_and_b32_e32 v57, 0xffff0000, v151
	v_lshl_add_u64 v[48:49], v[226:227], 0, v[228:229]
	v_pk_fma_f32 v[46:47], v[46:47], v[220:221], v[52:53]
	v_pk_fma_f32 v[44:45], v[44:45], v[218:219], v[50:51]
	v_pk_fma_f32 v[50:51], v[42:43], v[216:217], v[56:57]
	v_pk_fma_f32 v[42:43], v[40:41], v[214:215], v[54:55]
	v_cvt_pk_bf16_f32 v40, v44, v45
	v_cvt_pk_bf16_f32 v41, v46, v47
	v_lshlrev_b32_e32 v44, 16, v146
	v_cvt_pk_bf16_f32 v42, v42, v43
	v_cvt_pk_bf16_f32 v43, v50, v51
	global_store_dwordx4 v[48:49], v[40:43], off
	v_and_b32_e32 v45, 0xffff0000, v146
	v_lshlrev_b32_e32 v46, 16, v147
	v_lshlrev_b32_e32 v40, 16, v144
	v_and_b32_e32 v41, 0xffff0000, v144
	v_and_b32_e32 v47, 0xffff0000, v147
	v_lshlrev_b32_e32 v42, 16, v145
	v_and_b32_e32 v43, 0xffff0000, v145
	v_pk_fma_f32 v[36:37], v[36:37], v[210:211], v[40:41]
	v_pk_fma_f32 v[40:41], v[34:35], v[208:209], v[46:47]
	v_pk_fma_f32 v[34:35], v[32:33], v[206:207], v[44:45]
	v_pk_fma_f32 v[38:39], v[38:39], v[212:213], v[42:43]
	v_cvt_pk_bf16_f32 v32, v36, v37
	v_lshlrev_b32_e32 v36, 16, v141
	v_cvt_pk_bf16_f32 v33, v38, v39
	v_cvt_pk_bf16_f32 v34, v34, v35
	v_cvt_pk_bf16_f32 v35, v40, v41
	global_store_dwordx4 v[48:49], v[32:35], off offset:256
	v_and_b32_e32 v37, 0xffff0000, v141
	v_lshlrev_b32_e32 v38, 16, v142
	v_lshlrev_b32_e32 v34, 16, v140
	v_and_b32_e32 v35, 0xffff0000, v140
	v_and_b32_e32 v39, 0xffff0000, v142
	v_lshlrev_b32_e32 v40, 16, v143
	v_and_b32_e32 v41, 0xffff0000, v143
	v_lshl_add_u64 v[32:33], v[226:227], 0, v[224:225]
	v_pk_fma_f32 v[30:31], v[30:31], v[220:221], v[36:37]
	v_pk_fma_f32 v[28:29], v[28:29], v[218:219], v[34:35]
	v_pk_fma_f32 v[34:35], v[26:27], v[216:217], v[40:41]
	v_pk_fma_f32 v[26:27], v[24:25], v[214:215], v[38:39]
	v_cvt_pk_bf16_f32 v24, v28, v29
	v_cvt_pk_bf16_f32 v25, v30, v31
	v_lshlrev_b32_e32 v28, 16, v138
	v_cvt_pk_bf16_f32 v26, v26, v27
	v_cvt_pk_bf16_f32 v27, v34, v35
	global_store_dwordx4 v[32:33], v[24:27], off
	v_and_b32_e32 v29, 0xffff0000, v138
	v_lshlrev_b32_e32 v30, 16, v139
	v_lshlrev_b32_e32 v24, 16, v136
	v_and_b32_e32 v25, 0xffff0000, v136
	v_and_b32_e32 v31, 0xffff0000, v139
	v_lshlrev_b32_e32 v26, 16, v137
	v_and_b32_e32 v27, 0xffff0000, v137
	v_pk_fma_f32 v[20:21], v[20:21], v[210:211], v[24:25]
	v_pk_fma_f32 v[24:25], v[18:19], v[208:209], v[30:31]
	v_pk_fma_f32 v[18:19], v[16:17], v[206:207], v[28:29]
	v_pk_fma_f32 v[22:23], v[22:23], v[212:213], v[26:27]
	v_cvt_pk_bf16_f32 v16, v20, v21
	v_lshlrev_b32_e32 v20, 16, v133
	v_cvt_pk_bf16_f32 v17, v22, v23
	v_cvt_pk_bf16_f32 v18, v18, v19
	v_cvt_pk_bf16_f32 v19, v24, v25
	global_store_dwordx4 v[32:33], v[16:19], off offset:256
	v_and_b32_e32 v21, 0xffff0000, v133
	v_lshlrev_b32_e32 v22, 16, v134
	v_lshlrev_b32_e32 v18, 16, v132
	v_and_b32_e32 v19, 0xffff0000, v132
	v_and_b32_e32 v23, 0xffff0000, v134
	v_lshlrev_b32_e32 v24, 16, v135
	v_and_b32_e32 v25, 0xffff0000, v135
	v_lshl_add_u64 v[16:17], v[226:227], 0, v[222:223]
	v_pk_fma_f32 v[14:15], v[14:15], v[220:221], v[20:21]
	v_pk_fma_f32 v[12:13], v[12:13], v[218:219], v[18:19]
	v_pk_fma_f32 v[18:19], v[10:11], v[216:217], v[24:25]
	v_pk_fma_f32 v[10:11], v[8:9], v[214:215], v[22:23]
	v_cvt_pk_bf16_f32 v8, v12, v13
	v_cvt_pk_bf16_f32 v9, v14, v15
	v_lshlrev_b32_e32 v12, 16, v130
	v_cvt_pk_bf16_f32 v10, v10, v11
	v_cvt_pk_bf16_f32 v11, v18, v19
	global_store_dwordx4 v[16:17], v[8:11], off
	v_and_b32_e32 v13, 0xffff0000, v130
	v_lshlrev_b32_e32 v14, 16, v131
	v_lshlrev_b32_e32 v8, 16, v128
	v_and_b32_e32 v9, 0xffff0000, v128
	v_and_b32_e32 v15, 0xffff0000, v131
	v_lshlrev_b32_e32 v10, 16, v129
	v_and_b32_e32 v11, 0xffff0000, v129
	v_pk_fma_f32 v[4:5], v[4:5], v[210:211], v[8:9]
	v_pk_fma_f32 v[8:9], v[2:3], v[208:209], v[14:15]
	v_pk_fma_f32 v[2:3], v[0:1], v[206:207], v[12:13]
	v_pk_fma_f32 v[6:7], v[6:7], v[212:213], v[10:11]
	v_cvt_pk_bf16_f32 v0, v4, v5
	s_nop 0
	v_cvt_pk_bf16_f32 v1, v6, v7
	v_cvt_pk_bf16_f32 v2, v2, v3
	v_cvt_pk_bf16_f32 v3, v8, v9
	global_store_dwordx4 v[16:17], v[0:3], off offset:256
	s_cbranch_vccz .LBB0_1086
	s_waitcnt vmcnt(0)
	s_cmpk_gt_u32 s30, 0xff
	s_cbranch_scc1 .LBB0_1101
	s_barrier
